# remaining v_xor+v_mov pair shuffles replaced by one packed multiply by 1.0 with lane-select/neg modifiers (291 sites, bit-exact)
# speedup vs baseline: 1.0132x; 1.0092x over previous
.LBB0_134:
	global_load_dword v6, v[22:23], off
	v_lshrrev_b32_e32 v26, 2, v11
	v_add_u32_e32 v25, 0x200, v25
	v_and_b32_e32 v26, 0x3ffffff8, v26
	v_cmp_lt_u32_e32 vcc, s34, v25
	v_add_u32_e32 v11, 8, v11
	v_lshl_add_u64 v[22:23], v[22:23], 0, s[26:27]
	v_add_u32_e32 v26, v24, v26
	v_add_u32_e32 v24, 64, v24
	s_or_b64 s[62:63], vcc, s[62:63]
	s_waitcnt vmcnt(0)
	ds_write_b64 v26, v[6:7]
	s_andn2_b64 exec, exec, s[62:63]
	s_cbranch_execnz .LBB0_134
	s_or_b64 exec, exec, s[62:63]
	v_mov_b32_e32 v6, v62
	s_waitcnt lgkmcnt(0)
	s_barrier
	s_mov_b32 s43, s40
	v_and_b32_e32 v11, 15, v6
	v_cvt_f32_ubyte0_e32 v22, v11
	v_mul_f32_e32 v23, 0x3b800000, v22
	v_sin_f32_e32 v22, v23
	v_cos_f32_e32 v24, v23
	v_lshlrev_b32_e32 v6, 4, v6
	v_and_b32_e32 v6, 0xffffff00, v6
	v_xor_b32_e32 v25, 0x80000000, v22
	v_mov_b32_e32 v23, v25
	v_pk_mul_f32 v[26:27], v[24:25], v[22:23] op_sel:[1,0] op_sel_hi:[0,1]
	v_pk_fma_f32 v[26:27], v[24:25], v[24:25], v[26:27] op_sel_hi:[1,0,1]
	v_lshlrev_b32_e32 v11, 3, v11
	v_pk_mul_f32 v[32:33], 1.0, v[26:27] op_sel:[0,1] op_sel_hi:[0,1] neg_lo:[0,1]
	v_pk_mul_f32 v[30:31], v[26:27], v[32:33] op_sel:[1,0] op_sel_hi:[0,1]
	v_pk_fma_f32 v[30:31], v[26:27], v[26:27], v[30:31] op_sel_hi:[1,0,1]
	v_pk_mul_f32 v[28:29], v[22:23], v[26:27] op_sel:[0,1] op_sel_hi:[1,0]
	v_pk_mul_f32 v[34:35], 1.0, v[30:31] op_sel:[0,1] op_sel_hi:[0,1] neg_lo:[0,1]
	v_pk_mul_f32 v[50:51], v[30:31], v[34:35] op_sel:[1,0] op_sel_hi:[0,1]
	v_pk_fma_f32 v[50:51], v[30:31], v[30:31], v[50:51] op_sel_hi:[1,0,1]
	v_pk_mul_f32 v[36:37], v[22:23], v[30:31] op_sel:[0,1] op_sel_hi:[1,0]
	v_pk_mul_f32 v[70:71], v[34:35], v[50:51] op_sel:[0,1] op_sel_hi:[1,0]
	v_pk_mul_f32 v[54:55], v[22:23], v[50:51] op_sel:[0,1] op_sel_hi:[1,0]
	v_pk_fma_f32 v[70:71], v[30:31], v[50:51], v[70:71] op_sel_hi:[0,1,1]
	v_pk_mul_f32 v[74:75], v[22:23], v[70:71] op_sel:[0,1] op_sel_hi:[1,0]
	v_pk_fma_f32 v[28:29], v[24:25], v[26:27], v[28:29] op_sel_hi:[0,1,1]
	v_pk_fma_f32 v[36:37], v[24:25], v[30:31], v[36:37] op_sel_hi:[0,1,1]
	v_pk_fma_f32 v[54:55], v[24:25], v[50:51], v[54:55] op_sel_hi:[0,1,1]
	v_pk_fma_f32 v[74:75], v[24:25], v[70:71], v[74:75] op_sel_hi:[0,1,1]
	v_lshlrev_b32_e32 v25, 3, v6
	v_add3_u32 v11, 0, v11, v25
	v_ashrrev_i32_e32 v25, 2, v6
	v_add_u32_e32 v25, v11, v25
	ds_read2_b64 v[92:95], v25 offset1:16
	ds_read2_b64 v[96:99], v25 offset0:33 offset1:49
	ds_read2_b64 v[100:103], v25 offset0:66 offset1:82
	ds_read2_b64 v[104:107], v25 offset0:132 offset1:148
	ds_read2_b64 v[108:111], v25 offset0:99 offset1:115
	ds_read2_b64 v[112:115], v25 offset0:165 offset1:181
	ds_read2_b64 v[116:119], v25 offset0:198 offset1:214
	ds_read2_b64 v[120:123], v25 offset0:231 offset1:247
	s_waitcnt lgkmcnt(4)
	v_pk_add_f32 v[124:125], v[92:93], v[104:105]
	v_pk_add_f32 v[92:93], v[92:93], v[104:105] neg_lo:[0,1] neg_hi:[0,1]
	v_pk_add_f32 v[104:105], v[94:95], v[106:107]
	v_pk_add_f32 v[94:95], v[94:95], v[106:107] neg_lo:[0,1] neg_hi:[0,1]
	s_mov_b32 s45, s36
	v_pk_mul_f32 v[106:107], v[94:95], s[38:39]
	s_waitcnt lgkmcnt(1)
	v_pk_add_f32 v[126:127], v[102:103], v[118:119]
	v_pk_fma_f32 v[94:95], v[94:95], s[36:37], v[106:107] op_sel:[0,0,1] op_sel_hi:[1,0,0]
	v_pk_add_f32 v[106:107], v[96:97], v[112:113]
	v_pk_add_f32 v[96:97], v[96:97], v[112:113] neg_lo:[0,1] neg_hi:[0,1]
	v_pk_add_f32 v[102:103], v[102:103], v[118:119] neg_lo:[0,1] neg_hi:[0,1]
	v_pk_mul_f32 v[112:113], v[96:97], s[42:43]
	s_mov_b32 s62, s39
	v_pk_mul_f32 v[118:119], v[102:103], s[44:45]
	v_pk_fma_f32 v[96:97], v[96:97], s[40:41], v[112:113] op_sel:[0,0,1] op_sel_hi:[1,0,0]
	v_pk_add_f32 v[112:113], v[98:99], v[114:115]
	v_pk_add_f32 v[98:99], v[98:99], v[114:115] neg_lo:[0,1] neg_hi:[0,1]
	v_pk_fma_f32 v[102:103], v[102:103], s[62:63], v[118:119] op_sel:[0,0,1] op_sel_hi:[1,0,0] neg_lo:[1,0,0] neg_hi:[1,0,0]
	s_waitcnt lgkmcnt(0)
	v_pk_add_f32 v[118:119], v[108:109], v[120:121]
	v_pk_add_f32 v[108:109], v[108:109], v[120:121] neg_lo:[0,1] neg_hi:[0,1]
	v_pk_mul_f32 v[114:115], v[98:99], s[44:45]
	v_pk_mul_f32 v[120:121], v[108:109], s[42:43]
	v_pk_fma_f32 v[98:99], v[98:99], s[62:63], v[114:115] op_sel:[0,0,1] op_sel_hi:[1,0,0]
	v_pk_add_f32 v[114:115], v[100:101], v[116:117]
	v_pk_add_f32 v[116:117], v[100:101], v[116:117] neg_lo:[0,1] neg_hi:[0,1]
	v_pk_fma_f32 v[108:109], v[108:109], s[40:41], v[120:121] op_sel:[0,0,1] op_sel_hi:[1,0,0] neg_lo:[1,0,0] neg_hi:[1,0,0]
	v_pk_add_f32 v[120:121], v[110:111], v[122:123]
	v_pk_add_f32 v[110:111], v[110:111], v[122:123] neg_lo:[0,1] neg_hi:[0,1]
	s_nop 0
	v_pk_mul_f32 v[122:123], v[110:111], s[38:39]
	s_nop 0
	v_pk_fma_f32 v[110:111], v[110:111], s[36:37], v[122:123] op_sel:[0,0,1] op_sel_hi:[1,0,0] neg_lo:[1,0,0] neg_hi:[1,0,0]
	v_pk_add_f32 v[122:123], v[124:125], v[114:115]
	v_pk_add_f32 v[114:115], v[124:125], v[114:115] neg_lo:[0,1] neg_hi:[0,1]
	v_pk_add_f32 v[124:125], v[104:105], v[126:127]
	v_pk_add_f32 v[104:105], v[104:105], v[126:127] neg_lo:[0,1] neg_hi:[0,1]
	v_pk_add_f32 v[128:129], v[112:113], v[120:121]
	v_pk_add_f32 v[112:113], v[112:113], v[120:121] neg_lo:[0,1] neg_hi:[0,1]
	v_pk_add_f32 v[100:101], v[92:93], v[116:117] op_sel:[0,1] op_sel_hi:[1,0] neg_hi:[0,1]
	v_pk_add_f32 v[92:93], v[92:93], v[116:117] op_sel:[0,1] op_sel_hi:[1,0] neg_lo:[0,1]
	v_pk_add_f32 v[116:117], v[94:95], v[102:103]
	v_pk_add_f32 v[94:95], v[94:95], v[102:103] neg_lo:[0,1] neg_hi:[0,1]
	v_pk_mul_f32 v[126:127], v[104:105], s[42:43]
	v_pk_mul_f32 v[120:121], v[112:113], s[42:43]
	v_pk_mul_f32 v[102:103], v[94:95], s[42:43]
	v_pk_fma_f32 v[104:105], v[104:105], s[40:41], v[126:127] op_sel:[0,0,1] op_sel_hi:[1,0,0]
	v_pk_add_f32 v[126:127], v[106:107], v[118:119]
	v_pk_add_f32 v[118:119], v[106:107], v[118:119] neg_lo:[0,1] neg_hi:[0,1]
	v_pk_fma_f32 v[112:113], v[112:113], s[40:41], v[120:121] op_sel:[0,0,1] op_sel_hi:[1,0,0] neg_lo:[1,0,0] neg_hi:[1,0,0]
	v_pk_fma_f32 v[94:95], v[94:95], s[40:41], v[102:103] op_sel:[0,0,1] op_sel_hi:[1,0,0]
	v_pk_add_f32 v[102:103], v[96:97], v[108:109]
	v_pk_add_f32 v[120:121], v[98:99], v[110:111]
	v_pk_add_f32 v[98:99], v[98:99], v[110:111] neg_lo:[0,1] neg_hi:[0,1]
	v_pk_add_f32 v[108:109], v[96:97], v[108:109] neg_lo:[0,1] neg_hi:[0,1]
	v_pk_mul_f32 v[110:111], v[98:99], s[42:43]
	v_pk_add_f32 v[130:131], v[100:101], v[102:103]
	v_pk_add_f32 v[100:101], v[100:101], v[102:103] neg_lo:[0,1] neg_hi:[0,1]
	v_pk_add_f32 v[102:103], v[116:117], v[120:121]
	v_pk_add_f32 v[120:121], v[116:117], v[120:121] neg_lo:[0,1] neg_hi:[0,1]
	v_pk_mul_f32 v[38:39], v[28:29], 1.0 op_sel:[1,0] op_sel_hi:[1,0] neg_lo:[1,0]
	v_pk_mul_f32 v[42:43], v[32:33], v[30:31] op_sel:[0,1] op_sel_hi:[1,0]
	v_pk_fma_f32 v[98:99], v[98:99], s[40:41], v[110:111] op_sel:[0,0,1] op_sel_hi:[1,0,0] neg_lo:[1,0,0] neg_hi:[1,0,0]
	v_pk_add_f32 v[106:107], v[114:115], v[118:119] op_sel:[0,1] op_sel_hi:[1,0] neg_hi:[0,1]
	v_pk_add_f32 v[114:115], v[114:115], v[118:119] op_sel:[0,1] op_sel_hi:[1,0] neg_lo:[0,1]
	v_pk_add_f32 v[118:119], v[104:105], v[112:113]
	v_pk_add_f32 v[112:113], v[104:105], v[112:113] neg_lo:[0,1] neg_hi:[0,1]
	v_pk_mul_f32 v[40:41], v[36:37], 1.0 op_sel:[1,0] op_sel_hi:[1,0] neg_lo:[1,0]
	v_pk_fma_f32 v[42:43], v[26:27], v[30:31], v[42:43] op_sel_hi:[0,1,1]
	v_pk_mul_f32 v[46:47], v[30:31], v[38:39] op_sel:[1,0] op_sel_hi:[0,1]
	v_pk_add_f32 v[96:97], v[92:93], v[108:109] op_sel:[0,1] op_sel_hi:[1,0] neg_hi:[0,1]
	v_pk_add_f32 v[92:93], v[92:93], v[108:109] op_sel:[0,1] op_sel_hi:[1,0] neg_lo:[0,1]
	v_pk_add_f32 v[108:109], v[94:95], v[98:99]
	v_pk_add_f32 v[98:99], v[94:95], v[98:99] neg_lo:[0,1] neg_hi:[0,1]
	v_pk_add_f32 v[116:117], v[100:101], v[120:121] op_sel:[0,1] op_sel_hi:[1,0] neg_hi:[0,1]
	v_pk_mul_f32 v[44:45], v[42:43], 1.0 op_sel:[1,0] op_sel_hi:[1,0] neg_lo:[1,0]
	v_pk_fma_f32 v[46:47], v[30:31], v[28:29], v[46:47] op_sel_hi:[1,0,1]
	v_pk_add_f32 v[104:105], v[114:115], v[112:113] op_sel:[0,1] op_sel_hi:[1,0] neg_hi:[0,1]
	v_pk_add_f32 v[100:101], v[100:101], v[120:121] op_sel:[0,1] op_sel_hi:[1,0] neg_lo:[0,1]
	v_pk_mul_f32 v[120:121], v[40:41], v[116:117] op_sel:[0,1] op_sel_hi:[1,0]
	v_pk_mul_f32 v[48:49], v[46:47], 1.0 op_sel:[1,0] op_sel_hi:[1,0] neg_lo:[1,0]
	v_pk_add_f32 v[110:111], v[122:123], v[126:127]
	v_pk_add_f32 v[122:123], v[122:123], v[126:127] neg_lo:[0,1] neg_hi:[0,1]
	v_pk_add_f32 v[126:127], v[124:125], v[128:129]
	v_pk_add_f32 v[94:95], v[92:93], v[98:99] op_sel:[0,1] op_sel_hi:[1,0] neg_hi:[0,1]
	v_pk_fma_f32 v[116:117], v[36:37], v[116:117], v[120:121] op_sel_hi:[0,1,1]
	v_pk_mul_f32 v[120:121], v[44:45], v[104:105] op_sel:[0,1] op_sel_hi:[1,0]
	v_pk_mul_f32 v[52:53], v[50:51], 1.0 op_sel:[1,0] op_sel_hi:[1,0] neg_lo:[1,0]
	v_pk_mul_f32 v[58:59], v[32:33], v[50:51] op_sel:[0,1] op_sel_hi:[1,0]
	v_pk_add_f32 v[132:133], v[110:111], v[126:127]
	v_pk_add_f32 v[110:111], v[110:111], v[126:127] neg_lo:[0,1] neg_hi:[0,1]
	v_pk_fma_f32 v[104:105], v[42:43], v[104:105], v[120:121] op_sel_hi:[0,1,1]
	v_pk_mul_f32 v[120:121], v[48:49], v[94:95] op_sel:[0,1] op_sel_hi:[1,0]
	v_pk_mul_f32 v[56:57], v[54:55], 1.0 op_sel:[1,0] op_sel_hi:[1,0] neg_lo:[1,0]
	v_pk_fma_f32 v[58:59], v[26:27], v[50:51], v[58:59] op_sel_hi:[0,1,1]
	v_pk_mul_f32 v[66:67], v[38:39], v[50:51] op_sel:[0,1] op_sel_hi:[1,0]
	v_pk_add_f32 v[112:113], v[114:115], v[112:113] op_sel:[0,1] op_sel_hi:[1,0] neg_lo:[0,1]
	v_pk_add_f32 v[114:115], v[130:131], v[102:103]
	v_pk_add_f32 v[102:103], v[130:131], v[102:103] neg_lo:[0,1] neg_hi:[0,1]
	v_pk_fma_f32 v[94:95], v[46:47], v[94:95], v[120:121] op_sel_hi:[0,1,1]
	v_pk_mul_f32 v[120:121], v[52:53], v[110:111] op_sel:[0,1] op_sel_hi:[1,0]
	v_pk_mul_f32 v[60:61], v[58:59], 1.0 op_sel:[1,0] op_sel_hi:[1,0] neg_lo:[1,0]
	v_pk_fma_f32 v[66:67], v[28:29], v[50:51], v[66:67] op_sel_hi:[0,1,1]
	v_pk_add_f32 v[128:129], v[124:125], v[128:129] neg_lo:[0,1] neg_hi:[0,1]
	v_pk_add_f32 v[126:127], v[106:107], v[118:119]
	v_pk_add_f32 v[106:107], v[106:107], v[118:119] neg_lo:[0,1] neg_hi:[0,1]
	v_pk_fma_f32 v[110:111], v[50:51], v[110:111], v[120:121] op_sel_hi:[0,1,1]
	v_pk_mul_f32 v[120:121], v[56:57], v[102:103] op_sel:[0,1] op_sel_hi:[1,0]
	v_pk_mul_f32 v[68:69], v[66:67], 1.0 op_sel:[1,0] op_sel_hi:[1,0] neg_lo:[1,0]
	v_pk_add_f32 v[118:119], v[96:97], v[108:109]
	v_pk_add_f32 v[96:97], v[96:97], v[108:109] neg_lo:[0,1] neg_hi:[0,1]
	v_pk_fma_f32 v[102:103], v[54:55], v[102:103], v[120:121] op_sel_hi:[0,1,1]
	v_pk_mul_f32 v[120:121], v[60:61], v[106:107] op_sel:[0,1] op_sel_hi:[1,0]
	v_pk_mul_f32 v[72:73], v[70:71], 1.0 op_sel:[1,0] op_sel_hi:[1,0] neg_lo:[1,0]
	v_pk_mul_f32 v[78:79], v[32:33], v[70:71] op_sel:[0,1] op_sel_hi:[1,0]
	v_pk_add_f32 v[124:125], v[122:123], v[128:129] op_sel:[0,1] op_sel_hi:[1,0] neg_hi:[0,1]
	v_pk_add_f32 v[122:123], v[122:123], v[128:129] op_sel:[0,1] op_sel_hi:[1,0] neg_lo:[0,1]
	v_pk_fma_f32 v[106:107], v[58:59], v[106:107], v[120:121] op_sel_hi:[0,1,1]
	v_pk_mul_f32 v[120:121], v[68:69], v[96:97] op_sel:[0,1] op_sel_hi:[1,0]
	v_pk_mul_f32 v[76:77], v[74:75], 1.0 op_sel:[1,0] op_sel_hi:[1,0] neg_lo:[1,0]
	v_pk_fma_f32 v[78:79], v[26:27], v[70:71], v[78:79] op_sel_hi:[0,1,1]
	v_pk_mul_f32 v[82:83], v[38:39], v[70:71] op_sel:[0,1] op_sel_hi:[1,0]
	v_pk_fma_f32 v[96:97], v[66:67], v[96:97], v[120:121] op_sel_hi:[0,1,1]
	v_pk_mul_f32 v[120:121], v[72:73], v[122:123] op_sel:[0,1] op_sel_hi:[1,0]
	v_pk_mul_f32 v[80:81], v[78:79], 1.0 op_sel:[1,0] op_sel_hi:[1,0] neg_lo:[1,0]
	v_pk_fma_f32 v[82:83], v[28:29], v[70:71], v[82:83] op_sel_hi:[0,1,1]
	v_pk_add_f32 v[92:93], v[92:93], v[98:99] op_sel:[0,1] op_sel_hi:[1,0] neg_lo:[0,1]
	v_pk_mul_f32 v[98:99], v[22:23], v[114:115] op_sel:[0,1] op_sel_hi:[1,0]
	v_pk_fma_f32 v[120:121], v[70:71], v[122:123], v[120:121] op_sel_hi:[0,1,1]
	v_pk_mul_f32 v[122:123], v[76:77], v[100:101] op_sel:[0,1] op_sel_hi:[1,0]
	v_pk_mul_f32 v[84:85], v[82:83], 1.0 op_sel:[1,0] op_sel_hi:[1,0] neg_lo:[1,0]
	v_pk_fma_f32 v[98:99], v[24:25], v[114:115], v[98:99] op_sel_hi:[0,1,1]
	v_pk_mul_f32 v[114:115], v[38:39], v[118:119] op_sel:[0,1] op_sel_hi:[1,0]
	v_pk_fma_f32 v[100:101], v[74:75], v[100:101], v[122:123] op_sel_hi:[0,1,1]
	v_pk_mul_f32 v[122:123], v[80:81], v[112:113] op_sel:[0,1] op_sel_hi:[1,0]
	v_add_u32_e32 v6, 0x2000, v6
	v_pk_mul_f32 v[108:109], v[32:33], v[126:127] op_sel:[0,1] op_sel_hi:[1,0]
	v_pk_fma_f32 v[114:115], v[28:29], v[118:119], v[114:115] op_sel_hi:[0,1,1]
	v_pk_mul_f32 v[118:119], v[34:35], v[124:125] op_sel:[0,1] op_sel_hi:[1,0]
	v_pk_fma_f32 v[112:113], v[78:79], v[112:113], v[122:123] op_sel_hi:[0,1,1]
	v_pk_mul_f32 v[122:123], v[84:85], v[92:93] op_sel:[0,1] op_sel_hi:[1,0]
	v_ashrrev_i32_e32 v6, 2, v6
	v_pk_fma_f32 v[108:109], v[26:27], v[126:127], v[108:109] op_sel_hi:[0,1,1]
	v_pk_fma_f32 v[118:119], v[30:31], v[124:125], v[118:119] op_sel_hi:[0,1,1]
	v_pk_fma_f32 v[92:93], v[82:83], v[92:93], v[122:123] op_sel_hi:[0,1,1]
	ds_write2_b64 v25, v[132:133], v[110:111] offset1:16
	ds_write2_b64 v25, v[118:119], v[120:121] offset0:33 offset1:49
	ds_write2_b64 v25, v[108:109], v[106:107] offset0:66 offset1:82
	ds_write2_b64 v25, v[104:105], v[112:113] offset0:99 offset1:115
	ds_write2_b64 v25, v[98:99], v[102:103] offset0:132 offset1:148
	ds_write2_b64 v25, v[116:117], v[100:101] offset0:165 offset1:181
	ds_write2_b64 v25, v[114:115], v[96:97] offset0:198 offset1:214
	ds_write2_b64 v25, v[94:95], v[92:93] offset0:231 offset1:247
	v_add3_u32 v6, v11, v6, s35
	ds_read2_b64 v[92:95], v6 offset1:16
	ds_read2_b64 v[96:99], v6 offset0:33 offset1:49
	ds_read2_b64 v[100:103], v6 offset0:66 offset1:82
	ds_read2_b64 v[104:107], v6 offset0:132 offset1:148
	ds_read2_b64 v[108:111], v6 offset0:99 offset1:115
	ds_read2_b64 v[112:115], v6 offset0:165 offset1:181
	ds_read2_b64 v[116:119], v6 offset0:198 offset1:214
	ds_read2_b64 v[120:123], v6 offset0:231 offset1:247
	s_waitcnt lgkmcnt(4)
	v_pk_add_f32 v[124:125], v[92:93], v[104:105]
	v_pk_add_f32 v[92:93], v[92:93], v[104:105] neg_lo:[0,1] neg_hi:[0,1]
	v_pk_add_f32 v[104:105], v[94:95], v[106:107]
	v_pk_add_f32 v[94:95], v[94:95], v[106:107] neg_lo:[0,1] neg_hi:[0,1]
	s_waitcnt lgkmcnt(1)
	v_pk_add_f32 v[126:127], v[102:103], v[118:119]
	v_pk_mul_f32 v[106:107], v[94:95], s[38:39]
	v_pk_add_f32 v[102:103], v[102:103], v[118:119] neg_lo:[0,1] neg_hi:[0,1]
	v_pk_fma_f32 v[94:95], v[94:95], s[36:37], v[106:107] op_sel:[0,0,1] op_sel_hi:[1,0,0]
	v_pk_add_f32 v[106:107], v[96:97], v[112:113]
	v_pk_add_f32 v[96:97], v[96:97], v[112:113] neg_lo:[0,1] neg_hi:[0,1]
	v_pk_mul_f32 v[118:119], v[102:103], s[44:45]
	v_pk_mul_f32 v[112:113], v[96:97], s[42:43]
	v_pk_fma_f32 v[102:103], v[102:103], s[62:63], v[118:119] op_sel:[0,0,1] op_sel_hi:[1,0,0] neg_lo:[1,0,0] neg_hi:[1,0,0]
	s_waitcnt lgkmcnt(0)
	v_pk_add_f32 v[118:119], v[108:109], v[120:121]
	v_pk_add_f32 v[108:109], v[108:109], v[120:121] neg_lo:[0,1] neg_hi:[0,1]
	v_pk_fma_f32 v[96:97], v[96:97], s[40:41], v[112:113] op_sel:[0,0,1] op_sel_hi:[1,0,0]
	v_pk_add_f32 v[112:113], v[98:99], v[114:115]
	v_pk_add_f32 v[98:99], v[98:99], v[114:115] neg_lo:[0,1] neg_hi:[0,1]
	v_pk_mul_f32 v[120:121], v[108:109], s[42:43]
	v_pk_mul_f32 v[114:115], v[98:99], s[44:45]
	v_pk_fma_f32 v[108:109], v[108:109], s[40:41], v[120:121] op_sel:[0,0,1] op_sel_hi:[1,0,0] neg_lo:[1,0,0] neg_hi:[1,0,0]
	v_pk_add_f32 v[120:121], v[110:111], v[122:123]
	v_pk_add_f32 v[110:111], v[110:111], v[122:123] neg_lo:[0,1] neg_hi:[0,1]
	v_pk_fma_f32 v[98:99], v[98:99], s[62:63], v[114:115] op_sel:[0,0,1] op_sel_hi:[1,0,0]
	v_pk_add_f32 v[114:115], v[100:101], v[116:117]
	v_pk_mul_f32 v[122:123], v[110:111], s[38:39]
	v_pk_add_f32 v[116:117], v[100:101], v[116:117] neg_lo:[0,1] neg_hi:[0,1]
	v_pk_fma_f32 v[110:111], v[110:111], s[36:37], v[122:123] op_sel:[0,0,1] op_sel_hi:[1,0,0] neg_lo:[1,0,0] neg_hi:[1,0,0]
	v_pk_add_f32 v[122:123], v[124:125], v[114:115]
	v_pk_add_f32 v[114:115], v[124:125], v[114:115] neg_lo:[0,1] neg_hi:[0,1]
	v_pk_add_f32 v[124:125], v[104:105], v[126:127]
	v_pk_add_f32 v[104:105], v[104:105], v[126:127] neg_lo:[0,1] neg_hi:[0,1]
	s_nop 0
	v_pk_mul_f32 v[126:127], v[104:105], s[42:43]
	v_pk_add_f32 v[128:129], v[112:113], v[120:121]
	v_pk_add_f32 v[112:113], v[112:113], v[120:121] neg_lo:[0,1] neg_hi:[0,1]
	v_pk_fma_f32 v[104:105], v[104:105], s[40:41], v[126:127] op_sel:[0,0,1] op_sel_hi:[1,0,0]
	v_pk_add_f32 v[126:127], v[106:107], v[118:119]
	v_pk_add_f32 v[118:119], v[106:107], v[118:119] neg_lo:[0,1] neg_hi:[0,1]
	v_pk_mul_f32 v[120:121], v[112:113], s[42:43]
	v_pk_add_f32 v[100:101], v[92:93], v[116:117] op_sel:[0,1] op_sel_hi:[1,0] neg_hi:[0,1]
	v_pk_add_f32 v[92:93], v[92:93], v[116:117] op_sel:[0,1] op_sel_hi:[1,0] neg_lo:[0,1]
	v_pk_add_f32 v[116:117], v[94:95], v[102:103]
	v_pk_add_f32 v[94:95], v[94:95], v[102:103] neg_lo:[0,1] neg_hi:[0,1]
	v_pk_fma_f32 v[112:113], v[112:113], s[40:41], v[120:121] op_sel:[0,0,1] op_sel_hi:[1,0,0] neg_lo:[1,0,0] neg_hi:[1,0,0]
	v_pk_mul_f32 v[102:103], v[94:95], s[42:43]
	s_nop 0
	v_pk_fma_f32 v[94:95], v[94:95], s[40:41], v[102:103] op_sel:[0,0,1] op_sel_hi:[1,0,0]
	v_pk_add_f32 v[102:103], v[96:97], v[108:109]
	v_pk_add_f32 v[120:121], v[98:99], v[110:111]
	v_pk_add_f32 v[98:99], v[98:99], v[110:111] neg_lo:[0,1] neg_hi:[0,1]
	v_pk_add_f32 v[106:107], v[114:115], v[118:119] op_sel:[0,1] op_sel_hi:[1,0] neg_hi:[0,1]
	v_pk_add_f32 v[114:115], v[114:115], v[118:119] op_sel:[0,1] op_sel_hi:[1,0] neg_lo:[0,1]
	v_pk_add_f32 v[118:119], v[104:105], v[112:113]
	v_pk_add_f32 v[112:113], v[104:105], v[112:113] neg_lo:[0,1] neg_hi:[0,1]
	v_pk_add_f32 v[108:109], v[96:97], v[108:109] neg_lo:[0,1] neg_hi:[0,1]
	v_pk_mul_f32 v[110:111], v[98:99], s[42:43]
	v_pk_add_f32 v[130:131], v[100:101], v[102:103]
	v_pk_add_f32 v[100:101], v[100:101], v[102:103] neg_lo:[0,1] neg_hi:[0,1]
	v_pk_add_f32 v[102:103], v[116:117], v[120:121]
	v_pk_fma_f32 v[98:99], v[98:99], s[40:41], v[110:111] op_sel:[0,0,1] op_sel_hi:[1,0,0] neg_lo:[1,0,0] neg_hi:[1,0,0]
	v_pk_add_f32 v[110:111], v[122:123], v[126:127]
	v_pk_add_f32 v[122:123], v[122:123], v[126:127] neg_lo:[0,1] neg_hi:[0,1]
	v_pk_add_f32 v[126:127], v[124:125], v[128:129]
	v_pk_add_f32 v[104:105], v[114:115], v[112:113] op_sel:[0,1] op_sel_hi:[1,0] neg_hi:[0,1]
	v_pk_add_f32 v[112:113], v[114:115], v[112:113] op_sel:[0,1] op_sel_hi:[1,0] neg_lo:[0,1]
	v_pk_add_f32 v[114:115], v[130:131], v[102:103]
	v_pk_add_f32 v[124:125], v[124:125], v[128:129] neg_lo:[0,1] neg_hi:[0,1]
	v_pk_add_f32 v[96:97], v[92:93], v[108:109] op_sel:[0,1] op_sel_hi:[1,0] neg_hi:[0,1]
	v_pk_add_f32 v[92:93], v[92:93], v[108:109] op_sel:[0,1] op_sel_hi:[1,0] neg_lo:[0,1]
	v_pk_add_f32 v[108:109], v[94:95], v[98:99]
	v_pk_add_f32 v[132:133], v[110:111], v[126:127]
	v_pk_add_f32 v[110:111], v[110:111], v[126:127] neg_lo:[0,1] neg_hi:[0,1]
	v_pk_add_f32 v[126:127], v[106:107], v[118:119]
	v_pk_mul_f32 v[22:23], v[22:23], v[114:115] op_sel:[0,1] op_sel_hi:[1,0]
	v_pk_mul_f32 v[128:129], v[124:125], 1.0 op_sel:[1,0] op_sel_hi:[0,0] neg_hi:[1,0]
	v_pk_add_f32 v[116:117], v[116:117], v[120:121] neg_lo:[0,1] neg_hi:[0,1]
	v_pk_add_f32 v[106:107], v[106:107], v[118:119] neg_lo:[0,1] neg_hi:[0,1]
	v_pk_add_f32 v[118:119], v[96:97], v[108:109]
	v_pk_fma_f32 v[22:23], v[24:25], v[114:115], v[22:23] op_sel_hi:[0,1,1]
	v_pk_mul_f32 v[24:25], v[32:33], v[126:127] op_sel:[0,1] op_sel_hi:[1,0]
	v_pk_mul_f32 v[120:121], v[116:117], 1.0 op_sel:[1,0] op_sel_hi:[0,0] neg_hi:[1,0]
	v_pk_add_f32 v[94:95], v[94:95], v[98:99] neg_lo:[0,1] neg_hi:[0,1]
	v_pk_add_f32 v[124:125], v[122:123], v[128:129]
	v_pk_fma_f32 v[24:25], v[26:27], v[126:127], v[24:25] op_sel_hi:[0,1,1]
	v_pk_mul_f32 v[26:27], v[38:39], v[118:119] op_sel:[0,1] op_sel_hi:[1,0]
	v_pk_mul_f32 v[98:99], v[94:95], 1.0 op_sel:[1,0] op_sel_hi:[0,0] neg_hi:[1,0]
	v_pk_add_f32 v[116:117], v[100:101], v[120:121]
	v_pk_fma_f32 v[26:27], v[28:29], v[118:119], v[26:27] op_sel_hi:[0,1,1]
	v_pk_mul_f32 v[28:29], v[34:35], v[124:125] op_sel:[0,1] op_sel_hi:[1,0]
	v_pk_add_f32 v[94:95], v[92:93], v[98:99]
	v_pk_fma_f32 v[28:29], v[30:31], v[124:125], v[28:29] op_sel_hi:[0,1,1]
	v_pk_mul_f32 v[30:31], v[40:41], v[116:117] op_sel:[0,1] op_sel_hi:[1,0]
	v_pk_add_f32 v[122:123], v[122:123], v[128:129] neg_lo:[0,1] neg_hi:[0,1]
	v_pk_add_f32 v[102:103], v[130:131], v[102:103] neg_lo:[0,1] neg_hi:[0,1]
	v_pk_add_f32 v[100:101], v[100:101], v[120:121] neg_lo:[0,1] neg_hi:[0,1]
	v_pk_add_f32 v[96:97], v[96:97], v[108:109] neg_lo:[0,1] neg_hi:[0,1]
	v_pk_add_f32 v[92:93], v[92:93], v[98:99] neg_lo:[0,1] neg_hi:[0,1]
	v_pk_fma_f32 v[30:31], v[36:37], v[116:117], v[30:31] op_sel_hi:[0,1,1]
	v_pk_mul_f32 v[32:33], v[44:45], v[104:105] op_sel:[0,1] op_sel_hi:[1,0]
	v_pk_mul_f32 v[34:35], v[48:49], v[94:95] op_sel:[0,1] op_sel_hi:[1,0]
	v_pk_mul_f32 v[36:37], v[52:53], v[110:111] op_sel:[0,1] op_sel_hi:[1,0]
	v_pk_fma_f32 v[32:33], v[42:43], v[104:105], v[32:33] op_sel_hi:[0,1,1]
	v_pk_fma_f32 v[34:35], v[46:47], v[94:95], v[34:35] op_sel_hi:[0,1,1]
	v_pk_fma_f32 v[36:37], v[50:51], v[110:111], v[36:37] op_sel_hi:[0,1,1]
	v_pk_mul_f32 v[38:39], v[56:57], v[102:103] op_sel:[0,1] op_sel_hi:[1,0]
	v_pk_mul_f32 v[40:41], v[60:61], v[106:107] op_sel:[0,1] op_sel_hi:[1,0]
	v_pk_mul_f32 v[42:43], v[68:69], v[96:97] op_sel:[0,1] op_sel_hi:[1,0]
	v_pk_mul_f32 v[44:45], v[72:73], v[122:123] op_sel:[0,1] op_sel_hi:[1,0]
	v_pk_mul_f32 v[46:47], v[76:77], v[100:101] op_sel:[0,1] op_sel_hi:[1,0]
	v_pk_mul_f32 v[48:49], v[80:81], v[112:113] op_sel:[0,1] op_sel_hi:[1,0]
	v_pk_mul_f32 v[50:51], v[84:85], v[92:93] op_sel:[0,1] op_sel_hi:[1,0]
	v_pk_fma_f32 v[38:39], v[54:55], v[102:103], v[38:39] op_sel_hi:[0,1,1]
	v_pk_fma_f32 v[40:41], v[58:59], v[106:107], v[40:41] op_sel_hi:[0,1,1]
	v_pk_fma_f32 v[42:43], v[66:67], v[96:97], v[42:43] op_sel_hi:[0,1,1]
	v_pk_fma_f32 v[44:45], v[70:71], v[122:123], v[44:45] op_sel_hi:[0,1,1]
	v_pk_fma_f32 v[46:47], v[74:75], v[100:101], v[46:47] op_sel_hi:[0,1,1]
	v_pk_fma_f32 v[48:49], v[78:79], v[112:113], v[48:49] op_sel_hi:[0,1,1]
	v_pk_fma_f32 v[50:51], v[82:83], v[92:93], v[50:51] op_sel_hi:[0,1,1]
	ds_write2_b64 v6, v[132:133], v[36:37] offset1:16
	ds_write2_b64 v6, v[28:29], v[44:45] offset0:33 offset1:49
	ds_write2_b64 v6, v[24:25], v[40:41] offset0:66 offset1:82
	ds_write2_b64 v6, v[32:33], v[48:49] offset0:99 offset1:115
	ds_write2_b64 v6, v[22:23], v[38:39] offset0:132 offset1:148
	ds_write2_b64 v6, v[30:31], v[46:47] offset0:165 offset1:181
	ds_write2_b64 v6, v[26:27], v[42:43] offset0:198 offset1:214
	ds_write2_b64 v6, v[34:35], v[50:51] offset0:231 offset1:247
	v_mov_b32_e32 v6, v62
	s_waitcnt lgkmcnt(0)
	s_barrier
	s_lshl_b32 s24, s71, 6
	v_bfe_i32 v11, v6, 1, 27
	v_lshl_add_u32 v68, v6, 7, 0
	v_lshl_add_u32 v11, v11, 3, v68
	ds_read2_b64 v[22:25], v11 offset1:1
	ds_read2_b64 v[26:29], v11 offset0:2 offset1:3
	ds_read2_b64 v[30:33], v11 offset0:8 offset1:9
	ds_read2_b64 v[34:37], v11 offset0:4 offset1:5
	ds_read2_b64 v[38:41], v11 offset0:6 offset1:7
	ds_read2_b64 v[42:45], v11 offset0:10 offset1:11
	ds_read2_b64 v[46:49], v11 offset0:12 offset1:13
	ds_read2_b64 v[50:53], v11 offset0:14 offset1:15
	s_waitcnt lgkmcnt(5)
	v_pk_add_f32 v[54:55], v[22:23], v[30:31]
	v_pk_add_f32 v[22:23], v[22:23], v[30:31] neg_lo:[0,1] neg_hi:[0,1]
	v_pk_add_f32 v[30:31], v[24:25], v[32:33]
	v_pk_add_f32 v[24:25], v[24:25], v[32:33] neg_lo:[0,1] neg_hi:[0,1]
	s_waitcnt lgkmcnt(1)
	v_pk_add_f32 v[56:57], v[36:37], v[48:49]
	v_pk_mul_f32 v[32:33], v[24:25], s[38:39]
	v_pk_add_f32 v[36:37], v[36:37], v[48:49] neg_lo:[0,1] neg_hi:[0,1]
	v_pk_fma_f32 v[24:25], v[24:25], s[36:37], v[32:33] op_sel:[0,0,1] op_sel_hi:[1,0,0]
	v_pk_add_f32 v[32:33], v[26:27], v[42:43]
	v_pk_add_f32 v[26:27], v[26:27], v[42:43] neg_lo:[0,1] neg_hi:[0,1]
	v_pk_mul_f32 v[48:49], v[36:37], s[44:45]
	v_pk_mul_f32 v[42:43], v[26:27], s[42:43]
	v_pk_fma_f32 v[36:37], v[36:37], s[62:63], v[48:49] op_sel:[0,0,1] op_sel_hi:[1,0,0] neg_lo:[1,0,0] neg_hi:[1,0,0]
	v_pk_fma_f32 v[26:27], v[26:27], s[40:41], v[42:43] op_sel:[0,0,1] op_sel_hi:[1,0,0]
	v_pk_add_f32 v[42:43], v[28:29], v[44:45]
	v_pk_add_f32 v[28:29], v[28:29], v[44:45] neg_lo:[0,1] neg_hi:[0,1]
	s_waitcnt lgkmcnt(0)
	v_pk_add_f32 v[48:49], v[38:39], v[50:51]
	v_pk_add_f32 v[38:39], v[38:39], v[50:51] neg_lo:[0,1] neg_hi:[0,1]
	v_pk_mul_f32 v[44:45], v[28:29], s[44:45]
	v_pk_mul_f32 v[50:51], v[38:39], s[42:43]
	v_pk_fma_f32 v[28:29], v[28:29], s[62:63], v[44:45] op_sel:[0,0,1] op_sel_hi:[1,0,0]
	v_pk_add_f32 v[44:45], v[34:35], v[46:47]
	v_pk_add_f32 v[46:47], v[34:35], v[46:47] neg_lo:[0,1] neg_hi:[0,1]
	v_pk_fma_f32 v[38:39], v[38:39], s[40:41], v[50:51] op_sel:[0,0,1] op_sel_hi:[1,0,0] neg_lo:[1,0,0] neg_hi:[1,0,0]
	v_pk_add_f32 v[50:51], v[40:41], v[52:53]
	v_pk_add_f32 v[40:41], v[40:41], v[52:53] neg_lo:[0,1] neg_hi:[0,1]
	s_nop 0
	v_pk_mul_f32 v[52:53], v[40:41], s[38:39]
	v_pk_add_f32 v[58:59], v[42:43], v[50:51]
	v_pk_add_f32 v[42:43], v[42:43], v[50:51] neg_lo:[0,1] neg_hi:[0,1]
	v_pk_fma_f32 v[40:41], v[40:41], s[36:37], v[52:53] op_sel:[0,0,1] op_sel_hi:[1,0,0] neg_lo:[1,0,0] neg_hi:[1,0,0]
	v_pk_add_f32 v[52:53], v[54:55], v[44:45]
	v_pk_add_f32 v[44:45], v[54:55], v[44:45] neg_lo:[0,1] neg_hi:[0,1]
	v_pk_add_f32 v[54:55], v[30:31], v[56:57]
	v_pk_add_f32 v[30:31], v[30:31], v[56:57] neg_lo:[0,1] neg_hi:[0,1]
	v_pk_mul_f32 v[50:51], v[42:43], s[42:43]
	v_pk_add_f32 v[34:35], v[22:23], v[46:47] op_sel:[0,1] op_sel_hi:[1,0] neg_hi:[0,1]
	v_pk_add_f32 v[22:23], v[22:23], v[46:47] op_sel:[0,1] op_sel_hi:[1,0] neg_lo:[0,1]
	v_pk_add_f32 v[46:47], v[24:25], v[36:37]
	v_pk_add_f32 v[24:25], v[24:25], v[36:37] neg_lo:[0,1] neg_hi:[0,1]
	v_pk_mul_f32 v[56:57], v[30:31], s[42:43]
	v_pk_fma_f32 v[42:43], v[42:43], s[40:41], v[50:51] op_sel:[0,0,1] op_sel_hi:[1,0,0] neg_lo:[1,0,0] neg_hi:[1,0,0]
	v_pk_mul_f32 v[36:37], v[24:25], s[42:43]
	v_pk_add_f32 v[50:51], v[28:29], v[40:41]
	v_pk_add_f32 v[28:29], v[28:29], v[40:41] neg_lo:[0,1] neg_hi:[0,1]
	v_pk_fma_f32 v[30:31], v[30:31], s[40:41], v[56:57] op_sel:[0,0,1] op_sel_hi:[1,0,0]
	v_pk_add_f32 v[56:57], v[32:33], v[48:49]
	v_pk_add_f32 v[48:49], v[32:33], v[48:49] neg_lo:[0,1] neg_hi:[0,1]
	v_pk_fma_f32 v[24:25], v[24:25], s[40:41], v[36:37] op_sel:[0,0,1] op_sel_hi:[1,0,0]
	v_pk_add_f32 v[36:37], v[26:27], v[38:39]
	v_pk_add_f32 v[38:39], v[26:27], v[38:39] neg_lo:[0,1] neg_hi:[0,1]
	v_pk_mul_f32 v[40:41], v[28:29], s[42:43]
	s_nop 0
	v_pk_fma_f32 v[28:29], v[28:29], s[40:41], v[40:41] op_sel:[0,0,1] op_sel_hi:[1,0,0] neg_lo:[1,0,0] neg_hi:[1,0,0]
	v_lshl_add_u32 v6, v6, 4, v90
	v_pk_add_f32 v[40:41], v[52:53], v[56:57]
	v_pk_add_f32 v[52:53], v[52:53], v[56:57] neg_lo:[0,1] neg_hi:[0,1]
	v_pk_add_f32 v[56:57], v[54:55], v[58:59]
	v_pk_add_f32 v[58:59], v[54:55], v[58:59] neg_lo:[0,1] neg_hi:[0,1]
	v_pk_add_f32 v[32:33], v[44:45], v[48:49] op_sel:[0,1] op_sel_hi:[1,0] neg_hi:[0,1]
	v_pk_add_f32 v[44:45], v[44:45], v[48:49] op_sel:[0,1] op_sel_hi:[1,0] neg_lo:[0,1]
	v_pk_add_f32 v[48:49], v[30:31], v[42:43]
	v_pk_add_f32 v[42:43], v[30:31], v[42:43] neg_lo:[0,1] neg_hi:[0,1]
	v_pk_add_f32 v[60:61], v[34:35], v[36:37]
	v_pk_add_f32 v[34:35], v[34:35], v[36:37] neg_lo:[0,1] neg_hi:[0,1]
	v_pk_add_f32 v[36:37], v[46:47], v[50:51]
	v_pk_add_f32 v[50:51], v[46:47], v[50:51] neg_lo:[0,1] neg_hi:[0,1]
	v_pk_add_f32 v[26:27], v[22:23], v[38:39] op_sel:[0,1] op_sel_hi:[1,0] neg_hi:[0,1]
	v_pk_add_f32 v[22:23], v[22:23], v[38:39] op_sel:[0,1] op_sel_hi:[1,0] neg_lo:[0,1]
	v_pk_add_f32 v[38:39], v[24:25], v[28:29]
	v_pk_add_f32 v[28:29], v[24:25], v[28:29] neg_lo:[0,1] neg_hi:[0,1]
	v_ashrrev_i32_e32 v6, 5, v6
	v_pk_add_f32 v[66:67], v[40:41], v[56:57]
	v_pk_add_f32 v[40:41], v[40:41], v[56:57] neg_lo:[0,1] neg_hi:[0,1]
	v_lshlrev_b32_e32 v6, 3, v6
	v_pk_add_f32 v[54:55], v[52:53], v[58:59] op_sel:[0,1] op_sel_hi:[1,0] neg_hi:[0,1]
	v_pk_add_f32 v[52:53], v[52:53], v[58:59] op_sel:[0,1] op_sel_hi:[1,0] neg_lo:[0,1]
	v_pk_add_f32 v[56:57], v[32:33], v[48:49]
	v_pk_add_f32 v[32:33], v[32:33], v[48:49] neg_lo:[0,1] neg_hi:[0,1]
	v_pk_add_f32 v[30:31], v[44:45], v[42:43] op_sel:[0,1] op_sel_hi:[1,0] neg_hi:[0,1]
	v_pk_add_f32 v[42:43], v[44:45], v[42:43] op_sel:[0,1] op_sel_hi:[1,0] neg_lo:[0,1]
	v_pk_add_f32 v[44:45], v[60:61], v[36:37]
	v_pk_add_f32 v[36:37], v[60:61], v[36:37] neg_lo:[0,1] neg_hi:[0,1]
	v_pk_add_f32 v[46:47], v[34:35], v[50:51] op_sel:[0,1] op_sel_hi:[1,0] neg_hi:[0,1]
	v_pk_add_f32 v[34:35], v[34:35], v[50:51] op_sel:[0,1] op_sel_hi:[1,0] neg_lo:[0,1]
	v_pk_add_f32 v[48:49], v[26:27], v[38:39]
	v_pk_add_f32 v[26:27], v[26:27], v[38:39] neg_lo:[0,1] neg_hi:[0,1]
	v_pk_add_f32 v[24:25], v[22:23], v[28:29] op_sel:[0,1] op_sel_hi:[1,0] neg_hi:[0,1]
	v_pk_add_f32 v[22:23], v[22:23], v[28:29] op_sel:[0,1] op_sel_hi:[1,0] neg_lo:[0,1]
	ds_write2_b64 v11, v[66:67], v[40:41] offset1:1
	ds_write2_b64 v11, v[54:55], v[52:53] offset0:2 offset1:3
	ds_write2_b64 v11, v[56:57], v[32:33] offset0:4 offset1:5
	ds_write2_b64 v11, v[30:31], v[42:43] offset0:6 offset1:7
	ds_write2_b64 v11, v[44:45], v[36:37] offset0:8 offset1:9
	ds_write2_b64 v11, v[46:47], v[34:35] offset0:10 offset1:11
	ds_write2_b64 v11, v[48:49], v[26:27] offset0:12 offset1:13
	ds_write2_b64 v11, v[24:25], v[22:23] offset0:14 offset1:15
	v_add3_u32 v6, v68, v6, s35
	ds_read2_b64 v[22:25], v6 offset1:1
	ds_read2_b64 v[26:29], v6 offset0:2 offset1:3
	ds_read2_b64 v[30:33], v6 offset0:8 offset1:9
	ds_read2_b64 v[34:37], v6 offset0:4 offset1:5
	ds_read2_b64 v[38:41], v6 offset0:6 offset1:7
	ds_read2_b64 v[42:45], v6 offset0:10 offset1:11
	ds_read2_b64 v[46:49], v6 offset0:12 offset1:13
	ds_read2_b64 v[50:53], v6 offset0:14 offset1:15
	s_waitcnt lgkmcnt(5)
	v_pk_add_f32 v[54:55], v[22:23], v[30:31]
	v_pk_add_f32 v[22:23], v[22:23], v[30:31] neg_lo:[0,1] neg_hi:[0,1]
	v_pk_add_f32 v[30:31], v[24:25], v[32:33]
	v_pk_add_f32 v[24:25], v[24:25], v[32:33] neg_lo:[0,1] neg_hi:[0,1]
	s_waitcnt lgkmcnt(1)
	v_pk_add_f32 v[56:57], v[36:37], v[48:49]
	v_pk_mul_f32 v[32:33], v[24:25], s[38:39]
	v_pk_add_f32 v[36:37], v[36:37], v[48:49] neg_lo:[0,1] neg_hi:[0,1]
	v_pk_fma_f32 v[24:25], v[24:25], s[36:37], v[32:33] op_sel:[0,0,1] op_sel_hi:[1,0,0]
	v_pk_add_f32 v[32:33], v[26:27], v[42:43]
	v_pk_add_f32 v[26:27], v[26:27], v[42:43] neg_lo:[0,1] neg_hi:[0,1]
	v_pk_mul_f32 v[48:49], v[36:37], s[44:45]
	v_pk_mul_f32 v[42:43], v[26:27], s[42:43]
	v_pk_fma_f32 v[36:37], v[36:37], s[62:63], v[48:49] op_sel:[0,0,1] op_sel_hi:[1,0,0] neg_lo:[1,0,0] neg_hi:[1,0,0]
	v_pk_fma_f32 v[26:27], v[26:27], s[40:41], v[42:43] op_sel:[0,0,1] op_sel_hi:[1,0,0]
	v_pk_add_f32 v[42:43], v[28:29], v[44:45]
	v_pk_add_f32 v[28:29], v[28:29], v[44:45] neg_lo:[0,1] neg_hi:[0,1]
	s_waitcnt lgkmcnt(0)
	v_pk_add_f32 v[48:49], v[38:39], v[50:51]
	v_pk_add_f32 v[38:39], v[38:39], v[50:51] neg_lo:[0,1] neg_hi:[0,1]
	v_pk_mul_f32 v[44:45], v[28:29], s[44:45]
	v_pk_mul_f32 v[50:51], v[38:39], s[42:43]
	v_pk_fma_f32 v[28:29], v[28:29], s[62:63], v[44:45] op_sel:[0,0,1] op_sel_hi:[1,0,0]
	v_pk_add_f32 v[44:45], v[34:35], v[46:47]
	v_pk_add_f32 v[46:47], v[34:35], v[46:47] neg_lo:[0,1] neg_hi:[0,1]
	v_pk_fma_f32 v[38:39], v[38:39], s[40:41], v[50:51] op_sel:[0,0,1] op_sel_hi:[1,0,0] neg_lo:[1,0,0] neg_hi:[1,0,0]
	v_pk_add_f32 v[50:51], v[40:41], v[52:53]
	v_pk_add_f32 v[40:41], v[40:41], v[52:53] neg_lo:[0,1] neg_hi:[0,1]
	s_nop 0
	v_pk_mul_f32 v[52:53], v[40:41], s[38:39]
	v_pk_add_f32 v[58:59], v[42:43], v[50:51]
	v_pk_add_f32 v[42:43], v[42:43], v[50:51] neg_lo:[0,1] neg_hi:[0,1]
	v_pk_fma_f32 v[40:41], v[40:41], s[36:37], v[52:53] op_sel:[0,0,1] op_sel_hi:[1,0,0] neg_lo:[1,0,0] neg_hi:[1,0,0]
	v_pk_mul_f32 v[50:51], v[42:43], s[42:43]
	v_pk_add_f32 v[34:35], v[22:23], v[46:47] op_sel:[0,1] op_sel_hi:[1,0] neg_hi:[0,1]
	v_pk_add_f32 v[22:23], v[22:23], v[46:47] op_sel:[0,1] op_sel_hi:[1,0] neg_lo:[0,1]
	v_pk_add_f32 v[46:47], v[24:25], v[36:37]
	v_pk_add_f32 v[24:25], v[24:25], v[36:37] neg_lo:[0,1] neg_hi:[0,1]
	v_pk_add_f32 v[52:53], v[54:55], v[44:45]
	v_pk_add_f32 v[44:45], v[54:55], v[44:45] neg_lo:[0,1] neg_hi:[0,1]
	v_pk_add_f32 v[54:55], v[30:31], v[56:57]
	v_pk_add_f32 v[30:31], v[30:31], v[56:57] neg_lo:[0,1] neg_hi:[0,1]
	v_pk_fma_f32 v[42:43], v[42:43], s[40:41], v[50:51] op_sel:[0,0,1] op_sel_hi:[1,0,0] neg_lo:[1,0,0] neg_hi:[1,0,0]
	v_pk_mul_f32 v[36:37], v[24:25], s[42:43]
	v_pk_add_f32 v[50:51], v[28:29], v[40:41]
	v_pk_add_f32 v[28:29], v[28:29], v[40:41] neg_lo:[0,1] neg_hi:[0,1]
	s_and_b32 s24, s24, 0xc0
	v_pk_mul_f32 v[56:57], v[30:31], s[42:43]
	v_pk_fma_f32 v[24:25], v[24:25], s[40:41], v[36:37] op_sel:[0,0,1] op_sel_hi:[1,0,0]
	v_pk_add_f32 v[36:37], v[26:27], v[38:39]
	v_pk_add_f32 v[38:39], v[26:27], v[38:39] neg_lo:[0,1] neg_hi:[0,1]
	v_pk_mul_f32 v[40:41], v[28:29], s[42:43]
	s_lshl_b64 s[62:63], s[50:51], 19
	v_pk_fma_f32 v[30:31], v[30:31], s[40:41], v[56:57] op_sel:[0,0,1] op_sel_hi:[1,0,0]
	v_pk_add_f32 v[56:57], v[32:33], v[48:49]
	v_pk_add_f32 v[48:49], v[32:33], v[48:49] neg_lo:[0,1] neg_hi:[0,1]
	s_nop 0
	v_pk_fma_f32 v[28:29], v[28:29], s[40:41], v[40:41] op_sel:[0,0,1] op_sel_hi:[1,0,0] neg_lo:[1,0,0] neg_hi:[1,0,0]
	s_add_u32 s43, s3, s62
	s_nop 0
	s_nop 0
	v_pk_add_f32 v[26:27], v[22:23], v[38:39] op_sel:[0,1] op_sel_hi:[1,0] neg_hi:[0,1]
	v_pk_add_f32 v[22:23], v[22:23], v[38:39] op_sel:[0,1] op_sel_hi:[1,0] neg_lo:[0,1]
	v_pk_add_f32 v[38:39], v[24:25], v[28:29]
	v_pk_add_f32 v[24:25], v[24:25], v[28:29] neg_lo:[0,1] neg_hi:[0,1]
	s_addc_u32 s45, s29, s63
	s_lshl_b32 s64, s24, 2
	v_pk_add_f32 v[40:41], v[52:53], v[56:57]
	v_pk_add_f32 v[52:53], v[52:53], v[56:57] neg_lo:[0,1] neg_hi:[0,1]
	v_pk_add_f32 v[56:57], v[54:55], v[58:59]
	v_pk_add_f32 v[54:55], v[54:55], v[58:59] neg_lo:[0,1] neg_hi:[0,1]
	v_pk_add_f32 v[32:33], v[44:45], v[48:49] op_sel:[0,1] op_sel_hi:[1,0] neg_hi:[0,1]
	v_pk_add_f32 v[44:45], v[44:45], v[48:49] op_sel:[0,1] op_sel_hi:[1,0] neg_lo:[0,1]
	v_pk_add_f32 v[48:49], v[30:31], v[42:43]
	v_pk_add_f32 v[42:43], v[30:31], v[42:43] neg_lo:[0,1] neg_hi:[0,1]
	v_pk_add_f32 v[60:61], v[34:35], v[36:37]
	v_pk_add_f32 v[34:35], v[34:35], v[36:37] neg_lo:[0,1] neg_hi:[0,1]
	v_pk_add_f32 v[36:37], v[46:47], v[50:51]
	v_pk_add_f32 v[46:47], v[46:47], v[50:51] neg_lo:[0,1] neg_hi:[0,1]
	v_pk_mul_f32 v[28:29], v[24:25], 1.0 op_sel:[1,0] op_sel_hi:[0,0] neg_hi:[1,0]
	s_add_u32 s64, s43, s64
	v_pk_mul_f32 v[58:59], v[54:55], 1.0 op_sel:[1,0] op_sel_hi:[0,0] neg_hi:[1,0]
	s_nop 0
	v_pk_mul_f32 v[50:51], v[46:47], 1.0 op_sel:[1,0] op_sel_hi:[0,0] neg_hi:[1,0]
	v_pk_add_f32 v[66:67], v[40:41], v[56:57]
	v_pk_add_f32 v[40:41], v[40:41], v[56:57] neg_lo:[0,1] neg_hi:[0,1]
	v_pk_add_f32 v[24:25], v[22:23], v[28:29]
	v_pk_add_f32 v[22:23], v[22:23], v[28:29] neg_lo:[0,1] neg_hi:[0,1]
	s_addc_u32 s65, s45, 0
	v_pk_add_f32 v[54:55], v[52:53], v[58:59]
	v_pk_add_f32 v[52:53], v[52:53], v[58:59] neg_lo:[0,1] neg_hi:[0,1]
	v_pk_add_f32 v[56:57], v[32:33], v[48:49]
	v_pk_add_f32 v[32:33], v[32:33], v[48:49] neg_lo:[0,1] neg_hi:[0,1]
	v_pk_add_f32 v[30:31], v[44:45], v[42:43] op_sel:[0,1] op_sel_hi:[1,0] neg_hi:[0,1]
	v_pk_add_f32 v[42:43], v[44:45], v[42:43] op_sel:[0,1] op_sel_hi:[1,0] neg_lo:[0,1]
	v_pk_add_f32 v[44:45], v[60:61], v[36:37]
	v_pk_add_f32 v[36:37], v[60:61], v[36:37] neg_lo:[0,1] neg_hi:[0,1]
	v_pk_add_f32 v[46:47], v[34:35], v[50:51]
	v_pk_add_f32 v[34:35], v[34:35], v[50:51] neg_lo:[0,1] neg_hi:[0,1]
	v_pk_add_f32 v[48:49], v[26:27], v[38:39]
	v_pk_add_f32 v[26:27], v[26:27], v[38:39] neg_lo:[0,1] neg_hi:[0,1]
	ds_write2_b64 v6, v[66:67], v[40:41] offset1:1
	ds_write2_b64 v6, v[54:55], v[52:53] offset0:2 offset1:3
	ds_write2_b64 v6, v[56:57], v[32:33] offset0:4 offset1:5
	ds_write2_b64 v6, v[30:31], v[42:43] offset0:6 offset1:7
	ds_write2_b64 v6, v[44:45], v[36:37] offset0:8 offset1:9
	ds_write2_b64 v6, v[46:47], v[34:35] offset0:10 offset1:11
	ds_write2_b64 v6, v[48:49], v[26:27] offset0:12 offset1:13
	ds_write2_b64 v6, v[24:25], v[22:23] offset0:14 offset1:15
	v_lshl_add_u64 v[22:23], s[64:65], 0, v[20:21]
	s_mov_b64 s[64:65], 0
	v_mov_b32_e32 v11, v9
	v_mov_b64_e32 v[24:25], v[62:63]
	s_waitcnt lgkmcnt(0)
	s_barrier

.LBB0_271:
	global_load_dword v40, v35, s[18:19]
	v_lshl_add_u64 v[44:45], s[18:19], 0, v[34:35]
	global_load_dword v42, v[44:45], off
	s_waitcnt vmcnt(9)
	v_cvt_f32_f16_e32 v62, v6
	v_cvt_f32_f16_sdwa v44, v6 dst_sel:DWORD dst_unused:UNUSED_PAD src0_sel:WORD_1
	v_cvt_f32_f16_e32 v45, v7
	v_cvt_f32_f16_e32 v47, v8
	v_cvt_f32_f16_sdwa v48, v8 dst_sel:DWORD dst_unused:UNUSED_PAD src0_sel:WORD_1
	v_cvt_f32_f16_e32 v49, v9
	v_cvt_f32_f16_sdwa v8, v9 dst_sel:DWORD dst_unused:UNUSED_PAD src0_sel:WORD_1
	s_waitcnt vmcnt(8)
	v_cvt_f32_f16_e32 v9, v30
	s_waitcnt vmcnt(7)
	v_cvt_f32_f16_sdwa v52, v26 dst_sel:DWORD dst_unused:UNUSED_PAD src0_sel:WORD_1
	v_cvt_f32_f16_e32 v53, v27
	v_cvt_f32_f16_sdwa v46, v7 dst_sel:DWORD dst_unused:UNUSED_PAD src0_sel:WORD_1
	v_cvt_f32_f16_sdwa v50, v30 dst_sel:DWORD dst_unused:UNUSED_PAD src0_sel:WORD_1
	v_cvt_f32_f16_e32 v51, v31
	v_cvt_f32_f16_sdwa v30, v31 dst_sel:DWORD dst_unused:UNUSED_PAD src0_sel:WORD_1
	v_cvt_f32_f16_e32 v31, v32
	v_cvt_f32_f16_sdwa v7, v33 dst_sel:DWORD dst_unused:UNUSED_PAD src0_sel:WORD_1
	v_cvt_f32_f16_sdwa v32, v32 dst_sel:DWORD dst_unused:UNUSED_PAD src0_sel:WORD_1
	v_cvt_f32_f16_e32 v33, v33
	v_cvt_f32_f16_sdwa v26, v27 dst_sel:DWORD dst_unused:UNUSED_PAD src0_sel:WORD_1
	v_cvt_f32_f16_e32 v27, v28
	v_cvt_f32_f16_sdwa v54, v28 dst_sel:DWORD dst_unused:UNUSED_PAD src0_sel:WORD_1
	v_cvt_f32_f16_e32 v55, v29
	s_waitcnt vmcnt(6)
	v_cvt_f32_f16_e32 v28, v18
	v_cvt_f32_f16_sdwa v56, v18 dst_sel:DWORD dst_unused:UNUSED_PAD src0_sel:WORD_1
	v_cvt_f32_f16_e32 v57, v19
	v_cvt_f32_f16_sdwa v18, v19 dst_sel:DWORD dst_unused:UNUSED_PAD src0_sel:WORD_1
	v_cvt_f32_f16_e32 v19, v20
	v_cvt_f32_f16_sdwa v58, v20 dst_sel:DWORD dst_unused:UNUSED_PAD src0_sel:WORD_1
	v_cvt_f32_f16_e32 v59, v21
	v_cvt_f32_f16_sdwa v29, v29 dst_sel:DWORD dst_unused:UNUSED_PAD src0_sel:WORD_1
	v_cvt_f32_f16_sdwa v21, v21 dst_sel:DWORD dst_unused:UNUSED_PAD src0_sel:WORD_1
	v_cvt_f32_f16_e32 v20, v120
	s_waitcnt vmcnt(5)
	v_cvt_f32_f16_e32 v63, v22
	v_mul_f32_e32 v62, 0x3b800000, v62
	v_pk_mul_f32 v[44:45], v[44:45], s[38:39] op_sel_hi:[1,0]
	v_pk_mul_f32 v[8:9], v[8:9], s[38:39] op_sel_hi:[1,0]
	v_pk_mul_f32 v[52:53], v[52:53], s[38:39] op_sel_hi:[1,0]
	v_pk_mul_f32 v[46:47], v[46:47], s[38:39] op_sel_hi:[1,0]
	v_pk_mul_f32 v[48:49], v[48:49], s[38:39] op_sel_hi:[1,0]
	v_pk_mul_f32 v[50:51], v[50:51], s[38:39] op_sel_hi:[1,0]
	v_pk_mul_f32 v[30:31], v[30:31], s[38:39] op_sel_hi:[1,0]
	v_mul_f32_e32 v7, 0x3b800000, v7
	v_pk_mul_f32 v[32:33], v[32:33], s[38:39] op_sel_hi:[1,0]
	v_pk_mul_f32 v[26:27], v[26:27], s[38:39] op_sel_hi:[1,0]
	v_pk_mul_f32 v[54:55], v[54:55], s[38:39] op_sel_hi:[1,0]
	v_pk_mul_f32 v[56:57], v[56:57], s[38:39] op_sel_hi:[1,0]
	v_pk_mul_f32 v[18:19], v[18:19], s[38:39] op_sel_hi:[1,0]
	v_pk_mul_f32 v[58:59], v[58:59], s[38:39] op_sel_hi:[1,0]
	ds_write2_b32 v135, v44, v45 offset0:1 offset1:2
	ds_write2_b32 v135, v46, v47 offset0:3 offset1:4
	ds_write2_b32 v135, v48, v49 offset0:5 offset1:6
	ds_write2_b32 v135, v8, v9 offset0:7 offset1:8
	ds_write2_b32 v135, v50, v51 offset0:9 offset1:10
	ds_write2_b32 v135, v30, v31 offset0:11 offset1:12
	ds_write2_b32 v135, v32, v33 offset0:13 offset1:14
	v_pk_mov_b32 v[8:9], v[52:53], v[52:53] op_sel:[1,0]
	v_pk_mul_f32 v[28:29], v[28:29], s[38:39] op_sel_hi:[1,0]
	v_pk_mul_f32 v[20:21], v[20:21], s[38:39] op_sel_hi:[1,0]
	v_mul_f32_e32 v63, 0x3b800000, v63
	v_pk_mov_b32 v[26:27], v[26:27], v[26:27] op_sel:[1,0]
	v_pk_mov_b32 v[30:31], v[54:55], v[54:55] op_sel:[1,0]
	v_pk_mov_b32 v[32:33], v[56:57], v[56:57] op_sel:[1,0]
	v_pk_mov_b32 v[18:19], v[18:19], v[18:19] op_sel:[1,0]
	v_pk_mov_b32 v[44:45], v[58:59], v[58:59] op_sel:[1,0]
	ds_write_b64 v136, v[8:9]
	ds_write_b64 v137, v[26:27]
	ds_write_b64 v138, v[30:31]
	ds_write_b64 v139, v[28:29]
	ds_write_b64 v140, v[32:33]
	ds_write_b64 v141, v[18:19]
	ds_write_b64 v142, v[44:45]
	ds_write_b64 v143, v[20:21]
	v_cvt_f32_f16_e32 v9, v25
	s_waitcnt vmcnt(4)
	v_cvt_f32_f16_sdwa v18, v14 dst_sel:DWORD dst_unused:UNUSED_PAD src0_sel:WORD_1
	v_cvt_f32_f16_e32 v19, v15
	v_cvt_f32_f16_sdwa v60, v22 dst_sel:DWORD dst_unused:UNUSED_PAD src0_sel:WORD_1
	v_cvt_f32_f16_e32 v61, v23
	s_mov_b32 s10, s69
	s_mov_b32 s71, s64
	s_mov_b32 s78, s67
	v_pk_mul_f32 v[60:61], v[60:61], s[38:39] op_sel_hi:[1,0]
	s_mov_b32 s73, s50
	s_mov_b32 s76, s63
	s_waitcnt vmcnt(1)
	v_fma_mix_f32 v6, v6, s38, v40 op_sel_hi:[1,0,0]
	s_nop 0
	v_cndmask_b32_e64 v6, v62, v6, s[6:7]
	s_waitcnt vmcnt(0)
	v_fma_mix_f32 v8, v22, s38, v42 op_sel_hi:[1,0,0]
	ds_write2_b32 v135, v6, v7 offset1:15
	v_cvt_f32_f16_sdwa v6, v23 dst_sel:DWORD dst_unused:UNUSED_PAD src0_sel:WORD_1
	v_cvt_f32_f16_e32 v7, v24
	v_cndmask_b32_e64 v20, v63, v8, s[8:9]
	v_cvt_f32_f16_sdwa v8, v24 dst_sel:DWORD dst_unused:UNUSED_PAD src0_sel:WORD_1
	ds_write2_b32 v144, v60, v61 offset0:1 offset1:2
	v_pk_mul_f32 v[6:7], v[6:7], s[38:39] op_sel_hi:[1,0]
	ds_write2_b32 v144, v6, v7 offset0:3 offset1:4
	v_pk_mul_f32 v[6:7], v[8:9], s[38:39] op_sel_hi:[1,0]
	v_cvt_f32_f16_sdwa v8, v25 dst_sel:DWORD dst_unused:UNUSED_PAD src0_sel:WORD_1
	v_cvt_f32_f16_e32 v9, v14
	ds_write2_b32 v144, v6, v7 offset0:5 offset1:6
	v_cvt_f32_f16_sdwa v14, v17 dst_sel:DWORD dst_unused:UNUSED_PAD src0_sel:WORD_1
	v_pk_mul_f32 v[6:7], v[8:9], s[38:39] op_sel_hi:[1,0]
	ds_write2_b32 v144, v6, v7 offset0:7 offset1:8
	v_pk_mul_f32 v[6:7], v[18:19], s[38:39] op_sel_hi:[1,0]
	ds_write2_b32 v144, v6, v7 offset0:9 offset1:10
	v_cvt_f32_f16_sdwa v6, v15 dst_sel:DWORD dst_unused:UNUSED_PAD src0_sel:WORD_1
	v_cvt_f32_f16_e32 v7, v16
	v_cvt_f32_f16_sdwa v8, v16 dst_sel:DWORD dst_unused:UNUSED_PAD src0_sel:WORD_1
	v_cvt_f32_f16_e32 v9, v17
	v_mul_f32_e32 v14, 0x3b800000, v14
	v_pk_mul_f32 v[6:7], v[6:7], s[38:39] op_sel_hi:[1,0]
	ds_write2_b32 v144, v6, v7 offset0:11 offset1:12
	v_pk_mul_f32 v[6:7], v[8:9], s[38:39] op_sel_hi:[1,0]
	ds_write2_b32 v144, v6, v7 offset0:13 offset1:14
	v_cvt_f32_f16_sdwa v6, v10 dst_sel:DWORD dst_unused:UNUSED_PAD src0_sel:WORD_1
	v_cvt_f32_f16_e32 v7, v11
	v_cvt_f32_f16_sdwa v8, v11 dst_sel:DWORD dst_unused:UNUSED_PAD src0_sel:WORD_1
	v_cvt_f32_f16_e32 v9, v12
	ds_write2_b32 v144, v20, v14 offset1:15
	v_pk_mul_f32 v[6:7], v[6:7], s[38:39] op_sel_hi:[1,0]
	s_nop 0
	v_pk_mov_b32 v[6:7], v[6:7], v[6:7] op_sel:[1,0]
	ds_write_b64 v145, v[6:7]
	v_pk_mul_f32 v[6:7], v[8:9], s[38:39] op_sel_hi:[1,0]
	v_cvt_f32_f16_sdwa v8, v12 dst_sel:DWORD dst_unused:UNUSED_PAD src0_sel:WORD_1
	v_cvt_f32_f16_e32 v9, v13
	v_pk_mov_b32 v[6:7], v[6:7], v[6:7] op_sel:[1,0]
	ds_write_b64 v147, v[6:7]
	v_cvt_f32_f16_sdwa v7, v13 dst_sel:DWORD dst_unused:UNUSED_PAD src0_sel:WORD_1
	v_pk_mul_f32 v[8:9], v[8:9], s[38:39] op_sel_hi:[1,0]
	v_cvt_f32_f16_e32 v6, v2
	v_pk_mov_b32 v[8:9], v[8:9], v[8:9] op_sel:[1,0]
	ds_write_b64 v148, v[8:9]
	v_cvt_f32_f16_sdwa v8, v2 dst_sel:DWORD dst_unused:UNUSED_PAD src0_sel:WORD_1
	v_cvt_f32_f16_e32 v9, v3
	v_cvt_f32_f16_sdwa v2, v3 dst_sel:DWORD dst_unused:UNUSED_PAD src0_sel:WORD_1
	v_cvt_f32_f16_e32 v3, v4
	v_pk_mul_f32 v[6:7], v[6:7], s[38:39] op_sel_hi:[1,0]
	ds_write_b64 v149, v[6:7]
	v_pk_mul_f32 v[6:7], v[8:9], s[38:39] op_sel_hi:[1,0]
	v_pk_mul_f32 v[2:3], v[2:3], s[38:39] op_sel_hi:[1,0]
	v_pk_mov_b32 v[6:7], v[6:7], v[6:7] op_sel:[1,0]
	ds_write_b64 v150, v[6:7]
	v_pk_mov_b32 v[2:3], v[2:3], v[2:3] op_sel:[1,0]
	v_cvt_f32_f16_sdwa v6, v4 dst_sel:DWORD dst_unused:UNUSED_PAD src0_sel:WORD_1
	v_cvt_f32_f16_e32 v7, v5
	ds_write_b64 v151, v[2:3]
	v_cvt_f32_f16_sdwa v3, v5 dst_sel:DWORD dst_unused:UNUSED_PAD src0_sel:WORD_1
	v_cvt_f32_f16_e32 v2, v43
	v_pk_mul_f32 v[4:5], v[6:7], s[38:39] op_sel_hi:[1,0]
	v_pk_mul_f32 v[2:3], v[2:3], s[38:39] op_sel_hi:[1,0]
	v_pk_mov_b32 v[4:5], v[4:5], v[4:5] op_sel:[1,0]
	ds_write_b64 v152, v[4:5]
	ds_write_b64 v153, v[2:3]
	v_mov_b32_e32 v2, v1
	s_waitcnt lgkmcnt(0)
	s_barrier
	s_nop 0
	v_and_b32_e32 v3, 0x1ff, v2
	v_lshlrev_b32_e32 v2, 5, v2
	v_and_or_b32 v2, v2, s3, v3
	v_cvt_f32_u32_e32 v4, v3
	v_ashrrev_i32_e32 v3, 5, v2
	v_lshlrev_b32_e32 v5, 3, v2
	v_lshlrev_b32_e32 v3, 3, v3
	v_add3_u32 v40, 0, v5, v3
	v_add_u32_e32 v155, 0x10800, v40
	ds_read_b64 v[156:157], v40
	ds_read_b64 v[158:159], v40 offset:4224
	ds_read_b64 v[160:161], v40 offset:8448
	ds_read_b64 v[162:163], v40 offset:12672
	ds_read_b64 v[164:165], v40 offset:16896
	ds_read_b64 v[166:167], v40 offset:21120
	ds_read_b64 v[168:169], v40 offset:25344
	ds_read_b64 v[170:171], v40 offset:29568
	ds_read_b64 v[172:173], v40 offset:33792
	ds_read_b64 v[174:175], v40 offset:38016
	ds_read_b64 v[176:177], v40 offset:42240
	ds_read_b64 v[178:179], v40 offset:46464
	ds_read_b64 v[180:181], v40 offset:50688
	ds_read_b64 v[182:183], v40 offset:54912
	ds_read_b64 v[184:185], v40 offset:59136
	ds_read_b64 v[186:187], v40 offset:63360
	v_add_u32_e32 v201, 0x11880, v40
	v_add_u32_e32 v224, 0x12900, v40
	v_add_u32_e32 v225, 0x13980, v40
	ds_read_b64 v[188:189], v155
	ds_read_b64 v[190:191], v201
	ds_read_b64 v[192:193], v224
	ds_read_b64 v[194:195], v225
	v_add_u32_e32 v226, 0x14a00, v40
	s_waitcnt lgkmcnt(3)
	v_pk_add_f32 v[222:223], v[156:157], v[188:189]
	v_pk_add_f32 v[156:157], v[156:157], v[188:189] neg_lo:[0,1] neg_hi:[0,1]
	s_waitcnt lgkmcnt(2)
	v_pk_add_f32 v[188:189], v[158:159], v[190:191]
	v_pk_add_f32 v[158:159], v[158:159], v[190:191] neg_lo:[0,1] neg_hi:[0,1]
	v_add_u32_e32 v227, 0x15a80, v40
	v_pk_mul_f32 v[190:191], v[158:159], s[46:47]
	v_add_u32_e32 v228, 0x16b00, v40
	v_pk_fma_f32 v[158:159], v[158:159], s[42:43], v[190:191] op_sel:[0,0,1] op_sel_hi:[1,0,0]
	s_waitcnt lgkmcnt(1)
	v_pk_add_f32 v[190:191], v[160:161], v[192:193]
	v_pk_add_f32 v[160:161], v[160:161], v[192:193] neg_lo:[0,1] neg_hi:[0,1]
	v_add_u32_e32 v229, 0x17b80, v40
	v_pk_mul_f32 v[192:193], v[160:161], s[62:63]
	ds_read_b64 v[196:197], v226
	ds_read_b64 v[198:199], v227
	ds_read_b64 v[202:203], v228
	ds_read_b64 v[204:205], v229
	v_pk_fma_f32 v[160:161], v[160:161], s[50:51], v[192:193] op_sel:[0,0,1] op_sel_hi:[1,0,0]
	s_waitcnt lgkmcnt(4)
	v_pk_add_f32 v[192:193], v[162:163], v[194:195]
	v_pk_add_f32 v[162:163], v[162:163], v[194:195] neg_lo:[0,1] neg_hi:[0,1]
	v_add_u32_e32 v230, 0x18c00, v40
	v_pk_mul_f32 v[194:195], v[162:163], s[66:67]
	v_add_u32_e32 v231, 0x19c80, v40
	v_pk_fma_f32 v[162:163], v[162:163], s[64:65], v[194:195] op_sel:[0,0,1] op_sel_hi:[1,0,0]
	s_waitcnt lgkmcnt(3)
	v_pk_add_f32 v[194:195], v[164:165], v[196:197]
	v_pk_add_f32 v[164:165], v[164:165], v[196:197] neg_lo:[0,1] neg_hi:[0,1]
	v_add_u32_e32 v232, 0x1ad00, v40
	v_pk_mul_f32 v[196:197], v[164:165], s[68:69]
	v_add_u32_e32 v233, 0x1bd80, v40
	v_pk_fma_f32 v[164:165], v[164:165], s[10:11], v[196:197] op_sel:[0,0,1] op_sel_hi:[1,0,0]
	s_waitcnt lgkmcnt(2)
	v_pk_add_f32 v[196:197], v[166:167], v[198:199]
	v_pk_add_f32 v[166:167], v[166:167], v[198:199] neg_lo:[0,1] neg_hi:[0,1]
	ds_read_b64 v[206:207], v230
	ds_read_b64 v[208:209], v231
	ds_read_b64 v[210:211], v232
	ds_read_b64 v[212:213], v233
	v_pk_mul_f32 v[198:199], v[166:167], s[70:71]
	v_add_u32_e32 v234, 0x1ce00, v40
	v_pk_fma_f32 v[166:167], v[166:167], s[78:79], v[198:199] op_sel:[0,0,1] op_sel_hi:[1,0,0]
	s_waitcnt lgkmcnt(5)
	v_pk_add_f32 v[198:199], v[168:169], v[202:203]
	v_pk_add_f32 v[168:169], v[168:169], v[202:203] neg_lo:[0,1] neg_hi:[0,1]
	v_add_u32_e32 v235, 0x1de80, v40
	v_pk_mul_f32 v[202:203], v[168:169], s[72:73]
	v_add_u32_e32 v236, 0x1ef00, v40
	v_pk_fma_f32 v[168:169], v[168:169], s[76:77], v[202:203] op_sel:[0,0,1] op_sel_hi:[1,0,0]
	s_waitcnt lgkmcnt(4)
	v_pk_add_f32 v[202:203], v[170:171], v[204:205]
	v_pk_add_f32 v[170:171], v[170:171], v[204:205] neg_lo:[0,1] neg_hi:[0,1]
	v_add_u32_e32 v237, 0x1ff80, v40
	v_pk_mul_f32 v[204:205], v[170:171], s[40:41]
	ds_read_b64 v[214:215], v234
	ds_read_b64 v[216:217], v235
	ds_read_b64 v[218:219], v236
	ds_read_b64 v[220:221], v237
	v_pk_fma_f32 v[170:171], v[170:171], s[44:45], v[204:205] op_sel:[0,0,1] op_sel_hi:[1,0,0]
	s_waitcnt lgkmcnt(7)
	v_pk_add_f32 v[204:205], v[172:173], v[206:207]
	v_pk_add_f32 v[206:207], v[172:173], v[206:207] neg_lo:[0,1] neg_hi:[0,1]
	v_mul_f32_e32 v4, 0x38800000, v4
	s_waitcnt lgkmcnt(6)
	v_pk_add_f32 v[172:173], v[174:175], v[208:209]
	v_pk_add_f32 v[174:175], v[174:175], v[208:209] neg_lo:[0,1] neg_hi:[0,1]
	v_sin_f32_e32 v2, v4
	v_pk_mul_f32 v[208:209], v[174:175], s[40:41]
	v_cos_f32_e32 v4, v4
	v_pk_fma_f32 v[174:175], v[174:175], s[44:45], v[208:209] op_sel:[0,0,1] op_sel_hi:[1,0,0] neg_lo:[1,0,0] neg_hi:[1,0,0]
	s_waitcnt lgkmcnt(5)
	v_pk_add_f32 v[208:209], v[176:177], v[210:211]
	v_pk_add_f32 v[176:177], v[176:177], v[210:211] neg_lo:[0,1] neg_hi:[0,1]
	v_xor_b32_e32 v5, 0x80000000, v2
	v_pk_mul_f32 v[210:211], v[176:177], s[72:73]
	v_mov_b32_e32 v3, v5
	v_pk_fma_f32 v[176:177], v[176:177], s[76:77], v[210:211] op_sel:[0,0,1] op_sel_hi:[1,0,0] neg_lo:[1,0,0] neg_hi:[1,0,0]
	s_waitcnt lgkmcnt(4)
	v_pk_add_f32 v[210:211], v[178:179], v[212:213]
	v_pk_add_f32 v[178:179], v[178:179], v[212:213] neg_lo:[0,1] neg_hi:[0,1]
	v_pk_mul_f32 v[6:7], v[4:5], v[2:3] op_sel:[1,0] op_sel_hi:[0,1]
	v_pk_mul_f32 v[212:213], v[178:179], s[70:71]
	v_pk_fma_f32 v[6:7], v[4:5], v[4:5], v[6:7] op_sel_hi:[1,0,1]
	v_pk_fma_f32 v[178:179], v[178:179], s[78:79], v[212:213] op_sel:[0,0,1] op_sel_hi:[1,0,0] neg_lo:[1,0,0] neg_hi:[1,0,0]
	s_waitcnt lgkmcnt(3)
	v_pk_add_f32 v[212:213], v[180:181], v[214:215]
	v_pk_add_f32 v[180:181], v[180:181], v[214:215] neg_lo:[0,1] neg_hi:[0,1]
	v_pk_mul_f32 v[12:13], v[6:7], 1.0 op_sel:[1,0] op_sel_hi:[1,0] neg_lo:[1,0]
	v_pk_mul_f32 v[214:215], v[180:181], s[68:69]
	s_nop 0
	v_pk_fma_f32 v[180:181], v[180:181], s[10:11], v[214:215] op_sel:[0,0,1] op_sel_hi:[1,0,0] neg_lo:[1,0,0] neg_hi:[1,0,0]
	s_waitcnt lgkmcnt(2)
	v_pk_add_f32 v[214:215], v[182:183], v[216:217]
	v_pk_add_f32 v[182:183], v[182:183], v[216:217] neg_lo:[0,1] neg_hi:[0,1]
	v_pk_mul_f32 v[10:11], v[6:7], v[12:13] op_sel:[1,0] op_sel_hi:[0,1]
	v_pk_mul_f32 v[216:217], v[182:183], s[66:67]
	v_pk_fma_f32 v[10:11], v[6:7], v[6:7], v[10:11] op_sel_hi:[1,0,1]
	v_pk_fma_f32 v[182:183], v[182:183], s[64:65], v[216:217] op_sel:[0,0,1] op_sel_hi:[1,0,0] neg_lo:[1,0,0] neg_hi:[1,0,0]
	s_waitcnt lgkmcnt(1)
	v_pk_add_f32 v[216:217], v[184:185], v[218:219]
	v_pk_add_f32 v[184:185], v[184:185], v[218:219] neg_lo:[0,1] neg_hi:[0,1]
	v_pk_mul_f32 v[14:15], v[10:11], 1.0 op_sel:[1,0] op_sel_hi:[1,0] neg_lo:[1,0]
	v_pk_mul_f32 v[218:219], v[184:185], s[62:63]
	s_nop 0
	v_pk_fma_f32 v[184:185], v[184:185], s[50:51], v[218:219] op_sel:[0,0,1] op_sel_hi:[1,0,0] neg_lo:[1,0,0] neg_hi:[1,0,0]
	s_waitcnt lgkmcnt(0)
	v_pk_add_f32 v[218:219], v[186:187], v[220:221]
	v_pk_add_f32 v[186:187], v[186:187], v[220:221] neg_lo:[0,1] neg_hi:[0,1]
	v_pk_mul_f32 v[26:27], v[10:11], v[14:15] op_sel:[1,0] op_sel_hi:[0,1]
	v_pk_mul_f32 v[220:221], v[186:187], s[46:47]
	v_pk_fma_f32 v[26:27], v[10:11], v[10:11], v[26:27] op_sel_hi:[1,0,1]
	v_pk_fma_f32 v[186:187], v[186:187], s[42:43], v[220:221] op_sel:[0,0,1] op_sel_hi:[1,0,0] neg_lo:[1,0,0] neg_hi:[1,0,0]
	v_pk_add_f32 v[220:221], v[222:223], v[204:205]
	v_pk_add_f32 v[204:205], v[222:223], v[204:205] neg_lo:[0,1] neg_hi:[0,1]
	v_pk_add_f32 v[222:223], v[188:189], v[172:173]
	v_pk_add_f32 v[172:173], v[188:189], v[172:173] neg_lo:[0,1] neg_hi:[0,1]
	v_pk_mul_f32 v[50:51], v[14:15], v[26:27] op_sel:[0,1] op_sel_hi:[1,0]
	v_pk_mul_f32 v[188:189], v[172:173], s[62:63]
	v_pk_fma_f32 v[50:51], v[10:11], v[26:27], v[50:51] op_sel_hi:[0,1,1]
	v_pk_fma_f32 v[172:173], v[172:173], s[50:51], v[188:189] op_sel:[0,0,1] op_sel_hi:[1,0,0]
	v_pk_add_f32 v[188:189], v[190:191], v[208:209]
	v_pk_add_f32 v[190:191], v[190:191], v[208:209] neg_lo:[0,1] neg_hi:[0,1]
	v_pk_mul_f32 v[66:67], v[14:15], v[50:51] op_sel:[0,1] op_sel_hi:[1,0]
	v_pk_mul_f32 v[208:209], v[190:191], s[68:69]
	v_pk_fma_f32 v[66:67], v[10:11], v[50:51], v[66:67] op_sel_hi:[0,1,1]
	v_pk_fma_f32 v[190:191], v[190:191], s[10:11], v[208:209] op_sel:[0,0,1] op_sel_hi:[1,0,0]
	v_pk_add_f32 v[208:209], v[192:193], v[210:211]
	v_pk_add_f32 v[192:193], v[192:193], v[210:211] neg_lo:[0,1] neg_hi:[0,1]
	v_pk_mul_f32 v[82:83], v[14:15], v[66:67] op_sel:[0,1] op_sel_hi:[1,0]
	v_pk_mul_f32 v[210:211], v[192:193], s[72:73]
	v_pk_fma_f32 v[82:83], v[10:11], v[66:67], v[82:83] op_sel_hi:[0,1,1]
	v_pk_fma_f32 v[192:193], v[192:193], s[76:77], v[210:211] op_sel:[0,0,1] op_sel_hi:[1,0,0]
	v_pk_add_f32 v[210:211], v[194:195], v[212:213]
	v_pk_add_f32 v[212:213], v[194:195], v[212:213] neg_lo:[0,1] neg_hi:[0,1]
	v_pk_mul_f32 v[98:99], v[14:15], v[82:83] op_sel:[0,1] op_sel_hi:[1,0]
	v_pk_add_f32 v[194:195], v[196:197], v[214:215]
	v_pk_add_f32 v[196:197], v[196:197], v[214:215] neg_lo:[0,1] neg_hi:[0,1]
	v_pk_fma_f32 v[98:99], v[10:11], v[82:83], v[98:99] op_sel_hi:[0,1,1]
	v_pk_mul_f32 v[214:215], v[196:197], s[72:73]
	v_pk_mul_f32 v[114:115], v[14:15], v[98:99] op_sel:[0,1] op_sel_hi:[1,0]
	v_pk_fma_f32 v[196:197], v[196:197], s[76:77], v[214:215] op_sel:[0,0,1] op_sel_hi:[1,0,0] neg_lo:[1,0,0] neg_hi:[1,0,0]
	v_pk_add_f32 v[214:215], v[198:199], v[216:217]
	v_pk_add_f32 v[198:199], v[198:199], v[216:217] neg_lo:[0,1] neg_hi:[0,1]
	v_pk_mul_f32 v[8:9], v[2:3], v[6:7] op_sel:[0,1] op_sel_hi:[1,0]
	v_pk_mul_f32 v[216:217], v[198:199], s[68:69]
	v_pk_fma_f32 v[114:115], v[10:11], v[98:99], v[114:115] op_sel_hi:[0,1,1]
	v_pk_fma_f32 v[198:199], v[198:199], s[10:11], v[216:217] op_sel:[0,0,1] op_sel_hi:[1,0,0] neg_lo:[1,0,0] neg_hi:[1,0,0]
	v_pk_add_f32 v[216:217], v[202:203], v[218:219]
	v_pk_add_f32 v[202:203], v[202:203], v[218:219] neg_lo:[0,1] neg_hi:[0,1]
	v_pk_fma_f32 v[8:9], v[4:5], v[6:7], v[8:9] op_sel_hi:[0,1,1]
	v_pk_mul_f32 v[218:219], v[202:203], s[62:63]
	v_pk_mul_f32 v[16:17], v[2:3], v[10:11] op_sel:[0,1] op_sel_hi:[1,0]
	v_pk_fma_f32 v[202:203], v[202:203], s[50:51], v[218:219] op_sel:[0,0,1] op_sel_hi:[1,0,0] neg_lo:[1,0,0] neg_hi:[1,0,0]
	v_pk_add_f32 v[218:219], v[156:157], v[206:207] op_sel:[0,1] op_sel_hi:[1,0] neg_hi:[0,1]
	v_pk_add_f32 v[156:157], v[156:157], v[206:207] op_sel:[0,1] op_sel_hi:[1,0] neg_lo:[0,1]
	v_pk_add_f32 v[206:207], v[158:159], v[174:175]
	v_pk_add_f32 v[158:159], v[158:159], v[174:175] neg_lo:[0,1] neg_hi:[0,1]
	v_pk_mul_f32 v[30:31], v[2:3], v[26:27] op_sel:[0,1] op_sel_hi:[1,0]
	v_pk_mul_f32 v[174:175], v[158:159], s[62:63]
	v_pk_mul_f32 v[54:55], v[2:3], v[50:51] op_sel:[0,1] op_sel_hi:[1,0]
	v_pk_fma_f32 v[158:159], v[158:159], s[50:51], v[174:175] op_sel:[0,0,1] op_sel_hi:[1,0,0]
	v_pk_add_f32 v[174:175], v[160:161], v[176:177]
	v_pk_add_f32 v[160:161], v[160:161], v[176:177] neg_lo:[0,1] neg_hi:[0,1]
	v_pk_mul_f32 v[70:71], v[2:3], v[66:67] op_sel:[0,1] op_sel_hi:[1,0]
	v_pk_mul_f32 v[176:177], v[160:161], s[68:69]
	v_pk_mul_f32 v[86:87], v[2:3], v[82:83] op_sel:[0,1] op_sel_hi:[1,0]
	v_pk_fma_f32 v[160:161], v[160:161], s[10:11], v[176:177] op_sel:[0,0,1] op_sel_hi:[1,0,0]
	v_pk_add_f32 v[176:177], v[162:163], v[178:179]
	v_pk_add_f32 v[162:163], v[162:163], v[178:179] neg_lo:[0,1] neg_hi:[0,1]
	v_pk_mul_f32 v[102:103], v[2:3], v[98:99] op_sel:[0,1] op_sel_hi:[1,0]
	v_pk_mul_f32 v[178:179], v[162:163], s[72:73]
	v_pk_mul_f32 v[118:119], v[2:3], v[114:115] op_sel:[0,1] op_sel_hi:[1,0]
	v_pk_fma_f32 v[162:163], v[162:163], s[76:77], v[178:179] op_sel:[0,0,1] op_sel_hi:[1,0,0]
	v_pk_add_f32 v[178:179], v[164:165], v[180:181]
	v_pk_add_f32 v[180:181], v[164:165], v[180:181] neg_lo:[0,1] neg_hi:[0,1]
	v_pk_mul_f32 v[20:21], v[8:9], 1.0 op_sel:[1,0] op_sel_hi:[1,0] neg_lo:[1,0]
	v_pk_add_f32 v[164:165], v[166:167], v[182:183]
	v_pk_add_f32 v[166:167], v[166:167], v[182:183] neg_lo:[0,1] neg_hi:[0,1]
	s_nop 0
	v_pk_mul_f32 v[182:183], v[166:167], s[72:73]
	v_pk_fma_f32 v[16:17], v[4:5], v[10:11], v[16:17] op_sel_hi:[0,1,1]
	v_pk_fma_f32 v[166:167], v[166:167], s[76:77], v[182:183] op_sel:[0,0,1] op_sel_hi:[1,0,0] neg_lo:[1,0,0] neg_hi:[1,0,0]
	v_pk_add_f32 v[182:183], v[168:169], v[184:185]
	v_pk_add_f32 v[168:169], v[168:169], v[184:185] neg_lo:[0,1] neg_hi:[0,1]
	v_pk_mul_f32 v[18:19], v[12:13], v[10:11] op_sel:[0,1] op_sel_hi:[1,0]
	v_pk_mul_f32 v[184:185], v[168:169], s[68:69]
	v_pk_fma_f32 v[30:31], v[4:5], v[26:27], v[30:31] op_sel_hi:[0,1,1]
	v_pk_fma_f32 v[168:169], v[168:169], s[10:11], v[184:185] op_sel:[0,0,1] op_sel_hi:[1,0,0] neg_lo:[1,0,0] neg_hi:[1,0,0]
	v_pk_add_f32 v[184:185], v[170:171], v[186:187]
	v_pk_add_f32 v[170:171], v[170:171], v[186:187] neg_lo:[0,1] neg_hi:[0,1]
	v_pk_mul_f32 v[42:43], v[12:13], v[26:27] op_sel:[0,1] op_sel_hi:[1,0]
	v_pk_mul_f32 v[186:187], v[170:171], s[62:63]
	v_pk_fma_f32 v[54:55], v[4:5], v[50:51], v[54:55] op_sel_hi:[0,1,1]
	v_pk_fma_f32 v[170:171], v[170:171], s[50:51], v[186:187] op_sel:[0,0,1] op_sel_hi:[1,0,0] neg_lo:[1,0,0] neg_hi:[1,0,0]
	v_pk_add_f32 v[186:187], v[220:221], v[210:211]
	v_pk_add_f32 v[210:211], v[220:221], v[210:211] neg_lo:[0,1] neg_hi:[0,1]
	v_pk_add_f32 v[220:221], v[222:223], v[194:195]
	v_pk_add_f32 v[194:195], v[222:223], v[194:195] neg_lo:[0,1] neg_hi:[0,1]
	v_pk_mul_f32 v[58:59], v[12:13], v[50:51] op_sel:[0,1] op_sel_hi:[1,0]
	v_pk_mul_f32 v[222:223], v[194:195], s[68:69]
	v_pk_fma_f32 v[70:71], v[4:5], v[66:67], v[70:71] op_sel_hi:[0,1,1]
	v_pk_fma_f32 v[194:195], v[194:195], s[10:11], v[222:223] op_sel:[0,0,1] op_sel_hi:[1,0,0]
	v_pk_add_f32 v[222:223], v[188:189], v[214:215]
	v_pk_add_f32 v[214:215], v[188:189], v[214:215] neg_lo:[0,1] neg_hi:[0,1]
	v_pk_mul_f32 v[74:75], v[12:13], v[66:67] op_sel:[0,1] op_sel_hi:[1,0]
	v_pk_add_f32 v[188:189], v[208:209], v[216:217]
	v_pk_add_f32 v[208:209], v[208:209], v[216:217] neg_lo:[0,1] neg_hi:[0,1]
	v_pk_fma_f32 v[86:87], v[4:5], v[82:83], v[86:87] op_sel_hi:[0,1,1]
	v_pk_mul_f32 v[216:217], v[208:209], s[68:69]
	v_pk_mul_f32 v[90:91], v[12:13], v[82:83] op_sel:[0,1] op_sel_hi:[1,0]
	v_pk_fma_f32 v[208:209], v[208:209], s[10:11], v[216:217] op_sel:[0,0,1] op_sel_hi:[1,0,0] neg_lo:[1,0,0] neg_hi:[1,0,0]
	v_pk_add_f32 v[216:217], v[204:205], v[212:213] op_sel:[0,1] op_sel_hi:[1,0] neg_hi:[0,1]
	v_pk_add_f32 v[204:205], v[204:205], v[212:213] op_sel:[0,1] op_sel_hi:[1,0] neg_lo:[0,1]
	v_pk_add_f32 v[212:213], v[172:173], v[196:197]
	v_pk_add_f32 v[172:173], v[172:173], v[196:197] neg_lo:[0,1] neg_hi:[0,1]
	v_pk_fma_f32 v[102:103], v[4:5], v[98:99], v[102:103] op_sel_hi:[0,1,1]
	v_pk_mul_f32 v[196:197], v[172:173], s[68:69]
	v_pk_mul_f32 v[106:107], v[12:13], v[98:99] op_sel:[0,1] op_sel_hi:[1,0]
	v_pk_fma_f32 v[172:173], v[172:173], s[10:11], v[196:197] op_sel:[0,0,1] op_sel_hi:[1,0,0]
	v_pk_add_f32 v[196:197], v[190:191], v[198:199]
	v_pk_add_f32 v[198:199], v[190:191], v[198:199] neg_lo:[0,1] neg_hi:[0,1]
	v_pk_fma_f32 v[118:119], v[4:5], v[114:115], v[118:119] op_sel_hi:[0,1,1]
	v_pk_add_f32 v[190:191], v[192:193], v[202:203]
	v_pk_add_f32 v[192:193], v[192:193], v[202:203] neg_lo:[0,1] neg_hi:[0,1]
	v_pk_mul_f32 v[122:123], v[12:13], v[114:115] op_sel:[0,1] op_sel_hi:[1,0]
	v_pk_mul_f32 v[202:203], v[192:193], s[68:69]
	v_pk_fma_f32 v[18:19], v[6:7], v[10:11], v[18:19] op_sel_hi:[0,1,1]
	v_pk_fma_f32 v[192:193], v[192:193], s[10:11], v[202:203] op_sel:[0,0,1] op_sel_hi:[1,0,0] neg_lo:[1,0,0] neg_hi:[1,0,0]
	v_pk_add_f32 v[202:203], v[218:219], v[178:179]
	v_pk_add_f32 v[178:179], v[218:219], v[178:179] neg_lo:[0,1] neg_hi:[0,1]
	v_pk_add_f32 v[218:219], v[206:207], v[164:165]
	v_pk_add_f32 v[164:165], v[206:207], v[164:165] neg_lo:[0,1] neg_hi:[0,1]
	v_pk_mul_f32 v[22:23], v[10:11], v[20:21] op_sel:[1,0] op_sel_hi:[0,1]
	v_pk_mul_f32 v[206:207], v[164:165], s[68:69]
	v_pk_fma_f32 v[42:43], v[6:7], v[26:27], v[42:43] op_sel_hi:[0,1,1]
	v_pk_fma_f32 v[164:165], v[164:165], s[10:11], v[206:207] op_sel:[0,0,1] op_sel_hi:[1,0,0]
	v_pk_add_f32 v[206:207], v[174:175], v[182:183]
	v_pk_add_f32 v[182:183], v[174:175], v[182:183] neg_lo:[0,1] neg_hi:[0,1]
	v_pk_mul_f32 v[46:47], v[20:21], v[26:27] op_sel:[0,1] op_sel_hi:[1,0]
	v_pk_add_f32 v[174:175], v[176:177], v[184:185]
	v_pk_add_f32 v[176:177], v[176:177], v[184:185] neg_lo:[0,1] neg_hi:[0,1]
	v_pk_fma_f32 v[58:59], v[6:7], v[50:51], v[58:59] op_sel_hi:[0,1,1]
	v_pk_mul_f32 v[184:185], v[176:177], s[68:69]
	v_pk_mul_f32 v[62:63], v[20:21], v[50:51] op_sel:[0,1] op_sel_hi:[1,0]
	v_pk_fma_f32 v[176:177], v[176:177], s[10:11], v[184:185] op_sel:[0,0,1] op_sel_hi:[1,0,0] neg_lo:[1,0,0] neg_hi:[1,0,0]
	v_pk_add_f32 v[184:185], v[156:157], v[180:181] op_sel:[0,1] op_sel_hi:[1,0] neg_hi:[0,1]
	v_pk_add_f32 v[156:157], v[156:157], v[180:181] op_sel:[0,1] op_sel_hi:[1,0] neg_lo:[0,1]
	v_pk_add_f32 v[180:181], v[158:159], v[166:167]
	v_pk_add_f32 v[158:159], v[158:159], v[166:167] neg_lo:[0,1] neg_hi:[0,1]
	v_pk_fma_f32 v[74:75], v[6:7], v[66:67], v[74:75] op_sel_hi:[0,1,1]
	v_pk_mul_f32 v[166:167], v[158:159], s[68:69]
	v_pk_mul_f32 v[78:79], v[20:21], v[66:67] op_sel:[0,1] op_sel_hi:[1,0]
	v_pk_fma_f32 v[158:159], v[158:159], s[10:11], v[166:167] op_sel:[0,0,1] op_sel_hi:[1,0,0]
	v_pk_add_f32 v[166:167], v[160:161], v[168:169]
	v_pk_add_f32 v[168:169], v[160:161], v[168:169] neg_lo:[0,1] neg_hi:[0,1]
	v_pk_fma_f32 v[90:91], v[6:7], v[82:83], v[90:91] op_sel_hi:[0,1,1]
	v_pk_add_f32 v[160:161], v[162:163], v[170:171]
	v_pk_add_f32 v[162:163], v[162:163], v[170:171] neg_lo:[0,1] neg_hi:[0,1]
	v_pk_mul_f32 v[94:95], v[20:21], v[82:83] op_sel:[0,1] op_sel_hi:[1,0]
	v_pk_mul_f32 v[170:171], v[162:163], s[68:69]
	v_pk_fma_f32 v[106:107], v[6:7], v[98:99], v[106:107] op_sel_hi:[0,1,1]
	v_pk_fma_f32 v[162:163], v[162:163], s[10:11], v[170:171] op_sel:[0,0,1] op_sel_hi:[1,0,0] neg_lo:[1,0,0] neg_hi:[1,0,0]
	v_pk_add_f32 v[170:171], v[186:187], v[222:223]
	v_pk_add_f32 v[186:187], v[186:187], v[222:223] neg_lo:[0,1] neg_hi:[0,1]
	v_pk_add_f32 v[222:223], v[220:221], v[188:189]
	v_pk_add_f32 v[220:221], v[220:221], v[188:189] neg_lo:[0,1] neg_hi:[0,1]
	v_pk_mul_f32 v[110:111], v[20:21], v[98:99] op_sel:[0,1] op_sel_hi:[1,0]
	v_pk_add_f32 v[188:189], v[210:211], v[214:215] op_sel:[0,1] op_sel_hi:[1,0] neg_hi:[0,1]
	v_pk_add_f32 v[210:211], v[210:211], v[214:215] op_sel:[0,1] op_sel_hi:[1,0] neg_lo:[0,1]
	v_pk_add_f32 v[214:215], v[194:195], v[208:209]
	v_pk_add_f32 v[208:209], v[194:195], v[208:209] neg_lo:[0,1] neg_hi:[0,1]
	v_pk_fma_f32 v[122:123], v[6:7], v[114:115], v[122:123] op_sel_hi:[0,1,1]
	v_pk_add_f32 v[194:195], v[216:217], v[196:197]
	v_pk_add_f32 v[196:197], v[216:217], v[196:197] neg_lo:[0,1] neg_hi:[0,1]
	v_pk_add_f32 v[216:217], v[212:213], v[190:191]
	v_pk_add_f32 v[212:213], v[212:213], v[190:191] neg_lo:[0,1] neg_hi:[0,1]
	v_pk_mul_f32 v[126:127], v[20:21], v[114:115] op_sel:[0,1] op_sel_hi:[1,0]
	v_pk_add_f32 v[190:191], v[204:205], v[198:199] op_sel:[0,1] op_sel_hi:[1,0] neg_hi:[0,1]
	v_pk_add_f32 v[198:199], v[204:205], v[198:199] op_sel:[0,1] op_sel_hi:[1,0] neg_lo:[0,1]
	v_pk_add_f32 v[204:205], v[172:173], v[192:193]
	v_pk_add_f32 v[192:193], v[172:173], v[192:193] neg_lo:[0,1] neg_hi:[0,1]
	v_xor_b32_e32 v24, 0x80000000, v17
	v_pk_add_f32 v[172:173], v[202:203], v[206:207]
	v_pk_add_f32 v[202:203], v[202:203], v[206:207] neg_lo:[0,1] neg_hi:[0,1]
	v_pk_add_f32 v[206:207], v[218:219], v[174:175]
	v_pk_add_f32 v[218:219], v[218:219], v[174:175] neg_lo:[0,1] neg_hi:[0,1]
	v_xor_b32_e32 v28, 0x80000000, v19
	v_pk_add_f32 v[174:175], v[178:179], v[182:183] op_sel:[0,1] op_sel_hi:[1,0] neg_hi:[0,1]
	v_pk_add_f32 v[178:179], v[178:179], v[182:183] op_sel:[0,1] op_sel_hi:[1,0] neg_lo:[0,1]
	v_pk_add_f32 v[182:183], v[164:165], v[176:177]
	v_pk_add_f32 v[176:177], v[164:165], v[176:177] neg_lo:[0,1] neg_hi:[0,1]
	v_pk_fma_f32 v[22:23], v[10:11], v[8:9], v[22:23] op_sel_hi:[1,0,1]
	v_pk_add_f32 v[164:165], v[184:185], v[166:167]
	v_pk_add_f32 v[166:167], v[184:185], v[166:167] neg_lo:[0,1] neg_hi:[0,1]
	v_pk_add_f32 v[184:185], v[180:181], v[160:161]
	v_pk_add_f32 v[180:181], v[180:181], v[160:161] neg_lo:[0,1] neg_hi:[0,1]
	v_pk_fma_f32 v[46:47], v[8:9], v[26:27], v[46:47] op_sel_hi:[0,1,1]
	v_pk_add_f32 v[160:161], v[156:157], v[168:169] op_sel:[0,1] op_sel_hi:[1,0] neg_hi:[0,1]
	v_pk_add_f32 v[156:157], v[156:157], v[168:169] op_sel:[0,1] op_sel_hi:[1,0] neg_lo:[0,1]
	v_pk_add_f32 v[168:169], v[158:159], v[162:163]
	v_pk_add_f32 v[162:163], v[158:159], v[162:163] neg_lo:[0,1] neg_hi:[0,1]
	v_pk_fma_f32 v[62:63], v[8:9], v[50:51], v[62:63] op_sel_hi:[0,1,1]
	v_pk_add_f32 v[158:159], v[170:171], v[222:223]
	v_pk_add_f32 v[170:171], v[170:171], v[222:223] neg_lo:[0,1] neg_hi:[0,1]
	v_pk_add_f32 v[222:223], v[186:187], v[220:221] op_sel:[0,1] op_sel_hi:[1,0] neg_hi:[0,1]
	v_pk_add_f32 v[186:187], v[186:187], v[220:221] op_sel:[0,1] op_sel_hi:[1,0] neg_lo:[0,1]
	v_pk_add_f32 v[220:221], v[188:189], v[214:215]
	v_pk_add_f32 v[188:189], v[188:189], v[214:215] neg_lo:[0,1] neg_hi:[0,1]
	v_pk_add_f32 v[214:215], v[210:211], v[208:209] op_sel:[0,1] op_sel_hi:[1,0] neg_hi:[0,1]
	v_pk_add_f32 v[208:209], v[210:211], v[208:209] op_sel:[0,1] op_sel_hi:[1,0] neg_lo:[0,1]
	v_pk_add_f32 v[210:211], v[194:195], v[216:217]
	v_pk_add_f32 v[194:195], v[194:195], v[216:217] neg_lo:[0,1] neg_hi:[0,1]
	v_pk_add_f32 v[216:217], v[196:197], v[212:213] op_sel:[0,1] op_sel_hi:[1,0] neg_hi:[0,1]
	v_pk_add_f32 v[196:197], v[196:197], v[212:213] op_sel:[0,1] op_sel_hi:[1,0] neg_lo:[0,1]
	v_pk_add_f32 v[212:213], v[190:191], v[204:205]
	v_pk_add_f32 v[190:191], v[190:191], v[204:205] neg_lo:[0,1] neg_hi:[0,1]
	v_pk_add_f32 v[204:205], v[198:199], v[192:193] op_sel:[0,1] op_sel_hi:[1,0] neg_hi:[0,1]
	v_pk_add_f32 v[192:193], v[198:199], v[192:193] op_sel:[0,1] op_sel_hi:[1,0] neg_lo:[0,1]
	v_pk_add_f32 v[198:199], v[172:173], v[206:207]
	v_pk_add_f32 v[172:173], v[172:173], v[206:207] neg_lo:[0,1] neg_hi:[0,1]
	v_pk_mul_f32 v[2:3], v[2:3], v[198:199] op_sel:[0,1] op_sel_hi:[1,0]
	v_pk_add_f32 v[206:207], v[202:203], v[218:219] op_sel:[0,1] op_sel_hi:[1,0] neg_hi:[0,1]
	v_pk_add_f32 v[202:203], v[202:203], v[218:219] op_sel:[0,1] op_sel_hi:[1,0] neg_lo:[0,1]
	v_pk_add_f32 v[218:219], v[174:175], v[182:183]
	v_pk_add_f32 v[174:175], v[174:175], v[182:183] neg_lo:[0,1] neg_hi:[0,1]
	v_pk_add_f32 v[182:183], v[178:179], v[176:177] op_sel:[0,1] op_sel_hi:[1,0] neg_hi:[0,1]
	v_pk_add_f32 v[176:177], v[178:179], v[176:177] op_sel:[0,1] op_sel_hi:[1,0] neg_lo:[0,1]
	v_pk_add_f32 v[178:179], v[164:165], v[184:185]
	v_pk_fma_f32 v[2:3], v[4:5], v[198:199], v[2:3] op_sel_hi:[0,1,1]
	v_pk_mul_f32 v[4:5], v[12:13], v[210:211] op_sel:[0,1] op_sel_hi:[1,0]
	v_pk_fma_f32 v[78:79], v[8:9], v[66:67], v[78:79] op_sel_hi:[0,1,1]
	v_pk_fma_f32 v[4:5], v[6:7], v[210:211], v[4:5] op_sel_hi:[0,1,1]
	v_pk_mul_f32 v[6:7], v[20:21], v[178:179] op_sel:[0,1] op_sel_hi:[1,0]
	v_pk_fma_f32 v[94:95], v[8:9], v[82:83], v[94:95] op_sel_hi:[0,1,1]
	v_pk_fma_f32 v[110:111], v[8:9], v[98:99], v[110:111] op_sel_hi:[0,1,1]
	v_pk_fma_f32 v[126:127], v[8:9], v[114:115], v[126:127] op_sel_hi:[0,1,1]
	v_mov_b32_e32 v25, v17
	v_mov_b32_e32 v29, v19
	v_pk_fma_f32 v[6:7], v[8:9], v[178:179], v[6:7] op_sel_hi:[0,1,1]
	v_pk_mul_f32 v[8:9], v[14:15], v[220:221] op_sel:[0,1] op_sel_hi:[1,0]
	v_pk_mul_f32 v[32:33], v[22:23], 1.0 op_sel:[1,0] op_sel_hi:[1,0] neg_lo:[1,0]
	v_pk_mul_f32 v[44:45], v[26:27], 1.0 op_sel:[1,0] op_sel_hi:[1,0] neg_lo:[1,0]
	v_pk_mul_f32 v[48:49], v[30:31], 1.0 op_sel:[1,0] op_sel_hi:[1,0] neg_lo:[1,0]
	v_pk_mul_f32 v[52:53], v[42:43], 1.0 op_sel:[1,0] op_sel_hi:[1,0] neg_lo:[1,0]
	v_pk_add_f32 v[164:165], v[164:165], v[184:185] neg_lo:[0,1] neg_hi:[0,1]
	v_pk_add_f32 v[184:185], v[166:167], v[180:181] op_sel:[0,1] op_sel_hi:[1,0] neg_hi:[0,1]
	v_pk_add_f32 v[166:167], v[166:167], v[180:181] op_sel:[0,1] op_sel_hi:[1,0] neg_lo:[0,1]
	v_pk_add_f32 v[180:181], v[160:161], v[168:169]
	v_pk_fma_f32 v[8:9], v[10:11], v[220:221], v[8:9] op_sel_hi:[0,1,1]
	v_pk_mul_f32 v[10:11], v[24:25], v[218:219] op_sel:[0,1] op_sel_hi:[1,0]
	v_pk_mul_f32 v[12:13], v[28:29], v[212:213] op_sel:[0,1] op_sel_hi:[1,0]
	v_xor_b32_e32 v56, 0x80000000, v47
	v_xor_b32_e32 v60, 0x80000000, v51
	v_xor_b32_e32 v64, 0x80000000, v55
	v_xor_b32_e32 v68, 0x80000000, v59
	v_xor_b32_e32 v72, 0x80000000, v63
	v_xor_b32_e32 v76, 0x80000000, v67
	v_xor_b32_e32 v80, 0x80000000, v71
	v_mov_b32_e32 v57, v47
	v_mov_b32_e32 v61, v51
	v_mov_b32_e32 v65, v55
	v_mov_b32_e32 v69, v59
	v_mov_b32_e32 v73, v63
	v_mov_b32_e32 v77, v67
	v_mov_b32_e32 v81, v71
	v_pk_add_f32 v[160:161], v[160:161], v[168:169] neg_lo:[0,1] neg_hi:[0,1]
	v_pk_add_f32 v[168:169], v[156:157], v[162:163] op_sel:[0,1] op_sel_hi:[1,0] neg_hi:[0,1]
	v_pk_fma_f32 v[10:11], v[16:17], v[218:219], v[10:11] op_sel_hi:[0,1,1]
	v_pk_fma_f32 v[12:13], v[18:19], v[212:213], v[12:13] op_sel_hi:[0,1,1]
	v_pk_mul_f32 v[14:15], v[32:33], v[180:181] op_sel:[0,1] op_sel_hi:[1,0]
	v_pk_mul_f32 v[16:17], v[44:45], v[222:223] op_sel:[0,1] op_sel_hi:[1,0]
	v_pk_mul_f32 v[18:19], v[48:49], v[206:207] op_sel:[0,1] op_sel_hi:[1,0]
	v_pk_mul_f32 v[20:21], v[52:53], v[216:217] op_sel:[0,1] op_sel_hi:[1,0]
	v_xor_b32_e32 v84, 0x80000000, v75
	v_xor_b32_e32 v88, 0x80000000, v79
	v_xor_b32_e32 v92, 0x80000000, v83
	v_xor_b32_e32 v96, 0x80000000, v87
	v_xor_b32_e32 v100, 0x80000000, v91
	v_xor_b32_e32 v104, 0x80000000, v95
	v_xor_b32_e32 v108, 0x80000000, v99
	v_xor_b32_e32 v112, 0x80000000, v103
	v_xor_b32_e32 v116, 0x80000000, v107
	v_xor_b32_e32 v120, 0x80000000, v111
	v_xor_b32_e32 v124, 0x80000000, v115
	v_xor_b32_e32 v128, 0x80000000, v119
	v_xor_b32_e32 v130, 0x80000000, v123
	v_xor_b32_e32 v132, 0x80000000, v127
	v_mov_b32_e32 v85, v75
	v_mov_b32_e32 v89, v79
	v_mov_b32_e32 v93, v83
	v_mov_b32_e32 v97, v87
	v_mov_b32_e32 v101, v91
	v_mov_b32_e32 v105, v95
	v_mov_b32_e32 v109, v99
	v_mov_b32_e32 v113, v103
	v_mov_b32_e32 v117, v107
	v_mov_b32_e32 v121, v111
	v_mov_b32_e32 v125, v115
	v_mov_b32_e32 v129, v119
	v_mov_b32_e32 v131, v123
	v_mov_b32_e32 v133, v127
	v_pk_add_f32 v[156:157], v[156:157], v[162:163] op_sel:[0,1] op_sel_hi:[1,0] neg_lo:[0,1]
	v_pk_fma_f32 v[14:15], v[22:23], v[180:181], v[14:15] op_sel_hi:[0,1,1]
	v_pk_fma_f32 v[16:17], v[26:27], v[222:223], v[16:17] op_sel_hi:[0,1,1]
	v_pk_fma_f32 v[18:19], v[30:31], v[206:207], v[18:19] op_sel_hi:[0,1,1]
	v_pk_fma_f32 v[20:21], v[42:43], v[216:217], v[20:21] op_sel_hi:[0,1,1]
	v_pk_mul_f32 v[22:23], v[56:57], v[184:185] op_sel:[0,1] op_sel_hi:[1,0]
	v_pk_mul_f32 v[24:25], v[60:61], v[214:215] op_sel:[0,1] op_sel_hi:[1,0]
	v_pk_mul_f32 v[26:27], v[64:65], v[182:183] op_sel:[0,1] op_sel_hi:[1,0]
	v_pk_mul_f32 v[28:29], v[68:69], v[204:205] op_sel:[0,1] op_sel_hi:[1,0]
	v_pk_mul_f32 v[30:31], v[72:73], v[168:169] op_sel:[0,1] op_sel_hi:[1,0]
	v_pk_mul_f32 v[32:33], v[76:77], v[170:171] op_sel:[0,1] op_sel_hi:[1,0]
	v_pk_mul_f32 v[42:43], v[80:81], v[172:173] op_sel:[0,1] op_sel_hi:[1,0]
	v_pk_fma_f32 v[22:23], v[46:47], v[184:185], v[22:23] op_sel_hi:[0,1,1]
	v_pk_fma_f32 v[24:25], v[50:51], v[214:215], v[24:25] op_sel_hi:[0,1,1]
	v_pk_fma_f32 v[26:27], v[54:55], v[182:183], v[26:27] op_sel_hi:[0,1,1]
	v_pk_fma_f32 v[28:29], v[58:59], v[204:205], v[28:29] op_sel_hi:[0,1,1]
	v_pk_fma_f32 v[30:31], v[62:63], v[168:169], v[30:31] op_sel_hi:[0,1,1]
	v_pk_fma_f32 v[32:33], v[66:67], v[170:171], v[32:33] op_sel_hi:[0,1,1]
	v_pk_fma_f32 v[42:43], v[70:71], v[172:173], v[42:43] op_sel_hi:[0,1,1]
	v_pk_mul_f32 v[44:45], v[84:85], v[194:195] op_sel:[0,1] op_sel_hi:[1,0]
	v_pk_mul_f32 v[46:47], v[88:89], v[164:165] op_sel:[0,1] op_sel_hi:[1,0]
	v_pk_mul_f32 v[48:49], v[92:93], v[188:189] op_sel:[0,1] op_sel_hi:[1,0]
	v_pk_mul_f32 v[50:51], v[96:97], v[174:175] op_sel:[0,1] op_sel_hi:[1,0]
	v_pk_mul_f32 v[52:53], v[100:101], v[190:191] op_sel:[0,1] op_sel_hi:[1,0]
	v_pk_mul_f32 v[54:55], v[104:105], v[160:161] op_sel:[0,1] op_sel_hi:[1,0]
	v_pk_mul_f32 v[56:57], v[108:109], v[186:187] op_sel:[0,1] op_sel_hi:[1,0]
	v_pk_mul_f32 v[58:59], v[112:113], v[202:203] op_sel:[0,1] op_sel_hi:[1,0]
	v_pk_mul_f32 v[60:61], v[116:117], v[196:197] op_sel:[0,1] op_sel_hi:[1,0]
	v_pk_mul_f32 v[62:63], v[120:121], v[166:167] op_sel:[0,1] op_sel_hi:[1,0]
	v_pk_mul_f32 v[64:65], v[124:125], v[208:209] op_sel:[0,1] op_sel_hi:[1,0]
	v_pk_mul_f32 v[66:67], v[128:129], v[176:177] op_sel:[0,1] op_sel_hi:[1,0]
	v_pk_mul_f32 v[68:69], v[130:131], v[192:193] op_sel:[0,1] op_sel_hi:[1,0]
	v_pk_mul_f32 v[70:71], v[132:133], v[156:157] op_sel:[0,1] op_sel_hi:[1,0]
	v_pk_fma_f32 v[44:45], v[74:75], v[194:195], v[44:45] op_sel_hi:[0,1,1]
	v_pk_fma_f32 v[46:47], v[78:79], v[164:165], v[46:47] op_sel_hi:[0,1,1]
	v_pk_fma_f32 v[48:49], v[82:83], v[188:189], v[48:49] op_sel_hi:[0,1,1]
	v_pk_fma_f32 v[50:51], v[86:87], v[174:175], v[50:51] op_sel_hi:[0,1,1]
	v_pk_fma_f32 v[52:53], v[90:91], v[190:191], v[52:53] op_sel_hi:[0,1,1]
	v_pk_fma_f32 v[54:55], v[94:95], v[160:161], v[54:55] op_sel_hi:[0,1,1]
	v_pk_fma_f32 v[56:57], v[98:99], v[186:187], v[56:57] op_sel_hi:[0,1,1]
	v_pk_fma_f32 v[58:59], v[102:103], v[202:203], v[58:59] op_sel_hi:[0,1,1]
	v_pk_fma_f32 v[60:61], v[106:107], v[196:197], v[60:61] op_sel_hi:[0,1,1]
	v_pk_fma_f32 v[62:63], v[110:111], v[166:167], v[62:63] op_sel_hi:[0,1,1]
	v_pk_fma_f32 v[64:65], v[114:115], v[208:209], v[64:65] op_sel_hi:[0,1,1]
	v_pk_fma_f32 v[66:67], v[118:119], v[176:177], v[66:67] op_sel_hi:[0,1,1]
	v_pk_fma_f32 v[68:69], v[122:123], v[192:193], v[68:69] op_sel_hi:[0,1,1]
	v_pk_fma_f32 v[70:71], v[126:127], v[156:157], v[70:71] op_sel_hi:[0,1,1]
	ds_write_b64 v40, v[158:159]
	ds_write_b64 v40, v[32:33] offset:4224
	ds_write_b64 v40, v[16:17] offset:8448
	ds_write_b64 v40, v[56:57] offset:12672
	ds_write_b64 v40, v[8:9] offset:16896
	ds_write_b64 v40, v[48:49] offset:21120
	ds_write_b64 v40, v[24:25] offset:25344
	ds_write_b64 v40, v[64:65] offset:29568
	ds_write_b64 v40, v[4:5] offset:33792
	ds_write_b64 v40, v[44:45] offset:38016
	ds_write_b64 v40, v[20:21] offset:42240
	ds_write_b64 v40, v[60:61] offset:46464
	ds_write_b64 v40, v[12:13] offset:50688
	ds_write_b64 v40, v[52:53] offset:54912
	ds_write_b64 v40, v[28:29] offset:59136
	ds_write_b64 v40, v[68:69] offset:63360
	ds_write_b64 v155, v[2:3]
	ds_write_b64 v201, v[42:43]
	ds_write_b64 v224, v[18:19]
	ds_write_b64 v225, v[58:59]
	ds_write_b64 v226, v[10:11]
	ds_write_b64 v227, v[50:51]
	ds_write_b64 v228, v[26:27]
	ds_write_b64 v229, v[66:67]
	ds_write_b64 v230, v[6:7]
	ds_write_b64 v231, v[46:47]
	ds_write_b64 v232, v[22:23]
	ds_write_b64 v233, v[62:63]
	ds_write_b64 v234, v[14:15]
	ds_write_b64 v235, v[54:55]
	ds_write_b64 v236, v[30:31]
	ds_write_b64 v237, v[70:71]
	v_mov_b32_e32 v2, v1
	s_waitcnt lgkmcnt(0)
	s_barrier
	s_nop 0
	v_and_b32_e32 v3, 15, v2
	v_lshlrev_b32_e32 v2, 5, v2
	v_and_b32_e32 v4, 0xfffffe00, v2
	v_lshl_add_u32 v5, v4, 3, 0
	v_lshlrev_b32_e32 v6, 3, v3
	v_ashrrev_i32_e32 v7, 2, v4
	v_add3_u32 v40, v5, v6, v7
	v_add_u32_e32 v155, 0x800, v40
	ds_read2_b64 v[156:159], v40 offset1:16
	ds_read2_b64 v[160:163], v40 offset0:33 offset1:49
	ds_read2_b64 v[164:167], v40 offset0:66 offset1:82
	ds_read2_b64 v[168:171], v40 offset0:99 offset1:115
	ds_read2_b64 v[172:175], v40 offset0:132 offset1:148
	ds_read2_b64 v[176:179], v40 offset0:165 offset1:181
	ds_read2_b64 v[180:183], v40 offset0:198 offset1:214
	ds_read2_b64 v[184:187], v40 offset0:231 offset1:247
	ds_read2_b64 v[188:191], v155 offset0:8 offset1:24
	ds_read2_b64 v[192:195], v155 offset0:41 offset1:57
	ds_read2_b64 v[196:199], v155 offset0:74 offset1:90
	ds_read2_b64 v[202:205], v155 offset0:107 offset1:123
	ds_read2_b64 v[206:209], v155 offset0:140 offset1:156
	ds_read2_b64 v[210:213], v155 offset0:173 offset1:189
	ds_read2_b64 v[214:217], v155 offset0:206 offset1:222
	ds_read2_b64 v[218:221], v155 offset0:239 offset1:255
	s_waitcnt lgkmcnt(7)
	v_pk_add_f32 v[222:223], v[156:157], v[188:189]
	v_pk_add_f32 v[156:157], v[156:157], v[188:189] neg_lo:[0,1] neg_hi:[0,1]
	v_pk_add_f32 v[188:189], v[158:159], v[190:191]
	v_pk_add_f32 v[158:159], v[158:159], v[190:191] neg_lo:[0,1] neg_hi:[0,1]
	v_cvt_f32_ubyte0_e32 v2, v3
	v_pk_mul_f32 v[190:191], v[158:159], s[46:47]
	v_mul_f32_e32 v3, 0x3b000000, v2
	v_pk_fma_f32 v[158:159], v[158:159], s[42:43], v[190:191] op_sel:[0,0,1] op_sel_hi:[1,0,0]
	s_waitcnt lgkmcnt(6)
	v_pk_add_f32 v[190:191], v[160:161], v[192:193]
	v_pk_add_f32 v[160:161], v[160:161], v[192:193] neg_lo:[0,1] neg_hi:[0,1]
	v_sin_f32_e32 v2, v3
	v_pk_mul_f32 v[192:193], v[160:161], s[62:63]
	v_cos_f32_e32 v4, v3
	v_pk_fma_f32 v[160:161], v[160:161], s[50:51], v[192:193] op_sel:[0,0,1] op_sel_hi:[1,0,0]
	v_pk_add_f32 v[192:193], v[162:163], v[194:195]
	v_pk_add_f32 v[162:163], v[162:163], v[194:195] neg_lo:[0,1] neg_hi:[0,1]
	v_xor_b32_e32 v5, 0x80000000, v2
	v_pk_mul_f32 v[194:195], v[162:163], s[66:67]
	v_mov_b32_e32 v3, v5
	v_pk_fma_f32 v[162:163], v[162:163], s[64:65], v[194:195] op_sel:[0,0,1] op_sel_hi:[1,0,0]
	s_waitcnt lgkmcnt(5)
	v_pk_add_f32 v[194:195], v[164:165], v[196:197]
	v_pk_add_f32 v[164:165], v[164:165], v[196:197] neg_lo:[0,1] neg_hi:[0,1]
	v_pk_mul_f32 v[6:7], v[4:5], v[2:3] op_sel:[1,0] op_sel_hi:[0,1]
	v_pk_mul_f32 v[196:197], v[164:165], s[68:69]
	v_pk_fma_f32 v[6:7], v[4:5], v[4:5], v[6:7] op_sel_hi:[1,0,1]
	v_pk_fma_f32 v[164:165], v[164:165], s[10:11], v[196:197] op_sel:[0,0,1] op_sel_hi:[1,0,0]
	v_pk_add_f32 v[196:197], v[166:167], v[198:199]
	v_pk_add_f32 v[166:167], v[166:167], v[198:199] neg_lo:[0,1] neg_hi:[0,1]
	v_pk_mul_f32 v[12:13], v[6:7], 1.0 op_sel:[1,0] op_sel_hi:[1,0] neg_lo:[1,0]
	v_pk_mul_f32 v[198:199], v[166:167], s[70:71]
	s_nop 0
	v_pk_fma_f32 v[166:167], v[166:167], s[78:79], v[198:199] op_sel:[0,0,1] op_sel_hi:[1,0,0]
	s_waitcnt lgkmcnt(4)
	v_pk_add_f32 v[198:199], v[168:169], v[202:203]
	v_pk_add_f32 v[168:169], v[168:169], v[202:203] neg_lo:[0,1] neg_hi:[0,1]
	v_pk_mul_f32 v[10:11], v[6:7], v[12:13] op_sel:[1,0] op_sel_hi:[0,1]
	v_pk_mul_f32 v[202:203], v[168:169], s[72:73]
	v_pk_fma_f32 v[10:11], v[6:7], v[6:7], v[10:11] op_sel_hi:[1,0,1]
	v_pk_fma_f32 v[168:169], v[168:169], s[76:77], v[202:203] op_sel:[0,0,1] op_sel_hi:[1,0,0]
	v_pk_add_f32 v[202:203], v[170:171], v[204:205]
	v_pk_add_f32 v[170:171], v[170:171], v[204:205] neg_lo:[0,1] neg_hi:[0,1]
	v_pk_mul_f32 v[14:15], v[10:11], 1.0 op_sel:[1,0] op_sel_hi:[1,0] neg_lo:[1,0]
	v_pk_mul_f32 v[204:205], v[170:171], s[40:41]
	s_nop 0
	v_pk_fma_f32 v[170:171], v[170:171], s[44:45], v[204:205] op_sel:[0,0,1] op_sel_hi:[1,0,0]
	s_waitcnt lgkmcnt(3)
	v_pk_add_f32 v[204:205], v[172:173], v[206:207]
	v_pk_add_f32 v[206:207], v[172:173], v[206:207] neg_lo:[0,1] neg_hi:[0,1]
	v_pk_mul_f32 v[26:27], v[10:11], v[14:15] op_sel:[1,0] op_sel_hi:[0,1]
	v_pk_add_f32 v[172:173], v[174:175], v[208:209]
	v_pk_add_f32 v[174:175], v[174:175], v[208:209] neg_lo:[0,1] neg_hi:[0,1]
	v_pk_fma_f32 v[26:27], v[10:11], v[10:11], v[26:27] op_sel_hi:[1,0,1]
	v_pk_mul_f32 v[208:209], v[174:175], s[40:41]
	v_pk_mul_f32 v[50:51], v[14:15], v[26:27] op_sel:[0,1] op_sel_hi:[1,0]
	v_pk_fma_f32 v[174:175], v[174:175], s[44:45], v[208:209] op_sel:[0,0,1] op_sel_hi:[1,0,0] neg_lo:[1,0,0] neg_hi:[1,0,0]
	s_waitcnt lgkmcnt(2)
	v_pk_add_f32 v[208:209], v[176:177], v[210:211]
	v_pk_add_f32 v[176:177], v[176:177], v[210:211] neg_lo:[0,1] neg_hi:[0,1]
	v_pk_fma_f32 v[50:51], v[10:11], v[26:27], v[50:51] op_sel_hi:[0,1,1]
	v_pk_mul_f32 v[210:211], v[176:177], s[72:73]
	v_pk_mul_f32 v[66:67], v[14:15], v[50:51] op_sel:[0,1] op_sel_hi:[1,0]
	v_pk_fma_f32 v[176:177], v[176:177], s[76:77], v[210:211] op_sel:[0,0,1] op_sel_hi:[1,0,0] neg_lo:[1,0,0] neg_hi:[1,0,0]
	v_pk_add_f32 v[210:211], v[178:179], v[212:213]
	v_pk_add_f32 v[178:179], v[178:179], v[212:213] neg_lo:[0,1] neg_hi:[0,1]
	v_pk_fma_f32 v[66:67], v[10:11], v[50:51], v[66:67] op_sel_hi:[0,1,1]
	v_pk_mul_f32 v[212:213], v[178:179], s[70:71]
	v_pk_mul_f32 v[82:83], v[14:15], v[66:67] op_sel:[0,1] op_sel_hi:[1,0]
	v_pk_fma_f32 v[178:179], v[178:179], s[78:79], v[212:213] op_sel:[0,0,1] op_sel_hi:[1,0,0] neg_lo:[1,0,0] neg_hi:[1,0,0]
	s_waitcnt lgkmcnt(1)
	v_pk_add_f32 v[212:213], v[180:181], v[214:215]
	v_pk_add_f32 v[180:181], v[180:181], v[214:215] neg_lo:[0,1] neg_hi:[0,1]
	v_pk_fma_f32 v[82:83], v[10:11], v[66:67], v[82:83] op_sel_hi:[0,1,1]
	v_pk_mul_f32 v[214:215], v[180:181], s[68:69]
	v_pk_mul_f32 v[98:99], v[14:15], v[82:83] op_sel:[0,1] op_sel_hi:[1,0]
	v_pk_fma_f32 v[180:181], v[180:181], s[10:11], v[214:215] op_sel:[0,0,1] op_sel_hi:[1,0,0] neg_lo:[1,0,0] neg_hi:[1,0,0]
	v_pk_add_f32 v[214:215], v[182:183], v[216:217]
	v_pk_add_f32 v[182:183], v[182:183], v[216:217] neg_lo:[0,1] neg_hi:[0,1]
	v_pk_fma_f32 v[98:99], v[10:11], v[82:83], v[98:99] op_sel_hi:[0,1,1]
	v_pk_mul_f32 v[216:217], v[182:183], s[66:67]
	v_pk_mul_f32 v[114:115], v[14:15], v[98:99] op_sel:[0,1] op_sel_hi:[1,0]
	v_pk_fma_f32 v[182:183], v[182:183], s[64:65], v[216:217] op_sel:[0,0,1] op_sel_hi:[1,0,0] neg_lo:[1,0,0] neg_hi:[1,0,0]
	s_waitcnt lgkmcnt(0)
	v_pk_add_f32 v[216:217], v[184:185], v[218:219]
	v_pk_add_f32 v[184:185], v[184:185], v[218:219] neg_lo:[0,1] neg_hi:[0,1]
	v_pk_mul_f32 v[8:9], v[2:3], v[6:7] op_sel:[0,1] op_sel_hi:[1,0]
	v_pk_mul_f32 v[218:219], v[184:185], s[62:63]
	v_pk_fma_f32 v[114:115], v[10:11], v[98:99], v[114:115] op_sel_hi:[0,1,1]
	v_pk_fma_f32 v[184:185], v[184:185], s[50:51], v[218:219] op_sel:[0,0,1] op_sel_hi:[1,0,0] neg_lo:[1,0,0] neg_hi:[1,0,0]
	v_pk_add_f32 v[218:219], v[186:187], v[220:221]
	v_pk_add_f32 v[186:187], v[186:187], v[220:221] neg_lo:[0,1] neg_hi:[0,1]
	v_pk_fma_f32 v[8:9], v[4:5], v[6:7], v[8:9] op_sel_hi:[0,1,1]
	v_pk_mul_f32 v[220:221], v[186:187], s[46:47]
	v_pk_mul_f32 v[16:17], v[2:3], v[10:11] op_sel:[0,1] op_sel_hi:[1,0]
	v_pk_fma_f32 v[186:187], v[186:187], s[42:43], v[220:221] op_sel:[0,0,1] op_sel_hi:[1,0,0] neg_lo:[1,0,0] neg_hi:[1,0,0]
	v_pk_add_f32 v[220:221], v[222:223], v[204:205]
	v_pk_add_f32 v[204:205], v[222:223], v[204:205] neg_lo:[0,1] neg_hi:[0,1]
	v_pk_add_f32 v[222:223], v[188:189], v[172:173]
	v_pk_add_f32 v[172:173], v[188:189], v[172:173] neg_lo:[0,1] neg_hi:[0,1]
	v_pk_mul_f32 v[30:31], v[2:3], v[26:27] op_sel:[0,1] op_sel_hi:[1,0]
	v_pk_mul_f32 v[188:189], v[172:173], s[62:63]
	v_pk_mul_f32 v[54:55], v[2:3], v[50:51] op_sel:[0,1] op_sel_hi:[1,0]
	v_pk_fma_f32 v[172:173], v[172:173], s[50:51], v[188:189] op_sel:[0,0,1] op_sel_hi:[1,0,0]
	v_pk_add_f32 v[188:189], v[190:191], v[208:209]
	v_pk_add_f32 v[190:191], v[190:191], v[208:209] neg_lo:[0,1] neg_hi:[0,1]
	v_pk_mul_f32 v[70:71], v[2:3], v[66:67] op_sel:[0,1] op_sel_hi:[1,0]
	v_pk_mul_f32 v[208:209], v[190:191], s[68:69]
	v_pk_mul_f32 v[86:87], v[2:3], v[82:83] op_sel:[0,1] op_sel_hi:[1,0]
	v_pk_fma_f32 v[190:191], v[190:191], s[10:11], v[208:209] op_sel:[0,0,1] op_sel_hi:[1,0,0]
	v_pk_add_f32 v[208:209], v[192:193], v[210:211]
	v_pk_add_f32 v[192:193], v[192:193], v[210:211] neg_lo:[0,1] neg_hi:[0,1]
	v_pk_mul_f32 v[102:103], v[2:3], v[98:99] op_sel:[0,1] op_sel_hi:[1,0]
	v_pk_mul_f32 v[210:211], v[192:193], s[72:73]
	v_pk_mul_f32 v[118:119], v[2:3], v[114:115] op_sel:[0,1] op_sel_hi:[1,0]
	v_pk_fma_f32 v[192:193], v[192:193], s[76:77], v[210:211] op_sel:[0,0,1] op_sel_hi:[1,0,0]
	v_pk_add_f32 v[210:211], v[194:195], v[212:213]
	v_pk_add_f32 v[212:213], v[194:195], v[212:213] neg_lo:[0,1] neg_hi:[0,1]
	v_pk_mul_f32 v[20:21], v[8:9], 1.0 op_sel:[1,0] op_sel_hi:[1,0] neg_lo:[1,0]
	v_pk_add_f32 v[194:195], v[196:197], v[214:215]
	v_pk_add_f32 v[196:197], v[196:197], v[214:215] neg_lo:[0,1] neg_hi:[0,1]
	s_nop 0
	v_pk_mul_f32 v[214:215], v[196:197], s[72:73]
	v_pk_fma_f32 v[16:17], v[4:5], v[10:11], v[16:17] op_sel_hi:[0,1,1]
	v_pk_fma_f32 v[196:197], v[196:197], s[76:77], v[214:215] op_sel:[0,0,1] op_sel_hi:[1,0,0] neg_lo:[1,0,0] neg_hi:[1,0,0]
	v_pk_add_f32 v[214:215], v[198:199], v[216:217]
	v_pk_add_f32 v[198:199], v[198:199], v[216:217] neg_lo:[0,1] neg_hi:[0,1]
	v_pk_mul_f32 v[18:19], v[12:13], v[10:11] op_sel:[0,1] op_sel_hi:[1,0]
	v_pk_mul_f32 v[216:217], v[198:199], s[68:69]
	v_pk_fma_f32 v[30:31], v[4:5], v[26:27], v[30:31] op_sel_hi:[0,1,1]
	v_pk_fma_f32 v[198:199], v[198:199], s[10:11], v[216:217] op_sel:[0,0,1] op_sel_hi:[1,0,0] neg_lo:[1,0,0] neg_hi:[1,0,0]
	v_pk_add_f32 v[216:217], v[202:203], v[218:219]
	v_pk_add_f32 v[202:203], v[202:203], v[218:219] neg_lo:[0,1] neg_hi:[0,1]
	v_pk_mul_f32 v[42:43], v[12:13], v[26:27] op_sel:[0,1] op_sel_hi:[1,0]
	v_pk_mul_f32 v[218:219], v[202:203], s[62:63]
	v_pk_fma_f32 v[54:55], v[4:5], v[50:51], v[54:55] op_sel_hi:[0,1,1]
	v_pk_fma_f32 v[202:203], v[202:203], s[50:51], v[218:219] op_sel:[0,0,1] op_sel_hi:[1,0,0] neg_lo:[1,0,0] neg_hi:[1,0,0]
	v_pk_add_f32 v[218:219], v[156:157], v[206:207] op_sel:[0,1] op_sel_hi:[1,0] neg_hi:[0,1]
	v_pk_add_f32 v[156:157], v[156:157], v[206:207] op_sel:[0,1] op_sel_hi:[1,0] neg_lo:[0,1]
	v_pk_add_f32 v[206:207], v[158:159], v[174:175]
	v_pk_add_f32 v[158:159], v[158:159], v[174:175] neg_lo:[0,1] neg_hi:[0,1]
	v_pk_mul_f32 v[58:59], v[12:13], v[50:51] op_sel:[0,1] op_sel_hi:[1,0]
	v_pk_mul_f32 v[174:175], v[158:159], s[62:63]
	v_pk_fma_f32 v[70:71], v[4:5], v[66:67], v[70:71] op_sel_hi:[0,1,1]
	v_pk_fma_f32 v[158:159], v[158:159], s[50:51], v[174:175] op_sel:[0,0,1] op_sel_hi:[1,0,0]
	v_pk_add_f32 v[174:175], v[160:161], v[176:177]
	v_pk_add_f32 v[160:161], v[160:161], v[176:177] neg_lo:[0,1] neg_hi:[0,1]
	v_pk_mul_f32 v[74:75], v[12:13], v[66:67] op_sel:[0,1] op_sel_hi:[1,0]
	v_pk_mul_f32 v[176:177], v[160:161], s[68:69]
	v_pk_fma_f32 v[86:87], v[4:5], v[82:83], v[86:87] op_sel_hi:[0,1,1]
	v_pk_fma_f32 v[160:161], v[160:161], s[10:11], v[176:177] op_sel:[0,0,1] op_sel_hi:[1,0,0]
	v_pk_add_f32 v[176:177], v[162:163], v[178:179]
	v_pk_add_f32 v[162:163], v[162:163], v[178:179] neg_lo:[0,1] neg_hi:[0,1]
	v_pk_mul_f32 v[90:91], v[12:13], v[82:83] op_sel:[0,1] op_sel_hi:[1,0]
	v_pk_mul_f32 v[178:179], v[162:163], s[72:73]
	v_pk_fma_f32 v[102:103], v[4:5], v[98:99], v[102:103] op_sel_hi:[0,1,1]
	v_pk_fma_f32 v[162:163], v[162:163], s[76:77], v[178:179] op_sel:[0,0,1] op_sel_hi:[1,0,0]
	v_pk_add_f32 v[178:179], v[164:165], v[180:181]
	v_pk_add_f32 v[180:181], v[164:165], v[180:181] neg_lo:[0,1] neg_hi:[0,1]
	v_pk_mul_f32 v[106:107], v[12:13], v[98:99] op_sel:[0,1] op_sel_hi:[1,0]
	v_pk_add_f32 v[164:165], v[166:167], v[182:183]
	v_pk_add_f32 v[166:167], v[166:167], v[182:183] neg_lo:[0,1] neg_hi:[0,1]
	v_pk_fma_f32 v[118:119], v[4:5], v[114:115], v[118:119] op_sel_hi:[0,1,1]
	v_pk_mul_f32 v[182:183], v[166:167], s[72:73]
	v_pk_mul_f32 v[122:123], v[12:13], v[114:115] op_sel:[0,1] op_sel_hi:[1,0]
	v_pk_fma_f32 v[166:167], v[166:167], s[76:77], v[182:183] op_sel:[0,0,1] op_sel_hi:[1,0,0] neg_lo:[1,0,0] neg_hi:[1,0,0]
	v_pk_add_f32 v[182:183], v[168:169], v[184:185]
	v_pk_add_f32 v[168:169], v[168:169], v[184:185] neg_lo:[0,1] neg_hi:[0,1]
	v_pk_fma_f32 v[18:19], v[6:7], v[10:11], v[18:19] op_sel_hi:[0,1,1]
	v_pk_mul_f32 v[184:185], v[168:169], s[68:69]
	v_pk_mul_f32 v[22:23], v[10:11], v[20:21] op_sel:[1,0] op_sel_hi:[0,1]
	v_pk_fma_f32 v[168:169], v[168:169], s[10:11], v[184:185] op_sel:[0,0,1] op_sel_hi:[1,0,0] neg_lo:[1,0,0] neg_hi:[1,0,0]
	v_pk_add_f32 v[184:185], v[170:171], v[186:187]
	v_pk_add_f32 v[170:171], v[170:171], v[186:187] neg_lo:[0,1] neg_hi:[0,1]
	v_pk_fma_f32 v[42:43], v[6:7], v[26:27], v[42:43] op_sel_hi:[0,1,1]
	v_pk_mul_f32 v[186:187], v[170:171], s[62:63]
	v_pk_mul_f32 v[46:47], v[20:21], v[26:27] op_sel:[0,1] op_sel_hi:[1,0]
	v_pk_fma_f32 v[170:171], v[170:171], s[50:51], v[186:187] op_sel:[0,0,1] op_sel_hi:[1,0,0] neg_lo:[1,0,0] neg_hi:[1,0,0]
	v_pk_add_f32 v[186:187], v[220:221], v[210:211]
	v_pk_add_f32 v[210:211], v[220:221], v[210:211] neg_lo:[0,1] neg_hi:[0,1]
	v_pk_add_f32 v[220:221], v[222:223], v[194:195]
	v_pk_add_f32 v[194:195], v[222:223], v[194:195] neg_lo:[0,1] neg_hi:[0,1]
	v_pk_fma_f32 v[58:59], v[6:7], v[50:51], v[58:59] op_sel_hi:[0,1,1]
	v_pk_mul_f32 v[222:223], v[194:195], s[68:69]
	v_pk_mul_f32 v[62:63], v[20:21], v[50:51] op_sel:[0,1] op_sel_hi:[1,0]
	v_pk_fma_f32 v[194:195], v[194:195], s[10:11], v[222:223] op_sel:[0,0,1] op_sel_hi:[1,0,0]
	v_pk_add_f32 v[222:223], v[188:189], v[214:215]
	v_pk_add_f32 v[214:215], v[188:189], v[214:215] neg_lo:[0,1] neg_hi:[0,1]
	v_pk_fma_f32 v[74:75], v[6:7], v[66:67], v[74:75] op_sel_hi:[0,1,1]
	v_pk_add_f32 v[188:189], v[208:209], v[216:217]
	v_pk_add_f32 v[208:209], v[208:209], v[216:217] neg_lo:[0,1] neg_hi:[0,1]
	v_pk_mul_f32 v[78:79], v[20:21], v[66:67] op_sel:[0,1] op_sel_hi:[1,0]
	v_pk_mul_f32 v[216:217], v[208:209], s[68:69]
	v_pk_fma_f32 v[90:91], v[6:7], v[82:83], v[90:91] op_sel_hi:[0,1,1]
	v_pk_fma_f32 v[208:209], v[208:209], s[10:11], v[216:217] op_sel:[0,0,1] op_sel_hi:[1,0,0] neg_lo:[1,0,0] neg_hi:[1,0,0]
	v_pk_add_f32 v[216:217], v[204:205], v[212:213] op_sel:[0,1] op_sel_hi:[1,0] neg_hi:[0,1]
	v_pk_add_f32 v[204:205], v[204:205], v[212:213] op_sel:[0,1] op_sel_hi:[1,0] neg_lo:[0,1]
	v_pk_add_f32 v[212:213], v[172:173], v[196:197]
	v_pk_add_f32 v[172:173], v[172:173], v[196:197] neg_lo:[0,1] neg_hi:[0,1]
	v_pk_mul_f32 v[94:95], v[20:21], v[82:83] op_sel:[0,1] op_sel_hi:[1,0]
	v_pk_mul_f32 v[196:197], v[172:173], s[68:69]
	v_pk_fma_f32 v[106:107], v[6:7], v[98:99], v[106:107] op_sel_hi:[0,1,1]
	v_pk_fma_f32 v[172:173], v[172:173], s[10:11], v[196:197] op_sel:[0,0,1] op_sel_hi:[1,0,0]
	v_pk_add_f32 v[196:197], v[190:191], v[198:199]
	v_pk_add_f32 v[198:199], v[190:191], v[198:199] neg_lo:[0,1] neg_hi:[0,1]
	v_pk_mul_f32 v[110:111], v[20:21], v[98:99] op_sel:[0,1] op_sel_hi:[1,0]
	v_pk_add_f32 v[190:191], v[192:193], v[202:203]
	v_pk_add_f32 v[192:193], v[192:193], v[202:203] neg_lo:[0,1] neg_hi:[0,1]
	v_pk_fma_f32 v[122:123], v[6:7], v[114:115], v[122:123] op_sel_hi:[0,1,1]
	v_pk_mul_f32 v[202:203], v[192:193], s[68:69]
	v_pk_mul_f32 v[126:127], v[20:21], v[114:115] op_sel:[0,1] op_sel_hi:[1,0]
	v_pk_fma_f32 v[192:193], v[192:193], s[10:11], v[202:203] op_sel:[0,0,1] op_sel_hi:[1,0,0] neg_lo:[1,0,0] neg_hi:[1,0,0]
	v_pk_add_f32 v[202:203], v[218:219], v[178:179]
	v_pk_add_f32 v[178:179], v[218:219], v[178:179] neg_lo:[0,1] neg_hi:[0,1]
	v_pk_add_f32 v[218:219], v[206:207], v[164:165]
	v_pk_add_f32 v[164:165], v[206:207], v[164:165] neg_lo:[0,1] neg_hi:[0,1]
	v_xor_b32_e32 v24, 0x80000000, v17
	v_pk_mul_f32 v[206:207], v[164:165], s[68:69]
	v_xor_b32_e32 v28, 0x80000000, v19
	v_pk_fma_f32 v[164:165], v[164:165], s[10:11], v[206:207] op_sel:[0,0,1] op_sel_hi:[1,0,0]
	v_pk_add_f32 v[206:207], v[174:175], v[182:183]
	v_pk_add_f32 v[182:183], v[174:175], v[182:183] neg_lo:[0,1] neg_hi:[0,1]
	v_pk_fma_f32 v[22:23], v[10:11], v[8:9], v[22:23] op_sel_hi:[1,0,1]
	v_pk_add_f32 v[174:175], v[176:177], v[184:185]
	v_pk_add_f32 v[176:177], v[176:177], v[184:185] neg_lo:[0,1] neg_hi:[0,1]
	v_pk_fma_f32 v[46:47], v[8:9], v[26:27], v[46:47] op_sel_hi:[0,1,1]
	v_pk_mul_f32 v[184:185], v[176:177], s[68:69]
	v_pk_fma_f32 v[62:63], v[8:9], v[50:51], v[62:63] op_sel_hi:[0,1,1]
	v_pk_fma_f32 v[176:177], v[176:177], s[10:11], v[184:185] op_sel:[0,0,1] op_sel_hi:[1,0,0] neg_lo:[1,0,0] neg_hi:[1,0,0]
	v_pk_add_f32 v[184:185], v[156:157], v[180:181] op_sel:[0,1] op_sel_hi:[1,0] neg_hi:[0,1]
	v_pk_add_f32 v[156:157], v[156:157], v[180:181] op_sel:[0,1] op_sel_hi:[1,0] neg_lo:[0,1]
	v_pk_add_f32 v[180:181], v[158:159], v[166:167]
	v_pk_add_f32 v[158:159], v[158:159], v[166:167] neg_lo:[0,1] neg_hi:[0,1]
	v_pk_fma_f32 v[78:79], v[8:9], v[66:67], v[78:79] op_sel_hi:[0,1,1]
	v_pk_mul_f32 v[166:167], v[158:159], s[68:69]
	v_pk_fma_f32 v[94:95], v[8:9], v[82:83], v[94:95] op_sel_hi:[0,1,1]
	v_pk_fma_f32 v[158:159], v[158:159], s[10:11], v[166:167] op_sel:[0,0,1] op_sel_hi:[1,0,0]
	v_pk_add_f32 v[166:167], v[160:161], v[168:169]
	v_pk_add_f32 v[168:169], v[160:161], v[168:169] neg_lo:[0,1] neg_hi:[0,1]
	v_pk_fma_f32 v[110:111], v[8:9], v[98:99], v[110:111] op_sel_hi:[0,1,1]
	v_pk_add_f32 v[160:161], v[162:163], v[170:171]
	v_pk_add_f32 v[162:163], v[162:163], v[170:171] neg_lo:[0,1] neg_hi:[0,1]
	v_pk_fma_f32 v[126:127], v[8:9], v[114:115], v[126:127] op_sel_hi:[0,1,1]
	v_pk_mul_f32 v[170:171], v[162:163], s[68:69]
	v_mov_b32_e32 v25, v17
	v_pk_fma_f32 v[162:163], v[162:163], s[10:11], v[170:171] op_sel:[0,0,1] op_sel_hi:[1,0,0] neg_lo:[1,0,0] neg_hi:[1,0,0]
	v_pk_add_f32 v[170:171], v[186:187], v[222:223]
	v_pk_add_f32 v[186:187], v[186:187], v[222:223] neg_lo:[0,1] neg_hi:[0,1]
	v_pk_add_f32 v[222:223], v[220:221], v[188:189]
	v_pk_add_f32 v[220:221], v[220:221], v[188:189] neg_lo:[0,1] neg_hi:[0,1]
	s_mov_b32 s10, s60
	s_nop 0
	s_nop 0
	v_pk_add_f32 v[188:189], v[210:211], v[214:215] op_sel:[0,1] op_sel_hi:[1,0] neg_hi:[0,1]
	v_pk_add_f32 v[210:211], v[210:211], v[214:215] op_sel:[0,1] op_sel_hi:[1,0] neg_lo:[0,1]
	v_pk_add_f32 v[214:215], v[194:195], v[208:209]
	v_pk_add_f32 v[208:209], v[194:195], v[208:209] neg_lo:[0,1] neg_hi:[0,1]
	s_add_i32 s60, s60, s28
	s_nop 0
	s_nop 0
	v_pk_add_f32 v[194:195], v[216:217], v[196:197]
	v_pk_add_f32 v[196:197], v[216:217], v[196:197] neg_lo:[0,1] neg_hi:[0,1]
	v_pk_add_f32 v[216:217], v[212:213], v[190:191]
	v_pk_add_f32 v[212:213], v[212:213], v[190:191] neg_lo:[0,1] neg_hi:[0,1]
	s_cmpk_gt_i32 s60, 0x7ff
	s_nop 0
	s_nop 0
	v_pk_add_f32 v[190:191], v[204:205], v[198:199] op_sel:[0,1] op_sel_hi:[1,0] neg_hi:[0,1]
	v_pk_add_f32 v[198:199], v[204:205], v[198:199] op_sel:[0,1] op_sel_hi:[1,0] neg_lo:[0,1]
	v_pk_add_f32 v[204:205], v[172:173], v[192:193]
	v_pk_add_f32 v[192:193], v[172:173], v[192:193] neg_lo:[0,1] neg_hi:[0,1]
	s_cselect_b64 s[76:77], -1, 0
	s_nop 0
	s_nop 0
	v_pk_add_f32 v[172:173], v[202:203], v[206:207]
	v_pk_add_f32 v[202:203], v[202:203], v[206:207] neg_lo:[0,1] neg_hi:[0,1]
	v_pk_add_f32 v[206:207], v[218:219], v[174:175]
	v_pk_add_f32 v[218:219], v[218:219], v[174:175] neg_lo:[0,1] neg_hi:[0,1]
	s_cmpk_lt_i32 s60, 0x800
	s_nop 0
	s_nop 0
	v_pk_add_f32 v[174:175], v[178:179], v[182:183] op_sel:[0,1] op_sel_hi:[1,0] neg_hi:[0,1]
	v_pk_add_f32 v[178:179], v[178:179], v[182:183] op_sel:[0,1] op_sel_hi:[1,0] neg_lo:[0,1]
	v_pk_add_f32 v[182:183], v[164:165], v[176:177]
	v_pk_add_f32 v[176:177], v[164:165], v[176:177] neg_lo:[0,1] neg_hi:[0,1]
	s_cselect_b32 s45, s60, s10
	s_nop 0
	s_nop 0
	v_pk_add_f32 v[164:165], v[184:185], v[166:167]
	v_pk_add_f32 v[166:167], v[184:185], v[166:167] neg_lo:[0,1] neg_hi:[0,1]
	v_pk_add_f32 v[184:185], v[180:181], v[160:161]
	v_pk_add_f32 v[180:181], v[180:181], v[160:161] neg_lo:[0,1] neg_hi:[0,1]
	s_lshl_b32 s11, s45, 1
	s_nop 0
	s_nop 0
	v_pk_add_f32 v[160:161], v[156:157], v[168:169] op_sel:[0,1] op_sel_hi:[1,0] neg_hi:[0,1]
	v_pk_add_f32 v[156:157], v[156:157], v[168:169] op_sel:[0,1] op_sel_hi:[1,0] neg_lo:[0,1]
	v_pk_add_f32 v[168:169], v[158:159], v[162:163]
	v_pk_add_f32 v[158:159], v[158:159], v[162:163] neg_lo:[0,1] neg_hi:[0,1]
	v_mov_b32_e32 v29, v19
	v_pk_mul_f32 v[162:163], v[158:159], 1.0 op_sel:[1,0] op_sel_hi:[0,0] neg_hi:[1,0]
	v_pk_add_f32 v[158:159], v[170:171], v[222:223]
	v_pk_add_f32 v[170:171], v[170:171], v[222:223] neg_lo:[0,1] neg_hi:[0,1]
	v_pk_add_f32 v[222:223], v[186:187], v[220:221] op_sel:[0,1] op_sel_hi:[1,0] neg_hi:[0,1]
	v_pk_add_f32 v[186:187], v[186:187], v[220:221] op_sel:[0,1] op_sel_hi:[1,0] neg_lo:[0,1]
	v_pk_add_f32 v[220:221], v[188:189], v[214:215]
	v_pk_add_f32 v[188:189], v[188:189], v[214:215] neg_lo:[0,1] neg_hi:[0,1]
	v_pk_add_f32 v[214:215], v[210:211], v[208:209] op_sel:[0,1] op_sel_hi:[1,0] neg_hi:[0,1]
	v_pk_add_f32 v[208:209], v[210:211], v[208:209] op_sel:[0,1] op_sel_hi:[1,0] neg_lo:[0,1]
	v_pk_add_f32 v[210:211], v[194:195], v[216:217]
	v_pk_add_f32 v[194:195], v[194:195], v[216:217] neg_lo:[0,1] neg_hi:[0,1]
	v_pk_add_f32 v[216:217], v[196:197], v[212:213] op_sel:[0,1] op_sel_hi:[1,0] neg_hi:[0,1]
	v_pk_add_f32 v[196:197], v[196:197], v[212:213] op_sel:[0,1] op_sel_hi:[1,0] neg_lo:[0,1]
	v_pk_add_f32 v[212:213], v[190:191], v[204:205]
	v_pk_add_f32 v[190:191], v[190:191], v[204:205] neg_lo:[0,1] neg_hi:[0,1]
	v_pk_add_f32 v[204:205], v[198:199], v[192:193] op_sel:[0,1] op_sel_hi:[1,0] neg_hi:[0,1]
	v_pk_add_f32 v[192:193], v[198:199], v[192:193] op_sel:[0,1] op_sel_hi:[1,0] neg_lo:[0,1]
	v_pk_add_f32 v[198:199], v[172:173], v[206:207]
	v_pk_add_f32 v[172:173], v[172:173], v[206:207] neg_lo:[0,1] neg_hi:[0,1]
	v_pk_mul_f32 v[2:3], v[2:3], v[198:199] op_sel:[0,1] op_sel_hi:[1,0]
	v_pk_add_f32 v[206:207], v[202:203], v[218:219] op_sel:[0,1] op_sel_hi:[1,0] neg_hi:[0,1]
	v_pk_add_f32 v[202:203], v[202:203], v[218:219] op_sel:[0,1] op_sel_hi:[1,0] neg_lo:[0,1]
	v_pk_add_f32 v[218:219], v[174:175], v[182:183]
	v_pk_add_f32 v[174:175], v[174:175], v[182:183] neg_lo:[0,1] neg_hi:[0,1]
	v_pk_add_f32 v[182:183], v[178:179], v[176:177] op_sel:[0,1] op_sel_hi:[1,0] neg_hi:[0,1]
	v_pk_add_f32 v[176:177], v[178:179], v[176:177] op_sel:[0,1] op_sel_hi:[1,0] neg_lo:[0,1]
	v_pk_add_f32 v[178:179], v[164:165], v[184:185]
	v_pk_fma_f32 v[2:3], v[4:5], v[198:199], v[2:3] op_sel_hi:[0,1,1]
	v_pk_mul_f32 v[4:5], v[12:13], v[210:211] op_sel:[0,1] op_sel_hi:[1,0]
	s_and_b32 s10, s45, 0x3ff
	v_pk_fma_f32 v[4:5], v[6:7], v[210:211], v[4:5] op_sel_hi:[0,1,1]
	v_pk_mul_f32 v[6:7], v[20:21], v[178:179] op_sel:[0,1] op_sel_hi:[1,0]
	s_and_b32 s11, s11, 0xfffff800
	v_pk_fma_f32 v[6:7], v[8:9], v[178:179], v[6:7] op_sel_hi:[0,1,1]
	v_pk_mul_f32 v[8:9], v[14:15], v[220:221] op_sel:[0,1] op_sel_hi:[1,0]
	v_pk_mul_f32 v[32:33], v[22:23], 1.0 op_sel:[1,0] op_sel_hi:[1,0] neg_lo:[1,0]
	v_pk_mul_f32 v[44:45], v[26:27], 1.0 op_sel:[1,0] op_sel_hi:[1,0] neg_lo:[1,0]
	v_pk_mul_f32 v[48:49], v[30:31], 1.0 op_sel:[1,0] op_sel_hi:[1,0] neg_lo:[1,0]
	v_pk_mul_f32 v[52:53], v[42:43], 1.0 op_sel:[1,0] op_sel_hi:[1,0] neg_lo:[1,0]
	v_pk_add_f32 v[164:165], v[164:165], v[184:185] neg_lo:[0,1] neg_hi:[0,1]
	v_pk_add_f32 v[184:185], v[166:167], v[180:181] op_sel:[0,1] op_sel_hi:[1,0] neg_hi:[0,1]
	v_pk_add_f32 v[166:167], v[166:167], v[180:181] op_sel:[0,1] op_sel_hi:[1,0] neg_lo:[0,1]
	v_pk_add_f32 v[180:181], v[160:161], v[168:169]
	v_pk_fma_f32 v[8:9], v[10:11], v[220:221], v[8:9] op_sel_hi:[0,1,1]
	v_pk_mul_f32 v[10:11], v[24:25], v[218:219] op_sel:[0,1] op_sel_hi:[1,0]
	v_pk_mul_f32 v[12:13], v[28:29], v[212:213] op_sel:[0,1] op_sel_hi:[1,0]
	s_or_b32 s10, s11, s10
	v_xor_b32_e32 v56, 0x80000000, v47
	v_xor_b32_e32 v60, 0x80000000, v51
	v_xor_b32_e32 v64, 0x80000000, v55
	v_xor_b32_e32 v68, 0x80000000, v59
	v_xor_b32_e32 v72, 0x80000000, v63
	v_xor_b32_e32 v76, 0x80000000, v67
	v_xor_b32_e32 v80, 0x80000000, v71
	v_mov_b32_e32 v57, v47
	v_mov_b32_e32 v61, v51
	v_mov_b32_e32 v65, v55
	v_mov_b32_e32 v69, v59
	v_mov_b32_e32 v73, v63
	v_mov_b32_e32 v77, v67
	v_mov_b32_e32 v81, v71
	v_pk_add_f32 v[160:161], v[160:161], v[168:169] neg_lo:[0,1] neg_hi:[0,1]
	v_pk_add_f32 v[168:169], v[156:157], v[162:163]
	v_pk_fma_f32 v[10:11], v[16:17], v[218:219], v[10:11] op_sel_hi:[0,1,1]
	v_pk_fma_f32 v[12:13], v[18:19], v[212:213], v[12:13] op_sel_hi:[0,1,1]
	v_pk_mul_f32 v[14:15], v[32:33], v[180:181] op_sel:[0,1] op_sel_hi:[1,0]
	v_pk_mul_f32 v[16:17], v[44:45], v[222:223] op_sel:[0,1] op_sel_hi:[1,0]
	v_pk_mul_f32 v[18:19], v[48:49], v[206:207] op_sel:[0,1] op_sel_hi:[1,0]
	v_pk_mul_f32 v[20:21], v[52:53], v[216:217] op_sel:[0,1] op_sel_hi:[1,0]
	s_ashr_i32 s11, s10, 31
	v_xor_b32_e32 v84, 0x80000000, v75
	v_xor_b32_e32 v88, 0x80000000, v79
	v_xor_b32_e32 v92, 0x80000000, v83
	v_xor_b32_e32 v96, 0x80000000, v87
	v_xor_b32_e32 v100, 0x80000000, v91
	v_xor_b32_e32 v104, 0x80000000, v95
	v_xor_b32_e32 v108, 0x80000000, v99
	v_xor_b32_e32 v112, 0x80000000, v103
	v_xor_b32_e32 v116, 0x80000000, v107
	v_xor_b32_e32 v120, 0x80000000, v111
	v_xor_b32_e32 v124, 0x80000000, v115
	v_xor_b32_e32 v128, 0x80000000, v119
	v_xor_b32_e32 v130, 0x80000000, v123
	v_xor_b32_e32 v132, 0x80000000, v127
	v_mov_b32_e32 v85, v75
	v_mov_b32_e32 v89, v79
	v_mov_b32_e32 v93, v83
	v_mov_b32_e32 v97, v87
	v_mov_b32_e32 v101, v91
	v_mov_b32_e32 v105, v95
	v_mov_b32_e32 v109, v99
	v_mov_b32_e32 v113, v103
	v_mov_b32_e32 v117, v107
	v_mov_b32_e32 v121, v111
	v_mov_b32_e32 v125, v115
	v_mov_b32_e32 v129, v119
	v_mov_b32_e32 v131, v123
	v_mov_b32_e32 v133, v127
	v_pk_add_f32 v[156:157], v[156:157], v[162:163] neg_lo:[0,1] neg_hi:[0,1]
	v_pk_fma_f32 v[14:15], v[22:23], v[180:181], v[14:15] op_sel_hi:[0,1,1]
	v_pk_fma_f32 v[16:17], v[26:27], v[222:223], v[16:17] op_sel_hi:[0,1,1]
	v_pk_fma_f32 v[18:19], v[30:31], v[206:207], v[18:19] op_sel_hi:[0,1,1]
	v_pk_fma_f32 v[20:21], v[42:43], v[216:217], v[20:21] op_sel_hi:[0,1,1]
	v_pk_mul_f32 v[22:23], v[56:57], v[184:185] op_sel:[0,1] op_sel_hi:[1,0]
	v_pk_mul_f32 v[24:25], v[60:61], v[214:215] op_sel:[0,1] op_sel_hi:[1,0]
	v_pk_mul_f32 v[26:27], v[64:65], v[182:183] op_sel:[0,1] op_sel_hi:[1,0]
	v_pk_mul_f32 v[28:29], v[68:69], v[204:205] op_sel:[0,1] op_sel_hi:[1,0]
	v_pk_mul_f32 v[30:31], v[72:73], v[168:169] op_sel:[0,1] op_sel_hi:[1,0]
	v_pk_mul_f32 v[32:33], v[76:77], v[170:171] op_sel:[0,1] op_sel_hi:[1,0]
	v_pk_mul_f32 v[42:43], v[80:81], v[172:173] op_sel:[0,1] op_sel_hi:[1,0]
	s_lshl_b64 s[78:79], s[10:11], 15
	s_bitset1_b32 s10, 10
	v_pk_fma_f32 v[22:23], v[46:47], v[184:185], v[22:23] op_sel_hi:[0,1,1]
	v_pk_fma_f32 v[24:25], v[50:51], v[214:215], v[24:25] op_sel_hi:[0,1,1]
	v_pk_fma_f32 v[26:27], v[54:55], v[182:183], v[26:27] op_sel_hi:[0,1,1]
	v_pk_fma_f32 v[28:29], v[58:59], v[204:205], v[28:29] op_sel_hi:[0,1,1]
	v_pk_fma_f32 v[30:31], v[62:63], v[168:169], v[30:31] op_sel_hi:[0,1,1]
	v_pk_fma_f32 v[32:33], v[66:67], v[170:171], v[32:33] op_sel_hi:[0,1,1]
	v_pk_fma_f32 v[42:43], v[70:71], v[172:173], v[42:43] op_sel_hi:[0,1,1]
	v_pk_mul_f32 v[44:45], v[84:85], v[194:195] op_sel:[0,1] op_sel_hi:[1,0]
	v_pk_mul_f32 v[46:47], v[88:89], v[164:165] op_sel:[0,1] op_sel_hi:[1,0]
	v_pk_mul_f32 v[48:49], v[92:93], v[188:189] op_sel:[0,1] op_sel_hi:[1,0]
	v_pk_mul_f32 v[50:51], v[96:97], v[174:175] op_sel:[0,1] op_sel_hi:[1,0]
	v_pk_mul_f32 v[52:53], v[100:101], v[190:191] op_sel:[0,1] op_sel_hi:[1,0]
	v_pk_mul_f32 v[54:55], v[104:105], v[160:161] op_sel:[0,1] op_sel_hi:[1,0]
	v_pk_mul_f32 v[56:57], v[108:109], v[186:187] op_sel:[0,1] op_sel_hi:[1,0]
	v_pk_mul_f32 v[58:59], v[112:113], v[202:203] op_sel:[0,1] op_sel_hi:[1,0]
	v_pk_mul_f32 v[60:61], v[116:117], v[196:197] op_sel:[0,1] op_sel_hi:[1,0]
	v_pk_mul_f32 v[62:63], v[120:121], v[166:167] op_sel:[0,1] op_sel_hi:[1,0]
	v_pk_mul_f32 v[64:65], v[124:125], v[208:209] op_sel:[0,1] op_sel_hi:[1,0]
	v_pk_mul_f32 v[66:67], v[128:129], v[176:177] op_sel:[0,1] op_sel_hi:[1,0]
	v_pk_mul_f32 v[68:69], v[130:131], v[192:193] op_sel:[0,1] op_sel_hi:[1,0]
	v_pk_mul_f32 v[70:71], v[132:133], v[156:157] op_sel:[0,1] op_sel_hi:[1,0]
	s_ashr_i32 s11, s10, 31
	v_pk_fma_f32 v[44:45], v[74:75], v[194:195], v[44:45] op_sel_hi:[0,1,1]
	v_pk_fma_f32 v[46:47], v[78:79], v[164:165], v[46:47] op_sel_hi:[0,1,1]
	v_pk_fma_f32 v[48:49], v[82:83], v[188:189], v[48:49] op_sel_hi:[0,1,1]
	v_pk_fma_f32 v[50:51], v[86:87], v[174:175], v[50:51] op_sel_hi:[0,1,1]
	v_pk_fma_f32 v[52:53], v[90:91], v[190:191], v[52:53] op_sel_hi:[0,1,1]
	v_pk_fma_f32 v[54:55], v[94:95], v[160:161], v[54:55] op_sel_hi:[0,1,1]
	v_pk_fma_f32 v[56:57], v[98:99], v[186:187], v[56:57] op_sel_hi:[0,1,1]
	v_pk_fma_f32 v[58:59], v[102:103], v[202:203], v[58:59] op_sel_hi:[0,1,1]
	v_pk_fma_f32 v[60:61], v[106:107], v[196:197], v[60:61] op_sel_hi:[0,1,1]
	v_pk_fma_f32 v[62:63], v[110:111], v[166:167], v[62:63] op_sel_hi:[0,1,1]
	v_pk_fma_f32 v[64:65], v[114:115], v[208:209], v[64:65] op_sel_hi:[0,1,1]
	v_pk_fma_f32 v[66:67], v[118:119], v[176:177], v[66:67] op_sel_hi:[0,1,1]
	v_pk_fma_f32 v[68:69], v[122:123], v[192:193], v[68:69] op_sel_hi:[0,1,1]
	v_pk_fma_f32 v[70:71], v[126:127], v[156:157], v[70:71] op_sel_hi:[0,1,1]
	ds_write2_b64 v40, v[158:159], v[32:33] offset1:16
	ds_write2_b64 v40, v[16:17], v[56:57] offset0:33 offset1:49
	ds_write2_b64 v40, v[8:9], v[48:49] offset0:66 offset1:82
	ds_write2_b64 v40, v[24:25], v[64:65] offset0:99 offset1:115
	ds_write2_b64 v40, v[4:5], v[44:45] offset0:132 offset1:148
	ds_write2_b64 v40, v[20:21], v[60:61] offset0:165 offset1:181
	ds_write2_b64 v40, v[12:13], v[52:53] offset0:198 offset1:214
	ds_write2_b64 v40, v[28:29], v[68:69] offset0:231 offset1:247
	ds_write2_b64 v155, v[2:3], v[42:43] offset0:8 offset1:24
	ds_write2_b64 v155, v[18:19], v[58:59] offset0:41 offset1:57
	ds_write2_b64 v155, v[10:11], v[50:51] offset0:74 offset1:90
	ds_write2_b64 v155, v[26:27], v[66:67] offset0:107 offset1:123
	ds_write2_b64 v155, v[6:7], v[46:47] offset0:140 offset1:156
	ds_write2_b64 v155, v[22:23], v[62:63] offset0:173 offset1:189
	ds_write2_b64 v155, v[14:15], v[54:55] offset0:206 offset1:222
	ds_write2_b64 v155, v[30:31], v[70:71] offset0:239 offset1:255
	s_lshl_b64 s[10:11], s[10:11], 15
	v_lshl_add_u64 v[2:3], v[36:37], 0, s[78:79]
	s_waitcnt lgkmcnt(0)
	s_barrier
	global_load_dwordx4 v[6:9], v[2:3], off nt
	global_load_dwordx4 v[30:33], v[2:3], off offset:16 nt
	v_lshl_add_u64 v[2:3], v[36:37], 0, s[10:11]
	global_load_dwordx4 v[26:29], v[2:3], off nt
	global_load_dwordx4 v[18:21], v[2:3], off offset:16 nt
	v_mov_b32_e32 v120, 0
	s_and_saveexec_b64 s[10:11], s[0:1]
	s_cbranch_execz .LBB0_273
	global_load_ushort v120, v[2:3], off offset:32

.LBB0_275:
	s_or_b64 exec, exec, s[10:11]
	v_mov_b32_e32 v40, v1
	s_mov_b32 s73, s50
	v_ashrrev_i32_e32 v42, 31, v40
	v_lshrrev_b32_e32 v42, 23, v42
	v_add_u32_e32 v42, v40, v42
	v_ashrrev_i32_e32 v42, 9, v42
	v_mul_i32_i24_e32 v44, 0x200, v42
	v_sub_u32_e32 v70, v40, v44
	v_lshlrev_b32_e32 v40, 14, v42
	v_lshlrev_b32_e32 v42, 1, v70
	v_bfrev_b32_e32 v42, v42
	v_lshrrev_b32_e32 v42, 22, v42
	v_sub_u32_e32 v42, 0x400, v42
	v_bfrev_b32_e32 v42, v42
	v_lshrrev_b32_e32 v42, 18, v42
	v_and_b32_e32 v42, 0x3ff0, v42
	v_cmp_eq_u32_e64 s[10:11], 0, v70
	v_lshl_add_u32 v44, v70, 5, v40
	v_lshlrev_b32_e32 v45, 3, v44
	v_cndmask_b32_e64 v42, v42, 16, s[10:11]
	v_or_b32_e32 v40, v42, v40
	v_ashrrev_i32_e32 v44, 2, v44
	v_ashrrev_i32_e32 v42, 5, v40
	v_add3_u32 v44, 0, v45, v44
	v_lshlrev_b32_e32 v40, 3, v40
	v_lshlrev_b32_e32 v42, 3, v42
	v_add3_u32 v40, 0, v40, v42
	ds_read2_b64 v[46:49], v44 offset1:1
	ds_read2_b64 v[50:53], v44 offset0:2 offset1:3
	ds_read2_b64 v[76:79], v40 offset1:1
	ds_read2_b64 v[80:83], v40 offset0:2 offset1:3
	ds_read2_b64 v[54:57], v44 offset0:4 offset1:5
	ds_read2_b64 v[58:61], v44 offset0:6 offset1:7
	ds_read2_b64 v[84:87], v40 offset0:4 offset1:5
	ds_read2_b64 v[88:91], v40 offset0:6 offset1:7
	ds_read2_b64 v[62:65], v44 offset0:8 offset1:9
	ds_read2_b64 v[66:69], v44 offset0:10 offset1:11
	ds_read2_b64 v[100:103], v40 offset0:8 offset1:9
	ds_read2_b64 v[104:107], v40 offset0:10 offset1:11
	ds_read2_b64 v[72:75], v44 offset0:12 offset1:13
	ds_read2_b64 v[92:95], v44 offset0:14 offset1:15
	ds_read2_b64 v[108:111], v40 offset0:12 offset1:13
	ds_read2_b64 v[112:115], v40 offset0:14 offset1:15
	s_waitcnt lgkmcnt(7)
	v_pk_add_f32 v[96:97], v[46:47], v[62:63]
	v_pk_add_f32 v[46:47], v[46:47], v[62:63] neg_lo:[0,1] neg_hi:[0,1]
	v_pk_add_f32 v[62:63], v[48:49], v[64:65]
	v_pk_add_f32 v[48:49], v[48:49], v[64:65] neg_lo:[0,1] neg_hi:[0,1]
	s_waitcnt lgkmcnt(3)
	v_pk_add_f32 v[98:99], v[56:57], v[74:75]
	v_pk_mul_f32 v[64:65], v[48:49], s[62:63]
	v_pk_add_f32 v[56:57], v[56:57], v[74:75] neg_lo:[0,1] neg_hi:[0,1]
	v_pk_fma_f32 v[48:49], v[48:49], s[50:51], v[64:65] op_sel:[0,0,1] op_sel_hi:[1,0,0]
	v_pk_add_f32 v[64:65], v[50:51], v[66:67]
	v_pk_add_f32 v[50:51], v[50:51], v[66:67] neg_lo:[0,1] neg_hi:[0,1]
	s_mov_b32 s80, s63
	v_pk_mul_f32 v[74:75], v[56:57], s[72:73]
	s_mov_b32 s78, s69
	v_pk_mul_f32 v[66:67], v[50:51], s[68:69]
	v_pk_fma_f32 v[56:57], v[56:57], s[80:81], v[74:75] op_sel:[0,0,1] op_sel_hi:[1,0,0] neg_lo:[1,0,0] neg_hi:[1,0,0]
	s_waitcnt lgkmcnt(2)
	v_pk_add_f32 v[74:75], v[58:59], v[92:93]
	v_pk_add_f32 v[58:59], v[58:59], v[92:93] neg_lo:[0,1] neg_hi:[0,1]
	v_pk_fma_f32 v[50:51], v[50:51], s[78:79], v[66:67] op_sel:[0,0,1] op_sel_hi:[1,0,0]
	v_pk_add_f32 v[66:67], v[52:53], v[68:69]
	v_pk_add_f32 v[52:53], v[52:53], v[68:69] neg_lo:[0,1] neg_hi:[0,1]
	v_pk_mul_f32 v[92:93], v[58:59], s[68:69]
	v_pk_mul_f32 v[68:69], v[52:53], s[72:73]
	v_pk_fma_f32 v[58:59], v[58:59], s[78:79], v[92:93] op_sel:[0,0,1] op_sel_hi:[1,0,0] neg_lo:[1,0,0] neg_hi:[1,0,0]
	v_pk_add_f32 v[92:93], v[60:61], v[94:95]
	v_pk_add_f32 v[60:61], v[60:61], v[94:95] neg_lo:[0,1] neg_hi:[0,1]
	v_pk_fma_f32 v[52:53], v[52:53], s[80:81], v[68:69] op_sel:[0,0,1] op_sel_hi:[1,0,0]
	v_pk_add_f32 v[68:69], v[54:55], v[72:73]
	v_pk_add_f32 v[54:55], v[54:55], v[72:73] neg_lo:[0,1] neg_hi:[0,1]
	v_pk_mul_f32 v[94:95], v[60:61], s[62:63]
	v_pk_add_f32 v[116:117], v[66:67], v[92:93]
	v_pk_add_f32 v[66:67], v[66:67], v[92:93] neg_lo:[0,1] neg_hi:[0,1]
	v_xor_b32_e32 v73, 0x80000000, v54
	v_pk_fma_f32 v[60:61], v[60:61], s[50:51], v[94:95] op_sel:[0,0,1] op_sel_hi:[1,0,0] neg_lo:[1,0,0] neg_hi:[1,0,0]
	v_pk_add_f32 v[94:95], v[96:97], v[68:69]
	v_pk_add_f32 v[68:69], v[96:97], v[68:69] neg_lo:[0,1] neg_hi:[0,1]
	v_pk_add_f32 v[96:97], v[62:63], v[98:99]
	v_pk_add_f32 v[62:63], v[62:63], v[98:99] neg_lo:[0,1] neg_hi:[0,1]
	v_pk_mul_f32 v[92:93], v[66:67], s[68:69]
	v_mov_b32_e32 v72, v55
	v_pk_mul_f32 v[98:99], v[62:63], s[68:69]
	v_pk_fma_f32 v[66:67], v[66:67], s[78:79], v[92:93] op_sel:[0,0,1] op_sel_hi:[1,0,0] neg_lo:[1,0,0] neg_hi:[1,0,0]
	v_pk_add_f32 v[54:55], v[46:47], v[72:73]
	v_pk_add_f32 v[46:47], v[46:47], v[72:73] neg_lo:[0,1] neg_hi:[0,1]
	v_pk_add_f32 v[72:73], v[48:49], v[56:57]
	v_pk_add_f32 v[48:49], v[48:49], v[56:57] neg_lo:[0,1] neg_hi:[0,1]
	v_pk_add_f32 v[92:93], v[52:53], v[60:61]
	v_pk_add_f32 v[52:53], v[52:53], v[60:61] neg_lo:[0,1] neg_hi:[0,1]
	v_pk_fma_f32 v[62:63], v[62:63], s[78:79], v[98:99] op_sel:[0,0,1] op_sel_hi:[1,0,0]
	v_pk_add_f32 v[98:99], v[64:65], v[74:75]
	v_pk_mul_f32 v[56:57], v[48:49], s[68:69]
	v_pk_mul_f32 v[60:61], v[52:53], s[68:69]
	v_pk_fma_f32 v[48:49], v[48:49], s[78:79], v[56:57] op_sel:[0,0,1] op_sel_hi:[1,0,0]
	v_pk_add_f32 v[56:57], v[50:51], v[58:59]
	v_pk_fma_f32 v[52:53], v[52:53], s[78:79], v[60:61] op_sel:[0,0,1] op_sel_hi:[1,0,0] neg_lo:[1,0,0] neg_hi:[1,0,0]
	v_pk_add_f32 v[60:61], v[94:95], v[98:99]
	v_pk_add_f32 v[118:119], v[94:95], v[98:99] neg_lo:[0,1] neg_hi:[0,1]
	v_pk_add_f32 v[94:95], v[96:97], v[116:117]
	v_pk_add_f32 v[116:117], v[96:97], v[116:117] neg_lo:[0,1] neg_hi:[0,1]
	v_pk_add_f32 v[128:129], v[54:55], v[56:57]
	v_pk_add_f32 v[54:55], v[54:55], v[56:57] neg_lo:[0,1] neg_hi:[0,1]
	v_pk_add_f32 v[56:57], v[72:73], v[92:93]
	v_pk_add_f32 v[92:93], v[72:73], v[92:93] neg_lo:[0,1] neg_hi:[0,1]
	v_pk_add_f32 v[96:97], v[78:79], v[102:103]
	v_pk_add_f32 v[78:79], v[78:79], v[102:103] neg_lo:[0,1] neg_hi:[0,1]
	v_pk_mul_f32 v[130:131], v[92:93], 1.0 op_sel:[1,0] op_sel_hi:[0,0] neg_hi:[1,0]
	v_pk_add_f32 v[92:93], v[76:77], v[100:101]
	v_pk_add_f32 v[76:77], v[76:77], v[100:101] neg_lo:[0,1] neg_hi:[0,1]
	v_pk_mul_f32 v[100:101], v[78:79], s[62:63]
	v_bfrev_b32_e32 v40, v70
	v_pk_fma_f32 v[78:79], v[78:79], s[50:51], v[100:101] op_sel:[0,0,1] op_sel_hi:[1,0,0]
	v_pk_add_f32 v[100:101], v[80:81], v[104:105]
	v_pk_add_f32 v[80:81], v[80:81], v[104:105] neg_lo:[0,1] neg_hi:[0,1]
	v_lshrrev_b32_e32 v40, 23, v40
	v_pk_mul_f32 v[102:103], v[80:81], s[68:69]
	v_cvt_f32_u32_e32 v40, v40
	v_pk_fma_f32 v[80:81], v[80:81], s[78:79], v[102:103] op_sel:[0,0,1] op_sel_hi:[1,0,0]
	v_pk_add_f32 v[102:103], v[82:83], v[106:107]
	v_pk_add_f32 v[82:83], v[82:83], v[106:107] neg_lo:[0,1] neg_hi:[0,1]
	v_mul_f32_e32 v40, 0x38000000, v40
	v_pk_mul_f32 v[104:105], v[82:83], s[72:73]
	v_ashrrev_i32_e32 v71, 31, v70
	v_pk_fma_f32 v[82:83], v[82:83], s[80:81], v[104:105] op_sel:[0,0,1] op_sel_hi:[1,0,0]
	s_waitcnt lgkmcnt(1)
	v_pk_add_f32 v[104:105], v[84:85], v[108:109]
	v_pk_add_f32 v[106:107], v[84:85], v[108:109] neg_lo:[0,1] neg_hi:[0,1]
	v_pk_add_f32 v[74:75], v[64:65], v[74:75] neg_lo:[0,1] neg_hi:[0,1]
	v_pk_add_f32 v[84:85], v[86:87], v[110:111]
	v_pk_add_f32 v[86:87], v[86:87], v[110:111] neg_lo:[0,1] neg_hi:[0,1]
	v_cndmask_b32_e64 v40, v40, v154, s[10:11]
	v_pk_mul_f32 v[108:109], v[86:87], s[72:73]
	v_lshl_add_u64 v[44:45], v[70:71], 3, s[26:27]
	v_pk_fma_f32 v[86:87], v[86:87], s[80:81], v[108:109] op_sel:[0,0,1] op_sel_hi:[1,0,0] neg_lo:[1,0,0] neg_hi:[1,0,0]
	s_waitcnt lgkmcnt(0)
	v_pk_add_f32 v[108:109], v[88:89], v[112:113]
	v_pk_add_f32 v[88:89], v[88:89], v[112:113] neg_lo:[0,1] neg_hi:[0,1]
	s_nop 0
	v_pk_mul_f32 v[110:111], v[88:89], s[68:69]
	v_pk_add_f32 v[50:51], v[50:51], v[58:59] neg_lo:[0,1] neg_hi:[0,1]
	v_pk_fma_f32 v[88:89], v[88:89], s[78:79], v[110:111] op_sel:[0,0,1] op_sel_hi:[1,0,0] neg_lo:[1,0,0] neg_hi:[1,0,0]
	v_pk_add_f32 v[110:111], v[90:91], v[114:115]
	v_pk_add_f32 v[90:91], v[90:91], v[114:115] neg_lo:[0,1] neg_hi:[0,1]
	s_nop 0
	v_pk_mul_f32 v[112:113], v[90:91], s[62:63]
	v_pk_add_f32 v[124:125], v[62:63], v[66:67]
	v_pk_fma_f32 v[90:91], v[90:91], s[50:51], v[112:113] op_sel:[0,0,1] op_sel_hi:[1,0,0] neg_lo:[1,0,0] neg_hi:[1,0,0]
	v_pk_add_f32 v[112:113], v[92:93], v[104:105]
	v_pk_add_f32 v[92:93], v[92:93], v[104:105] neg_lo:[0,1] neg_hi:[0,1]
	v_pk_add_f32 v[104:105], v[96:97], v[84:85]
	v_pk_add_f32 v[84:85], v[96:97], v[84:85] neg_lo:[0,1] neg_hi:[0,1]
	v_pk_add_f32 v[66:67], v[62:63], v[66:67] neg_lo:[0,1] neg_hi:[0,1]
	v_pk_mul_f32 v[96:97], v[84:85], s[68:69]
	v_cos_f32_e32 v71, v40
	v_pk_fma_f32 v[84:85], v[84:85], s[78:79], v[96:97] op_sel:[0,0,1] op_sel_hi:[1,0,0]
	v_pk_add_f32 v[96:97], v[100:101], v[108:109]
	v_pk_add_f32 v[108:109], v[100:101], v[108:109] neg_lo:[0,1] neg_hi:[0,1]
	v_cmp_ne_u32_e32 vcc, 0, v70
	s_nop 0
	s_nop 0
	v_pk_add_f32 v[100:101], v[102:103], v[110:111]
	v_pk_add_f32 v[102:103], v[102:103], v[110:111] neg_lo:[0,1] neg_hi:[0,1]
	v_xor_b32_e32 v59, 0x80000000, v50
	v_pk_mul_f32 v[110:111], v[102:103], s[68:69]
	v_pk_add_f32 v[64:65], v[68:69], v[74:75] op_sel:[0,1] op_sel_hi:[1,0] neg_hi:[0,1]
	v_pk_fma_f32 v[102:103], v[102:103], s[78:79], v[110:111] op_sel:[0,0,1] op_sel_hi:[1,0,0] neg_lo:[1,0,0] neg_hi:[1,0,0]
	v_pk_add_f32 v[110:111], v[76:77], v[106:107] op_sel:[0,1] op_sel_hi:[1,0] neg_hi:[0,1]
	v_pk_add_f32 v[76:77], v[76:77], v[106:107] op_sel:[0,1] op_sel_hi:[1,0] neg_lo:[0,1]
	v_pk_add_f32 v[106:107], v[78:79], v[86:87]
	v_pk_add_f32 v[78:79], v[78:79], v[86:87] neg_lo:[0,1] neg_hi:[0,1]
	v_pk_add_f32 v[122:123], v[68:69], v[74:75] op_sel:[0,1] op_sel_hi:[1,0] neg_lo:[0,1]
	v_pk_mul_f32 v[86:87], v[78:79], s[68:69]
	v_xor_b32_e32 v127, 0x80000000, v66
	v_pk_fma_f32 v[78:79], v[78:79], s[78:79], v[86:87] op_sel:[0,0,1] op_sel_hi:[1,0,0]
	v_pk_add_f32 v[86:87], v[80:81], v[88:89]
	v_pk_add_f32 v[88:89], v[80:81], v[88:89] neg_lo:[0,1] neg_hi:[0,1]
	v_mov_b32_e32 v58, v51
	v_pk_add_f32 v[80:81], v[82:83], v[90:91]
	v_pk_add_f32 v[82:83], v[82:83], v[90:91] neg_lo:[0,1] neg_hi:[0,1]
	v_mov_b32_e32 v126, v67
	v_pk_mul_f32 v[90:91], v[82:83], s[68:69]
	v_sin_f32_e32 v70, v40
	v_pk_fma_f32 v[82:83], v[82:83], s[78:79], v[90:91] op_sel:[0,0,1] op_sel_hi:[1,0,0] neg_lo:[1,0,0] neg_hi:[1,0,0]
	v_pk_add_f32 v[132:133], v[46:47], v[58:59]
	v_pk_add_f32 v[156:157], v[46:47], v[58:59] neg_lo:[0,1] neg_hi:[0,1]
	v_pk_add_f32 v[46:47], v[48:49], v[52:53]
	v_pk_add_f32 v[52:53], v[48:49], v[52:53] neg_lo:[0,1] neg_hi:[0,1]
	v_pk_add_f32 v[98:99], v[60:61], v[94:95]
	v_pk_add_f32 v[94:95], v[60:61], v[94:95] neg_lo:[0,1] neg_hi:[0,1]
	v_pk_add_f32 v[74:75], v[118:119], v[116:117] op_sel:[0,1] op_sel_hi:[1,0] neg_hi:[0,1]
	v_pk_add_f32 v[68:69], v[118:119], v[116:117] op_sel:[0,1] op_sel_hi:[1,0] neg_lo:[0,1]
	v_pk_add_f32 v[72:73], v[64:65], v[124:125]
	v_pk_add_f32 v[62:63], v[64:65], v[124:125] neg_lo:[0,1] neg_hi:[0,1]
	v_pk_add_f32 v[60:61], v[122:123], v[126:127]
	v_pk_add_f32 v[66:67], v[122:123], v[126:127] neg_lo:[0,1] neg_hi:[0,1]
	v_pk_add_f32 v[114:115], v[112:113], v[96:97]
	v_pk_add_f32 v[96:97], v[112:113], v[96:97] neg_lo:[0,1] neg_hi:[0,1]
	v_pk_add_f32 v[112:113], v[104:105], v[100:101]
	v_pk_add_f32 v[100:101], v[104:105], v[100:101] neg_lo:[0,1] neg_hi:[0,1]
	v_pk_add_f32 v[104:105], v[92:93], v[108:109] op_sel:[0,1] op_sel_hi:[1,0] neg_hi:[0,1]
	v_pk_add_f32 v[92:93], v[92:93], v[108:109] op_sel:[0,1] op_sel_hi:[1,0] neg_lo:[0,1]
	v_pk_add_f32 v[108:109], v[84:85], v[102:103]
	v_pk_add_f32 v[102:103], v[84:85], v[102:103] neg_lo:[0,1] neg_hi:[0,1]
	v_pk_add_f32 v[118:119], v[106:107], v[80:81]
	v_pk_add_f32 v[106:107], v[106:107], v[80:81] neg_lo:[0,1] neg_hi:[0,1]
	v_pk_add_f32 v[122:123], v[76:77], v[88:89] op_sel:[0,1] op_sel_hi:[1,0] neg_hi:[0,1]
	v_pk_add_f32 v[124:125], v[76:77], v[88:89] op_sel:[0,1] op_sel_hi:[1,0] neg_lo:[0,1]
	v_pk_add_f32 v[76:77], v[78:79], v[82:83] neg_lo:[0,1] neg_hi:[0,1]
	v_pk_mul_f32 v[158:159], v[52:53], 1.0 op_sel:[1,0] op_sel_hi:[0,0] neg_hi:[1,0]
	v_pk_add_f32 v[64:65], v[128:129], v[56:57]
	v_pk_add_f32 v[50:51], v[128:129], v[56:57] neg_lo:[0,1] neg_hi:[0,1]
	v_pk_add_f32 v[116:117], v[110:111], v[86:87]
	v_pk_add_f32 v[110:111], v[110:111], v[86:87] neg_lo:[0,1] neg_hi:[0,1]
	v_pk_add_f32 v[126:127], v[78:79], v[82:83]
	v_pk_mul_f32 v[128:129], v[76:77], 1.0 op_sel:[1,0] op_sel_hi:[0,0] neg_hi:[1,0]
	v_pk_add_f32 v[56:57], v[54:55], v[130:131]
	v_pk_add_f32 v[58:59], v[54:55], v[130:131] neg_lo:[0,1] neg_hi:[0,1]
	v_pk_add_f32 v[54:55], v[132:133], v[46:47]
	v_pk_add_f32 v[48:49], v[132:133], v[46:47] neg_lo:[0,1] neg_hi:[0,1]
	v_pk_add_f32 v[46:47], v[156:157], v[158:159]
	v_pk_add_f32 v[52:53], v[156:157], v[158:159] neg_lo:[0,1] neg_hi:[0,1]
	v_pk_add_f32 v[90:91], v[114:115], v[112:113]
	v_pk_add_f32 v[86:87], v[114:115], v[112:113] neg_lo:[0,1] neg_hi:[0,1]
	v_pk_add_f32 v[80:81], v[96:97], v[100:101] op_sel:[0,1] op_sel_hi:[1,0] neg_hi:[0,1]
	v_pk_add_f32 v[84:85], v[96:97], v[100:101] op_sel:[0,1] op_sel_hi:[1,0] neg_lo:[0,1]
	v_pk_add_f32 v[76:77], v[104:105], v[108:109]
	v_pk_add_f32 v[78:79], v[104:105], v[108:109] neg_lo:[0,1] neg_hi:[0,1]
	v_pk_add_f32 v[82:83], v[92:93], v[102:103] op_sel:[0,1] op_sel_hi:[1,0] neg_hi:[0,1]
	v_pk_add_f32 v[88:89], v[92:93], v[102:103] op_sel:[0,1] op_sel_hi:[1,0] neg_lo:[0,1]
	v_pk_add_f32 v[92:93], v[116:117], v[118:119]
	v_pk_add_f32 v[100:101], v[116:117], v[118:119] neg_lo:[0,1] neg_hi:[0,1]
	v_pk_add_f32 v[102:103], v[110:111], v[106:107] op_sel:[0,1] op_sel_hi:[1,0] neg_hi:[0,1]
	v_pk_add_f32 v[106:107], v[110:111], v[106:107] op_sel:[0,1] op_sel_hi:[1,0] neg_lo:[0,1]
	v_pk_add_f32 v[108:109], v[122:123], v[126:127]
	v_pk_add_f32 v[110:111], v[122:123], v[126:127] neg_lo:[0,1] neg_hi:[0,1]
	v_pk_add_f32 v[112:113], v[124:125], v[128:129]
	v_pk_add_f32 v[118:119], v[124:125], v[128:129] neg_lo:[0,1] neg_hi:[0,1]
	v_mul_f32_e32 v40, 0x3f3504f3, v71
	v_mul_f32_e32 v104, 0xbec3ef15, v71
	v_mul_f32_e32 v96, 0xbf6c835e, v71
	s_and_saveexec_b64 s[10:11], vcc
	s_xor_b64 s[10:11], exec, s[10:11]
	s_cbranch_execz .LBB0_277
	v_pk_add_f32 v[114:115], v[98:99], v[118:119]
	v_pk_add_f32 v[98:99], v[98:99], v[118:119] neg_lo:[0,1] neg_hi:[0,1]
	v_mul_f32_e32 v42, 0.5, v114
	v_pk_fma_f32 v[116:117], v[70:71], 0, v[70:71] op_sel:[0,0,1] op_sel_hi:[1,0,0] neg_lo:[1,0,0]
	v_mov_b32_e32 v114, v98
	v_pk_mul_f32 v[114:115], v[114:115], s[74:75]
	s_mov_b32 s78, s63
	v_pk_mul_f32 v[118:119], v[116:117], v[114:115] op_sel:[0,1] op_sel_hi:[1,0]
	v_pk_mul_f32 v[114:115], v[116:117], v[114:115]
	s_mov_b32 s79, s50
	v_sub_f32_e32 v97, v114, v115
	v_fma_mixlo_f16 v105, v99, s75, v97
	v_fma_f32 v97, v99, 0.5, -v97
	v_cvt_f16_f32_sdwa v97, -v97 dst_sel:WORD_1 dst_unused:UNUSED_PAD src0_sel:DWORD
	v_pk_add_f32 v[98:99], v[118:119], v[118:119] op_sel:[0,1] op_sel_hi:[0,1]
	s_waitcnt vmcnt(0)
	v_pk_add_f32 v[114:115], v[42:43], v[98:99]
	v_pk_add_f32 v[98:99], v[42:43], v[98:99] op_sel_hi:[0,1] neg_lo:[0,1] neg_hi:[0,1]
	v_cvt_pk_f16_f32 v42, v114, v99
	v_lshlrev_b32_e32 v98, 16, v105
	v_or_b32_sdwa v99, v97, v42 dst_sel:DWORD dst_unused:UNUSED_PAD src0_sel:DWORD src1_sel:WORD_1
	v_or_b32_sdwa v98, v98, v42 dst_sel:DWORD dst_unused:UNUSED_PAD src0_sel:DWORD src1_sel:WORD_0
	global_store_dwordx2 v[44:45], v[98:99], off
	v_pk_add_f32 v[98:99], v[94:95], v[112:113]
	v_pk_add_f32 v[94:95], v[94:95], v[112:113] neg_lo:[0,1] neg_hi:[0,1]
	v_mul_f32_e32 v42, 0.5, v98
	v_mov_b32_e32 v98, v71
	v_mov_b32_e32 v112, v71
	v_mov_b32_e32 v113, v70
	v_pk_fma_f32 v[114:115], v[70:71], 0, v[112:113] op_sel_hi:[1,0,1] neg_lo:[0,0,1] neg_hi:[0,0,1]
	v_pk_fma_f32 v[116:117], v[70:71], 0, v[98:99] op_sel_hi:[1,0,1]
	v_mov_b32_e32 v98, v94
	v_pk_mov_b32 v[114:115], v[114:115], v[116:117] op_sel:[1,0]
	v_pk_mul_f32 v[98:99], v[98:99], s[74:75]
	s_mov_b32 s51, s63
	v_pk_mul_f32 v[116:117], v[114:115], v[98:99] op_sel:[0,1] op_sel_hi:[1,0]
	v_pk_mul_f32 v[98:99], v[114:115], v[98:99]
	v_pk_add_f32 v[114:115], v[74:75], v[110:111]
	v_sub_f32_e32 v94, v98, v99
	v_fma_mixlo_f16 v97, v95, s75, v94
	v_fma_f32 v94, v95, 0.5, -v94
	v_cvt_f16_f32_sdwa v105, -v94 dst_sel:WORD_1 dst_unused:UNUSED_PAD src0_sel:DWORD
	v_pk_add_f32 v[94:95], v[116:117], v[116:117] op_sel:[0,1] op_sel_hi:[0,1]
	v_pk_add_f32 v[98:99], v[42:43], v[94:95]
	v_pk_add_f32 v[94:95], v[42:43], v[94:95] op_sel_hi:[0,1] neg_lo:[0,1] neg_hi:[0,1]
	v_cvt_pk_f16_f32 v42, v98, v95
	v_lshlrev_b32_e32 v94, 16, v97
	v_add_co_u32_e32 v98, vcc, s31, v44
	v_or_b32_sdwa v95, v105, v42 dst_sel:DWORD dst_unused:UNUSED_PAD src0_sel:DWORD src1_sel:WORD_1
	v_or_b32_sdwa v94, v94, v42 dst_sel:DWORD dst_unused:UNUSED_PAD src0_sel:DWORD src1_sel:WORD_0
	v_addc_co_u32_e32 v99, vcc, 0, v45, vcc
	global_store_dwordx2 v[98:99], v[94:95], off offset:-4096
	v_pk_mul_f32 v[94:95], v[112:113], s[68:69]
	v_pk_add_f32 v[74:75], v[74:75], v[110:111] neg_lo:[0,1] neg_hi:[0,1]
	v_mul_f32_e32 v42, 0.5, v114
	v_pk_add_f32 v[110:111], v[40:41], v[94:95] op_sel:[0,1] op_sel_hi:[0,1] neg_lo:[0,1] neg_hi:[0,1]
	v_pk_fma_f32 v[116:117], v[112:113], s[68:69], v[40:41] op_sel_hi:[1,1,0]
	v_mov_b32_e32 v114, v74
	v_mov_b32_e32 v111, v117
	v_pk_mul_f32 v[114:115], v[114:115], s[74:75]
	s_mov_b32 s45, s41
	v_pk_mul_f32 v[116:117], v[110:111], v[114:115] op_sel:[0,1] op_sel_hi:[1,0]
	v_pk_mul_f32 v[114:115], v[110:111], v[114:115]
	s_mov_b32 s65, s67
	v_sub_f32_e32 v40, v114, v115
	v_fma_mixlo_f16 v97, v75, s75, v40
	v_fma_f32 v40, v75, 0.5, -v40
	v_cvt_f16_f32_sdwa v40, -v40 dst_sel:WORD_1 dst_unused:UNUSED_PAD src0_sel:DWORD
	v_pk_add_f32 v[74:75], v[116:117], v[116:117] op_sel:[0,1] op_sel_hi:[0,1]
	v_pk_add_f32 v[114:115], v[42:43], v[74:75]
	v_pk_add_f32 v[74:75], v[42:43], v[74:75] op_sel_hi:[0,1] neg_lo:[0,1] neg_hi:[0,1]
	v_cvt_pk_f16_f32 v42, v114, v75
	v_lshlrev_b32_e32 v74, 16, v97
	v_or_b32_sdwa v75, v40, v42 dst_sel:DWORD dst_unused:UNUSED_PAD src0_sel:DWORD src1_sel:WORD_1
	v_or_b32_sdwa v74, v74, v42 dst_sel:DWORD dst_unused:UNUSED_PAD src0_sel:DWORD src1_sel:WORD_0
	global_store_dwordx2 v[98:99], v[74:75], off
	v_pk_fma_f32 v[74:75], v[112:113], s[68:69], v[94:95] op_sel:[0,0,1] op_sel_hi:[1,1,0] neg_lo:[0,0,1] neg_hi:[0,0,1]
	v_pk_add_f32 v[94:95], v[68:69], v[108:109]
	v_pk_add_f32 v[68:69], v[68:69], v[108:109] neg_lo:[0,1] neg_hi:[0,1]
	v_mul_f32_e32 v40, 0.5, v94
	v_mov_b32_e32 v94, v68
	v_pk_mul_f32 v[94:95], v[94:95], s[74:75]
	v_mov_b32_e32 v75, v110
	v_mov_b32_e32 v111, v74
	v_pk_mul_f32 v[74:75], v[74:75], v[94:95]
	v_pk_mul_f32 v[98:99], v[110:111], v[94:95]
	v_sub_f32_e32 v42, v74, v75
	v_fma_mixlo_f16 v94, v69, s75, v42
	v_fma_f32 v42, v69, 0.5, -v42
	v_cvt_f16_f32_sdwa v42, -v42 dst_sel:WORD_1 dst_unused:UNUSED_PAD src0_sel:DWORD
	v_pk_add_f32 v[68:69], v[98:99], v[98:99] op_sel:[1,0] op_sel_hi:[1,0]
	s_nop 0
	v_pk_add_f32 v[74:75], v[40:41], v[68:69]
	v_pk_add_f32 v[68:69], v[40:41], v[68:69] op_sel_hi:[0,1] neg_lo:[0,1] neg_hi:[0,1]
	v_cvt_pk_f16_f32 v40, v74, v69
	v_lshlrev_b32_e32 v68, 16, v94
	v_add_co_u32_e32 v74, vcc, s30, v44
	v_or_b32_sdwa v69, v42, v40 dst_sel:DWORD dst_unused:UNUSED_PAD src0_sel:DWORD src1_sel:WORD_1
	v_or_b32_sdwa v68, v68, v40 dst_sel:DWORD dst_unused:UNUSED_PAD src0_sel:DWORD src1_sel:WORD_0
	v_addc_co_u32_e32 v75, vcc, 0, v45, vcc
	global_store_dwordx2 v[74:75], v[68:69], off offset:-4096
	v_mov_b32_e32 v42, v71
	v_pk_mul_f32 v[68:69], v[70:71], s[78:79] op_sel_hi:[0,1]
	v_pk_add_f32 v[94:95], v[72:73], v[106:107]
	v_pk_add_f32 v[72:73], v[72:73], v[106:107] neg_lo:[0,1] neg_hi:[0,1]
	v_mul_f32_e32 v40, 0.5, v94
	v_pk_fma_f32 v[98:99], v[42:43], s[50:51], v[68:69] op_sel_hi:[0,1,1] neg_lo:[0,0,1] neg_hi:[0,0,1]
	v_pk_fma_f32 v[106:107], v[42:43], s[50:51], v[68:69] op_sel_hi:[0,1,1]
	v_mov_b32_e32 v94, v72
	v_mov_b32_e32 v108, v98
	v_mov_b32_e32 v109, v107
	v_pk_mul_f32 v[94:95], v[94:95], s[74:75]
	s_mov_b32 s78, s41
	v_pk_mul_f32 v[110:111], v[108:109], v[94:95] op_sel:[0,1] op_sel_hi:[1,0]
	v_pk_mul_f32 v[94:95], v[108:109], v[94:95]
	s_mov_b32 s79, s44
	v_sub_f32_e32 v72, v94, v95
	v_fma_mixlo_f16 v97, v73, s75, v72
	v_fma_f32 v72, v73, 0.5, -v72
	v_cvt_f16_f32_sdwa v105, -v72 dst_sel:WORD_1 dst_unused:UNUSED_PAD src0_sel:DWORD
	v_pk_add_f32 v[72:73], v[110:111], v[110:111] op_sel:[0,1] op_sel_hi:[0,1]
	v_pk_add_f32 v[94:95], v[40:41], v[72:73]
	v_pk_add_f32 v[72:73], v[40:41], v[72:73] op_sel_hi:[0,1] neg_lo:[0,1] neg_hi:[0,1]
	v_cvt_pk_f16_f32 v40, v94, v73
	v_lshlrev_b32_e32 v72, 16, v97
	v_or_b32_sdwa v73, v105, v40 dst_sel:DWORD dst_unused:UNUSED_PAD src0_sel:DWORD src1_sel:WORD_1
	v_or_b32_sdwa v72, v72, v40 dst_sel:DWORD dst_unused:UNUSED_PAD src0_sel:DWORD src1_sel:WORD_0
	global_store_dwordx2 v[74:75], v[72:73], off
	v_pk_add_f32 v[72:73], v[62:63], v[102:103]
	v_sub_f32_e32 v75, v63, v103
	v_mov_b32_e32 v105, v62
	v_pk_mov_b32 v[62:63], v[68:69], v[102:103] op_sel:[1,0]
	v_mul_f32_e32 v40, 0.5, v73
	v_pk_add_f32 v[62:63], v[104:105], v[62:63] neg_lo:[0,1] neg_hi:[0,1]
	v_mul_f32_e32 v74, 0.5, v72
	v_pk_mul_f32 v[94:95], v[62:63], v[40:41]
	s_nop 0
	v_mul_f32_e32 v62, v62, v95
	v_fma_f32 v40, -v98, v40, v62
	v_fma_mixlo_f16 v69, v75, s75, v40
	v_fma_f32 v40, v75, 0.5, -v40
	v_pk_fma_f32 v[102:103], v[98:99], v[94:95], v[94:95] op_sel:[0,1,0] op_sel_hi:[1,0,1]
	v_cvt_f16_f32_sdwa v40, -v40 dst_sel:WORD_1 dst_unused:UNUSED_PAD src0_sel:DWORD
	v_pk_add_f32 v[62:63], v[74:75], v[102:103]
	v_lshlrev_b32_e32 v69, 16, v69
	v_fma_f32 v63, v72, 0.5, -v102
	v_cvt_pk_f16_f32 v62, v62, v63
	v_add_co_u32_e32 v72, vcc, s33, v44
	v_or_b32_sdwa v63, v40, v62 dst_sel:DWORD dst_unused:UNUSED_PAD src0_sel:DWORD src1_sel:WORD_1
	v_or_b32_sdwa v62, v69, v62 dst_sel:DWORD dst_unused:UNUSED_PAD src0_sel:DWORD src1_sel:WORD_0
	v_addc_co_u32_e32 v73, vcc, 0, v45, vcc
	global_store_dwordx2 v[72:73], v[62:63], off offset:-4096
	v_pk_add_f32 v[62:63], v[100:101], v[60:61]
	v_pk_add_f32 v[60:61], v[60:61], v[100:101] neg_lo:[0,1] neg_hi:[0,1]
	v_mul_f32_e32 v40, 0.5, v62
	v_mov_b32_e32 v62, v60
	v_pk_mov_b32 v[74:75], v[98:99], v[106:107] op_sel:[1,0]
	v_pk_mul_f32 v[62:63], v[62:63], s[74:75]
	s_nop 0
	v_pk_mul_f32 v[94:95], v[74:75], v[62:63] op_sel:[0,1] op_sel_hi:[1,0]
	v_pk_mul_f32 v[62:63], v[74:75], v[62:63]
	s_nop 0
	v_sub_f32_e32 v60, v62, v63
	v_fma_mixlo_f16 v69, v61, s75, v60
	v_fma_f32 v60, v61, 0.5, -v60
	v_cvt_f16_f32_sdwa v97, -v60 dst_sel:WORD_1 dst_unused:UNUSED_PAD src0_sel:DWORD
	v_pk_add_f32 v[60:61], v[94:95], v[94:95] op_sel:[0,1] op_sel_hi:[0,1]
	v_pk_add_f32 v[62:63], v[40:41], v[60:61]
	v_pk_add_f32 v[60:61], v[40:41], v[60:61] op_sel_hi:[0,1] neg_lo:[0,1] neg_hi:[0,1]
	v_cvt_pk_f16_f32 v40, v62, v61
	v_lshlrev_b32_e32 v60, 16, v69
	v_or_b32_sdwa v61, v97, v40 dst_sel:DWORD dst_unused:UNUSED_PAD src0_sel:DWORD src1_sel:WORD_1
	v_or_b32_sdwa v60, v60, v40 dst_sel:DWORD dst_unused:UNUSED_PAD src0_sel:DWORD src1_sel:WORD_0
	global_store_dwordx2 v[72:73], v[60:61], off
	v_pk_add_f32 v[60:61], v[92:93], v[66:67]
	v_mov_b32_e32 v97, v66
	v_mov_b32_e32 v69, v92
	v_sub_f32_e32 v63, v67, v93
	v_mul_f32_e32 v40, 0.5, v61
	v_pk_add_f32 v[66:67], v[96:97], v[68:69] neg_lo:[0,1] neg_hi:[0,1]
	v_mul_f32_e32 v62, 0.5, v60
	v_pk_mul_f32 v[68:69], v[66:67], v[40:41]
	s_nop 0
	v_mul_f32_e32 v61, v66, v69
	v_fma_f32 v40, -v99, v40, v61
	v_fma_mixlo_f16 v61, v63, s75, v40
	v_fma_f32 v40, v63, 0.5, -v40
	v_cvt_f16_f32_sdwa v40, -v40 dst_sel:WORD_1 dst_unused:UNUSED_PAD src0_sel:DWORD
	v_pk_fma_f32 v[72:73], v[74:75], v[68:69], v[68:69] op_sel:[0,1,0] op_sel_hi:[1,0,1]
	v_pk_add_f32 v[66:67], v[64:65], v[88:89]
	v_pk_add_f32 v[62:63], v[62:63], v[72:73]
	v_fma_f32 v60, v60, 0.5, -v72
	v_cvt_pk_f16_f32 v60, v62, v60
	v_lshlrev_b32_e32 v62, 16, v61
	v_or_b32_sdwa v61, v40, v60 dst_sel:DWORD dst_unused:UNUSED_PAD src0_sel:DWORD src1_sel:WORD_1
	v_or_b32_sdwa v60, v62, v60 dst_sel:DWORD dst_unused:UNUSED_PAD src0_sel:DWORD src1_sel:WORD_0
	v_add_co_u32_e32 v62, vcc, s34, v44
	v_pk_add_f32 v[64:65], v[64:65], v[88:89] neg_lo:[0,1] neg_hi:[0,1]
	s_nop 0
	v_addc_co_u32_e32 v63, vcc, 0, v45, vcc
	global_store_dwordx2 v[62:63], v[60:61], off offset:-4096
	v_pk_mul_f32 v[60:61], v[70:71], s[44:45] op_sel_hi:[0,1]
	v_mul_f32_e32 v40, 0.5, v66
	v_pk_fma_f32 v[68:69], v[42:43], s[78:79], v[60:61] op_sel_hi:[0,1,1] neg_lo:[0,0,1] neg_hi:[0,0,1]
	v_pk_fma_f32 v[72:73], v[42:43], s[78:79], v[60:61] op_sel_hi:[0,1,1]
	v_mov_b32_e32 v66, v64
	v_mov_b32_e32 v74, v68
	v_mov_b32_e32 v75, v73
	v_pk_mul_f32 v[66:67], v[66:67], s[74:75]
	s_mov_b32 s78, s67
	v_pk_mul_f32 v[88:89], v[74:75], v[66:67] op_sel:[0,1] op_sel_hi:[1,0]
	v_pk_mul_f32 v[66:67], v[74:75], v[66:67]
	s_mov_b32 s79, s64
	v_sub_f32_e32 v64, v66, v67
	v_fma_mixlo_f16 v74, v65, s75, v64
	v_fma_f32 v64, v65, 0.5, -v64
	v_cvt_f16_f32_sdwa v75, -v64 dst_sel:WORD_1 dst_unused:UNUSED_PAD src0_sel:DWORD
	v_pk_add_f32 v[64:65], v[88:89], v[88:89] op_sel:[0,1] op_sel_hi:[0,1]
	v_pk_add_f32 v[66:67], v[40:41], v[64:65]
	v_pk_add_f32 v[64:65], v[40:41], v[64:65] op_sel_hi:[0,1] neg_lo:[0,1] neg_hi:[0,1]
	v_cvt_pk_f16_f32 v40, v66, v65
	v_lshlrev_b32_e32 v64, 16, v74
	v_or_b32_sdwa v65, v75, v40 dst_sel:DWORD dst_unused:UNUSED_PAD src0_sel:DWORD src1_sel:WORD_1
	v_or_b32_sdwa v64, v64, v40 dst_sel:DWORD dst_unused:UNUSED_PAD src0_sel:DWORD src1_sel:WORD_0
	global_store_dwordx2 v[62:63], v[64:65], off
	v_mul_f32_e32 v62, 0xbe47c5c2, v71
	v_pk_add_f32 v[64:65], v[50:51], v[82:83]
	v_sub_f32_e32 v67, v51, v83
	v_mov_b32_e32 v63, v50
	v_pk_mov_b32 v[50:51], v[60:61], v[82:83] op_sel:[1,0]
	v_mul_f32_e32 v40, 0.5, v65
	v_pk_add_f32 v[50:51], v[62:63], v[50:51] neg_lo:[0,1] neg_hi:[0,1]
	v_mul_f32_e32 v66, 0.5, v64
	v_pk_mul_f32 v[62:63], v[50:51], v[40:41]
	s_nop 0
	v_mul_f32_e32 v50, v50, v63
	v_fma_f32 v40, -v68, v40, v50
	v_fma_mixlo_f16 v61, v67, s75, v40
	v_fma_f32 v40, v67, 0.5, -v40
	v_pk_fma_f32 v[74:75], v[68:69], v[62:63], v[62:63] op_sel:[0,1,0] op_sel_hi:[1,0,1]
	v_cvt_f16_f32_sdwa v40, -v40 dst_sel:WORD_1 dst_unused:UNUSED_PAD src0_sel:DWORD
	v_pk_add_f32 v[50:51], v[66:67], v[74:75]
	v_lshlrev_b32_e32 v61, 16, v61
	v_fma_f32 v51, v64, 0.5, -v74
	v_cvt_pk_f16_f32 v50, v50, v51
	v_add_co_u32_e32 v62, vcc, s35, v44
	v_or_b32_sdwa v51, v40, v50 dst_sel:DWORD dst_unused:UNUSED_PAD src0_sel:DWORD src1_sel:WORD_1
	v_or_b32_sdwa v50, v61, v50 dst_sel:DWORD dst_unused:UNUSED_PAD src0_sel:DWORD src1_sel:WORD_0
	v_addc_co_u32_e32 v63, vcc, 0, v45, vcc
	global_store_dwordx2 v[62:63], v[50:51], off offset:-4096
	v_pk_mul_f32 v[50:51], v[70:71], s[64:65] op_sel_hi:[0,1]
	v_pk_add_f32 v[64:65], v[78:79], v[56:57]
	v_pk_add_f32 v[56:57], v[56:57], v[78:79] neg_lo:[0,1] neg_hi:[0,1]
	v_mul_f32_e32 v40, 0.5, v64
	v_pk_fma_f32 v[66:67], v[42:43], s[78:79], v[50:51] op_sel_hi:[0,1,1] neg_lo:[0,0,1] neg_hi:[0,0,1]
	v_pk_fma_f32 v[74:75], v[42:43], s[78:79], v[50:51] op_sel_hi:[0,1,1]
	v_mov_b32_e32 v64, v56
	v_mov_b32_e32 v78, v66
	v_mov_b32_e32 v79, v75
	v_pk_mul_f32 v[64:65], v[64:65], s[74:75]
	s_nop 0
	v_pk_mul_f32 v[82:83], v[78:79], v[64:65] op_sel:[0,1] op_sel_hi:[1,0]
	v_pk_mul_f32 v[64:65], v[78:79], v[64:65]
	s_nop 0
	v_sub_f32_e32 v42, v64, v65
	v_fma_mixlo_f16 v61, v57, s75, v42
	v_fma_f32 v42, v57, 0.5, -v42
	v_cvt_f16_f32_sdwa v42, -v42 dst_sel:WORD_1 dst_unused:UNUSED_PAD src0_sel:DWORD
	v_pk_add_f32 v[56:57], v[82:83], v[82:83] op_sel:[0,1] op_sel_hi:[0,1]
	v_pk_add_f32 v[64:65], v[40:41], v[56:57]
	v_pk_add_f32 v[56:57], v[40:41], v[56:57] op_sel_hi:[0,1] neg_lo:[0,1] neg_hi:[0,1]
	v_cvt_pk_f16_f32 v40, v64, v57
	v_lshlrev_b32_e32 v56, 16, v61
	v_or_b32_sdwa v57, v42, v40 dst_sel:DWORD dst_unused:UNUSED_PAD src0_sel:DWORD src1_sel:WORD_1
	v_or_b32_sdwa v56, v56, v40 dst_sel:DWORD dst_unused:UNUSED_PAD src0_sel:DWORD src1_sel:WORD_0
	global_store_dwordx2 v[62:63], v[56:57], off
	v_mul_f32_e32 v56, 0xbf54db31, v71
	v_pk_add_f32 v[62:63], v[76:77], v[58:59]
	v_sub_f32_e32 v61, v59, v77
	v_mov_b32_e32 v57, v58
	v_pk_mov_b32 v[58:59], v[50:51], v[76:77] op_sel:[1,0]
	v_mul_f32_e32 v40, 0.5, v63
	v_pk_add_f32 v[56:57], v[56:57], v[58:59] neg_lo:[0,1] neg_hi:[0,1]
	v_mul_f32_e32 v42, 0.5, v62
	v_pk_mul_f32 v[58:59], v[56:57], v[40:41]
	s_nop 0
	v_mul_f32_e32 v51, v56, v59
	v_fma_f32 v40, -v66, v40, v51
	v_fma_mixlo_f16 v51, v61, s75, v40
	v_fma_f32 v40, v61, 0.5, -v40
	v_cvt_f16_f32_sdwa v40, -v40 dst_sel:WORD_1 dst_unused:UNUSED_PAD src0_sel:DWORD
	v_pk_fma_f32 v[64:65], v[66:67], v[58:59], v[58:59] op_sel:[0,1,0] op_sel_hi:[1,0,1]
	v_lshlrev_b32_e32 v51, 16, v51
	v_pk_add_f32 v[56:57], v[42:43], v[64:65]
	v_fma_f32 v42, v62, 0.5, -v64
	v_cvt_pk_f16_f32 v42, v56, v42
	v_add_co_u32_e32 v58, vcc, s39, v44
	v_or_b32_sdwa v57, v40, v42 dst_sel:DWORD dst_unused:UNUSED_PAD src0_sel:DWORD src1_sel:WORD_1
	v_or_b32_sdwa v56, v51, v42 dst_sel:DWORD dst_unused:UNUSED_PAD src0_sel:DWORD src1_sel:WORD_0
	v_addc_co_u32_e32 v59, vcc, 0, v45, vcc
	global_store_dwordx2 v[58:59], v[56:57], off offset:-4096
	v_pk_add_f32 v[56:57], v[84:85], v[54:55]
	v_pk_add_f32 v[54:55], v[54:55], v[84:85] neg_lo:[0,1] neg_hi:[0,1]
	v_mul_f32_e32 v40, 0.5, v56
	v_mov_b32_e32 v56, v54
	v_pk_mov_b32 v[62:63], v[66:67], v[74:75] op_sel:[1,0]
	v_pk_mul_f32 v[56:57], v[56:57], s[74:75]
	s_nop 0
	v_pk_mul_f32 v[64:65], v[62:63], v[56:57] op_sel:[0,1] op_sel_hi:[1,0]
	v_pk_mul_f32 v[56:57], v[62:63], v[56:57]
	s_nop 0
	v_sub_f32_e32 v42, v56, v57
	v_fma_mixlo_f16 v51, v55, s75, v42
	v_fma_f32 v42, v55, 0.5, -v42
	v_cvt_f16_f32_sdwa v42, -v42 dst_sel:WORD_1 dst_unused:UNUSED_PAD src0_sel:DWORD
	v_pk_add_f32 v[54:55], v[64:65], v[64:65] op_sel:[0,1] op_sel_hi:[0,1]
	v_pk_add_f32 v[56:57], v[40:41], v[54:55]
	v_pk_add_f32 v[54:55], v[40:41], v[54:55] op_sel_hi:[0,1] neg_lo:[0,1] neg_hi:[0,1]
	v_cvt_pk_f16_f32 v40, v56, v55
	v_lshlrev_b32_e32 v51, 16, v51
	v_or_b32_sdwa v55, v42, v40 dst_sel:DWORD dst_unused:UNUSED_PAD src0_sel:DWORD src1_sel:WORD_1
	v_or_b32_sdwa v54, v51, v40 dst_sel:DWORD dst_unused:UNUSED_PAD src0_sel:DWORD src1_sel:WORD_0
	global_store_dwordx2 v[58:59], v[54:55], off
	v_mul_f32_e32 v54, 0xbf0e39da, v71
	v_pk_add_f32 v[56:57], v[80:81], v[48:49]
	v_mov_b32_e32 v55, v48
	v_mov_b32_e32 v51, v80
	v_sub_f32_e32 v58, v49, v81
	v_mul_f32_e32 v40, 0.5, v57
	v_pk_add_f32 v[48:49], v[54:55], v[50:51] neg_lo:[0,1] neg_hi:[0,1]
	v_mul_f32_e32 v42, 0.5, v56
	v_pk_mul_f32 v[50:51], v[48:49], v[40:41]
	s_nop 0
	v_mul_f32_e32 v48, v48, v51
	v_fma_f32 v40, -v67, v40, v48
	v_pk_fma_f32 v[54:55], v[62:63], v[50:51], v[50:51] op_sel:[0,1,0] op_sel_hi:[1,0,1]
	v_fma_mixlo_f16 v50, v58, s75, v40
	v_fma_f32 v40, v58, 0.5, -v40
	v_cvt_f16_f32_sdwa v40, -v40 dst_sel:WORD_1 dst_unused:UNUSED_PAD src0_sel:DWORD
	v_pk_add_f32 v[48:49], v[42:43], v[54:55]
	v_fma_f32 v42, v56, 0.5, -v54
	v_cvt_pk_f16_f32 v42, v48, v42
	v_lshlrev_b32_e32 v48, 16, v50
	v_add_co_u32_e32 v50, vcc, s43, v44
	v_or_b32_sdwa v49, v40, v42 dst_sel:DWORD dst_unused:UNUSED_PAD src0_sel:DWORD src1_sel:WORD_1
	v_or_b32_sdwa v48, v48, v42 dst_sel:DWORD dst_unused:UNUSED_PAD src0_sel:DWORD src1_sel:WORD_0
	v_addc_co_u32_e32 v51, vcc, 0, v45, vcc
	global_store_dwordx2 v[50:51], v[48:49], off offset:-4096
	v_pk_add_f32 v[48:49], v[86:87], v[46:47]
	v_pk_add_f32 v[46:47], v[46:47], v[86:87] neg_lo:[0,1] neg_hi:[0,1]
	v_mul_f32_e32 v40, 0.5, v48
	v_mov_b32_e32 v48, v46
	v_pk_mov_b32 v[54:55], v[68:69], v[72:73] op_sel:[1,0]
	v_pk_mul_f32 v[48:49], v[48:49], s[74:75]
	s_nop 0
	v_pk_mul_f32 v[56:57], v[54:55], v[48:49] op_sel:[0,1] op_sel_hi:[1,0]
	v_pk_mul_f32 v[48:49], v[54:55], v[48:49]
	s_nop 0
	v_sub_f32_e32 v42, v48, v49
	v_fma_mixlo_f16 v54, v47, s75, v42
	v_fma_f32 v42, v47, 0.5, -v42
	v_pk_add_f32 v[46:47], v[56:57], v[56:57] op_sel:[0,1] op_sel_hi:[0,1]
	v_pk_add_f32 v[48:49], v[40:41], v[46:47]
	v_pk_add_f32 v[46:47], v[40:41], v[46:47] op_sel_hi:[0,1] neg_lo:[0,1] neg_hi:[0,1]
	v_cvt_pk_f16_f32 v56, v48, v47
	v_pk_add_f32 v[46:47], v[52:53], v[90:91]
	v_pk_add_f32 v[48:49], v[52:53], v[90:91] neg_lo:[0,1] neg_hi:[0,1]
	v_mov_b32_e32 v52, v46
	v_mov_b32_e32 v53, v49
	v_mov_b32_e32 v49, v47
	v_pk_mul_f32 v[46:47], v[48:49], s[74:75]
	v_fma_f32 v40, v71, s40, -v60
	v_pk_mul_f32 v[48:49], v[68:69], v[46:47] op_sel:[1,0]
	v_lshlrev_b32_e32 v57, 16, v54
	v_pk_fma_f32 v[54:55], v[40:41], v[46:47], v[48:49] op_sel:[0,1,0] op_sel_hi:[0,0,1] neg_hi:[0,0,1]
	s_nop 0
	s_nop 0
	v_pk_fma_f32 v[46:47], v[52:53], 0.5, v[54:55] op_sel_hi:[1,0,1]
	v_cvt_f16_f32_sdwa v42, -v42 dst_sel:WORD_1 dst_unused:UNUSED_PAD src0_sel:DWORD
	v_cvt_f16_f32_e32 v40, v46
	v_cvt_f16_f32_sdwa v48, v47 dst_sel:WORD_1 dst_unused:UNUSED_PAD src0_sel:DWORD
	v_or_b32_sdwa v46, v57, v56 dst_sel:DWORD dst_unused:UNUSED_PAD src0_sel:DWORD src1_sel:WORD_0
	v_or_b32_sdwa v47, v42, v56 dst_sel:DWORD dst_unused:UNUSED_PAD src0_sel:DWORD src1_sel:WORD_1
	v_pk_fma_f32 v[116:117], v[52:53], 0.5, v[54:55] op_sel_hi:[1,0,1] neg_lo:[0,0,1] neg_hi:[0,0,1]
	v_or_b32_e32 v114, v48, v40
	global_store_dwordx2 v[50:51], v[46:47], off

.LBB0_428:
	s_ashr_i32 s17, s16, 31
	s_lshl_b64 s[6:7], s[16:17], 2
	s_add_u32 s6, s48, s6
	s_addc_u32 s7, s49, s7
	global_load_dwordx2 v[40:41], v151, s[6:7]
	s_waitcnt vmcnt(0)
	v_cvt_f32_f16_e32 v36, v10
	v_cvt_f32_f16_sdwa v42, v10 dst_sel:DWORD dst_unused:UNUSED_PAD src0_sel:WORD_1
	v_cvt_f32_f16_e32 v43, v11
	v_cvt_f32_f16_e32 v45, v12
	v_cvt_f32_f16_sdwa v46, v12 dst_sel:DWORD dst_unused:UNUSED_PAD src0_sel:WORD_1
	v_cvt_f32_f16_e32 v47, v13
	v_cvt_f32_f16_sdwa v12, v13 dst_sel:DWORD dst_unused:UNUSED_PAD src0_sel:WORD_1
	v_cvt_f32_f16_e32 v13, v30
	v_cvt_f32_f16_sdwa v50, v26 dst_sel:DWORD dst_unused:UNUSED_PAD src0_sel:WORD_1
	v_cvt_f32_f16_e32 v51, v27
	v_cvt_f32_f16_sdwa v44, v11 dst_sel:DWORD dst_unused:UNUSED_PAD src0_sel:WORD_1
	v_cvt_f32_f16_sdwa v48, v30 dst_sel:DWORD dst_unused:UNUSED_PAD src0_sel:WORD_1
	v_cvt_f32_f16_e32 v49, v31
	v_cvt_f32_f16_sdwa v30, v31 dst_sel:DWORD dst_unused:UNUSED_PAD src0_sel:WORD_1
	v_cvt_f32_f16_e32 v31, v32
	v_cvt_f32_f16_sdwa v11, v33 dst_sel:DWORD dst_unused:UNUSED_PAD src0_sel:WORD_1
	v_cvt_f32_f16_sdwa v32, v32 dst_sel:DWORD dst_unused:UNUSED_PAD src0_sel:WORD_1
	v_cvt_f32_f16_e32 v33, v33
	v_cvt_f32_f16_sdwa v26, v27 dst_sel:DWORD dst_unused:UNUSED_PAD src0_sel:WORD_1
	v_cvt_f32_f16_e32 v27, v28
	v_cvt_f32_f16_sdwa v52, v28 dst_sel:DWORD dst_unused:UNUSED_PAD src0_sel:WORD_1
	v_cvt_f32_f16_e32 v53, v29
	v_cvt_f32_f16_e32 v28, v22
	v_cvt_f32_f16_sdwa v54, v22 dst_sel:DWORD dst_unused:UNUSED_PAD src0_sel:WORD_1
	v_cvt_f32_f16_e32 v55, v23
	v_cvt_f32_f16_sdwa v22, v23 dst_sel:DWORD dst_unused:UNUSED_PAD src0_sel:WORD_1
	v_cvt_f32_f16_e32 v23, v24
	v_cvt_f32_f16_sdwa v56, v24 dst_sel:DWORD dst_unused:UNUSED_PAD src0_sel:WORD_1
	v_cvt_f32_f16_e32 v57, v25
	v_cvt_f32_f16_sdwa v29, v29 dst_sel:DWORD dst_unused:UNUSED_PAD src0_sel:WORD_1
	v_cvt_f32_f16_sdwa v25, v25 dst_sel:DWORD dst_unused:UNUSED_PAD src0_sel:WORD_1
	v_cvt_f32_f16_e32 v24, v38
	v_cvt_f32_f16_sdwa v60, v19 dst_sel:DWORD dst_unused:UNUSED_PAD src0_sel:WORD_1
	v_cvt_f32_f16_e32 v61, v20
	v_cvt_f32_f16_e32 v38, v18
	v_cvt_f32_f16_e32 v59, v19
	v_mul_f32_e32 v19, 0x3b800000, v36
	v_pk_mul_f32 v[42:43], v[42:43], s[24:25] op_sel_hi:[1,0]
	v_pk_mul_f32 v[12:13], v[12:13], s[24:25] op_sel_hi:[1,0]
	v_pk_mul_f32 v[50:51], v[50:51], s[24:25] op_sel_hi:[1,0]
	v_pk_mul_f32 v[44:45], v[44:45], s[24:25] op_sel_hi:[1,0]
	v_pk_mul_f32 v[46:47], v[46:47], s[24:25] op_sel_hi:[1,0]
	v_pk_mul_f32 v[48:49], v[48:49], s[24:25] op_sel_hi:[1,0]
	v_pk_mul_f32 v[30:31], v[30:31], s[24:25] op_sel_hi:[1,0]
	v_mul_f32_e32 v11, 0x3b800000, v11
	v_pk_mul_f32 v[32:33], v[32:33], s[24:25] op_sel_hi:[1,0]
	v_pk_mul_f32 v[26:27], v[26:27], s[24:25] op_sel_hi:[1,0]
	v_pk_mul_f32 v[52:53], v[52:53], s[24:25] op_sel_hi:[1,0]
	v_pk_mul_f32 v[54:55], v[54:55], s[24:25] op_sel_hi:[1,0]
	v_pk_mul_f32 v[22:23], v[22:23], s[24:25] op_sel_hi:[1,0]
	v_pk_mul_f32 v[56:57], v[56:57], s[24:25] op_sel_hi:[1,0]
	ds_write2_b32 v131, v42, v43 offset0:1 offset1:2
	ds_write2_b32 v131, v44, v45 offset0:3 offset1:4
	ds_write2_b32 v131, v46, v47 offset0:5 offset1:6
	ds_write2_b32 v131, v12, v13 offset0:7 offset1:8
	ds_write2_b32 v131, v48, v49 offset0:9 offset1:10
	ds_write2_b32 v131, v30, v31 offset0:11 offset1:12
	ds_write2_b32 v131, v32, v33 offset0:13 offset1:14
	v_pk_mov_b32 v[12:13], v[50:51], v[50:51] op_sel:[1,0]
	v_pk_mul_f32 v[28:29], v[28:29], s[24:25] op_sel_hi:[1,0]
	v_pk_mul_f32 v[24:25], v[24:25], s[24:25] op_sel_hi:[1,0]
	v_pk_mov_b32 v[26:27], v[26:27], v[26:27] op_sel:[1,0]
	v_pk_mov_b32 v[30:31], v[52:53], v[52:53] op_sel:[1,0]
	v_pk_mov_b32 v[32:33], v[54:55], v[54:55] op_sel:[1,0]
	v_pk_mov_b32 v[22:23], v[22:23], v[22:23] op_sel:[1,0]
	v_pk_mov_b32 v[42:43], v[56:57], v[56:57] op_sel:[1,0]
	v_cvt_f32_f16_sdwa v58, v18 dst_sel:DWORD dst_unused:UNUSED_PAD src0_sel:WORD_1
	v_mul_f32_e32 v36, 0x3b800000, v38
	s_mov_b32 s6, s65
	v_pk_mul_f32 v[58:59], v[58:59], s[24:25] op_sel_hi:[1,0]
	v_fma_mix_f32 v10, v10, s24, v40 op_sel_hi:[1,0,0]
	s_nop 0
	v_cndmask_b32_e64 v10, v19, v10, s[4:5]
	ds_write2_b32 v131, v10, v11 offset1:15
	ds_write_b64 v132, v[12:13] offset:32824
	ds_write_b64 v133, v[26:27] offset:32824
	ds_write_b64 v134, v[30:31] offset:32824
	ds_write_b64 v135, v[28:29] offset:32824
	ds_write_b64 v136, v[32:33] offset:32824
	ds_write_b64 v137, v[22:23] offset:32824
	ds_write_b64 v138, v[42:43] offset:32824
	ds_write_b64 v139, v[24:25] offset:32824
	v_cvt_f32_f16_sdwa v10, v20 dst_sel:DWORD dst_unused:UNUSED_PAD src0_sel:WORD_1
	v_cvt_f32_f16_e32 v11, v21
	v_pk_mul_f32 v[12:13], v[60:61], s[24:25] op_sel_hi:[1,0]
	v_fma_mix_f32 v18, v18, s24, v41 op_sel_hi:[1,0,0]
	ds_write2_b32 v140, v12, v13 offset0:3 offset1:4
	v_cvt_f32_f16_sdwa v12, v21 dst_sel:DWORD dst_unused:UNUSED_PAD src0_sel:WORD_1
	v_cvt_f32_f16_e32 v13, v14
	v_cndmask_b32_e64 v36, v36, v18, s[4:5]
	v_cvt_f32_f16_sdwa v18, v14 dst_sel:DWORD dst_unused:UNUSED_PAD src0_sel:WORD_1
	v_cvt_f32_f16_e32 v19, v15
	v_pk_mul_f32 v[10:11], v[10:11], s[24:25] op_sel_hi:[1,0]
	ds_write2_b32 v140, v10, v11 offset0:5 offset1:6
	v_pk_mul_f32 v[10:11], v[12:13], s[24:25] op_sel_hi:[1,0]
	ds_write2_b32 v140, v10, v11 offset0:7 offset1:8
	v_pk_mul_f32 v[10:11], v[18:19], s[24:25] op_sel_hi:[1,0]
	ds_write2_b32 v140, v10, v11 offset0:9 offset1:10
	v_cvt_f32_f16_sdwa v10, v15 dst_sel:DWORD dst_unused:UNUSED_PAD src0_sel:WORD_1
	v_cvt_f32_f16_e32 v11, v16
	v_cvt_f32_f16_sdwa v12, v16 dst_sel:DWORD dst_unused:UNUSED_PAD src0_sel:WORD_1
	v_cvt_f32_f16_e32 v13, v17
	v_cvt_f32_f16_sdwa v14, v17 dst_sel:DWORD dst_unused:UNUSED_PAD src0_sel:WORD_1
	v_pk_mul_f32 v[10:11], v[10:11], s[24:25] op_sel_hi:[1,0]
	ds_write2_b32 v140, v10, v11 offset0:11 offset1:12
	v_pk_mul_f32 v[10:11], v[12:13], s[24:25] op_sel_hi:[1,0]
	ds_write2_b32 v140, v10, v11 offset0:13 offset1:14
	v_cvt_f32_f16_sdwa v10, v6 dst_sel:DWORD dst_unused:UNUSED_PAD src0_sel:WORD_1
	v_cvt_f32_f16_e32 v11, v7
	v_cvt_f32_f16_sdwa v6, v7 dst_sel:DWORD dst_unused:UNUSED_PAD src0_sel:WORD_1
	v_cvt_f32_f16_e32 v7, v8
	v_mul_f32_e32 v14, 0x3b800000, v14
	v_pk_mul_f32 v[10:11], v[10:11], s[24:25] op_sel_hi:[1,0]
	ds_write2_b32 v140, v58, v59 offset0:1 offset1:2
	v_pk_mov_b32 v[10:11], v[10:11], v[10:11] op_sel:[1,0]
	ds_write2_b32 v140, v36, v14 offset1:15
	ds_write_b64 v141, v[10:11] offset:32824
	v_cvt_f32_f16_sdwa v10, v8 dst_sel:DWORD dst_unused:UNUSED_PAD src0_sel:WORD_1
	v_cvt_f32_f16_e32 v11, v9
	v_pk_mul_f32 v[6:7], v[6:7], s[24:25] op_sel_hi:[1,0]
	s_nop 0
	v_pk_mov_b32 v[6:7], v[6:7], v[6:7] op_sel:[1,0]
	ds_write_b64 v142, v[6:7] offset:32824
	v_cvt_f32_f16_sdwa v7, v9 dst_sel:DWORD dst_unused:UNUSED_PAD src0_sel:WORD_1
	v_pk_mul_f32 v[8:9], v[10:11], s[24:25] op_sel_hi:[1,0]
	v_cvt_f32_f16_e32 v6, v2
	v_pk_mov_b32 v[8:9], v[8:9], v[8:9] op_sel:[1,0]
	ds_write_b64 v143, v[8:9] offset:32824
	v_cvt_f32_f16_sdwa v8, v2 dst_sel:DWORD dst_unused:UNUSED_PAD src0_sel:WORD_1
	v_cvt_f32_f16_e32 v9, v3
	v_cvt_f32_f16_sdwa v2, v3 dst_sel:DWORD dst_unused:UNUSED_PAD src0_sel:WORD_1
	v_cvt_f32_f16_e32 v3, v4
	v_pk_mul_f32 v[6:7], v[6:7], s[24:25] op_sel_hi:[1,0]
	ds_write_b64 v144, v[6:7] offset:32824
	v_pk_mul_f32 v[6:7], v[8:9], s[24:25] op_sel_hi:[1,0]
	v_pk_mul_f32 v[2:3], v[2:3], s[24:25] op_sel_hi:[1,0]
	v_pk_mov_b32 v[6:7], v[6:7], v[6:7] op_sel:[1,0]
	ds_write_b64 v145, v[6:7] offset:32824
	v_pk_mov_b32 v[2:3], v[2:3], v[2:3] op_sel:[1,0]
	v_cvt_f32_f16_sdwa v6, v4 dst_sel:DWORD dst_unused:UNUSED_PAD src0_sel:WORD_1
	v_cvt_f32_f16_e32 v7, v5
	ds_write_b64 v148, v[2:3] offset:32824
	v_cvt_f32_f16_sdwa v3, v5 dst_sel:DWORD dst_unused:UNUSED_PAD src0_sel:WORD_1
	v_cvt_f32_f16_e32 v2, v39
	v_pk_mul_f32 v[4:5], v[6:7], s[24:25] op_sel_hi:[1,0]
	v_pk_mul_f32 v[2:3], v[2:3], s[24:25] op_sel_hi:[1,0]
	v_pk_mov_b32 v[4:5], v[4:5], v[4:5] op_sel:[1,0]
	ds_write_b64 v149, v[4:5] offset:32824
	ds_write_b64 v150, v[2:3] offset:32824
	v_mov_b32_e32 v2, v130
	s_waitcnt lgkmcnt(0)
	s_barrier
	s_nop 0
	v_and_b32_e32 v3, 0xff, v2
	v_lshlrev_b32_e32 v4, 5, v2
	v_and_or_b32 v3, v4, s29, v3
	v_ashrrev_i32_e32 v4, 5, v3
	v_lshlrev_b32_e32 v3, 3, v3
	v_lshlrev_b32_e32 v6, 3, v4
	v_add3_u32 v36, 0, v3, v6
	ds_read_b64 v[154:155], v36
	ds_read_b64 v[156:157], v36 offset:2112
	ds_read_b64 v[158:159], v36 offset:4224
	ds_read_b64 v[160:161], v36 offset:6336
	ds_read_b64 v[162:163], v36 offset:8448
	ds_read_b64 v[164:165], v36 offset:10560
	ds_read_b64 v[166:167], v36 offset:12672
	ds_read_b64 v[168:169], v36 offset:14784
	ds_read_b64 v[170:171], v36 offset:16896
	ds_read_b64 v[172:173], v36 offset:19008
	ds_read_b64 v[174:175], v36 offset:21120
	ds_read_b64 v[176:177], v36 offset:23232
	ds_read_b64 v[178:179], v36 offset:25344
	ds_read_b64 v[180:181], v36 offset:27456
	ds_read_b64 v[182:183], v36 offset:29568
	ds_read_b64 v[184:185], v36 offset:31680
	ds_read_b64 v[186:187], v36 offset:33792
	ds_read_b64 v[188:189], v36 offset:35904
	ds_read_b64 v[190:191], v36 offset:38016
	ds_read_b64 v[192:193], v36 offset:40128
	ds_read_b64 v[194:195], v36 offset:42240
	ds_read_b64 v[196:197], v36 offset:44352
	ds_read_b64 v[198:199], v36 offset:46464
	ds_read_b64 v[204:205], v36 offset:48576
	ds_read_b64 v[206:207], v36 offset:50688
	ds_read_b64 v[208:209], v36 offset:52800
	ds_read_b64 v[210:211], v36 offset:54912
	ds_read_b64 v[212:213], v36 offset:57024
	ds_read_b64 v[214:215], v36 offset:59136
	ds_read_b64 v[216:217], v36 offset:61248
	ds_read_b64 v[218:219], v36 offset:63360
	ds_read_b64 v[220:221], v36 offset:65472
	s_waitcnt lgkmcnt(14)
	v_pk_add_f32 v[222:223], v[154:155], v[186:187]
	v_pk_add_f32 v[154:155], v[154:155], v[186:187] neg_lo:[0,1] neg_hi:[0,1]
	v_pk_add_f32 v[186:187], v[156:157], v[188:189]
	v_pk_add_f32 v[156:157], v[156:157], v[188:189] neg_lo:[0,1] neg_hi:[0,1]
	v_cvt_f32_ubyte0_e32 v2, v2
	v_pk_mul_f32 v[188:189], v[156:157], s[40:41]
	v_mul_f32_e32 v5, 0x39000000, v2
	v_pk_fma_f32 v[156:157], v[156:157], s[36:37], v[188:189] op_sel:[0,0,1] op_sel_hi:[1,0,0]
	s_waitcnt lgkmcnt(13)
	v_pk_add_f32 v[188:189], v[158:159], v[190:191]
	v_pk_add_f32 v[158:159], v[158:159], v[190:191] neg_lo:[0,1] neg_hi:[0,1]
	v_sin_f32_e32 v2, v5
	v_pk_mul_f32 v[190:191], v[158:159], s[44:45]
	v_cos_f32_e32 v4, v5
	v_pk_fma_f32 v[158:159], v[158:159], s[42:43], v[190:191] op_sel:[0,0,1] op_sel_hi:[1,0,0]
	s_waitcnt lgkmcnt(12)
	v_pk_add_f32 v[190:191], v[160:161], v[192:193]
	v_pk_add_f32 v[160:161], v[160:161], v[192:193] neg_lo:[0,1] neg_hi:[0,1]
	v_xor_b32_e32 v5, 0x80000000, v2
	v_pk_mul_f32 v[192:193], v[160:161], s[62:63]
	v_mov_b32_e32 v3, v5
	v_pk_fma_f32 v[160:161], v[160:161], s[50:51], v[192:193] op_sel:[0,0,1] op_sel_hi:[1,0,0]
	s_waitcnt lgkmcnt(11)
	v_pk_add_f32 v[192:193], v[162:163], v[194:195]
	v_pk_add_f32 v[162:163], v[162:163], v[194:195] neg_lo:[0,1] neg_hi:[0,1]
	v_pk_mul_f32 v[6:7], v[4:5], v[2:3] op_sel:[1,0] op_sel_hi:[0,1]
	v_pk_mul_f32 v[194:195], v[162:163], s[68:69]
	v_pk_fma_f32 v[6:7], v[4:5], v[4:5], v[6:7] op_sel_hi:[1,0,1]
	v_pk_fma_f32 v[162:163], v[162:163], s[64:65], v[194:195] op_sel:[0,0,1] op_sel_hi:[1,0,0]
	s_waitcnt lgkmcnt(10)
	v_pk_add_f32 v[194:195], v[164:165], v[196:197]
	v_pk_add_f32 v[164:165], v[164:165], v[196:197] neg_lo:[0,1] neg_hi:[0,1]
	v_pk_mul_f32 v[12:13], v[6:7], 1.0 op_sel:[1,0] op_sel_hi:[1,0] neg_lo:[1,0]
	v_pk_mul_f32 v[196:197], v[164:165], s[70:71]
	s_nop 0
	v_pk_fma_f32 v[164:165], v[164:165], s[46:47], v[196:197] op_sel:[0,0,1] op_sel_hi:[1,0,0]
	s_waitcnt lgkmcnt(9)
	v_pk_add_f32 v[196:197], v[166:167], v[198:199]
	v_pk_add_f32 v[166:167], v[166:167], v[198:199] neg_lo:[0,1] neg_hi:[0,1]
	v_pk_mul_f32 v[10:11], v[6:7], v[12:13] op_sel:[1,0] op_sel_hi:[0,1]
	v_pk_mul_f32 v[198:199], v[166:167], s[76:77]
	v_pk_fma_f32 v[10:11], v[6:7], v[6:7], v[10:11] op_sel_hi:[1,0,1]
	v_pk_fma_f32 v[166:167], v[166:167], s[72:73], v[198:199] op_sel:[0,0,1] op_sel_hi:[1,0,0]
	s_waitcnt lgkmcnt(8)
	v_pk_add_f32 v[198:199], v[168:169], v[204:205]
	v_pk_add_f32 v[168:169], v[168:169], v[204:205] neg_lo:[0,1] neg_hi:[0,1]
	v_pk_mul_f32 v[14:15], v[10:11], 1.0 op_sel:[1,0] op_sel_hi:[1,0] neg_lo:[1,0]
	v_pk_mul_f32 v[204:205], v[168:169], s[26:27]
	s_nop 0
	v_pk_fma_f32 v[168:169], v[168:169], s[38:39], v[204:205] op_sel:[0,0,1] op_sel_hi:[1,0,0]
	s_waitcnt lgkmcnt(7)
	v_pk_add_f32 v[204:205], v[170:171], v[206:207]
	v_pk_add_f32 v[206:207], v[170:171], v[206:207] neg_lo:[0,1] neg_hi:[0,1]
	v_pk_mul_f32 v[26:27], v[10:11], v[14:15] op_sel:[1,0] op_sel_hi:[0,1]
	s_waitcnt lgkmcnt(6)
	v_pk_add_f32 v[170:171], v[172:173], v[208:209]
	v_pk_add_f32 v[172:173], v[172:173], v[208:209] neg_lo:[0,1] neg_hi:[0,1]
	v_pk_fma_f32 v[26:27], v[10:11], v[10:11], v[26:27] op_sel_hi:[1,0,1]
	v_pk_mul_f32 v[208:209], v[172:173], s[26:27]
	v_pk_mul_f32 v[46:47], v[14:15], v[26:27] op_sel:[0,1] op_sel_hi:[1,0]
	v_pk_fma_f32 v[172:173], v[172:173], s[38:39], v[208:209] op_sel:[0,0,1] op_sel_hi:[1,0,0] neg_lo:[1,0,0] neg_hi:[1,0,0]
	s_waitcnt lgkmcnt(5)
	v_pk_add_f32 v[208:209], v[174:175], v[210:211]
	v_pk_add_f32 v[174:175], v[174:175], v[210:211] neg_lo:[0,1] neg_hi:[0,1]
	v_pk_fma_f32 v[46:47], v[10:11], v[26:27], v[46:47] op_sel_hi:[0,1,1]
	v_pk_mul_f32 v[210:211], v[174:175], s[76:77]
	v_pk_mul_f32 v[62:63], v[14:15], v[46:47] op_sel:[0,1] op_sel_hi:[1,0]
	v_pk_fma_f32 v[174:175], v[174:175], s[72:73], v[210:211] op_sel:[0,0,1] op_sel_hi:[1,0,0] neg_lo:[1,0,0] neg_hi:[1,0,0]
	s_waitcnt lgkmcnt(4)
	v_pk_add_f32 v[210:211], v[176:177], v[212:213]
	v_pk_add_f32 v[176:177], v[176:177], v[212:213] neg_lo:[0,1] neg_hi:[0,1]
	v_pk_fma_f32 v[62:63], v[10:11], v[46:47], v[62:63] op_sel_hi:[0,1,1]
	v_pk_mul_f32 v[212:213], v[176:177], s[70:71]
	v_pk_mul_f32 v[78:79], v[14:15], v[62:63] op_sel:[0,1] op_sel_hi:[1,0]
	v_pk_fma_f32 v[176:177], v[176:177], s[46:47], v[212:213] op_sel:[0,0,1] op_sel_hi:[1,0,0] neg_lo:[1,0,0] neg_hi:[1,0,0]
	s_waitcnt lgkmcnt(3)
	v_pk_add_f32 v[212:213], v[178:179], v[214:215]
	v_pk_add_f32 v[178:179], v[178:179], v[214:215] neg_lo:[0,1] neg_hi:[0,1]
	v_pk_fma_f32 v[78:79], v[10:11], v[62:63], v[78:79] op_sel_hi:[0,1,1]
	v_pk_mul_f32 v[214:215], v[178:179], s[68:69]
	v_pk_mul_f32 v[94:95], v[14:15], v[78:79] op_sel:[0,1] op_sel_hi:[1,0]
	v_pk_fma_f32 v[178:179], v[178:179], s[64:65], v[214:215] op_sel:[0,0,1] op_sel_hi:[1,0,0] neg_lo:[1,0,0] neg_hi:[1,0,0]
	s_waitcnt lgkmcnt(2)
	v_pk_add_f32 v[214:215], v[180:181], v[216:217]
	v_pk_add_f32 v[180:181], v[180:181], v[216:217] neg_lo:[0,1] neg_hi:[0,1]
	v_pk_fma_f32 v[94:95], v[10:11], v[78:79], v[94:95] op_sel_hi:[0,1,1]
	v_pk_mul_f32 v[216:217], v[180:181], s[62:63]
	v_pk_mul_f32 v[110:111], v[14:15], v[94:95] op_sel:[0,1] op_sel_hi:[1,0]
	v_pk_fma_f32 v[180:181], v[180:181], s[50:51], v[216:217] op_sel:[0,0,1] op_sel_hi:[1,0,0] neg_lo:[1,0,0] neg_hi:[1,0,0]
	s_waitcnt lgkmcnt(1)
	v_pk_add_f32 v[216:217], v[182:183], v[218:219]
	v_pk_add_f32 v[182:183], v[182:183], v[218:219] neg_lo:[0,1] neg_hi:[0,1]
	v_pk_mul_f32 v[8:9], v[2:3], v[6:7] op_sel:[0,1] op_sel_hi:[1,0]
	v_pk_mul_f32 v[218:219], v[182:183], s[44:45]
	v_pk_fma_f32 v[110:111], v[10:11], v[94:95], v[110:111] op_sel_hi:[0,1,1]
	v_pk_fma_f32 v[182:183], v[182:183], s[42:43], v[218:219] op_sel:[0,0,1] op_sel_hi:[1,0,0] neg_lo:[1,0,0] neg_hi:[1,0,0]
	s_waitcnt lgkmcnt(0)
	v_pk_add_f32 v[218:219], v[184:185], v[220:221]
	v_pk_add_f32 v[184:185], v[184:185], v[220:221] neg_lo:[0,1] neg_hi:[0,1]
	v_pk_fma_f32 v[8:9], v[4:5], v[6:7], v[8:9] op_sel_hi:[0,1,1]
	v_pk_mul_f32 v[220:221], v[184:185], s[40:41]
	v_pk_mul_f32 v[16:17], v[2:3], v[10:11] op_sel:[0,1] op_sel_hi:[1,0]
	v_pk_fma_f32 v[184:185], v[184:185], s[36:37], v[220:221] op_sel:[0,0,1] op_sel_hi:[1,0,0] neg_lo:[1,0,0] neg_hi:[1,0,0]
	v_pk_add_f32 v[220:221], v[222:223], v[204:205]
	v_pk_add_f32 v[204:205], v[222:223], v[204:205] neg_lo:[0,1] neg_hi:[0,1]
	v_pk_add_f32 v[222:223], v[186:187], v[170:171]
	v_pk_add_f32 v[170:171], v[186:187], v[170:171] neg_lo:[0,1] neg_hi:[0,1]
	v_pk_mul_f32 v[30:31], v[2:3], v[26:27] op_sel:[0,1] op_sel_hi:[1,0]
	v_pk_mul_f32 v[186:187], v[170:171], s[44:45]
	v_pk_mul_f32 v[50:51], v[2:3], v[46:47] op_sel:[0,1] op_sel_hi:[1,0]
	v_pk_fma_f32 v[170:171], v[170:171], s[42:43], v[186:187] op_sel:[0,0,1] op_sel_hi:[1,0,0]
	v_pk_add_f32 v[186:187], v[188:189], v[208:209]
	v_pk_add_f32 v[188:189], v[188:189], v[208:209] neg_lo:[0,1] neg_hi:[0,1]
	v_pk_mul_f32 v[66:67], v[2:3], v[62:63] op_sel:[0,1] op_sel_hi:[1,0]
	v_pk_mul_f32 v[208:209], v[188:189], s[68:69]
	v_pk_mul_f32 v[82:83], v[2:3], v[78:79] op_sel:[0,1] op_sel_hi:[1,0]
	v_pk_fma_f32 v[188:189], v[188:189], s[64:65], v[208:209] op_sel:[0,0,1] op_sel_hi:[1,0,0]
	v_pk_add_f32 v[208:209], v[190:191], v[210:211]
	v_pk_add_f32 v[190:191], v[190:191], v[210:211] neg_lo:[0,1] neg_hi:[0,1]
	v_pk_mul_f32 v[98:99], v[2:3], v[94:95] op_sel:[0,1] op_sel_hi:[1,0]
	v_pk_mul_f32 v[210:211], v[190:191], s[76:77]
	v_pk_mul_f32 v[114:115], v[2:3], v[110:111] op_sel:[0,1] op_sel_hi:[1,0]
	v_pk_fma_f32 v[190:191], v[190:191], s[72:73], v[210:211] op_sel:[0,0,1] op_sel_hi:[1,0,0]
	v_pk_add_f32 v[210:211], v[192:193], v[212:213]
	v_pk_add_f32 v[212:213], v[192:193], v[212:213] neg_lo:[0,1] neg_hi:[0,1]
	v_pk_mul_f32 v[20:21], v[8:9], 1.0 op_sel:[1,0] op_sel_hi:[1,0] neg_lo:[1,0]
	v_pk_add_f32 v[192:193], v[194:195], v[214:215]
	v_pk_add_f32 v[194:195], v[194:195], v[214:215] neg_lo:[0,1] neg_hi:[0,1]
	s_nop 0
	v_pk_mul_f32 v[214:215], v[194:195], s[76:77]
	v_pk_fma_f32 v[16:17], v[4:5], v[10:11], v[16:17] op_sel_hi:[0,1,1]
	v_pk_fma_f32 v[194:195], v[194:195], s[72:73], v[214:215] op_sel:[0,0,1] op_sel_hi:[1,0,0] neg_lo:[1,0,0] neg_hi:[1,0,0]
	v_pk_add_f32 v[214:215], v[196:197], v[216:217]
	v_pk_add_f32 v[196:197], v[196:197], v[216:217] neg_lo:[0,1] neg_hi:[0,1]
	v_pk_mul_f32 v[18:19], v[12:13], v[10:11] op_sel:[0,1] op_sel_hi:[1,0]
	v_pk_mul_f32 v[216:217], v[196:197], s[68:69]
	v_pk_fma_f32 v[30:31], v[4:5], v[26:27], v[30:31] op_sel_hi:[0,1,1]
	v_pk_fma_f32 v[196:197], v[196:197], s[64:65], v[216:217] op_sel:[0,0,1] op_sel_hi:[1,0,0] neg_lo:[1,0,0] neg_hi:[1,0,0]
	v_pk_add_f32 v[216:217], v[198:199], v[218:219]
	v_pk_add_f32 v[198:199], v[198:199], v[218:219] neg_lo:[0,1] neg_hi:[0,1]
	v_pk_mul_f32 v[38:39], v[12:13], v[26:27] op_sel:[0,1] op_sel_hi:[1,0]
	v_pk_mul_f32 v[218:219], v[198:199], s[44:45]
	v_pk_fma_f32 v[50:51], v[4:5], v[46:47], v[50:51] op_sel_hi:[0,1,1]
	v_pk_fma_f32 v[198:199], v[198:199], s[42:43], v[218:219] op_sel:[0,0,1] op_sel_hi:[1,0,0] neg_lo:[1,0,0] neg_hi:[1,0,0]
	v_pk_add_f32 v[218:219], v[154:155], v[206:207] op_sel:[0,1] op_sel_hi:[1,0] neg_hi:[0,1]
	v_pk_add_f32 v[154:155], v[154:155], v[206:207] op_sel:[0,1] op_sel_hi:[1,0] neg_lo:[0,1]
	v_pk_add_f32 v[206:207], v[156:157], v[172:173]
	v_pk_add_f32 v[156:157], v[156:157], v[172:173] neg_lo:[0,1] neg_hi:[0,1]
	v_pk_mul_f32 v[54:55], v[12:13], v[46:47] op_sel:[0,1] op_sel_hi:[1,0]
	v_pk_mul_f32 v[172:173], v[156:157], s[44:45]
	v_pk_fma_f32 v[66:67], v[4:5], v[62:63], v[66:67] op_sel_hi:[0,1,1]
	v_pk_fma_f32 v[156:157], v[156:157], s[42:43], v[172:173] op_sel:[0,0,1] op_sel_hi:[1,0,0]
	v_pk_add_f32 v[172:173], v[158:159], v[174:175]
	v_pk_add_f32 v[158:159], v[158:159], v[174:175] neg_lo:[0,1] neg_hi:[0,1]
	v_pk_mul_f32 v[70:71], v[12:13], v[62:63] op_sel:[0,1] op_sel_hi:[1,0]
	v_pk_mul_f32 v[174:175], v[158:159], s[68:69]
	v_pk_fma_f32 v[82:83], v[4:5], v[78:79], v[82:83] op_sel_hi:[0,1,1]
	v_pk_fma_f32 v[158:159], v[158:159], s[64:65], v[174:175] op_sel:[0,0,1] op_sel_hi:[1,0,0]
	v_pk_add_f32 v[174:175], v[160:161], v[176:177]
	v_pk_add_f32 v[160:161], v[160:161], v[176:177] neg_lo:[0,1] neg_hi:[0,1]
	v_pk_mul_f32 v[86:87], v[12:13], v[78:79] op_sel:[0,1] op_sel_hi:[1,0]
	v_pk_mul_f32 v[176:177], v[160:161], s[76:77]
	v_pk_fma_f32 v[98:99], v[4:5], v[94:95], v[98:99] op_sel_hi:[0,1,1]
	v_pk_fma_f32 v[160:161], v[160:161], s[72:73], v[176:177] op_sel:[0,0,1] op_sel_hi:[1,0,0]
	v_pk_add_f32 v[176:177], v[162:163], v[178:179]
	v_pk_add_f32 v[178:179], v[162:163], v[178:179] neg_lo:[0,1] neg_hi:[0,1]
	v_pk_mul_f32 v[102:103], v[12:13], v[94:95] op_sel:[0,1] op_sel_hi:[1,0]
	v_pk_add_f32 v[162:163], v[164:165], v[180:181]
	v_pk_add_f32 v[164:165], v[164:165], v[180:181] neg_lo:[0,1] neg_hi:[0,1]
	v_pk_fma_f32 v[114:115], v[4:5], v[110:111], v[114:115] op_sel_hi:[0,1,1]
	v_pk_mul_f32 v[180:181], v[164:165], s[76:77]
	v_pk_mul_f32 v[118:119], v[12:13], v[110:111] op_sel:[0,1] op_sel_hi:[1,0]
	v_pk_fma_f32 v[164:165], v[164:165], s[72:73], v[180:181] op_sel:[0,0,1] op_sel_hi:[1,0,0] neg_lo:[1,0,0] neg_hi:[1,0,0]
	v_pk_add_f32 v[180:181], v[166:167], v[182:183]
	v_pk_add_f32 v[166:167], v[166:167], v[182:183] neg_lo:[0,1] neg_hi:[0,1]
	v_pk_fma_f32 v[18:19], v[6:7], v[10:11], v[18:19] op_sel_hi:[0,1,1]
	v_pk_mul_f32 v[182:183], v[166:167], s[68:69]
	v_pk_mul_f32 v[22:23], v[10:11], v[20:21] op_sel:[1,0] op_sel_hi:[0,1]
	v_pk_fma_f32 v[166:167], v[166:167], s[64:65], v[182:183] op_sel:[0,0,1] op_sel_hi:[1,0,0] neg_lo:[1,0,0] neg_hi:[1,0,0]
	v_pk_add_f32 v[182:183], v[168:169], v[184:185]
	v_pk_add_f32 v[168:169], v[168:169], v[184:185] neg_lo:[0,1] neg_hi:[0,1]
	v_pk_fma_f32 v[38:39], v[6:7], v[26:27], v[38:39] op_sel_hi:[0,1,1]
	v_pk_mul_f32 v[184:185], v[168:169], s[44:45]
	v_pk_mul_f32 v[42:43], v[20:21], v[26:27] op_sel:[0,1] op_sel_hi:[1,0]
	v_pk_fma_f32 v[168:169], v[168:169], s[42:43], v[184:185] op_sel:[0,0,1] op_sel_hi:[1,0,0] neg_lo:[1,0,0] neg_hi:[1,0,0]
	v_pk_add_f32 v[184:185], v[220:221], v[210:211]
	v_pk_add_f32 v[210:211], v[220:221], v[210:211] neg_lo:[0,1] neg_hi:[0,1]
	v_pk_add_f32 v[220:221], v[222:223], v[192:193]
	v_pk_add_f32 v[192:193], v[222:223], v[192:193] neg_lo:[0,1] neg_hi:[0,1]
	v_pk_fma_f32 v[54:55], v[6:7], v[46:47], v[54:55] op_sel_hi:[0,1,1]
	v_pk_mul_f32 v[222:223], v[192:193], s[68:69]
	v_pk_mul_f32 v[58:59], v[20:21], v[46:47] op_sel:[0,1] op_sel_hi:[1,0]
	v_pk_fma_f32 v[192:193], v[192:193], s[64:65], v[222:223] op_sel:[0,0,1] op_sel_hi:[1,0,0]
	v_pk_add_f32 v[222:223], v[186:187], v[214:215]
	v_pk_add_f32 v[214:215], v[186:187], v[214:215] neg_lo:[0,1] neg_hi:[0,1]
	v_pk_fma_f32 v[70:71], v[6:7], v[62:63], v[70:71] op_sel_hi:[0,1,1]
	v_pk_add_f32 v[186:187], v[208:209], v[216:217]
	v_pk_add_f32 v[208:209], v[208:209], v[216:217] neg_lo:[0,1] neg_hi:[0,1]
	v_pk_mul_f32 v[74:75], v[20:21], v[62:63] op_sel:[0,1] op_sel_hi:[1,0]
	v_pk_mul_f32 v[216:217], v[208:209], s[68:69]
	v_pk_fma_f32 v[86:87], v[6:7], v[78:79], v[86:87] op_sel_hi:[0,1,1]
	v_pk_fma_f32 v[208:209], v[208:209], s[64:65], v[216:217] op_sel:[0,0,1] op_sel_hi:[1,0,0] neg_lo:[1,0,0] neg_hi:[1,0,0]
	v_pk_add_f32 v[216:217], v[204:205], v[212:213] op_sel:[0,1] op_sel_hi:[1,0] neg_hi:[0,1]
	v_pk_add_f32 v[204:205], v[204:205], v[212:213] op_sel:[0,1] op_sel_hi:[1,0] neg_lo:[0,1]
	v_pk_add_f32 v[212:213], v[170:171], v[194:195]
	v_pk_add_f32 v[170:171], v[170:171], v[194:195] neg_lo:[0,1] neg_hi:[0,1]
	v_pk_mul_f32 v[90:91], v[20:21], v[78:79] op_sel:[0,1] op_sel_hi:[1,0]
	v_pk_mul_f32 v[194:195], v[170:171], s[68:69]
	v_pk_fma_f32 v[102:103], v[6:7], v[94:95], v[102:103] op_sel_hi:[0,1,1]
	v_pk_fma_f32 v[170:171], v[170:171], s[64:65], v[194:195] op_sel:[0,0,1] op_sel_hi:[1,0,0]
	v_pk_add_f32 v[194:195], v[188:189], v[196:197]
	v_pk_add_f32 v[196:197], v[188:189], v[196:197] neg_lo:[0,1] neg_hi:[0,1]
	v_pk_mul_f32 v[106:107], v[20:21], v[94:95] op_sel:[0,1] op_sel_hi:[1,0]
	v_pk_add_f32 v[188:189], v[190:191], v[198:199]
	v_pk_add_f32 v[190:191], v[190:191], v[198:199] neg_lo:[0,1] neg_hi:[0,1]
	v_pk_fma_f32 v[118:119], v[6:7], v[110:111], v[118:119] op_sel_hi:[0,1,1]
	v_pk_mul_f32 v[198:199], v[190:191], s[68:69]
	v_pk_mul_f32 v[122:123], v[20:21], v[110:111] op_sel:[0,1] op_sel_hi:[1,0]
	v_pk_fma_f32 v[190:191], v[190:191], s[64:65], v[198:199] op_sel:[0,0,1] op_sel_hi:[1,0,0] neg_lo:[1,0,0] neg_hi:[1,0,0]
	v_pk_add_f32 v[198:199], v[218:219], v[176:177]
	v_pk_add_f32 v[176:177], v[218:219], v[176:177] neg_lo:[0,1] neg_hi:[0,1]
	v_pk_add_f32 v[218:219], v[206:207], v[162:163]
	v_pk_add_f32 v[162:163], v[206:207], v[162:163] neg_lo:[0,1] neg_hi:[0,1]
	v_xor_b32_e32 v24, 0x80000000, v17
	v_pk_mul_f32 v[206:207], v[162:163], s[68:69]
	v_xor_b32_e32 v28, 0x80000000, v19
	v_pk_fma_f32 v[162:163], v[162:163], s[64:65], v[206:207] op_sel:[0,0,1] op_sel_hi:[1,0,0]
	v_pk_add_f32 v[206:207], v[172:173], v[180:181]
	v_pk_add_f32 v[180:181], v[172:173], v[180:181] neg_lo:[0,1] neg_hi:[0,1]
	v_pk_fma_f32 v[22:23], v[10:11], v[8:9], v[22:23] op_sel_hi:[1,0,1]
	v_pk_add_f32 v[172:173], v[174:175], v[182:183]
	v_pk_add_f32 v[174:175], v[174:175], v[182:183] neg_lo:[0,1] neg_hi:[0,1]
	v_pk_fma_f32 v[42:43], v[8:9], v[26:27], v[42:43] op_sel_hi:[0,1,1]
	v_pk_mul_f32 v[182:183], v[174:175], s[68:69]
	v_pk_fma_f32 v[58:59], v[8:9], v[46:47], v[58:59] op_sel_hi:[0,1,1]
	v_pk_fma_f32 v[174:175], v[174:175], s[64:65], v[182:183] op_sel:[0,0,1] op_sel_hi:[1,0,0] neg_lo:[1,0,0] neg_hi:[1,0,0]
	v_pk_add_f32 v[182:183], v[154:155], v[178:179] op_sel:[0,1] op_sel_hi:[1,0] neg_hi:[0,1]
	v_pk_add_f32 v[154:155], v[154:155], v[178:179] op_sel:[0,1] op_sel_hi:[1,0] neg_lo:[0,1]
	v_pk_add_f32 v[178:179], v[156:157], v[164:165]
	v_pk_add_f32 v[156:157], v[156:157], v[164:165] neg_lo:[0,1] neg_hi:[0,1]
	v_pk_fma_f32 v[74:75], v[8:9], v[62:63], v[74:75] op_sel_hi:[0,1,1]
	v_pk_mul_f32 v[164:165], v[156:157], s[68:69]
	v_pk_fma_f32 v[90:91], v[8:9], v[78:79], v[90:91] op_sel_hi:[0,1,1]
	v_pk_fma_f32 v[156:157], v[156:157], s[64:65], v[164:165] op_sel:[0,0,1] op_sel_hi:[1,0,0]
	v_pk_add_f32 v[164:165], v[158:159], v[166:167]
	v_pk_add_f32 v[166:167], v[158:159], v[166:167] neg_lo:[0,1] neg_hi:[0,1]
	v_pk_fma_f32 v[106:107], v[8:9], v[94:95], v[106:107] op_sel_hi:[0,1,1]
	v_pk_add_f32 v[158:159], v[160:161], v[168:169]
	v_pk_add_f32 v[160:161], v[160:161], v[168:169] neg_lo:[0,1] neg_hi:[0,1]
	v_pk_fma_f32 v[122:123], v[8:9], v[110:111], v[122:123] op_sel_hi:[0,1,1]
	v_pk_mul_f32 v[168:169], v[160:161], s[68:69]
	v_mov_b32_e32 v25, v17
	v_pk_fma_f32 v[160:161], v[160:161], s[64:65], v[168:169] op_sel:[0,0,1] op_sel_hi:[1,0,0] neg_lo:[1,0,0] neg_hi:[1,0,0]
	v_pk_add_f32 v[168:169], v[184:185], v[222:223]
	v_pk_add_f32 v[184:185], v[184:185], v[222:223] neg_lo:[0,1] neg_hi:[0,1]
	v_pk_add_f32 v[222:223], v[220:221], v[186:187]
	v_pk_add_f32 v[220:221], v[220:221], v[186:187] neg_lo:[0,1] neg_hi:[0,1]
	v_mov_b32_e32 v29, v19
	v_pk_add_f32 v[186:187], v[210:211], v[214:215] op_sel:[0,1] op_sel_hi:[1,0] neg_hi:[0,1]
	v_pk_add_f32 v[210:211], v[210:211], v[214:215] op_sel:[0,1] op_sel_hi:[1,0] neg_lo:[0,1]
	v_pk_add_f32 v[214:215], v[192:193], v[208:209]
	v_pk_add_f32 v[208:209], v[192:193], v[208:209] neg_lo:[0,1] neg_hi:[0,1]
	v_xor_b32_e32 v32, 0x80000000, v23
	v_pk_add_f32 v[192:193], v[216:217], v[194:195]
	v_pk_add_f32 v[194:195], v[216:217], v[194:195] neg_lo:[0,1] neg_hi:[0,1]
	v_pk_add_f32 v[216:217], v[212:213], v[188:189]
	v_pk_add_f32 v[212:213], v[212:213], v[188:189] neg_lo:[0,1] neg_hi:[0,1]
	v_xor_b32_e32 v40, 0x80000000, v27
	v_pk_add_f32 v[188:189], v[204:205], v[196:197] op_sel:[0,1] op_sel_hi:[1,0] neg_hi:[0,1]
	v_pk_add_f32 v[196:197], v[204:205], v[196:197] op_sel:[0,1] op_sel_hi:[1,0] neg_lo:[0,1]
	v_pk_add_f32 v[204:205], v[170:171], v[190:191]
	v_pk_add_f32 v[190:191], v[170:171], v[190:191] neg_lo:[0,1] neg_hi:[0,1]
	v_xor_b32_e32 v44, 0x80000000, v31
	v_pk_add_f32 v[170:171], v[198:199], v[206:207]
	v_pk_add_f32 v[198:199], v[198:199], v[206:207] neg_lo:[0,1] neg_hi:[0,1]
	v_pk_add_f32 v[206:207], v[218:219], v[172:173]
	v_pk_add_f32 v[218:219], v[218:219], v[172:173] neg_lo:[0,1] neg_hi:[0,1]
	v_xor_b32_e32 v48, 0x80000000, v39
	v_pk_add_f32 v[172:173], v[176:177], v[180:181] op_sel:[0,1] op_sel_hi:[1,0] neg_hi:[0,1]
	v_pk_add_f32 v[176:177], v[176:177], v[180:181] op_sel:[0,1] op_sel_hi:[1,0] neg_lo:[0,1]
	v_pk_add_f32 v[180:181], v[162:163], v[174:175]
	v_pk_add_f32 v[174:175], v[162:163], v[174:175] neg_lo:[0,1] neg_hi:[0,1]
	v_mov_b32_e32 v33, v23
	v_pk_add_f32 v[162:163], v[182:183], v[164:165]
	v_pk_add_f32 v[164:165], v[182:183], v[164:165] neg_lo:[0,1] neg_hi:[0,1]
	v_pk_add_f32 v[182:183], v[178:179], v[158:159]
	v_pk_add_f32 v[178:179], v[178:179], v[158:159] neg_lo:[0,1] neg_hi:[0,1]
	v_mov_b32_e32 v41, v27
	v_pk_add_f32 v[158:159], v[154:155], v[166:167] op_sel:[0,1] op_sel_hi:[1,0] neg_hi:[0,1]
	v_pk_add_f32 v[154:155], v[154:155], v[166:167] op_sel:[0,1] op_sel_hi:[1,0] neg_lo:[0,1]
	v_pk_add_f32 v[166:167], v[156:157], v[160:161]
	v_pk_add_f32 v[156:157], v[156:157], v[160:161] neg_lo:[0,1] neg_hi:[0,1]
	v_mov_b32_e32 v45, v31
	v_pk_mul_f32 v[160:161], v[156:157], 1.0 op_sel:[1,0] op_sel_hi:[0,0] neg_hi:[1,0]
	v_pk_add_f32 v[156:157], v[168:169], v[222:223]
	v_pk_add_f32 v[168:169], v[168:169], v[222:223] neg_lo:[0,1] neg_hi:[0,1]
	v_pk_add_f32 v[222:223], v[184:185], v[220:221] op_sel:[0,1] op_sel_hi:[1,0] neg_hi:[0,1]
	v_pk_add_f32 v[184:185], v[184:185], v[220:221] op_sel:[0,1] op_sel_hi:[1,0] neg_lo:[0,1]
	v_pk_add_f32 v[220:221], v[186:187], v[214:215]
	v_pk_add_f32 v[186:187], v[186:187], v[214:215] neg_lo:[0,1] neg_hi:[0,1]
	v_pk_add_f32 v[214:215], v[210:211], v[208:209] op_sel:[0,1] op_sel_hi:[1,0] neg_hi:[0,1]
	v_pk_add_f32 v[208:209], v[210:211], v[208:209] op_sel:[0,1] op_sel_hi:[1,0] neg_lo:[0,1]
	v_pk_add_f32 v[210:211], v[192:193], v[216:217]
	v_pk_add_f32 v[192:193], v[192:193], v[216:217] neg_lo:[0,1] neg_hi:[0,1]
	v_pk_add_f32 v[216:217], v[194:195], v[212:213] op_sel:[0,1] op_sel_hi:[1,0] neg_hi:[0,1]
	v_pk_add_f32 v[194:195], v[194:195], v[212:213] op_sel:[0,1] op_sel_hi:[1,0] neg_lo:[0,1]
	v_pk_add_f32 v[212:213], v[188:189], v[204:205]
	v_pk_add_f32 v[188:189], v[188:189], v[204:205] neg_lo:[0,1] neg_hi:[0,1]
	v_pk_add_f32 v[204:205], v[196:197], v[190:191] op_sel:[0,1] op_sel_hi:[1,0] neg_hi:[0,1]
	v_pk_add_f32 v[190:191], v[196:197], v[190:191] op_sel:[0,1] op_sel_hi:[1,0] neg_lo:[0,1]
	v_pk_add_f32 v[196:197], v[170:171], v[206:207]
	v_pk_add_f32 v[170:171], v[170:171], v[206:207] neg_lo:[0,1] neg_hi:[0,1]
	v_pk_mul_f32 v[2:3], v[2:3], v[196:197] op_sel:[0,1] op_sel_hi:[1,0]
	v_pk_add_f32 v[206:207], v[198:199], v[218:219] op_sel:[0,1] op_sel_hi:[1,0] neg_hi:[0,1]
	v_pk_add_f32 v[198:199], v[198:199], v[218:219] op_sel:[0,1] op_sel_hi:[1,0] neg_lo:[0,1]
	v_pk_add_f32 v[218:219], v[172:173], v[180:181]
	v_pk_add_f32 v[172:173], v[172:173], v[180:181] neg_lo:[0,1] neg_hi:[0,1]
	v_pk_add_f32 v[180:181], v[176:177], v[174:175] op_sel:[0,1] op_sel_hi:[1,0] neg_hi:[0,1]
	v_pk_add_f32 v[174:175], v[176:177], v[174:175] op_sel:[0,1] op_sel_hi:[1,0] neg_lo:[0,1]
	v_pk_add_f32 v[176:177], v[162:163], v[182:183]
	v_pk_fma_f32 v[2:3], v[4:5], v[196:197], v[2:3] op_sel_hi:[0,1,1]
	v_pk_mul_f32 v[4:5], v[12:13], v[210:211] op_sel:[0,1] op_sel_hi:[1,0]
	v_mov_b32_e32 v49, v39
	v_pk_fma_f32 v[4:5], v[6:7], v[210:211], v[4:5] op_sel_hi:[0,1,1]
	v_pk_mul_f32 v[6:7], v[20:21], v[176:177] op_sel:[0,1] op_sel_hi:[1,0]
	v_pk_add_f32 v[162:163], v[162:163], v[182:183] neg_lo:[0,1] neg_hi:[0,1]
	v_pk_fma_f32 v[6:7], v[8:9], v[176:177], v[6:7] op_sel_hi:[0,1,1]
	v_pk_mul_f32 v[8:9], v[14:15], v[220:221] op_sel:[0,1] op_sel_hi:[1,0]
	v_pk_add_f32 v[182:183], v[164:165], v[178:179] op_sel:[0,1] op_sel_hi:[1,0] neg_hi:[0,1]
	v_pk_add_f32 v[164:165], v[164:165], v[178:179] op_sel:[0,1] op_sel_hi:[1,0] neg_lo:[0,1]
	v_pk_add_f32 v[178:179], v[158:159], v[166:167]
	v_pk_fma_f32 v[8:9], v[10:11], v[220:221], v[8:9] op_sel_hi:[0,1,1]
	v_pk_mul_f32 v[10:11], v[24:25], v[218:219] op_sel:[0,1] op_sel_hi:[1,0]
	v_pk_mul_f32 v[12:13], v[28:29], v[212:213] op_sel:[0,1] op_sel_hi:[1,0]
	v_xor_b32_e32 v52, 0x80000000, v43
	v_xor_b32_e32 v56, 0x80000000, v47
	v_xor_b32_e32 v60, 0x80000000, v51
	v_xor_b32_e32 v64, 0x80000000, v55
	v_xor_b32_e32 v68, 0x80000000, v59
	v_xor_b32_e32 v72, 0x80000000, v63
	v_xor_b32_e32 v76, 0x80000000, v67
	v_mov_b32_e32 v53, v43
	v_mov_b32_e32 v57, v47
	v_mov_b32_e32 v61, v51
	v_mov_b32_e32 v65, v55
	v_mov_b32_e32 v69, v59
	v_mov_b32_e32 v73, v63
	v_mov_b32_e32 v77, v67
	v_pk_add_f32 v[158:159], v[158:159], v[166:167] neg_lo:[0,1] neg_hi:[0,1]
	v_pk_add_f32 v[166:167], v[154:155], v[160:161]
	v_pk_fma_f32 v[10:11], v[16:17], v[218:219], v[10:11] op_sel_hi:[0,1,1]
	v_pk_fma_f32 v[12:13], v[18:19], v[212:213], v[12:13] op_sel_hi:[0,1,1]
	v_pk_mul_f32 v[14:15], v[32:33], v[178:179] op_sel:[0,1] op_sel_hi:[1,0]
	v_pk_mul_f32 v[16:17], v[40:41], v[222:223] op_sel:[0,1] op_sel_hi:[1,0]
	v_pk_mul_f32 v[18:19], v[44:45], v[206:207] op_sel:[0,1] op_sel_hi:[1,0]
	v_pk_mul_f32 v[20:21], v[48:49], v[216:217] op_sel:[0,1] op_sel_hi:[1,0]
	v_xor_b32_e32 v80, 0x80000000, v71
	v_xor_b32_e32 v84, 0x80000000, v75
	v_xor_b32_e32 v88, 0x80000000, v79
	v_xor_b32_e32 v92, 0x80000000, v83
	v_xor_b32_e32 v96, 0x80000000, v87
	v_xor_b32_e32 v100, 0x80000000, v91
	v_xor_b32_e32 v104, 0x80000000, v95
	v_xor_b32_e32 v108, 0x80000000, v99
	v_xor_b32_e32 v112, 0x80000000, v103
	v_xor_b32_e32 v116, 0x80000000, v107
	v_xor_b32_e32 v120, 0x80000000, v111
	v_xor_b32_e32 v124, 0x80000000, v115
	v_xor_b32_e32 v126, 0x80000000, v119
	v_xor_b32_e32 v128, 0x80000000, v123
	v_mov_b32_e32 v81, v71
	v_mov_b32_e32 v85, v75
	v_mov_b32_e32 v89, v79
	v_mov_b32_e32 v93, v83
	v_mov_b32_e32 v97, v87
	v_mov_b32_e32 v101, v91
	v_mov_b32_e32 v105, v95
	v_mov_b32_e32 v109, v99
	v_mov_b32_e32 v113, v103
	v_mov_b32_e32 v117, v107
	v_mov_b32_e32 v121, v111
	v_mov_b32_e32 v125, v115
	v_mov_b32_e32 v127, v119
	v_mov_b32_e32 v129, v123
	v_pk_add_f32 v[154:155], v[154:155], v[160:161] neg_lo:[0,1] neg_hi:[0,1]
	v_pk_fma_f32 v[14:15], v[22:23], v[178:179], v[14:15] op_sel_hi:[0,1,1]
	v_pk_fma_f32 v[16:17], v[26:27], v[222:223], v[16:17] op_sel_hi:[0,1,1]
	v_pk_fma_f32 v[18:19], v[30:31], v[206:207], v[18:19] op_sel_hi:[0,1,1]
	v_pk_fma_f32 v[20:21], v[38:39], v[216:217], v[20:21] op_sel_hi:[0,1,1]
	v_pk_mul_f32 v[22:23], v[52:53], v[182:183] op_sel:[0,1] op_sel_hi:[1,0]
	v_pk_mul_f32 v[24:25], v[56:57], v[214:215] op_sel:[0,1] op_sel_hi:[1,0]
	v_pk_mul_f32 v[26:27], v[60:61], v[180:181] op_sel:[0,1] op_sel_hi:[1,0]
	v_pk_mul_f32 v[28:29], v[64:65], v[204:205] op_sel:[0,1] op_sel_hi:[1,0]
	v_pk_mul_f32 v[30:31], v[68:69], v[166:167] op_sel:[0,1] op_sel_hi:[1,0]
	v_pk_mul_f32 v[32:33], v[72:73], v[168:169] op_sel:[0,1] op_sel_hi:[1,0]
	v_pk_mul_f32 v[38:39], v[76:77], v[170:171] op_sel:[0,1] op_sel_hi:[1,0]
	v_pk_fma_f32 v[22:23], v[42:43], v[182:183], v[22:23] op_sel_hi:[0,1,1]
	v_pk_fma_f32 v[24:25], v[46:47], v[214:215], v[24:25] op_sel_hi:[0,1,1]
	v_pk_fma_f32 v[26:27], v[50:51], v[180:181], v[26:27] op_sel_hi:[0,1,1]
	v_pk_fma_f32 v[28:29], v[54:55], v[204:205], v[28:29] op_sel_hi:[0,1,1]
	v_pk_fma_f32 v[30:31], v[58:59], v[166:167], v[30:31] op_sel_hi:[0,1,1]
	v_pk_fma_f32 v[32:33], v[62:63], v[168:169], v[32:33] op_sel_hi:[0,1,1]
	v_pk_fma_f32 v[38:39], v[66:67], v[170:171], v[38:39] op_sel_hi:[0,1,1]
	v_pk_mul_f32 v[40:41], v[80:81], v[192:193] op_sel:[0,1] op_sel_hi:[1,0]
	v_pk_mul_f32 v[42:43], v[84:85], v[162:163] op_sel:[0,1] op_sel_hi:[1,0]
	v_pk_mul_f32 v[44:45], v[88:89], v[186:187] op_sel:[0,1] op_sel_hi:[1,0]
	v_pk_mul_f32 v[46:47], v[92:93], v[172:173] op_sel:[0,1] op_sel_hi:[1,0]
	v_pk_mul_f32 v[48:49], v[96:97], v[188:189] op_sel:[0,1] op_sel_hi:[1,0]
	v_pk_mul_f32 v[50:51], v[100:101], v[158:159] op_sel:[0,1] op_sel_hi:[1,0]
	v_pk_mul_f32 v[52:53], v[104:105], v[184:185] op_sel:[0,1] op_sel_hi:[1,0]
	v_pk_mul_f32 v[54:55], v[108:109], v[198:199] op_sel:[0,1] op_sel_hi:[1,0]
	v_pk_mul_f32 v[56:57], v[112:113], v[194:195] op_sel:[0,1] op_sel_hi:[1,0]
	v_pk_mul_f32 v[58:59], v[116:117], v[164:165] op_sel:[0,1] op_sel_hi:[1,0]
	v_pk_mul_f32 v[60:61], v[120:121], v[208:209] op_sel:[0,1] op_sel_hi:[1,0]
	v_pk_mul_f32 v[62:63], v[124:125], v[174:175] op_sel:[0,1] op_sel_hi:[1,0]
	v_pk_mul_f32 v[64:65], v[126:127], v[190:191] op_sel:[0,1] op_sel_hi:[1,0]
	v_pk_mul_f32 v[66:67], v[128:129], v[154:155] op_sel:[0,1] op_sel_hi:[1,0]
	v_pk_fma_f32 v[40:41], v[70:71], v[192:193], v[40:41] op_sel_hi:[0,1,1]
	v_pk_fma_f32 v[42:43], v[74:75], v[162:163], v[42:43] op_sel_hi:[0,1,1]
	v_pk_fma_f32 v[44:45], v[78:79], v[186:187], v[44:45] op_sel_hi:[0,1,1]
	v_pk_fma_f32 v[46:47], v[82:83], v[172:173], v[46:47] op_sel_hi:[0,1,1]
	v_pk_fma_f32 v[48:49], v[86:87], v[188:189], v[48:49] op_sel_hi:[0,1,1]
	v_pk_fma_f32 v[50:51], v[90:91], v[158:159], v[50:51] op_sel_hi:[0,1,1]
	v_pk_fma_f32 v[52:53], v[94:95], v[184:185], v[52:53] op_sel_hi:[0,1,1]
	v_pk_fma_f32 v[54:55], v[98:99], v[198:199], v[54:55] op_sel_hi:[0,1,1]
	v_pk_fma_f32 v[56:57], v[102:103], v[194:195], v[56:57] op_sel_hi:[0,1,1]
	v_pk_fma_f32 v[58:59], v[106:107], v[164:165], v[58:59] op_sel_hi:[0,1,1]
	v_pk_fma_f32 v[60:61], v[110:111], v[208:209], v[60:61] op_sel_hi:[0,1,1]
	v_pk_fma_f32 v[62:63], v[114:115], v[174:175], v[62:63] op_sel_hi:[0,1,1]
	v_pk_fma_f32 v[64:65], v[118:119], v[190:191], v[64:65] op_sel_hi:[0,1,1]
	v_pk_fma_f32 v[66:67], v[122:123], v[154:155], v[66:67] op_sel_hi:[0,1,1]
	ds_write_b64 v36, v[156:157]
	ds_write_b64 v36, v[32:33] offset:2112
	ds_write_b64 v36, v[16:17] offset:4224
	ds_write_b64 v36, v[52:53] offset:6336
	ds_write_b64 v36, v[8:9] offset:8448
	ds_write_b64 v36, v[44:45] offset:10560
	ds_write_b64 v36, v[24:25] offset:12672
	ds_write_b64 v36, v[60:61] offset:14784
	ds_write_b64 v36, v[4:5] offset:16896
	ds_write_b64 v36, v[40:41] offset:19008
	ds_write_b64 v36, v[20:21] offset:21120
	ds_write_b64 v36, v[56:57] offset:23232
	ds_write_b64 v36, v[12:13] offset:25344
	ds_write_b64 v36, v[48:49] offset:27456
	ds_write_b64 v36, v[28:29] offset:29568
	ds_write_b64 v36, v[64:65] offset:31680
	ds_write_b64 v36, v[2:3] offset:33792
	ds_write_b64 v36, v[38:39] offset:35904
	ds_write_b64 v36, v[18:19] offset:38016
	ds_write_b64 v36, v[54:55] offset:40128
	ds_write_b64 v36, v[10:11] offset:42240
	ds_write_b64 v36, v[46:47] offset:44352
	ds_write_b64 v36, v[26:27] offset:46464
	ds_write_b64 v36, v[62:63] offset:48576
	ds_write_b64 v36, v[6:7] offset:50688
	ds_write_b64 v36, v[42:43] offset:52800
	ds_write_b64 v36, v[22:23] offset:54912
	ds_write_b64 v36, v[58:59] offset:57024
	ds_write_b64 v36, v[14:15] offset:59136
	ds_write_b64 v36, v[50:51] offset:61248
	ds_write_b64 v36, v[30:31] offset:63360
	ds_write_b64 v36, v[66:67] offset:65472
	v_mov_b32_e32 v3, v130
	s_waitcnt lgkmcnt(0)
	s_barrier
	s_nop 0
	v_and_b32_e32 v5, 15, v3
	v_cvt_f32_ubyte0_e32 v2, v5
	v_mul_f32_e32 v4, 0x3b800000, v2
	v_sin_f32_e32 v2, v4
	v_cos_f32_e32 v4, v4
	v_lshlrev_b32_e32 v66, 3, v5
	v_lshlrev_b32_e32 v36, 4, v3
	v_xor_b32_e32 v5, 0x80000000, v2
	v_mov_b32_e32 v3, v5
	v_pk_mul_f32 v[6:7], v[4:5], v[2:3] op_sel:[1,0] op_sel_hi:[0,1]
	v_pk_fma_f32 v[6:7], v[4:5], v[4:5], v[6:7] op_sel_hi:[0,1,1]
	v_pk_mul_f32 v[12:13], 1.0, v[6:7] op_sel:[0,1] op_sel_hi:[0,1] neg_lo:[0,1]
	v_pk_mul_f32 v[10:11], v[6:7], v[12:13] op_sel:[1,0] op_sel_hi:[0,1]
	v_pk_fma_f32 v[10:11], v[6:7], v[6:7], v[10:11] op_sel_hi:[1,0,1]
	v_pk_mul_f32 v[8:9], v[2:3], v[6:7] op_sel:[0,1] op_sel_hi:[1,0]
	v_pk_mul_f32 v[14:15], 1.0, v[10:11] op_sel:[0,1] op_sel_hi:[0,1] neg_lo:[0,1]
	v_pk_mul_f32 v[30:31], v[10:11], v[14:15] op_sel:[1,0] op_sel_hi:[0,1]
	v_pk_fma_f32 v[30:31], v[10:11], v[10:11], v[30:31] op_sel_hi:[1,0,1]
	v_pk_mul_f32 v[16:17], v[2:3], v[10:11] op_sel:[0,1] op_sel_hi:[1,0]
	v_pk_mul_f32 v[50:51], v[14:15], v[30:31] op_sel:[0,1] op_sel_hi:[1,0]
	v_pk_mul_f32 v[38:39], v[2:3], v[30:31] op_sel:[0,1] op_sel_hi:[1,0]
	v_pk_fma_f32 v[50:51], v[10:11], v[30:31], v[50:51] op_sel_hi:[0,1,1]
	v_pk_mul_f32 v[54:55], v[2:3], v[50:51] op_sel:[0,1] op_sel_hi:[1,0]
	v_pk_fma_f32 v[8:9], v[4:5], v[6:7], v[8:9] op_sel_hi:[0,1,1]
	v_pk_fma_f32 v[16:17], v[4:5], v[10:11], v[16:17] op_sel_hi:[0,1,1]
	v_pk_fma_f32 v[38:39], v[4:5], v[30:31], v[38:39] op_sel_hi:[0,1,1]
	v_pk_fma_f32 v[54:55], v[4:5], v[50:51], v[54:55] op_sel_hi:[0,1,1]
	v_and_b32_e32 v5, 0xffffff00, v36
	v_lshlrev_b32_e32 v36, 3, v5
	v_add3_u32 v36, 0, v66, v36
	v_ashrrev_i32_e32 v66, 2, v5
	v_add_u32_e32 v108, v36, v66
	ds_read2_b64 v[66:69], v108 offset1:16
	ds_read2_b64 v[70:73], v108 offset0:33 offset1:49
	ds_read2_b64 v[74:77], v108 offset0:66 offset1:82
	ds_read2_b64 v[78:81], v108 offset0:132 offset1:148
	ds_read2_b64 v[82:85], v108 offset0:99 offset1:115
	ds_read2_b64 v[86:89], v108 offset0:165 offset1:181
	ds_read2_b64 v[90:93], v108 offset0:198 offset1:214
	ds_read2_b64 v[94:97], v108 offset0:231 offset1:247
	s_waitcnt lgkmcnt(4)
	v_pk_add_f32 v[98:99], v[66:67], v[78:79]
	v_pk_add_f32 v[66:67], v[66:67], v[78:79] neg_lo:[0,1] neg_hi:[0,1]
	v_pk_add_f32 v[78:79], v[68:69], v[80:81]
	v_pk_add_f32 v[68:69], v[68:69], v[80:81] neg_lo:[0,1] neg_hi:[0,1]
	s_waitcnt lgkmcnt(1)
	v_pk_add_f32 v[100:101], v[76:77], v[92:93]
	v_pk_mul_f32 v[80:81], v[68:69], s[44:45]
	v_pk_add_f32 v[76:77], v[76:77], v[92:93] neg_lo:[0,1] neg_hi:[0,1]
	v_pk_fma_f32 v[68:69], v[68:69], s[42:43], v[80:81] op_sel:[0,0,1] op_sel_hi:[1,0,0]
	v_pk_add_f32 v[80:81], v[70:71], v[86:87]
	v_pk_add_f32 v[70:71], v[70:71], v[86:87] neg_lo:[0,1] neg_hi:[0,1]
	v_pk_mul_f32 v[92:93], v[76:77], s[76:77]
	v_pk_mul_f32 v[86:87], v[70:71], s[68:69]
	v_pk_fma_f32 v[76:77], v[76:77], s[72:73], v[92:93] op_sel:[0,0,1] op_sel_hi:[1,0,0] neg_lo:[1,0,0] neg_hi:[1,0,0]
	v_pk_fma_f32 v[70:71], v[70:71], s[64:65], v[86:87] op_sel:[0,0,1] op_sel_hi:[1,0,0]
	v_pk_add_f32 v[86:87], v[72:73], v[88:89]
	v_pk_add_f32 v[72:73], v[72:73], v[88:89] neg_lo:[0,1] neg_hi:[0,1]
	s_waitcnt lgkmcnt(0)
	v_pk_add_f32 v[92:93], v[82:83], v[94:95]
	v_pk_add_f32 v[82:83], v[82:83], v[94:95] neg_lo:[0,1] neg_hi:[0,1]
	v_pk_mul_f32 v[88:89], v[72:73], s[76:77]
	v_pk_mul_f32 v[94:95], v[82:83], s[68:69]
	v_pk_fma_f32 v[72:73], v[72:73], s[72:73], v[88:89] op_sel:[0,0,1] op_sel_hi:[1,0,0]
	v_pk_add_f32 v[88:89], v[74:75], v[90:91]
	v_pk_add_f32 v[90:91], v[74:75], v[90:91] neg_lo:[0,1] neg_hi:[0,1]
	v_pk_fma_f32 v[82:83], v[82:83], s[64:65], v[94:95] op_sel:[0,0,1] op_sel_hi:[1,0,0] neg_lo:[1,0,0] neg_hi:[1,0,0]
	v_pk_add_f32 v[94:95], v[84:85], v[96:97]
	v_pk_add_f32 v[84:85], v[84:85], v[96:97] neg_lo:[0,1] neg_hi:[0,1]
	s_nop 0
	v_pk_mul_f32 v[96:97], v[84:85], s[44:45]
	s_nop 0
	v_pk_fma_f32 v[84:85], v[84:85], s[42:43], v[96:97] op_sel:[0,0,1] op_sel_hi:[1,0,0] neg_lo:[1,0,0] neg_hi:[1,0,0]
	v_pk_add_f32 v[96:97], v[98:99], v[88:89]
	v_pk_add_f32 v[88:89], v[98:99], v[88:89] neg_lo:[0,1] neg_hi:[0,1]
	v_pk_add_f32 v[98:99], v[78:79], v[100:101]
	v_pk_add_f32 v[78:79], v[78:79], v[100:101] neg_lo:[0,1] neg_hi:[0,1]
	v_pk_add_f32 v[102:103], v[86:87], v[94:95]
	v_pk_add_f32 v[86:87], v[86:87], v[94:95] neg_lo:[0,1] neg_hi:[0,1]
	v_pk_add_f32 v[74:75], v[66:67], v[90:91] op_sel:[0,1] op_sel_hi:[1,0] neg_hi:[0,1]
	v_pk_add_f32 v[66:67], v[66:67], v[90:91] op_sel:[0,1] op_sel_hi:[1,0] neg_lo:[0,1]
	v_pk_add_f32 v[90:91], v[68:69], v[76:77]
	v_pk_add_f32 v[68:69], v[68:69], v[76:77] neg_lo:[0,1] neg_hi:[0,1]
	v_pk_mul_f32 v[100:101], v[78:79], s[68:69]
	v_pk_mul_f32 v[94:95], v[86:87], s[68:69]
	v_pk_mul_f32 v[76:77], v[68:69], s[68:69]
	v_pk_fma_f32 v[78:79], v[78:79], s[64:65], v[100:101] op_sel:[0,0,1] op_sel_hi:[1,0,0]
	v_pk_add_f32 v[100:101], v[80:81], v[92:93]
	v_pk_add_f32 v[92:93], v[80:81], v[92:93] neg_lo:[0,1] neg_hi:[0,1]
	v_pk_fma_f32 v[86:87], v[86:87], s[64:65], v[94:95] op_sel:[0,0,1] op_sel_hi:[1,0,0] neg_lo:[1,0,0] neg_hi:[1,0,0]
	v_pk_fma_f32 v[68:69], v[68:69], s[64:65], v[76:77] op_sel:[0,0,1] op_sel_hi:[1,0,0]
	v_pk_add_f32 v[76:77], v[70:71], v[82:83]
	v_pk_add_f32 v[94:95], v[72:73], v[84:85]
	v_pk_add_f32 v[72:73], v[72:73], v[84:85] neg_lo:[0,1] neg_hi:[0,1]
	v_pk_add_f32 v[82:83], v[70:71], v[82:83] neg_lo:[0,1] neg_hi:[0,1]
	v_pk_mul_f32 v[84:85], v[72:73], s[68:69]
	v_pk_add_f32 v[104:105], v[74:75], v[76:77]
	v_pk_add_f32 v[74:75], v[74:75], v[76:77] neg_lo:[0,1] neg_hi:[0,1]
	v_pk_add_f32 v[76:77], v[90:91], v[94:95]
	v_pk_add_f32 v[94:95], v[90:91], v[94:95] neg_lo:[0,1] neg_hi:[0,1]
	v_pk_mul_f32 v[18:19], v[8:9], 1.0 op_sel:[1,0] op_sel_hi:[1,0] neg_lo:[1,0]
	v_pk_mul_f32 v[22:23], v[12:13], v[10:11] op_sel:[0,1] op_sel_hi:[1,0]
	v_pk_fma_f32 v[72:73], v[72:73], s[64:65], v[84:85] op_sel:[0,0,1] op_sel_hi:[1,0,0] neg_lo:[1,0,0] neg_hi:[1,0,0]
	v_pk_add_f32 v[80:81], v[88:89], v[92:93] op_sel:[0,1] op_sel_hi:[1,0] neg_hi:[0,1]
	v_pk_add_f32 v[88:89], v[88:89], v[92:93] op_sel:[0,1] op_sel_hi:[1,0] neg_lo:[0,1]
	v_pk_add_f32 v[92:93], v[78:79], v[86:87]
	v_pk_add_f32 v[86:87], v[78:79], v[86:87] neg_lo:[0,1] neg_hi:[0,1]
	v_pk_mul_f32 v[20:21], v[16:17], 1.0 op_sel:[1,0] op_sel_hi:[1,0] neg_lo:[1,0]
	v_pk_fma_f32 v[22:23], v[6:7], v[10:11], v[22:23] op_sel_hi:[0,1,1]
	v_pk_mul_f32 v[26:27], v[10:11], v[18:19] op_sel:[1,0] op_sel_hi:[0,1]
	v_pk_add_f32 v[70:71], v[66:67], v[82:83] op_sel:[0,1] op_sel_hi:[1,0] neg_hi:[0,1]
	v_pk_add_f32 v[66:67], v[66:67], v[82:83] op_sel:[0,1] op_sel_hi:[1,0] neg_lo:[0,1]
	v_pk_add_f32 v[82:83], v[68:69], v[72:73]
	v_pk_add_f32 v[72:73], v[68:69], v[72:73] neg_lo:[0,1] neg_hi:[0,1]
	v_pk_add_f32 v[90:91], v[74:75], v[94:95] op_sel:[0,1] op_sel_hi:[1,0] neg_hi:[0,1]
	v_pk_mul_f32 v[24:25], v[22:23], 1.0 op_sel:[1,0] op_sel_hi:[1,0] neg_lo:[1,0]
	v_pk_fma_f32 v[26:27], v[10:11], v[8:9], v[26:27] op_sel_hi:[1,0,1]
	v_pk_add_f32 v[78:79], v[88:89], v[86:87] op_sel:[0,1] op_sel_hi:[1,0] neg_hi:[0,1]
	v_pk_add_f32 v[74:75], v[74:75], v[94:95] op_sel:[0,1] op_sel_hi:[1,0] neg_lo:[0,1]
	v_pk_mul_f32 v[94:95], v[20:21], v[90:91] op_sel:[0,1] op_sel_hi:[1,0]
	v_pk_mul_f32 v[28:29], v[26:27], 1.0 op_sel:[1,0] op_sel_hi:[1,0] neg_lo:[1,0]
	v_pk_add_f32 v[84:85], v[96:97], v[100:101]
	v_pk_add_f32 v[96:97], v[96:97], v[100:101] neg_lo:[0,1] neg_hi:[0,1]
	v_pk_add_f32 v[100:101], v[98:99], v[102:103]
	v_pk_add_f32 v[68:69], v[66:67], v[72:73] op_sel:[0,1] op_sel_hi:[1,0] neg_hi:[0,1]
	v_pk_fma_f32 v[90:91], v[16:17], v[90:91], v[94:95] op_sel_hi:[0,1,1]
	v_pk_mul_f32 v[94:95], v[24:25], v[78:79] op_sel:[0,1] op_sel_hi:[1,0]
	v_pk_mul_f32 v[32:33], v[30:31], 1.0 op_sel:[1,0] op_sel_hi:[1,0] neg_lo:[1,0]
	v_pk_mul_f32 v[42:43], v[12:13], v[30:31] op_sel:[0,1] op_sel_hi:[1,0]
	v_pk_add_f32 v[106:107], v[84:85], v[100:101]
	v_pk_add_f32 v[84:85], v[84:85], v[100:101] neg_lo:[0,1] neg_hi:[0,1]
	v_pk_fma_f32 v[78:79], v[22:23], v[78:79], v[94:95] op_sel_hi:[0,1,1]
	v_pk_mul_f32 v[94:95], v[28:29], v[68:69] op_sel:[0,1] op_sel_hi:[1,0]
	v_pk_mul_f32 v[40:41], v[38:39], 1.0 op_sel:[1,0] op_sel_hi:[1,0] neg_lo:[1,0]
	v_pk_fma_f32 v[42:43], v[6:7], v[30:31], v[42:43] op_sel_hi:[0,1,1]
	v_pk_mul_f32 v[46:47], v[18:19], v[30:31] op_sel:[0,1] op_sel_hi:[1,0]
	v_pk_add_f32 v[86:87], v[88:89], v[86:87] op_sel:[0,1] op_sel_hi:[1,0] neg_lo:[0,1]
	v_pk_add_f32 v[88:89], v[104:105], v[76:77]
	v_pk_add_f32 v[76:77], v[104:105], v[76:77] neg_lo:[0,1] neg_hi:[0,1]
	v_pk_fma_f32 v[68:69], v[26:27], v[68:69], v[94:95] op_sel_hi:[0,1,1]
	v_pk_mul_f32 v[94:95], v[32:33], v[84:85] op_sel:[0,1] op_sel_hi:[1,0]
	v_pk_mul_f32 v[44:45], v[42:43], 1.0 op_sel:[1,0] op_sel_hi:[1,0] neg_lo:[1,0]
	v_pk_fma_f32 v[46:47], v[8:9], v[30:31], v[46:47] op_sel_hi:[0,1,1]
	v_pk_add_f32 v[102:103], v[98:99], v[102:103] neg_lo:[0,1] neg_hi:[0,1]
	v_pk_add_f32 v[100:101], v[80:81], v[92:93]
	v_pk_add_f32 v[80:81], v[80:81], v[92:93] neg_lo:[0,1] neg_hi:[0,1]
	v_pk_fma_f32 v[84:85], v[30:31], v[84:85], v[94:95] op_sel_hi:[0,1,1]
	v_pk_mul_f32 v[94:95], v[40:41], v[76:77] op_sel:[0,1] op_sel_hi:[1,0]
	v_pk_mul_f32 v[48:49], v[46:47], 1.0 op_sel:[1,0] op_sel_hi:[1,0] neg_lo:[1,0]
	v_pk_add_f32 v[92:93], v[70:71], v[82:83]
	v_pk_add_f32 v[70:71], v[70:71], v[82:83] neg_lo:[0,1] neg_hi:[0,1]
	v_pk_fma_f32 v[76:77], v[38:39], v[76:77], v[94:95] op_sel_hi:[0,1,1]
	v_pk_mul_f32 v[94:95], v[44:45], v[80:81] op_sel:[0,1] op_sel_hi:[1,0]
	v_pk_mul_f32 v[52:53], v[50:51], 1.0 op_sel:[1,0] op_sel_hi:[1,0] neg_lo:[1,0]
	v_pk_mul_f32 v[58:59], v[12:13], v[50:51] op_sel:[0,1] op_sel_hi:[1,0]
	v_pk_add_f32 v[98:99], v[96:97], v[102:103] op_sel:[0,1] op_sel_hi:[1,0] neg_hi:[0,1]
	v_pk_add_f32 v[96:97], v[96:97], v[102:103] op_sel:[0,1] op_sel_hi:[1,0] neg_lo:[0,1]
	v_pk_fma_f32 v[80:81], v[42:43], v[80:81], v[94:95] op_sel_hi:[0,1,1]
	v_pk_mul_f32 v[94:95], v[48:49], v[70:71] op_sel:[0,1] op_sel_hi:[1,0]
	v_pk_mul_f32 v[56:57], v[54:55], 1.0 op_sel:[1,0] op_sel_hi:[1,0] neg_lo:[1,0]
	v_pk_fma_f32 v[58:59], v[6:7], v[50:51], v[58:59] op_sel_hi:[0,1,1]
	v_pk_mul_f32 v[62:63], v[18:19], v[50:51] op_sel:[0,1] op_sel_hi:[1,0]
	v_pk_fma_f32 v[70:71], v[46:47], v[70:71], v[94:95] op_sel_hi:[0,1,1]
	v_pk_mul_f32 v[94:95], v[52:53], v[96:97] op_sel:[0,1] op_sel_hi:[1,0]
	v_pk_mul_f32 v[60:61], v[58:59], 1.0 op_sel:[1,0] op_sel_hi:[1,0] neg_lo:[1,0]
	v_pk_fma_f32 v[62:63], v[8:9], v[50:51], v[62:63] op_sel_hi:[0,1,1]
	v_pk_add_f32 v[66:67], v[66:67], v[72:73] op_sel:[0,1] op_sel_hi:[1,0] neg_lo:[0,1]
	v_pk_mul_f32 v[72:73], v[2:3], v[88:89] op_sel:[0,1] op_sel_hi:[1,0]
	v_pk_fma_f32 v[94:95], v[50:51], v[96:97], v[94:95] op_sel_hi:[0,1,1]
	v_pk_mul_f32 v[96:97], v[56:57], v[74:75] op_sel:[0,1] op_sel_hi:[1,0]
	v_pk_mul_f32 v[64:65], v[62:63], 1.0 op_sel:[1,0] op_sel_hi:[1,0] neg_lo:[1,0]
	v_pk_fma_f32 v[72:73], v[4:5], v[88:89], v[72:73] op_sel_hi:[0,1,1]
	v_pk_mul_f32 v[88:89], v[18:19], v[92:93] op_sel:[0,1] op_sel_hi:[1,0]
	v_pk_fma_f32 v[74:75], v[54:55], v[74:75], v[96:97] op_sel_hi:[0,1,1]
	v_pk_mul_f32 v[96:97], v[60:61], v[86:87] op_sel:[0,1] op_sel_hi:[1,0]
	v_add_u32_e32 v5, 0x2000, v5
	v_pk_mul_f32 v[82:83], v[12:13], v[100:101] op_sel:[0,1] op_sel_hi:[1,0]
	v_pk_fma_f32 v[88:89], v[8:9], v[92:93], v[88:89] op_sel_hi:[0,1,1]
	v_pk_mul_f32 v[92:93], v[14:15], v[98:99] op_sel:[0,1] op_sel_hi:[1,0]
	v_pk_fma_f32 v[86:87], v[58:59], v[86:87], v[96:97] op_sel_hi:[0,1,1]
	v_pk_mul_f32 v[96:97], v[64:65], v[66:67] op_sel:[0,1] op_sel_hi:[1,0]
	v_ashrrev_i32_e32 v5, 2, v5
	v_pk_fma_f32 v[82:83], v[6:7], v[100:101], v[82:83] op_sel_hi:[0,1,1]
	v_pk_fma_f32 v[92:93], v[10:11], v[98:99], v[92:93] op_sel_hi:[0,1,1]
	v_pk_fma_f32 v[66:67], v[62:63], v[66:67], v[96:97] op_sel_hi:[0,1,1]
	ds_write2_b64 v108, v[106:107], v[84:85] offset1:16
	ds_write2_b64 v108, v[92:93], v[94:95] offset0:33 offset1:49
	ds_write2_b64 v108, v[82:83], v[80:81] offset0:66 offset1:82
	ds_write2_b64 v108, v[78:79], v[86:87] offset0:99 offset1:115
	ds_write2_b64 v108, v[72:73], v[76:77] offset0:132 offset1:148
	ds_write2_b64 v108, v[90:91], v[74:75] offset0:165 offset1:181
	ds_write2_b64 v108, v[88:89], v[70:71] offset0:198 offset1:214
	ds_write2_b64 v108, v[68:69], v[66:67] offset0:231 offset1:247
	v_add3_u32 v36, v36, v5, s30
	ds_read2_b64 v[66:69], v36 offset1:16
	ds_read2_b64 v[70:73], v36 offset0:33 offset1:49
	ds_read2_b64 v[74:77], v36 offset0:66 offset1:82
	ds_read2_b64 v[78:81], v36 offset0:132 offset1:148
	ds_read2_b64 v[82:85], v36 offset0:99 offset1:115
	ds_read2_b64 v[86:89], v36 offset0:165 offset1:181
	ds_read2_b64 v[90:93], v36 offset0:198 offset1:214
	ds_read2_b64 v[94:97], v36 offset0:231 offset1:247
	s_waitcnt lgkmcnt(4)
	v_pk_add_f32 v[98:99], v[66:67], v[78:79]
	v_pk_add_f32 v[66:67], v[66:67], v[78:79] neg_lo:[0,1] neg_hi:[0,1]
	v_pk_add_f32 v[78:79], v[68:69], v[80:81]
	v_pk_add_f32 v[68:69], v[68:69], v[80:81] neg_lo:[0,1] neg_hi:[0,1]
	s_waitcnt lgkmcnt(1)
	v_pk_add_f32 v[100:101], v[76:77], v[92:93]
	v_pk_mul_f32 v[80:81], v[68:69], s[44:45]
	v_pk_add_f32 v[76:77], v[76:77], v[92:93] neg_lo:[0,1] neg_hi:[0,1]
	v_pk_fma_f32 v[68:69], v[68:69], s[42:43], v[80:81] op_sel:[0,0,1] op_sel_hi:[1,0,0]
	v_pk_add_f32 v[80:81], v[70:71], v[86:87]
	v_pk_add_f32 v[70:71], v[70:71], v[86:87] neg_lo:[0,1] neg_hi:[0,1]
	v_pk_mul_f32 v[92:93], v[76:77], s[76:77]
	v_pk_mul_f32 v[86:87], v[70:71], s[68:69]
	v_pk_fma_f32 v[76:77], v[76:77], s[72:73], v[92:93] op_sel:[0,0,1] op_sel_hi:[1,0,0] neg_lo:[1,0,0] neg_hi:[1,0,0]
	s_waitcnt lgkmcnt(0)
	v_pk_add_f32 v[92:93], v[82:83], v[94:95]
	v_pk_add_f32 v[82:83], v[82:83], v[94:95] neg_lo:[0,1] neg_hi:[0,1]
	v_pk_fma_f32 v[70:71], v[70:71], s[64:65], v[86:87] op_sel:[0,0,1] op_sel_hi:[1,0,0]
	v_pk_add_f32 v[86:87], v[72:73], v[88:89]
	v_pk_add_f32 v[72:73], v[72:73], v[88:89] neg_lo:[0,1] neg_hi:[0,1]
	v_pk_mul_f32 v[94:95], v[82:83], s[68:69]
	v_pk_mul_f32 v[88:89], v[72:73], s[76:77]
	v_pk_fma_f32 v[82:83], v[82:83], s[64:65], v[94:95] op_sel:[0,0,1] op_sel_hi:[1,0,0] neg_lo:[1,0,0] neg_hi:[1,0,0]
	v_pk_add_f32 v[94:95], v[84:85], v[96:97]
	v_pk_add_f32 v[84:85], v[84:85], v[96:97] neg_lo:[0,1] neg_hi:[0,1]
	v_pk_fma_f32 v[72:73], v[72:73], s[72:73], v[88:89] op_sel:[0,0,1] op_sel_hi:[1,0,0]
	v_pk_add_f32 v[88:89], v[74:75], v[90:91]
	v_pk_mul_f32 v[96:97], v[84:85], s[44:45]
	v_pk_add_f32 v[90:91], v[74:75], v[90:91] neg_lo:[0,1] neg_hi:[0,1]
	v_pk_fma_f32 v[84:85], v[84:85], s[42:43], v[96:97] op_sel:[0,0,1] op_sel_hi:[1,0,0] neg_lo:[1,0,0] neg_hi:[1,0,0]
	v_pk_add_f32 v[96:97], v[98:99], v[88:89]
	v_pk_add_f32 v[88:89], v[98:99], v[88:89] neg_lo:[0,1] neg_hi:[0,1]
	v_pk_add_f32 v[98:99], v[78:79], v[100:101]
	v_pk_add_f32 v[78:79], v[78:79], v[100:101] neg_lo:[0,1] neg_hi:[0,1]
	v_pk_add_f32 v[102:103], v[86:87], v[94:95]
	v_pk_add_f32 v[86:87], v[86:87], v[94:95] neg_lo:[0,1] neg_hi:[0,1]
	v_pk_mul_f32 v[100:101], v[78:79], s[68:69]
	v_pk_mul_f32 v[94:95], v[86:87], s[68:69]
	v_pk_fma_f32 v[78:79], v[78:79], s[64:65], v[100:101] op_sel:[0,0,1] op_sel_hi:[1,0,0]
	v_pk_add_f32 v[100:101], v[80:81], v[92:93]
	v_pk_add_f32 v[92:93], v[80:81], v[92:93] neg_lo:[0,1] neg_hi:[0,1]
	v_pk_fma_f32 v[86:87], v[86:87], s[64:65], v[94:95] op_sel:[0,0,1] op_sel_hi:[1,0,0] neg_lo:[1,0,0] neg_hi:[1,0,0]
	v_pk_add_f32 v[74:75], v[66:67], v[90:91] op_sel:[0,1] op_sel_hi:[1,0] neg_hi:[0,1]
	v_pk_add_f32 v[66:67], v[66:67], v[90:91] op_sel:[0,1] op_sel_hi:[1,0] neg_lo:[0,1]
	v_pk_add_f32 v[90:91], v[68:69], v[76:77]
	v_pk_add_f32 v[68:69], v[68:69], v[76:77] neg_lo:[0,1] neg_hi:[0,1]
	v_pk_add_f32 v[94:95], v[72:73], v[84:85]
	v_pk_add_f32 v[72:73], v[72:73], v[84:85] neg_lo:[0,1] neg_hi:[0,1]
	v_pk_mul_f32 v[76:77], v[68:69], s[68:69]
	v_pk_mul_f32 v[84:85], v[72:73], s[68:69]
	v_pk_fma_f32 v[68:69], v[68:69], s[64:65], v[76:77] op_sel:[0,0,1] op_sel_hi:[1,0,0]
	v_pk_add_f32 v[76:77], v[70:71], v[82:83]
	v_pk_fma_f32 v[72:73], v[72:73], s[64:65], v[84:85] op_sel:[0,0,1] op_sel_hi:[1,0,0] neg_lo:[1,0,0] neg_hi:[1,0,0]
	v_pk_add_f32 v[80:81], v[88:89], v[92:93] op_sel:[0,1] op_sel_hi:[1,0] neg_hi:[0,1]
	v_pk_add_f32 v[88:89], v[88:89], v[92:93] op_sel:[0,1] op_sel_hi:[1,0] neg_lo:[0,1]
	v_pk_add_f32 v[92:93], v[78:79], v[86:87]
	v_pk_add_f32 v[86:87], v[78:79], v[86:87] neg_lo:[0,1] neg_hi:[0,1]
	s_add_i32 s65, s65, s28
	v_pk_add_f32 v[82:83], v[70:71], v[82:83] neg_lo:[0,1] neg_hi:[0,1]
	s_nop 0
	v_pk_add_f32 v[104:105], v[74:75], v[76:77]
	v_pk_add_f32 v[74:75], v[74:75], v[76:77] neg_lo:[0,1] neg_hi:[0,1]
	v_pk_add_f32 v[76:77], v[90:91], v[94:95]
	s_cmpk_gt_i32 s65, 0x3ff
	s_nop 0
	v_pk_add_f32 v[84:85], v[96:97], v[100:101]
	v_pk_add_f32 v[96:97], v[96:97], v[100:101] neg_lo:[0,1] neg_hi:[0,1]
	v_pk_add_f32 v[100:101], v[98:99], v[102:103]
	s_nop 0
	v_pk_add_f32 v[78:79], v[88:89], v[86:87] op_sel:[0,1] op_sel_hi:[1,0] neg_hi:[0,1]
	v_pk_add_f32 v[86:87], v[88:89], v[86:87] op_sel:[0,1] op_sel_hi:[1,0] neg_lo:[0,1]
	v_pk_add_f32 v[88:89], v[104:105], v[76:77]
	s_cselect_b64 s[80:81], -1, 0
	s_cmpk_lt_i32 s65, 0x400
	v_pk_add_f32 v[98:99], v[98:99], v[102:103] neg_lo:[0,1] neg_hi:[0,1]
	v_pk_add_f32 v[70:71], v[66:67], v[82:83] op_sel:[0,1] op_sel_hi:[1,0] neg_hi:[0,1]
	v_pk_add_f32 v[66:67], v[66:67], v[82:83] op_sel:[0,1] op_sel_hi:[1,0] neg_lo:[0,1]
	v_pk_add_f32 v[82:83], v[68:69], v[72:73]
	v_pk_add_f32 v[106:107], v[84:85], v[100:101]
	v_pk_add_f32 v[84:85], v[84:85], v[100:101] neg_lo:[0,1] neg_hi:[0,1]
	v_pk_add_f32 v[100:101], v[80:81], v[92:93]
	v_pk_mul_f32 v[2:3], v[2:3], v[88:89] op_sel:[0,1] op_sel_hi:[1,0]
	s_cselect_b32 s6, s65, s6
	v_pk_mul_f32 v[102:103], v[98:99], 1.0 op_sel:[1,0] op_sel_hi:[0,0] neg_hi:[1,0]
	v_pk_add_f32 v[90:91], v[90:91], v[94:95] neg_lo:[0,1] neg_hi:[0,1]
	s_nop 0
	v_pk_add_f32 v[80:81], v[80:81], v[92:93] neg_lo:[0,1] neg_hi:[0,1]
	v_pk_add_f32 v[92:93], v[70:71], v[82:83]
	v_pk_fma_f32 v[2:3], v[4:5], v[88:89], v[2:3] op_sel_hi:[0,1,1]
	v_pk_mul_f32 v[4:5], v[12:13], v[100:101] op_sel:[0,1] op_sel_hi:[1,0]
	s_lshl_b32 s8, s6, 1
	s_lshl_b32 s6, s6, 2
	v_pk_mul_f32 v[94:95], v[90:91], 1.0 op_sel:[1,0] op_sel_hi:[0,0] neg_hi:[1,0]
	v_pk_add_f32 v[68:69], v[68:69], v[72:73] neg_lo:[0,1] neg_hi:[0,1]
	v_pk_add_f32 v[98:99], v[96:97], v[102:103]
	s_nop 0
	v_pk_fma_f32 v[4:5], v[6:7], v[100:101], v[4:5] op_sel_hi:[0,1,1]
	v_pk_mul_f32 v[6:7], v[18:19], v[92:93] op_sel:[0,1] op_sel_hi:[1,0]
	s_and_b32 s7, s8, 0x3fe
	s_and_b32 s6, s6, 0xfffff800
	v_pk_mul_f32 v[72:73], v[68:69], 1.0 op_sel:[1,0] op_sel_hi:[0,0] neg_hi:[1,0]
	v_pk_add_f32 v[90:91], v[74:75], v[94:95]
	s_nop 0
	v_pk_fma_f32 v[6:7], v[8:9], v[92:93], v[6:7] op_sel_hi:[0,1,1]
	v_pk_mul_f32 v[8:9], v[14:15], v[98:99] op_sel:[0,1] op_sel_hi:[1,0]
	s_or_b32 s6, s7, s6
	v_pk_add_f32 v[68:69], v[66:67], v[72:73]
	v_pk_fma_f32 v[8:9], v[10:11], v[98:99], v[8:9] op_sel_hi:[0,1,1]
	v_pk_mul_f32 v[10:11], v[20:21], v[90:91] op_sel:[0,1] op_sel_hi:[1,0]
	s_ashr_i32 s7, s6, 31
	v_pk_add_f32 v[96:97], v[96:97], v[102:103] neg_lo:[0,1] neg_hi:[0,1]
	v_pk_add_f32 v[76:77], v[104:105], v[76:77] neg_lo:[0,1] neg_hi:[0,1]
	v_pk_add_f32 v[74:75], v[74:75], v[94:95] neg_lo:[0,1] neg_hi:[0,1]
	v_pk_add_f32 v[70:71], v[70:71], v[82:83] neg_lo:[0,1] neg_hi:[0,1]
	v_pk_add_f32 v[66:67], v[66:67], v[72:73] neg_lo:[0,1] neg_hi:[0,1]
	v_pk_fma_f32 v[10:11], v[16:17], v[90:91], v[10:11] op_sel_hi:[0,1,1]
	v_pk_mul_f32 v[12:13], v[24:25], v[78:79] op_sel:[0,1] op_sel_hi:[1,0]
	v_pk_mul_f32 v[14:15], v[28:29], v[68:69] op_sel:[0,1] op_sel_hi:[1,0]
	v_pk_mul_f32 v[16:17], v[32:33], v[84:85] op_sel:[0,1] op_sel_hi:[1,0]
	s_lshl_b64 s[82:83], s[6:7], 14
	s_bitset1_b32 s6, 10
	v_pk_fma_f32 v[12:13], v[22:23], v[78:79], v[12:13] op_sel_hi:[0,1,1]
	v_pk_fma_f32 v[14:15], v[26:27], v[68:69], v[14:15] op_sel_hi:[0,1,1]
	v_pk_fma_f32 v[16:17], v[30:31], v[84:85], v[16:17] op_sel_hi:[0,1,1]
	v_pk_mul_f32 v[18:19], v[40:41], v[76:77] op_sel:[0,1] op_sel_hi:[1,0]
	v_pk_mul_f32 v[20:21], v[44:45], v[80:81] op_sel:[0,1] op_sel_hi:[1,0]
	v_pk_mul_f32 v[22:23], v[48:49], v[70:71] op_sel:[0,1] op_sel_hi:[1,0]
	v_pk_mul_f32 v[24:25], v[52:53], v[96:97] op_sel:[0,1] op_sel_hi:[1,0]
	v_pk_mul_f32 v[26:27], v[56:57], v[74:75] op_sel:[0,1] op_sel_hi:[1,0]
	v_pk_mul_f32 v[28:29], v[60:61], v[86:87] op_sel:[0,1] op_sel_hi:[1,0]
	v_pk_mul_f32 v[30:31], v[64:65], v[66:67] op_sel:[0,1] op_sel_hi:[1,0]
	s_ashr_i32 s7, s6, 31
	v_pk_fma_f32 v[18:19], v[38:39], v[76:77], v[18:19] op_sel_hi:[0,1,1]
	v_pk_fma_f32 v[20:21], v[42:43], v[80:81], v[20:21] op_sel_hi:[0,1,1]
	v_pk_fma_f32 v[22:23], v[46:47], v[70:71], v[22:23] op_sel_hi:[0,1,1]
	v_pk_fma_f32 v[24:25], v[50:51], v[96:97], v[24:25] op_sel_hi:[0,1,1]
	v_pk_fma_f32 v[26:27], v[54:55], v[74:75], v[26:27] op_sel_hi:[0,1,1]
	v_pk_fma_f32 v[28:29], v[58:59], v[86:87], v[28:29] op_sel_hi:[0,1,1]
	v_pk_fma_f32 v[30:31], v[62:63], v[66:67], v[30:31] op_sel_hi:[0,1,1]
	ds_write2_b64 v36, v[106:107], v[16:17] offset1:16
	ds_write2_b64 v36, v[8:9], v[24:25] offset0:33 offset1:49
	ds_write2_b64 v36, v[4:5], v[20:21] offset0:66 offset1:82
	ds_write2_b64 v36, v[12:13], v[28:29] offset0:99 offset1:115
	ds_write2_b64 v36, v[2:3], v[18:19] offset0:132 offset1:148
	ds_write2_b64 v36, v[10:11], v[26:27] offset0:165 offset1:181
	ds_write2_b64 v36, v[6:7], v[22:23] offset0:198 offset1:214
	ds_write2_b64 v36, v[14:15], v[30:31] offset0:231 offset1:247
	s_lshl_b64 s[6:7], s[6:7], 14
	v_lshl_add_u64 v[2:3], v[34:35], 0, s[82:83]
	s_waitcnt lgkmcnt(0)
	s_barrier
	global_load_dwordx4 v[10:13], v[2:3], off nt
	global_load_dwordx4 v[30:33], v[2:3], off offset:16 nt
	v_lshl_add_u64 v[2:3], v[34:35], 0, s[6:7]
	global_load_dwordx4 v[26:29], v[2:3], off nt
	global_load_dwordx4 v[22:25], v[2:3], off offset:16 nt
	v_mov_b32_e32 v38, 0
	s_and_saveexec_b64 s[6:7], s[0:1]
	s_cbranch_execz .LBB0_430
	global_load_ushort v38, v[2:3], off offset:32

.LBB0_432:
	s_or_b64 exec, exec, s[6:7]
	v_mov_b32_e32 v36, v130
	s_mov_b32 s75, s42
	v_ashrrev_i32_e32 v40, 31, v36
	v_add_u32_sdwa v40, v36, v40 dst_sel:DWORD dst_unused:UNUSED_PAD src0_sel:DWORD src1_sel:BYTE_3
	v_ashrrev_i32_e32 v40, 8, v40
	v_mul_i32_i24_e32 v41, 0x100, v40
	v_sub_u32_e32 v66, v36, v41
	v_lshlrev_b32_e32 v41, 1, v66
	v_bfrev_b32_e32 v41, v41
	v_lshrrev_b32_e32 v41, 23, v41
	v_sub_u32_e32 v41, 0x200, v41
	v_bfrev_b32_e32 v41, v41
	v_lshrrev_b32_e32 v41, 19, v41
	v_and_b32_e32 v41, 0x1ff0, v41
	v_cmp_eq_u32_e64 s[6:7], 0, v66
	v_lshlrev_b32_e32 v40, 13, v40
	v_lshl_add_u32 v42, v66, 5, v40
	v_cndmask_b32_e64 v41, v41, 16, s[6:7]
	v_or_b32_e32 v40, v41, v40
	v_lshlrev_b32_e32 v43, 3, v42
	v_ashrrev_i32_e32 v42, 2, v42
	v_ashrrev_i32_e32 v41, 5, v40
	v_add3_u32 v88, 0, v43, v42
	v_lshlrev_b32_e32 v40, 3, v40
	v_lshlrev_b32_e32 v41, 3, v41
	v_add_u32_e32 v36, 0xffffff00, v36
	v_add3_u32 v40, 0, v40, v41
	ds_read2_b64 v[42:45], v88 offset1:1
	ds_read2_b64 v[46:49], v88 offset0:2 offset1:3
	ds_read2_b64 v[72:75], v40 offset1:1
	ds_read2_b64 v[76:79], v40 offset0:2 offset1:3
	ds_read2_b64 v[50:53], v88 offset0:4 offset1:5
	ds_read2_b64 v[54:57], v88 offset0:6 offset1:7
	ds_read2_b64 v[80:83], v40 offset0:4 offset1:5
	ds_read2_b64 v[84:87], v40 offset0:6 offset1:7
	ds_read2_b64 v[58:61], v88 offset0:8 offset1:9
	ds_read2_b64 v[62:65], v88 offset0:10 offset1:11
	ds_read2_b64 v[96:99], v40 offset0:8 offset1:9
	ds_read2_b64 v[100:103], v40 offset0:10 offset1:11
	ds_read2_b64 v[68:71], v88 offset0:12 offset1:13
	ds_read2_b64 v[88:91], v88 offset0:14 offset1:15
	ds_read2_b64 v[104:107], v40 offset0:12 offset1:13
	ds_read2_b64 v[108:111], v40 offset0:14 offset1:15
	v_mov_b32_e32 v40, s16
	v_cmp_gt_u32_e64 s[8:9], s33, v36
	s_waitcnt lgkmcnt(7)
	v_pk_add_f32 v[92:93], v[42:43], v[58:59]
	v_pk_add_f32 v[42:43], v[42:43], v[58:59] neg_lo:[0,1] neg_hi:[0,1]
	v_pk_add_f32 v[58:59], v[44:45], v[60:61]
	v_pk_add_f32 v[44:45], v[44:45], v[60:61] neg_lo:[0,1] neg_hi:[0,1]
	v_addc_co_u32_e64 v40, s[8:9], 0, v40, s[8:9]
	v_pk_mul_f32 v[60:61], v[44:45], s[44:45]
	s_waitcnt lgkmcnt(3)
	v_pk_add_f32 v[94:95], v[52:53], v[70:71]
	v_pk_add_f32 v[52:53], v[52:53], v[70:71] neg_lo:[0,1] neg_hi:[0,1]
	v_pk_fma_f32 v[44:45], v[44:45], s[42:43], v[60:61] op_sel:[0,0,1] op_sel_hi:[1,0,0]
	v_pk_add_f32 v[60:61], v[46:47], v[62:63]
	v_pk_add_f32 v[46:47], v[46:47], v[62:63] neg_lo:[0,1] neg_hi:[0,1]
	s_mov_b32 s67, s64
	s_mov_b32 s8, s45
	v_pk_mul_f32 v[70:71], v[52:53], s[74:75]
	v_pk_mul_f32 v[62:63], v[46:47], s[66:67]
	v_pk_fma_f32 v[52:53], v[52:53], s[8:9], v[70:71] op_sel:[0,0,1] op_sel_hi:[1,0,0] neg_lo:[1,0,0] neg_hi:[1,0,0]
	s_waitcnt lgkmcnt(2)
	v_pk_add_f32 v[70:71], v[54:55], v[88:89]
	v_pk_add_f32 v[54:55], v[54:55], v[88:89] neg_lo:[0,1] neg_hi:[0,1]
	v_pk_fma_f32 v[46:47], v[46:47], s[64:65], v[62:63] op_sel:[0,0,1] op_sel_hi:[1,0,0]
	v_pk_add_f32 v[62:63], v[48:49], v[64:65]
	v_pk_add_f32 v[48:49], v[48:49], v[64:65] neg_lo:[0,1] neg_hi:[0,1]
	v_pk_mul_f32 v[88:89], v[54:55], s[66:67]
	v_pk_mul_f32 v[64:65], v[48:49], s[74:75]
	v_pk_fma_f32 v[54:55], v[54:55], s[64:65], v[88:89] op_sel:[0,0,1] op_sel_hi:[1,0,0] neg_lo:[1,0,0] neg_hi:[1,0,0]
	v_pk_add_f32 v[88:89], v[56:57], v[90:91]
	v_pk_add_f32 v[56:57], v[56:57], v[90:91] neg_lo:[0,1] neg_hi:[0,1]
	v_pk_fma_f32 v[48:49], v[48:49], s[8:9], v[64:65] op_sel:[0,0,1] op_sel_hi:[1,0,0]
	v_pk_add_f32 v[64:65], v[50:51], v[68:69]
	v_pk_add_f32 v[50:51], v[50:51], v[68:69] neg_lo:[0,1] neg_hi:[0,1]
	v_pk_mul_f32 v[90:91], v[56:57], s[44:45]
	v_pk_add_f32 v[112:113], v[62:63], v[88:89]
	v_pk_add_f32 v[62:63], v[62:63], v[88:89] neg_lo:[0,1] neg_hi:[0,1]
	v_xor_b32_e32 v69, 0x80000000, v50
	v_pk_fma_f32 v[56:57], v[56:57], s[42:43], v[90:91] op_sel:[0,0,1] op_sel_hi:[1,0,0] neg_lo:[1,0,0] neg_hi:[1,0,0]
	v_pk_add_f32 v[90:91], v[92:93], v[64:65]
	v_pk_add_f32 v[64:65], v[92:93], v[64:65] neg_lo:[0,1] neg_hi:[0,1]
	v_pk_add_f32 v[92:93], v[58:59], v[94:95]
	v_pk_add_f32 v[58:59], v[58:59], v[94:95] neg_lo:[0,1] neg_hi:[0,1]
	v_pk_mul_f32 v[88:89], v[62:63], s[66:67]
	v_mov_b32_e32 v68, v51
	v_pk_mul_f32 v[94:95], v[58:59], s[66:67]
	v_pk_fma_f32 v[62:63], v[62:63], s[64:65], v[88:89] op_sel:[0,0,1] op_sel_hi:[1,0,0] neg_lo:[1,0,0] neg_hi:[1,0,0]
	v_pk_add_f32 v[50:51], v[42:43], v[68:69]
	v_pk_add_f32 v[42:43], v[42:43], v[68:69] neg_lo:[0,1] neg_hi:[0,1]
	v_pk_add_f32 v[68:69], v[44:45], v[52:53]
	v_pk_add_f32 v[44:45], v[44:45], v[52:53] neg_lo:[0,1] neg_hi:[0,1]
	v_pk_add_f32 v[88:89], v[48:49], v[56:57]
	v_pk_add_f32 v[48:49], v[48:49], v[56:57] neg_lo:[0,1] neg_hi:[0,1]
	v_pk_fma_f32 v[58:59], v[58:59], s[64:65], v[94:95] op_sel:[0,0,1] op_sel_hi:[1,0,0]
	v_pk_add_f32 v[94:95], v[60:61], v[70:71]
	v_pk_mul_f32 v[52:53], v[44:45], s[66:67]
	v_pk_mul_f32 v[56:57], v[48:49], s[66:67]
	v_pk_fma_f32 v[44:45], v[44:45], s[64:65], v[52:53] op_sel:[0,0,1] op_sel_hi:[1,0,0]
	v_pk_add_f32 v[52:53], v[46:47], v[54:55]
	v_pk_fma_f32 v[48:49], v[48:49], s[64:65], v[56:57] op_sel:[0,0,1] op_sel_hi:[1,0,0] neg_lo:[1,0,0] neg_hi:[1,0,0]
	v_pk_add_f32 v[56:57], v[90:91], v[94:95]
	v_pk_add_f32 v[114:115], v[90:91], v[94:95] neg_lo:[0,1] neg_hi:[0,1]
	v_pk_add_f32 v[90:91], v[92:93], v[112:113]
	v_pk_add_f32 v[112:113], v[92:93], v[112:113] neg_lo:[0,1] neg_hi:[0,1]
	v_pk_add_f32 v[122:123], v[50:51], v[52:53]
	v_pk_add_f32 v[50:51], v[50:51], v[52:53] neg_lo:[0,1] neg_hi:[0,1]
	v_pk_add_f32 v[52:53], v[68:69], v[88:89]
	v_pk_add_f32 v[88:89], v[68:69], v[88:89] neg_lo:[0,1] neg_hi:[0,1]
	v_pk_add_f32 v[92:93], v[74:75], v[98:99]
	v_pk_add_f32 v[74:75], v[74:75], v[98:99] neg_lo:[0,1] neg_hi:[0,1]
	v_pk_mul_f32 v[124:125], v[88:89], 1.0 op_sel:[1,0] op_sel_hi:[0,0] neg_hi:[1,0]
	v_pk_add_f32 v[88:89], v[72:73], v[96:97]
	v_pk_add_f32 v[72:73], v[72:73], v[96:97] neg_lo:[0,1] neg_hi:[0,1]
	v_pk_mul_f32 v[96:97], v[74:75], s[44:45]
	v_bfrev_b32_e32 v36, v66
	v_pk_fma_f32 v[74:75], v[74:75], s[42:43], v[96:97] op_sel:[0,0,1] op_sel_hi:[1,0,0]
	v_pk_add_f32 v[96:97], v[76:77], v[100:101]
	v_pk_add_f32 v[76:77], v[76:77], v[100:101] neg_lo:[0,1] neg_hi:[0,1]
	v_ashrrev_i32_e32 v41, 31, v40
	v_pk_mul_f32 v[98:99], v[76:77], s[66:67]
	v_cvt_f32_ubyte3_e32 v36, v36
	v_pk_fma_f32 v[76:77], v[76:77], s[64:65], v[98:99] op_sel:[0,0,1] op_sel_hi:[1,0,0]
	v_pk_add_f32 v[98:99], v[78:79], v[102:103]
	v_pk_add_f32 v[78:79], v[78:79], v[102:103] neg_lo:[0,1] neg_hi:[0,1]
	v_lshlrev_b64 v[40:41], 15, v[40:41]
	v_pk_mul_f32 v[100:101], v[78:79], s[74:75]
	v_mul_f32_e32 v36, 0x38800000, v36
	v_pk_fma_f32 v[78:79], v[78:79], s[8:9], v[100:101] op_sel:[0,0,1] op_sel_hi:[1,0,0]
	s_waitcnt lgkmcnt(1)
	v_pk_add_f32 v[100:101], v[80:81], v[104:105]
	v_pk_add_f32 v[102:103], v[80:81], v[104:105] neg_lo:[0,1] neg_hi:[0,1]
	v_ashrrev_i32_e32 v67, 31, v66
	v_pk_add_f32 v[80:81], v[82:83], v[106:107]
	v_pk_add_f32 v[82:83], v[82:83], v[106:107] neg_lo:[0,1] neg_hi:[0,1]
	v_lshl_add_u64 v[40:41], s[18:19], 0, v[40:41]
	v_pk_mul_f32 v[104:105], v[82:83], s[74:75]
	v_pk_add_f32 v[60:61], v[60:61], v[70:71] neg_lo:[0,1] neg_hi:[0,1]
	v_pk_fma_f32 v[82:83], v[82:83], s[8:9], v[104:105] op_sel:[0,0,1] op_sel_hi:[1,0,0] neg_lo:[1,0,0] neg_hi:[1,0,0]
	s_waitcnt lgkmcnt(0)
	v_pk_add_f32 v[104:105], v[84:85], v[108:109]
	v_pk_add_f32 v[84:85], v[84:85], v[108:109] neg_lo:[0,1] neg_hi:[0,1]
	v_cndmask_b32_e64 v36, v36, v152, s[6:7]
	v_pk_mul_f32 v[106:107], v[84:85], s[66:67]
	v_lshl_add_u64 v[40:41], v[66:67], 3, v[40:41]
	v_pk_fma_f32 v[84:85], v[84:85], s[64:65], v[106:107] op_sel:[0,0,1] op_sel_hi:[1,0,0] neg_lo:[1,0,0] neg_hi:[1,0,0]
	v_pk_add_f32 v[106:107], v[86:87], v[110:111]
	v_pk_add_f32 v[86:87], v[86:87], v[110:111] neg_lo:[0,1] neg_hi:[0,1]
	v_xor_b32_e32 v71, 0x80000000, v60
	v_pk_mul_f32 v[108:109], v[86:87], s[44:45]
	v_pk_add_f32 v[46:47], v[46:47], v[54:55] neg_lo:[0,1] neg_hi:[0,1]
	v_pk_fma_f32 v[86:87], v[86:87], s[42:43], v[108:109] op_sel:[0,0,1] op_sel_hi:[1,0,0] neg_lo:[1,0,0] neg_hi:[1,0,0]
	v_pk_add_f32 v[108:109], v[88:89], v[100:101]
	v_pk_add_f32 v[88:89], v[88:89], v[100:101] neg_lo:[0,1] neg_hi:[0,1]
	v_pk_add_f32 v[100:101], v[92:93], v[80:81]
	v_pk_add_f32 v[80:81], v[92:93], v[80:81] neg_lo:[0,1] neg_hi:[0,1]
	v_mov_b32_e32 v70, v61
	v_pk_mul_f32 v[92:93], v[80:81], s[66:67]
	v_pk_add_f32 v[118:119], v[58:59], v[62:63]
	v_pk_fma_f32 v[80:81], v[80:81], s[64:65], v[92:93] op_sel:[0,0,1] op_sel_hi:[1,0,0]
	v_pk_add_f32 v[92:93], v[96:97], v[104:105]
	v_pk_add_f32 v[104:105], v[96:97], v[104:105] neg_lo:[0,1] neg_hi:[0,1]
	v_pk_add_f32 v[120:121], v[58:59], v[62:63] neg_lo:[0,1] neg_hi:[0,1]
	v_pk_add_f32 v[96:97], v[98:99], v[106:107]
	v_pk_add_f32 v[98:99], v[98:99], v[106:107] neg_lo:[0,1] neg_hi:[0,1]
	v_cos_f32_e32 v67, v36
	v_pk_mul_f32 v[106:107], v[98:99], s[66:67]
	v_cmp_ne_u32_e32 vcc, 0, v66
	v_pk_fma_f32 v[98:99], v[98:99], s[64:65], v[106:107] op_sel:[0,0,1] op_sel_hi:[1,0,0] neg_lo:[1,0,0] neg_hi:[1,0,0]
	v_pk_add_f32 v[106:107], v[72:73], v[102:103] op_sel:[0,1] op_sel_hi:[1,0] neg_hi:[0,1]
	v_pk_add_f32 v[72:73], v[72:73], v[102:103] op_sel:[0,1] op_sel_hi:[1,0] neg_lo:[0,1]
	v_pk_add_f32 v[102:103], v[74:75], v[82:83]
	v_pk_add_f32 v[74:75], v[74:75], v[82:83] neg_lo:[0,1] neg_hi:[0,1]
	v_xor_b32_e32 v55, 0x80000000, v46
	v_pk_mul_f32 v[82:83], v[74:75], s[66:67]
	v_pk_add_f32 v[116:117], v[64:65], v[70:71] neg_lo:[0,1] neg_hi:[0,1]
	v_pk_fma_f32 v[74:75], v[74:75], s[64:65], v[82:83] op_sel:[0,0,1] op_sel_hi:[1,0,0]
	v_pk_add_f32 v[82:83], v[76:77], v[84:85]
	v_pk_add_f32 v[84:85], v[76:77], v[84:85] neg_lo:[0,1] neg_hi:[0,1]
	v_pk_add_f32 v[76:77], v[78:79], v[86:87]
	v_pk_add_f32 v[78:79], v[78:79], v[86:87] neg_lo:[0,1] neg_hi:[0,1]
	v_mov_b32_e32 v54, v47
	v_pk_mul_f32 v[86:87], v[78:79], s[66:67]
	s_nop 0
	v_pk_fma_f32 v[78:79], v[78:79], s[64:65], v[86:87] op_sel:[0,0,1] op_sel_hi:[1,0,0] neg_lo:[1,0,0] neg_hi:[1,0,0]
	v_pk_add_f32 v[86:87], v[108:109], v[92:93]
	v_pk_add_f32 v[92:93], v[108:109], v[92:93] neg_lo:[0,1] neg_hi:[0,1]
	v_pk_add_f32 v[108:109], v[100:101], v[96:97]
	v_pk_add_f32 v[96:97], v[100:101], v[96:97] neg_lo:[0,1] neg_hi:[0,1]
	v_sin_f32_e32 v66, v36
	v_pk_add_f32 v[60:61], v[64:65], v[70:71]
	v_pk_add_f32 v[126:127], v[42:43], v[54:55]
	v_pk_add_f32 v[128:129], v[42:43], v[54:55] neg_lo:[0,1] neg_hi:[0,1]
	v_pk_add_f32 v[42:43], v[44:45], v[48:49]
	v_pk_add_f32 v[48:49], v[44:45], v[48:49] neg_lo:[0,1] neg_hi:[0,1]
	v_pk_add_f32 v[94:95], v[56:57], v[90:91]
	v_pk_add_f32 v[90:91], v[56:57], v[90:91] neg_lo:[0,1] neg_hi:[0,1]
	v_pk_add_f32 v[70:71], v[114:115], v[112:113] op_sel:[0,1] op_sel_hi:[1,0] neg_hi:[0,1]
	v_pk_add_f32 v[64:65], v[114:115], v[112:113] op_sel:[0,1] op_sel_hi:[1,0] neg_lo:[0,1]
	v_pk_add_f32 v[56:57], v[116:117], v[120:121] op_sel:[0,1] op_sel_hi:[1,0] neg_hi:[0,1]
	v_pk_add_f32 v[62:63], v[116:117], v[120:121] op_sel:[0,1] op_sel_hi:[1,0] neg_lo:[0,1]
	v_pk_mul_f32 v[100:101], v[96:97], 1.0 op_sel:[1,0] op_sel_hi:[0,0] neg_hi:[1,0]
	v_pk_add_f32 v[96:97], v[88:89], v[104:105] op_sel:[0,1] op_sel_hi:[1,0] neg_hi:[0,1]
	v_pk_add_f32 v[88:89], v[88:89], v[104:105] op_sel:[0,1] op_sel_hi:[1,0] neg_lo:[0,1]
	v_pk_add_f32 v[104:105], v[80:81], v[98:99]
	v_pk_add_f32 v[98:99], v[80:81], v[98:99] neg_lo:[0,1] neg_hi:[0,1]
	v_pk_add_f32 v[112:113], v[102:103], v[76:77]
	v_pk_add_f32 v[102:103], v[102:103], v[76:77] neg_lo:[0,1] neg_hi:[0,1]
	v_pk_add_f32 v[114:115], v[72:73], v[84:85] op_sel:[0,1] op_sel_hi:[1,0] neg_hi:[0,1]
	v_pk_add_f32 v[116:117], v[72:73], v[84:85] op_sel:[0,1] op_sel_hi:[1,0] neg_lo:[0,1]
	v_pk_add_f32 v[72:73], v[74:75], v[78:79] neg_lo:[0,1] neg_hi:[0,1]
	v_pk_mul_f32 v[154:155], v[48:49], 1.0 op_sel:[1,0] op_sel_hi:[0,0] neg_hi:[1,0]
	v_pk_add_f32 v[68:69], v[60:61], v[118:119]
	v_pk_add_f32 v[58:59], v[60:61], v[118:119] neg_lo:[0,1] neg_hi:[0,1]
	v_pk_add_f32 v[110:111], v[106:107], v[82:83]
	v_pk_add_f32 v[106:107], v[106:107], v[82:83] neg_lo:[0,1] neg_hi:[0,1]
	v_pk_add_f32 v[118:119], v[74:75], v[78:79]
	v_pk_mul_f32 v[120:121], v[72:73], 1.0 op_sel:[1,0] op_sel_hi:[0,0] neg_hi:[1,0]
	v_pk_add_f32 v[60:61], v[122:123], v[52:53]
	v_pk_add_f32 v[46:47], v[122:123], v[52:53] neg_lo:[0,1] neg_hi:[0,1]
	v_pk_add_f32 v[52:53], v[50:51], v[124:125]
	v_pk_add_f32 v[54:55], v[50:51], v[124:125] neg_lo:[0,1] neg_hi:[0,1]
	v_pk_add_f32 v[50:51], v[126:127], v[42:43]
	v_pk_add_f32 v[44:45], v[126:127], v[42:43] neg_lo:[0,1] neg_hi:[0,1]
	v_pk_add_f32 v[42:43], v[128:129], v[154:155]
	v_pk_add_f32 v[48:49], v[128:129], v[154:155] neg_lo:[0,1] neg_hi:[0,1]
	v_pk_add_f32 v[84:85], v[86:87], v[108:109]
	v_pk_add_f32 v[86:87], v[86:87], v[108:109] neg_lo:[0,1] neg_hi:[0,1]
	v_pk_add_f32 v[78:79], v[92:93], v[100:101]
	v_pk_add_f32 v[74:75], v[92:93], v[100:101] neg_lo:[0,1] neg_hi:[0,1]
	v_pk_add_f32 v[72:73], v[96:97], v[104:105]
	v_pk_add_f32 v[76:77], v[96:97], v[104:105] neg_lo:[0,1] neg_hi:[0,1]
	v_pk_add_f32 v[82:83], v[88:89], v[98:99] op_sel:[0,1] op_sel_hi:[1,0] neg_hi:[0,1]
	v_pk_add_f32 v[80:81], v[88:89], v[98:99] op_sel:[0,1] op_sel_hi:[1,0] neg_lo:[0,1]
	v_pk_add_f32 v[88:89], v[110:111], v[112:113]
	v_pk_add_f32 v[96:97], v[110:111], v[112:113] neg_lo:[0,1] neg_hi:[0,1]
	v_pk_add_f32 v[98:99], v[106:107], v[102:103] op_sel:[0,1] op_sel_hi:[1,0] neg_hi:[0,1]
	v_pk_add_f32 v[102:103], v[106:107], v[102:103] op_sel:[0,1] op_sel_hi:[1,0] neg_lo:[0,1]
	v_pk_add_f32 v[104:105], v[114:115], v[118:119]
	v_pk_add_f32 v[106:107], v[114:115], v[118:119] neg_lo:[0,1] neg_hi:[0,1]
	v_pk_add_f32 v[108:109], v[116:117], v[120:121]
	v_pk_add_f32 v[114:115], v[116:117], v[120:121] neg_lo:[0,1] neg_hi:[0,1]
	v_mul_f32_e32 v36, 0x3f3504f3, v67
	v_mul_f32_e32 v100, 0xbec3ef15, v67
	v_mul_f32_e32 v92, 0xbf6c835e, v67
	s_and_saveexec_b64 s[6:7], vcc
	s_xor_b64 s[6:7], exec, s[6:7]
	s_cbranch_execz .LBB0_434
	v_pk_add_f32 v[110:111], v[94:95], v[114:115]
	v_pk_add_f32 v[94:95], v[94:95], v[114:115] neg_lo:[0,1] neg_hi:[0,1]
	v_mul_f32_e32 v112, 0.5, v110
	v_pk_fma_f32 v[114:115], v[66:67], 0, v[66:67] op_sel:[0,0,1] op_sel_hi:[1,0,0] neg_lo:[1,0,0]
	v_mov_b32_e32 v110, v94
	v_pk_mul_f32 v[110:111], v[110:111], s[78:79]
	s_mov_b32 s8, s45
	v_pk_mul_f32 v[116:117], v[114:115], v[110:111] op_sel:[0,1] op_sel_hi:[1,0]
	v_pk_mul_f32 v[110:111], v[114:115], v[110:111]
	s_mov_b32 s9, s42
	v_sub_f32_e32 v93, v110, v111
	v_fma_mixlo_f16 v101, v95, s79, v93
	v_fma_f32 v93, v95, 0.5, -v93
	v_cvt_f16_f32_sdwa v93, -v93 dst_sel:WORD_1 dst_unused:UNUSED_PAD src0_sel:DWORD
	v_pk_add_f32 v[94:95], v[116:117], v[116:117] op_sel:[0,1] op_sel_hi:[0,1]
	v_pk_add_f32 v[110:111], v[112:113], v[94:95]
	v_pk_add_f32 v[94:95], v[112:113], v[94:95] op_sel_hi:[0,1] neg_lo:[0,1] neg_hi:[0,1]
	v_cvt_pk_f16_f32 v94, v110, v95
	v_lshlrev_b32_e32 v101, 16, v101
	v_or_b32_sdwa v95, v93, v94 dst_sel:DWORD dst_unused:UNUSED_PAD src0_sel:DWORD src1_sel:WORD_1
	v_or_b32_sdwa v94, v101, v94 dst_sel:DWORD dst_unused:UNUSED_PAD src0_sel:DWORD src1_sel:WORD_0
	global_store_dwordx2 v[40:41], v[94:95], off
	v_pk_add_f32 v[94:95], v[90:91], v[108:109]
	v_pk_add_f32 v[90:91], v[90:91], v[108:109] neg_lo:[0,1] neg_hi:[0,1]
	v_mul_f32_e32 v110, 0.5, v94
	v_mov_b32_e32 v94, v67
	v_mov_b32_e32 v108, v67
	v_mov_b32_e32 v109, v66
	v_pk_fma_f32 v[112:113], v[66:67], 0, v[108:109] op_sel_hi:[1,0,1] neg_lo:[0,0,1] neg_hi:[0,0,1]
	v_pk_fma_f32 v[114:115], v[66:67], 0, v[94:95] op_sel_hi:[1,0,1]
	v_mov_b32_e32 v94, v90
	v_pk_mov_b32 v[112:113], v[112:113], v[114:115] op_sel:[1,0]
	v_pk_mul_f32 v[94:95], v[94:95], s[78:79]
	s_mov_b32 s43, s45
	v_pk_mul_f32 v[114:115], v[112:113], v[94:95] op_sel:[0,1] op_sel_hi:[1,0]
	v_pk_mul_f32 v[94:95], v[112:113], v[94:95]
	v_pk_fma_f32 v[112:113], v[108:109], s[68:69], v[36:37] op_sel_hi:[1,1,0]
	v_sub_f32_e32 v90, v94, v95
	v_fma_mixlo_f16 v93, v91, s79, v90
	v_fma_f32 v90, v91, 0.5, -v90
	v_cvt_f16_f32_sdwa v101, -v90 dst_sel:WORD_1 dst_unused:UNUSED_PAD src0_sel:DWORD
	v_pk_add_f32 v[90:91], v[114:115], v[114:115] op_sel:[0,1] op_sel_hi:[0,1]
	v_pk_add_f32 v[94:95], v[110:111], v[90:91]
	v_pk_add_f32 v[90:91], v[110:111], v[90:91] op_sel_hi:[0,1] neg_lo:[0,1] neg_hi:[0,1]
	v_cvt_pk_f16_f32 v90, v94, v91
	v_lshlrev_b32_e32 v93, 16, v93
	v_or_b32_sdwa v91, v101, v90 dst_sel:DWORD dst_unused:UNUSED_PAD src0_sel:DWORD src1_sel:WORD_1
	v_or_b32_sdwa v90, v93, v90 dst_sel:DWORD dst_unused:UNUSED_PAD src0_sel:DWORD src1_sel:WORD_0
	global_store_dwordx2 v[40:41], v[90:91], off offset:2048
	v_pk_mul_f32 v[90:91], v[108:109], s[68:69]
	v_pk_add_f32 v[94:95], v[70:71], v[106:107]
	v_pk_add_f32 v[70:71], v[70:71], v[106:107] neg_lo:[0,1] neg_hi:[0,1]
	v_mul_f32_e32 v110, 0.5, v94
	v_pk_add_f32 v[106:107], v[36:37], v[90:91] op_sel:[0,1] op_sel_hi:[0,1] neg_lo:[0,1] neg_hi:[0,1]
	v_mov_b32_e32 v94, v70
	v_mov_b32_e32 v107, v113
	v_pk_mul_f32 v[94:95], v[94:95], s[78:79]
	v_mov_b32_e32 v101, v58
	v_pk_mul_f32 v[112:113], v[106:107], v[94:95] op_sel:[0,1] op_sel_hi:[1,0]
	v_pk_mul_f32 v[94:95], v[106:107], v[94:95]
	s_mov_b32 s39, s27
	v_sub_f32_e32 v36, v94, v95
	v_fma_mixlo_f16 v93, v71, s79, v36
	v_fma_f32 v36, v71, 0.5, -v36
	v_pk_add_f32 v[70:71], v[112:113], v[112:113] op_sel:[0,1] op_sel_hi:[0,1]
	v_cvt_f16_f32_sdwa v36, -v36 dst_sel:WORD_1 dst_unused:UNUSED_PAD src0_sel:DWORD
	v_pk_add_f32 v[94:95], v[110:111], v[70:71]
	v_pk_add_f32 v[70:71], v[110:111], v[70:71] op_sel_hi:[0,1] neg_lo:[0,1] neg_hi:[0,1]
	v_cvt_pk_f16_f32 v70, v94, v71
	v_add_co_u32_e32 v94, vcc, s34, v40
	v_lshlrev_b32_e32 v93, 16, v93
	s_nop 0
	v_addc_co_u32_e32 v95, vcc, 0, v41, vcc
	v_add_co_u32_e32 v110, vcc, s3, v40
	v_or_b32_sdwa v71, v36, v70 dst_sel:DWORD dst_unused:UNUSED_PAD src0_sel:DWORD src1_sel:WORD_1
	v_or_b32_sdwa v70, v93, v70 dst_sel:DWORD dst_unused:UNUSED_PAD src0_sel:DWORD src1_sel:WORD_0
	v_addc_co_u32_e32 v111, vcc, 0, v41, vcc
	global_store_dwordx2 v[110:111], v[70:71], off offset:-4096
	v_pk_fma_f32 v[70:71], v[108:109], s[68:69], v[90:91] op_sel:[0,0,1] op_sel_hi:[1,1,0] neg_lo:[0,0,1] neg_hi:[0,0,1]
	v_pk_add_f32 v[90:91], v[64:65], v[104:105]
	v_pk_add_f32 v[64:65], v[64:65], v[104:105] neg_lo:[0,1] neg_hi:[0,1]
	v_mul_f32_e32 v36, 0.5, v90
	v_mov_b32_e32 v90, v64
	v_pk_mul_f32 v[90:91], v[90:91], s[78:79]
	v_mov_b32_e32 v71, v106
	v_mov_b32_e32 v107, v70
	v_pk_mul_f32 v[70:71], v[70:71], v[90:91]
	v_pk_mul_f32 v[104:105], v[106:107], v[90:91]
	v_sub_f32_e32 v64, v70, v71
	v_fma_mixlo_f16 v90, v65, s79, v64
	v_fma_f32 v64, v65, 0.5, -v64
	v_cvt_f16_f32_sdwa v91, -v64 dst_sel:WORD_1 dst_unused:UNUSED_PAD src0_sel:DWORD
	v_pk_add_f32 v[64:65], v[104:105], v[104:105] op_sel:[1,0] op_sel_hi:[1,0]
	s_nop 0
	v_pk_add_f32 v[70:71], v[36:37], v[64:65]
	v_pk_add_f32 v[64:65], v[36:37], v[64:65] op_sel_hi:[0,1] neg_lo:[0,1] neg_hi:[0,1]
	v_cvt_pk_f16_f32 v36, v70, v65
	v_lshlrev_b32_e32 v64, 16, v90
	v_or_b32_sdwa v65, v91, v36 dst_sel:DWORD dst_unused:UNUSED_PAD src0_sel:DWORD src1_sel:WORD_1
	v_or_b32_sdwa v64, v64, v36 dst_sel:DWORD dst_unused:UNUSED_PAD src0_sel:DWORD src1_sel:WORD_0
	global_store_dwordx2 v[94:95], v[64:65], off offset:2048
	v_mov_b32_e32 v64, v67
	v_pk_mul_f32 v[70:71], v[66:67], s[8:9] op_sel_hi:[0,1]
	v_pk_add_f32 v[90:91], v[68:69], v[102:103]
	v_pk_add_f32 v[68:69], v[68:69], v[102:103] neg_lo:[0,1] neg_hi:[0,1]
	v_mul_f32_e32 v36, 0.5, v90
	v_pk_fma_f32 v[94:95], v[64:65], s[42:43], v[70:71] op_sel_hi:[0,1,1] neg_lo:[0,0,1] neg_hi:[0,0,1]
	v_pk_fma_f32 v[102:103], v[64:65], s[42:43], v[70:71] op_sel_hi:[0,1,1]
	v_mov_b32_e32 v90, v68
	v_mov_b32_e32 v104, v94
	v_mov_b32_e32 v105, v103
	v_pk_mul_f32 v[90:91], v[90:91], s[78:79]
	s_mov_b32 s8, s27
	v_pk_mul_f32 v[106:107], v[104:105], v[90:91] op_sel:[0,1] op_sel_hi:[1,0]
	v_pk_mul_f32 v[90:91], v[104:105], v[90:91]
	s_mov_b32 s9, s38
	v_sub_f32_e32 v65, v90, v91
	v_fma_mixlo_f16 v93, v69, s79, v65
	v_fma_f32 v65, v69, 0.5, -v65
	v_cvt_f16_f32_sdwa v65, -v65 dst_sel:WORD_1 dst_unused:UNUSED_PAD src0_sel:DWORD
	v_pk_add_f32 v[68:69], v[106:107], v[106:107] op_sel:[0,1] op_sel_hi:[0,1]
	v_pk_add_f32 v[90:91], v[36:37], v[68:69]
	v_pk_add_f32 v[68:69], v[36:37], v[68:69] op_sel_hi:[0,1] neg_lo:[0,1] neg_hi:[0,1]
	v_cvt_pk_f16_f32 v36, v90, v69
	v_lshlrev_b32_e32 v68, 16, v93
	v_or_b32_sdwa v69, v65, v36 dst_sel:DWORD dst_unused:UNUSED_PAD src0_sel:DWORD src1_sel:WORD_1
	v_or_b32_sdwa v68, v68, v36 dst_sel:DWORD dst_unused:UNUSED_PAD src0_sel:DWORD src1_sel:WORD_0
	global_store_dwordx2 v[110:111], v[68:69], off
	v_pk_add_f32 v[68:69], v[58:59], v[98:99]
	v_sub_f32_e32 v65, v59, v99
	v_pk_mov_b32 v[58:59], v[70:71], v[98:99] op_sel:[1,0]
	v_mul_f32_e32 v36, 0.5, v69
	v_pk_add_f32 v[58:59], v[100:101], v[58:59] neg_lo:[0,1] neg_hi:[0,1]
	v_mul_f32_e32 v90, 0.5, v68
	v_pk_mul_f32 v[98:99], v[58:59], v[36:37]
	v_mov_b32_e32 v93, v62
	v_mul_f32_e32 v58, v58, v99
	v_fma_f32 v36, -v94, v36, v58
	v_fma_mixlo_f16 v69, v65, s79, v36
	v_fma_f32 v36, v65, 0.5, -v36
	v_pk_fma_f32 v[100:101], v[94:95], v[98:99], v[98:99] op_sel:[0,1,0] op_sel_hi:[1,0,1]
	v_cvt_f16_f32_sdwa v36, -v36 dst_sel:WORD_1 dst_unused:UNUSED_PAD src0_sel:DWORD
	v_pk_add_f32 v[58:59], v[90:91], v[100:101]
	v_lshlrev_b32_e32 v65, 16, v69
	v_fma_f32 v59, v68, 0.5, -v100
	v_cvt_pk_f16_f32 v58, v58, v59
	v_or_b32_sdwa v59, v36, v58 dst_sel:DWORD dst_unused:UNUSED_PAD src0_sel:DWORD src1_sel:WORD_1
	v_or_b32_sdwa v58, v65, v58 dst_sel:DWORD dst_unused:UNUSED_PAD src0_sel:DWORD src1_sel:WORD_0
	global_store_dwordx2 v[110:111], v[58:59], off offset:2048
	v_pk_add_f32 v[58:59], v[96:97], v[56:57]
	v_pk_add_f32 v[56:57], v[56:57], v[96:97] neg_lo:[0,1] neg_hi:[0,1]
	v_mul_f32_e32 v36, 0.5, v58
	v_mov_b32_e32 v58, v56
	v_pk_mov_b32 v[68:69], v[94:95], v[102:103] op_sel:[1,0]
	v_pk_mul_f32 v[58:59], v[58:59], s[78:79]
	s_nop 0
	v_pk_mul_f32 v[90:91], v[68:69], v[58:59] op_sel:[0,1] op_sel_hi:[1,0]
	v_pk_mul_f32 v[58:59], v[68:69], v[58:59]
	s_nop 0
	v_sub_f32_e32 v56, v58, v59
	v_fma_mixlo_f16 v65, v57, s79, v56
	v_fma_f32 v56, v57, 0.5, -v56
	v_cvt_f16_f32_sdwa v71, -v56 dst_sel:WORD_1 dst_unused:UNUSED_PAD src0_sel:DWORD
	v_pk_add_f32 v[56:57], v[90:91], v[90:91] op_sel:[0,1] op_sel_hi:[0,1]
	v_pk_add_f32 v[58:59], v[36:37], v[56:57]
	v_pk_add_f32 v[56:57], v[36:37], v[56:57] op_sel_hi:[0,1] neg_lo:[0,1] neg_hi:[0,1]
	v_cvt_pk_f16_f32 v36, v58, v57
	v_add_co_u32_e32 v58, vcc, s35, v40
	v_lshlrev_b32_e32 v56, 16, v65
	s_nop 0
	v_addc_co_u32_e32 v59, vcc, 0, v41, vcc
	v_add_co_u32_e32 v90, vcc, s37, v40
	v_or_b32_sdwa v57, v71, v36 dst_sel:DWORD dst_unused:UNUSED_PAD src0_sel:DWORD src1_sel:WORD_1
	v_or_b32_sdwa v56, v56, v36 dst_sel:DWORD dst_unused:UNUSED_PAD src0_sel:DWORD src1_sel:WORD_0
	v_addc_co_u32_e32 v91, vcc, 0, v41, vcc
	global_store_dwordx2 v[90:91], v[56:57], off offset:-4096
	v_pk_add_f32 v[56:57], v[88:89], v[62:63]
	v_mov_b32_e32 v71, v88
	v_sub_f32_e32 v65, v63, v89
	v_mul_f32_e32 v36, 0.5, v57
	v_pk_add_f32 v[62:63], v[92:93], v[70:71] neg_lo:[0,1] neg_hi:[0,1]
	v_mul_f32_e32 v94, 0.5, v56
	v_pk_mul_f32 v[70:71], v[62:63], v[36:37]
	s_nop 0
	v_mul_f32_e32 v57, v62, v71
	v_fma_f32 v36, -v95, v36, v57
	v_fma_mixlo_f16 v57, v65, s79, v36
	v_fma_f32 v36, v65, 0.5, -v36
	v_cvt_f16_f32_sdwa v36, -v36 dst_sel:WORD_1 dst_unused:UNUSED_PAD src0_sel:DWORD
	v_pk_fma_f32 v[68:69], v[68:69], v[70:71], v[70:71] op_sel:[0,1,0] op_sel_hi:[1,0,1]
	s_nop 0
	v_pk_add_f32 v[62:63], v[94:95], v[68:69]
	v_fma_f32 v56, v56, 0.5, -v68
	v_cvt_pk_f16_f32 v56, v62, v56
	v_lshlrev_b32_e32 v62, 16, v57
	v_or_b32_sdwa v57, v36, v56 dst_sel:DWORD dst_unused:UNUSED_PAD src0_sel:DWORD src1_sel:WORD_1
	v_or_b32_sdwa v56, v62, v56 dst_sel:DWORD dst_unused:UNUSED_PAD src0_sel:DWORD src1_sel:WORD_0
	global_store_dwordx2 v[58:59], v[56:57], off offset:2048
	v_pk_mul_f32 v[56:57], v[66:67], s[38:39] op_sel_hi:[0,1]
	v_pk_add_f32 v[58:59], v[60:61], v[80:81]
	v_pk_add_f32 v[60:61], v[60:61], v[80:81] neg_lo:[0,1] neg_hi:[0,1]
	v_mul_f32_e32 v36, 0.5, v58
	v_pk_fma_f32 v[62:63], v[64:65], s[8:9], v[56:57] op_sel_hi:[0,1,1] neg_lo:[0,0,1] neg_hi:[0,0,1]
	v_pk_fma_f32 v[68:69], v[64:65], s[8:9], v[56:57] op_sel_hi:[0,1,1]
	v_mov_b32_e32 v58, v60
	v_mov_b32_e32 v70, v62
	v_mov_b32_e32 v71, v69
	v_pk_mul_f32 v[58:59], v[58:59], s[78:79]
	s_mov_b32 s8, s47
	v_pk_mul_f32 v[80:81], v[70:71], v[58:59] op_sel:[0,1] op_sel_hi:[1,0]
	v_pk_mul_f32 v[58:59], v[70:71], v[58:59]
	s_mov_b32 s9, s46
	v_sub_f32_e32 v58, v58, v59
	v_fma_mixlo_f16 v65, v61, s79, v58
	v_fma_f32 v58, v61, 0.5, -v58
	v_cvt_f16_f32_sdwa v70, -v58 dst_sel:WORD_1 dst_unused:UNUSED_PAD src0_sel:DWORD
	v_pk_add_f32 v[58:59], v[80:81], v[80:81] op_sel:[0,1] op_sel_hi:[0,1]
	v_pk_add_f32 v[60:61], v[36:37], v[58:59]
	v_pk_add_f32 v[58:59], v[36:37], v[58:59] op_sel_hi:[0,1] neg_lo:[0,1] neg_hi:[0,1]
	v_cvt_pk_f16_f32 v36, v60, v59
	v_lshlrev_b32_e32 v58, 16, v65
	v_or_b32_sdwa v59, v70, v36 dst_sel:DWORD dst_unused:UNUSED_PAD src0_sel:DWORD src1_sel:WORD_1
	v_or_b32_sdwa v58, v58, v36 dst_sel:DWORD dst_unused:UNUSED_PAD src0_sel:DWORD src1_sel:WORD_0
	global_store_dwordx2 v[90:91], v[58:59], off
	v_mul_f32_e32 v58, 0xbe47c5c2, v67
	v_pk_add_f32 v[60:61], v[46:47], v[82:83]
	v_sub_f32_e32 v65, v47, v83
	v_mov_b32_e32 v59, v46
	v_pk_mov_b32 v[46:47], v[56:57], v[82:83] op_sel:[1,0]
	v_mul_f32_e32 v36, 0.5, v61
	v_pk_add_f32 v[46:47], v[58:59], v[46:47] neg_lo:[0,1] neg_hi:[0,1]
	v_mul_f32_e32 v70, 0.5, v60
	v_pk_mul_f32 v[58:59], v[46:47], v[36:37]
	s_nop 0
	v_mul_f32_e32 v46, v46, v59
	v_fma_f32 v36, -v62, v36, v46
	v_fma_mixlo_f16 v57, v65, s79, v36
	v_fma_f32 v36, v65, 0.5, -v36
	v_pk_fma_f32 v[80:81], v[62:63], v[58:59], v[58:59] op_sel:[0,1,0] op_sel_hi:[1,0,1]
	v_cvt_f16_f32_sdwa v36, -v36 dst_sel:WORD_1 dst_unused:UNUSED_PAD src0_sel:DWORD
	v_pk_add_f32 v[46:47], v[70:71], v[80:81]
	v_lshlrev_b32_e32 v57, 16, v57
	v_fma_f32 v47, v60, 0.5, -v80
	v_cvt_pk_f16_f32 v46, v46, v47
	v_or_b32_sdwa v47, v36, v46 dst_sel:DWORD dst_unused:UNUSED_PAD src0_sel:DWORD src1_sel:WORD_1
	v_or_b32_sdwa v46, v57, v46 dst_sel:DWORD dst_unused:UNUSED_PAD src0_sel:DWORD src1_sel:WORD_0
	global_store_dwordx2 v[90:91], v[46:47], off offset:2048
	v_pk_mul_f32 v[46:47], v[66:67], s[8:9] op_sel_hi:[0,1]
	v_pk_add_f32 v[58:59], v[76:77], v[52:53]
	v_pk_add_f32 v[52:53], v[52:53], v[76:77] neg_lo:[0,1] neg_hi:[0,1]
	v_mul_f32_e32 v36, 0.5, v58
	v_pk_fma_f32 v[60:61], v[64:65], s[46:47], v[46:47] op_sel_hi:[0,1,1] neg_lo:[0,0,1] neg_hi:[0,0,1]
	v_pk_fma_f32 v[64:65], v[64:65], s[46:47], v[46:47] op_sel_hi:[0,1,1]
	v_mov_b32_e32 v58, v52
	v_mov_b32_e32 v70, v60
	v_mov_b32_e32 v71, v65
	v_pk_mul_f32 v[58:59], v[58:59], s[78:79]
	s_nop 0
	v_pk_mul_f32 v[76:77], v[70:71], v[58:59] op_sel:[0,1] op_sel_hi:[1,0]
	v_pk_mul_f32 v[58:59], v[70:71], v[58:59]
	s_nop 0
	v_sub_f32_e32 v52, v58, v59
	v_fma_mixlo_f16 v57, v53, s79, v52
	v_fma_f32 v52, v53, 0.5, -v52
	v_cvt_f16_f32_sdwa v66, -v52 dst_sel:WORD_1 dst_unused:UNUSED_PAD src0_sel:DWORD
	v_pk_add_f32 v[52:53], v[76:77], v[76:77] op_sel:[0,1] op_sel_hi:[0,1]
	v_pk_add_f32 v[58:59], v[36:37], v[52:53]
	v_pk_add_f32 v[52:53], v[36:37], v[52:53] op_sel_hi:[0,1] neg_lo:[0,1] neg_hi:[0,1]
	v_cvt_pk_f16_f32 v36, v58, v53
	v_add_co_u32_e32 v58, vcc, s51, v40
	v_lshlrev_b32_e32 v52, 16, v57
	s_nop 0
	v_addc_co_u32_e32 v59, vcc, 0, v41, vcc
	v_add_co_u32_e32 v70, vcc, s60, v40
	v_or_b32_sdwa v53, v66, v36 dst_sel:DWORD dst_unused:UNUSED_PAD src0_sel:DWORD src1_sel:WORD_1
	v_or_b32_sdwa v52, v52, v36 dst_sel:DWORD dst_unused:UNUSED_PAD src0_sel:DWORD src1_sel:WORD_0
	v_addc_co_u32_e32 v71, vcc, 0, v41, vcc
	global_store_dwordx2 v[70:71], v[52:53], off offset:-4096
	v_mul_f32_e32 v52, 0xbf54db31, v67
	v_pk_add_f32 v[76:77], v[72:73], v[54:55]
	v_sub_f32_e32 v57, v55, v73
	v_mov_b32_e32 v53, v54
	v_pk_mov_b32 v[54:55], v[46:47], v[72:73] op_sel:[1,0]
	v_mul_f32_e32 v36, 0.5, v77
	v_pk_add_f32 v[52:53], v[52:53], v[54:55] neg_lo:[0,1] neg_hi:[0,1]
	v_mul_f32_e32 v66, 0.5, v76
	v_pk_mul_f32 v[54:55], v[52:53], v[36:37]
	s_nop 0
	v_mul_f32_e32 v47, v52, v55
	v_fma_f32 v36, -v60, v36, v47
	v_fma_mixlo_f16 v47, v57, s79, v36
	v_fma_f32 v36, v57, 0.5, -v36
	v_pk_fma_f32 v[72:73], v[60:61], v[54:55], v[54:55] op_sel:[0,1,0] op_sel_hi:[1,0,1]
	v_cvt_f16_f32_sdwa v36, -v36 dst_sel:WORD_1 dst_unused:UNUSED_PAD src0_sel:DWORD
	v_pk_add_f32 v[52:53], v[66:67], v[72:73]
	v_lshlrev_b32_e32 v47, 16, v47
	v_fma_f32 v53, v76, 0.5, -v72
	v_cvt_pk_f16_f32 v52, v52, v53
	v_or_b32_sdwa v53, v36, v52 dst_sel:DWORD dst_unused:UNUSED_PAD src0_sel:DWORD src1_sel:WORD_1
	v_or_b32_sdwa v52, v47, v52 dst_sel:DWORD dst_unused:UNUSED_PAD src0_sel:DWORD src1_sel:WORD_0
	global_store_dwordx2 v[58:59], v[52:53], off offset:2048
	v_pk_add_f32 v[52:53], v[74:75], v[50:51]
	v_pk_add_f32 v[50:51], v[50:51], v[74:75] neg_lo:[0,1] neg_hi:[0,1]
	v_mul_f32_e32 v36, 0.5, v52
	v_mov_b32_e32 v52, v50
	v_pk_mov_b32 v[54:55], v[60:61], v[64:65] op_sel:[1,0]
	v_pk_mul_f32 v[52:53], v[52:53], s[78:79]
	s_nop 0
	v_pk_mul_f32 v[58:59], v[54:55], v[52:53] op_sel:[0,1] op_sel_hi:[1,0]
	v_pk_mul_f32 v[52:53], v[54:55], v[52:53]
	s_nop 0
	v_sub_f32_e32 v47, v52, v53
	v_fma_mixlo_f16 v57, v51, s79, v47
	v_fma_f32 v47, v51, 0.5, -v47
	v_cvt_f16_f32_sdwa v47, -v47 dst_sel:WORD_1 dst_unused:UNUSED_PAD src0_sel:DWORD
	v_pk_add_f32 v[50:51], v[58:59], v[58:59] op_sel:[0,1] op_sel_hi:[0,1]
	v_pk_add_f32 v[52:53], v[36:37], v[50:51]
	v_pk_add_f32 v[50:51], v[36:37], v[50:51] op_sel_hi:[0,1] neg_lo:[0,1] neg_hi:[0,1]
	v_cvt_pk_f16_f32 v36, v52, v51
	v_lshlrev_b32_e32 v50, 16, v57
	v_or_b32_sdwa v51, v47, v36 dst_sel:DWORD dst_unused:UNUSED_PAD src0_sel:DWORD src1_sel:WORD_1
	v_or_b32_sdwa v50, v50, v36 dst_sel:DWORD dst_unused:UNUSED_PAD src0_sel:DWORD src1_sel:WORD_0
	global_store_dwordx2 v[70:71], v[50:51], off
	v_mul_f32_e32 v50, 0xbf0e39da, v67
	v_pk_add_f32 v[52:53], v[78:79], v[44:45]
	v_mov_b32_e32 v51, v44
	v_mov_b32_e32 v47, v78
	v_sub_f32_e32 v57, v45, v79
	v_mul_f32_e32 v36, 0.5, v53
	v_pk_add_f32 v[44:45], v[50:51], v[46:47] neg_lo:[0,1] neg_hi:[0,1]
	v_mul_f32_e32 v58, 0.5, v52
	v_pk_mul_f32 v[46:47], v[44:45], v[36:37]
	s_nop 0
	v_mul_f32_e32 v44, v44, v47
	v_fma_f32 v36, -v61, v36, v44
	v_pk_fma_f32 v[50:51], v[54:55], v[46:47], v[46:47] op_sel:[0,1,0] op_sel_hi:[1,0,1]
	v_fma_mixlo_f16 v46, v57, s79, v36
	v_fma_f32 v36, v57, 0.5, -v36
	v_cvt_f16_f32_sdwa v36, -v36 dst_sel:WORD_1 dst_unused:UNUSED_PAD src0_sel:DWORD
	v_pk_add_f32 v[44:45], v[58:59], v[50:51]
	v_lshlrev_b32_e32 v46, 16, v46
	v_fma_f32 v45, v52, 0.5, -v50
	v_cvt_pk_f16_f32 v44, v44, v45
	v_or_b32_sdwa v45, v36, v44 dst_sel:DWORD dst_unused:UNUSED_PAD src0_sel:DWORD src1_sel:WORD_1
	v_or_b32_sdwa v44, v46, v44 dst_sel:DWORD dst_unused:UNUSED_PAD src0_sel:DWORD src1_sel:WORD_0
	global_store_dwordx2 v[70:71], v[44:45], off offset:2048
	v_pk_add_f32 v[44:45], v[86:87], v[42:43]
	v_pk_add_f32 v[42:43], v[42:43], v[86:87] neg_lo:[0,1] neg_hi:[0,1]
	v_mul_f32_e32 v36, 0.5, v44
	v_mov_b32_e32 v44, v42
	v_pk_mov_b32 v[46:47], v[62:63], v[68:69] op_sel:[1,0]
	v_pk_mul_f32 v[44:45], v[44:45], s[78:79]
	s_nop 0
	v_pk_mul_f32 v[50:51], v[46:47], v[44:45] op_sel:[0,1] op_sel_hi:[1,0]
	v_pk_mul_f32 v[44:45], v[46:47], v[44:45]
	s_nop 0
	v_sub_f32_e32 v42, v44, v45
	v_fma_mixlo_f16 v46, v43, s79, v42
	v_fma_f32 v42, v43, 0.5, -v42
	v_cvt_f16_f32_sdwa v47, -v42 dst_sel:WORD_1 dst_unused:UNUSED_PAD src0_sel:DWORD
	v_pk_add_f32 v[42:43], v[50:51], v[50:51] op_sel:[0,1] op_sel_hi:[0,1]
	v_pk_add_f32 v[44:45], v[36:37], v[42:43]
	v_pk_add_f32 v[42:43], v[36:37], v[42:43] op_sel_hi:[0,1] neg_lo:[0,1] neg_hi:[0,1]
	v_cvt_pk_f16_f32 v36, v44, v43
	v_lshlrev_b32_e32 v42, 16, v46
	v_or_b32_sdwa v43, v47, v36 dst_sel:DWORD dst_unused:UNUSED_PAD src0_sel:DWORD src1_sel:WORD_1
	v_pk_add_f32 v[44:45], v[48:49], v[84:85]
	v_pk_add_f32 v[46:47], v[48:49], v[84:85] neg_lo:[0,1] neg_hi:[0,1]
	v_mov_b32_e32 v48, v44
	v_mov_b32_e32 v49, v47
	v_mov_b32_e32 v47, v45
	v_pk_mul_f32 v[44:45], v[46:47], s[78:79]
	v_or_b32_sdwa v42, v42, v36 dst_sel:DWORD dst_unused:UNUSED_PAD src0_sel:DWORD src1_sel:WORD_0
	v_fma_f32 v36, v67, s26, -v56
	v_pk_mul_f32 v[46:47], v[62:63], v[44:45] op_sel:[1,0]
	s_nop 0
	v_pk_fma_f32 v[50:51], v[36:37], v[44:45], v[46:47] op_sel:[0,1,0] op_sel_hi:[0,0,1] neg_hi:[0,0,1]
	s_nop 0
	v_pk_fma_f32 v[44:45], v[48:49], 0.5, v[50:51] op_sel_hi:[1,0,1]
	v_pk_fma_f32 v[112:113], v[48:49], 0.5, v[50:51] op_sel_hi:[1,0,1] neg_lo:[0,0,1] neg_hi:[0,0,1]
	v_cvt_f16_f32_e32 v36, v44
	v_cvt_f16_f32_sdwa v46, v45 dst_sel:WORD_1 dst_unused:UNUSED_PAD src0_sel:DWORD
	v_add_co_u32_e32 v44, vcc, s61, v40
	v_or_b32_e32 v110, v46, v36
	s_nop 0
	v_addc_co_u32_e32 v45, vcc, 0, v41, vcc
	global_store_dwordx2 v[44:45], v[42:43], off

.LBB0_499:
	v_mov_b32_e32 v2, v210
	s_mov_b32 s43, s8
	v_and_b32_e32 v3, 0x1ff, v2
	v_lshlrev_b32_e32 v2, 5, v2
	v_and_or_b32 v2, v2, s94, v3
	v_ashrrev_i32_e32 v4, 5, v2
	v_lshlrev_b32_e32 v2, 3, v2
	v_lshlrev_b32_e32 v4, 3, v4
	v_add3_u32 v18, 0, v2, v4
	ds_read_b64 v[128:129], v18
	ds_read_b64 v[134:135], v18 offset:4224
	ds_read_b64 v[136:137], v18 offset:8448
	ds_read_b64 v[138:139], v18 offset:12672
	ds_read_b64 v[140:141], v18 offset:16896
	ds_read_b64 v[142:143], v18 offset:21120
	ds_read_b64 v[132:133], v18 offset:25344
	ds_read_b64 v[130:131], v18 offset:29568
	ds_read_b64 v[144:145], v18 offset:33792
	ds_read_b64 v[148:149], v18 offset:38016
	ds_read_b64 v[150:151], v18 offset:42240
	ds_read_b64 v[152:153], v18 offset:46464
	s_waitcnt lgkmcnt(10)
	v_pk_mul_f32 v[162:163], v[134:135], s[10:11]
	s_mov_b32 s74, s11
	v_pk_fma_f32 v[162:163], v[134:135], s[8:9], v[162:163] op_sel:[0,0,1] op_sel_hi:[1,0,0]
	s_waitcnt lgkmcnt(2)
	v_pk_mul_f32 v[178:179], v[148:149], s[42:43]
	v_pk_add_f32 v[194:195], v[134:135], v[148:149]
	v_pk_add_f32 v[134:135], v[134:135], v[148:149] neg_lo:[0,1] neg_hi:[0,1]
	v_pk_mul_f32 v[164:165], v[136:137], s[18:19]
	s_mov_b32 s41, s16
	v_pk_fma_f32 v[178:179], v[148:149], s[74:75], v[178:179] op_sel:[0,0,1] op_sel_hi:[1,0,0] neg_lo:[1,0,0] neg_hi:[1,0,0]
	v_pk_mul_f32 v[148:149], v[134:135], s[18:19]
	v_pk_fma_f32 v[164:165], v[136:137], s[16:17], v[164:165] op_sel:[0,0,1] op_sel_hi:[1,0,0]
	s_mov_b32 s80, s19
	s_waitcnt lgkmcnt(1)
	v_pk_mul_f32 v[180:181], v[150:151], s[40:41]
	v_pk_fma_f32 v[134:135], v[134:135], s[16:17], v[148:149] op_sel:[0,0,1] op_sel_hi:[1,0,0]
	v_pk_add_f32 v[148:149], v[136:137], v[150:151]
	v_pk_add_f32 v[136:137], v[136:137], v[150:151] neg_lo:[0,1] neg_hi:[0,1]
	v_pk_mul_f32 v[166:167], v[138:139], s[26:27]
	s_mov_b32 s78, s37
	s_mov_b32 s39, s24
	v_pk_fma_f32 v[180:181], v[150:151], s[80:81], v[180:181] op_sel:[0,0,1] op_sel_hi:[1,0,0] neg_lo:[1,0,0] neg_hi:[1,0,0]
	v_pk_mul_f32 v[150:151], v[136:137], s[36:37]
	ds_read_b64 v[154:155], v18 offset:50688
	ds_read_b64 v[156:157], v18 offset:54912
	ds_read_b64 v[158:159], v18 offset:59136
	ds_read_b64 v[160:161], v18 offset:63360
	v_pk_fma_f32 v[166:167], v[138:139], s[24:25], v[166:167] op_sel:[0,0,1] op_sel_hi:[1,0,0]
	s_mov_b32 s0, s27
	s_waitcnt lgkmcnt(4)
	v_pk_mul_f32 v[182:183], v[152:153], s[38:39]
	v_pk_fma_f32 v[136:137], v[136:137], s[78:79], v[150:151] op_sel:[0,0,1] op_sel_hi:[1,0,0]
	v_pk_add_f32 v[150:151], v[138:139], v[152:153]
	v_pk_add_f32 v[138:139], v[138:139], v[152:153] neg_lo:[0,1] neg_hi:[0,1]
	v_pk_mul_f32 v[168:169], v[140:141], s[36:37]
	v_pk_fma_f32 v[182:183], v[152:153], s[0:1], v[182:183] op_sel:[0,0,1] op_sel_hi:[1,0,0] neg_lo:[1,0,0] neg_hi:[1,0,0]
	v_pk_mul_f32 v[152:153], v[138:139], s[40:41]
	v_pk_fma_f32 v[168:169], v[140:141], s[78:79], v[168:169] op_sel:[0,0,1] op_sel_hi:[1,0,0]
	v_pk_mul_f32 v[170:171], v[142:143], s[38:39]
	s_waitcnt lgkmcnt(3)
	v_pk_mul_f32 v[184:185], v[154:155], s[36:37]
	v_pk_fma_f32 v[138:139], v[138:139], s[80:81], v[152:153] op_sel:[0,0,1] op_sel_hi:[1,0,0]
	v_pk_add_f32 v[152:153], v[140:141], v[154:155]
	v_pk_add_f32 v[140:141], v[140:141], v[154:155] neg_lo:[0,1] neg_hi:[0,1]
	v_pk_fma_f32 v[170:171], v[142:143], s[0:1], v[170:171] op_sel:[0,0,1] op_sel_hi:[1,0,0]
	v_pk_fma_f32 v[184:185], v[154:155], s[78:79], v[184:185] op_sel:[0,0,1] op_sel_hi:[1,0,0] neg_lo:[1,0,0] neg_hi:[1,0,0]
	s_waitcnt lgkmcnt(2)
	v_pk_mul_f32 v[186:187], v[156:157], s[26:27]
	v_pk_mul_f32 v[154:155], v[140:141], 1.0 op_sel:[1,0] op_sel_hi:[0,0] neg_hi:[1,0]
	v_pk_add_f32 v[140:141], v[142:143], v[156:157]
	v_pk_add_f32 v[142:143], v[142:143], v[156:157] neg_lo:[0,1] neg_hi:[0,1]
	v_pk_mul_f32 v[172:173], v[132:133], s[40:41]
	v_pk_fma_f32 v[186:187], v[156:157], s[24:25], v[186:187] op_sel:[0,0,1] op_sel_hi:[1,0,0] neg_lo:[1,0,0] neg_hi:[1,0,0]
	v_pk_mul_f32 v[156:157], v[142:143], s[40:41]
	v_pk_fma_f32 v[172:173], v[132:133], s[80:81], v[172:173] op_sel:[0,0,1] op_sel_hi:[1,0,0]
	s_waitcnt lgkmcnt(1)
	v_pk_mul_f32 v[188:189], v[158:159], s[18:19]
	v_pk_fma_f32 v[142:143], v[142:143], s[80:81], v[156:157] op_sel:[0,0,1] op_sel_hi:[1,0,0] neg_lo:[1,0,0] neg_hi:[1,0,0]
	v_pk_add_f32 v[156:157], v[132:133], v[158:159]
	v_pk_add_f32 v[132:133], v[132:133], v[158:159] neg_lo:[0,1] neg_hi:[0,1]
	v_pk_mul_f32 v[174:175], v[130:131], s[42:43]
	v_pk_fma_f32 v[188:189], v[158:159], s[16:17], v[188:189] op_sel:[0,0,1] op_sel_hi:[1,0,0] neg_lo:[1,0,0] neg_hi:[1,0,0]
	v_pk_mul_f32 v[158:159], v[132:133], s[36:37]
	v_pk_fma_f32 v[174:175], v[130:131], s[74:75], v[174:175] op_sel:[0,0,1] op_sel_hi:[1,0,0]
	s_waitcnt lgkmcnt(0)
	v_pk_mul_f32 v[190:191], v[160:161], s[10:11]
	v_pk_fma_f32 v[132:133], v[132:133], s[78:79], v[158:159] op_sel:[0,0,1] op_sel_hi:[1,0,0] neg_lo:[1,0,0] neg_hi:[1,0,0]
	v_pk_add_f32 v[158:159], v[130:131], v[160:161]
	v_pk_add_f32 v[130:131], v[130:131], v[160:161] neg_lo:[0,1] neg_hi:[0,1]
	v_pk_mul_f32 v[176:177], v[144:145], 1.0 op_sel:[1,0] op_sel_hi:[0,0] neg_hi:[1,0]
	v_pk_fma_f32 v[190:191], v[160:161], s[8:9], v[190:191] op_sel:[0,0,1] op_sel_hi:[1,0,0] neg_lo:[1,0,0] neg_hi:[1,0,0]
	v_pk_mul_f32 v[160:161], v[130:131], s[18:19]
	v_pk_add_f32 v[192:193], v[128:129], v[144:145]
	v_pk_add_f32 v[144:145], v[128:129], v[144:145] neg_lo:[0,1] neg_hi:[0,1]
	v_pk_fma_f32 v[130:131], v[130:131], s[16:17], v[160:161] op_sel:[0,0,1] op_sel_hi:[1,0,0] neg_lo:[1,0,0] neg_hi:[1,0,0]
	v_pk_add_f32 v[160:161], v[128:129], v[176:177]
	v_pk_add_f32 v[128:129], v[128:129], v[176:177] neg_lo:[0,1] neg_hi:[0,1]
	v_pk_add_f32 v[176:177], v[162:163], v[178:179]
	v_pk_add_f32 v[162:163], v[162:163], v[178:179] neg_lo:[0,1] neg_hi:[0,1]
	v_cvt_f32_u32_e32 v2, v3
	v_pk_mul_f32 v[178:179], v[162:163], s[18:19]
	s_add_i32 s76, s72, s48
	v_pk_fma_f32 v[162:163], v[162:163], s[16:17], v[178:179] op_sel:[0,0,1] op_sel_hi:[1,0,0]
	v_pk_add_f32 v[178:179], v[164:165], v[180:181]
	v_pk_add_f32 v[164:165], v[164:165], v[180:181] neg_lo:[0,1] neg_hi:[0,1]
	v_mul_f32_e32 v2, 0x38800000, v2
	v_pk_mul_f32 v[180:181], v[164:165], s[36:37]
	v_sin_f32_e32 v34, v2
	v_pk_fma_f32 v[164:165], v[164:165], s[78:79], v[180:181] op_sel:[0,0,1] op_sel_hi:[1,0,0]
	v_pk_add_f32 v[180:181], v[166:167], v[182:183]
	v_pk_add_f32 v[166:167], v[166:167], v[182:183] neg_lo:[0,1] neg_hi:[0,1]
	v_cos_f32_e32 v30, v2
	v_pk_mul_f32 v[182:183], v[166:167], s[40:41]
	v_xor_b32_e32 v31, 0x80000000, v34
	v_pk_fma_f32 v[166:167], v[166:167], s[80:81], v[182:183] op_sel:[0,0,1] op_sel_hi:[1,0,0]
	v_pk_add_f32 v[182:183], v[168:169], v[184:185]
	v_pk_add_f32 v[184:185], v[168:169], v[184:185] neg_lo:[0,1] neg_hi:[0,1]
	v_mov_b32_e32 v35, v31
	v_pk_add_f32 v[168:169], v[170:171], v[186:187]
	v_pk_add_f32 v[170:171], v[170:171], v[186:187] neg_lo:[0,1] neg_hi:[0,1]
	v_pk_mul_f32 v[2:3], v[30:31], v[34:35] op_sel:[1,0] op_sel_hi:[0,1]
	v_pk_mul_f32 v[186:187], v[170:171], s[40:41]
	v_pk_fma_f32 v[44:45], v[30:31], v[30:31], v[2:3] op_sel_hi:[1,0,1]
	v_pk_fma_f32 v[170:171], v[170:171], s[80:81], v[186:187] op_sel:[0,0,1] op_sel_hi:[1,0,0] neg_lo:[1,0,0] neg_hi:[1,0,0]
	v_pk_add_f32 v[186:187], v[172:173], v[188:189]
	v_pk_add_f32 v[172:173], v[172:173], v[188:189] neg_lo:[0,1] neg_hi:[0,1]
	v_pk_mul_f32 v[2:3], v[34:35], v[44:45] op_sel:[0,1] op_sel_hi:[1,0]
	v_pk_mul_f32 v[188:189], v[172:173], s[36:37]
	v_pk_mul_f32 v[54:55], v[44:45], 1.0 op_sel:[1,0] op_sel_hi:[1,0] neg_lo:[1,0]
	v_pk_fma_f32 v[172:173], v[172:173], s[78:79], v[188:189] op_sel:[0,0,1] op_sel_hi:[1,0,0] neg_lo:[1,0,0] neg_hi:[1,0,0]
	v_pk_add_f32 v[188:189], v[174:175], v[190:191]
	v_pk_add_f32 v[174:175], v[174:175], v[190:191] neg_lo:[0,1] neg_hi:[0,1]
	s_nop 0
	v_pk_mul_f32 v[190:191], v[174:175], s[18:19]
	v_pk_fma_f32 v[46:47], v[30:31], v[44:45], v[2:3] op_sel_hi:[0,1,1]
	v_pk_fma_f32 v[174:175], v[174:175], s[16:17], v[190:191] op_sel:[0,0,1] op_sel_hi:[1,0,0] neg_lo:[1,0,0] neg_hi:[1,0,0]
	v_pk_add_f32 v[190:191], v[192:193], v[152:153]
	v_pk_add_f32 v[152:153], v[192:193], v[152:153] neg_lo:[0,1] neg_hi:[0,1]
	v_pk_add_f32 v[192:193], v[194:195], v[140:141]
	v_pk_add_f32 v[140:141], v[194:195], v[140:141] neg_lo:[0,1] neg_hi:[0,1]
	v_pk_mul_f32 v[2:3], v[44:45], v[54:55] op_sel:[1,0] op_sel_hi:[0,1]
	v_pk_mul_f32 v[194:195], v[140:141], s[36:37]
	v_pk_fma_f32 v[52:53], v[44:45], v[44:45], v[2:3] op_sel_hi:[1,0,1]
	v_pk_fma_f32 v[140:141], v[140:141], s[78:79], v[194:195] op_sel:[0,0,1] op_sel_hi:[1,0,0]
	v_pk_add_f32 v[194:195], v[148:149], v[156:157]
	v_pk_add_f32 v[156:157], v[148:149], v[156:157] neg_lo:[0,1] neg_hi:[0,1]
	v_pk_mul_f32 v[58:59], v[52:53], 1.0 op_sel:[1,0] op_sel_hi:[1,0] neg_lo:[1,0]
	v_pk_add_f32 v[148:149], v[150:151], v[158:159]
	v_pk_add_f32 v[150:151], v[150:151], v[158:159] neg_lo:[0,1] neg_hi:[0,1]
	s_nop 0
	v_pk_mul_f32 v[158:159], v[150:151], s[36:37]
	v_pk_mul_f32 v[2:3], v[52:53], v[58:59] op_sel:[1,0] op_sel_hi:[0,1]
	v_pk_fma_f32 v[150:151], v[150:151], s[78:79], v[158:159] op_sel:[0,0,1] op_sel_hi:[1,0,0] neg_lo:[1,0,0] neg_hi:[1,0,0]
	v_pk_add_f32 v[158:159], v[144:145], v[154:155]
	v_pk_add_f32 v[144:145], v[144:145], v[154:155] neg_lo:[0,1] neg_hi:[0,1]
	v_pk_add_f32 v[154:155], v[134:135], v[142:143]
	v_pk_add_f32 v[134:135], v[134:135], v[142:143] neg_lo:[0,1] neg_hi:[0,1]
	v_pk_fma_f32 v[48:49], v[52:53], v[52:53], v[2:3] op_sel_hi:[1,0,1]
	v_pk_mul_f32 v[142:143], v[134:135], s[36:37]
	v_pk_mul_f32 v[2:3], v[58:59], v[48:49] op_sel:[0,1] op_sel_hi:[1,0]
	v_pk_fma_f32 v[134:135], v[134:135], s[78:79], v[142:143] op_sel:[0,0,1] op_sel_hi:[1,0,0]
	v_pk_add_f32 v[142:143], v[136:137], v[132:133]
	v_pk_add_f32 v[136:137], v[136:137], v[132:133] neg_lo:[0,1] neg_hi:[0,1]
	v_pk_fma_f32 v[36:37], v[52:53], v[48:49], v[2:3] op_sel_hi:[0,1,1]
	v_pk_add_f32 v[132:133], v[138:139], v[130:131]
	v_pk_add_f32 v[130:131], v[138:139], v[130:131] neg_lo:[0,1] neg_hi:[0,1]
	v_pk_mul_f32 v[2:3], v[58:59], v[36:37] op_sel:[0,1] op_sel_hi:[1,0]
	v_pk_mul_f32 v[138:139], v[130:131], s[36:37]
	v_pk_fma_f32 v[26:27], v[52:53], v[36:37], v[2:3] op_sel_hi:[0,1,1]
	v_pk_fma_f32 v[130:131], v[130:131], s[78:79], v[138:139] op_sel:[0,0,1] op_sel_hi:[1,0,0] neg_lo:[1,0,0] neg_hi:[1,0,0]
	v_pk_add_f32 v[138:139], v[160:161], v[182:183]
	v_pk_add_f32 v[160:161], v[160:161], v[182:183] neg_lo:[0,1] neg_hi:[0,1]
	v_pk_add_f32 v[182:183], v[176:177], v[168:169]
	v_pk_add_f32 v[168:169], v[176:177], v[168:169] neg_lo:[0,1] neg_hi:[0,1]
	v_pk_mul_f32 v[2:3], v[58:59], v[26:27] op_sel:[0,1] op_sel_hi:[1,0]
	v_pk_mul_f32 v[176:177], v[168:169], s[36:37]
	v_pk_fma_f32 v[20:21], v[52:53], v[26:27], v[2:3] op_sel_hi:[0,1,1]
	v_pk_fma_f32 v[168:169], v[168:169], s[78:79], v[176:177] op_sel:[0,0,1] op_sel_hi:[1,0,0]
	v_pk_add_f32 v[176:177], v[178:179], v[186:187]
	v_pk_add_f32 v[186:187], v[178:179], v[186:187] neg_lo:[0,1] neg_hi:[0,1]
	v_pk_mul_f32 v[2:3], v[58:59], v[20:21] op_sel:[0,1] op_sel_hi:[1,0]
	v_pk_add_f32 v[178:179], v[180:181], v[188:189]
	v_pk_add_f32 v[180:181], v[180:181], v[188:189] neg_lo:[0,1] neg_hi:[0,1]
	v_pk_fma_f32 v[10:11], v[52:53], v[20:21], v[2:3] op_sel_hi:[0,1,1]
	v_pk_mul_f32 v[188:189], v[180:181], s[36:37]
	v_pk_mul_f32 v[2:3], v[58:59], v[10:11] op_sel:[0,1] op_sel_hi:[1,0]
	v_pk_fma_f32 v[180:181], v[180:181], s[78:79], v[188:189] op_sel:[0,0,1] op_sel_hi:[1,0,0] neg_lo:[1,0,0] neg_hi:[1,0,0]
	v_pk_add_f32 v[188:189], v[128:129], v[184:185] op_sel:[0,1] op_sel_hi:[1,0] neg_hi:[0,1]
	v_pk_add_f32 v[128:129], v[128:129], v[184:185] op_sel:[0,1] op_sel_hi:[1,0] neg_lo:[0,1]
	v_pk_add_f32 v[184:185], v[162:163], v[170:171]
	v_pk_add_f32 v[162:163], v[162:163], v[170:171] neg_lo:[0,1] neg_hi:[0,1]
	v_pk_fma_f32 v[4:5], v[52:53], v[10:11], v[2:3] op_sel_hi:[0,1,1]
	v_pk_mul_f32 v[170:171], v[162:163], s[36:37]
	v_pk_mul_f32 v[8:9], v[54:55], v[4:5] op_sel:[0,1] op_sel_hi:[1,0]
	v_pk_fma_f32 v[162:163], v[162:163], s[78:79], v[170:171] op_sel:[0,0,1] op_sel_hi:[1,0,0]
	v_pk_add_f32 v[170:171], v[164:165], v[172:173]
	v_pk_add_f32 v[172:173], v[164:165], v[172:173] neg_lo:[0,1] neg_hi:[0,1]
	v_pk_mul_f32 v[14:15], v[34:35], v[4:5] op_sel:[0,1] op_sel_hi:[1,0]
	v_pk_add_f32 v[164:165], v[166:167], v[174:175]
	v_pk_add_f32 v[166:167], v[166:167], v[174:175] neg_lo:[0,1] neg_hi:[0,1]
	v_pk_mul_f32 v[32:33], v[54:55], v[10:11] op_sel:[0,1] op_sel_hi:[1,0]
	v_pk_mul_f32 v[174:175], v[166:167], s[36:37]
	v_pk_mul_f32 v[40:41], v[34:35], v[10:11] op_sel:[0,1] op_sel_hi:[1,0]
	v_pk_fma_f32 v[166:167], v[166:167], s[78:79], v[174:175] op_sel:[0,0,1] op_sel_hi:[1,0,0] neg_lo:[1,0,0] neg_hi:[1,0,0]
	v_pk_add_f32 v[174:175], v[190:191], v[194:195]
	v_pk_add_f32 v[190:191], v[190:191], v[194:195] neg_lo:[0,1] neg_hi:[0,1]
	v_pk_add_f32 v[194:195], v[192:193], v[148:149]
	v_pk_add_f32 v[192:193], v[192:193], v[148:149] neg_lo:[0,1] neg_hi:[0,1]
	v_pk_mul_f32 v[62:63], v[54:55], v[20:21] op_sel:[0,1] op_sel_hi:[1,0]
	v_pk_add_f32 v[148:149], v[152:153], v[156:157] op_sel:[0,1] op_sel_hi:[1,0] neg_hi:[0,1]
	v_pk_add_f32 v[152:153], v[152:153], v[156:157] op_sel:[0,1] op_sel_hi:[1,0] neg_lo:[0,1]
	v_pk_add_f32 v[156:157], v[140:141], v[150:151]
	v_pk_add_f32 v[150:151], v[140:141], v[150:151] neg_lo:[0,1] neg_hi:[0,1]
	v_pk_mul_f32 v[66:67], v[34:35], v[20:21] op_sel:[0,1] op_sel_hi:[1,0]
	v_pk_add_f32 v[140:141], v[158:159], v[142:143]
	v_pk_add_f32 v[142:143], v[158:159], v[142:143] neg_lo:[0,1] neg_hi:[0,1]
	v_pk_add_f32 v[158:159], v[154:155], v[132:133]
	v_pk_add_f32 v[154:155], v[154:155], v[132:133] neg_lo:[0,1] neg_hi:[0,1]
	v_pk_mul_f32 v[78:79], v[54:55], v[26:27] op_sel:[0,1] op_sel_hi:[1,0]
	v_pk_add_f32 v[132:133], v[144:145], v[136:137] op_sel:[0,1] op_sel_hi:[1,0] neg_hi:[0,1]
	v_pk_add_f32 v[136:137], v[144:145], v[136:137] op_sel:[0,1] op_sel_hi:[1,0] neg_lo:[0,1]
	v_pk_add_f32 v[144:145], v[134:135], v[130:131]
	v_pk_add_f32 v[134:135], v[134:135], v[130:131] neg_lo:[0,1] neg_hi:[0,1]
	v_pk_mul_f32 v[82:83], v[34:35], v[26:27] op_sel:[0,1] op_sel_hi:[1,0]
	v_pk_add_f32 v[130:131], v[138:139], v[176:177]
	v_pk_add_f32 v[138:139], v[138:139], v[176:177] neg_lo:[0,1] neg_hi:[0,1]
	v_pk_add_f32 v[176:177], v[182:183], v[178:179]
	v_pk_add_f32 v[182:183], v[182:183], v[178:179] neg_lo:[0,1] neg_hi:[0,1]
	v_pk_mul_f32 v[92:93], v[54:55], v[36:37] op_sel:[0,1] op_sel_hi:[1,0]
	v_pk_add_f32 v[178:179], v[160:161], v[186:187] op_sel:[0,1] op_sel_hi:[1,0] neg_hi:[0,1]
	v_pk_add_f32 v[160:161], v[160:161], v[186:187] op_sel:[0,1] op_sel_hi:[1,0] neg_lo:[0,1]
	v_pk_add_f32 v[186:187], v[168:169], v[180:181]
	v_pk_add_f32 v[180:181], v[168:169], v[180:181] neg_lo:[0,1] neg_hi:[0,1]
	v_pk_mul_f32 v[96:97], v[34:35], v[36:37] op_sel:[0,1] op_sel_hi:[1,0]
	v_pk_add_f32 v[168:169], v[188:189], v[170:171]
	v_pk_add_f32 v[170:171], v[188:189], v[170:171] neg_lo:[0,1] neg_hi:[0,1]
	v_pk_add_f32 v[188:189], v[184:185], v[164:165]
	v_pk_add_f32 v[184:185], v[184:185], v[164:165] neg_lo:[0,1] neg_hi:[0,1]
	v_pk_mul_f32 v[106:107], v[54:55], v[48:49] op_sel:[0,1] op_sel_hi:[1,0]
	v_pk_add_f32 v[164:165], v[128:129], v[172:173] op_sel:[0,1] op_sel_hi:[1,0] neg_hi:[0,1]
	v_pk_add_f32 v[128:129], v[128:129], v[172:173] op_sel:[0,1] op_sel_hi:[1,0] neg_lo:[0,1]
	v_pk_add_f32 v[172:173], v[162:163], v[166:167]
	v_pk_add_f32 v[166:167], v[162:163], v[166:167] neg_lo:[0,1] neg_hi:[0,1]
	v_pk_mul_f32 v[110:111], v[34:35], v[48:49] op_sel:[0,1] op_sel_hi:[1,0]
	v_pk_add_f32 v[162:163], v[174:175], v[194:195]
	v_pk_add_f32 v[174:175], v[174:175], v[194:195] neg_lo:[0,1] neg_hi:[0,1]
	v_pk_add_f32 v[194:195], v[190:191], v[192:193] op_sel:[0,1] op_sel_hi:[1,0] neg_hi:[0,1]
	v_pk_add_f32 v[190:191], v[190:191], v[192:193] op_sel:[0,1] op_sel_hi:[1,0] neg_lo:[0,1]
	v_pk_add_f32 v[192:193], v[148:149], v[156:157]
	v_pk_add_f32 v[148:149], v[148:149], v[156:157] neg_lo:[0,1] neg_hi:[0,1]
	v_pk_add_f32 v[156:157], v[152:153], v[150:151] op_sel:[0,1] op_sel_hi:[1,0] neg_hi:[0,1]
	v_pk_add_f32 v[150:151], v[152:153], v[150:151] op_sel:[0,1] op_sel_hi:[1,0] neg_lo:[0,1]
	v_pk_add_f32 v[152:153], v[140:141], v[158:159]
	v_pk_add_f32 v[140:141], v[140:141], v[158:159] neg_lo:[0,1] neg_hi:[0,1]
	v_pk_add_f32 v[158:159], v[142:143], v[154:155] op_sel:[0,1] op_sel_hi:[1,0] neg_hi:[0,1]
	v_pk_add_f32 v[142:143], v[142:143], v[154:155] op_sel:[0,1] op_sel_hi:[1,0] neg_lo:[0,1]
	v_pk_add_f32 v[154:155], v[132:133], v[144:145]
	v_pk_add_f32 v[132:133], v[132:133], v[144:145] neg_lo:[0,1] neg_hi:[0,1]
	v_pk_add_f32 v[144:145], v[136:137], v[134:135] op_sel:[0,1] op_sel_hi:[1,0] neg_hi:[0,1]
	v_pk_add_f32 v[134:135], v[136:137], v[134:135] op_sel:[0,1] op_sel_hi:[1,0] neg_lo:[0,1]
	v_pk_add_f32 v[136:137], v[130:131], v[176:177]
	v_pk_mul_f32 v[120:121], v[54:55], v[52:53] op_sel:[0,1] op_sel_hi:[1,0]
	v_pk_mul_f32 v[124:125], v[34:35], v[52:53] op_sel:[0,1] op_sel_hi:[1,0]
	v_pk_mul_f32 v[34:35], v[34:35], v[136:137] op_sel:[0,1] op_sel_hi:[1,0]
	v_pk_mul_f32 v[72:73], v[46:47], 1.0 op_sel:[1,0] op_sel_hi:[1,0] neg_lo:[1,0]
	v_pk_fma_f32 v[8:9], v[44:45], v[4:5], v[8:9] op_sel_hi:[0,1,1]
	v_pk_fma_f32 v[14:15], v[30:31], v[4:5], v[14:15] op_sel_hi:[0,1,1]
	v_xor_b32_e32 v22, 0x80000000, v5
	v_pk_fma_f32 v[32:33], v[44:45], v[10:11], v[32:33] op_sel_hi:[0,1,1]
	v_pk_fma_f32 v[40:41], v[30:31], v[10:11], v[40:41] op_sel_hi:[0,1,1]
	v_pk_fma_f32 v[62:63], v[44:45], v[20:21], v[62:63] op_sel_hi:[0,1,1]
	v_pk_fma_f32 v[66:67], v[30:31], v[20:21], v[66:67] op_sel_hi:[0,1,1]
	v_pk_fma_f32 v[78:79], v[44:45], v[26:27], v[78:79] op_sel_hi:[0,1,1]
	v_pk_fma_f32 v[82:83], v[30:31], v[26:27], v[82:83] op_sel_hi:[0,1,1]
	v_pk_fma_f32 v[92:93], v[44:45], v[36:37], v[92:93] op_sel_hi:[0,1,1]
	v_pk_fma_f32 v[96:97], v[30:31], v[36:37], v[96:97] op_sel_hi:[0,1,1]
	v_pk_fma_f32 v[106:107], v[44:45], v[48:49], v[106:107] op_sel_hi:[0,1,1]
	v_pk_fma_f32 v[110:111], v[30:31], v[48:49], v[110:111] op_sel_hi:[0,1,1]
	v_pk_fma_f32 v[120:121], v[44:45], v[52:53], v[120:121] op_sel_hi:[0,1,1]
	v_pk_fma_f32 v[124:125], v[30:31], v[52:53], v[124:125] op_sel_hi:[0,1,1]
	v_mov_b32_e32 v23, v5
	v_pk_add_f32 v[130:131], v[130:131], v[176:177] neg_lo:[0,1] neg_hi:[0,1]
	v_pk_add_f32 v[176:177], v[138:139], v[182:183] op_sel:[0,1] op_sel_hi:[1,0] neg_hi:[0,1]
	v_pk_add_f32 v[138:139], v[138:139], v[182:183] op_sel:[0,1] op_sel_hi:[1,0] neg_lo:[0,1]
	v_pk_add_f32 v[182:183], v[178:179], v[186:187]
	v_pk_add_f32 v[178:179], v[178:179], v[186:187] neg_lo:[0,1] neg_hi:[0,1]
	v_pk_add_f32 v[186:187], v[160:161], v[180:181] op_sel:[0,1] op_sel_hi:[1,0] neg_hi:[0,1]
	v_pk_add_f32 v[160:161], v[160:161], v[180:181] op_sel:[0,1] op_sel_hi:[1,0] neg_lo:[0,1]
	v_pk_add_f32 v[180:181], v[168:169], v[188:189]
	v_pk_fma_f32 v[30:31], v[30:31], v[136:137], v[34:35] op_sel_hi:[0,1,1]
	v_pk_mul_f32 v[34:35], v[54:55], v[152:153] op_sel:[0,1] op_sel_hi:[1,0]
	v_pk_mul_f32 v[2:3], v[72:73], v[4:5] op_sel:[0,1] op_sel_hi:[1,0]
	v_xor_b32_e32 v12, 0x80000000, v9
	v_pk_mul_f32 v[24:25], v[72:73], v[10:11] op_sel:[0,1] op_sel_hi:[1,0]
	v_xor_b32_e32 v38, 0x80000000, v33
	v_xor_b32_e32 v50, 0x80000000, v11
	v_pk_mul_f32 v[56:57], v[72:73], v[20:21] op_sel:[0,1] op_sel_hi:[1,0]
	v_xor_b32_e32 v64, 0x80000000, v63
	v_xor_b32_e32 v70, 0x80000000, v21
	v_pk_mul_f32 v[74:75], v[72:73], v[26:27] op_sel:[0,1] op_sel_hi:[1,0]
	v_xor_b32_e32 v80, 0x80000000, v79
	v_xor_b32_e32 v86, 0x80000000, v27
	v_pk_mul_f32 v[88:89], v[72:73], v[36:37] op_sel:[0,1] op_sel_hi:[1,0]
	v_xor_b32_e32 v94, 0x80000000, v93
	v_xor_b32_e32 v100, 0x80000000, v37
	v_pk_mul_f32 v[102:103], v[72:73], v[48:49] op_sel:[0,1] op_sel_hi:[1,0]
	v_pk_mul_f32 v[108:109], v[106:107], 1.0 op_sel:[1,0] op_sel_hi:[1,0] neg_lo:[1,0]
	v_pk_mul_f32 v[114:115], v[48:49], 1.0 op_sel:[1,0] op_sel_hi:[1,0] neg_lo:[1,0]
	v_pk_mul_f32 v[116:117], v[52:53], v[72:73] op_sel:[1,0] op_sel_hi:[0,1]
	v_pk_mul_f32 v[122:123], v[120:121], 1.0 op_sel:[1,0] op_sel_hi:[1,0] neg_lo:[1,0]
	v_mov_b32_e32 v101, v37
	v_mov_b32_e32 v95, v93
	v_mov_b32_e32 v87, v27
	v_mov_b32_e32 v81, v79
	v_mov_b32_e32 v71, v21
	v_mov_b32_e32 v65, v63
	v_mov_b32_e32 v51, v11
	v_mov_b32_e32 v39, v33
	v_mov_b32_e32 v13, v9
	v_pk_fma_f32 v[34:35], v[44:45], v[152:153], v[34:35] op_sel_hi:[0,1,1]
	v_pk_mul_f32 v[44:45], v[72:73], v[180:181] op_sel:[0,1] op_sel_hi:[1,0]
	v_pk_mul_f32 v[22:23], v[150:151], v[22:23] op_sel:[1,0] op_sel_hi:[0,1]
	v_pk_fma_f32 v[2:3], v[46:47], v[4:5], v[2:3] op_sel_hi:[0,1,1]
	v_pk_fma_f32 v[24:25], v[46:47], v[10:11], v[24:25] op_sel_hi:[0,1,1]
	v_pk_fma_f32 v[56:57], v[46:47], v[20:21], v[56:57] op_sel_hi:[0,1,1]
	v_pk_fma_f32 v[74:75], v[46:47], v[26:27], v[74:75] op_sel_hi:[0,1,1]
	v_pk_mul_f32 v[84:85], v[82:83], 1.0 op_sel:[1,0] op_sel_hi:[1,0] neg_lo:[1,0]
	v_pk_fma_f32 v[88:89], v[46:47], v[36:37], v[88:89] op_sel_hi:[0,1,1]
	v_pk_fma_f32 v[102:103], v[46:47], v[48:49], v[102:103] op_sel_hi:[0,1,1]
	v_pk_fma_f32 v[116:117], v[52:53], v[46:47], v[116:117] op_sel_hi:[1,0,1]
	v_pk_fma_f32 v[44:45], v[46:47], v[180:181], v[44:45] op_sel_hi:[0,1,1]
	v_pk_mul_f32 v[46:47], v[58:59], v[192:193] op_sel:[0,1] op_sel_hi:[1,0]
	v_pk_mul_f32 v[54:55], v[122:123], v[154:155] op_sel:[0,1] op_sel_hi:[1,0]
	v_pk_mul_f32 v[72:73], v[114:115], v[194:195] op_sel:[0,1] op_sel_hi:[1,0]
	v_pk_mul_f32 v[108:109], v[108:109], v[158:159] op_sel:[0,1] op_sel_hi:[1,0]
	v_pk_mul_f32 v[100:101], v[100:101], v[156:157] op_sel:[0,1] op_sel_hi:[1,0]
	v_pk_mul_f32 v[94:95], v[94:95], v[144:145] op_sel:[0,1] op_sel_hi:[1,0]
	v_pk_mul_f32 v[86:87], v[174:175], v[86:87] op_sel:[1,0] op_sel_hi:[0,1]
	v_pk_mul_f32 v[80:81], v[140:141], v[80:81] op_sel:[1,0] op_sel_hi:[0,1]
	v_pk_mul_f32 v[70:71], v[148:149], v[70:71] op_sel:[1,0] op_sel_hi:[0,1]
	v_pk_mul_f32 v[64:65], v[132:133], v[64:65] op_sel:[1,0] op_sel_hi:[0,1]
	v_pk_mul_f32 v[50:51], v[190:191], v[50:51] op_sel:[1,0] op_sel_hi:[0,1]
	v_pk_mul_f32 v[38:39], v[142:143], v[38:39] op_sel:[1,0] op_sel_hi:[0,1]
	v_pk_fma_f32 v[4:5], v[150:151], v[4:5], v[22:23] op_sel_hi:[1,0,1]
	v_pk_mul_f32 v[12:13], v[134:135], v[12:13] op_sel:[1,0] op_sel_hi:[0,1]
	v_pk_mul_f32 v[112:113], v[110:111], 1.0 op_sel:[1,0] op_sel_hi:[1,0] neg_lo:[1,0]
	v_pk_fma_f32 v[46:47], v[52:53], v[192:193], v[46:47] op_sel_hi:[0,1,1]
	v_pk_fma_f32 v[54:55], v[120:121], v[154:155], v[54:55] op_sel_hi:[0,1,1]
	v_pk_fma_f32 v[48:49], v[48:49], v[194:195], v[72:73] op_sel_hi:[0,1,1]
	v_pk_fma_f32 v[106:107], v[106:107], v[158:159], v[108:109] op_sel_hi:[0,1,1]
	v_pk_fma_f32 v[36:37], v[36:37], v[156:157], v[100:101] op_sel_hi:[0,1,1]
	v_pk_fma_f32 v[92:93], v[92:93], v[144:145], v[94:95] op_sel_hi:[0,1,1]
	v_pk_fma_f32 v[26:27], v[174:175], v[26:27], v[86:87] op_sel_hi:[1,0,1]
	v_pk_mul_f32 v[84:85], v[130:131], v[84:85] op_sel:[1,0] op_sel_hi:[0,1]
	v_pk_fma_f32 v[78:79], v[140:141], v[78:79], v[80:81] op_sel_hi:[1,0,1]
	v_pk_fma_f32 v[20:21], v[148:149], v[20:21], v[70:71] op_sel_hi:[1,0,1]
	v_pk_fma_f32 v[62:63], v[132:133], v[62:63], v[64:65] op_sel_hi:[1,0,1]
	v_pk_fma_f32 v[10:11], v[190:191], v[10:11], v[50:51] op_sel_hi:[1,0,1]
	v_pk_fma_f32 v[32:33], v[142:143], v[32:33], v[38:39] op_sel_hi:[1,0,1]
	v_pk_fma_f32 v[8:9], v[134:135], v[8:9], v[12:13] op_sel_hi:[1,0,1]
	ds_write_b64 v18, v[162:163]
	ds_write_b64 v18, v[26:27] offset:4224
	ds_write_b64 v18, v[48:49] offset:8448
	ds_write_b64 v18, v[10:11] offset:12672
	ds_write_b64 v18, v[46:47] offset:16896
	ds_write_b64 v18, v[20:21] offset:21120
	ds_write_b64 v18, v[36:37] offset:25344
	ds_write_b64 v18, v[4:5] offset:29568
	ds_write_b64 v18, v[34:35] offset:33792
	ds_write_b64 v18, v[78:79] offset:38016
	ds_write_b64 v18, v[106:107] offset:42240
	ds_write_b64 v18, v[32:33] offset:46464
	ds_write_b64 v18, v[54:55] offset:50688
	ds_write_b64 v18, v[62:63] offset:54912
	ds_write_b64 v18, v[92:93] offset:59136
	ds_write_b64 v18, v[8:9] offset:63360
	v_add_u32_e32 v4, 0x10800, v18
	v_pk_mul_f32 v[42:43], v[40:41], 1.0 op_sel:[1,0] op_sel_hi:[1,0] neg_lo:[1,0]
	v_pk_mul_f32 v[72:73], v[112:113], v[176:177] op_sel:[0,1] op_sel_hi:[1,0]
	v_pk_fma_f32 v[82:83], v[130:131], v[82:83], v[84:85] op_sel_hi:[1,0,1]
	ds_write_b64 v4, v[30:31]
	v_add_u32_e32 v4, 0x11880, v18
	v_pk_mul_f32 v[126:127], v[124:125], 1.0 op_sel:[1,0] op_sel_hi:[1,0] neg_lo:[1,0]
	v_pk_fma_f32 v[72:73], v[110:111], v[176:177], v[72:73] op_sel_hi:[0,1,1]
	v_pk_mul_f32 v[42:43], v[138:139], v[42:43] op_sel:[1,0] op_sel_hi:[0,1]
	ds_write_b64 v4, v[82:83]
	v_add_u32_e32 v4, 0x12900, v18
	v_pk_mul_f32 v[68:69], v[66:67], 1.0 op_sel:[1,0] op_sel_hi:[1,0] neg_lo:[1,0]
	v_pk_mul_f32 v[52:53], v[126:127], v[182:183] op_sel:[0,1] op_sel_hi:[1,0]
	v_pk_fma_f32 v[40:41], v[138:139], v[40:41], v[42:43] op_sel_hi:[1,0,1]
	ds_write_b64 v4, v[72:73]
	v_add_u32_e32 v4, 0x13980, v18
	v_pk_mul_f32 v[98:99], v[96:97], 1.0 op_sel:[1,0] op_sel_hi:[1,0] neg_lo:[1,0]
	v_pk_fma_f32 v[52:53], v[124:125], v[182:183], v[52:53] op_sel_hi:[0,1,1]
	v_pk_mul_f32 v[68:69], v[178:179], v[68:69] op_sel:[1,0] op_sel_hi:[0,1]
	ds_write_b64 v4, v[40:41]
	v_add_u32_e32 v4, 0x14a00, v18
	v_pk_mul_f32 v[16:17], v[14:15], 1.0 op_sel:[1,0] op_sel_hi:[1,0] neg_lo:[1,0]
	v_pk_mul_f32 v[98:99], v[98:99], v[186:187] op_sel:[0,1] op_sel_hi:[1,0]
	v_pk_fma_f32 v[66:67], v[178:179], v[66:67], v[68:69] op_sel_hi:[1,0,1]
	ds_write_b64 v4, v[52:53]
	v_add_u32_e32 v4, 0x15a80, v18
	v_pk_fma_f32 v[96:97], v[96:97], v[186:187], v[98:99] op_sel_hi:[0,1,1]
	v_pk_mul_f32 v[16:17], v[160:161], v[16:17] op_sel:[1,0] op_sel_hi:[0,1]
	ds_write_b64 v4, v[66:67]
	v_add_u32_e32 v4, 0x16b00, v18
	v_pk_mul_f32 v[76:77], v[74:75], 1.0 op_sel:[1,0] op_sel_hi:[1,0] neg_lo:[1,0]
	v_pk_add_f32 v[168:169], v[168:169], v[188:189] neg_lo:[0,1] neg_hi:[0,1]
	v_pk_fma_f32 v[14:15], v[160:161], v[14:15], v[16:17] op_sel_hi:[1,0,1]
	ds_write_b64 v4, v[96:97]
	v_add_u32_e32 v4, 0x17b80, v18
	v_pk_mul_f32 v[104:105], v[102:103], 1.0 op_sel:[1,0] op_sel_hi:[1,0] neg_lo:[1,0]
	v_pk_add_f32 v[188:189], v[170:171], v[184:185] op_sel:[0,1] op_sel_hi:[1,0] neg_hi:[0,1]
	v_pk_mul_f32 v[76:77], v[168:169], v[76:77] op_sel:[1,0] op_sel_hi:[0,1]
	ds_write_b64 v4, v[14:15]
	v_add_u32_e32 v4, 0x18c00, v18
	v_pk_mul_f32 v[28:29], v[24:25], 1.0 op_sel:[1,0] op_sel_hi:[1,0] neg_lo:[1,0]
	v_pk_add_f32 v[170:171], v[170:171], v[184:185] op_sel:[0,1] op_sel_hi:[1,0] neg_lo:[0,1]
	v_pk_mul_f32 v[104:105], v[104:105], v[188:189] op_sel:[0,1] op_sel_hi:[1,0]
	v_pk_fma_f32 v[74:75], v[168:169], v[74:75], v[76:77] op_sel_hi:[1,0,1]
	ds_write_b64 v4, v[44:45]
	v_add_u32_e32 v4, 0x19c80, v18
	v_pk_mul_f32 v[118:119], v[116:117], 1.0 op_sel:[1,0] op_sel_hi:[1,0] neg_lo:[1,0]
	v_pk_add_f32 v[184:185], v[164:165], v[172:173]
	v_pk_fma_f32 v[102:103], v[102:103], v[188:189], v[104:105] op_sel_hi:[0,1,1]
	v_pk_mul_f32 v[28:29], v[170:171], v[28:29] op_sel:[1,0] op_sel_hi:[0,1]
	ds_write_b64 v4, v[74:75]
	v_add_u32_e32 v4, 0x1ad00, v18
	v_pk_mul_f32 v[60:61], v[56:57], 1.0 op_sel:[1,0] op_sel_hi:[1,0] neg_lo:[1,0]
	v_pk_add_f32 v[164:165], v[164:165], v[172:173] neg_lo:[0,1] neg_hi:[0,1]
	v_pk_mul_f32 v[58:59], v[118:119], v[184:185] op_sel:[0,1] op_sel_hi:[1,0]
	v_pk_fma_f32 v[24:25], v[170:171], v[24:25], v[28:29] op_sel_hi:[1,0,1]
	ds_write_b64 v4, v[102:103]
	v_add_u32_e32 v4, 0x1bd80, v18
	v_pk_mul_f32 v[90:91], v[88:89], 1.0 op_sel:[1,0] op_sel_hi:[1,0] neg_lo:[1,0]
	v_pk_add_f32 v[172:173], v[128:129], v[166:167] op_sel:[0,1] op_sel_hi:[1,0] neg_hi:[0,1]
	v_pk_fma_f32 v[58:59], v[116:117], v[184:185], v[58:59] op_sel_hi:[0,1,1]
	v_pk_mul_f32 v[60:61], v[164:165], v[60:61] op_sel:[1,0] op_sel_hi:[0,1]
	ds_write_b64 v4, v[24:25]
	v_add_u32_e32 v4, 0x1ce00, v18
	v_pk_mul_f32 v[6:7], v[2:3], 1.0 op_sel:[1,0] op_sel_hi:[1,0] neg_lo:[1,0]
	v_pk_add_f32 v[128:129], v[128:129], v[166:167] op_sel:[0,1] op_sel_hi:[1,0] neg_lo:[0,1]
	v_pk_mul_f32 v[90:91], v[90:91], v[172:173] op_sel:[0,1] op_sel_hi:[1,0]
	v_pk_fma_f32 v[56:57], v[164:165], v[56:57], v[60:61] op_sel_hi:[1,0,1]
	ds_write_b64 v4, v[58:59]
	v_add_u32_e32 v4, 0x1de80, v18
	v_pk_fma_f32 v[88:89], v[88:89], v[172:173], v[90:91] op_sel_hi:[0,1,1]
	v_pk_mul_f32 v[6:7], v[128:129], v[6:7] op_sel:[1,0] op_sel_hi:[0,1]
	ds_write_b64 v4, v[56:57]
	v_add_u32_e32 v4, 0x1ef00, v18
	v_pk_fma_f32 v[2:3], v[128:129], v[2:3], v[6:7] op_sel_hi:[1,0,1]
	ds_write_b64 v4, v[88:89]
	v_add_u32_e32 v4, 0x1ff80, v18
	ds_write_b64 v4, v[2:3]
	v_mov_b32_e32 v2, v210
	s_waitcnt lgkmcnt(0)
	s_barrier
	s_ashr_i32 s77, s76, 31
	v_and_b32_e32 v3, 15, v2
	v_lshlrev_b32_e32 v2, 5, v2
	v_and_b32_e32 v4, 0xfffffe00, v2
	v_lshl_add_u32 v5, v4, 3, 0
	v_lshlrev_b32_e32 v6, 3, v3
	v_ashrrev_i32_e32 v7, 2, v4
	v_add3_u32 v18, v5, v6, v7
	v_add_u32_e32 v196, 0x800, v18
	ds_read2_b64 v[128:131], v18 offset1:16
	ds_read2_b64 v[132:135], v18 offset0:33 offset1:49
	ds_read2_b64 v[136:139], v18 offset0:66 offset1:82
	ds_read2_b64 v[140:143], v18 offset0:99 offset1:115
	ds_read2_b64 v[148:151], v18 offset0:132 offset1:148
	ds_read2_b64 v[152:155], v18 offset0:165 offset1:181
	ds_read2_b64 v[156:159], v18 offset0:198 offset1:214
	ds_read2_b64 v[160:163], v18 offset0:231 offset1:247
	ds_read2_b64 v[164:167], v196 offset0:8 offset1:24
	ds_read2_b64 v[168:171], v196 offset0:41 offset1:57
	ds_read2_b64 v[172:175], v196 offset0:74 offset1:90
	ds_read2_b64 v[176:179], v196 offset0:107 offset1:123
	ds_read2_b64 v[180:183], v196 offset0:140 offset1:156
	ds_read2_b64 v[184:187], v196 offset0:173 offset1:189
	ds_read2_b64 v[188:191], v196 offset0:206 offset1:222
	ds_read2_b64 v[192:195], v196 offset0:239 offset1:255
	s_waitcnt lgkmcnt(7)
	v_pk_add_f32 v[144:145], v[128:129], v[164:165]
	v_pk_add_f32 v[128:129], v[128:129], v[164:165] neg_lo:[0,1] neg_hi:[0,1]
	v_pk_add_f32 v[164:165], v[130:131], v[166:167]
	v_pk_add_f32 v[130:131], v[130:131], v[166:167] neg_lo:[0,1] neg_hi:[0,1]
	v_cvt_f32_ubyte0_e32 v2, v3
	v_pk_mul_f32 v[166:167], v[130:131], s[10:11]
	v_mul_f32_e32 v3, 0x3b000000, v2
	v_pk_fma_f32 v[130:131], v[130:131], s[8:9], v[166:167] op_sel:[0,0,1] op_sel_hi:[1,0,0]
	s_waitcnt lgkmcnt(6)
	v_pk_add_f32 v[166:167], v[132:133], v[168:169]
	v_pk_add_f32 v[132:133], v[132:133], v[168:169] neg_lo:[0,1] neg_hi:[0,1]
	v_sin_f32_e32 v2, v3
	v_pk_mul_f32 v[168:169], v[132:133], s[18:19]
	v_cos_f32_e32 v4, v3
	v_pk_fma_f32 v[132:133], v[132:133], s[16:17], v[168:169] op_sel:[0,0,1] op_sel_hi:[1,0,0]
	v_pk_add_f32 v[168:169], v[134:135], v[170:171]
	v_pk_add_f32 v[134:135], v[134:135], v[170:171] neg_lo:[0,1] neg_hi:[0,1]
	v_xor_b32_e32 v5, 0x80000000, v2
	v_pk_mul_f32 v[170:171], v[134:135], s[26:27]
	v_mov_b32_e32 v3, v5
	v_pk_fma_f32 v[134:135], v[134:135], s[24:25], v[170:171] op_sel:[0,0,1] op_sel_hi:[1,0,0]
	s_waitcnt lgkmcnt(5)
	v_pk_add_f32 v[170:171], v[136:137], v[172:173]
	v_pk_add_f32 v[136:137], v[136:137], v[172:173] neg_lo:[0,1] neg_hi:[0,1]
	v_pk_mul_f32 v[6:7], v[4:5], v[2:3] op_sel:[1,0] op_sel_hi:[0,1]
	v_pk_mul_f32 v[172:173], v[136:137], s[36:37]
	v_pk_fma_f32 v[6:7], v[4:5], v[4:5], v[6:7] op_sel_hi:[1,0,1]
	v_pk_fma_f32 v[136:137], v[136:137], s[78:79], v[172:173] op_sel:[0,0,1] op_sel_hi:[1,0,0]
	v_pk_add_f32 v[172:173], v[138:139], v[174:175]
	v_pk_add_f32 v[138:139], v[138:139], v[174:175] neg_lo:[0,1] neg_hi:[0,1]
	v_pk_mul_f32 v[12:13], v[6:7], 1.0 op_sel:[1,0] op_sel_hi:[1,0] neg_lo:[1,0]
	v_pk_mul_f32 v[174:175], v[138:139], s[38:39]
	s_nop 0
	v_pk_fma_f32 v[138:139], v[138:139], s[0:1], v[174:175] op_sel:[0,0,1] op_sel_hi:[1,0,0]
	s_waitcnt lgkmcnt(4)
	v_pk_add_f32 v[174:175], v[140:141], v[176:177]
	v_pk_add_f32 v[140:141], v[140:141], v[176:177] neg_lo:[0,1] neg_hi:[0,1]
	v_pk_mul_f32 v[10:11], v[6:7], v[12:13] op_sel:[1,0] op_sel_hi:[0,1]
	v_pk_mul_f32 v[176:177], v[140:141], s[40:41]
	v_pk_fma_f32 v[10:11], v[6:7], v[6:7], v[10:11] op_sel_hi:[1,0,1]
	v_pk_fma_f32 v[140:141], v[140:141], s[80:81], v[176:177] op_sel:[0,0,1] op_sel_hi:[1,0,0]
	v_pk_add_f32 v[176:177], v[142:143], v[178:179]
	v_pk_add_f32 v[142:143], v[142:143], v[178:179] neg_lo:[0,1] neg_hi:[0,1]
	v_pk_mul_f32 v[14:15], v[10:11], 1.0 op_sel:[1,0] op_sel_hi:[1,0] neg_lo:[1,0]
	v_pk_mul_f32 v[178:179], v[142:143], s[42:43]
	s_nop 0
	v_pk_fma_f32 v[142:143], v[142:143], s[74:75], v[178:179] op_sel:[0,0,1] op_sel_hi:[1,0,0]
	s_waitcnt lgkmcnt(3)
	v_pk_add_f32 v[178:179], v[148:149], v[180:181]
	v_pk_add_f32 v[180:181], v[148:149], v[180:181] neg_lo:[0,1] neg_hi:[0,1]
	v_pk_mul_f32 v[28:29], v[10:11], v[14:15] op_sel:[1,0] op_sel_hi:[0,1]
	v_pk_add_f32 v[148:149], v[150:151], v[182:183]
	v_pk_add_f32 v[150:151], v[150:151], v[182:183] neg_lo:[0,1] neg_hi:[0,1]
	v_pk_fma_f32 v[28:29], v[10:11], v[10:11], v[28:29] op_sel_hi:[1,0,1]
	v_pk_mul_f32 v[182:183], v[150:151], s[42:43]
	v_pk_mul_f32 v[44:45], v[14:15], v[28:29] op_sel:[0,1] op_sel_hi:[1,0]
	v_pk_fma_f32 v[150:151], v[150:151], s[74:75], v[182:183] op_sel:[0,0,1] op_sel_hi:[1,0,0] neg_lo:[1,0,0] neg_hi:[1,0,0]
	s_waitcnt lgkmcnt(2)
	v_pk_add_f32 v[182:183], v[152:153], v[184:185]
	v_pk_add_f32 v[152:153], v[152:153], v[184:185] neg_lo:[0,1] neg_hi:[0,1]
	v_pk_fma_f32 v[44:45], v[10:11], v[28:29], v[44:45] op_sel_hi:[0,1,1]
	v_pk_mul_f32 v[184:185], v[152:153], s[40:41]
	v_pk_mul_f32 v[60:61], v[14:15], v[44:45] op_sel:[0,1] op_sel_hi:[1,0]
	v_pk_fma_f32 v[152:153], v[152:153], s[80:81], v[184:185] op_sel:[0,0,1] op_sel_hi:[1,0,0] neg_lo:[1,0,0] neg_hi:[1,0,0]
	v_pk_add_f32 v[184:185], v[154:155], v[186:187]
	v_pk_add_f32 v[154:155], v[154:155], v[186:187] neg_lo:[0,1] neg_hi:[0,1]
	v_pk_fma_f32 v[60:61], v[10:11], v[44:45], v[60:61] op_sel_hi:[0,1,1]
	v_pk_mul_f32 v[186:187], v[154:155], s[38:39]
	v_pk_mul_f32 v[76:77], v[14:15], v[60:61] op_sel:[0,1] op_sel_hi:[1,0]
	v_pk_fma_f32 v[154:155], v[154:155], s[0:1], v[186:187] op_sel:[0,0,1] op_sel_hi:[1,0,0] neg_lo:[1,0,0] neg_hi:[1,0,0]
	s_waitcnt lgkmcnt(1)
	v_pk_add_f32 v[186:187], v[156:157], v[188:189]
	v_pk_add_f32 v[156:157], v[156:157], v[188:189] neg_lo:[0,1] neg_hi:[0,1]
	v_pk_fma_f32 v[76:77], v[10:11], v[60:61], v[76:77] op_sel_hi:[0,1,1]
	v_pk_mul_f32 v[188:189], v[156:157], s[36:37]
	v_pk_mul_f32 v[92:93], v[14:15], v[76:77] op_sel:[0,1] op_sel_hi:[1,0]
	v_pk_fma_f32 v[156:157], v[156:157], s[78:79], v[188:189] op_sel:[0,0,1] op_sel_hi:[1,0,0] neg_lo:[1,0,0] neg_hi:[1,0,0]
	v_pk_add_f32 v[188:189], v[158:159], v[190:191]
	v_pk_add_f32 v[158:159], v[158:159], v[190:191] neg_lo:[0,1] neg_hi:[0,1]
	v_pk_fma_f32 v[92:93], v[10:11], v[76:77], v[92:93] op_sel_hi:[0,1,1]
	v_pk_mul_f32 v[190:191], v[158:159], s[26:27]
	v_pk_mul_f32 v[108:109], v[14:15], v[92:93] op_sel:[0,1] op_sel_hi:[1,0]
	v_pk_fma_f32 v[158:159], v[158:159], s[24:25], v[190:191] op_sel:[0,0,1] op_sel_hi:[1,0,0] neg_lo:[1,0,0] neg_hi:[1,0,0]
	s_waitcnt lgkmcnt(0)
	v_pk_add_f32 v[190:191], v[160:161], v[192:193]
	v_pk_add_f32 v[160:161], v[160:161], v[192:193] neg_lo:[0,1] neg_hi:[0,1]
	v_pk_mul_f32 v[8:9], v[2:3], v[6:7] op_sel:[0,1] op_sel_hi:[1,0]
	v_pk_mul_f32 v[192:193], v[160:161], s[18:19]
	v_pk_fma_f32 v[108:109], v[10:11], v[92:93], v[108:109] op_sel_hi:[0,1,1]
	v_pk_fma_f32 v[160:161], v[160:161], s[16:17], v[192:193] op_sel:[0,0,1] op_sel_hi:[1,0,0] neg_lo:[1,0,0] neg_hi:[1,0,0]
	v_pk_add_f32 v[192:193], v[162:163], v[194:195]
	v_pk_add_f32 v[162:163], v[162:163], v[194:195] neg_lo:[0,1] neg_hi:[0,1]
	v_pk_fma_f32 v[8:9], v[4:5], v[6:7], v[8:9] op_sel_hi:[0,1,1]
	v_pk_mul_f32 v[194:195], v[162:163], s[10:11]
	v_pk_mul_f32 v[16:17], v[2:3], v[10:11] op_sel:[0,1] op_sel_hi:[1,0]
	v_pk_fma_f32 v[162:163], v[162:163], s[8:9], v[194:195] op_sel:[0,0,1] op_sel_hi:[1,0,0] neg_lo:[1,0,0] neg_hi:[1,0,0]
	v_pk_add_f32 v[194:195], v[144:145], v[178:179]
	v_pk_add_f32 v[144:145], v[144:145], v[178:179] neg_lo:[0,1] neg_hi:[0,1]
	v_pk_add_f32 v[178:179], v[164:165], v[148:149]
	v_pk_add_f32 v[148:149], v[164:165], v[148:149] neg_lo:[0,1] neg_hi:[0,1]
	v_pk_mul_f32 v[32:33], v[2:3], v[28:29] op_sel:[0,1] op_sel_hi:[1,0]
	v_pk_mul_f32 v[164:165], v[148:149], s[18:19]
	v_pk_mul_f32 v[48:49], v[2:3], v[44:45] op_sel:[0,1] op_sel_hi:[1,0]
	v_pk_fma_f32 v[148:149], v[148:149], s[16:17], v[164:165] op_sel:[0,0,1] op_sel_hi:[1,0,0]
	v_pk_add_f32 v[164:165], v[166:167], v[182:183]
	v_pk_add_f32 v[166:167], v[166:167], v[182:183] neg_lo:[0,1] neg_hi:[0,1]
	v_pk_mul_f32 v[64:65], v[2:3], v[60:61] op_sel:[0,1] op_sel_hi:[1,0]
	v_pk_mul_f32 v[182:183], v[166:167], s[36:37]
	v_pk_mul_f32 v[80:81], v[2:3], v[76:77] op_sel:[0,1] op_sel_hi:[1,0]
	v_pk_fma_f32 v[166:167], v[166:167], s[78:79], v[182:183] op_sel:[0,0,1] op_sel_hi:[1,0,0]
	v_pk_add_f32 v[182:183], v[168:169], v[184:185]
	v_pk_add_f32 v[168:169], v[168:169], v[184:185] neg_lo:[0,1] neg_hi:[0,1]
	v_pk_mul_f32 v[96:97], v[2:3], v[92:93] op_sel:[0,1] op_sel_hi:[1,0]
	v_pk_mul_f32 v[184:185], v[168:169], s[40:41]
	v_pk_mul_f32 v[112:113], v[2:3], v[108:109] op_sel:[0,1] op_sel_hi:[1,0]
	v_pk_fma_f32 v[168:169], v[168:169], s[80:81], v[184:185] op_sel:[0,0,1] op_sel_hi:[1,0,0]
	v_pk_add_f32 v[184:185], v[170:171], v[186:187]
	v_pk_add_f32 v[186:187], v[170:171], v[186:187] neg_lo:[0,1] neg_hi:[0,1]
	v_pk_mul_f32 v[22:23], v[8:9], 1.0 op_sel:[1,0] op_sel_hi:[1,0] neg_lo:[1,0]
	v_pk_add_f32 v[170:171], v[172:173], v[188:189]
	v_pk_add_f32 v[172:173], v[172:173], v[188:189] neg_lo:[0,1] neg_hi:[0,1]
	s_nop 0
	v_pk_mul_f32 v[188:189], v[172:173], s[40:41]
	v_pk_fma_f32 v[16:17], v[4:5], v[10:11], v[16:17] op_sel_hi:[0,1,1]
	v_pk_fma_f32 v[172:173], v[172:173], s[80:81], v[188:189] op_sel:[0,0,1] op_sel_hi:[1,0,0] neg_lo:[1,0,0] neg_hi:[1,0,0]
	v_pk_add_f32 v[188:189], v[174:175], v[190:191]
	v_pk_add_f32 v[174:175], v[174:175], v[190:191] neg_lo:[0,1] neg_hi:[0,1]
	v_pk_mul_f32 v[20:21], v[12:13], v[10:11] op_sel:[0,1] op_sel_hi:[1,0]
	v_pk_mul_f32 v[190:191], v[174:175], s[36:37]
	v_pk_fma_f32 v[32:33], v[4:5], v[28:29], v[32:33] op_sel_hi:[0,1,1]
	v_pk_fma_f32 v[174:175], v[174:175], s[78:79], v[190:191] op_sel:[0,0,1] op_sel_hi:[1,0,0] neg_lo:[1,0,0] neg_hi:[1,0,0]
	v_pk_add_f32 v[190:191], v[176:177], v[192:193]
	v_pk_add_f32 v[176:177], v[176:177], v[192:193] neg_lo:[0,1] neg_hi:[0,1]
	v_pk_mul_f32 v[36:37], v[12:13], v[28:29] op_sel:[0,1] op_sel_hi:[1,0]
	v_pk_mul_f32 v[192:193], v[176:177], s[18:19]
	v_pk_fma_f32 v[48:49], v[4:5], v[44:45], v[48:49] op_sel_hi:[0,1,1]
	v_pk_fma_f32 v[176:177], v[176:177], s[16:17], v[192:193] op_sel:[0,0,1] op_sel_hi:[1,0,0] neg_lo:[1,0,0] neg_hi:[1,0,0]
	v_pk_add_f32 v[192:193], v[128:129], v[180:181] op_sel:[0,1] op_sel_hi:[1,0] neg_hi:[0,1]
	v_pk_add_f32 v[128:129], v[128:129], v[180:181] op_sel:[0,1] op_sel_hi:[1,0] neg_lo:[0,1]
	v_pk_add_f32 v[180:181], v[130:131], v[150:151]
	v_pk_add_f32 v[130:131], v[130:131], v[150:151] neg_lo:[0,1] neg_hi:[0,1]
	v_pk_mul_f32 v[52:53], v[12:13], v[44:45] op_sel:[0,1] op_sel_hi:[1,0]
	v_pk_mul_f32 v[150:151], v[130:131], s[18:19]
	v_pk_fma_f32 v[64:65], v[4:5], v[60:61], v[64:65] op_sel_hi:[0,1,1]
	v_pk_fma_f32 v[130:131], v[130:131], s[16:17], v[150:151] op_sel:[0,0,1] op_sel_hi:[1,0,0]
	v_pk_add_f32 v[150:151], v[132:133], v[152:153]
	v_pk_add_f32 v[132:133], v[132:133], v[152:153] neg_lo:[0,1] neg_hi:[0,1]
	v_pk_mul_f32 v[68:69], v[12:13], v[60:61] op_sel:[0,1] op_sel_hi:[1,0]
	v_pk_mul_f32 v[152:153], v[132:133], s[36:37]
	v_pk_fma_f32 v[80:81], v[4:5], v[76:77], v[80:81] op_sel_hi:[0,1,1]
	v_pk_fma_f32 v[132:133], v[132:133], s[78:79], v[152:153] op_sel:[0,0,1] op_sel_hi:[1,0,0]
	v_pk_add_f32 v[152:153], v[134:135], v[154:155]
	v_pk_add_f32 v[134:135], v[134:135], v[154:155] neg_lo:[0,1] neg_hi:[0,1]
	v_pk_mul_f32 v[84:85], v[12:13], v[76:77] op_sel:[0,1] op_sel_hi:[1,0]
	v_pk_mul_f32 v[154:155], v[134:135], s[40:41]
	v_pk_fma_f32 v[96:97], v[4:5], v[92:93], v[96:97] op_sel_hi:[0,1,1]
	v_pk_fma_f32 v[134:135], v[134:135], s[80:81], v[154:155] op_sel:[0,0,1] op_sel_hi:[1,0,0]
	v_pk_add_f32 v[154:155], v[136:137], v[156:157]
	v_pk_add_f32 v[156:157], v[136:137], v[156:157] neg_lo:[0,1] neg_hi:[0,1]
	v_pk_mul_f32 v[100:101], v[12:13], v[92:93] op_sel:[0,1] op_sel_hi:[1,0]
	v_pk_add_f32 v[136:137], v[138:139], v[158:159]
	v_pk_add_f32 v[138:139], v[138:139], v[158:159] neg_lo:[0,1] neg_hi:[0,1]
	v_pk_fma_f32 v[112:113], v[4:5], v[108:109], v[112:113] op_sel_hi:[0,1,1]
	v_pk_mul_f32 v[158:159], v[138:139], s[40:41]
	v_pk_mul_f32 v[116:117], v[12:13], v[108:109] op_sel:[0,1] op_sel_hi:[1,0]
	v_pk_fma_f32 v[138:139], v[138:139], s[80:81], v[158:159] op_sel:[0,0,1] op_sel_hi:[1,0,0] neg_lo:[1,0,0] neg_hi:[1,0,0]
	v_pk_add_f32 v[158:159], v[140:141], v[160:161]
	v_pk_add_f32 v[140:141], v[140:141], v[160:161] neg_lo:[0,1] neg_hi:[0,1]
	v_pk_fma_f32 v[20:21], v[6:7], v[10:11], v[20:21] op_sel_hi:[0,1,1]
	v_pk_mul_f32 v[160:161], v[140:141], s[36:37]
	v_pk_mul_f32 v[24:25], v[10:11], v[22:23] op_sel:[1,0] op_sel_hi:[0,1]
	v_pk_fma_f32 v[140:141], v[140:141], s[78:79], v[160:161] op_sel:[0,0,1] op_sel_hi:[1,0,0] neg_lo:[1,0,0] neg_hi:[1,0,0]
	v_pk_add_f32 v[160:161], v[142:143], v[162:163]
	v_pk_add_f32 v[142:143], v[142:143], v[162:163] neg_lo:[0,1] neg_hi:[0,1]
	v_pk_fma_f32 v[36:37], v[6:7], v[28:29], v[36:37] op_sel_hi:[0,1,1]
	v_pk_mul_f32 v[162:163], v[142:143], s[18:19]
	v_pk_mul_f32 v[40:41], v[22:23], v[28:29] op_sel:[0,1] op_sel_hi:[1,0]
	v_pk_fma_f32 v[142:143], v[142:143], s[16:17], v[162:163] op_sel:[0,0,1] op_sel_hi:[1,0,0] neg_lo:[1,0,0] neg_hi:[1,0,0]
	v_pk_add_f32 v[162:163], v[194:195], v[184:185]
	v_pk_add_f32 v[184:185], v[194:195], v[184:185] neg_lo:[0,1] neg_hi:[0,1]
	v_pk_add_f32 v[194:195], v[178:179], v[170:171]
	v_pk_add_f32 v[170:171], v[178:179], v[170:171] neg_lo:[0,1] neg_hi:[0,1]
	v_pk_fma_f32 v[52:53], v[6:7], v[44:45], v[52:53] op_sel_hi:[0,1,1]
	v_pk_mul_f32 v[178:179], v[170:171], s[36:37]
	v_pk_mul_f32 v[56:57], v[22:23], v[44:45] op_sel:[0,1] op_sel_hi:[1,0]
	v_pk_fma_f32 v[170:171], v[170:171], s[78:79], v[178:179] op_sel:[0,0,1] op_sel_hi:[1,0,0]
	v_pk_add_f32 v[178:179], v[164:165], v[188:189]
	v_pk_add_f32 v[188:189], v[164:165], v[188:189] neg_lo:[0,1] neg_hi:[0,1]
	v_pk_fma_f32 v[68:69], v[6:7], v[60:61], v[68:69] op_sel_hi:[0,1,1]
	v_pk_add_f32 v[164:165], v[182:183], v[190:191]
	v_pk_add_f32 v[182:183], v[182:183], v[190:191] neg_lo:[0,1] neg_hi:[0,1]
	v_pk_mul_f32 v[72:73], v[22:23], v[60:61] op_sel:[0,1] op_sel_hi:[1,0]
	v_pk_mul_f32 v[190:191], v[182:183], s[36:37]
	v_pk_fma_f32 v[84:85], v[6:7], v[76:77], v[84:85] op_sel_hi:[0,1,1]
	v_pk_fma_f32 v[182:183], v[182:183], s[78:79], v[190:191] op_sel:[0,0,1] op_sel_hi:[1,0,0] neg_lo:[1,0,0] neg_hi:[1,0,0]
	v_pk_add_f32 v[190:191], v[144:145], v[186:187] op_sel:[0,1] op_sel_hi:[1,0] neg_hi:[0,1]
	v_pk_add_f32 v[144:145], v[144:145], v[186:187] op_sel:[0,1] op_sel_hi:[1,0] neg_lo:[0,1]
	v_pk_add_f32 v[186:187], v[148:149], v[172:173]
	v_pk_add_f32 v[148:149], v[148:149], v[172:173] neg_lo:[0,1] neg_hi:[0,1]
	v_pk_mul_f32 v[88:89], v[22:23], v[76:77] op_sel:[0,1] op_sel_hi:[1,0]
	v_pk_mul_f32 v[172:173], v[148:149], s[36:37]
	v_pk_fma_f32 v[100:101], v[6:7], v[92:93], v[100:101] op_sel_hi:[0,1,1]
	v_pk_fma_f32 v[148:149], v[148:149], s[78:79], v[172:173] op_sel:[0,0,1] op_sel_hi:[1,0,0]
	v_pk_add_f32 v[172:173], v[166:167], v[174:175]
	v_pk_add_f32 v[174:175], v[166:167], v[174:175] neg_lo:[0,1] neg_hi:[0,1]
	v_pk_mul_f32 v[104:105], v[22:23], v[92:93] op_sel:[0,1] op_sel_hi:[1,0]
	v_pk_add_f32 v[166:167], v[168:169], v[176:177]
	v_pk_add_f32 v[168:169], v[168:169], v[176:177] neg_lo:[0,1] neg_hi:[0,1]
	v_pk_fma_f32 v[116:117], v[6:7], v[108:109], v[116:117] op_sel_hi:[0,1,1]
	v_pk_mul_f32 v[176:177], v[168:169], s[36:37]
	v_pk_mul_f32 v[120:121], v[22:23], v[108:109] op_sel:[0,1] op_sel_hi:[1,0]
	v_pk_fma_f32 v[168:169], v[168:169], s[78:79], v[176:177] op_sel:[0,0,1] op_sel_hi:[1,0,0] neg_lo:[1,0,0] neg_hi:[1,0,0]
	v_pk_add_f32 v[176:177], v[192:193], v[154:155]
	v_pk_add_f32 v[154:155], v[192:193], v[154:155] neg_lo:[0,1] neg_hi:[0,1]
	v_pk_add_f32 v[192:193], v[180:181], v[136:137]
	v_pk_add_f32 v[136:137], v[180:181], v[136:137] neg_lo:[0,1] neg_hi:[0,1]
	v_xor_b32_e32 v26, 0x80000000, v17
	v_pk_mul_f32 v[180:181], v[136:137], s[36:37]
	v_xor_b32_e32 v30, 0x80000000, v21
	v_pk_fma_f32 v[136:137], v[136:137], s[78:79], v[180:181] op_sel:[0,0,1] op_sel_hi:[1,0,0]
	v_pk_add_f32 v[180:181], v[150:151], v[158:159]
	v_pk_add_f32 v[158:159], v[150:151], v[158:159] neg_lo:[0,1] neg_hi:[0,1]
	v_pk_fma_f32 v[24:25], v[10:11], v[8:9], v[24:25] op_sel_hi:[1,0,1]
	v_pk_add_f32 v[150:151], v[152:153], v[160:161]
	v_pk_add_f32 v[152:153], v[152:153], v[160:161] neg_lo:[0,1] neg_hi:[0,1]
	v_pk_fma_f32 v[40:41], v[8:9], v[28:29], v[40:41] op_sel_hi:[0,1,1]
	v_pk_mul_f32 v[160:161], v[152:153], s[36:37]
	v_pk_fma_f32 v[56:57], v[8:9], v[44:45], v[56:57] op_sel_hi:[0,1,1]
	v_pk_fma_f32 v[152:153], v[152:153], s[78:79], v[160:161] op_sel:[0,0,1] op_sel_hi:[1,0,0] neg_lo:[1,0,0] neg_hi:[1,0,0]
	v_pk_add_f32 v[160:161], v[128:129], v[156:157] op_sel:[0,1] op_sel_hi:[1,0] neg_hi:[0,1]
	v_pk_add_f32 v[128:129], v[128:129], v[156:157] op_sel:[0,1] op_sel_hi:[1,0] neg_lo:[0,1]
	v_pk_add_f32 v[156:157], v[130:131], v[138:139]
	v_pk_add_f32 v[130:131], v[130:131], v[138:139] neg_lo:[0,1] neg_hi:[0,1]
	v_pk_fma_f32 v[72:73], v[8:9], v[60:61], v[72:73] op_sel_hi:[0,1,1]
	v_pk_mul_f32 v[138:139], v[130:131], s[36:37]
	v_pk_fma_f32 v[88:89], v[8:9], v[76:77], v[88:89] op_sel_hi:[0,1,1]
	v_pk_fma_f32 v[130:131], v[130:131], s[78:79], v[138:139] op_sel:[0,0,1] op_sel_hi:[1,0,0]
	v_pk_add_f32 v[138:139], v[132:133], v[140:141]
	v_pk_add_f32 v[140:141], v[132:133], v[140:141] neg_lo:[0,1] neg_hi:[0,1]
	v_pk_fma_f32 v[104:105], v[8:9], v[92:93], v[104:105] op_sel_hi:[0,1,1]
	v_pk_add_f32 v[132:133], v[134:135], v[142:143]
	v_pk_add_f32 v[134:135], v[134:135], v[142:143] neg_lo:[0,1] neg_hi:[0,1]
	v_pk_fma_f32 v[120:121], v[8:9], v[108:109], v[120:121] op_sel_hi:[0,1,1]
	v_pk_mul_f32 v[142:143], v[134:135], s[36:37]
	v_mov_b32_e32 v27, v17
	v_pk_fma_f32 v[134:135], v[134:135], s[78:79], v[142:143] op_sel:[0,0,1] op_sel_hi:[1,0,0] neg_lo:[1,0,0] neg_hi:[1,0,0]
	v_pk_add_f32 v[142:143], v[162:163], v[178:179]
	v_pk_add_f32 v[162:163], v[162:163], v[178:179] neg_lo:[0,1] neg_hi:[0,1]
	v_pk_add_f32 v[178:179], v[194:195], v[164:165]
	v_pk_add_f32 v[194:195], v[194:195], v[164:165] neg_lo:[0,1] neg_hi:[0,1]
	v_mov_b32_e32 v31, v21
	v_pk_add_f32 v[164:165], v[184:185], v[188:189] op_sel:[0,1] op_sel_hi:[1,0] neg_hi:[0,1]
	v_pk_add_f32 v[184:185], v[184:185], v[188:189] op_sel:[0,1] op_sel_hi:[1,0] neg_lo:[0,1]
	v_pk_add_f32 v[188:189], v[170:171], v[182:183]
	v_pk_add_f32 v[182:183], v[170:171], v[182:183] neg_lo:[0,1] neg_hi:[0,1]
	v_xor_b32_e32 v34, 0x80000000, v25
	v_pk_add_f32 v[170:171], v[190:191], v[172:173]
	v_pk_add_f32 v[172:173], v[190:191], v[172:173] neg_lo:[0,1] neg_hi:[0,1]
	v_pk_add_f32 v[190:191], v[186:187], v[166:167]
	v_pk_add_f32 v[186:187], v[186:187], v[166:167] neg_lo:[0,1] neg_hi:[0,1]
	v_xor_b32_e32 v38, 0x80000000, v29
	v_pk_add_f32 v[166:167], v[144:145], v[174:175] op_sel:[0,1] op_sel_hi:[1,0] neg_hi:[0,1]
	v_pk_add_f32 v[144:145], v[144:145], v[174:175] op_sel:[0,1] op_sel_hi:[1,0] neg_lo:[0,1]
	v_pk_add_f32 v[174:175], v[148:149], v[168:169]
	v_pk_add_f32 v[168:169], v[148:149], v[168:169] neg_lo:[0,1] neg_hi:[0,1]
	v_xor_b32_e32 v42, 0x80000000, v33
	v_pk_add_f32 v[148:149], v[176:177], v[180:181]
	v_pk_add_f32 v[176:177], v[176:177], v[180:181] neg_lo:[0,1] neg_hi:[0,1]
	v_pk_add_f32 v[180:181], v[192:193], v[150:151]
	v_pk_add_f32 v[192:193], v[192:193], v[150:151] neg_lo:[0,1] neg_hi:[0,1]
	v_xor_b32_e32 v46, 0x80000000, v37
	v_pk_add_f32 v[150:151], v[154:155], v[158:159] op_sel:[0,1] op_sel_hi:[1,0] neg_hi:[0,1]
	v_pk_add_f32 v[154:155], v[154:155], v[158:159] op_sel:[0,1] op_sel_hi:[1,0] neg_lo:[0,1]
	v_pk_add_f32 v[158:159], v[136:137], v[152:153]
	v_pk_add_f32 v[152:153], v[136:137], v[152:153] neg_lo:[0,1] neg_hi:[0,1]
	v_mov_b32_e32 v35, v25
	v_pk_add_f32 v[136:137], v[160:161], v[138:139]
	v_pk_add_f32 v[138:139], v[160:161], v[138:139] neg_lo:[0,1] neg_hi:[0,1]
	v_pk_add_f32 v[160:161], v[156:157], v[132:133]
	v_pk_add_f32 v[156:157], v[156:157], v[132:133] neg_lo:[0,1] neg_hi:[0,1]
	v_mov_b32_e32 v39, v29
	v_pk_add_f32 v[132:133], v[128:129], v[140:141] op_sel:[0,1] op_sel_hi:[1,0] neg_hi:[0,1]
	v_pk_add_f32 v[128:129], v[128:129], v[140:141] op_sel:[0,1] op_sel_hi:[1,0] neg_lo:[0,1]
	v_pk_add_f32 v[140:141], v[130:131], v[134:135]
	v_pk_add_f32 v[134:135], v[130:131], v[134:135] neg_lo:[0,1] neg_hi:[0,1]
	v_mov_b32_e32 v43, v33
	v_pk_add_f32 v[130:131], v[142:143], v[178:179]
	v_pk_add_f32 v[142:143], v[142:143], v[178:179] neg_lo:[0,1] neg_hi:[0,1]
	v_pk_add_f32 v[178:179], v[162:163], v[194:195] op_sel:[0,1] op_sel_hi:[1,0] neg_hi:[0,1]
	v_pk_add_f32 v[162:163], v[162:163], v[194:195] op_sel:[0,1] op_sel_hi:[1,0] neg_lo:[0,1]
	v_pk_add_f32 v[194:195], v[164:165], v[188:189]
	v_pk_add_f32 v[164:165], v[164:165], v[188:189] neg_lo:[0,1] neg_hi:[0,1]
	v_pk_add_f32 v[188:189], v[184:185], v[182:183] op_sel:[0,1] op_sel_hi:[1,0] neg_hi:[0,1]
	v_pk_add_f32 v[182:183], v[184:185], v[182:183] op_sel:[0,1] op_sel_hi:[1,0] neg_lo:[0,1]
	v_pk_add_f32 v[184:185], v[170:171], v[190:191]
	v_pk_add_f32 v[170:171], v[170:171], v[190:191] neg_lo:[0,1] neg_hi:[0,1]
	v_pk_add_f32 v[190:191], v[172:173], v[186:187] op_sel:[0,1] op_sel_hi:[1,0] neg_hi:[0,1]
	v_pk_add_f32 v[172:173], v[172:173], v[186:187] op_sel:[0,1] op_sel_hi:[1,0] neg_lo:[0,1]
	v_pk_add_f32 v[186:187], v[166:167], v[174:175]
	v_pk_add_f32 v[166:167], v[166:167], v[174:175] neg_lo:[0,1] neg_hi:[0,1]
	v_pk_add_f32 v[174:175], v[144:145], v[168:169] op_sel:[0,1] op_sel_hi:[1,0] neg_hi:[0,1]
	v_pk_add_f32 v[144:145], v[144:145], v[168:169] op_sel:[0,1] op_sel_hi:[1,0] neg_lo:[0,1]
	v_pk_add_f32 v[168:169], v[148:149], v[180:181]
	v_pk_add_f32 v[148:149], v[148:149], v[180:181] neg_lo:[0,1] neg_hi:[0,1]
	v_pk_mul_f32 v[2:3], v[2:3], v[168:169] op_sel:[0,1] op_sel_hi:[1,0]
	v_pk_add_f32 v[180:181], v[176:177], v[192:193] op_sel:[0,1] op_sel_hi:[1,0] neg_hi:[0,1]
	v_pk_add_f32 v[176:177], v[176:177], v[192:193] op_sel:[0,1] op_sel_hi:[1,0] neg_lo:[0,1]
	v_pk_add_f32 v[192:193], v[150:151], v[158:159]
	v_pk_add_f32 v[150:151], v[150:151], v[158:159] neg_lo:[0,1] neg_hi:[0,1]
	v_pk_add_f32 v[158:159], v[154:155], v[152:153] op_sel:[0,1] op_sel_hi:[1,0] neg_hi:[0,1]
	v_pk_add_f32 v[152:153], v[154:155], v[152:153] op_sel:[0,1] op_sel_hi:[1,0] neg_lo:[0,1]
	v_pk_add_f32 v[154:155], v[136:137], v[160:161]
	v_pk_fma_f32 v[2:3], v[4:5], v[168:169], v[2:3] op_sel_hi:[0,1,1]
	v_pk_mul_f32 v[4:5], v[12:13], v[184:185] op_sel:[0,1] op_sel_hi:[1,0]
	v_mov_b32_e32 v47, v37
	v_pk_fma_f32 v[4:5], v[6:7], v[184:185], v[4:5] op_sel_hi:[0,1,1]
	v_pk_mul_f32 v[6:7], v[22:23], v[154:155] op_sel:[0,1] op_sel_hi:[1,0]
	v_pk_add_f32 v[136:137], v[136:137], v[160:161] neg_lo:[0,1] neg_hi:[0,1]
	v_pk_fma_f32 v[6:7], v[8:9], v[154:155], v[6:7] op_sel_hi:[0,1,1]
	v_pk_mul_f32 v[8:9], v[14:15], v[194:195] op_sel:[0,1] op_sel_hi:[1,0]
	v_pk_add_f32 v[160:161], v[138:139], v[156:157] op_sel:[0,1] op_sel_hi:[1,0] neg_hi:[0,1]
	v_pk_add_f32 v[138:139], v[138:139], v[156:157] op_sel:[0,1] op_sel_hi:[1,0] neg_lo:[0,1]
	v_pk_add_f32 v[156:157], v[132:133], v[140:141]
	v_pk_fma_f32 v[8:9], v[10:11], v[194:195], v[8:9] op_sel_hi:[0,1,1]
	v_pk_mul_f32 v[10:11], v[26:27], v[192:193] op_sel:[0,1] op_sel_hi:[1,0]
	v_pk_mul_f32 v[12:13], v[30:31], v[186:187] op_sel:[0,1] op_sel_hi:[1,0]
	v_xor_b32_e32 v50, 0x80000000, v41
	v_xor_b32_e32 v54, 0x80000000, v45
	v_xor_b32_e32 v58, 0x80000000, v49
	v_xor_b32_e32 v62, 0x80000000, v53
	v_xor_b32_e32 v66, 0x80000000, v57
	v_xor_b32_e32 v70, 0x80000000, v61
	v_xor_b32_e32 v74, 0x80000000, v65
	v_mov_b32_e32 v51, v41
	v_mov_b32_e32 v55, v45
	v_mov_b32_e32 v59, v49
	v_mov_b32_e32 v63, v53
	v_mov_b32_e32 v67, v57
	v_mov_b32_e32 v71, v61
	v_mov_b32_e32 v75, v65
	v_pk_add_f32 v[132:133], v[132:133], v[140:141] neg_lo:[0,1] neg_hi:[0,1]
	v_pk_add_f32 v[140:141], v[128:129], v[134:135] op_sel:[0,1] op_sel_hi:[1,0] neg_hi:[0,1]
	v_pk_fma_f32 v[10:11], v[16:17], v[192:193], v[10:11] op_sel_hi:[0,1,1]
	v_pk_fma_f32 v[12:13], v[20:21], v[186:187], v[12:13] op_sel_hi:[0,1,1]
	v_pk_mul_f32 v[14:15], v[34:35], v[156:157] op_sel:[0,1] op_sel_hi:[1,0]
	v_pk_mul_f32 v[16:17], v[38:39], v[178:179] op_sel:[0,1] op_sel_hi:[1,0]
	v_pk_mul_f32 v[20:21], v[42:43], v[180:181] op_sel:[0,1] op_sel_hi:[1,0]
	v_pk_mul_f32 v[22:23], v[46:47], v[190:191] op_sel:[0,1] op_sel_hi:[1,0]
	v_xor_b32_e32 v78, 0x80000000, v69
	v_xor_b32_e32 v82, 0x80000000, v73
	v_xor_b32_e32 v86, 0x80000000, v77
	v_xor_b32_e32 v90, 0x80000000, v81
	v_xor_b32_e32 v94, 0x80000000, v85
	v_xor_b32_e32 v98, 0x80000000, v89
	v_xor_b32_e32 v102, 0x80000000, v93
	v_xor_b32_e32 v106, 0x80000000, v97
	v_xor_b32_e32 v110, 0x80000000, v101
	v_xor_b32_e32 v114, 0x80000000, v105
	v_xor_b32_e32 v118, 0x80000000, v109
	v_xor_b32_e32 v122, 0x80000000, v113
	v_xor_b32_e32 v124, 0x80000000, v117
	v_xor_b32_e32 v126, 0x80000000, v121
	v_mov_b32_e32 v79, v69
	v_mov_b32_e32 v83, v73
	v_mov_b32_e32 v87, v77
	v_mov_b32_e32 v91, v81
	v_mov_b32_e32 v95, v85
	v_mov_b32_e32 v99, v89
	v_mov_b32_e32 v103, v93
	v_mov_b32_e32 v107, v97
	v_mov_b32_e32 v111, v101
	v_mov_b32_e32 v115, v105
	v_mov_b32_e32 v119, v109
	v_mov_b32_e32 v123, v113
	v_mov_b32_e32 v125, v117
	v_mov_b32_e32 v127, v121
	v_pk_add_f32 v[128:129], v[128:129], v[134:135] op_sel:[0,1] op_sel_hi:[1,0] neg_lo:[0,1]
	v_pk_fma_f32 v[14:15], v[24:25], v[156:157], v[14:15] op_sel_hi:[0,1,1]
	v_pk_fma_f32 v[16:17], v[28:29], v[178:179], v[16:17] op_sel_hi:[0,1,1]
	v_pk_fma_f32 v[20:21], v[32:33], v[180:181], v[20:21] op_sel_hi:[0,1,1]
	v_pk_fma_f32 v[22:23], v[36:37], v[190:191], v[22:23] op_sel_hi:[0,1,1]
	v_pk_mul_f32 v[24:25], v[50:51], v[160:161] op_sel:[0,1] op_sel_hi:[1,0]
	v_pk_mul_f32 v[26:27], v[54:55], v[188:189] op_sel:[0,1] op_sel_hi:[1,0]
	v_pk_mul_f32 v[28:29], v[58:59], v[158:159] op_sel:[0,1] op_sel_hi:[1,0]
	v_pk_mul_f32 v[30:31], v[62:63], v[174:175] op_sel:[0,1] op_sel_hi:[1,0]
	v_pk_mul_f32 v[32:33], v[66:67], v[140:141] op_sel:[0,1] op_sel_hi:[1,0]
	v_pk_mul_f32 v[34:35], v[70:71], v[142:143] op_sel:[0,1] op_sel_hi:[1,0]
	v_pk_mul_f32 v[36:37], v[74:75], v[148:149] op_sel:[0,1] op_sel_hi:[1,0]
	v_pk_fma_f32 v[24:25], v[40:41], v[160:161], v[24:25] op_sel_hi:[0,1,1]
	v_pk_fma_f32 v[26:27], v[44:45], v[188:189], v[26:27] op_sel_hi:[0,1,1]
	v_pk_fma_f32 v[28:29], v[48:49], v[158:159], v[28:29] op_sel_hi:[0,1,1]
	v_pk_fma_f32 v[30:31], v[52:53], v[174:175], v[30:31] op_sel_hi:[0,1,1]
	v_pk_fma_f32 v[32:33], v[56:57], v[140:141], v[32:33] op_sel_hi:[0,1,1]
	v_pk_fma_f32 v[34:35], v[60:61], v[142:143], v[34:35] op_sel_hi:[0,1,1]
	v_pk_fma_f32 v[36:37], v[64:65], v[148:149], v[36:37] op_sel_hi:[0,1,1]
	v_pk_mul_f32 v[38:39], v[78:79], v[170:171] op_sel:[0,1] op_sel_hi:[1,0]
	v_pk_mul_f32 v[40:41], v[82:83], v[136:137] op_sel:[0,1] op_sel_hi:[1,0]
	v_pk_mul_f32 v[42:43], v[86:87], v[164:165] op_sel:[0,1] op_sel_hi:[1,0]
	v_pk_mul_f32 v[44:45], v[90:91], v[150:151] op_sel:[0,1] op_sel_hi:[1,0]
	v_pk_mul_f32 v[46:47], v[94:95], v[166:167] op_sel:[0,1] op_sel_hi:[1,0]
	v_pk_mul_f32 v[48:49], v[98:99], v[132:133] op_sel:[0,1] op_sel_hi:[1,0]
	v_pk_mul_f32 v[50:51], v[102:103], v[162:163] op_sel:[0,1] op_sel_hi:[1,0]
	v_pk_mul_f32 v[52:53], v[106:107], v[176:177] op_sel:[0,1] op_sel_hi:[1,0]
	v_pk_mul_f32 v[54:55], v[110:111], v[172:173] op_sel:[0,1] op_sel_hi:[1,0]
	v_pk_mul_f32 v[56:57], v[114:115], v[138:139] op_sel:[0,1] op_sel_hi:[1,0]
	v_pk_mul_f32 v[58:59], v[118:119], v[182:183] op_sel:[0,1] op_sel_hi:[1,0]
	v_pk_mul_f32 v[60:61], v[122:123], v[152:153] op_sel:[0,1] op_sel_hi:[1,0]
	v_pk_mul_f32 v[62:63], v[124:125], v[144:145] op_sel:[0,1] op_sel_hi:[1,0]
	v_pk_mul_f32 v[64:65], v[126:127], v[128:129] op_sel:[0,1] op_sel_hi:[1,0]
	v_pk_fma_f32 v[38:39], v[68:69], v[170:171], v[38:39] op_sel_hi:[0,1,1]
	v_pk_fma_f32 v[40:41], v[72:73], v[136:137], v[40:41] op_sel_hi:[0,1,1]
	v_pk_fma_f32 v[42:43], v[76:77], v[164:165], v[42:43] op_sel_hi:[0,1,1]
	v_pk_fma_f32 v[44:45], v[80:81], v[150:151], v[44:45] op_sel_hi:[0,1,1]
	v_pk_fma_f32 v[46:47], v[84:85], v[166:167], v[46:47] op_sel_hi:[0,1,1]
	v_pk_fma_f32 v[48:49], v[88:89], v[132:133], v[48:49] op_sel_hi:[0,1,1]
	v_pk_fma_f32 v[50:51], v[92:93], v[162:163], v[50:51] op_sel_hi:[0,1,1]
	v_pk_fma_f32 v[52:53], v[96:97], v[176:177], v[52:53] op_sel_hi:[0,1,1]
	v_pk_fma_f32 v[54:55], v[100:101], v[172:173], v[54:55] op_sel_hi:[0,1,1]
	v_pk_fma_f32 v[56:57], v[104:105], v[138:139], v[56:57] op_sel_hi:[0,1,1]
	v_pk_fma_f32 v[58:59], v[108:109], v[182:183], v[58:59] op_sel_hi:[0,1,1]
	v_pk_fma_f32 v[60:61], v[112:113], v[152:153], v[60:61] op_sel_hi:[0,1,1]
	v_pk_fma_f32 v[62:63], v[116:117], v[144:145], v[62:63] op_sel_hi:[0,1,1]
	v_pk_fma_f32 v[64:65], v[120:121], v[128:129], v[64:65] op_sel_hi:[0,1,1]
	ds_write2_b64 v18, v[130:131], v[34:35] offset1:16
	ds_write2_b64 v18, v[16:17], v[50:51] offset0:33 offset1:49
	ds_write2_b64 v18, v[8:9], v[42:43] offset0:66 offset1:82
	ds_write2_b64 v18, v[26:27], v[58:59] offset0:99 offset1:115
	ds_write2_b64 v18, v[4:5], v[38:39] offset0:132 offset1:148
	ds_write2_b64 v18, v[22:23], v[54:55] offset0:165 offset1:181
	ds_write2_b64 v18, v[12:13], v[46:47] offset0:198 offset1:214
	ds_write2_b64 v18, v[30:31], v[62:63] offset0:231 offset1:247
	ds_write2_b64 v196, v[2:3], v[36:37] offset0:8 offset1:24
	ds_write2_b64 v196, v[20:21], v[52:53] offset0:41 offset1:57
	ds_write2_b64 v196, v[10:11], v[44:45] offset0:74 offset1:90
	ds_write2_b64 v196, v[28:29], v[60:61] offset0:107 offset1:123
	ds_write2_b64 v196, v[6:7], v[40:41] offset0:140 offset1:156
	ds_write2_b64 v196, v[24:25], v[56:57] offset0:173 offset1:189
	ds_write2_b64 v196, v[14:15], v[48:49] offset0:206 offset1:222
	ds_write2_b64 v196, v[32:33], v[64:65] offset0:239 offset1:255
	v_ashrrev_i32_e32 v2, 31, v210
	v_lshrrev_b32_e32 v2, 23, v2
	v_add_u32_e32 v2, v210, v2
	s_lshl_b64 s[74:75], s[76:77], 16
	v_and_b32_e32 v2, 0xfffffe00, v2
	s_add_u32 s0, s54, s74
	v_sub_u32_e32 v2, v210, v2
	s_addc_u32 s1, s55, s75
	v_ashrrev_i32_e32 v3, 31, v2
	v_lshl_add_u64 v[14:15], v[2:3], 3, s[0:1]
	v_add_co_u32_e32 v2, vcc, s92, v14
	s_mov_b32 s0, 0x8000
	s_nop 0
	v_addc_co_u32_e32 v3, vcc, 0, v15, vcc
	v_add_co_u32_e32 v4, vcc, s95, v14
	s_waitcnt lgkmcnt(0)
	s_nop 0
	v_addc_co_u32_e32 v5, vcc, 0, v15, vcc
	v_add_co_u32_e32 v8, vcc, s96, v14
	s_barrier
	s_nop 0
	v_addc_co_u32_e32 v9, vcc, 0, v15, vcc
	global_load_dwordx2 v[24:25], v[4:5], off offset:-4096 nt
	global_load_dwordx2 v[12:13], v[4:5], off nt
	global_load_dwordx2 v[6:7], v[8:9], off offset:-4096 nt
	s_nop 0
	global_load_dwordx2 v[4:5], v[8:9], off nt
	v_add_co_u32_e32 v8, vcc, s0, v14
	s_waitcnt vmcnt(3)
	v_cvt_f32_f16_sdwa v174, v24 dst_sel:DWORD dst_unused:UNUSED_PAD src0_sel:WORD_1
	v_addc_co_u32_e32 v9, vcc, 0, v15, vcc
	v_add_co_u32_e32 v10, vcc, s34, v14
	v_cvt_f32_f16_e32 v175, v25
	s_nop 0
	v_addc_co_u32_e32 v11, vcc, 0, v15, vcc
	global_load_dwordx2 v[16:17], v[8:9], off offset:-4096 nt
	global_load_dwordx2 v[122:123], v[8:9], off nt
	global_load_dwordx2 v[46:47], v[10:11], off offset:-4096 nt
	global_load_dwordx2 v[36:37], v[10:11], off nt
	v_add_co_u32_e32 v8, vcc, s35, v14
	v_cvt_f32_f16_sdwa v177, v25 dst_sel:DWORD dst_unused:UNUSED_PAD src0_sel:WORD_1
	s_nop 0
	v_addc_co_u32_e32 v9, vcc, 0, v15, vcc
	v_add_co_u32_e32 v22, vcc, s30, v14
	v_cvt_f32_f16_e32 v176, v24
	s_nop 0
	v_addc_co_u32_e32 v23, vcc, 0, v15, vcc
	global_load_dwordx2 v[26:27], v[8:9], off offset:-4096 nt
	global_load_dwordx2 v[20:21], v[8:9], off nt
	global_load_dwordx2 v[10:11], v[22:23], off offset:-4096 nt
	s_nop 0
	global_load_dwordx2 v[8:9], v[22:23], off nt
	v_add_co_u32_e32 v22, vcc, s31, v14
	s_waitcnt vmcnt(10)
	v_cvt_f32_f16_sdwa v164, v12 dst_sel:DWORD dst_unused:UNUSED_PAD src0_sel:WORD_1
	v_addc_co_u32_e32 v23, vcc, 0, v15, vcc
	global_load_dwordx2 v[30:31], v[2:3], off offset:-4096 nt
	global_load_dwordx2 v[28:29], v[2:3], off nt
	s_nop 0
	global_load_dwordx2 v[2:3], v[22:23], off nt
	global_load_dwordx2 v[32:33], v[14:15], off nt
	v_mov_b32_e32 v14, v210
	v_cvt_f32_f16_e32 v165, v13
	v_ashrrev_i32_e32 v15, 31, v14
	v_lshrrev_b32_e32 v15, 23, v15
	v_add_u32_e32 v15, v14, v15
	v_ashrrev_i32_e32 v15, 9, v15
	v_mul_i32_i24_e32 v18, 0x200, v15
	v_sub_u32_e32 v18, v14, v18
	v_lshlrev_b32_e32 v14, 14, v15
	v_lshlrev_b32_e32 v15, 1, v18
	v_bfrev_b32_e32 v15, v15
	v_lshrrev_b32_e32 v15, 22, v15
	v_sub_u32_e32 v15, 0x400, v15
	v_bfrev_b32_e32 v15, v15
	v_lshrrev_b32_e32 v15, 18, v15
	v_and_b32_e32 v15, 0x3ff0, v15
	v_cmp_eq_u32_e64 s[0:1], 0, v18
	v_lshl_add_u32 v22, v18, 5, v14
	v_lshl_add_u32 v23, v22, 3, 0
	v_cndmask_b32_e64 v15, v15, 16, s[0:1]
	v_or_b32_e32 v14, v15, v14
	v_ashrrev_i32_e32 v22, 2, v22
	v_ashrrev_i32_e32 v15, 5, v14
	v_add_u32_e32 v211, v23, v22
	v_lshlrev_b32_e32 v14, 3, v14
	v_lshlrev_b32_e32 v15, 3, v15
	v_add3_u32 v212, 0, v14, v15
	ds_read2_b64 v[38:41], v211 offset1:1
	ds_read2_b64 v[42:45], v211 offset0:2 offset1:3
	ds_read2_b64 v[48:51], v212 offset1:1
	ds_read2_b64 v[52:55], v212 offset0:2 offset1:3
	ds_read2_b64 v[56:59], v211 offset0:4 offset1:5
	ds_read2_b64 v[60:63], v211 offset0:6 offset1:7
	ds_read2_b64 v[68:71], v212 offset0:4 offset1:5
	ds_read2_b64 v[72:75], v212 offset0:6 offset1:7
	ds_read2_b64 v[64:67], v211 offset0:8 offset1:9
	ds_read2_b64 v[76:79], v211 offset0:10 offset1:11
	ds_read2_b64 v[80:83], v212 offset0:8 offset1:9
	ds_read2_b64 v[98:101], v212 offset0:10 offset1:11
	ds_read2_b64 v[84:87], v211 offset0:12 offset1:13
	ds_read2_b64 v[88:91], v211 offset0:14 offset1:15
	ds_read2_b64 v[102:105], v212 offset0:12 offset1:13
	ds_read2_b64 v[106:109], v212 offset0:14 offset1:15
	s_waitcnt lgkmcnt(7)
	v_pk_add_f32 v[14:15], v[38:39], v[64:65]
	v_pk_add_f32 v[22:23], v[38:39], v[64:65] neg_lo:[0,1] neg_hi:[0,1]
	v_pk_add_f32 v[38:39], v[40:41], v[66:67] neg_lo:[0,1] neg_hi:[0,1]
	v_pk_add_f32 v[34:35], v[40:41], v[66:67]
	v_pk_mul_f32 v[40:41], v[38:39], s[18:19]
	v_cmp_ne_u32_e32 vcc, 0, v18
	v_pk_fma_f32 v[38:39], v[38:39], s[16:17], v[40:41] op_sel:[0,0,1] op_sel_hi:[1,0,0]
	s_waitcnt lgkmcnt(6)
	v_pk_add_f32 v[40:41], v[42:43], v[76:77]
	v_pk_add_f32 v[42:43], v[42:43], v[76:77] neg_lo:[0,1] neg_hi:[0,1]
	v_bfrev_b32_e32 v18, v18
	v_pk_mul_f32 v[64:65], v[42:43], s[36:37]
	v_lshrrev_b32_e32 v18, 23, v18
	v_pk_fma_f32 v[42:43], v[42:43], s[78:79], v[64:65] op_sel:[0,0,1] op_sel_hi:[1,0,0]
	v_pk_add_f32 v[64:65], v[44:45], v[78:79]
	v_pk_add_f32 v[44:45], v[44:45], v[78:79] neg_lo:[0,1] neg_hi:[0,1]
	s_waitcnt lgkmcnt(3)
	v_pk_add_f32 v[78:79], v[58:59], v[86:87]
	v_pk_mul_f32 v[66:67], v[44:45], s[40:41]
	v_pk_add_f32 v[58:59], v[58:59], v[86:87] neg_lo:[0,1] neg_hi:[0,1]
	v_pk_fma_f32 v[44:45], v[44:45], s[80:81], v[66:67] op_sel:[0,0,1] op_sel_hi:[1,0,0]
	v_pk_add_f32 v[66:67], v[56:57], v[84:85]
	v_pk_add_f32 v[76:77], v[56:57], v[84:85] neg_lo:[0,1] neg_hi:[0,1]
	v_pk_mul_f32 v[84:85], v[58:59], s[40:41]
	s_nop 0
	v_pk_fma_f32 v[58:59], v[58:59], s[80:81], v[84:85] op_sel:[0,0,1] op_sel_hi:[1,0,0] neg_lo:[1,0,0] neg_hi:[1,0,0]
	s_waitcnt lgkmcnt(2)
	v_pk_add_f32 v[84:85], v[60:61], v[88:89]
	v_pk_add_f32 v[60:61], v[60:61], v[88:89] neg_lo:[0,1] neg_hi:[0,1]
	s_nop 0
	v_pk_mul_f32 v[86:87], v[60:61], s[36:37]
	v_pk_add_f32 v[56:57], v[22:23], v[76:77] op_sel:[0,1] op_sel_hi:[1,0] neg_hi:[0,1]
	v_pk_fma_f32 v[60:61], v[60:61], s[78:79], v[86:87] op_sel:[0,0,1] op_sel_hi:[1,0,0] neg_lo:[1,0,0] neg_hi:[1,0,0]
	v_pk_add_f32 v[86:87], v[62:63], v[90:91]
	v_pk_add_f32 v[62:63], v[62:63], v[90:91] neg_lo:[0,1] neg_hi:[0,1]
	v_pk_add_f32 v[90:91], v[64:65], v[86:87]
	v_pk_mul_f32 v[88:89], v[62:63], s[18:19]
	v_pk_add_f32 v[64:65], v[64:65], v[86:87] neg_lo:[0,1] neg_hi:[0,1]
	v_pk_fma_f32 v[62:63], v[62:63], s[16:17], v[88:89] op_sel:[0,0,1] op_sel_hi:[1,0,0] neg_lo:[1,0,0] neg_hi:[1,0,0]
	v_pk_add_f32 v[88:89], v[14:15], v[66:67]
	v_pk_add_f32 v[14:15], v[14:15], v[66:67] neg_lo:[0,1] neg_hi:[0,1]
	v_pk_add_f32 v[66:67], v[34:35], v[78:79]
	v_pk_add_f32 v[34:35], v[34:35], v[78:79] neg_lo:[0,1] neg_hi:[0,1]
	v_pk_add_f32 v[22:23], v[22:23], v[76:77] op_sel:[0,1] op_sel_hi:[1,0] neg_lo:[0,1]
	v_pk_mul_f32 v[78:79], v[34:35], s[36:37]
	v_pk_add_f32 v[76:77], v[38:39], v[58:59]
	v_pk_add_f32 v[38:39], v[38:39], v[58:59] neg_lo:[0,1] neg_hi:[0,1]
	v_pk_fma_f32 v[34:35], v[34:35], s[78:79], v[78:79] op_sel:[0,0,1] op_sel_hi:[1,0,0]
	v_pk_add_f32 v[78:79], v[40:41], v[84:85]
	v_pk_add_f32 v[84:85], v[40:41], v[84:85] neg_lo:[0,1] neg_hi:[0,1]
	v_pk_mul_f32 v[86:87], v[64:65], s[36:37]
	v_pk_mul_f32 v[58:59], v[38:39], s[36:37]
	v_pk_fma_f32 v[64:65], v[64:65], s[78:79], v[86:87] op_sel:[0,0,1] op_sel_hi:[1,0,0] neg_lo:[1,0,0] neg_hi:[1,0,0]
	v_pk_fma_f32 v[38:39], v[38:39], s[78:79], v[58:59] op_sel:[0,0,1] op_sel_hi:[1,0,0]
	v_pk_add_f32 v[58:59], v[42:43], v[60:61]
	v_pk_add_f32 v[86:87], v[44:45], v[62:63]
	v_pk_add_f32 v[44:45], v[44:45], v[62:63] neg_lo:[0,1] neg_hi:[0,1]
	s_nop 0
	v_pk_mul_f32 v[62:63], v[44:45], s[36:37]
	v_pk_add_f32 v[40:41], v[14:15], v[84:85] op_sel:[0,1] op_sel_hi:[1,0] neg_hi:[0,1]
	v_pk_add_f32 v[14:15], v[14:15], v[84:85] op_sel:[0,1] op_sel_hi:[1,0] neg_lo:[0,1]
	v_pk_add_f32 v[84:85], v[34:35], v[64:65]
	v_pk_add_f32 v[64:65], v[34:35], v[64:65] neg_lo:[0,1] neg_hi:[0,1]
	v_pk_add_f32 v[94:95], v[56:57], v[58:59]
	v_pk_add_f32 v[56:57], v[56:57], v[58:59] neg_lo:[0,1] neg_hi:[0,1]
	v_pk_add_f32 v[58:59], v[76:77], v[86:87]
	v_pk_fma_f32 v[44:45], v[44:45], s[78:79], v[62:63] op_sel:[0,0,1] op_sel_hi:[1,0,0] neg_lo:[1,0,0] neg_hi:[1,0,0]
	v_pk_add_f32 v[62:63], v[88:89], v[78:79]
	v_pk_add_f32 v[78:79], v[88:89], v[78:79] neg_lo:[0,1] neg_hi:[0,1]
	v_pk_add_f32 v[88:89], v[66:67], v[90:91]
	v_pk_add_f32 v[110:111], v[76:77], v[86:87] neg_lo:[0,1] neg_hi:[0,1]
	v_pk_add_f32 v[86:87], v[94:95], v[58:59]
	v_pk_add_f32 v[34:35], v[94:95], v[58:59] neg_lo:[0,1] neg_hi:[0,1]
	v_pk_add_f32 v[58:59], v[50:51], v[82:83]
	v_pk_add_f32 v[50:51], v[50:51], v[82:83] neg_lo:[0,1] neg_hi:[0,1]
	v_pk_add_f32 v[60:61], v[42:43], v[60:61] neg_lo:[0,1] neg_hi:[0,1]
	v_pk_add_f32 v[148:149], v[62:63], v[88:89]
	v_pk_add_f32 v[138:139], v[62:63], v[88:89] neg_lo:[0,1] neg_hi:[0,1]
	v_pk_mul_f32 v[62:63], v[50:51], s[18:19]
	v_pk_add_f32 v[90:91], v[66:67], v[90:91] neg_lo:[0,1] neg_hi:[0,1]
	v_pk_fma_f32 v[50:51], v[50:51], s[16:17], v[62:63] op_sel:[0,0,1] op_sel_hi:[1,0,0]
	v_pk_add_f32 v[62:63], v[52:53], v[98:99]
	v_pk_add_f32 v[52:53], v[52:53], v[98:99] neg_lo:[0,1] neg_hi:[0,1]
	v_pk_add_f32 v[112:113], v[22:23], v[60:61] op_sel:[0,1] op_sel_hi:[1,0] neg_hi:[0,1]
	v_pk_add_f32 v[114:115], v[22:23], v[60:61] op_sel:[0,1] op_sel_hi:[1,0] neg_lo:[0,1]
	v_pk_add_f32 v[96:97], v[40:41], v[84:85]
	v_pk_add_f32 v[66:67], v[40:41], v[84:85] neg_lo:[0,1] neg_hi:[0,1]
	v_pk_add_f32 v[60:61], v[14:15], v[64:65] op_sel:[0,1] op_sel_hi:[1,0] neg_hi:[0,1]
	v_pk_add_f32 v[84:85], v[14:15], v[64:65] op_sel:[0,1] op_sel_hi:[1,0] neg_lo:[0,1]
	v_pk_mul_f32 v[64:65], v[52:53], s[36:37]
	s_nop 0
	v_pk_fma_f32 v[52:53], v[52:53], s[78:79], v[64:65] op_sel:[0,0,1] op_sel_hi:[1,0,0]
	v_pk_add_f32 v[64:65], v[54:55], v[100:101]
	v_pk_add_f32 v[54:55], v[54:55], v[100:101] neg_lo:[0,1] neg_hi:[0,1]
	s_nop 0
	v_pk_mul_f32 v[76:77], v[54:55], s[40:41]
	v_pk_add_f32 v[92:93], v[78:79], v[90:91] op_sel:[0,1] op_sel_hi:[1,0] neg_hi:[0,1]
	v_pk_fma_f32 v[54:55], v[54:55], s[80:81], v[76:77] op_sel:[0,0,1] op_sel_hi:[1,0,0]
	s_waitcnt lgkmcnt(1)
	v_pk_add_f32 v[76:77], v[68:69], v[102:103]
	v_pk_add_f32 v[88:89], v[78:79], v[90:91] op_sel:[0,1] op_sel_hi:[1,0] neg_lo:[0,1]
	v_pk_add_f32 v[78:79], v[68:69], v[102:103] neg_lo:[0,1] neg_hi:[0,1]
	v_pk_add_f32 v[68:69], v[70:71], v[104:105]
	v_pk_add_f32 v[70:71], v[70:71], v[104:105] neg_lo:[0,1] neg_hi:[0,1]
	v_pk_add_f32 v[22:23], v[38:39], v[44:45]
	v_pk_add_f32 v[116:117], v[38:39], v[44:45] neg_lo:[0,1] neg_hi:[0,1]
	v_pk_add_f32 v[40:41], v[56:57], v[110:111] op_sel:[0,1] op_sel_hi:[1,0] neg_hi:[0,1]
	v_pk_add_f32 v[44:45], v[56:57], v[110:111] op_sel:[0,1] op_sel_hi:[1,0] neg_lo:[0,1]
	v_pk_add_f32 v[56:57], v[48:49], v[80:81]
	v_pk_add_f32 v[48:49], v[48:49], v[80:81] neg_lo:[0,1] neg_hi:[0,1]
	v_pk_mul_f32 v[80:81], v[70:71], s[40:41]
	v_cvt_f32_u32_e32 v18, v18
	v_pk_fma_f32 v[70:71], v[70:71], s[80:81], v[80:81] op_sel:[0,0,1] op_sel_hi:[1,0,0] neg_lo:[1,0,0] neg_hi:[1,0,0]
	s_waitcnt lgkmcnt(0)
	v_pk_add_f32 v[80:81], v[72:73], v[106:107]
	v_pk_add_f32 v[72:73], v[72:73], v[106:107] neg_lo:[0,1] neg_hi:[0,1]
	v_mul_f32_e32 v18, 0x38000000, v18
	v_pk_mul_f32 v[82:83], v[72:73], s[36:37]
	v_cndmask_b32_e64 v18, v18, v208, s[0:1]
	v_pk_fma_f32 v[72:73], v[72:73], s[78:79], v[82:83] op_sel:[0,0,1] op_sel_hi:[1,0,0] neg_lo:[1,0,0] neg_hi:[1,0,0]
	v_pk_add_f32 v[82:83], v[74:75], v[108:109]
	v_pk_add_f32 v[74:75], v[74:75], v[108:109] neg_lo:[0,1] neg_hi:[0,1]
	s_nop 0
	v_pk_mul_f32 v[90:91], v[74:75], s[18:19]
	s_nop 0
	v_pk_fma_f32 v[74:75], v[74:75], s[16:17], v[90:91] op_sel:[0,0,1] op_sel_hi:[1,0,0] neg_lo:[1,0,0] neg_hi:[1,0,0]
	v_pk_add_f32 v[90:91], v[56:57], v[76:77]
	v_pk_add_f32 v[56:57], v[56:57], v[76:77] neg_lo:[0,1] neg_hi:[0,1]
	v_pk_add_f32 v[76:77], v[58:59], v[68:69]
	v_pk_add_f32 v[58:59], v[58:59], v[68:69] neg_lo:[0,1] neg_hi:[0,1]
	v_pk_add_f32 v[14:15], v[114:115], v[116:117] op_sel:[0,1] op_sel_hi:[1,0] neg_hi:[0,1]
	v_pk_mul_f32 v[68:69], v[58:59], s[36:37]
	v_pk_add_f32 v[38:39], v[114:115], v[116:117] op_sel:[0,1] op_sel_hi:[1,0] neg_lo:[0,1]
	v_pk_fma_f32 v[58:59], v[58:59], s[78:79], v[68:69] op_sel:[0,0,1] op_sel_hi:[1,0,0]
	v_pk_add_f32 v[68:69], v[62:63], v[80:81]
	v_pk_add_f32 v[80:81], v[62:63], v[80:81] neg_lo:[0,1] neg_hi:[0,1]
	s_waitcnt vmcnt(0)
	v_cvt_f32_f16_e32 v193, v33
	s_nop 0
	s_nop 0
	v_pk_add_f32 v[62:63], v[64:65], v[82:83]
	v_pk_add_f32 v[64:65], v[64:65], v[82:83] neg_lo:[0,1] neg_hi:[0,1]
	v_cvt_f32_f16_sdwa v192, v32 dst_sel:DWORD dst_unused:UNUSED_PAD src0_sel:WORD_1
	v_pk_mul_f32 v[82:83], v[64:65], s[36:37]
	v_cvt_f32_f16_e32 v194, v32
	v_pk_fma_f32 v[64:65], v[64:65], s[78:79], v[82:83] op_sel:[0,0,1] op_sel_hi:[1,0,0] neg_lo:[1,0,0] neg_hi:[1,0,0]
	v_pk_add_f32 v[82:83], v[48:49], v[78:79] op_sel:[0,1] op_sel_hi:[1,0] neg_hi:[0,1]
	v_pk_add_f32 v[48:49], v[48:49], v[78:79] op_sel:[0,1] op_sel_hi:[1,0] neg_lo:[0,1]
	v_pk_add_f32 v[78:79], v[50:51], v[70:71]
	v_pk_add_f32 v[50:51], v[50:51], v[70:71] neg_lo:[0,1] neg_hi:[0,1]
	v_cvt_f32_f16_sdwa v195, v33 dst_sel:DWORD dst_unused:UNUSED_PAD src0_sel:WORD_1
	v_pk_mul_f32 v[70:71], v[50:51], s[36:37]
	v_cvt_f32_f16_sdwa v170, v30 dst_sel:DWORD dst_unused:UNUSED_PAD src0_sel:WORD_1
	v_pk_fma_f32 v[50:51], v[50:51], s[78:79], v[70:71] op_sel:[0,0,1] op_sel_hi:[1,0,0]
	v_pk_add_f32 v[70:71], v[52:53], v[72:73]
	v_pk_add_f32 v[72:73], v[52:53], v[72:73] neg_lo:[0,1] neg_hi:[0,1]
	v_cvt_f32_f16_e32 v171, v31
	s_nop 0
	s_nop 0
	v_pk_add_f32 v[52:53], v[54:55], v[74:75]
	v_pk_add_f32 v[54:55], v[54:55], v[74:75] neg_lo:[0,1] neg_hi:[0,1]
	v_cvt_f32_f16_sdwa v185, v31 dst_sel:DWORD dst_unused:UNUSED_PAD src0_sel:WORD_1
	v_pk_mul_f32 v[74:75], v[54:55], s[36:37]
	v_cvt_f32_f16_e32 v184, v30
	v_pk_fma_f32 v[54:55], v[54:55], s[78:79], v[74:75] op_sel:[0,0,1] op_sel_hi:[1,0,0] neg_lo:[1,0,0] neg_hi:[1,0,0]
	v_pk_add_f32 v[74:75], v[90:91], v[68:69]
	v_pk_add_f32 v[68:69], v[90:91], v[68:69] neg_lo:[0,1] neg_hi:[0,1]
	v_pk_add_f32 v[90:91], v[76:77], v[62:63]
	v_pk_add_f32 v[62:63], v[76:77], v[62:63] neg_lo:[0,1] neg_hi:[0,1]
	v_cvt_f32_f16_sdwa v172, v28 dst_sel:DWORD dst_unused:UNUSED_PAD src0_sel:WORD_1
	v_pk_mul_f32 v[76:77], v[62:63], 1.0 op_sel:[1,0] op_sel_hi:[0,0] neg_hi:[1,0]
	s_nop 0
	v_pk_add_f32 v[62:63], v[56:57], v[80:81] op_sel:[0,1] op_sel_hi:[1,0] neg_hi:[0,1]
	v_pk_add_f32 v[56:57], v[56:57], v[80:81] op_sel:[0,1] op_sel_hi:[1,0] neg_lo:[0,1]
	v_pk_add_f32 v[80:81], v[58:59], v[64:65]
	v_pk_add_f32 v[58:59], v[58:59], v[64:65] neg_lo:[0,1] neg_hi:[0,1]
	v_cvt_f32_f16_e32 v173, v29
	v_pk_mul_f32 v[64:65], v[58:59], 1.0 op_sel:[1,0] op_sel_hi:[0,0] neg_hi:[1,0]
	v_pk_add_f32 v[58:59], v[82:83], v[70:71]
	v_pk_add_f32 v[70:71], v[82:83], v[70:71] neg_lo:[0,1] neg_hi:[0,1]
	v_pk_add_f32 v[82:83], v[78:79], v[52:53]
	v_pk_add_f32 v[52:53], v[78:79], v[52:53] neg_lo:[0,1] neg_hi:[0,1]
	v_pk_add_f32 v[118:119], v[58:59], v[82:83]
	v_pk_add_f32 v[134:135], v[58:59], v[82:83] neg_lo:[0,1] neg_hi:[0,1]
	v_cos_f32_e32 v83, v18
	v_sin_f32_e32 v82, v18
	v_cvt_f32_f16_sdwa v181, v29 dst_sel:DWORD dst_unused:UNUSED_PAD src0_sel:WORD_1
	v_cvt_f32_f16_e32 v180, v28
	v_cvt_f32_f16_sdwa v167, v13 dst_sel:DWORD dst_unused:UNUSED_PAD src0_sel:WORD_1
	v_cvt_f32_f16_e32 v166, v12
	v_cvt_f32_f16_e32 v154, v6
	v_cvt_f32_f16_e32 v155, v7
	v_cvt_f32_f16_sdwa v157, v7 dst_sel:DWORD dst_unused:UNUSED_PAD src0_sel:WORD_1
	v_cvt_f32_f16_sdwa v156, v6 dst_sel:DWORD dst_unused:UNUSED_PAD src0_sel:WORD_1
	v_cvt_f32_f16_sdwa v140, v4 dst_sel:DWORD dst_unused:UNUSED_PAD src0_sel:WORD_1
	v_cvt_f32_f16_e32 v141, v5
	v_cvt_f32_f16_sdwa v143, v5 dst_sel:DWORD dst_unused:UNUSED_PAD src0_sel:WORD_1
	v_cvt_f32_f16_e32 v142, v4
	v_cvt_f32_f16_e32 v124, v16
	v_cvt_f32_f16_e32 v125, v17
	v_cvt_f32_f16_sdwa v127, v17 dst_sel:DWORD dst_unused:UNUSED_PAD src0_sel:WORD_1
	v_cvt_f32_f16_sdwa v126, v16 dst_sel:DWORD dst_unused:UNUSED_PAD src0_sel:WORD_1
	v_cvt_f32_f16_sdwa v114, v122 dst_sel:DWORD dst_unused:UNUSED_PAD src0_sel:WORD_1
	v_cvt_f32_f16_e32 v115, v123
	v_cvt_f32_f16_sdwa v117, v123 dst_sel:DWORD dst_unused:UNUSED_PAD src0_sel:WORD_1
	v_cvt_f32_f16_e32 v116, v122
	v_pk_mul_f32 v[78:79], v[52:53], 1.0 op_sel:[1,0] op_sel_hi:[0,0] neg_hi:[1,0]
	s_nop 0
	v_pk_add_f32 v[52:53], v[48:49], v[72:73] op_sel:[0,1] op_sel_hi:[1,0] neg_hi:[0,1]
	v_pk_add_f32 v[48:49], v[48:49], v[72:73] op_sel:[0,1] op_sel_hi:[1,0] neg_lo:[0,1]
	v_pk_add_f32 v[72:73], v[50:51], v[54:55]
	v_pk_add_f32 v[50:51], v[50:51], v[54:55] neg_lo:[0,1] neg_hi:[0,1]
	v_pk_fma_f32 v[160:161], v[82:83], 0, v[82:83] op_sel:[0,0,1] op_sel_hi:[1,0,0] neg_lo:[1,0,0] neg_hi:[1,0,0]
	v_pk_mul_f32 v[54:55], v[50:51], 1.0 op_sel:[1,0] op_sel_hi:[0,0] neg_hi:[1,0]
	v_pk_fma_f32 v[198:199], v[82:83], 0, v[82:83] op_sel:[0,0,1] op_sel_hi:[1,0,0]
	v_pk_add_f32 v[42:43], v[112:113], v[22:23]
	v_pk_add_f32 v[22:23], v[112:113], v[22:23] neg_lo:[0,1] neg_hi:[0,1]
	v_pk_add_f32 v[98:99], v[74:75], v[90:91]
	v_pk_add_f32 v[100:101], v[74:75], v[90:91] neg_lo:[0,1] neg_hi:[0,1]
	v_pk_add_f32 v[102:103], v[68:69], v[76:77]
	v_pk_add_f32 v[106:107], v[68:69], v[76:77] neg_lo:[0,1] neg_hi:[0,1]
	v_pk_add_f32 v[104:105], v[62:63], v[80:81]
	v_pk_add_f32 v[108:109], v[62:63], v[80:81] neg_lo:[0,1] neg_hi:[0,1]
	v_pk_add_f32 v[110:111], v[56:57], v[64:65]
	v_pk_add_f32 v[112:113], v[56:57], v[64:65] neg_lo:[0,1] neg_hi:[0,1]
	v_pk_add_f32 v[152:153], v[70:71], v[78:79]
	v_pk_add_f32 v[162:163], v[70:71], v[78:79] neg_lo:[0,1] neg_hi:[0,1]
	v_pk_add_f32 v[178:179], v[52:53], v[72:73]
	v_pk_add_f32 v[182:183], v[52:53], v[72:73] neg_lo:[0,1] neg_hi:[0,1]
	v_pk_add_f32 v[188:189], v[48:49], v[54:55]
	v_pk_add_f32 v[196:197], v[48:49], v[54:55] neg_lo:[0,1] neg_hi:[0,1]
	v_pk_mul_f32 v[186:187], v[82:83], 0 op_sel_hi:[1,0]
	v_mov_b32_e32 v190, v160
	v_mov_b32_e32 v191, v199
	v_mul_f32_e32 v18, 0x3f3504f3, v83
	v_mul_f32_e32 v158, 0xbec3ef15, v83
	v_mul_f32_e32 v132, 0xbf6c835e, v83
	s_and_saveexec_b64 s[0:1], vcc
	s_xor_b64 s[0:1], exec, s[0:1]
	s_cbranch_execz .LBB0_501
	v_pk_add_f32 v[4:5], v[148:149], v[196:197]
	v_pk_add_f32 v[6:7], v[148:149], v[196:197] neg_lo:[0,1] neg_hi:[0,1]
	v_mul_f32_e32 v4, 0.5, v4
	v_mul_f32_e32 v12, 0.5, v7
	v_mov_b32_e32 v7, v5
	v_pk_mul_f32 v[6:7], v[6:7], s[44:45]
	v_pk_mov_b32 v[16:17], v[198:199], v[160:161] op_sel:[1,0]
	v_pk_mul_f32 v[24:25], v[190:191], v[6:7] op_sel:[0,1] op_sel_hi:[1,0]
	v_pk_mul_f32 v[6:7], v[190:191], v[6:7]
	v_pk_add_f32 v[24:25], v[24:25], v[24:25] op_sel:[0,1] op_sel_hi:[0,1]
	v_pk_add_f32 v[28:29], v[4:5], v[24:25] op_sel_hi:[0,1] neg_hi:[0,1]
	v_pk_add_f32 v[4:5], v[6:7], v[6:7] op_sel:[0,1] op_sel_hi:[0,1] neg_lo:[0,1] neg_hi:[0,1]
	v_pk_add_f32 v[6:7], v[12:13], v[4:5] op_sel_hi:[0,1] neg_hi:[0,1]
	v_pk_mul_f32 v[4:5], v[6:7], v[194:195]
	v_pk_mul_f32 v[6:7], v[6:7], v[192:193]
	v_pk_fma_f32 v[4:5], v[28:29], v[192:193], v[4:5]
	v_pk_fma_f32 v[6:7], v[28:29], v[194:195], v[6:7] neg_lo:[0,0,1] neg_hi:[0,0,1]
	s_mov_b32 s78, s19
	v_pk_add_f32 v[12:13], v[6:7], v[4:5] op_sel:[0,1] op_sel_hi:[1,0] neg_lo:[0,1]
	v_pk_add_f32 v[28:29], v[6:7], v[4:5] op_sel:[0,1] op_sel_hi:[1,0]
	v_pk_add_f32 v[4:5], v[4:5], v[6:7] op_sel:[1,0] op_sel_hi:[0,1] neg_lo:[0,1] neg_hi:[0,1]
	s_nop 0
	v_pk_mul_f32 v[12:13], v[12:13], 0.5 op_sel_hi:[1,0]
	v_mov_b32_e32 v29, v5
	v_mul_f32_e32 v24, v190, v12
	v_pk_fma_f32 v[30:31], v[190:191], v[12:13], v[24:25] op_sel_hi:[1,1,0] neg_lo:[1,0,0] neg_hi:[1,0,0]
	v_mul_f32_e32 v24, v160, v13
	v_pk_fma_f32 v[12:13], v[16:17], v[12:13], v[24:25] op_sel_hi:[1,1,0]
	v_mov_b32_e32 v16, v83
	v_mov_b32_e32 v30, v12
	v_pk_fma_f32 v[4:5], v[28:29], 0.5, v[12:13] op_sel_hi:[1,0,1] neg_lo:[0,0,1] neg_hi:[0,0,1]
	v_pk_fma_f32 v[122:123], v[28:29], 0.5, v[30:31] op_sel_hi:[1,0,1]
	v_pk_fma_f32 v[6:7], v[28:29], 0.5, v[30:31] op_sel_hi:[1,0,1] neg_lo:[1,0,0] neg_hi:[1,0,0]
	v_mov_b32_e32 v5, v123
	v_pk_mul_f32 v[24:25], v[4:5], s[6:7] op_sel_hi:[1,0]
	v_pk_add_f32 v[4:5], v[138:139], v[188:189]
	v_pk_add_f32 v[12:13], v[138:139], v[188:189] neg_lo:[0,1] neg_hi:[0,1]
	v_mov_b32_e32 v17, v82
	v_mul_f32_e32 v6, 0.5, v13
	v_pk_add_f32 v[28:29], v[186:187], v[16:17] neg_lo:[0,1] neg_hi:[0,1]
	v_pk_add_f32 v[30:31], v[186:187], v[16:17]
	v_mov_b32_e32 v13, v5
	v_pk_mov_b32 v[32:33], v[28:29], v[30:31] op_sel:[1,0]
	v_pk_mul_f32 v[12:13], v[12:13], s[44:45]
	v_mul_f32_e32 v4, 0.5, v4
	v_pk_mul_f32 v[48:49], v[32:33], v[12:13] op_sel:[0,1] op_sel_hi:[1,0]
	v_pk_mul_f32 v[12:13], v[32:33], v[12:13]
	v_pk_add_f32 v[48:49], v[48:49], v[48:49] op_sel:[0,1] op_sel_hi:[0,1]
	v_pk_add_f32 v[50:51], v[4:5], v[48:49] op_sel_hi:[0,1] neg_hi:[0,1]
	v_pk_add_f32 v[4:5], v[12:13], v[12:13] op_sel:[0,1] op_sel_hi:[0,1] neg_lo:[0,1] neg_hi:[0,1]
	v_pk_add_f32 v[12:13], v[6:7], v[4:5] op_sel_hi:[0,1] neg_hi:[0,1]
	v_pk_mul_f32 v[4:5], v[12:13], v[184:185]
	v_pk_mul_f32 v[12:13], v[12:13], v[170:171]
	v_pk_fma_f32 v[4:5], v[50:51], v[170:171], v[4:5]
	v_pk_fma_f32 v[12:13], v[50:51], v[184:185], v[12:13] neg_lo:[0,0,1] neg_hi:[0,0,1]
	v_mov_b32_e32 v31, v29
	v_pk_add_f32 v[48:49], v[12:13], v[4:5] op_sel:[0,1] op_sel_hi:[1,0] neg_lo:[0,1]
	v_pk_add_f32 v[50:51], v[12:13], v[4:5] op_sel:[0,1] op_sel_hi:[1,0]
	v_pk_add_f32 v[4:5], v[4:5], v[12:13] op_sel:[1,0] op_sel_hi:[0,1] neg_lo:[0,1] neg_hi:[0,1]
	v_pk_mul_f32 v[48:49], v[48:49], 0.5 op_sel_hi:[1,0]
	v_mov_b32_e32 v51, v5
	v_mul_f32_e32 v6, v29, v48
	v_pk_fma_f32 v[32:33], v[32:33], v[48:49], v[6:7] op_sel_hi:[1,1,0] neg_lo:[1,0,0] neg_hi:[1,0,0]
	v_mul_f32_e32 v6, v29, v49
	v_pk_fma_f32 v[28:29], v[30:31], v[48:49], v[6:7] op_sel_hi:[1,1,0]
	v_pk_mul_f32 v[12:13], v[16:17], s[36:37]
	v_mov_b32_e32 v32, v28
	v_pk_fma_f32 v[4:5], v[50:51], 0.5, v[28:29] op_sel_hi:[1,0,1] neg_lo:[0,0,1] neg_hi:[0,0,1]
	v_pk_fma_f32 v[138:139], v[50:51], 0.5, v[32:33] op_sel_hi:[1,0,1]
	v_pk_add_f32 v[16:17], v[92:93], v[182:183]
	v_mov_b32_e32 v5, v139
	v_pk_add_f32 v[28:29], v[92:93], v[182:183] neg_lo:[0,1] neg_hi:[0,1]
	v_pk_mul_f32 v[30:31], v[4:5], s[6:7] op_sel_hi:[1,0]
	v_pk_fma_f32 v[4:5], v[50:51], 0.5, v[32:33] op_sel_hi:[1,0,1] neg_lo:[1,0,0] neg_hi:[1,0,0]
	v_mul_f32_e32 v6, 0.5, v29
	v_pk_add_f32 v[32:33], v[18:19], v[12:13] op_sel:[0,1] op_sel_hi:[0,1] neg_lo:[0,1] neg_hi:[0,1]
	v_pk_add_f32 v[48:49], v[18:19], v[12:13] op_sel:[0,1] op_sel_hi:[0,1]
	v_mov_b32_e32 v29, v17
	v_mul_f32_e32 v4, 0.5, v16
	v_mov_b32_e32 v50, v32
	v_mov_b32_e32 v51, v49
	v_pk_mul_f32 v[16:17], v[28:29], s[44:45]
	v_pk_mov_b32 v[48:49], v[48:49], v[32:33] op_sel:[1,0]
	v_pk_mul_f32 v[28:29], v[50:51], v[16:17] op_sel:[0,1] op_sel_hi:[1,0]
	v_pk_mul_f32 v[16:17], v[50:51], v[16:17]
	v_pk_add_f32 v[28:29], v[28:29], v[28:29] op_sel:[0,1] op_sel_hi:[0,1]
	v_pk_add_f32 v[52:53], v[4:5], v[28:29] op_sel_hi:[0,1] neg_hi:[0,1]
	v_pk_add_f32 v[16:17], v[16:17], v[16:17] op_sel:[0,1] op_sel_hi:[0,1] neg_lo:[0,1] neg_hi:[0,1]
	v_pk_add_f32 v[28:29], v[6:7], v[16:17] op_sel_hi:[0,1] neg_hi:[0,1]
	v_pk_mul_f32 v[16:17], v[28:29], v[180:181]
	v_pk_mul_f32 v[28:29], v[28:29], v[172:173]
	v_pk_fma_f32 v[16:17], v[52:53], v[172:173], v[16:17]
	v_pk_fma_f32 v[28:29], v[52:53], v[180:181], v[28:29] neg_lo:[0,0,1] neg_hi:[0,0,1]
	v_sub_f32_e32 v6, v89, v179
	v_pk_add_f32 v[52:53], v[28:29], v[16:17] op_sel:[0,1] op_sel_hi:[1,0] neg_lo:[0,1]
	v_pk_add_f32 v[54:55], v[28:29], v[16:17] op_sel:[0,1] op_sel_hi:[1,0]
	v_pk_add_f32 v[16:17], v[16:17], v[28:29] op_sel:[1,0] op_sel_hi:[0,1] neg_lo:[0,1] neg_hi:[0,1]
	v_pk_mul_f32 v[52:53], v[52:53], 0.5 op_sel_hi:[1,0]
	v_mov_b32_e32 v55, v17
	v_mul_f32_e32 v4, v32, v52
	v_pk_fma_f32 v[56:57], v[50:51], v[52:53], v[4:5] op_sel_hi:[1,1,0] neg_lo:[1,0,0] neg_hi:[1,0,0]
	v_mul_f32_e32 v4, v32, v53
	v_pk_fma_f32 v[48:49], v[48:49], v[52:53], v[4:5] op_sel_hi:[1,1,0]
	v_pk_add_f32 v[28:29], v[88:89], v[178:179]
	v_mov_b32_e32 v56, v48
	v_pk_fma_f32 v[16:17], v[54:55], 0.5, v[48:49] op_sel_hi:[1,0,1] neg_lo:[0,0,1] neg_hi:[0,0,1]
	v_mov_b32_e32 v48, v12
	v_mov_b32_e32 v49, v88
	v_pk_mov_b32 v[12:13], v[12:13], v[178:179] op_sel:[1,0]
	v_mul_f32_e32 v18, 0.5, v29
	v_pk_add_f32 v[12:13], v[48:49], v[12:13] neg_lo:[0,1] neg_hi:[0,1]
	v_mul_f32_e32 v4, 0.5, v28
	v_pk_mul_f32 v[48:49], v[12:13], v[18:19]
	v_mov_b32_e32 v13, v32
	v_pk_fma_f32 v[50:51], v[50:51], v[48:49], v[48:49] op_sel:[0,1,0] op_sel_hi:[1,0,1]
	v_mov_b32_e32 v48, v49
	v_mov_b32_e32 v49, v18
	v_pk_mul_f32 v[48:49], v[12:13], v[48:49]
	v_pk_add_f32 v[52:53], v[4:5], v[50:51]
	v_mul_f32_e32 v6, 0.5, v6
	v_fma_f32 v53, v28, 0.5, -v50
	v_pk_add_f32 v[28:29], v[48:49], v[48:49] op_sel:[0,1] op_sel_hi:[0,1] neg_lo:[0,1] neg_hi:[0,1]
	v_pk_add_f32 v[48:49], v[6:7], v[28:29] op_sel_hi:[0,1] neg_hi:[0,1]
	v_pk_mul_f32 v[28:29], v[48:49], v[176:177]
	v_pk_mul_f32 v[48:49], v[48:49], v[174:175]
	v_pk_fma_f32 v[28:29], v[52:53], v[174:175], v[28:29]
	v_pk_fma_f32 v[48:49], v[52:53], v[176:177], v[48:49] neg_lo:[0,0,1] neg_hi:[0,0,1]
	v_pk_fma_f32 v[92:93], v[54:55], 0.5, v[56:57] op_sel_hi:[1,0,1]
	v_pk_add_f32 v[50:51], v[48:49], v[28:29] op_sel:[0,1] op_sel_hi:[1,0] neg_lo:[0,1]
	v_pk_add_f32 v[52:53], v[48:49], v[28:29] op_sel:[0,1] op_sel_hi:[1,0]
	v_mov_b32_e32 v17, v93
	v_pk_mul_f32 v[50:51], v[50:51], 0.5 op_sel_hi:[1,0]
	v_pk_mul_f32 v[64:65], v[16:17], s[6:7] op_sel_hi:[1,0]
	v_mul_f32_e32 v4, v12, v50
	v_pk_fma_f32 v[16:17], v[54:55], 0.5, v[56:57] op_sel_hi:[1,0,1] neg_lo:[1,0,0] neg_hi:[1,0,0]
	v_pk_fma_f32 v[54:55], v[12:13], v[50:51], v[4:5] op_sel_hi:[1,1,0] neg_lo:[1,0,0] neg_hi:[1,0,0]
	v_mov_b32_e32 v33, v12
	v_mul_f32_e32 v4, v12, v51
	v_pk_fma_f32 v[12:13], v[32:33], v[50:51], v[4:5] op_sel_hi:[1,1,0]
	v_pk_add_f32 v[28:29], v[28:29], v[48:49] op_sel:[1,0] op_sel_hi:[0,1] neg_lo:[0,1] neg_hi:[0,1]
	v_mov_b32_e32 v53, v29
	v_mov_b32_e32 v54, v12
	v_pk_fma_f32 v[12:13], v[52:53], 0.5, v[12:13] op_sel_hi:[1,0,1] neg_lo:[0,0,1] neg_hi:[0,0,1]
	v_pk_fma_f32 v[88:89], v[52:53], 0.5, v[54:55] op_sel_hi:[1,0,1]
	s_mov_b32 s79, s16
	v_mov_b32_e32 v13, v89
	v_pk_mul_f32 v[68:69], v[12:13], s[6:7] op_sel_hi:[1,0]
	v_pk_fma_f32 v[12:13], v[52:53], 0.5, v[54:55] op_sel_hi:[1,0,1] neg_lo:[1,0,0] neg_hi:[1,0,0]
	v_mov_b32_e32 v4, v83
	s_mov_b32 s17, s19
	v_pk_mul_f32 v[48:49], v[82:83], s[78:79] op_sel_hi:[0,1]
	v_pk_add_f32 v[28:29], v[96:97], v[162:163]
	v_pk_add_f32 v[32:33], v[96:97], v[162:163] neg_lo:[0,1] neg_hi:[0,1]
	v_pk_fma_f32 v[52:53], v[4:5], s[16:17], v[48:49] op_sel_hi:[0,1,1] neg_lo:[0,0,1] neg_hi:[0,0,1]
	v_mul_f32_e32 v12, 0.5, v33
	v_pk_fma_f32 v[50:51], v[4:5], s[16:17], v[48:49] op_sel_hi:[0,1,1]
	v_mov_b32_e32 v33, v29
	v_mul_f32_e32 v6, 0.5, v28
	v_mov_b32_e32 v54, v52
	v_mov_b32_e32 v55, v51
	v_pk_mul_f32 v[28:29], v[32:33], s[44:45]
	v_pk_mov_b32 v[56:57], v[50:51], v[52:53] op_sel:[1,0]
	v_pk_mul_f32 v[32:33], v[54:55], v[28:29] op_sel:[0,1] op_sel_hi:[1,0]
	v_pk_mul_f32 v[28:29], v[54:55], v[28:29]
	v_pk_add_f32 v[32:33], v[32:33], v[32:33] op_sel:[0,1] op_sel_hi:[0,1]
	v_pk_add_f32 v[58:59], v[6:7], v[32:33] op_sel_hi:[0,1] neg_hi:[0,1]
	v_pk_add_f32 v[28:29], v[28:29], v[28:29] op_sel:[0,1] op_sel_hi:[0,1] neg_lo:[0,1] neg_hi:[0,1]
	v_pk_add_f32 v[32:33], v[12:13], v[28:29] op_sel_hi:[0,1] neg_hi:[0,1]
	v_pk_mul_f32 v[28:29], v[32:33], v[166:167]
	v_pk_mul_f32 v[32:33], v[32:33], v[164:165]
	v_pk_fma_f32 v[28:29], v[58:59], v[164:165], v[28:29]
	v_pk_fma_f32 v[32:33], v[58:59], v[166:167], v[32:33] neg_lo:[0,0,1] neg_hi:[0,0,1]
	v_mov_b32_e32 v159, v66
	v_pk_add_f32 v[58:59], v[32:33], v[28:29] op_sel:[0,1] op_sel_hi:[1,0] neg_lo:[0,1]
	v_pk_add_f32 v[70:71], v[32:33], v[28:29] op_sel:[0,1] op_sel_hi:[1,0]
	v_pk_add_f32 v[28:29], v[28:29], v[32:33] op_sel:[1,0] op_sel_hi:[0,1] neg_lo:[0,1] neg_hi:[0,1]
	v_pk_mul_f32 v[58:59], v[58:59], 0.5 op_sel_hi:[1,0]
	v_mov_b32_e32 v71, v29
	v_mul_f32_e32 v6, v52, v58
	v_pk_fma_f32 v[72:73], v[54:55], v[58:59], v[6:7] op_sel_hi:[1,1,0] neg_lo:[1,0,0] neg_hi:[1,0,0]
	v_mul_f32_e32 v6, v52, v59
	v_pk_fma_f32 v[56:57], v[56:57], v[58:59], v[6:7] op_sel_hi:[1,1,0]
	v_sub_f32_e32 v12, v67, v153
	v_mov_b32_e32 v72, v56
	v_pk_fma_f32 v[28:29], v[70:71], 0.5, v[56:57] op_sel_hi:[1,0,1] neg_lo:[0,0,1] neg_hi:[0,0,1]
	v_pk_fma_f32 v[96:97], v[70:71], 0.5, v[72:73] op_sel_hi:[1,0,1]
	v_pk_mov_b32 v[56:57], v[48:49], v[152:153] op_sel:[1,0]
	v_mov_b32_e32 v29, v97
	v_pk_mul_f32 v[62:63], v[28:29], s[6:7] op_sel_hi:[1,0]
	v_pk_add_f32 v[28:29], v[66:67], v[152:153]
	v_pk_add_f32 v[56:57], v[158:159], v[56:57] neg_lo:[0,1] neg_hi:[0,1]
	v_mul_f32_e32 v18, 0.5, v29
	v_pk_mul_f32 v[58:59], v[56:57], v[18:19]
	v_mul_f32_e32 v6, 0.5, v28
	v_pk_fma_f32 v[54:55], v[54:55], v[58:59], v[58:59] op_sel:[0,1,0] op_sel_hi:[1,0,1]
	v_mov_b32_e32 v66, v56
	v_mov_b32_e32 v67, v52
	v_mov_b32_e32 v58, v59
	v_mov_b32_e32 v59, v18
	v_pk_mul_f32 v[58:59], v[66:67], v[58:59]
	v_pk_add_f32 v[66:67], v[6:7], v[54:55]
	v_mul_f32_e32 v12, 0.5, v12
	v_fma_f32 v67, v28, 0.5, -v54
	v_pk_add_f32 v[28:29], v[58:59], v[58:59] op_sel:[0,1] op_sel_hi:[0,1] neg_lo:[0,1] neg_hi:[0,1]
	v_pk_add_f32 v[54:55], v[12:13], v[28:29] op_sel_hi:[0,1] neg_hi:[0,1]
	v_pk_mul_f32 v[28:29], v[54:55], v[156:157]
	v_pk_mul_f32 v[54:55], v[54:55], v[154:155]
	v_pk_fma_f32 v[32:33], v[70:71], 0.5, v[72:73] op_sel_hi:[1,0,1] neg_lo:[1,0,0] neg_hi:[1,0,0]
	v_pk_fma_f32 v[58:59], v[66:67], v[154:155], v[28:29] neg_lo:[0,0,1] neg_hi:[0,0,1]
	v_pk_fma_f32 v[28:29], v[66:67], v[154:155], v[28:29]
	v_pk_fma_f32 v[70:71], v[66:67], v[156:157], v[54:55]
	v_pk_fma_f32 v[54:55], v[66:67], v[156:157], v[54:55] neg_lo:[0,0,1] neg_hi:[0,0,1]
	v_pk_add_f32 v[72:73], v[58:59], v[28:29] op_sel:[0,1] op_sel_hi:[1,0]
	v_pk_add_f32 v[66:67], v[70:71], v[54:55] op_sel_hi:[0,1] neg_lo:[0,1] neg_hi:[0,1]
	v_pk_add_f32 v[28:29], v[58:59], v[28:29] op_sel_hi:[0,1] neg_lo:[0,1] neg_hi:[0,1]
	v_pk_add_f32 v[54:55], v[70:71], v[54:55] op_sel:[0,1] op_sel_hi:[1,0]
	v_mov_b32_e32 v73, v67
	v_mov_b32_e32 v55, v29
	v_pk_mul_f32 v[28:29], v[54:55], 0.5 op_sel_hi:[1,0]
	v_mov_b32_e32 v133, v84
	v_pk_mul_f32 v[54:55], v[52:53], v[28:29] op_sel:[0,1] op_sel_hi:[0,0]
	v_pk_fma_f32 v[58:59], v[56:57], v[28:29], v[54:55] op_sel_hi:[0,1,1]
	v_pk_fma_f32 v[28:29], v[56:57], v[28:29], v[54:55] op_sel_hi:[0,1,1] neg_hi:[0,0,1]
	v_pk_fma_f32 v[54:55], v[72:73], 0.5, v[58:59] op_sel_hi:[1,0,1] neg_lo:[0,0,1] neg_hi:[0,0,1]
	v_pk_fma_f32 v[66:67], v[72:73], 0.5, v[28:29] op_sel_hi:[1,0,1]
	v_pk_add_f32 v[56:57], v[60:61], v[134:135] neg_lo:[0,1] neg_hi:[0,1]
	v_mov_b32_e32 v55, v67
	v_pk_mul_f32 v[90:91], v[54:55], s[6:7] op_sel_hi:[1,0]
	v_pk_add_f32 v[54:55], v[134:135], v[60:61]
	v_mul_f32_e32 v12, 0.5, v57
	v_mov_b32_e32 v57, v55
	v_mul_f32_e32 v6, 0.5, v54
	v_pk_mov_b32 v[58:59], v[52:53], v[50:51] op_sel:[1,0]
	v_pk_mul_f32 v[54:55], v[56:57], s[44:45]
	v_pk_fma_f32 v[28:29], v[72:73], 0.5, v[28:29] op_sel_hi:[1,0,1] neg_lo:[1,0,0] neg_hi:[1,0,0]
	v_pk_mul_f32 v[56:57], v[58:59], v[54:55] op_sel:[0,1] op_sel_hi:[1,0]
	v_pk_mul_f32 v[54:55], v[58:59], v[54:55]
	v_pk_add_f32 v[56:57], v[56:57], v[56:57] op_sel:[0,1] op_sel_hi:[0,1]
	v_pk_add_f32 v[60:61], v[6:7], v[56:57] op_sel_hi:[0,1] neg_hi:[0,1]
	v_pk_add_f32 v[54:55], v[54:55], v[54:55] op_sel:[0,1] op_sel_hi:[0,1] neg_lo:[0,1] neg_hi:[0,1]
	v_pk_add_f32 v[56:57], v[12:13], v[54:55] op_sel_hi:[0,1] neg_hi:[0,1]
	v_pk_mul_f32 v[54:55], v[56:57], v[142:143]
	v_pk_mul_f32 v[56:57], v[56:57], v[140:141]
	v_pk_fma_f32 v[54:55], v[60:61], v[140:141], v[54:55]
	v_pk_fma_f32 v[56:57], v[60:61], v[142:143], v[56:57] neg_lo:[0,0,1] neg_hi:[0,0,1]
	v_mov_b32_e32 v51, v53
	v_pk_add_f32 v[60:61], v[56:57], v[54:55] op_sel:[0,1] op_sel_hi:[1,0] neg_lo:[0,1]
	v_pk_add_f32 v[70:71], v[56:57], v[54:55] op_sel:[0,1] op_sel_hi:[1,0]
	v_pk_add_f32 v[54:55], v[54:55], v[56:57] op_sel:[1,0] op_sel_hi:[0,1] neg_lo:[0,1] neg_hi:[0,1]
	v_pk_mul_f32 v[60:61], v[60:61], 0.5 op_sel_hi:[1,0]
	v_mov_b32_e32 v71, v55
	v_mul_f32_e32 v6, v53, v60
	v_pk_fma_f32 v[72:73], v[58:59], v[60:61], v[6:7] op_sel_hi:[1,1,0] neg_lo:[1,0,0] neg_hi:[1,0,0]
	v_mul_f32_e32 v6, v53, v61
	v_pk_fma_f32 v[50:51], v[50:51], v[60:61], v[6:7] op_sel_hi:[1,1,0]
	v_pk_add_f32 v[54:55], v[118:119], v[84:85]
	v_mov_b32_e32 v72, v50
	v_mov_b32_e32 v49, v118
	v_pk_fma_f32 v[50:51], v[70:71], 0.5, v[50:51] op_sel_hi:[1,0,1] neg_lo:[0,0,1] neg_hi:[0,0,1]
	v_pk_fma_f32 v[60:61], v[70:71], 0.5, v[72:73] op_sel_hi:[1,0,1]
	v_mul_f32_e32 v18, 0.5, v55
	v_pk_add_f32 v[48:49], v[132:133], v[48:49] neg_lo:[0,1] neg_hi:[0,1]
	v_mov_b32_e32 v51, v61
	v_pk_mul_f32 v[56:57], v[48:49], v[18:19]
	v_pk_mul_f32 v[94:95], v[50:51], s[6:7] op_sel_hi:[1,0]
	v_pk_fma_f32 v[50:51], v[70:71], 0.5, v[72:73] op_sel_hi:[1,0,1] neg_lo:[1,0,0] neg_hi:[1,0,0]
	v_mul_f32_e32 v6, 0.5, v54
	v_pk_fma_f32 v[58:59], v[58:59], v[56:57], v[56:57] op_sel:[0,1,0] op_sel_hi:[1,0,1]
	v_mov_b32_e32 v70, v48
	v_mov_b32_e32 v71, v53
	v_mov_b32_e32 v56, v57
	v_mov_b32_e32 v57, v18
	v_sub_f32_e32 v12, v85, v119
	v_pk_mul_f32 v[56:57], v[70:71], v[56:57]
	v_pk_add_f32 v[70:71], v[6:7], v[58:59]
	v_mul_f32_e32 v12, 0.5, v12
	v_fma_f32 v71, v54, 0.5, -v58
	v_pk_add_f32 v[54:55], v[56:57], v[56:57] op_sel:[0,1] op_sel_hi:[0,1] neg_lo:[0,1] neg_hi:[0,1]
	v_pk_add_f32 v[56:57], v[12:13], v[54:55] op_sel_hi:[0,1] neg_hi:[0,1]
	v_pk_mul_f32 v[54:55], v[56:57], v[126:127]
	v_pk_mul_f32 v[56:57], v[56:57], v[124:125]
	v_pk_fma_f32 v[58:59], v[70:71], v[124:125], v[54:55] neg_lo:[0,0,1] neg_hi:[0,0,1]
	v_pk_fma_f32 v[54:55], v[70:71], v[124:125], v[54:55]
	v_pk_fma_f32 v[72:73], v[70:71], v[126:127], v[56:57]
	v_pk_fma_f32 v[56:57], v[70:71], v[126:127], v[56:57] neg_lo:[0,0,1] neg_hi:[0,0,1]
	v_pk_add_f32 v[70:71], v[58:59], v[54:55] op_sel:[0,1] op_sel_hi:[1,0]
	v_pk_add_f32 v[74:75], v[72:73], v[56:57] op_sel_hi:[0,1] neg_lo:[0,1] neg_hi:[0,1]
	v_pk_add_f32 v[54:55], v[58:59], v[54:55] op_sel_hi:[0,1] neg_lo:[0,1] neg_hi:[0,1]
	v_pk_add_f32 v[56:57], v[72:73], v[56:57] op_sel:[0,1] op_sel_hi:[1,0]
	v_mov_b32_e32 v71, v75
	v_mov_b32_e32 v57, v55
	v_pk_mul_f32 v[54:55], v[56:57], 0.5 op_sel_hi:[1,0]
	s_mov_b32 s78, s11
	v_pk_mul_f32 v[52:53], v[52:53], v[54:55] op_sel:[1,1] op_sel_hi:[1,0]
	s_mov_b32 s79, s8
	v_pk_fma_f32 v[56:57], v[48:49], v[54:55], v[52:53] op_sel_hi:[0,1,1]
	v_pk_fma_f32 v[48:49], v[48:49], v[54:55], v[52:53] op_sel_hi:[0,1,1] neg_hi:[0,0,1]
	s_nop 0
	v_pk_fma_f32 v[52:53], v[70:71], 0.5, v[56:57] op_sel_hi:[1,0,1] neg_lo:[0,0,1] neg_hi:[0,0,1]
	v_pk_fma_f32 v[84:85], v[70:71], 0.5, v[48:49] op_sel_hi:[1,0,1]
	s_mov_b32 s9, s11
	v_mov_b32_e32 v53, v85
	v_pk_mul_f32 v[80:81], v[52:53], s[6:7] op_sel_hi:[1,0]
	v_pk_mul_f32 v[118:119], v[82:83], s[78:79] op_sel_hi:[0,1]
	v_pk_add_f32 v[52:53], v[86:87], v[112:113]
	v_pk_add_f32 v[54:55], v[86:87], v[112:113] neg_lo:[0,1] neg_hi:[0,1]
	v_pk_fma_f32 v[58:59], v[4:5], s[8:9], v[118:119] op_sel_hi:[0,1,1] neg_lo:[0,0,1] neg_hi:[0,0,1]
	v_mul_f32_e32 v12, 0.5, v55
	v_pk_fma_f32 v[72:73], v[4:5], s[8:9], v[118:119] op_sel_hi:[0,1,1]
	v_mov_b32_e32 v55, v53
	v_mul_f32_e32 v6, 0.5, v52
	v_mov_b32_e32 v56, v58
	v_mov_b32_e32 v57, v73
	v_pk_mul_f32 v[52:53], v[54:55], s[44:45]
	v_pk_fma_f32 v[48:49], v[70:71], 0.5, v[48:49] op_sel_hi:[1,0,1] neg_lo:[1,0,0] neg_hi:[1,0,0]
	v_pk_mul_f32 v[54:55], v[56:57], v[52:53] op_sel:[0,1] op_sel_hi:[1,0]
	v_pk_mul_f32 v[52:53], v[56:57], v[52:53]
	v_pk_add_f32 v[54:55], v[54:55], v[54:55] op_sel:[0,1] op_sel_hi:[0,1]
	v_pk_add_f32 v[74:75], v[6:7], v[54:55] op_sel_hi:[0,1] neg_hi:[0,1]
	v_pk_add_f32 v[52:53], v[52:53], v[52:53] op_sel:[0,1] op_sel_hi:[0,1] neg_lo:[0,1] neg_hi:[0,1]
	v_pk_add_f32 v[54:55], v[12:13], v[52:53] op_sel_hi:[0,1] neg_hi:[0,1]
	v_pk_mul_f32 v[52:53], v[54:55], v[116:117]
	v_pk_mul_f32 v[54:55], v[54:55], v[114:115]
	v_pk_fma_f32 v[52:53], v[74:75], v[114:115], v[52:53]
	v_pk_fma_f32 v[54:55], v[74:75], v[116:117], v[54:55] neg_lo:[0,0,1] neg_hi:[0,0,1]
	v_pk_mov_b32 v[70:71], v[72:73], v[58:59] op_sel:[1,0]
	v_pk_add_f32 v[74:75], v[54:55], v[52:53] op_sel:[0,1] op_sel_hi:[1,0] neg_lo:[0,1]
	v_pk_add_f32 v[76:77], v[54:55], v[52:53] op_sel:[0,1] op_sel_hi:[1,0]
	v_pk_add_f32 v[52:53], v[52:53], v[54:55] op_sel:[1,0] op_sel_hi:[0,1] neg_lo:[0,1] neg_hi:[0,1]
	v_pk_mul_f32 v[74:75], v[74:75], 0.5 op_sel_hi:[1,0]
	v_mov_b32_e32 v77, v53
	v_mul_f32_e32 v6, v58, v74
	v_pk_fma_f32 v[112:113], v[56:57], v[74:75], v[6:7] op_sel_hi:[1,1,0] neg_lo:[1,0,0] neg_hi:[1,0,0]
	v_mul_f32_e32 v6, v58, v75
	v_pk_fma_f32 v[70:71], v[70:71], v[74:75], v[6:7] op_sel_hi:[1,1,0]
	v_pk_add_f32 v[54:55], v[34:35], v[110:111]
	v_mov_b32_e32 v112, v70
	v_pk_fma_f32 v[52:53], v[76:77], 0.5, v[70:71] op_sel_hi:[1,0,1] neg_lo:[0,0,1] neg_hi:[0,0,1]
	v_pk_fma_f32 v[86:87], v[76:77], 0.5, v[112:113] op_sel_hi:[1,0,1]
	v_sub_f32_e32 v12, v35, v111
	v_mov_b32_e32 v53, v87
	v_pk_mul_f32 v[78:79], v[52:53], s[6:7] op_sel_hi:[1,0]
	v_mul_f32_e32 v52, 0xbe47c5c2, v83
	v_mov_b32_e32 v53, v34
	v_pk_mov_b32 v[34:35], v[118:119], v[110:111] op_sel:[1,0]
	v_mul_f32_e32 v18, 0.5, v55
	v_pk_add_f32 v[34:35], v[52:53], v[34:35] neg_lo:[0,1] neg_hi:[0,1]
	v_mov_b32_e32 v71, v58
	v_pk_mul_f32 v[52:53], v[34:35], v[18:19]
	v_mov_b32_e32 v70, v34
	v_pk_fma_f32 v[56:57], v[56:57], v[52:53], v[52:53] op_sel:[0,1,0] op_sel_hi:[1,0,1]
	v_mov_b32_e32 v52, v53
	v_mov_b32_e32 v53, v18
	v_mul_f32_e32 v6, 0.5, v54
	v_pk_mul_f32 v[52:53], v[70:71], v[52:53]
	v_cvt_f32_f16_e32 v70, v46
	v_cvt_f32_f16_e32 v71, v47
	v_cvt_f32_f16_sdwa v47, v47 dst_sel:DWORD dst_unused:UNUSED_PAD src0_sel:WORD_1
	v_cvt_f32_f16_sdwa v46, v46 dst_sel:DWORD dst_unused:UNUSED_PAD src0_sel:WORD_1
	v_pk_fma_f32 v[74:75], v[76:77], 0.5, v[112:113] op_sel_hi:[1,0,1] neg_lo:[1,0,0] neg_hi:[1,0,0]
	v_mul_f32_e32 v12, 0.5, v12
	v_pk_add_f32 v[76:77], v[6:7], v[56:57]
	v_pk_add_f32 v[52:53], v[52:53], v[52:53] op_sel:[0,1] op_sel_hi:[0,1] neg_lo:[0,1] neg_hi:[0,1]
	v_fma_f32 v77, v54, 0.5, -v56
	v_pk_add_f32 v[54:55], v[12:13], v[52:53] op_sel_hi:[0,1] neg_hi:[0,1]
	v_pk_mul_f32 v[52:53], v[54:55], v[46:47]
	v_pk_mul_f32 v[54:55], v[54:55], v[70:71]
	v_pk_fma_f32 v[56:57], v[76:77], v[70:71], v[52:53] neg_lo:[0,0,1] neg_hi:[0,0,1]
	v_pk_fma_f32 v[52:53], v[76:77], v[70:71], v[52:53]
	v_pk_fma_f32 v[70:71], v[76:77], v[46:47], v[54:55]
	v_pk_fma_f32 v[46:47], v[76:77], v[46:47], v[54:55] neg_lo:[0,0,1] neg_hi:[0,0,1]
	v_pk_add_f32 v[54:55], v[56:57], v[52:53] op_sel:[0,1] op_sel_hi:[1,0]
	v_pk_add_f32 v[76:77], v[70:71], v[46:47] op_sel_hi:[0,1] neg_lo:[0,1] neg_hi:[0,1]
	v_pk_add_f32 v[52:53], v[56:57], v[52:53] op_sel_hi:[0,1] neg_lo:[0,1] neg_hi:[0,1]
	v_pk_add_f32 v[46:47], v[70:71], v[46:47] op_sel:[0,1] op_sel_hi:[1,0]
	v_mov_b32_e32 v55, v77
	v_mov_b32_e32 v47, v53
	v_pk_mul_f32 v[46:47], v[46:47], 0.5 op_sel_hi:[1,0]
	s_mov_b32 s25, s27
	v_pk_mul_f32 v[52:53], v[58:59], v[46:47] op_sel:[0,1] op_sel_hi:[0,0]
	v_pk_fma_f32 v[56:57], v[34:35], v[46:47], v[52:53] op_sel_hi:[0,1,1]
	v_pk_fma_f32 v[46:47], v[34:35], v[46:47], v[52:53] op_sel_hi:[0,1,1] neg_hi:[0,0,1]
	s_nop 0
	v_pk_fma_f32 v[52:53], v[54:55], 0.5, v[56:57] op_sel_hi:[1,0,1] neg_lo:[0,0,1] neg_hi:[0,0,1]
	v_pk_fma_f32 v[34:35], v[54:55], 0.5, v[46:47] op_sel_hi:[1,0,1]
	s_mov_b32 s78, s27
	v_mov_b32_e32 v53, v35
	v_pk_mul_f32 v[136:137], v[52:53], s[6:7] op_sel_hi:[1,0]
	v_pk_fma_f32 v[52:53], v[54:55], 0.5, v[46:47] op_sel_hi:[1,0,1] neg_lo:[1,0,0] neg_hi:[1,0,0]
	s_mov_b32 s79, s24
	v_pk_mul_f32 v[46:47], v[82:83], s[24:25] op_sel_hi:[0,1]
	v_pk_add_f32 v[54:55], v[108:109], v[40:41]
	v_pk_add_f32 v[40:41], v[40:41], v[108:109] neg_lo:[0,1] neg_hi:[0,1]
	v_pk_fma_f32 v[108:109], v[4:5], s[78:79], v[46:47] op_sel_hi:[0,1,1] neg_lo:[0,0,1] neg_hi:[0,0,1]
	v_mul_f32_e32 v12, 0.5, v41
	v_pk_fma_f32 v[70:71], v[4:5], s[78:79], v[46:47] op_sel_hi:[0,1,1]
	v_mov_b32_e32 v41, v55
	v_mov_b32_e32 v56, v108
	v_mov_b32_e32 v57, v71
	v_pk_mul_f32 v[40:41], v[40:41], s[44:45]
	v_mul_f32_e32 v6, 0.5, v54
	v_pk_mul_f32 v[54:55], v[56:57], v[40:41] op_sel:[0,1] op_sel_hi:[1,0]
	v_cvt_f32_f16_sdwa v76, v36 dst_sel:DWORD dst_unused:UNUSED_PAD src0_sel:WORD_1
	v_cvt_f32_f16_e32 v77, v37
	v_cvt_f32_f16_sdwa v37, v37 dst_sel:DWORD dst_unused:UNUSED_PAD src0_sel:WORD_1
	v_cvt_f32_f16_e32 v36, v36
	v_pk_mul_f32 v[40:41], v[56:57], v[40:41]
	v_pk_add_f32 v[54:55], v[54:55], v[54:55] op_sel:[0,1] op_sel_hi:[0,1]
	v_pk_add_f32 v[112:113], v[6:7], v[54:55] op_sel_hi:[0,1] neg_hi:[0,1]
	s_nop 0
	v_pk_add_f32 v[40:41], v[40:41], v[40:41] op_sel:[0,1] op_sel_hi:[0,1] neg_lo:[0,1] neg_hi:[0,1]
	v_pk_add_f32 v[54:55], v[12:13], v[40:41] op_sel_hi:[0,1] neg_hi:[0,1]
	v_pk_mul_f32 v[40:41], v[54:55], v[36:37]
	v_pk_mul_f32 v[54:55], v[54:55], v[76:77]
	v_pk_fma_f32 v[40:41], v[112:113], v[76:77], v[40:41]
	v_pk_fma_f32 v[36:37], v[112:113], v[36:37], v[54:55] neg_lo:[0,0,1] neg_hi:[0,0,1]
	v_pk_mov_b32 v[110:111], v[70:71], v[108:109] op_sel:[1,0]
	v_pk_add_f32 v[54:55], v[36:37], v[40:41] op_sel:[0,1] op_sel_hi:[1,0] neg_lo:[0,1]
	v_pk_add_f32 v[76:77], v[36:37], v[40:41] op_sel:[0,1] op_sel_hi:[1,0]
	v_pk_add_f32 v[36:37], v[40:41], v[36:37] op_sel:[1,0] op_sel_hi:[0,1] neg_lo:[0,1] neg_hi:[0,1]
	v_pk_mul_f32 v[54:55], v[54:55], 0.5 op_sel_hi:[1,0]
	v_mov_b32_e32 v77, v37
	v_mul_f32_e32 v4, v108, v54
	v_pk_fma_f32 v[112:113], v[56:57], v[54:55], v[4:5] op_sel_hi:[1,1,0] neg_lo:[1,0,0] neg_hi:[1,0,0]
	v_mul_f32_e32 v4, v108, v55
	v_pk_fma_f32 v[54:55], v[110:111], v[54:55], v[4:5] op_sel_hi:[1,1,0]
	v_sub_f32_e32 v6, v45, v105
	v_mov_b32_e32 v112, v54
	v_pk_fma_f32 v[40:41], v[76:77], 0.5, v[54:55] op_sel_hi:[1,0,1] neg_lo:[0,0,1] neg_hi:[0,0,1]
	v_pk_fma_f32 v[36:37], v[76:77], 0.5, v[112:113] op_sel_hi:[1,0,1]
	v_pk_add_f32 v[54:55], v[104:105], v[44:45]
	v_mov_b32_e32 v41, v37
	v_pk_mul_f32 v[130:131], v[40:41], s[6:7] op_sel_hi:[1,0]
	v_mul_f32_e32 v40, 0xbf54db31, v83
	v_mov_b32_e32 v41, v44
	v_pk_mov_b32 v[44:45], v[46:47], v[104:105] op_sel:[1,0]
	v_mul_f32_e32 v18, 0.5, v55
	v_pk_add_f32 v[40:41], v[40:41], v[44:45] neg_lo:[0,1] neg_hi:[0,1]
	v_mov_b32_e32 v105, v108
	v_pk_mul_f32 v[44:45], v[40:41], v[18:19]
	v_mov_b32_e32 v104, v40
	v_pk_fma_f32 v[56:57], v[56:57], v[44:45], v[44:45] op_sel:[0,1,0] op_sel_hi:[1,0,1]
	v_mov_b32_e32 v44, v45
	v_mov_b32_e32 v45, v18
	v_mul_f32_e32 v4, 0.5, v54
	v_pk_mul_f32 v[44:45], v[104:105], v[44:45]
	v_cvt_f32_f16_e32 v104, v26
	v_cvt_f32_f16_e32 v105, v27
	v_cvt_f32_f16_sdwa v27, v27 dst_sel:DWORD dst_unused:UNUSED_PAD src0_sel:WORD_1
	v_cvt_f32_f16_sdwa v26, v26 dst_sel:DWORD dst_unused:UNUSED_PAD src0_sel:WORD_1
	v_mul_f32_e32 v6, 0.5, v6
	v_pk_add_f32 v[110:111], v[4:5], v[56:57]
	v_pk_add_f32 v[44:45], v[44:45], v[44:45] op_sel:[0,1] op_sel_hi:[0,1] neg_lo:[0,1] neg_hi:[0,1]
	v_fma_f32 v111, v54, 0.5, -v56
	v_pk_add_f32 v[54:55], v[6:7], v[44:45] op_sel_hi:[0,1] neg_hi:[0,1]
	v_pk_mul_f32 v[44:45], v[54:55], v[26:27]
	v_pk_mul_f32 v[54:55], v[54:55], v[104:105]
	v_pk_fma_f32 v[56:57], v[110:111], v[104:105], v[44:45] neg_lo:[0,0,1] neg_hi:[0,0,1]
	v_pk_fma_f32 v[44:45], v[110:111], v[104:105], v[44:45]
	v_pk_fma_f32 v[104:105], v[110:111], v[26:27], v[54:55]
	v_pk_fma_f32 v[26:27], v[110:111], v[26:27], v[54:55] neg_lo:[0,0,1] neg_hi:[0,0,1]
	v_pk_add_f32 v[54:55], v[56:57], v[44:45] op_sel:[0,1] op_sel_hi:[1,0]
	v_pk_add_f32 v[110:111], v[104:105], v[26:27] op_sel_hi:[0,1] neg_lo:[0,1] neg_hi:[0,1]
	v_pk_add_f32 v[44:45], v[56:57], v[44:45] op_sel_hi:[0,1] neg_lo:[0,1] neg_hi:[0,1]
	v_pk_add_f32 v[26:27], v[104:105], v[26:27] op_sel:[0,1] op_sel_hi:[1,0]
	v_mov_b32_e32 v55, v111
	v_mov_b32_e32 v27, v45
	v_pk_mul_f32 v[26:27], v[26:27], 0.5 op_sel_hi:[1,0]
	v_mov_b32_e32 v47, v102
	v_pk_mul_f32 v[44:45], v[108:109], v[26:27] op_sel:[0,1] op_sel_hi:[0,0]
	v_pk_fma_f32 v[56:57], v[40:41], v[26:27], v[44:45] op_sel_hi:[0,1,1]
	v_pk_fma_f32 v[40:41], v[40:41], v[26:27], v[44:45] op_sel_hi:[0,1,1] neg_hi:[0,0,1]
	v_pk_fma_f32 v[44:45], v[54:55], 0.5, v[56:57] op_sel_hi:[1,0,1] neg_lo:[0,0,1] neg_hi:[0,0,1]
	v_pk_fma_f32 v[26:27], v[54:55], 0.5, v[40:41] op_sel_hi:[1,0,1]
	v_pk_fma_f32 v[56:57], v[54:55], 0.5, v[40:41] op_sel_hi:[1,0,1] neg_lo:[1,0,0] neg_hi:[1,0,0]
	v_pk_add_f32 v[40:41], v[106:107], v[42:43]
	v_pk_add_f32 v[42:43], v[42:43], v[106:107] neg_lo:[0,1] neg_hi:[0,1]
	v_mov_b32_e32 v45, v27
	v_mul_f32_e32 v6, 0.5, v43
	v_mov_b32_e32 v43, v41
	v_pk_mul_f32 v[120:121], v[44:45], s[6:7] op_sel_hi:[1,0]
	v_mul_f32_e32 v4, 0.5, v40
	v_pk_mov_b32 v[44:45], v[108:109], v[70:71] op_sel:[1,0]
	v_pk_mul_f32 v[40:41], v[42:43], s[44:45]
	v_cvt_f32_f16_sdwa v54, v20 dst_sel:DWORD dst_unused:UNUSED_PAD src0_sel:WORD_1
	v_pk_mul_f32 v[42:43], v[44:45], v[40:41] op_sel:[0,1] op_sel_hi:[1,0]
	v_cvt_f32_f16_e32 v55, v21
	v_cvt_f32_f16_sdwa v21, v21 dst_sel:DWORD dst_unused:UNUSED_PAD src0_sel:WORD_1
	v_cvt_f32_f16_e32 v20, v20
	v_pk_mul_f32 v[40:41], v[44:45], v[40:41]
	v_pk_add_f32 v[42:43], v[42:43], v[42:43] op_sel:[0,1] op_sel_hi:[0,1]
	v_pk_add_f32 v[104:105], v[4:5], v[42:43] op_sel_hi:[0,1] neg_hi:[0,1]
	s_nop 0
	v_pk_add_f32 v[40:41], v[40:41], v[40:41] op_sel:[0,1] op_sel_hi:[0,1] neg_lo:[0,1] neg_hi:[0,1]
	v_pk_add_f32 v[42:43], v[6:7], v[40:41] op_sel_hi:[0,1] neg_hi:[0,1]
	v_pk_mul_f32 v[40:41], v[42:43], v[20:21]
	v_pk_mul_f32 v[42:43], v[42:43], v[54:55]
	v_pk_fma_f32 v[40:41], v[104:105], v[54:55], v[40:41]
	v_pk_fma_f32 v[20:21], v[104:105], v[20:21], v[42:43] neg_lo:[0,0,1] neg_hi:[0,0,1]
	v_mov_b32_e32 v71, v109
	v_pk_add_f32 v[42:43], v[20:21], v[40:41] op_sel:[0,1] op_sel_hi:[1,0] neg_lo:[0,1]
	v_pk_add_f32 v[54:55], v[20:21], v[40:41] op_sel:[0,1] op_sel_hi:[1,0]
	v_pk_add_f32 v[20:21], v[40:41], v[20:21] op_sel:[1,0] op_sel_hi:[0,1] neg_lo:[0,1] neg_hi:[0,1]
	v_pk_mul_f32 v[42:43], v[42:43], 0.5 op_sel_hi:[1,0]
	v_mov_b32_e32 v55, v21
	v_mul_f32_e32 v4, v109, v42
	v_pk_fma_f32 v[104:105], v[44:45], v[42:43], v[4:5] op_sel_hi:[1,1,0] neg_lo:[1,0,0] neg_hi:[1,0,0]
	v_mul_f32_e32 v4, v109, v43
	v_pk_fma_f32 v[42:43], v[70:71], v[42:43], v[4:5] op_sel_hi:[1,1,0]
	v_sub_f32_e32 v6, v23, v103
	v_mov_b32_e32 v104, v42
	v_pk_fma_f32 v[40:41], v[54:55], 0.5, v[42:43] op_sel_hi:[1,0,1] neg_lo:[0,0,1] neg_hi:[0,0,1]
	v_pk_fma_f32 v[20:21], v[54:55], 0.5, v[104:105] op_sel_hi:[1,0,1]
	v_pk_add_f32 v[42:43], v[102:103], v[22:23]
	v_mov_b32_e32 v41, v21
	v_pk_mul_f32 v[128:129], v[40:41], s[6:7] op_sel_hi:[1,0]
	v_mul_f32_e32 v40, 0xbf0e39da, v83
	v_mov_b32_e32 v41, v22
	v_mul_f32_e32 v18, 0.5, v43
	v_pk_add_f32 v[22:23], v[40:41], v[46:47] neg_lo:[0,1] neg_hi:[0,1]
	v_mov_b32_e32 v47, v109
	v_pk_mul_f32 v[40:41], v[22:23], v[18:19]
	v_mov_b32_e32 v46, v22
	v_pk_fma_f32 v[44:45], v[44:45], v[40:41], v[40:41] op_sel:[0,1,0] op_sel_hi:[1,0,1]
	v_mov_b32_e32 v40, v41
	v_mov_b32_e32 v41, v18
	v_mul_f32_e32 v4, 0.5, v42
	v_pk_mul_f32 v[40:41], v[46:47], v[40:41]
	v_cvt_f32_f16_e32 v46, v10
	v_cvt_f32_f16_e32 v47, v11
	v_cvt_f32_f16_sdwa v11, v11 dst_sel:DWORD dst_unused:UNUSED_PAD src0_sel:WORD_1
	v_cvt_f32_f16_sdwa v10, v10 dst_sel:DWORD dst_unused:UNUSED_PAD src0_sel:WORD_1
	v_pk_fma_f32 v[70:71], v[54:55], 0.5, v[104:105] op_sel_hi:[1,0,1] neg_lo:[1,0,0] neg_hi:[1,0,0]
	v_mul_f32_e32 v6, 0.5, v6
	v_pk_add_f32 v[54:55], v[4:5], v[44:45]
	v_pk_add_f32 v[40:41], v[40:41], v[40:41] op_sel:[0,1] op_sel_hi:[0,1] neg_lo:[0,1] neg_hi:[0,1]
	v_fma_f32 v55, v42, 0.5, -v44
	v_pk_add_f32 v[42:43], v[6:7], v[40:41] op_sel_hi:[0,1] neg_hi:[0,1]
	v_pk_mul_f32 v[40:41], v[42:43], v[10:11]
	v_pk_mul_f32 v[42:43], v[42:43], v[46:47]
	v_pk_fma_f32 v[44:45], v[54:55], v[46:47], v[40:41] neg_lo:[0,0,1] neg_hi:[0,0,1]
	v_pk_fma_f32 v[40:41], v[54:55], v[46:47], v[40:41]
	v_pk_fma_f32 v[46:47], v[54:55], v[10:11], v[42:43]
	v_pk_fma_f32 v[10:11], v[54:55], v[10:11], v[42:43] neg_lo:[0,0,1] neg_hi:[0,0,1]
	v_pk_add_f32 v[42:43], v[44:45], v[40:41] op_sel:[0,1] op_sel_hi:[1,0]
	v_pk_add_f32 v[54:55], v[46:47], v[10:11] op_sel_hi:[0,1] neg_lo:[0,1] neg_hi:[0,1]
	v_pk_add_f32 v[40:41], v[44:45], v[40:41] op_sel_hi:[0,1] neg_lo:[0,1] neg_hi:[0,1]
	v_pk_add_f32 v[10:11], v[46:47], v[10:11] op_sel:[0,1] op_sel_hi:[1,0]
	v_mov_b32_e32 v43, v55
	v_mov_b32_e32 v11, v41
	v_pk_mul_f32 v[10:11], v[10:11], 0.5 op_sel_hi:[1,0]
	v_mov_b32_e32 v119, v98
	v_pk_mul_f32 v[40:41], v[108:109], v[10:11] op_sel:[1,1] op_sel_hi:[1,0]
	v_pk_fma_f32 v[76:77], v[76:77], 0.5, v[112:113] op_sel_hi:[1,0,1] neg_lo:[1,0,0] neg_hi:[1,0,0]
	v_pk_fma_f32 v[44:45], v[22:23], v[10:11], v[40:41] op_sel_hi:[0,1,1]
	v_pk_fma_f32 v[10:11], v[22:23], v[10:11], v[40:41] op_sel_hi:[0,1,1] neg_hi:[0,0,1]
	v_pk_fma_f32 v[22:23], v[42:43], 0.5, v[44:45] op_sel_hi:[1,0,1] neg_lo:[0,0,1] neg_hi:[0,0,1]
	v_pk_fma_f32 v[40:41], v[42:43], 0.5, v[10:11] op_sel_hi:[1,0,1]
	v_pk_fma_f32 v[54:55], v[42:43], 0.5, v[10:11] op_sel_hi:[1,0,1] neg_lo:[1,0,0] neg_hi:[1,0,0]
	v_pk_add_f32 v[10:11], v[100:101], v[14:15]
	v_pk_add_f32 v[14:15], v[14:15], v[100:101] neg_lo:[0,1] neg_hi:[0,1]
	v_mov_b32_e32 v23, v41
	v_mul_f32_e32 v6, 0.5, v15
	v_mov_b32_e32 v15, v11
	v_pk_mul_f32 v[150:151], v[22:23], s[6:7] op_sel_hi:[1,0]
	v_mul_f32_e32 v4, 0.5, v10
	v_pk_mov_b32 v[22:23], v[58:59], v[72:73] op_sel:[1,0]
	v_pk_mul_f32 v[10:11], v[14:15], s[44:45]
	v_cvt_f32_f16_sdwa v42, v8 dst_sel:DWORD dst_unused:UNUSED_PAD src0_sel:WORD_1
	v_pk_mul_f32 v[14:15], v[22:23], v[10:11] op_sel:[0,1] op_sel_hi:[1,0]
	v_cvt_f32_f16_e32 v43, v9
	v_cvt_f32_f16_sdwa v9, v9 dst_sel:DWORD dst_unused:UNUSED_PAD src0_sel:WORD_1
	v_cvt_f32_f16_e32 v8, v8
	v_pk_mul_f32 v[10:11], v[22:23], v[10:11]
	v_pk_add_f32 v[14:15], v[14:15], v[14:15] op_sel:[0,1] op_sel_hi:[0,1]
	v_pk_add_f32 v[44:45], v[4:5], v[14:15] op_sel_hi:[0,1] neg_hi:[0,1]
	s_nop 0
	v_pk_add_f32 v[10:11], v[10:11], v[10:11] op_sel:[0,1] op_sel_hi:[0,1] neg_lo:[0,1] neg_hi:[0,1]
	v_pk_add_f32 v[14:15], v[6:7], v[10:11] op_sel_hi:[0,1] neg_hi:[0,1]
	v_pk_mul_f32 v[10:11], v[14:15], v[8:9]
	v_pk_mul_f32 v[14:15], v[14:15], v[42:43]
	v_pk_fma_f32 v[10:11], v[44:45], v[42:43], v[10:11]
	v_pk_fma_f32 v[8:9], v[44:45], v[8:9], v[14:15] neg_lo:[0,0,1] neg_hi:[0,0,1]
	v_mov_b32_e32 v73, v59
	v_pk_add_f32 v[14:15], v[8:9], v[10:11] op_sel:[0,1] op_sel_hi:[1,0] neg_lo:[0,1]
	v_pk_add_f32 v[42:43], v[8:9], v[10:11] op_sel:[0,1] op_sel_hi:[1,0]
	v_pk_add_f32 v[8:9], v[10:11], v[8:9] op_sel:[1,0] op_sel_hi:[0,1] neg_lo:[0,1] neg_hi:[0,1]
	v_pk_mul_f32 v[14:15], v[14:15], 0.5 op_sel_hi:[1,0]
	v_mov_b32_e32 v43, v9
	v_mul_f32_e32 v4, v59, v14
	v_pk_fma_f32 v[44:45], v[22:23], v[14:15], v[4:5] op_sel_hi:[1,1,0] neg_lo:[1,0,0] neg_hi:[1,0,0]
	v_mul_f32_e32 v4, v59, v15
	v_pk_fma_f32 v[14:15], v[72:73], v[14:15], v[4:5] op_sel_hi:[1,1,0]
	v_sub_f32_e32 v6, v39, v99
	v_mov_b32_e32 v44, v14
	v_pk_fma_f32 v[8:9], v[42:43], 0.5, v[14:15] op_sel_hi:[1,0,1] neg_lo:[0,0,1] neg_hi:[0,0,1]
	v_pk_fma_f32 v[10:11], v[42:43], 0.5, v[44:45] op_sel_hi:[1,0,1]
	v_pk_add_f32 v[14:15], v[98:99], v[38:39]
	v_mov_b32_e32 v9, v11
	v_pk_mul_f32 v[168:169], v[8:9], s[6:7] op_sel_hi:[1,0]
	v_mul_f32_e32 v8, 0xbf7b14be, v83
	v_mov_b32_e32 v9, v38
	v_mul_f32_e32 v18, 0.5, v15
	v_pk_add_f32 v[8:9], v[8:9], v[118:119] neg_lo:[0,1] neg_hi:[0,1]
	v_pk_fma_f32 v[72:73], v[42:43], 0.5, v[44:45] op_sel_hi:[1,0,1] neg_lo:[1,0,0] neg_hi:[1,0,0]
	v_pk_mul_f32 v[38:39], v[8:9], v[18:19]
	v_mov_b32_e32 v42, v8
	v_pk_fma_f32 v[22:23], v[22:23], v[38:39], v[38:39] op_sel:[0,1,0] op_sel_hi:[1,0,1]
	v_mov_b32_e32 v43, v59
	v_mov_b32_e32 v38, v39
	v_mov_b32_e32 v39, v18
	v_mul_f32_e32 v4, 0.5, v14
	v_pk_mul_f32 v[38:39], v[42:43], v[38:39]
	v_cvt_f32_f16_e32 v44, v2
	v_cvt_f32_f16_e32 v45, v3
	v_cvt_f32_f16_sdwa v3, v3 dst_sel:DWORD dst_unused:UNUSED_PAD src0_sel:WORD_1
	v_cvt_f32_f16_sdwa v2, v2 dst_sel:DWORD dst_unused:UNUSED_PAD src0_sel:WORD_1
	v_mul_f32_e32 v6, 0.5, v6
	v_pk_add_f32 v[46:47], v[4:5], v[22:23]
	v_fma_f32 v4, v14, 0.5, -v22
	v_pk_add_f32 v[22:23], v[38:39], v[38:39] op_sel:[0,1] op_sel_hi:[0,1] neg_lo:[0,1] neg_hi:[0,1]
	v_pk_add_f32 v[38:39], v[6:7], v[22:23] op_sel_hi:[0,1] neg_hi:[0,1]
	v_mov_b32_e32 v14, v46
	v_mov_b32_e32 v15, v4
	v_pk_mul_f32 v[22:23], v[4:5], v[44:45] op_sel_hi:[0,1]
	v_pk_mul_f32 v[82:83], v[38:39], v[2:3]
	v_pk_mul_f32 v[46:47], v[46:47], v[2:3]
	v_pk_mul_f32 v[38:39], v[38:39], v[44:45]
	v_pk_fma_f32 v[98:99], v[14:15], v[44:45], v[82:83] neg_lo:[0,0,1] neg_hi:[0,0,1]
	v_pk_fma_f32 v[2:3], v[14:15], v[2:3], v[38:39] neg_lo:[0,0,1] neg_hi:[0,0,1]
	v_add_f32_e32 v4, v23, v83
	v_add_f32_e32 v6, v46, v38
	v_pk_add_f32 v[22:23], v[6:7], v[2:3] op_sel_hi:[0,1] neg_lo:[0,1] neg_hi:[0,1]
	v_pk_add_f32 v[38:39], v[98:99], v[4:5] op_sel_hi:[1,0] neg_lo:[0,1] neg_hi:[0,1]
	v_pk_add_f32 v[2:3], v[6:7], v[2:3] op_sel_hi:[0,1]
	v_mov_b32_e32 v39, v3
	v_pk_mul_f32 v[2:3], v[38:39], 0.5 op_sel_hi:[1,0]
	v_pk_add_f32 v[14:15], v[98:99], v[4:5] op_sel_hi:[1,0]
	v_mul_f32_e32 v4, v59, v3
	v_pk_fma_f32 v[38:39], v[42:43], v[2:3], v[4:5] op_sel_hi:[1,1,0] neg_lo:[0,0,1] neg_hi:[0,0,1]
	v_pk_mov_b32 v[42:43], v[58:59], v[8:9] op_sel:[1,0]
	v_mul_f32_e32 v4, v8, v3
	v_pk_fma_f32 v[2:3], v[42:43], v[2:3], v[4:5] op_sel_hi:[1,1,0]
	v_mov_b32_e32 v15, v23
	v_pk_fma_f32 v[8:9], v[14:15], 0.5, v[2:3] op_sel_hi:[1,0,1] neg_lo:[0,0,1] neg_hi:[0,0,1]
	v_pk_fma_f32 v[42:43], v[14:15], 0.5, v[38:39] op_sel_hi:[1,0,0]
	v_pk_fma_f32 v[2:3], v[14:15], 0.5, v[2:3] op_sel_hi:[1,0,1]
	v_mov_b32_e32 v9, v43
	v_pk_fma_f32 v[58:59], v[22:23], 0.5, v[38:39] op_sel_hi:[1,0,0] neg_lo:[1,0,0] neg_hi:[1,0,0]
	v_pk_mul_f32 v[144:145], v[8:9], s[6:7] op_sel_hi:[1,0]
	v_mov_b32_e32 v58, v2
	v_mov_b32_e32 v72, v10
	v_mov_b32_e32 v54, v40
	v_mov_b32_e32 v70, v20
	v_mov_b32_e32 v56, v26
	v_mov_b32_e32 v76, v36
	v_mov_b32_e32 v52, v34
	v_mov_b32_e32 v74, v86
	v_mov_b32_e32 v48, v84
	v_mov_b32_e32 v50, v60
	v_mov_b32_e32 v28, v66
	v_mov_b32_e32 v32, v96
	v_mov_b32_e32 v12, v88
	v_mov_b32_e32 v16, v92
	v_mov_b32_e32 v4, v138
	v_mov_b32_e32 v6, v122

.LBB0_503:
	s_or_b64 exec, exec, s[0:1]
	v_pk_mul_f32 v[22:23], v[32:33], s[6:7] op_sel_hi:[1,0]
	v_pk_add_f32 v[26:27], v[24:25], v[30:31]
	v_pk_add_f32 v[24:25], v[24:25], v[30:31] neg_lo:[0,1] neg_hi:[0,1]
	v_pk_add_f32 v[30:31], v[64:65], v[68:69]
	v_pk_add_f32 v[32:33], v[64:65], v[68:69] neg_lo:[0,1] neg_hi:[0,1]
	v_pk_add_f32 v[34:35], v[62:63], v[90:91]
	v_pk_add_f32 v[38:39], v[94:95], v[80:81]
	v_pk_add_f32 v[68:69], v[26:27], v[30:31]
	v_pk_add_f32 v[26:27], v[26:27], v[30:31] neg_lo:[0,1] neg_hi:[0,1]
	v_pk_mul_f32 v[30:31], v[32:33], 1.0 op_sel:[1,0] op_sel_hi:[0,0] neg_lo:[1,0]
	v_pk_mul_f32 v[20:21], v[50:51], s[6:7] op_sel_hi:[1,0]
	v_pk_add_f32 v[36:37], v[62:63], v[90:91] neg_lo:[0,1] neg_hi:[0,1]
	v_pk_add_f32 v[42:43], v[78:79], v[136:137]
	v_pk_add_f32 v[46:47], v[130:131], v[120:121]
	v_pk_add_f32 v[32:33], v[24:25], v[30:31]
	v_pk_add_f32 v[24:25], v[24:25], v[30:31] neg_lo:[0,1] neg_hi:[0,1]
	v_pk_add_f32 v[30:31], v[34:35], v[38:39]
	v_pk_add_f32 v[34:35], v[34:35], v[38:39] neg_lo:[0,1] neg_hi:[0,1]
	v_pk_add_f32 v[38:39], v[94:95], v[80:81] neg_lo:[0,1] neg_hi:[0,1]
	v_pk_add_f32 v[44:45], v[78:79], v[136:137] neg_lo:[0,1] neg_hi:[0,1]
	v_pk_add_f32 v[60:61], v[128:129], v[150:151]
	v_pk_add_f32 v[64:65], v[168:169], v[144:145]
	v_pk_add_f32 v[40:41], v[36:37], v[38:39] op_sel:[0,1] op_sel_hi:[1,0] neg_lo:[0,1]
	v_pk_add_f32 v[36:37], v[36:37], v[38:39] op_sel:[0,1] op_sel_hi:[1,0] neg_hi:[0,1]
	v_pk_add_f32 v[38:39], v[42:43], v[46:47]
	v_pk_add_f32 v[42:43], v[42:43], v[46:47] neg_lo:[0,1] neg_hi:[0,1]
	v_pk_add_f32 v[46:47], v[130:131], v[120:121] neg_lo:[0,1] neg_hi:[0,1]
	v_pk_add_f32 v[62:63], v[128:129], v[150:151] neg_lo:[0,1] neg_hi:[0,1]
	v_pk_add_f32 v[50:51], v[44:45], v[46:47] op_sel:[0,1] op_sel_hi:[1,0] neg_lo:[0,1]
	v_pk_add_f32 v[44:45], v[44:45], v[46:47] op_sel:[0,1] op_sel_hi:[1,0] neg_hi:[0,1]
	v_pk_add_f32 v[46:47], v[60:61], v[64:65]
	v_pk_add_f32 v[60:61], v[60:61], v[64:65] neg_lo:[0,1] neg_hi:[0,1]
	v_pk_add_f32 v[64:65], v[168:169], v[144:145] neg_lo:[0,1] neg_hi:[0,1]
	s_mov_b32 s78, s37
	s_mov_b32 s79, s36
	v_pk_add_f32 v[66:67], v[62:63], v[64:65] op_sel:[0,1] op_sel_hi:[1,0] neg_lo:[0,1]
	v_pk_add_f32 v[62:63], v[62:63], v[64:65] op_sel:[0,1] op_sel_hi:[1,0] neg_hi:[0,1]
	v_pk_add_f32 v[64:65], v[68:69], v[30:31]
	v_pk_add_f32 v[30:31], v[68:69], v[30:31] neg_lo:[0,1] neg_hi:[0,1]
	s_mov_b32 s0, s37
	v_pk_mul_f32 v[68:69], v[40:41], s[78:79]
	s_mov_b32 s80, s19
	v_pk_fma_f32 v[40:41], v[40:41], s[0:1], v[68:69] op_sel:[0,0,1] op_sel_hi:[1,0,0]
	s_mov_b32 s81, s18
	v_pk_add_f32 v[68:69], v[32:33], v[40:41]
	v_pk_add_f32 v[32:33], v[32:33], v[40:41] neg_lo:[0,1] neg_hi:[0,1]
	v_pk_mul_f32 v[40:41], v[34:35], 1.0 op_sel:[1,0] op_sel_hi:[0,0] neg_lo:[1,0]
	s_nop 0
	v_pk_add_f32 v[34:35], v[26:27], v[40:41]
	v_pk_add_f32 v[26:27], v[26:27], v[40:41] neg_lo:[0,1] neg_hi:[0,1]
	v_pk_mul_f32 v[40:41], v[36:37], s[78:79]
	s_mov_b32 s82, s19
	v_pk_fma_f32 v[36:37], v[36:37], s[0:1], v[40:41] op_sel:[0,0,1] op_sel_hi:[1,0,0] neg_lo:[1,0,0] neg_hi:[1,0,0]
	v_pk_mul_f32 v[2:3], v[72:73], s[6:7] op_sel_hi:[1,0]
	v_pk_add_f32 v[40:41], v[24:25], v[36:37]
	v_pk_add_f32 v[24:25], v[24:25], v[36:37] neg_lo:[0,1] neg_hi:[0,1]
	v_pk_add_f32 v[36:37], v[38:39], v[46:47]
	v_pk_add_f32 v[38:39], v[38:39], v[46:47] neg_lo:[0,1] neg_hi:[0,1]
	v_pk_mul_f32 v[46:47], v[66:67], s[78:79]
	v_pk_mul_f32 v[8:9], v[70:71], s[6:7] op_sel_hi:[1,0]
	v_pk_fma_f32 v[46:47], v[66:67], s[0:1], v[46:47] op_sel:[0,0,1] op_sel_hi:[1,0,0]
	v_pk_mul_f32 v[10:11], v[76:77], s[6:7] op_sel_hi:[1,0]
	v_pk_add_f32 v[66:67], v[50:51], v[46:47]
	v_pk_add_f32 v[46:47], v[50:51], v[46:47] neg_lo:[0,1] neg_hi:[0,1]
	v_pk_mul_f32 v[50:51], v[60:61], 1.0 op_sel:[1,0] op_sel_hi:[0,0] neg_lo:[1,0]
	v_pk_add_f32 v[60:61], v[42:43], v[50:51]
	v_pk_add_f32 v[42:43], v[42:43], v[50:51] neg_lo:[0,1] neg_hi:[0,1]
	v_pk_mul_f32 v[50:51], v[62:63], s[78:79]
	v_pk_mul_f32 v[14:15], v[74:75], s[6:7] op_sel_hi:[1,0]
	v_pk_fma_f32 v[50:51], v[62:63], s[0:1], v[50:51] op_sel:[0,0,1] op_sel_hi:[1,0,0] neg_lo:[1,0,0] neg_hi:[1,0,0]
	v_pk_mul_f32 v[16:17], v[16:17], s[6:7] op_sel_hi:[1,0]
	v_pk_add_f32 v[62:63], v[44:45], v[50:51]
	v_pk_add_f32 v[44:45], v[44:45], v[50:51] neg_lo:[0,1] neg_hi:[0,1]
	v_pk_add_f32 v[50:51], v[64:65], v[36:37]
	v_pk_add_f32 v[36:37], v[64:65], v[36:37] neg_lo:[0,1] neg_hi:[0,1]
	v_pk_mul_f32 v[64:65], v[66:67], s[80:81]
	v_pk_mul_f32 v[6:7], v[6:7], s[6:7] op_sel_hi:[1,0]
	v_pk_fma_f32 v[64:65], v[66:67], s[16:17], v[64:65] op_sel:[0,0,1] op_sel_hi:[1,0,0]
	s_mov_b32 s17, s40
	v_pk_add_f32 v[66:67], v[68:69], v[64:65]
	v_pk_add_f32 v[64:65], v[68:69], v[64:65] neg_lo:[0,1] neg_hi:[0,1]
	v_pk_mul_f32 v[68:69], v[60:61], s[78:79]
	s_mov_b32 s88, s11
	v_pk_fma_f32 v[60:61], v[60:61], s[0:1], v[68:69] op_sel:[0,0,1] op_sel_hi:[1,0,0]
	s_mov_b32 s89, s10
	v_pk_add_f32 v[68:69], v[34:35], v[60:61]
	v_pk_add_f32 v[34:35], v[34:35], v[60:61] neg_lo:[0,1] neg_hi:[0,1]
	v_pk_mul_f32 v[60:61], v[62:63], s[16:17]
	s_mov_b32 s62, s27
	v_pk_fma_f32 v[60:61], v[62:63], s[82:83], v[60:61] op_sel:[0,0,1] op_sel_hi:[1,0,0]
	s_mov_b32 s63, s26
	v_pk_add_f32 v[62:63], v[40:41], v[60:61]
	v_pk_add_f32 v[40:41], v[40:41], v[60:61] neg_lo:[0,1] neg_hi:[0,1]
	v_pk_mul_f32 v[60:61], v[38:39], 1.0 op_sel:[1,0] op_sel_hi:[0,0] neg_lo:[1,0]
	s_nop 0
	v_pk_add_f32 v[38:39], v[30:31], v[60:61]
	v_pk_add_f32 v[30:31], v[30:31], v[60:61] neg_lo:[0,1] neg_hi:[0,1]
	v_pk_mul_f32 v[60:61], v[46:47], s[16:17]
	s_mov_b32 s84, s27
	v_pk_fma_f32 v[46:47], v[46:47], s[82:83], v[60:61] op_sel:[0,0,1] op_sel_hi:[1,0,0] neg_lo:[1,0,0] neg_hi:[1,0,0]
	s_mov_b32 s86, s11
	v_pk_add_f32 v[60:61], v[32:33], v[46:47]
	v_pk_add_f32 v[32:33], v[32:33], v[46:47] neg_lo:[0,1] neg_hi:[0,1]
	v_pk_mul_f32 v[46:47], v[42:43], s[78:79]
	s_ashr_i32 s73, s72, 31
	v_pk_fma_f32 v[42:43], s[0:1], v[42:43], v[46:47] op_sel:[0,0,1] op_sel_hi:[0,1,0] neg_lo:[0,1,0] neg_hi:[0,1,0]
	v_pk_add_f32 v[46:47], v[26:27], v[42:43]
	v_pk_add_f32 v[26:27], v[26:27], v[42:43] neg_lo:[0,1] neg_hi:[0,1]
	v_pk_mul_f32 v[42:43], v[44:45], s[80:81]
	s_nop 0
	v_pk_fma_f32 v[42:43], s[16:17], v[44:45], v[42:43] op_sel:[0,0,1] op_sel_hi:[0,1,0] neg_lo:[0,1,0] neg_hi:[0,1,0]
	v_pk_add_f32 v[44:45], v[24:25], v[42:43]
	v_pk_add_f32 v[24:25], v[24:25], v[42:43] neg_lo:[0,1] neg_hi:[0,1]
	v_pk_fma_f32 v[42:43], v[58:59], s[6:7], v[2:3] op_sel_hi:[1,0,1]
	v_pk_fma_f32 v[2:3], v[58:59], s[6:7], v[2:3] op_sel_hi:[1,0,1] neg_lo:[0,0,1] neg_hi:[0,0,1]
	v_pk_fma_f32 v[58:59], v[54:55], s[6:7], v[8:9] op_sel_hi:[1,0,1]
	v_pk_fma_f32 v[8:9], v[54:55], s[6:7], v[8:9] op_sel_hi:[1,0,1] neg_lo:[0,0,1] neg_hi:[0,0,1]
	v_pk_fma_f32 v[54:55], v[56:57], s[6:7], v[10:11] op_sel_hi:[1,0,1]
	v_pk_fma_f32 v[10:11], v[56:57], s[6:7], v[10:11] op_sel_hi:[1,0,1] neg_lo:[0,0,1] neg_hi:[0,0,1]
	v_pk_fma_f32 v[56:57], v[52:53], s[6:7], v[14:15] op_sel_hi:[1,0,1]
	v_pk_fma_f32 v[14:15], v[52:53], s[6:7], v[14:15] op_sel_hi:[1,0,1] neg_lo:[0,0,1] neg_hi:[0,0,1]
	v_pk_fma_f32 v[52:53], v[48:49], s[6:7], v[20:21] op_sel_hi:[1,0,1]
	v_pk_fma_f32 v[20:21], v[48:49], s[6:7], v[20:21] op_sel_hi:[1,0,1] neg_lo:[0,0,1] neg_hi:[0,0,1]
	v_pk_fma_f32 v[48:49], v[28:29], s[6:7], v[22:23] op_sel_hi:[1,0,1]
	v_pk_fma_f32 v[22:23], v[28:29], s[6:7], v[22:23] op_sel_hi:[1,0,1] neg_lo:[0,0,1] neg_hi:[0,0,1]
	v_pk_fma_f32 v[28:29], v[12:13], s[6:7], v[16:17] op_sel_hi:[1,0,1]
	v_pk_fma_f32 v[12:13], v[12:13], s[6:7], v[16:17] op_sel_hi:[1,0,1] neg_lo:[0,0,1] neg_hi:[0,0,1]
	v_pk_fma_f32 v[16:17], v[4:5], s[6:7], v[6:7] op_sel_hi:[1,0,1]
	v_pk_fma_f32 v[4:5], v[4:5], s[6:7], v[6:7] op_sel_hi:[1,0,1] neg_lo:[0,0,1] neg_hi:[0,0,1]
	v_pk_add_f32 v[6:7], v[58:59], v[42:43]
	v_pk_add_f32 v[42:43], v[42:43], v[58:59] neg_lo:[0,1] neg_hi:[0,1]
	v_pk_mul_f32 v[58:59], v[8:9], 1.0 op_sel:[1,0] op_sel_hi:[0,0] neg_lo:[1,0]
	v_pk_add_f32 v[8:9], v[2:3], v[58:59]
	v_pk_add_f32 v[2:3], v[2:3], v[58:59] neg_lo:[0,1] neg_hi:[0,1]
	v_pk_add_f32 v[58:59], v[56:57], v[54:55]
	v_pk_add_f32 v[54:55], v[54:55], v[56:57] neg_lo:[0,1] neg_hi:[0,1]
	v_pk_mul_f32 v[56:57], v[14:15], 1.0 op_sel:[1,0] op_sel_hi:[0,0] neg_lo:[1,0]
	v_pk_add_f32 v[14:15], v[10:11], v[56:57]
	v_pk_add_f32 v[10:11], v[10:11], v[56:57] neg_lo:[0,1] neg_hi:[0,1]
	v_pk_add_f32 v[56:57], v[48:49], v[52:53]
	v_pk_add_f32 v[48:49], v[52:53], v[48:49] neg_lo:[0,1] neg_hi:[0,1]
	v_pk_mul_f32 v[52:53], v[22:23], 1.0 op_sel:[1,0] op_sel_hi:[0,0] neg_lo:[1,0]
	v_pk_add_f32 v[22:23], v[20:21], v[52:53]
	v_pk_add_f32 v[20:21], v[20:21], v[52:53] neg_lo:[0,1] neg_hi:[0,1]
	v_pk_add_f32 v[52:53], v[16:17], v[28:29]
	v_pk_add_f32 v[16:17], v[28:29], v[16:17] neg_lo:[0,1] neg_hi:[0,1]
	v_pk_mul_f32 v[28:29], v[4:5], 1.0 op_sel:[1,0] op_sel_hi:[0,0] neg_lo:[1,0]
	v_pk_add_f32 v[4:5], v[12:13], v[28:29]
	v_pk_add_f32 v[12:13], v[12:13], v[28:29] neg_lo:[0,1] neg_hi:[0,1]
	v_pk_add_f32 v[28:29], v[58:59], v[6:7]
	v_pk_add_f32 v[6:7], v[6:7], v[58:59] neg_lo:[0,1] neg_hi:[0,1]
	v_pk_mul_f32 v[58:59], v[14:15], s[78:79]
	s_nop 0
	v_pk_fma_f32 v[14:15], s[0:1], v[14:15], v[58:59] op_sel:[0,0,1] op_sel_hi:[0,1,0]
	v_pk_add_f32 v[58:59], v[14:15], v[8:9]
	v_pk_add_f32 v[8:9], v[8:9], v[14:15] neg_lo:[0,1] neg_hi:[0,1]
	v_pk_mul_f32 v[14:15], v[54:55], 1.0 op_sel:[1,0] op_sel_hi:[0,0] neg_lo:[1,0]
	v_pk_add_f32 v[54:55], v[14:15], v[42:43]
	v_pk_add_f32 v[14:15], v[42:43], v[14:15] neg_lo:[0,1] neg_hi:[0,1]
	v_pk_mul_f32 v[42:43], v[10:11], s[78:79]
	s_nop 0
	v_pk_fma_f32 v[10:11], s[0:1], v[10:11], v[42:43] op_sel:[0,0,1] op_sel_hi:[0,1,0] neg_lo:[0,1,0] neg_hi:[0,1,0]
	v_pk_add_f32 v[42:43], v[10:11], v[2:3]
	v_pk_add_f32 v[2:3], v[2:3], v[10:11] neg_lo:[0,1] neg_hi:[0,1]
	v_pk_add_f32 v[10:11], v[52:53], v[56:57]
	v_pk_add_f32 v[52:53], v[56:57], v[52:53] neg_lo:[0,1] neg_hi:[0,1]
	v_pk_mul_f32 v[56:57], v[4:5], s[78:79]
	s_nop 0
	v_pk_fma_f32 v[4:5], s[0:1], v[4:5], v[56:57] op_sel:[0,0,1] op_sel_hi:[0,1,0]
	v_pk_add_f32 v[56:57], v[4:5], v[22:23]
	v_pk_add_f32 v[4:5], v[22:23], v[4:5] neg_lo:[0,1] neg_hi:[0,1]
	v_pk_mul_f32 v[22:23], v[16:17], 1.0 op_sel:[1,0] op_sel_hi:[0,0] neg_lo:[1,0]
	v_pk_add_f32 v[16:17], v[22:23], v[48:49]
	v_pk_add_f32 v[22:23], v[48:49], v[22:23] neg_lo:[0,1] neg_hi:[0,1]
	v_pk_mul_f32 v[48:49], v[12:13], s[78:79]
	s_nop 0
	v_pk_fma_f32 v[12:13], s[0:1], v[12:13], v[48:49] op_sel:[0,0,1] op_sel_hi:[0,1,0] neg_lo:[0,1,0] neg_hi:[0,1,0]
	v_pk_add_f32 v[48:49], v[12:13], v[20:21]
	v_pk_add_f32 v[12:13], v[20:21], v[12:13] neg_lo:[0,1] neg_hi:[0,1]
	v_pk_add_f32 v[20:21], v[10:11], v[28:29]
	v_pk_add_f32 v[10:11], v[28:29], v[10:11] neg_lo:[0,1] neg_hi:[0,1]
	v_pk_mul_f32 v[28:29], v[56:57], s[80:81]
	s_nop 0
	v_pk_fma_f32 v[28:29], s[16:17], v[56:57], v[28:29] op_sel:[0,0,1] op_sel_hi:[0,1,0]
	v_pk_add_f32 v[56:57], v[28:29], v[58:59]
	v_pk_add_f32 v[28:29], v[58:59], v[28:29] neg_lo:[0,1] neg_hi:[0,1]
	v_pk_mul_f32 v[58:59], v[16:17], s[78:79]
	s_nop 0
	v_pk_fma_f32 v[16:17], s[0:1], v[16:17], v[58:59] op_sel:[0,0,1] op_sel_hi:[0,1,0]
	v_pk_add_f32 v[58:59], v[16:17], v[54:55]
	v_pk_add_f32 v[16:17], v[54:55], v[16:17] neg_lo:[0,1] neg_hi:[0,1]
	v_pk_mul_f32 v[54:55], v[48:49], s[16:17]
	s_nop 0
	v_pk_fma_f32 v[48:49], s[82:83], v[48:49], v[54:55] op_sel:[0,0,1] op_sel_hi:[0,1,0]
	v_pk_add_f32 v[54:55], v[48:49], v[42:43]
	v_pk_add_f32 v[42:43], v[42:43], v[48:49] neg_lo:[0,1] neg_hi:[0,1]
	v_pk_mul_f32 v[48:49], v[52:53], 1.0 op_sel:[1,0] op_sel_hi:[0,0] neg_lo:[1,0]
	v_pk_add_f32 v[52:53], v[48:49], v[6:7]
	v_pk_add_f32 v[6:7], v[6:7], v[48:49] neg_lo:[0,1] neg_hi:[0,1]
	v_pk_mul_f32 v[48:49], v[4:5], s[16:17]
	s_nop 0
	v_pk_fma_f32 v[4:5], s[82:83], v[4:5], v[48:49] op_sel:[0,0,1] op_sel_hi:[0,1,0] neg_lo:[0,1,0] neg_hi:[0,1,0]
	v_pk_add_f32 v[48:49], v[4:5], v[8:9]
	v_pk_add_f32 v[4:5], v[8:9], v[4:5] neg_lo:[0,1] neg_hi:[0,1]
	v_pk_mul_f32 v[8:9], v[22:23], s[78:79]
	s_nop 0
	v_pk_fma_f32 v[8:9], s[0:1], v[22:23], v[8:9] op_sel:[0,0,1] op_sel_hi:[0,1,0] neg_lo:[0,1,0] neg_hi:[0,1,0]
	v_pk_add_f32 v[22:23], v[8:9], v[14:15]
	v_pk_add_f32 v[8:9], v[14:15], v[8:9] neg_lo:[0,1] neg_hi:[0,1]
	v_pk_mul_f32 v[14:15], v[12:13], s[80:81]
	s_nop 0
	v_pk_fma_f32 v[12:13], s[16:17], v[12:13], v[14:15] op_sel:[0,0,1] op_sel_hi:[0,1,0] neg_lo:[0,1,0] neg_hi:[0,1,0]
	v_pk_add_f32 v[14:15], v[12:13], v[2:3]
	v_pk_add_f32 v[2:3], v[2:3], v[12:13] neg_lo:[0,1] neg_hi:[0,1]
	ds_write_b64 v211, v[50:51]
	ds_write_b64 v212, v[20:21]
	ds_write_b64 v211, v[66:67] offset:8
	ds_write_b64 v212, v[56:57] offset:8
	ds_write_b64 v211, v[68:69] offset:16
	ds_write_b64 v212, v[58:59] offset:16
	ds_write_b64 v211, v[62:63] offset:24
	ds_write_b64 v212, v[54:55] offset:24
	ds_write_b64 v211, v[38:39] offset:32
	ds_write_b64 v212, v[52:53] offset:32
	ds_write_b64 v211, v[60:61] offset:40
	ds_write_b64 v212, v[48:49] offset:40
	ds_write_b64 v211, v[46:47] offset:48
	ds_write_b64 v212, v[22:23] offset:48
	ds_write_b64 v211, v[44:45] offset:56
	ds_write_b64 v212, v[14:15] offset:56
	ds_write_b64 v211, v[36:37] offset:64
	ds_write_b64 v212, v[10:11] offset:64
	ds_write_b64 v211, v[64:65] offset:72
	ds_write_b64 v212, v[28:29] offset:72
	ds_write_b64 v211, v[34:35] offset:80
	ds_write_b64 v212, v[16:17] offset:80
	ds_write_b64 v211, v[40:41] offset:88
	ds_write_b64 v212, v[42:43] offset:88
	ds_write_b64 v211, v[30:31] offset:96
	ds_write_b64 v212, v[6:7] offset:96
	ds_write_b64 v211, v[32:33] offset:104
	ds_write_b64 v212, v[4:5] offset:104
	ds_write_b64 v211, v[26:27] offset:112
	ds_write_b64 v212, v[8:9] offset:112
	ds_write_b64 v211, v[24:25] offset:120
	ds_write_b64 v212, v[2:3] offset:120
	v_mov_b32_e32 v2, v210
	s_waitcnt lgkmcnt(0)
	s_barrier
	s_nop 0
	v_and_b32_e32 v3, 15, v2
	v_lshlrev_b32_e32 v5, 3, v3
	v_cvt_f32_ubyte0_e32 v3, v3
	v_mul_f32_e32 v3, 0x3b000000, v3
	v_sin_f32_e32 v17, v3
	v_cos_f32_e32 v16, v3
	v_lshlrev_b32_e32 v2, 5, v2
	v_and_b32_e32 v2, 0xfffffe00, v2
	v_lshl_add_u32 v4, v2, 3, 0
	v_ashrrev_i32_e32 v2, 2, v2
	v_pk_mul_f32 v[72:73], v[16:17], 1.0 op_sel:[1,0] op_sel_hi:[1,0] neg_lo:[1,0]
	v_add3_u32 v2, v4, v5, v2
	v_pk_mul_f32 v[4:5], v[16:17], v[72:73] op_sel:[1,0] op_sel_hi:[0,1]
	v_pk_fma_f32 v[74:75], v[16:17], v[16:17], v[4:5] op_sel_hi:[1,0,1]
	v_add_u32_e32 v3, 0x800, v2
	v_pk_mul_f32 v[4:5], v[72:73], v[74:75] op_sel:[0,1] op_sel_hi:[1,0]
	v_pk_mul_f32 v[78:79], v[74:75], 1.0 op_sel:[1,0] op_sel_hi:[1,0] neg_lo:[1,0]
	v_pk_fma_f32 v[76:77], v[16:17], v[74:75], v[4:5] op_sel_hi:[0,1,1]
	v_pk_mul_f32 v[4:5], v[74:75], v[78:79] op_sel:[1,0] op_sel_hi:[0,1]
	v_pk_fma_f32 v[80:81], v[74:75], v[74:75], v[4:5] op_sel_hi:[1,0,1]
	v_pk_mul_f32 v[84:85], v[76:77], 1.0 op_sel:[1,0] op_sel_hi:[1,0] neg_lo:[1,0]
	v_pk_mul_f32 v[4:5], v[80:81], v[72:73] op_sel:[1,0] op_sel_hi:[0,1]
	v_pk_fma_f32 v[86:87], v[16:17], v[80:81], v[4:5] op_sel_hi:[0,1,1]
	v_pk_mul_f32 v[4:5], v[78:79], v[80:81] op_sel:[0,1] op_sel_hi:[1,0]
	v_pk_mul_f32 v[82:83], v[80:81], 1.0 op_sel:[1,0] op_sel_hi:[1,0] neg_lo:[1,0]
	v_pk_fma_f32 v[90:91], v[74:75], v[80:81], v[4:5] op_sel_hi:[0,1,1]
	v_pk_mul_f32 v[4:5], v[80:81], v[84:85] op_sel:[1,0] op_sel_hi:[0,1]
	v_pk_fma_f32 v[94:95], v[80:81], v[76:77], v[4:5] op_sel_hi:[1,0,1]
	v_pk_mul_f32 v[4:5], v[80:81], v[82:83] op_sel:[1,0] op_sel_hi:[0,1]
	v_pk_fma_f32 v[98:99], v[80:81], v[80:81], v[4:5] op_sel_hi:[1,0,1]
	v_pk_mul_f32 v[88:89], v[86:87], 1.0 op_sel:[1,0] op_sel_hi:[1,0] neg_lo:[1,0]
	v_pk_mul_f32 v[4:5], v[98:99], v[72:73] op_sel:[1,0] op_sel_hi:[0,1]
	v_pk_fma_f32 v[102:103], v[16:17], v[98:99], v[4:5] op_sel_hi:[0,1,1]
	v_pk_mul_f32 v[4:5], v[78:79], v[98:99] op_sel:[0,1] op_sel_hi:[1,0]
	v_pk_mul_f32 v[92:93], v[90:91], 1.0 op_sel:[1,0] op_sel_hi:[1,0] neg_lo:[1,0]
	v_pk_fma_f32 v[106:107], v[74:75], v[98:99], v[4:5] op_sel_hi:[0,1,1]
	v_pk_mul_f32 v[4:5], v[98:99], v[84:85] op_sel:[1,0] op_sel_hi:[0,1]
	v_pk_fma_f32 v[110:111], v[76:77], v[98:99], v[4:5] op_sel_hi:[0,1,1]
	v_pk_mul_f32 v[4:5], v[82:83], v[98:99] op_sel:[0,1] op_sel_hi:[1,0]
	v_pk_mul_f32 v[96:97], v[94:95], 1.0 op_sel:[1,0] op_sel_hi:[1,0] neg_lo:[1,0]
	v_pk_fma_f32 v[114:115], v[80:81], v[98:99], v[4:5] op_sel_hi:[0,1,1]
	v_pk_mul_f32 v[4:5], v[114:115], v[72:73] op_sel:[1,0] op_sel_hi:[0,1]
	v_pk_fma_f32 v[118:119], v[16:17], v[114:115], v[4:5] op_sel_hi:[0,1,1]
	v_pk_mul_f32 v[4:5], v[78:79], v[114:115] op_sel:[0,1] op_sel_hi:[1,0]
	v_pk_mul_f32 v[100:101], v[98:99], 1.0 op_sel:[1,0] op_sel_hi:[1,0] neg_lo:[1,0]
	v_pk_fma_f32 v[122:123], v[74:75], v[114:115], v[4:5] op_sel_hi:[0,1,1]
	v_pk_mul_f32 v[4:5], v[114:115], v[84:85] op_sel:[1,0] op_sel_hi:[0,1]
	v_pk_fma_f32 v[126:127], v[76:77], v[114:115], v[4:5] op_sel_hi:[0,1,1]
	v_pk_mul_f32 v[4:5], v[82:83], v[114:115] op_sel:[0,1] op_sel_hi:[1,0]
	v_pk_mul_f32 v[104:105], v[102:103], 1.0 op_sel:[1,0] op_sel_hi:[1,0] neg_lo:[1,0]
	v_pk_fma_f32 v[130:131], v[80:81], v[114:115], v[4:5] op_sel_hi:[0,1,1]
	v_pk_mul_f32 v[4:5], v[130:131], v[72:73] op_sel:[1,0] op_sel_hi:[0,1]
	v_pk_fma_f32 v[134:135], v[16:17], v[130:131], v[4:5] op_sel_hi:[0,1,1]
	v_pk_mul_f32 v[4:5], v[78:79], v[130:131] op_sel:[0,1] op_sel_hi:[1,0]
	v_pk_mul_f32 v[108:109], v[106:107], 1.0 op_sel:[1,0] op_sel_hi:[1,0] neg_lo:[1,0]
	v_pk_fma_f32 v[138:139], v[74:75], v[130:131], v[4:5] op_sel_hi:[0,1,1]
	v_pk_mul_f32 v[4:5], v[130:131], v[84:85] op_sel:[1,0] op_sel_hi:[0,1]
	v_pk_fma_f32 v[142:143], v[76:77], v[130:131], v[4:5] op_sel_hi:[0,1,1]
	v_pk_mul_f32 v[4:5], v[82:83], v[130:131] op_sel:[0,1] op_sel_hi:[1,0]
	v_pk_mul_f32 v[112:113], v[110:111], 1.0 op_sel:[1,0] op_sel_hi:[1,0] neg_lo:[1,0]
	v_pk_fma_f32 v[148:149], v[80:81], v[130:131], v[4:5] op_sel_hi:[0,1,1]
	v_pk_mul_f32 v[4:5], v[148:149], v[72:73] op_sel:[1,0] op_sel_hi:[0,1]
	v_pk_fma_f32 v[152:153], v[16:17], v[148:149], v[4:5] op_sel_hi:[0,1,1]
	v_pk_mul_f32 v[4:5], v[78:79], v[148:149] op_sel:[0,1] op_sel_hi:[1,0]
	v_pk_mul_f32 v[116:117], v[114:115], 1.0 op_sel:[1,0] op_sel_hi:[1,0] neg_lo:[1,0]
	v_pk_fma_f32 v[156:157], v[74:75], v[148:149], v[4:5] op_sel_hi:[0,1,1]
	v_pk_mul_f32 v[4:5], v[148:149], v[84:85] op_sel:[1,0] op_sel_hi:[0,1]
	v_pk_fma_f32 v[160:161], v[76:77], v[148:149], v[4:5] op_sel_hi:[0,1,1]
	v_pk_mul_f32 v[4:5], v[82:83], v[148:149] op_sel:[0,1] op_sel_hi:[1,0]
	v_pk_mul_f32 v[120:121], v[118:119], 1.0 op_sel:[1,0] op_sel_hi:[1,0] neg_lo:[1,0]
	v_pk_fma_f32 v[164:165], v[80:81], v[148:149], v[4:5] op_sel_hi:[0,1,1]
	v_pk_mul_f32 v[4:5], v[164:165], v[72:73] op_sel:[1,0] op_sel_hi:[0,1]
	v_pk_fma_f32 v[168:169], v[16:17], v[164:165], v[4:5] op_sel_hi:[0,1,1]
	v_pk_mul_f32 v[4:5], v[78:79], v[164:165] op_sel:[0,1] op_sel_hi:[1,0]
	v_pk_mul_f32 v[124:125], v[122:123], 1.0 op_sel:[1,0] op_sel_hi:[1,0] neg_lo:[1,0]
	v_pk_fma_f32 v[172:173], v[74:75], v[164:165], v[4:5] op_sel_hi:[0,1,1]
	v_pk_mul_f32 v[4:5], v[164:165], v[84:85] op_sel:[1,0] op_sel_hi:[0,1]
	v_pk_fma_f32 v[176:177], v[76:77], v[164:165], v[4:5] op_sel_hi:[0,1,1]
	v_pk_mul_f32 v[4:5], v[82:83], v[164:165] op_sel:[0,1] op_sel_hi:[1,0]
	v_pk_mul_f32 v[128:129], v[126:127], 1.0 op_sel:[1,0] op_sel_hi:[1,0] neg_lo:[1,0]
	v_pk_fma_f32 v[180:181], v[80:81], v[164:165], v[4:5] op_sel_hi:[0,1,1]
	v_pk_mul_f32 v[4:5], v[180:181], v[72:73] op_sel:[1,0] op_sel_hi:[0,1]
	v_pk_fma_f32 v[184:185], v[16:17], v[180:181], v[4:5] op_sel_hi:[0,1,1]
	v_pk_mul_f32 v[4:5], v[78:79], v[180:181] op_sel:[0,1] op_sel_hi:[1,0]
	v_pk_mul_f32 v[132:133], v[130:131], 1.0 op_sel:[1,0] op_sel_hi:[1,0] neg_lo:[1,0]
	v_pk_fma_f32 v[188:189], v[74:75], v[180:181], v[4:5] op_sel_hi:[0,1,1]
	v_pk_mul_f32 v[4:5], v[180:181], v[84:85] op_sel:[1,0] op_sel_hi:[0,1]
	v_pk_fma_f32 v[192:193], v[76:77], v[180:181], v[4:5] op_sel_hi:[0,1,1]
	ds_read2_b64 v[4:7], v2 offset1:16
	ds_read2_b64 v[8:11], v2 offset0:33 offset1:49
	ds_read2_b64 v[12:15], v2 offset0:66 offset1:82
	ds_read2_b64 v[20:23], v2 offset0:99 offset1:115
	ds_read2_b64 v[24:27], v2 offset0:132 offset1:148
	ds_read2_b64 v[28:31], v2 offset0:165 offset1:181
	ds_read2_b64 v[32:35], v2 offset0:198 offset1:214
	ds_read2_b64 v[36:39], v2 offset0:231 offset1:247
	ds_read2_b64 v[40:43], v3 offset0:8 offset1:24
	ds_read2_b64 v[44:47], v3 offset0:41 offset1:57
	ds_read2_b64 v[48:51], v3 offset0:74 offset1:90
	ds_read2_b64 v[52:55], v3 offset0:107 offset1:123
	ds_read2_b64 v[56:59], v3 offset0:140 offset1:156
	ds_read2_b64 v[60:63], v3 offset0:173 offset1:189
	ds_read2_b64 v[64:67], v3 offset0:206 offset1:222
	ds_read2_b64 v[68:71], v3 offset0:239 offset1:255
	s_waitcnt lgkmcnt(7)
	v_pk_mul_f32 v[72:73], v[72:73], v[40:41] op_sel:[0,1] op_sel_hi:[1,0]
	v_pk_mul_f32 v[136:137], v[134:135], 1.0 op_sel:[1,0] op_sel_hi:[1,0] neg_lo:[1,0]
	v_pk_fma_f32 v[16:17], v[16:17], v[40:41], v[72:73] op_sel_hi:[0,1,1]
	v_pk_mul_f32 v[40:41], v[24:25], v[78:79] op_sel:[1,0] op_sel_hi:[0,1]
	v_pk_fma_f32 v[24:25], v[24:25], v[74:75], v[40:41] op_sel_hi:[1,0,1]
	s_waitcnt lgkmcnt(3)
	v_pk_mul_f32 v[40:41], v[56:57], v[84:85] op_sel:[1,0] op_sel_hi:[0,1]
	v_pk_fma_f32 v[40:41], v[76:77], v[56:57], v[40:41] op_sel_hi:[0,1,1]
	v_pk_mul_f32 v[56:57], v[12:13], v[82:83] op_sel:[1,0] op_sel_hi:[0,1]
	v_pk_fma_f32 v[12:13], v[12:13], v[80:81], v[56:57] op_sel_hi:[1,0,1]
	v_pk_mul_f32 v[56:57], v[88:89], v[48:49] op_sel:[0,1] op_sel_hi:[1,0]
	v_pk_mul_f32 v[140:141], v[138:139], 1.0 op_sel:[1,0] op_sel_hi:[1,0] neg_lo:[1,0]
	v_pk_fma_f32 v[48:49], v[86:87], v[48:49], v[56:57] op_sel_hi:[0,1,1]
	v_pk_mul_f32 v[56:57], v[32:33], v[92:93] op_sel:[1,0] op_sel_hi:[0,1]
	v_pk_fma_f32 v[32:33], v[32:33], v[90:91], v[56:57] op_sel_hi:[1,0,1]
	s_waitcnt lgkmcnt(1)
	v_pk_mul_f32 v[56:57], v[64:65], v[96:97] op_sel:[1,0] op_sel_hi:[0,1]
	v_pk_fma_f32 v[56:57], v[94:95], v[64:65], v[56:57] op_sel_hi:[0,1,1]
	v_pk_mul_f32 v[64:65], v[8:9], v[100:101] op_sel:[1,0] op_sel_hi:[0,1]
	v_pk_fma_f32 v[8:9], v[8:9], v[98:99], v[64:65] op_sel_hi:[1,0,1]
	v_pk_mul_f32 v[64:65], v[44:45], v[104:105] op_sel:[1,0] op_sel_hi:[0,1]
	v_pk_fma_f32 v[44:45], v[44:45], v[102:103], v[64:65] op_sel_hi:[1,0,1]
	v_pk_mul_f32 v[64:65], v[28:29], v[108:109] op_sel:[1,0] op_sel_hi:[0,1]
	v_pk_fma_f32 v[28:29], v[28:29], v[106:107], v[64:65] op_sel_hi:[1,0,1]
	v_pk_mul_f32 v[64:65], v[112:113], v[60:61] op_sel:[0,1] op_sel_hi:[1,0]
	v_xor_b32_e32 v144, 0x80000000, v143
	v_pk_fma_f32 v[60:61], v[110:111], v[60:61], v[64:65] op_sel_hi:[0,1,1]
	v_pk_mul_f32 v[64:65], v[20:21], v[116:117] op_sel:[1,0] op_sel_hi:[0,1]
	v_pk_fma_f32 v[20:21], v[20:21], v[114:115], v[64:65] op_sel_hi:[1,0,1]
	v_pk_mul_f32 v[64:65], v[52:53], v[120:121] op_sel:[1,0] op_sel_hi:[0,1]
	v_pk_fma_f32 v[52:53], v[52:53], v[118:119], v[64:65] op_sel_hi:[1,0,1]
	v_pk_mul_f32 v[64:65], v[36:37], v[124:125] op_sel:[1,0] op_sel_hi:[0,1]
	v_pk_fma_f32 v[36:37], v[36:37], v[122:123], v[64:65] op_sel_hi:[1,0,1]
	s_waitcnt lgkmcnt(0)
	v_pk_mul_f32 v[64:65], v[128:129], v[68:69] op_sel:[0,1] op_sel_hi:[1,0]
	v_mov_b32_e32 v145, v143
	v_pk_fma_f32 v[64:65], v[126:127], v[68:69], v[64:65] op_sel_hi:[0,1,1]
	v_pk_mul_f32 v[68:69], v[6:7], v[132:133] op_sel:[1,0] op_sel_hi:[0,1]
	v_pk_fma_f32 v[6:7], v[6:7], v[130:131], v[68:69] op_sel_hi:[1,0,1]
	v_pk_mul_f32 v[68:69], v[42:43], v[136:137] op_sel:[1,0] op_sel_hi:[0,1]
	v_pk_fma_f32 v[42:43], v[42:43], v[134:135], v[68:69] op_sel_hi:[1,0,1]
	v_pk_mul_f32 v[68:69], v[26:27], v[140:141] op_sel:[1,0] op_sel_hi:[0,1]
	v_pk_mul_f32 v[150:151], v[148:149], 1.0 op_sel:[1,0] op_sel_hi:[1,0] neg_lo:[1,0]
	v_pk_fma_f32 v[26:27], v[26:27], v[138:139], v[68:69] op_sel_hi:[1,0,1]
	v_pk_mul_f32 v[68:69], v[58:59], v[144:145] op_sel:[1,0] op_sel_hi:[0,1]
	v_pk_mul_f32 v[154:155], v[152:153], 1.0 op_sel:[1,0] op_sel_hi:[1,0] neg_lo:[1,0]
	v_pk_fma_f32 v[58:59], v[58:59], v[142:143], v[68:69] op_sel_hi:[1,0,1]
	v_pk_mul_f32 v[68:69], v[14:15], v[150:151] op_sel:[1,0] op_sel_hi:[0,1]
	v_pk_mul_f32 v[158:159], v[156:157], 1.0 op_sel:[1,0] op_sel_hi:[1,0] neg_lo:[1,0]
	v_pk_fma_f32 v[14:15], v[14:15], v[148:149], v[68:69] op_sel_hi:[1,0,1]
	v_pk_mul_f32 v[68:69], v[50:51], v[154:155] op_sel:[1,0] op_sel_hi:[0,1]
	v_pk_mul_f32 v[162:163], v[160:161], 1.0 op_sel:[1,0] op_sel_hi:[1,0] neg_lo:[1,0]
	v_pk_fma_f32 v[50:51], v[50:51], v[152:153], v[68:69] op_sel_hi:[1,0,1]
	v_pk_mul_f32 v[68:69], v[34:35], v[158:159] op_sel:[1,0] op_sel_hi:[0,1]
	v_pk_mul_f32 v[166:167], v[164:165], 1.0 op_sel:[1,0] op_sel_hi:[1,0] neg_lo:[1,0]
	v_pk_fma_f32 v[34:35], v[34:35], v[156:157], v[68:69] op_sel_hi:[1,0,1]
	v_pk_mul_f32 v[68:69], v[162:163], v[66:67] op_sel:[0,1] op_sel_hi:[1,0]
	v_pk_mul_f32 v[170:171], v[168:169], 1.0 op_sel:[1,0] op_sel_hi:[1,0] neg_lo:[1,0]
	v_pk_fma_f32 v[66:67], v[160:161], v[66:67], v[68:69] op_sel_hi:[0,1,1]
	v_pk_mul_f32 v[68:69], v[10:11], v[166:167] op_sel:[1,0] op_sel_hi:[0,1]
	v_pk_mul_f32 v[174:175], v[172:173], 1.0 op_sel:[1,0] op_sel_hi:[1,0] neg_lo:[1,0]
	v_pk_fma_f32 v[10:11], v[10:11], v[164:165], v[68:69] op_sel_hi:[1,0,1]
	v_pk_mul_f32 v[68:69], v[46:47], v[170:171] op_sel:[1,0] op_sel_hi:[0,1]
	v_pk_mul_f32 v[178:179], v[176:177], 1.0 op_sel:[1,0] op_sel_hi:[1,0] neg_lo:[1,0]
	v_pk_fma_f32 v[46:47], v[46:47], v[168:169], v[68:69] op_sel_hi:[1,0,1]
	v_pk_mul_f32 v[68:69], v[30:31], v[174:175] op_sel:[1,0] op_sel_hi:[0,1]
	v_pk_mul_f32 v[182:183], v[180:181], 1.0 op_sel:[1,0] op_sel_hi:[1,0] neg_lo:[1,0]
	v_pk_fma_f32 v[30:31], v[30:31], v[172:173], v[68:69] op_sel_hi:[1,0,1]
	v_pk_mul_f32 v[68:69], v[62:63], v[178:179] op_sel:[1,0] op_sel_hi:[0,1]
	v_pk_mul_f32 v[186:187], v[184:185], 1.0 op_sel:[1,0] op_sel_hi:[1,0] neg_lo:[1,0]
	v_pk_fma_f32 v[62:63], v[62:63], v[176:177], v[68:69] op_sel_hi:[1,0,1]
	v_pk_mul_f32 v[68:69], v[22:23], v[182:183] op_sel:[1,0] op_sel_hi:[0,1]
	v_pk_mul_f32 v[190:191], v[188:189], 1.0 op_sel:[1,0] op_sel_hi:[1,0] neg_lo:[1,0]
	v_pk_fma_f32 v[22:23], v[22:23], v[180:181], v[68:69] op_sel_hi:[1,0,1]
	v_pk_mul_f32 v[68:69], v[54:55], v[186:187] op_sel:[1,0] op_sel_hi:[0,1]
	v_pk_mul_f32 v[194:195], v[192:193], 1.0 op_sel:[1,0] op_sel_hi:[1,0] neg_lo:[1,0]
	v_pk_fma_f32 v[54:55], v[54:55], v[184:185], v[68:69] op_sel_hi:[1,0,1]
	v_pk_mul_f32 v[68:69], v[38:39], v[190:191] op_sel:[1,0] op_sel_hi:[0,1]
	v_pk_fma_f32 v[38:39], v[38:39], v[188:189], v[68:69] op_sel_hi:[1,0,1]
	v_pk_mul_f32 v[68:69], v[70:71], v[194:195] op_sel:[1,0] op_sel_hi:[0,1]
	v_pk_fma_f32 v[68:69], v[70:71], v[192:193], v[68:69] op_sel_hi:[1,0,1]
	v_pk_add_f32 v[70:71], v[4:5], v[6:7]
	v_pk_add_f32 v[4:5], v[4:5], v[6:7] neg_lo:[0,1] neg_hi:[0,1]
	v_pk_add_f32 v[6:7], v[8:9], v[10:11]
	v_pk_add_f32 v[8:9], v[8:9], v[10:11] neg_lo:[0,1] neg_hi:[0,1]
	v_pk_add_f32 v[10:11], v[12:13], v[14:15]
	v_pk_add_f32 v[12:13], v[12:13], v[14:15] neg_lo:[0,1] neg_hi:[0,1]
	v_pk_add_f32 v[14:15], v[20:21], v[22:23]
	v_pk_add_f32 v[20:21], v[20:21], v[22:23] neg_lo:[0,1] neg_hi:[0,1]
	v_pk_add_f32 v[22:23], v[24:25], v[26:27]
	v_pk_add_f32 v[24:25], v[24:25], v[26:27] neg_lo:[0,1] neg_hi:[0,1]
	v_pk_add_f32 v[26:27], v[28:29], v[30:31]
	v_pk_add_f32 v[28:29], v[28:29], v[30:31] neg_lo:[0,1] neg_hi:[0,1]
	v_pk_add_f32 v[30:31], v[32:33], v[34:35]
	v_pk_add_f32 v[32:33], v[32:33], v[34:35] neg_lo:[0,1] neg_hi:[0,1]
	v_pk_add_f32 v[34:35], v[36:37], v[38:39]
	v_pk_add_f32 v[36:37], v[36:37], v[38:39] neg_lo:[0,1] neg_hi:[0,1]
	v_pk_add_f32 v[38:39], v[16:17], v[42:43]
	v_pk_add_f32 v[16:17], v[16:17], v[42:43] neg_lo:[0,1] neg_hi:[0,1]
	v_pk_add_f32 v[42:43], v[44:45], v[46:47]
	v_pk_add_f32 v[44:45], v[44:45], v[46:47] neg_lo:[0,1] neg_hi:[0,1]
	v_pk_add_f32 v[46:47], v[48:49], v[50:51]
	v_pk_add_f32 v[48:49], v[48:49], v[50:51] neg_lo:[0,1] neg_hi:[0,1]
	v_pk_add_f32 v[50:51], v[52:53], v[54:55]
	v_pk_add_f32 v[52:53], v[52:53], v[54:55] neg_lo:[0,1] neg_hi:[0,1]
	v_pk_add_f32 v[54:55], v[40:41], v[58:59]
	v_pk_add_f32 v[40:41], v[40:41], v[58:59] neg_lo:[0,1] neg_hi:[0,1]
	v_pk_add_f32 v[58:59], v[60:61], v[62:63]
	v_pk_add_f32 v[60:61], v[60:61], v[62:63] neg_lo:[0,1] neg_hi:[0,1]
	v_pk_add_f32 v[62:63], v[56:57], v[66:67]
	v_pk_add_f32 v[56:57], v[56:57], v[66:67] neg_lo:[0,1] neg_hi:[0,1]
	v_pk_add_f32 v[66:67], v[64:65], v[68:69]
	v_pk_add_f32 v[64:65], v[64:65], v[68:69] neg_lo:[0,1] neg_hi:[0,1]
	v_pk_add_f32 v[68:69], v[70:71], v[6:7]
	v_pk_add_f32 v[6:7], v[70:71], v[6:7] neg_lo:[0,1] neg_hi:[0,1]
	v_pk_mul_f32 v[70:71], v[8:9], 1.0 op_sel:[1,0] op_sel_hi:[0,0] neg_lo:[1,0]
	v_pk_add_f32 v[8:9], v[4:5], v[70:71]
	v_pk_add_f32 v[4:5], v[4:5], v[70:71] neg_lo:[0,1] neg_hi:[0,1]
	v_pk_add_f32 v[70:71], v[10:11], v[14:15]
	v_pk_add_f32 v[10:11], v[10:11], v[14:15] neg_lo:[0,1] neg_hi:[0,1]
	v_pk_mul_f32 v[14:15], v[20:21], 1.0 op_sel:[1,0] op_sel_hi:[0,0] neg_lo:[1,0]
	v_pk_add_f32 v[20:21], v[12:13], v[14:15]
	v_pk_add_f32 v[12:13], v[12:13], v[14:15] neg_lo:[0,1] neg_hi:[0,1]
	v_pk_add_f32 v[14:15], v[22:23], v[26:27]
	v_pk_add_f32 v[22:23], v[22:23], v[26:27] neg_lo:[0,1] neg_hi:[0,1]
	v_pk_mul_f32 v[26:27], v[28:29], 1.0 op_sel:[1,0] op_sel_hi:[0,0] neg_lo:[1,0]
	v_pk_add_f32 v[28:29], v[24:25], v[26:27]
	v_pk_add_f32 v[24:25], v[24:25], v[26:27] neg_lo:[0,1] neg_hi:[0,1]
	v_pk_add_f32 v[26:27], v[30:31], v[34:35]
	v_pk_add_f32 v[30:31], v[30:31], v[34:35] neg_lo:[0,1] neg_hi:[0,1]
	v_pk_mul_f32 v[34:35], v[36:37], 1.0 op_sel:[1,0] op_sel_hi:[0,0] neg_lo:[1,0]
	v_pk_add_f32 v[36:37], v[32:33], v[34:35]
	v_pk_add_f32 v[32:33], v[32:33], v[34:35] neg_lo:[0,1] neg_hi:[0,1]
	v_pk_add_f32 v[34:35], v[38:39], v[42:43]
	v_pk_add_f32 v[38:39], v[38:39], v[42:43] neg_lo:[0,1] neg_hi:[0,1]
	v_pk_mul_f32 v[42:43], v[44:45], 1.0 op_sel:[1,0] op_sel_hi:[0,0] neg_lo:[1,0]
	v_pk_add_f32 v[44:45], v[16:17], v[42:43]
	v_pk_add_f32 v[16:17], v[16:17], v[42:43] neg_lo:[0,1] neg_hi:[0,1]
	v_pk_add_f32 v[42:43], v[46:47], v[50:51]
	v_pk_add_f32 v[46:47], v[46:47], v[50:51] neg_lo:[0,1] neg_hi:[0,1]
	v_pk_mul_f32 v[50:51], v[52:53], 1.0 op_sel:[1,0] op_sel_hi:[0,0] neg_lo:[1,0]
	v_pk_add_f32 v[52:53], v[48:49], v[50:51]
	v_pk_add_f32 v[48:49], v[48:49], v[50:51] neg_lo:[0,1] neg_hi:[0,1]
	v_pk_add_f32 v[50:51], v[54:55], v[58:59]
	v_pk_add_f32 v[54:55], v[54:55], v[58:59] neg_lo:[0,1] neg_hi:[0,1]
	v_pk_mul_f32 v[58:59], v[60:61], 1.0 op_sel:[1,0] op_sel_hi:[0,0] neg_lo:[1,0]
	v_pk_add_f32 v[60:61], v[40:41], v[58:59]
	v_pk_add_f32 v[40:41], v[40:41], v[58:59] neg_lo:[0,1] neg_hi:[0,1]
	v_pk_add_f32 v[58:59], v[62:63], v[66:67]
	v_pk_add_f32 v[62:63], v[62:63], v[66:67] neg_lo:[0,1] neg_hi:[0,1]
	v_pk_mul_f32 v[66:67], v[64:65], 1.0 op_sel:[1,0] op_sel_hi:[0,0] neg_lo:[1,0]
	v_pk_add_f32 v[64:65], v[56:57], v[66:67]
	v_pk_add_f32 v[56:57], v[56:57], v[66:67] neg_lo:[0,1] neg_hi:[0,1]
	v_pk_add_f32 v[66:67], v[68:69], v[70:71]
	v_pk_add_f32 v[68:69], v[68:69], v[70:71] neg_lo:[0,1] neg_hi:[0,1]
	v_pk_mul_f32 v[70:71], v[20:21], s[78:79]
	s_nop 0
	v_pk_fma_f32 v[20:21], s[0:1], v[20:21], v[70:71] op_sel:[0,0,1] op_sel_hi:[0,1,0]
	v_pk_add_f32 v[70:71], v[8:9], v[20:21]
	v_pk_add_f32 v[8:9], v[8:9], v[20:21] neg_lo:[0,1] neg_hi:[0,1]
	v_pk_mul_f32 v[20:21], v[10:11], 1.0 op_sel:[1,0] op_sel_hi:[0,0] neg_lo:[1,0]
	v_pk_add_f32 v[10:11], v[6:7], v[20:21]
	v_pk_add_f32 v[6:7], v[6:7], v[20:21] neg_lo:[0,1] neg_hi:[0,1]
	v_pk_mul_f32 v[20:21], v[12:13], s[78:79]
	s_nop 0
	v_pk_fma_f32 v[12:13], s[0:1], v[12:13], v[20:21] op_sel:[0,0,1] op_sel_hi:[0,1,0] neg_lo:[0,1,0] neg_hi:[0,1,0]
	v_pk_add_f32 v[20:21], v[4:5], v[12:13]
	v_pk_add_f32 v[4:5], v[4:5], v[12:13] neg_lo:[0,1] neg_hi:[0,1]
	v_pk_add_f32 v[12:13], v[14:15], v[26:27]
	v_pk_add_f32 v[14:15], v[14:15], v[26:27] neg_lo:[0,1] neg_hi:[0,1]
	v_pk_mul_f32 v[26:27], v[36:37], s[78:79]
	s_nop 0
	v_pk_fma_f32 v[26:27], s[0:1], v[36:37], v[26:27] op_sel:[0,0,1] op_sel_hi:[0,1,0]
	v_pk_add_f32 v[36:37], v[28:29], v[26:27]
	v_pk_add_f32 v[26:27], v[28:29], v[26:27] neg_lo:[0,1] neg_hi:[0,1]
	v_pk_mul_f32 v[28:29], v[30:31], 1.0 op_sel:[1,0] op_sel_hi:[0,0] neg_lo:[1,0]
	v_pk_add_f32 v[30:31], v[22:23], v[28:29]
	v_pk_add_f32 v[22:23], v[22:23], v[28:29] neg_lo:[0,1] neg_hi:[0,1]
	v_pk_mul_f32 v[28:29], v[32:33], s[78:79]
	s_nop 0
	v_pk_fma_f32 v[28:29], s[0:1], v[32:33], v[28:29] op_sel:[0,0,1] op_sel_hi:[0,1,0] neg_lo:[0,1,0] neg_hi:[0,1,0]
	v_pk_add_f32 v[32:33], v[24:25], v[28:29]
	v_pk_add_f32 v[24:25], v[24:25], v[28:29] neg_lo:[0,1] neg_hi:[0,1]
	v_pk_add_f32 v[28:29], v[34:35], v[42:43]
	v_pk_add_f32 v[34:35], v[34:35], v[42:43] neg_lo:[0,1] neg_hi:[0,1]
	v_pk_mul_f32 v[42:43], v[52:53], s[78:79]
	s_nop 0
	v_pk_fma_f32 v[42:43], s[0:1], v[52:53], v[42:43] op_sel:[0,0,1] op_sel_hi:[0,1,0]
	v_pk_add_f32 v[52:53], v[44:45], v[42:43]
	v_pk_add_f32 v[42:43], v[44:45], v[42:43] neg_lo:[0,1] neg_hi:[0,1]
	v_pk_mul_f32 v[44:45], v[46:47], 1.0 op_sel:[1,0] op_sel_hi:[0,0] neg_lo:[1,0]
	v_pk_add_f32 v[46:47], v[38:39], v[44:45]
	v_pk_add_f32 v[38:39], v[38:39], v[44:45] neg_lo:[0,1] neg_hi:[0,1]
	v_pk_mul_f32 v[44:45], v[48:49], s[78:79]
	s_nop 0
	v_pk_fma_f32 v[44:45], s[0:1], v[48:49], v[44:45] op_sel:[0,0,1] op_sel_hi:[0,1,0] neg_lo:[0,1,0] neg_hi:[0,1,0]
	v_pk_add_f32 v[48:49], v[16:17], v[44:45]
	v_pk_add_f32 v[16:17], v[16:17], v[44:45] neg_lo:[0,1] neg_hi:[0,1]
	v_pk_add_f32 v[44:45], v[50:51], v[58:59]
	v_pk_add_f32 v[50:51], v[50:51], v[58:59] neg_lo:[0,1] neg_hi:[0,1]
	v_pk_mul_f32 v[58:59], v[64:65], s[78:79]
	s_nop 0
	v_pk_fma_f32 v[58:59], s[0:1], v[64:65], v[58:59] op_sel:[0,0,1] op_sel_hi:[0,1,0]
	v_pk_add_f32 v[64:65], v[60:61], v[58:59]
	v_pk_add_f32 v[58:59], v[60:61], v[58:59] neg_lo:[0,1] neg_hi:[0,1]
	v_pk_mul_f32 v[60:61], v[62:63], 1.0 op_sel:[1,0] op_sel_hi:[0,0] neg_lo:[1,0]
	v_pk_add_f32 v[62:63], v[54:55], v[60:61]
	v_pk_add_f32 v[54:55], v[54:55], v[60:61] neg_lo:[0,1] neg_hi:[0,1]
	v_pk_mul_f32 v[60:61], v[56:57], s[78:79]
	s_nop 0
	v_pk_fma_f32 v[56:57], s[0:1], v[56:57], v[60:61] op_sel:[0,0,1] op_sel_hi:[0,1,0] neg_lo:[0,1,0] neg_hi:[0,1,0]
	v_pk_add_f32 v[60:61], v[40:41], v[56:57]
	v_pk_add_f32 v[40:41], v[40:41], v[56:57] neg_lo:[0,1] neg_hi:[0,1]
	v_pk_add_f32 v[56:57], v[66:67], v[12:13]
	v_pk_add_f32 v[12:13], v[66:67], v[12:13] neg_lo:[0,1] neg_hi:[0,1]
	v_pk_mul_f32 v[66:67], v[36:37], s[80:81]
	s_nop 0
	v_pk_fma_f32 v[36:37], s[16:17], v[36:37], v[66:67] op_sel:[0,0,1] op_sel_hi:[0,1,0]
	v_pk_add_f32 v[66:67], v[70:71], v[36:37]
	v_pk_add_f32 v[36:37], v[70:71], v[36:37] neg_lo:[0,1] neg_hi:[0,1]
	v_pk_mul_f32 v[70:71], v[30:31], s[78:79]
	s_nop 0
	v_pk_fma_f32 v[30:31], s[0:1], v[30:31], v[70:71] op_sel:[0,0,1] op_sel_hi:[0,1,0]
	v_pk_add_f32 v[70:71], v[10:11], v[30:31]
	v_pk_add_f32 v[10:11], v[10:11], v[30:31] neg_lo:[0,1] neg_hi:[0,1]
	v_pk_mul_f32 v[30:31], v[32:33], s[16:17]
	s_nop 0
	v_pk_fma_f32 v[30:31], s[82:83], v[32:33], v[30:31] op_sel:[0,0,1] op_sel_hi:[0,1,0]
	v_pk_add_f32 v[32:33], v[20:21], v[30:31]
	v_pk_add_f32 v[20:21], v[20:21], v[30:31] neg_lo:[0,1] neg_hi:[0,1]
	v_pk_mul_f32 v[30:31], v[14:15], 1.0 op_sel:[1,0] op_sel_hi:[0,0] neg_lo:[1,0]
	v_pk_add_f32 v[14:15], v[68:69], v[30:31]
	v_pk_add_f32 v[30:31], v[68:69], v[30:31] neg_lo:[0,1] neg_hi:[0,1]
	v_pk_mul_f32 v[68:69], v[26:27], s[16:17]
	s_nop 0
	v_pk_fma_f32 v[26:27], s[82:83], v[26:27], v[68:69] op_sel:[0,0,1] op_sel_hi:[0,1,0] neg_lo:[0,1,0] neg_hi:[0,1,0]
	v_pk_add_f32 v[68:69], v[8:9], v[26:27]
	v_pk_add_f32 v[8:9], v[8:9], v[26:27] neg_lo:[0,1] neg_hi:[0,1]
	v_pk_mul_f32 v[26:27], v[22:23], s[78:79]
	s_nop 0
	v_pk_fma_f32 v[22:23], s[0:1], v[22:23], v[26:27] op_sel:[0,0,1] op_sel_hi:[0,1,0] neg_lo:[0,1,0] neg_hi:[0,1,0]
	v_pk_add_f32 v[26:27], v[6:7], v[22:23]
	v_pk_add_f32 v[6:7], v[6:7], v[22:23] neg_lo:[0,1] neg_hi:[0,1]
	v_pk_mul_f32 v[22:23], v[24:25], s[80:81]
	s_nop 0
	v_pk_fma_f32 v[22:23], s[16:17], v[24:25], v[22:23] op_sel:[0,0,1] op_sel_hi:[0,1,0] neg_lo:[0,1,0] neg_hi:[0,1,0]
	v_pk_add_f32 v[24:25], v[4:5], v[22:23]
	v_pk_add_f32 v[4:5], v[4:5], v[22:23] neg_lo:[0,1] neg_hi:[0,1]
	v_pk_add_f32 v[22:23], v[28:29], v[44:45]
	v_pk_add_f32 v[28:29], v[28:29], v[44:45] neg_lo:[0,1] neg_hi:[0,1]
	v_pk_mul_f32 v[44:45], v[64:65], s[80:81]
	s_nop 0
	v_pk_fma_f32 v[44:45], s[16:17], v[64:65], v[44:45] op_sel:[0,0,1] op_sel_hi:[0,1,0]
	v_pk_add_f32 v[64:65], v[52:53], v[44:45]
	v_pk_add_f32 v[44:45], v[52:53], v[44:45] neg_lo:[0,1] neg_hi:[0,1]
	v_pk_mul_f32 v[52:53], v[62:63], s[78:79]
	s_nop 0
	v_pk_fma_f32 v[52:53], s[0:1], v[62:63], v[52:53] op_sel:[0,0,1] op_sel_hi:[0,1,0]
	v_pk_add_f32 v[62:63], v[46:47], v[52:53]
	v_pk_add_f32 v[46:47], v[46:47], v[52:53] neg_lo:[0,1] neg_hi:[0,1]
	v_pk_mul_f32 v[52:53], v[60:61], s[16:17]
	s_nop 0
	v_pk_fma_f32 v[52:53], s[82:83], v[60:61], v[52:53] op_sel:[0,0,1] op_sel_hi:[0,1,0]
	v_pk_add_f32 v[60:61], v[48:49], v[52:53]
	v_pk_add_f32 v[48:49], v[48:49], v[52:53] neg_lo:[0,1] neg_hi:[0,1]
	v_pk_mul_f32 v[52:53], v[50:51], 1.0 op_sel:[1,0] op_sel_hi:[0,0] neg_lo:[1,0]
	v_pk_add_f32 v[50:51], v[34:35], v[52:53]
	v_pk_add_f32 v[34:35], v[34:35], v[52:53] neg_lo:[0,1] neg_hi:[0,1]
	v_pk_mul_f32 v[52:53], v[58:59], s[16:17]
	s_nop 0
	v_pk_fma_f32 v[52:53], s[82:83], v[58:59], v[52:53] op_sel:[0,0,1] op_sel_hi:[0,1,0] neg_lo:[0,1,0] neg_hi:[0,1,0]
	v_pk_add_f32 v[58:59], v[42:43], v[52:53]
	v_pk_add_f32 v[42:43], v[42:43], v[52:53] neg_lo:[0,1] neg_hi:[0,1]
	v_pk_mul_f32 v[52:53], v[54:55], s[78:79]
	s_nop 0
	v_pk_fma_f32 v[52:53], s[0:1], v[54:55], v[52:53] op_sel:[0,0,1] op_sel_hi:[0,1,0] neg_lo:[0,1,0] neg_hi:[0,1,0]
	v_pk_add_f32 v[54:55], v[38:39], v[52:53]
	v_pk_add_f32 v[38:39], v[38:39], v[52:53] neg_lo:[0,1] neg_hi:[0,1]
	v_pk_mul_f32 v[52:53], v[40:41], s[80:81]
	s_nop 0
	v_pk_fma_f32 v[40:41], s[16:17], v[40:41], v[52:53] op_sel:[0,0,1] op_sel_hi:[0,1,0] neg_lo:[0,1,0] neg_hi:[0,1,0]
	v_pk_add_f32 v[52:53], v[16:17], v[40:41]
	v_pk_add_f32 v[16:17], v[16:17], v[40:41] neg_lo:[0,1] neg_hi:[0,1]
	v_pk_add_f32 v[40:41], v[56:57], v[22:23]
	v_pk_add_f32 v[22:23], v[56:57], v[22:23] neg_lo:[0,1] neg_hi:[0,1]
	v_pk_mul_f32 v[56:57], v[64:65], s[88:89]
	s_nop 0
	v_pk_fma_f32 v[56:57], v[64:65], s[8:9], v[56:57] op_sel:[0,0,1] op_sel_hi:[1,0,0]
	s_mov_b32 s9, s42
	v_pk_add_f32 v[64:65], v[66:67], v[56:57]
	v_pk_add_f32 v[56:57], v[66:67], v[56:57] neg_lo:[0,1] neg_hi:[0,1]
	v_pk_mul_f32 v[66:67], v[62:63], s[80:81]
	s_nop 0
	v_pk_fma_f32 v[62:63], s[16:17], v[62:63], v[66:67] op_sel:[0,0,1] op_sel_hi:[0,1,0]
	v_pk_add_f32 v[66:67], v[70:71], v[62:63]
	v_pk_add_f32 v[62:63], v[70:71], v[62:63] neg_lo:[0,1] neg_hi:[0,1]
	v_pk_mul_f32 v[70:71], v[60:61], s[62:63]
	s_nop 0
	v_pk_fma_f32 v[60:61], v[60:61], s[24:25], v[70:71] op_sel:[0,0,1] op_sel_hi:[1,0,0]
	s_mov_b32 s25, s38
	v_pk_add_f32 v[70:71], v[32:33], v[60:61]
	v_pk_add_f32 v[32:33], v[32:33], v[60:61] neg_lo:[0,1] neg_hi:[0,1]
	v_pk_mul_f32 v[60:61], v[50:51], s[78:79]
	s_nop 0
	v_pk_fma_f32 v[50:51], s[0:1], v[50:51], v[60:61] op_sel:[0,0,1] op_sel_hi:[0,1,0]
	v_pk_add_f32 v[60:61], v[14:15], v[50:51]
	v_pk_add_f32 v[14:15], v[14:15], v[50:51] neg_lo:[0,1] neg_hi:[0,1]
	v_pk_mul_f32 v[50:51], v[58:59], s[24:25]
	s_nop 0
	v_pk_fma_f32 v[50:51], s[84:85], v[58:59], v[50:51] op_sel:[0,0,1] op_sel_hi:[0,1,0]
	v_pk_add_f32 v[58:59], v[68:69], v[50:51]
	v_pk_add_f32 v[50:51], v[68:69], v[50:51] neg_lo:[0,1] neg_hi:[0,1]
	v_pk_mul_f32 v[68:69], v[54:55], s[16:17]
	s_nop 0
	v_pk_fma_f32 v[54:55], s[82:83], v[54:55], v[68:69] op_sel:[0,0,1] op_sel_hi:[0,1,0]
	v_pk_add_f32 v[68:69], v[26:27], v[54:55]
	v_pk_add_f32 v[26:27], v[26:27], v[54:55] neg_lo:[0,1] neg_hi:[0,1]
	v_pk_mul_f32 v[54:55], v[52:53], s[8:9]
	s_nop 0
	v_pk_fma_f32 v[52:53], s[86:87], v[52:53], v[54:55] op_sel:[0,0,1] op_sel_hi:[0,1,0]
	v_pk_add_f32 v[54:55], v[24:25], v[52:53]
	v_pk_add_f32 v[24:25], v[24:25], v[52:53] neg_lo:[0,1] neg_hi:[0,1]
	v_pk_mul_f32 v[52:53], v[28:29], 1.0 op_sel:[1,0] op_sel_hi:[0,0] neg_lo:[1,0]
	v_pk_add_f32 v[28:29], v[12:13], v[52:53]
	v_pk_add_f32 v[12:13], v[12:13], v[52:53] neg_lo:[0,1] neg_hi:[0,1]
	v_pk_mul_f32 v[52:53], v[44:45], s[8:9]
	s_nop 0
	v_pk_fma_f32 v[44:45], s[86:87], v[44:45], v[52:53] op_sel:[0,0,1] op_sel_hi:[0,1,0] neg_lo:[0,1,0] neg_hi:[0,1,0]
	v_pk_add_f32 v[52:53], v[36:37], v[44:45]
	v_pk_add_f32 v[36:37], v[36:37], v[44:45] neg_lo:[0,1] neg_hi:[0,1]
	v_pk_mul_f32 v[44:45], v[46:47], s[16:17]
	s_nop 0
	v_pk_fma_f32 v[44:45], s[82:83], v[46:47], v[44:45] op_sel:[0,0,1] op_sel_hi:[0,1,0] neg_lo:[0,1,0] neg_hi:[0,1,0]
	v_pk_add_f32 v[46:47], v[10:11], v[44:45]
	v_pk_add_f32 v[10:11], v[10:11], v[44:45] neg_lo:[0,1] neg_hi:[0,1]
	v_pk_mul_f32 v[44:45], v[48:49], s[24:25]
	s_nop 0
	v_pk_fma_f32 v[44:45], s[84:85], v[48:49], v[44:45] op_sel:[0,0,1] op_sel_hi:[0,1,0] neg_lo:[0,1,0] neg_hi:[0,1,0]
	v_pk_add_f32 v[48:49], v[20:21], v[44:45]
	v_pk_add_f32 v[20:21], v[20:21], v[44:45] neg_lo:[0,1] neg_hi:[0,1]
	v_pk_mul_f32 v[44:45], v[34:35], s[78:79]
	s_nop 0
	v_pk_fma_f32 v[34:35], v[34:35], s[0:1], v[44:45] op_sel:[0,0,1] op_sel_hi:[1,0,0] neg_lo:[1,0,0] neg_hi:[1,0,0]
	s_lshl_b64 s[0:1], s[72:73], 2
	v_pk_add_f32 v[44:45], v[30:31], v[34:35]
	v_pk_add_f32 v[30:31], v[30:31], v[34:35] neg_lo:[0,1] neg_hi:[0,1]
	v_pk_mul_f32 v[34:35], v[42:43], s[62:63]
	s_add_u32 s0, s49, s0
	v_pk_fma_f32 v[34:35], v[42:43], s[24:25], v[34:35] op_sel:[0,0,1] op_sel_hi:[1,0,0] neg_lo:[1,0,0] neg_hi:[1,0,0]
	s_addc_u32 s1, s60, s1
	v_pk_add_f32 v[42:43], v[8:9], v[34:35]
	v_pk_add_f32 v[8:9], v[8:9], v[34:35] neg_lo:[0,1] neg_hi:[0,1]
	v_pk_mul_f32 v[34:35], v[38:39], s[80:81]
	s_lshl_b64 s[62:63], s[76:77], 2
	v_pk_fma_f32 v[34:35], v[38:39], s[16:17], v[34:35] op_sel:[0,0,1] op_sel_hi:[1,0,0] neg_lo:[1,0,0] neg_hi:[1,0,0]
	s_add_u32 s62, s22, s62
	v_pk_add_f32 v[38:39], v[6:7], v[34:35]
	v_pk_add_f32 v[6:7], v[6:7], v[34:35] neg_lo:[0,1] neg_hi:[0,1]
	v_pk_mul_f32 v[34:35], v[16:17], s[88:89]
	s_addc_u32 s63, s23, s63
	v_pk_fma_f32 v[16:17], s[8:9], v[16:17], v[34:35] op_sel:[0,0,1] op_sel_hi:[0,1,0] neg_lo:[0,1,0] neg_hi:[0,1,0]
	v_pk_add_f32 v[34:35], v[4:5], v[16:17]
	v_pk_add_f32 v[4:5], v[4:5], v[16:17] neg_lo:[0,1] neg_hi:[0,1]
	ds_write2_b64 v2, v[40:41], v[64:65] offset1:16
	ds_write2_b64 v2, v[66:67], v[70:71] offset0:33 offset1:49
	ds_write2_b64 v2, v[60:61], v[58:59] offset0:66 offset1:82
	ds_write2_b64 v2, v[68:69], v[54:55] offset0:99 offset1:115
	ds_write2_b64 v2, v[28:29], v[52:53] offset0:132 offset1:148
	ds_write2_b64 v2, v[46:47], v[48:49] offset0:165 offset1:181
	ds_write2_b64 v2, v[44:45], v[42:43] offset0:198 offset1:214
	ds_write2_b64 v2, v[38:39], v[34:35] offset0:231 offset1:247
	ds_write2_b64 v3, v[22:23], v[56:57] offset0:8 offset1:24
	ds_write2_b64 v3, v[62:63], v[32:33] offset0:41 offset1:57
	ds_write2_b64 v3, v[14:15], v[50:51] offset0:74 offset1:90
	ds_write2_b64 v3, v[26:27], v[24:25] offset0:107 offset1:123
	ds_write2_b64 v3, v[12:13], v[36:37] offset0:140 offset1:156
	ds_write2_b64 v3, v[10:11], v[20:21] offset0:173 offset1:189
	ds_write2_b64 v3, v[30:31], v[8:9] offset0:206 offset1:222
	ds_write2_b64 v3, v[6:7], v[4:5] offset0:239 offset1:255
	s_waitcnt lgkmcnt(0)
	s_barrier
	global_load_dword v30, v206, s[0:1]
	global_load_dword v20, v207, s[0:1]
	v_ashrrev_i32_e32 v2, 31, v210
	v_lshrrev_b32_e32 v2, 22, v2
	v_add_u32_e32 v2, v210, v2
	v_ashrrev_i32_e32 v2, 10, v2
	v_mul_i32_i24_e32 v3, 0x400, v2
	global_load_dword v31, v205, s[0:1]
	global_load_dword v24, v205, s[62:63]
	s_add_u32 s0, s87, s74
	v_sub_u32_e32 v21, v210, v3
	v_lshlrev_b32_e32 v36, 14, v2
	s_addc_u32 s1, s90, s75
	v_ashrrev_i32_e32 v37, 31, v36
	v_lshlrev_b32_e32 v32, 4, v21
	v_lshl_add_u64 v[2:3], v[36:37], 1, s[0:1]
	v_ashrrev_i32_e32 v33, 31, v32
	v_lshl_add_u64 v[2:3], v[32:33], 1, v[2:3]
	global_load_dwordx4 v[10:13], v[2:3], off offset:16 nt
	global_load_dwordx4 v[14:17], v[2:3], off nt
	v_cmp_lt_i32_e32 vcc, 0, v21
	v_mov_b32_e32 v39, 0
	v_mov_b32_e32 v41, 0
	s_and_saveexec_b64 s[72:73], vcc
	s_cbranch_execz .LBB0_505
	global_load_ushort v41, v[2:3], off offset:-2

.LBB0_511:
	s_or_b64 exec, exec, s[0:1]
	v_mov_b32_e32 v25, v210
	s_mov_b32 s72, s37
	v_and_b32_e32 v28, 0x1ff, v25
	v_cvt_f32_u32_e32 v34, v28
	v_lshlrev_b32_e32 v25, 5, v25
	v_and_or_b32 v25, v25, s94, v28
	v_ashrrev_i32_e32 v28, 5, v25
	v_mul_f32_e32 v34, 0x38800000, v34
	v_sin_f32_e32 v43, v34
	v_cos_f32_e32 v42, v34
	v_lshlrev_b32_e32 v25, 3, v25
	v_lshlrev_b32_e32 v28, 3, v28
	v_pk_mul_f32 v[44:45], v[42:43], 1.0 op_sel:[1,0] op_sel_hi:[1,0] neg_lo:[1,0]
	s_nop 0
	v_pk_mul_f32 v[46:47], v[42:43], v[44:45] op_sel:[1,0] op_sel_hi:[0,1]
	v_pk_fma_f32 v[46:47], v[42:43], v[42:43], v[46:47] op_sel_hi:[1,0,1]
	v_add3_u32 v25, 0, v25, v28
	v_pk_mul_f32 v[50:51], 1.0, v[46:47] op_sel:[0,1] op_sel_hi:[0,1] neg_lo:[0,1]
	v_pk_mul_f32 v[52:53], v[46:47], v[50:51] op_sel:[1,0] op_sel_hi:[0,1]
	v_pk_fma_f32 v[52:53], v[46:47], v[46:47], v[52:53] op_sel_hi:[1,0,1]
	v_add_u32_e32 v28, 0x10800, v25
	v_pk_mul_f32 v[54:55], 1.0, v[52:53] op_sel:[0,1] op_sel_hi:[0,1] neg_lo:[0,1]
	v_pk_mul_f32 v[70:71], v[52:53], v[54:55] op_sel:[1,0] op_sel_hi:[0,1]
	v_pk_fma_f32 v[70:71], v[52:53], v[52:53], v[70:71] op_sel_hi:[1,0,1]
	v_pk_mul_f32 v[48:49], v[44:45], v[46:47] op_sel:[0,1] op_sel_hi:[1,0]
	v_pk_mul_f32 v[86:87], v[54:55], v[70:71] op_sel:[0,1] op_sel_hi:[1,0]
	ds_read_b64 v[168:169], v25
	ds_read_b64 v[170:171], v25 offset:4224
	ds_read_b64 v[172:173], v25 offset:8448
	ds_read_b64 v[174:175], v25 offset:12672
	ds_read_b64 v[176:177], v25 offset:16896
	ds_read_b64 v[178:179], v25 offset:21120
	ds_read_b64 v[180:181], v25 offset:25344
	ds_read_b64 v[182:183], v25 offset:29568
	ds_read_b64 v[184:185], v25 offset:33792
	ds_read_b64 v[186:187], v25 offset:38016
	ds_read_b64 v[188:189], v25 offset:42240
	ds_read_b64 v[190:191], v25 offset:46464
	ds_read_b64 v[192:193], v25 offset:50688
	ds_read_b64 v[194:195], v25 offset:54912
	ds_read_b64 v[196:197], v25 offset:59136
	ds_read_b64 v[198:199], v25 offset:63360
	v_pk_fma_f32 v[86:87], v[52:53], v[70:71], v[86:87] op_sel_hi:[0,1,1]
	v_pk_mul_f32 v[102:103], v[54:55], v[86:87] op_sel:[0,1] op_sel_hi:[1,0]
	v_add_u32_e32 v34, 0x11880, v25
	v_pk_fma_f32 v[102:103], v[52:53], v[86:87], v[102:103] op_sel_hi:[0,1,1]
	v_pk_mul_f32 v[118:119], v[54:55], v[102:103] op_sel:[0,1] op_sel_hi:[1,0]
	v_add_u32_e32 v38, 0x12900, v25
	v_pk_fma_f32 v[118:119], v[52:53], v[102:103], v[118:119] op_sel_hi:[0,1,1]
	v_pk_mul_f32 v[134:135], v[54:55], v[118:119] op_sel:[0,1] op_sel_hi:[1,0]
	v_add_u32_e32 v40, 0x13980, v25
	v_pk_fma_f32 v[134:135], v[52:53], v[118:119], v[134:135] op_sel_hi:[0,1,1]
	v_pk_mul_f32 v[152:153], v[54:55], v[134:135] op_sel:[0,1] op_sel_hi:[1,0]
	ds_read_b64 v[212:213], v28
	ds_read_b64 v[214:215], v34
	ds_read_b64 v[216:217], v38
	ds_read_b64 v[218:219], v40
	v_add_u32_e32 v28, 0x14a00, v25
	v_pk_fma_f32 v[48:49], v[42:43], v[46:47], v[48:49] op_sel_hi:[0,1,1]
	v_pk_fma_f32 v[152:153], v[52:53], v[134:135], v[152:153] op_sel_hi:[0,1,1]
	v_add_u32_e32 v34, 0x15a80, v25
	v_add_u32_e32 v38, 0x16b00, v25
	v_add_u32_e32 v40, 0x17b80, v25
	ds_read_b64 v[220:221], v28
	ds_read_b64 v[222:223], v34
	ds_read_b64 v[224:225], v38
	ds_read_b64 v[226:227], v40
	v_add_u32_e32 v28, 0x18c00, v25
	v_pk_mul_f32 v[56:57], v[48:49], 1.0 op_sel:[1,0] op_sel_hi:[1,0] neg_lo:[1,0]
	v_pk_mul_f32 v[58:59], v[44:45], v[52:53] op_sel:[0,1] op_sel_hi:[1,0]
	v_pk_mul_f32 v[74:75], v[44:45], v[70:71] op_sel:[0,1] op_sel_hi:[1,0]
	v_pk_mul_f32 v[90:91], v[44:45], v[86:87] op_sel:[0,1] op_sel_hi:[1,0]
	v_pk_mul_f32 v[106:107], v[44:45], v[102:103] op_sel:[0,1] op_sel_hi:[1,0]
	v_pk_mul_f32 v[122:123], v[44:45], v[118:119] op_sel:[0,1] op_sel_hi:[1,0]
	v_pk_mul_f32 v[138:139], v[44:45], v[134:135] op_sel:[0,1] op_sel_hi:[1,0]
	v_pk_mul_f32 v[156:157], v[44:45], v[152:153] op_sel:[0,1] op_sel_hi:[1,0]
	v_add_u32_e32 v34, 0x19c80, v25
	v_add_u32_e32 v38, 0x1ad00, v25
	v_add_u32_e32 v40, 0x1bd80, v25
	ds_read_b64 v[228:229], v28
	ds_read_b64 v[230:231], v34
	ds_read_b64 v[232:233], v38
	ds_read_b64 v[234:235], v40
	v_add_u32_e32 v28, 0x1ce00, v25
	s_waitcnt lgkmcnt(11)
	v_pk_mul_f32 v[44:45], v[44:45], v[212:213] op_sel:[0,1] op_sel_hi:[1,0]
	v_pk_fma_f32 v[58:59], v[42:43], v[52:53], v[58:59] op_sel_hi:[0,1,1]
	v_pk_mul_f32 v[62:63], v[50:51], v[52:53] op_sel:[0,1] op_sel_hi:[1,0]
	v_pk_mul_f32 v[66:67], v[52:53], v[56:57] op_sel:[1,0] op_sel_hi:[0,1]
	v_pk_fma_f32 v[74:75], v[42:43], v[70:71], v[74:75] op_sel_hi:[0,1,1]
	v_pk_mul_f32 v[78:79], v[50:51], v[70:71] op_sel:[0,1] op_sel_hi:[1,0]
	v_pk_fma_f32 v[90:91], v[42:43], v[86:87], v[90:91] op_sel_hi:[0,1,1]
	v_pk_mul_f32 v[94:95], v[50:51], v[86:87] op_sel:[0,1] op_sel_hi:[1,0]
	v_pk_fma_f32 v[106:107], v[42:43], v[102:103], v[106:107] op_sel_hi:[0,1,1]
	v_pk_mul_f32 v[110:111], v[50:51], v[102:103] op_sel:[0,1] op_sel_hi:[1,0]
	v_pk_fma_f32 v[122:123], v[42:43], v[118:119], v[122:123] op_sel_hi:[0,1,1]
	v_pk_mul_f32 v[126:127], v[50:51], v[118:119] op_sel:[0,1] op_sel_hi:[1,0]
	v_pk_fma_f32 v[138:139], v[42:43], v[134:135], v[138:139] op_sel_hi:[0,1,1]
	v_pk_mul_f32 v[142:143], v[50:51], v[134:135] op_sel:[0,1] op_sel_hi:[1,0]
	v_pk_fma_f32 v[156:157], v[42:43], v[152:153], v[156:157] op_sel_hi:[0,1,1]
	v_pk_mul_f32 v[160:161], v[50:51], v[152:153] op_sel:[0,1] op_sel_hi:[1,0]
	v_add_u32_e32 v34, 0x1de80, v25
	v_add_u32_e32 v38, 0x1ef00, v25
	v_add_u32_e32 v40, 0x1ff80, v25
	ds_read_b64 v[236:237], v28
	ds_read_b64 v[238:239], v34
	ds_read_b64 v[240:241], v38
	ds_read_b64 v[242:243], v40
	v_pk_fma_f32 v[42:43], v[42:43], v[212:213], v[44:45] op_sel_hi:[0,1,1]
	v_pk_mul_f32 v[44:45], v[184:185], v[50:51] op_sel:[1,0] op_sel_hi:[0,1]
	v_pk_fma_f32 v[62:63], v[46:47], v[52:53], v[62:63] op_sel_hi:[0,1,1]
	v_pk_fma_f32 v[66:67], v[52:53], v[48:49], v[66:67] op_sel_hi:[1,0,1]
	v_pk_fma_f32 v[78:79], v[46:47], v[70:71], v[78:79] op_sel_hi:[0,1,1]
	v_pk_mul_f32 v[82:83], v[56:57], v[70:71] op_sel:[0,1] op_sel_hi:[1,0]
	v_pk_fma_f32 v[94:95], v[46:47], v[86:87], v[94:95] op_sel_hi:[0,1,1]
	v_pk_mul_f32 v[98:99], v[56:57], v[86:87] op_sel:[0,1] op_sel_hi:[1,0]
	v_pk_fma_f32 v[110:111], v[46:47], v[102:103], v[110:111] op_sel_hi:[0,1,1]
	v_pk_mul_f32 v[114:115], v[56:57], v[102:103] op_sel:[0,1] op_sel_hi:[1,0]
	v_pk_fma_f32 v[126:127], v[46:47], v[118:119], v[126:127] op_sel_hi:[0,1,1]
	v_pk_mul_f32 v[130:131], v[56:57], v[118:119] op_sel:[0,1] op_sel_hi:[1,0]
	v_pk_fma_f32 v[142:143], v[46:47], v[134:135], v[142:143] op_sel_hi:[0,1,1]
	v_pk_mul_f32 v[148:149], v[56:57], v[134:135] op_sel:[0,1] op_sel_hi:[1,0]
	v_pk_fma_f32 v[160:161], v[46:47], v[152:153], v[160:161] op_sel_hi:[0,1,1]
	v_pk_mul_f32 v[164:165], v[56:57], v[152:153] op_sel:[0,1] op_sel_hi:[1,0]
	v_pk_fma_f32 v[44:45], v[184:185], v[46:47], v[44:45] op_sel_hi:[1,0,1]
	s_waitcnt lgkmcnt(7)
	v_pk_mul_f32 v[46:47], v[56:57], v[228:229] op_sel:[0,1] op_sel_hi:[1,0]
	v_xor_b32_e32 v60, 0x80000000, v59
	v_xor_b32_e32 v64, 0x80000000, v63
	v_xor_b32_e32 v68, 0x80000000, v67
	v_xor_b32_e32 v72, 0x80000000, v71
	v_pk_fma_f32 v[82:83], v[48:49], v[70:71], v[82:83] op_sel_hi:[0,1,1]
	v_pk_fma_f32 v[98:99], v[48:49], v[86:87], v[98:99] op_sel_hi:[0,1,1]
	v_pk_fma_f32 v[114:115], v[48:49], v[102:103], v[114:115] op_sel_hi:[0,1,1]
	v_pk_fma_f32 v[130:131], v[48:49], v[118:119], v[130:131] op_sel_hi:[0,1,1]
	v_pk_fma_f32 v[148:149], v[48:49], v[134:135], v[148:149] op_sel_hi:[0,1,1]
	v_pk_fma_f32 v[164:165], v[48:49], v[152:153], v[164:165] op_sel_hi:[0,1,1]
	v_mov_b32_e32 v61, v59
	v_mov_b32_e32 v65, v63
	v_mov_b32_e32 v69, v67
	v_mov_b32_e32 v73, v71
	v_pk_fma_f32 v[46:47], v[48:49], v[228:229], v[46:47] op_sel_hi:[0,1,1]
	v_pk_mul_f32 v[48:49], v[176:177], v[54:55] op_sel:[1,0] op_sel_hi:[0,1]
	v_xor_b32_e32 v76, 0x80000000, v75
	v_xor_b32_e32 v80, 0x80000000, v79
	v_xor_b32_e32 v84, 0x80000000, v83
	v_xor_b32_e32 v88, 0x80000000, v87
	v_xor_b32_e32 v92, 0x80000000, v91
	v_xor_b32_e32 v96, 0x80000000, v95
	v_xor_b32_e32 v100, 0x80000000, v99
	v_xor_b32_e32 v104, 0x80000000, v103
	v_xor_b32_e32 v136, 0x80000000, v135
	v_mov_b32_e32 v77, v75
	v_mov_b32_e32 v81, v79
	v_mov_b32_e32 v85, v83
	v_mov_b32_e32 v89, v87
	v_mov_b32_e32 v93, v91
	v_mov_b32_e32 v97, v95
	v_mov_b32_e32 v101, v99
	v_mov_b32_e32 v105, v103
	v_mov_b32_e32 v137, v135
	v_pk_fma_f32 v[48:49], v[176:177], v[52:53], v[48:49] op_sel_hi:[1,0,1]
	v_pk_mul_f32 v[50:51], v[60:61], v[220:221] op_sel:[0,1] op_sel_hi:[1,0]
	v_pk_mul_f32 v[52:53], v[192:193], v[64:65] op_sel:[1,0] op_sel_hi:[0,1]
	s_waitcnt lgkmcnt(3)
	v_pk_mul_f32 v[54:55], v[68:69], v[236:237] op_sel:[0,1] op_sel_hi:[1,0]
	v_pk_mul_f32 v[56:57], v[172:173], v[72:73] op_sel:[1,0] op_sel_hi:[0,1]
	v_xor_b32_e32 v108, 0x80000000, v107
	v_xor_b32_e32 v112, 0x80000000, v111
	v_xor_b32_e32 v116, 0x80000000, v115
	v_xor_b32_e32 v120, 0x80000000, v119
	v_xor_b32_e32 v124, 0x80000000, v123
	v_xor_b32_e32 v128, 0x80000000, v127
	v_xor_b32_e32 v132, 0x80000000, v131
	v_xor_b32_e32 v140, 0x80000000, v139
	v_xor_b32_e32 v144, 0x80000000, v143
	v_xor_b32_e32 v150, 0x80000000, v149
	v_xor_b32_e32 v154, 0x80000000, v153
	v_xor_b32_e32 v158, 0x80000000, v157
	v_xor_b32_e32 v162, 0x80000000, v161
	v_xor_b32_e32 v166, 0x80000000, v165
	v_mov_b32_e32 v109, v107
	v_mov_b32_e32 v113, v111
	v_mov_b32_e32 v117, v115
	v_mov_b32_e32 v121, v119
	v_mov_b32_e32 v125, v123
	v_mov_b32_e32 v129, v127
	v_mov_b32_e32 v133, v131
	v_mov_b32_e32 v141, v139
	v_mov_b32_e32 v145, v143
	v_mov_b32_e32 v151, v149
	v_mov_b32_e32 v155, v153
	v_mov_b32_e32 v159, v157
	v_mov_b32_e32 v163, v161
	v_mov_b32_e32 v167, v165
	v_pk_fma_f32 v[50:51], v[58:59], v[220:221], v[50:51] op_sel_hi:[0,1,1]
	v_pk_fma_f32 v[52:53], v[192:193], v[62:63], v[52:53] op_sel_hi:[1,0,1]
	v_pk_fma_f32 v[54:55], v[66:67], v[236:237], v[54:55] op_sel_hi:[0,1,1]
	v_pk_fma_f32 v[56:57], v[172:173], v[70:71], v[56:57] op_sel_hi:[1,0,1]
	v_pk_mul_f32 v[58:59], v[216:217], v[76:77] op_sel:[1,0] op_sel_hi:[0,1]
	v_pk_mul_f32 v[60:61], v[188:189], v[80:81] op_sel:[1,0] op_sel_hi:[0,1]
	v_pk_mul_f32 v[62:63], v[84:85], v[232:233] op_sel:[0,1] op_sel_hi:[1,0]
	v_pk_mul_f32 v[64:65], v[180:181], v[88:89] op_sel:[1,0] op_sel_hi:[0,1]
	v_pk_mul_f32 v[66:67], v[224:225], v[92:93] op_sel:[1,0] op_sel_hi:[0,1]
	v_pk_mul_f32 v[68:69], v[196:197], v[96:97] op_sel:[1,0] op_sel_hi:[0,1]
	s_waitcnt lgkmcnt(1)
	v_pk_mul_f32 v[70:71], v[100:101], v[240:241] op_sel:[0,1] op_sel_hi:[1,0]
	v_pk_mul_f32 v[72:73], v[170:171], v[104:105] op_sel:[1,0] op_sel_hi:[0,1]
	v_pk_mul_f32 v[88:89], v[174:175], v[136:137] op_sel:[1,0] op_sel_hi:[0,1]
	v_pk_fma_f32 v[58:59], v[216:217], v[74:75], v[58:59] op_sel_hi:[1,0,1]
	v_pk_fma_f32 v[60:61], v[188:189], v[78:79], v[60:61] op_sel_hi:[1,0,1]
	v_pk_fma_f32 v[62:63], v[82:83], v[232:233], v[62:63] op_sel_hi:[0,1,1]
	v_pk_fma_f32 v[64:65], v[180:181], v[86:87], v[64:65] op_sel_hi:[1,0,1]
	v_pk_fma_f32 v[66:67], v[224:225], v[90:91], v[66:67] op_sel_hi:[1,0,1]
	v_pk_fma_f32 v[68:69], v[196:197], v[94:95], v[68:69] op_sel_hi:[1,0,1]
	v_pk_fma_f32 v[70:71], v[98:99], v[240:241], v[70:71] op_sel_hi:[0,1,1]
	v_pk_fma_f32 v[72:73], v[170:171], v[102:103], v[72:73] op_sel_hi:[1,0,1]
	v_pk_mul_f32 v[74:75], v[214:215], v[108:109] op_sel:[1,0] op_sel_hi:[0,1]
	v_pk_mul_f32 v[76:77], v[186:187], v[112:113] op_sel:[1,0] op_sel_hi:[0,1]
	v_pk_mul_f32 v[78:79], v[230:231], v[116:117] op_sel:[1,0] op_sel_hi:[0,1]
	v_pk_mul_f32 v[80:81], v[178:179], v[120:121] op_sel:[1,0] op_sel_hi:[0,1]
	v_pk_mul_f32 v[82:83], v[222:223], v[124:125] op_sel:[1,0] op_sel_hi:[0,1]
	v_pk_mul_f32 v[84:85], v[194:195], v[128:129] op_sel:[1,0] op_sel_hi:[0,1]
	v_pk_mul_f32 v[86:87], v[132:133], v[238:239] op_sel:[0,1] op_sel_hi:[1,0]
	v_pk_fma_f32 v[88:89], v[174:175], v[134:135], v[88:89] op_sel_hi:[1,0,1]
	v_pk_mul_f32 v[90:91], v[218:219], v[140:141] op_sel:[1,0] op_sel_hi:[0,1]
	v_pk_mul_f32 v[92:93], v[190:191], v[144:145] op_sel:[1,0] op_sel_hi:[0,1]
	v_pk_mul_f32 v[94:95], v[234:235], v[150:151] op_sel:[1,0] op_sel_hi:[0,1]
	v_pk_mul_f32 v[96:97], v[182:183], v[154:155] op_sel:[1,0] op_sel_hi:[0,1]
	v_pk_mul_f32 v[98:99], v[226:227], v[158:159] op_sel:[1,0] op_sel_hi:[0,1]
	v_pk_mul_f32 v[100:101], v[198:199], v[162:163] op_sel:[1,0] op_sel_hi:[0,1]
	s_waitcnt lgkmcnt(0)
	v_pk_mul_f32 v[102:103], v[242:243], v[166:167] op_sel:[1,0] op_sel_hi:[0,1]
	v_pk_fma_f32 v[74:75], v[214:215], v[106:107], v[74:75] op_sel_hi:[1,0,1]
	v_pk_fma_f32 v[76:77], v[186:187], v[110:111], v[76:77] op_sel_hi:[1,0,1]
	v_pk_fma_f32 v[78:79], v[230:231], v[114:115], v[78:79] op_sel_hi:[1,0,1]
	v_pk_fma_f32 v[80:81], v[178:179], v[118:119], v[80:81] op_sel_hi:[1,0,1]
	v_pk_fma_f32 v[82:83], v[222:223], v[122:123], v[82:83] op_sel_hi:[1,0,1]
	v_pk_fma_f32 v[84:85], v[194:195], v[126:127], v[84:85] op_sel_hi:[1,0,1]
	v_pk_fma_f32 v[86:87], v[130:131], v[238:239], v[86:87] op_sel_hi:[0,1,1]
	v_pk_fma_f32 v[90:91], v[218:219], v[138:139], v[90:91] op_sel_hi:[1,0,1]
	v_pk_fma_f32 v[92:93], v[190:191], v[142:143], v[92:93] op_sel_hi:[1,0,1]
	v_pk_fma_f32 v[94:95], v[234:235], v[148:149], v[94:95] op_sel_hi:[1,0,1]
	v_pk_fma_f32 v[96:97], v[182:183], v[152:153], v[96:97] op_sel_hi:[1,0,1]
	v_pk_fma_f32 v[98:99], v[226:227], v[156:157], v[98:99] op_sel_hi:[1,0,1]
	v_pk_fma_f32 v[100:101], v[198:199], v[160:161], v[100:101] op_sel_hi:[1,0,1]
	v_pk_fma_f32 v[102:103], v[242:243], v[164:165], v[102:103] op_sel_hi:[1,0,1]
	v_pk_add_f32 v[104:105], v[168:169], v[72:73]
	v_pk_add_f32 v[106:107], v[56:57], v[88:89]
	v_pk_add_f32 v[56:57], v[56:57], v[88:89] neg_lo:[0,1] neg_hi:[0,1]
	v_pk_add_f32 v[72:73], v[168:169], v[72:73] neg_lo:[0,1] neg_hi:[0,1]
	v_pk_add_f32 v[88:89], v[48:49], v[80:81]
	v_pk_add_f32 v[48:49], v[48:49], v[80:81] neg_lo:[0,1] neg_hi:[0,1]
	v_pk_add_f32 v[80:81], v[64:65], v[96:97]
	v_pk_add_f32 v[64:65], v[64:65], v[96:97] neg_lo:[0,1] neg_hi:[0,1]
	v_pk_add_f32 v[96:97], v[44:45], v[76:77]
	v_pk_add_f32 v[44:45], v[44:45], v[76:77] neg_lo:[0,1] neg_hi:[0,1]
	v_pk_add_f32 v[76:77], v[60:61], v[92:93]
	v_pk_add_f32 v[60:61], v[60:61], v[92:93] neg_lo:[0,1] neg_hi:[0,1]
	v_pk_add_f32 v[92:93], v[52:53], v[84:85]
	v_pk_add_f32 v[52:53], v[52:53], v[84:85] neg_lo:[0,1] neg_hi:[0,1]
	v_pk_add_f32 v[84:85], v[68:69], v[100:101]
	v_pk_add_f32 v[68:69], v[68:69], v[100:101] neg_lo:[0,1] neg_hi:[0,1]
	v_pk_add_f32 v[100:101], v[42:43], v[74:75]
	v_pk_add_f32 v[42:43], v[42:43], v[74:75] neg_lo:[0,1] neg_hi:[0,1]
	v_pk_add_f32 v[74:75], v[58:59], v[90:91]
	v_pk_add_f32 v[58:59], v[58:59], v[90:91] neg_lo:[0,1] neg_hi:[0,1]
	v_pk_add_f32 v[90:91], v[50:51], v[82:83]
	v_pk_add_f32 v[50:51], v[50:51], v[82:83] neg_lo:[0,1] neg_hi:[0,1]
	v_pk_add_f32 v[82:83], v[66:67], v[98:99]
	v_pk_add_f32 v[66:67], v[66:67], v[98:99] neg_lo:[0,1] neg_hi:[0,1]
	v_pk_add_f32 v[98:99], v[46:47], v[78:79]
	v_pk_add_f32 v[46:47], v[46:47], v[78:79] neg_lo:[0,1] neg_hi:[0,1]
	v_pk_add_f32 v[78:79], v[62:63], v[94:95]
	v_pk_add_f32 v[62:63], v[62:63], v[94:95] neg_lo:[0,1] neg_hi:[0,1]
	v_pk_add_f32 v[94:95], v[54:55], v[86:87]
	v_pk_add_f32 v[54:55], v[54:55], v[86:87] neg_lo:[0,1] neg_hi:[0,1]
	v_pk_add_f32 v[86:87], v[70:71], v[102:103]
	v_pk_add_f32 v[70:71], v[70:71], v[102:103] neg_lo:[0,1] neg_hi:[0,1]
	v_pk_add_f32 v[102:103], v[104:105], v[106:107]
	v_pk_add_f32 v[104:105], v[104:105], v[106:107] neg_lo:[0,1] neg_hi:[0,1]
	v_pk_mul_f32 v[106:107], v[56:57], 1.0 op_sel:[1,0] op_sel_hi:[0,0] neg_lo:[1,0]
	v_pk_add_f32 v[56:57], v[72:73], v[106:107]
	v_pk_add_f32 v[72:73], v[72:73], v[106:107] neg_lo:[0,1] neg_hi:[0,1]
	v_pk_add_f32 v[106:107], v[88:89], v[80:81]
	v_pk_add_f32 v[80:81], v[88:89], v[80:81] neg_lo:[0,1] neg_hi:[0,1]
	v_pk_mul_f32 v[88:89], v[64:65], 1.0 op_sel:[1,0] op_sel_hi:[0,0] neg_lo:[1,0]
	v_pk_add_f32 v[64:65], v[48:49], v[88:89]
	v_pk_add_f32 v[48:49], v[48:49], v[88:89] neg_lo:[0,1] neg_hi:[0,1]
	v_pk_add_f32 v[88:89], v[96:97], v[76:77]
	v_pk_add_f32 v[76:77], v[96:97], v[76:77] neg_lo:[0,1] neg_hi:[0,1]
	v_pk_mul_f32 v[96:97], v[60:61], 1.0 op_sel:[1,0] op_sel_hi:[0,0] neg_lo:[1,0]
	v_pk_add_f32 v[60:61], v[44:45], v[96:97]
	v_pk_add_f32 v[44:45], v[44:45], v[96:97] neg_lo:[0,1] neg_hi:[0,1]
	v_pk_add_f32 v[96:97], v[92:93], v[84:85]
	v_pk_add_f32 v[84:85], v[92:93], v[84:85] neg_lo:[0,1] neg_hi:[0,1]
	v_pk_mul_f32 v[92:93], v[68:69], 1.0 op_sel:[1,0] op_sel_hi:[0,0] neg_lo:[1,0]
	v_pk_add_f32 v[68:69], v[52:53], v[92:93]
	v_pk_add_f32 v[52:53], v[52:53], v[92:93] neg_lo:[0,1] neg_hi:[0,1]
	v_pk_add_f32 v[92:93], v[100:101], v[74:75]
	v_pk_add_f32 v[74:75], v[100:101], v[74:75] neg_lo:[0,1] neg_hi:[0,1]
	v_pk_mul_f32 v[100:101], v[58:59], 1.0 op_sel:[1,0] op_sel_hi:[0,0] neg_lo:[1,0]
	v_pk_add_f32 v[58:59], v[42:43], v[100:101]
	v_pk_add_f32 v[42:43], v[42:43], v[100:101] neg_lo:[0,1] neg_hi:[0,1]
	v_pk_add_f32 v[100:101], v[90:91], v[82:83]
	v_pk_add_f32 v[82:83], v[90:91], v[82:83] neg_lo:[0,1] neg_hi:[0,1]
	v_pk_mul_f32 v[90:91], v[66:67], 1.0 op_sel:[1,0] op_sel_hi:[0,0] neg_lo:[1,0]
	v_pk_add_f32 v[66:67], v[50:51], v[90:91]
	v_pk_add_f32 v[50:51], v[50:51], v[90:91] neg_lo:[0,1] neg_hi:[0,1]
	v_pk_add_f32 v[90:91], v[98:99], v[78:79]
	v_pk_add_f32 v[78:79], v[98:99], v[78:79] neg_lo:[0,1] neg_hi:[0,1]
	v_pk_mul_f32 v[98:99], v[62:63], 1.0 op_sel:[1,0] op_sel_hi:[0,0] neg_lo:[1,0]
	v_pk_add_f32 v[62:63], v[46:47], v[98:99]
	v_pk_add_f32 v[46:47], v[46:47], v[98:99] neg_lo:[0,1] neg_hi:[0,1]
	v_pk_add_f32 v[98:99], v[94:95], v[86:87]
	v_pk_add_f32 v[86:87], v[94:95], v[86:87] neg_lo:[0,1] neg_hi:[0,1]
	v_pk_mul_f32 v[94:95], v[70:71], 1.0 op_sel:[1,0] op_sel_hi:[0,0] neg_lo:[1,0]
	s_mov_b32 s73, s36
	v_pk_add_f32 v[70:71], v[54:55], v[94:95]
	v_pk_add_f32 v[54:55], v[54:55], v[94:95] neg_lo:[0,1] neg_hi:[0,1]
	v_pk_add_f32 v[94:95], v[102:103], v[106:107]
	v_pk_add_f32 v[102:103], v[102:103], v[106:107] neg_lo:[0,1] neg_hi:[0,1]
	s_mov_b32 s0, s37
	v_pk_mul_f32 v[106:107], v[64:65], s[72:73]
	s_mov_b32 s74, s19
	v_pk_fma_f32 v[64:65], v[64:65], s[0:1], v[106:107] op_sel:[0,0,1] op_sel_hi:[1,0,0]
	s_mov_b32 s75, s18
	v_pk_add_f32 v[106:107], v[56:57], v[64:65]
	v_pk_add_f32 v[56:57], v[56:57], v[64:65] neg_lo:[0,1] neg_hi:[0,1]
	v_pk_mul_f32 v[64:65], v[80:81], 1.0 op_sel:[1,0] op_sel_hi:[0,0] neg_lo:[1,0]
	s_nop 0
	v_pk_add_f32 v[80:81], v[104:105], v[64:65]
	v_pk_add_f32 v[64:65], v[104:105], v[64:65] neg_lo:[0,1] neg_hi:[0,1]
	v_pk_mul_f32 v[104:105], v[48:49], s[72:73]
	s_mov_b32 s76, s19
	v_pk_fma_f32 v[48:49], v[48:49], s[0:1], v[104:105] op_sel:[0,0,1] op_sel_hi:[1,0,0] neg_lo:[1,0,0] neg_hi:[1,0,0]
	s_mov_b32 s62, s11
	v_pk_add_f32 v[104:105], v[72:73], v[48:49]
	v_pk_add_f32 v[48:49], v[72:73], v[48:49] neg_lo:[0,1] neg_hi:[0,1]
	v_pk_add_f32 v[72:73], v[88:89], v[96:97]
	v_pk_add_f32 v[88:89], v[88:89], v[96:97] neg_lo:[0,1] neg_hi:[0,1]
	v_pk_mul_f32 v[96:97], v[68:69], s[72:73]
	s_mov_b32 s63, s10
	v_pk_fma_f32 v[68:69], v[68:69], s[0:1], v[96:97] op_sel:[0,0,1] op_sel_hi:[1,0,0]
	s_mov_b32 s78, s27
	v_pk_add_f32 v[96:97], v[60:61], v[68:69]
	v_pk_add_f32 v[60:61], v[60:61], v[68:69] neg_lo:[0,1] neg_hi:[0,1]
	v_pk_mul_f32 v[68:69], v[84:85], 1.0 op_sel:[1,0] op_sel_hi:[0,0] neg_lo:[1,0]
	s_nop 0
	v_pk_add_f32 v[84:85], v[76:77], v[68:69]
	v_pk_add_f32 v[68:69], v[76:77], v[68:69] neg_lo:[0,1] neg_hi:[0,1]
	v_pk_mul_f32 v[76:77], v[52:53], s[72:73]
	v_pk_mul_f32 v[108:109], v[96:97], s[74:75]
	v_pk_fma_f32 v[52:53], v[52:53], s[0:1], v[76:77] op_sel:[0,0,1] op_sel_hi:[1,0,0] neg_lo:[1,0,0] neg_hi:[1,0,0]
	v_pk_fma_f32 v[96:97], v[96:97], s[16:17], v[108:109] op_sel:[0,0,1] op_sel_hi:[1,0,0]
	v_pk_add_f32 v[76:77], v[44:45], v[52:53]
	v_pk_add_f32 v[44:45], v[44:45], v[52:53] neg_lo:[0,1] neg_hi:[0,1]
	v_pk_add_f32 v[52:53], v[92:93], v[100:101]
	v_pk_add_f32 v[92:93], v[92:93], v[100:101] neg_lo:[0,1] neg_hi:[0,1]
	v_pk_mul_f32 v[100:101], v[66:67], s[72:73]
	s_mov_b32 s17, s40
	v_pk_fma_f32 v[66:67], v[66:67], s[0:1], v[100:101] op_sel:[0,0,1] op_sel_hi:[1,0,0]
	v_pk_add_f32 v[108:109], v[106:107], v[96:97]
	v_pk_add_f32 v[100:101], v[58:59], v[66:67]
	v_pk_add_f32 v[58:59], v[58:59], v[66:67] neg_lo:[0,1] neg_hi:[0,1]
	v_pk_mul_f32 v[66:67], v[82:83], 1.0 op_sel:[1,0] op_sel_hi:[0,0] neg_lo:[1,0]
	v_pk_add_f32 v[82:83], v[74:75], v[66:67]
	v_pk_add_f32 v[66:67], v[74:75], v[66:67] neg_lo:[0,1] neg_hi:[0,1]
	v_pk_mul_f32 v[74:75], v[50:51], s[72:73]
	v_pk_add_f32 v[96:97], v[106:107], v[96:97] neg_lo:[0,1] neg_hi:[0,1]
	v_pk_fma_f32 v[50:51], v[50:51], s[0:1], v[74:75] op_sel:[0,0,1] op_sel_hi:[1,0,0] neg_lo:[1,0,0] neg_hi:[1,0,0]
	v_pk_mul_f32 v[106:107], v[84:85], s[72:73]
	v_pk_add_f32 v[74:75], v[42:43], v[50:51]
	v_pk_add_f32 v[42:43], v[42:43], v[50:51] neg_lo:[0,1] neg_hi:[0,1]
	v_pk_add_f32 v[50:51], v[90:91], v[98:99]
	v_pk_add_f32 v[90:91], v[90:91], v[98:99] neg_lo:[0,1] neg_hi:[0,1]
	v_pk_mul_f32 v[98:99], v[70:71], s[72:73]
	v_pk_fma_f32 v[84:85], v[84:85], s[0:1], v[106:107] op_sel:[0,0,1] op_sel_hi:[1,0,0]
	v_pk_fma_f32 v[70:71], v[70:71], s[0:1], v[98:99] op_sel:[0,0,1] op_sel_hi:[1,0,0]
	v_pk_add_f32 v[106:107], v[80:81], v[84:85]
	v_pk_add_f32 v[98:99], v[62:63], v[70:71]
	v_pk_add_f32 v[62:63], v[62:63], v[70:71] neg_lo:[0,1] neg_hi:[0,1]
	v_pk_mul_f32 v[70:71], v[86:87], 1.0 op_sel:[1,0] op_sel_hi:[0,0] neg_lo:[1,0]
	v_pk_mul_f32 v[110:111], v[98:99], s[74:75]
	v_pk_add_f32 v[86:87], v[78:79], v[70:71]
	v_pk_add_f32 v[70:71], v[78:79], v[70:71] neg_lo:[0,1] neg_hi:[0,1]
	v_pk_mul_f32 v[78:79], v[54:55], s[72:73]
	v_pk_fma_f32 v[98:99], v[98:99], s[16:17], v[110:111] op_sel:[0,0,1] op_sel_hi:[1,0,0]
	v_pk_fma_f32 v[54:55], v[54:55], s[0:1], v[78:79] op_sel:[0,0,1] op_sel_hi:[1,0,0] neg_lo:[1,0,0] neg_hi:[1,0,0]
	v_pk_add_f32 v[110:111], v[100:101], v[98:99]
	v_pk_add_f32 v[98:99], v[100:101], v[98:99] neg_lo:[0,1] neg_hi:[0,1]
	v_pk_mul_f32 v[100:101], v[86:87], s[72:73]
	v_pk_add_f32 v[78:79], v[46:47], v[54:55]
	v_pk_fma_f32 v[86:87], v[86:87], s[0:1], v[100:101] op_sel:[0,0,1] op_sel_hi:[1,0,0]
	v_pk_add_f32 v[46:47], v[46:47], v[54:55] neg_lo:[0,1] neg_hi:[0,1]
	v_pk_add_f32 v[100:101], v[82:83], v[86:87]
	v_pk_add_f32 v[82:83], v[82:83], v[86:87] neg_lo:[0,1] neg_hi:[0,1]
	v_pk_mul_f32 v[86:87], v[78:79], s[16:17]
	v_pk_add_f32 v[80:81], v[80:81], v[84:85] neg_lo:[0,1] neg_hi:[0,1]
	v_pk_fma_f32 v[78:79], v[78:79], s[76:77], v[86:87] op_sel:[0,0,1] op_sel_hi:[1,0,0]
	v_pk_mul_f32 v[84:85], v[76:77], s[16:17]
	v_pk_add_f32 v[86:87], v[74:75], v[78:79]
	v_pk_add_f32 v[74:75], v[74:75], v[78:79] neg_lo:[0,1] neg_hi:[0,1]
	v_pk_mul_f32 v[78:79], v[90:91], 1.0 op_sel:[1,0] op_sel_hi:[0,0] neg_lo:[1,0]
	v_pk_add_f32 v[90:91], v[92:93], v[78:79]
	v_pk_add_f32 v[78:79], v[92:93], v[78:79] neg_lo:[0,1] neg_hi:[0,1]
	v_pk_mul_f32 v[92:93], v[62:63], s[16:17]
	v_pk_fma_f32 v[76:77], v[76:77], s[76:77], v[84:85] op_sel:[0,0,1] op_sel_hi:[1,0,0]
	v_pk_fma_f32 v[62:63], v[62:63], s[76:77], v[92:93] op_sel:[0,0,1] op_sel_hi:[1,0,0] neg_lo:[1,0,0] neg_hi:[1,0,0]
	v_pk_add_f32 v[84:85], v[104:105], v[76:77]
	v_pk_add_f32 v[92:93], v[58:59], v[62:63]
	v_pk_add_f32 v[58:59], v[58:59], v[62:63] neg_lo:[0,1] neg_hi:[0,1]
	v_pk_mul_f32 v[62:63], v[70:71], s[72:73]
	v_pk_add_f32 v[76:77], v[104:105], v[76:77] neg_lo:[0,1] neg_hi:[0,1]
	v_pk_fma_f32 v[62:63], v[70:71], s[0:1], v[62:63] op_sel:[0,0,1] op_sel_hi:[1,0,0] neg_lo:[1,0,0] neg_hi:[1,0,0]
	v_pk_mul_f32 v[104:105], v[88:89], 1.0 op_sel:[1,0] op_sel_hi:[0,0] neg_lo:[1,0]
	v_pk_add_f32 v[70:71], v[66:67], v[62:63]
	v_pk_add_f32 v[62:63], v[66:67], v[62:63] neg_lo:[0,1] neg_hi:[0,1]
	v_pk_mul_f32 v[66:67], v[46:47], s[74:75]
	s_nop 0
	v_pk_fma_f32 v[46:47], v[46:47], s[16:17], v[66:67] op_sel:[0,0,1] op_sel_hi:[1,0,0] neg_lo:[1,0,0] neg_hi:[1,0,0]
	s_mov_b32 s79, s26
	v_pk_add_f32 v[66:67], v[42:43], v[46:47]
	v_pk_add_f32 v[42:43], v[42:43], v[46:47] neg_lo:[0,1] neg_hi:[0,1]
	v_pk_mul_f32 v[46:47], v[110:111], s[62:63]
	v_pk_add_f32 v[88:89], v[102:103], v[104:105]
	v_pk_fma_f32 v[46:47], v[110:111], s[8:9], v[46:47] op_sel:[0,0,1] op_sel_hi:[1,0,0]
	v_pk_add_f32 v[102:103], v[102:103], v[104:105] neg_lo:[0,1] neg_hi:[0,1]
	v_pk_add_f32 v[46:47], v[108:109], v[46:47]
	v_pk_mul_f32 v[108:109], v[100:101], s[74:75]
	v_pk_mul_f32 v[104:105], v[60:61], s[16:17]
	v_pk_fma_f32 v[100:101], v[100:101], s[16:17], v[108:109] op_sel:[0,0,1] op_sel_hi:[1,0,0]
	v_pk_fma_f32 v[60:61], v[60:61], s[76:77], v[104:105] op_sel:[0,0,1] op_sel_hi:[1,0,0] neg_lo:[1,0,0] neg_hi:[1,0,0]
	v_pk_add_f32 v[100:101], v[106:107], v[100:101]
	v_pk_mul_f32 v[106:107], v[86:87], s[78:79]
	v_pk_add_f32 v[104:105], v[56:57], v[60:61]
	v_pk_fma_f32 v[86:87], v[86:87], s[24:25], v[106:107] op_sel:[0,0,1] op_sel_hi:[1,0,0]
	v_pk_add_f32 v[56:57], v[56:57], v[60:61] neg_lo:[0,1] neg_hi:[0,1]
	v_pk_mul_f32 v[60:61], v[68:69], s[72:73]
	v_pk_add_f32 v[84:85], v[84:85], v[86:87]
	v_pk_mul_f32 v[86:87], v[90:91], s[72:73]
	v_pk_fma_f32 v[60:61], v[68:69], s[0:1], v[60:61] op_sel:[0,0,1] op_sel_hi:[1,0,0] neg_lo:[1,0,0] neg_hi:[1,0,0]
	v_pk_fma_f32 v[86:87], v[90:91], s[0:1], v[86:87] op_sel:[0,0,1] op_sel_hi:[1,0,0]
	v_pk_mul_f32 v[90:91], v[70:71], s[16:17]
	v_pk_add_f32 v[68:69], v[64:65], v[60:61]
	v_pk_fma_f32 v[70:71], v[70:71], s[76:77], v[90:91] op_sel:[0,0,1] op_sel_hi:[1,0,0]
	s_mov_b32 s9, s42
	s_mov_b32 s25, s38
	v_pk_add_f32 v[68:69], v[68:69], v[70:71]
	s_mov_b32 s82, s11
	v_pk_mul_f32 v[70:71], v[66:67], s[8:9]
	s_mov_b32 s80, s27
	v_pk_fma_f32 v[66:67], v[66:67], s[82:83], v[70:71] op_sel:[0,0,1] op_sel_hi:[1,0,0]
	v_pk_mul_f32 v[70:71], v[74:75], s[24:25]
	v_pk_add_f32 v[60:61], v[64:65], v[60:61] neg_lo:[0,1] neg_hi:[0,1]
	v_pk_fma_f32 v[70:71], v[74:75], s[80:81], v[70:71] op_sel:[0,0,1] op_sel_hi:[1,0,0] neg_lo:[1,0,0] neg_hi:[1,0,0]
	v_pk_mul_f32 v[64:65], v[44:45], s[74:75]
	v_pk_add_f32 v[70:71], v[76:77], v[70:71]
	v_pk_mul_f32 v[76:77], v[58:59], s[78:79]
	v_pk_fma_f32 v[44:45], v[44:45], s[16:17], v[64:65] op_sel:[0,0,1] op_sel_hi:[1,0,0] neg_lo:[1,0,0] neg_hi:[1,0,0]
	v_pk_fma_f32 v[58:59], v[58:59], s[24:25], v[76:77] op_sel:[0,0,1] op_sel_hi:[1,0,0] neg_lo:[1,0,0] neg_hi:[1,0,0]
	v_pk_add_f32 v[64:65], v[48:49], v[44:45]
	v_pk_add_f32 v[56:57], v[56:57], v[58:59]
	v_pk_mul_f32 v[58:59], v[62:63], s[74:75]
	v_pk_add_f32 v[44:45], v[48:49], v[44:45] neg_lo:[0,1] neg_hi:[0,1]
	v_pk_fma_f32 v[58:59], s[16:17], v[62:63], v[58:59] op_sel:[0,0,1] op_sel_hi:[0,1,0] neg_lo:[0,1,0] neg_hi:[0,1,0]
	v_pk_add_f32 v[58:59], v[60:61], v[58:59]
	v_pk_mul_f32 v[60:61], v[42:43], s[62:63]
	v_pk_add_f32 v[54:55], v[94:95], v[72:73] neg_lo:[0,1] neg_hi:[0,1]
	v_pk_add_f32 v[64:65], v[64:65], v[66:67]
	v_pk_add_f32 v[66:67], v[52:53], v[50:51] neg_lo:[0,1] neg_hi:[0,1]
	v_pk_fma_f32 v[42:43], v[42:43], s[8:9], v[60:61] op_sel:[0,0,1] op_sel_hi:[1,0,0] neg_lo:[1,0,0] neg_hi:[1,0,0]
	v_pk_add_f32 v[86:87], v[88:89], v[86:87]
	v_pk_mul_f32 v[88:89], v[92:93], s[24:25]
	v_pk_add_f32 v[48:49], v[54:55], v[66:67] op_sel:[0,1] op_sel_hi:[1,0] neg_lo:[0,1]
	v_pk_mul_f32 v[54:55], v[98:99], s[8:9]
	v_pk_mul_f32 v[66:67], v[82:83], s[16:17]
	v_pk_mul_f32 v[74:75], v[78:79], s[72:73]
	v_pk_add_f32 v[42:43], v[44:45], v[42:43]
	v_pk_add_f32 v[44:45], v[94:95], v[72:73]
	v_pk_add_f32 v[50:51], v[52:53], v[50:51]
	v_pk_fma_f32 v[88:89], v[92:93], s[80:81], v[88:89] op_sel:[0,0,1] op_sel_hi:[1,0,0]
	v_pk_fma_f32 v[54:55], v[98:99], s[82:83], v[54:55] op_sel:[0,0,1] op_sel_hi:[1,0,0] neg_lo:[1,0,0] neg_hi:[1,0,0]
	v_pk_fma_f32 v[66:67], v[82:83], s[76:77], v[66:67] op_sel:[0,0,1] op_sel_hi:[1,0,0] neg_lo:[1,0,0] neg_hi:[1,0,0]
	v_pk_fma_f32 v[74:75], v[78:79], s[0:1], v[74:75] op_sel:[0,0,1] op_sel_hi:[1,0,0] neg_lo:[1,0,0] neg_hi:[1,0,0]
	v_pk_add_f32 v[44:45], v[44:45], v[50:51]
	v_lshl_add_u32 v21, v21, 3, v36
	v_pk_add_f32 v[88:89], v[104:105], v[88:89]
	v_pk_add_f32 v[54:55], v[96:97], v[54:55]
	v_pk_add_f32 v[66:67], v[80:81], v[66:67]
	v_pk_add_f32 v[74:75], v[102:103], v[74:75]
	ds_write_b64 v25, v[44:45]
	ds_write_b64 v25, v[46:47] offset:4224
	ds_write_b64 v25, v[100:101] offset:8448
	ds_write_b64 v25, v[84:85] offset:12672
	ds_write_b64 v25, v[86:87] offset:16896
	ds_write_b64 v25, v[88:89] offset:21120
	ds_write_b64 v25, v[68:69] offset:25344
	ds_write_b64 v25, v[64:65] offset:29568
	ds_write_b64 v25, v[48:49] offset:33792
	ds_write_b64 v25, v[54:55] offset:38016
	ds_write_b64 v25, v[66:67] offset:42240
	ds_write_b64 v25, v[70:71] offset:46464
	ds_write_b64 v25, v[74:75] offset:50688
	ds_write_b64 v25, v[56:57] offset:54912
	ds_write_b64 v25, v[58:59] offset:59136
	ds_write_b64 v25, v[42:43] offset:63360
	v_ashrrev_i32_e32 v25, 5, v21
	v_lshlrev_b32_e32 v21, 3, v21
	v_lshlrev_b32_e32 v25, 3, v25
	s_waitcnt vmcnt(0)
	v_lshlrev_b32_e32 v41, 16, v41
	v_lshlrev_b32_e32 v39, 16, v39
	v_lshlrev_b32_e32 v35, 16, v35
	v_lshlrev_b32_e32 v29, 16, v29
	v_and_b32_e32 v48, 0xffff0000, v14
	v_add3_u32 v21, 0, v21, v25
	v_mov_b32_e32 v40, v48
	s_waitcnt lgkmcnt(0)
	s_barrier
	v_pk_mul_f32 v[44:45], v[30:31], v[40:41]
	ds_read2_b64 v[40:43], v21 offset1:1
	v_lshlrev_b32_e32 v28, 16, v14
	v_lshlrev_b32_e32 v49, 16, v15
	v_pk_fma_f32 v[44:45], v[30:31], v[28:29], v[44:45] op_sel:[0,0,1] op_sel_hi:[1,0,0]
	v_mov_b32_e32 v28, v31
	v_pk_fma_f32 v[44:45], v[20:21], v[48:49], v[44:45] op_sel_hi:[0,1,1]
	v_pk_add_f32 v[50:51], v[24:25], v[44:45] op_sel_hi:[0,1]
	ds_read2_b64 v[44:47], v21 offset0:2 offset1:3
	s_waitcnt lgkmcnt(1)
	v_pk_mul_f32 v[40:41], v[50:51], v[40:41]
	v_and_b32_e32 v51, 16, v16
	v_and_b32_e32 v50, 0xffff0000, v15
	v_pk_mov_b32 v[14:15], v[48:49], v[50:51] op_sel:[1,0]
	v_lshlrev_b32_e32 v53, 16, v16
	v_pk_mul_f32 v[14:15], v[30:31], v[14:15] op_sel_hi:[0,1]
	v_mov_b32_e32 v52, v50
	v_pk_fma_f32 v[14:15], v[28:29], v[48:49], v[14:15] op_sel_hi:[0,1,1]
	v_pk_fma_f32 v[14:15], v[20:21], v[52:53], v[14:15] op_sel_hi:[0,1,1]
	v_pk_add_f32 v[14:15], v[24:25], v[14:15] op_sel_hi:[0,1]
	v_pk_mul_f32 v[14:15], v[14:15], v[42:43]
	v_and_b32_e32 v43, 16, v17
	v_and_b32_e32 v42, 0xffff0000, v16
	v_lshlrev_b32_e32 v49, 16, v17
	v_mov_b32_e32 v48, v42
	v_pk_mov_b32 v[42:43], v[52:53], v[42:43] op_sel:[1,0]
	v_pk_mov_b32 v[16:17], v[16:17], v[10:11] op_sel:[1,0]
	v_pk_mul_f32 v[42:43], v[30:31], v[42:43] op_sel_hi:[0,1]
	v_and_b32_e32 v17, 16, v17
	v_and_b32_e32 v16, 0xffff0000, v16
	v_pk_fma_f32 v[42:43], v[28:29], v[52:53], v[42:43] op_sel_hi:[0,1,1]
	v_mov_b32_e32 v50, v16
	v_pk_mov_b32 v[16:17], v[48:49], v[16:17] op_sel:[1,0]
	v_pk_fma_f32 v[42:43], v[20:21], v[48:49], v[42:43] op_sel_hi:[0,1,1]
	v_pk_mul_f32 v[16:17], v[30:31], v[16:17] op_sel_hi:[0,1]
	v_pk_add_f32 v[42:43], v[24:25], v[42:43] op_sel_hi:[0,1]
	v_lshlrev_b32_e32 v51, 16, v10
	v_pk_fma_f32 v[16:17], v[28:29], v[48:49], v[16:17] op_sel_hi:[0,1,1]
	s_waitcnt lgkmcnt(0)
	v_pk_mul_f32 v[42:43], v[42:43], v[44:45]
	v_pk_fma_f32 v[16:17], v[20:21], v[50:51], v[16:17] op_sel_hi:[0,1,1]
	v_and_b32_e32 v45, 16, v11
	v_and_b32_e32 v44, 0xffff0000, v10
	v_pk_add_f32 v[16:17], v[24:25], v[16:17] op_sel_hi:[0,1]
	v_mov_b32_e32 v52, v44
	v_pk_mov_b32 v[44:45], v[50:51], v[44:45] op_sel:[1,0]
	v_pk_mul_f32 v[16:17], v[16:17], v[46:47]
	v_pk_mul_f32 v[48:49], v[30:31], v[44:45] op_sel_hi:[0,1]
	ds_read2_b64 v[44:47], v21 offset0:4 offset1:5
	v_lshlrev_b32_e32 v53, 16, v11
	v_pk_fma_f32 v[48:49], v[28:29], v[50:51], v[48:49] op_sel_hi:[0,1,1]
	v_pk_fma_f32 v[48:49], v[20:21], v[52:53], v[48:49] op_sel_hi:[0,1,1]
	v_pk_add_f32 v[54:55], v[24:25], v[48:49] op_sel_hi:[0,1]
	ds_read2_b64 v[48:51], v21 offset0:6 offset1:7
	s_waitcnt lgkmcnt(1)
	v_pk_mul_f32 v[44:45], v[54:55], v[44:45]
	v_and_b32_e32 v55, 16, v12
	v_and_b32_e32 v54, 0xffff0000, v11
	v_pk_mov_b32 v[10:11], v[52:53], v[54:55] op_sel:[1,0]
	v_lshlrev_b32_e32 v57, 16, v12
	v_pk_mul_f32 v[10:11], v[30:31], v[10:11] op_sel_hi:[0,1]
	v_mov_b32_e32 v56, v54
	v_pk_fma_f32 v[10:11], v[28:29], v[52:53], v[10:11] op_sel_hi:[0,1,1]
	v_pk_fma_f32 v[10:11], v[20:21], v[56:57], v[10:11] op_sel_hi:[0,1,1]
	v_pk_add_f32 v[10:11], v[24:25], v[10:11] op_sel_hi:[0,1]
	v_and_b32_e32 v38, 0xffff0000, v13
	v_pk_mul_f32 v[10:11], v[10:11], v[46:47]
	v_and_b32_e32 v47, 16, v13
	v_and_b32_e32 v46, 0xffff0000, v12
	v_lshlrev_b32_e32 v53, 16, v13
	v_mov_b32_e32 v52, v46
	v_pk_mov_b32 v[12:13], v[56:57], v[46:47] op_sel:[1,0]
	v_mov_b32_e32 v46, v53
	v_mov_b32_e32 v47, v38
	v_pk_mul_f32 v[12:13], v[30:31], v[12:13] op_sel_hi:[0,1]
	v_pk_mul_f32 v[46:47], v[30:31], v[46:47] op_sel_hi:[0,1]
	v_pk_fma_f32 v[12:13], v[28:29], v[56:57], v[12:13] op_sel_hi:[0,1,1]
	v_pk_fma_f32 v[46:47], v[28:29], v[52:53], v[46:47] op_sel_hi:[0,1,1]
	v_pk_fma_f32 v[12:13], v[20:21], v[52:53], v[12:13] op_sel_hi:[0,1,1]
	v_pk_fma_f32 v[38:39], v[20:21], v[38:39], v[46:47] op_sel_hi:[0,1,1]
	s_xor_b64 s[70:71], s[70:71], -1
	v_pk_add_f32 v[12:13], v[24:25], v[12:13] op_sel_hi:[0,1]
	v_pk_add_f32 v[38:39], v[24:25], v[38:39] op_sel_hi:[0,1]
	s_waitcnt lgkmcnt(0)
	v_pk_mul_f32 v[12:13], v[12:13], v[48:49]
	v_pk_mul_f32 v[38:39], v[38:39], v[50:51]
	s_mov_b64 s[0:1], -1
	s_and_b64 vcc, exec, s[70:71]
	s_cbranch_vccz .LBB0_513
	v_bfe_u32 v46, v15, 16, 1
	v_add3_u32 v47, v15, v46, s4
	v_bfe_u32 v46, v14, 16, 1
	v_bfe_u32 v48, v16, 16, 1
	v_bfe_u32 v50, v42, 16, 1
	v_bfe_u32 v34, v17, 16, 1
	v_bfe_u32 v49, v40, 16, 1
	v_add3_u32 v50, v42, v50, s4
	v_add3_u32 v48, v16, v48, s4
	v_add3_u32 v46, v14, v46, s4
	v_bfe_u32 v25, v43, 16, 1
	v_bfe_u32 v28, v41, 16, 1
	v_add3_u32 v34, v17, v34, s4
	v_add3_u32 v49, v40, v49, s4
	v_lshrrev_b32_e32 v51, 16, v46
	v_lshrrev_b32_e32 v52, 16, v48
	v_lshrrev_b32_e32 v48, 16, v50
	v_bfe_u32 v50, v11, 16, 1
	v_add3_u32 v28, v41, v28, s4
	v_add3_u32 v25, v43, v25, s4
	v_lshrrev_b32_e32 v46, 16, v49
	v_and_or_b32 v49, v34, s91, v52
	v_and_or_b32 v47, v47, s91, v51
	v_add3_u32 v51, v11, v50, s4
	v_bfe_u32 v50, v10, 16, 1
	v_bfe_u32 v52, v38, 16, 1
	v_bfe_u32 v53, v44, 16, 1
	v_bfe_u32 v54, v12, 16, 1
	v_lshl_add_u64 v[36:37], v[36:37], 1, s[50:51]
	v_and_or_b32 v48, v25, s91, v48
	v_and_or_b32 v46, v28, s91, v46
	v_bfe_u32 v25, v13, 16, 1
	v_bfe_u32 v28, v45, 16, 1
	v_bfe_u32 v34, v39, 16, 1
	v_add3_u32 v54, v12, v54, s4
	v_add3_u32 v53, v44, v53, s4
	v_add3_u32 v52, v38, v52, s4
	v_add3_u32 v50, v10, v50, s4
	v_add3_u32 v34, v39, v34, s4
	v_add3_u32 v28, v45, v28, s4
	v_add3_u32 v25, v13, v25, s4
	v_lshrrev_b32_e32 v55, 16, v50
	v_lshrrev_b32_e32 v56, 16, v52
	v_lshrrev_b32_e32 v50, 16, v53
	v_lshrrev_b32_e32 v52, 16, v54
	v_lshl_add_u64 v[32:33], v[32:33], 1, v[36:37]
	v_and_or_b32 v52, v25, s91, v52
	v_and_or_b32 v50, v28, s91, v50
	v_and_or_b32 v53, v34, s91, v56
	v_and_or_b32 v51, v51, s91, v55
	global_store_dwordx4 v[32:33], v[46:49], off
	global_store_dwordx4 v[32:33], v[50:53], off offset:16
	s_mov_b64 s[0:1], 0

.LBB0_534:
	v_mov_b32_e32 v2, v210
	s_mov_b32 s43, s8
	v_and_b32_e32 v3, 0xff, v2
	v_lshlrev_b32_e32 v4, 5, v2
	v_and_or_b32 v3, v4, s33, v3
	v_ashrrev_i32_e32 v4, 5, v3
	v_lshlrev_b32_e32 v3, 3, v3
	v_lshlrev_b32_e32 v4, 3, v4
	v_add3_u32 v18, 0, v3, v4
	ds_read_b64 v[128:129], v18
	ds_read_b64 v[132:133], v18 offset:2112
	ds_read_b64 v[134:135], v18 offset:4224
	ds_read_b64 v[136:137], v18 offset:6336
	ds_read_b64 v[138:139], v18 offset:8448
	ds_read_b64 v[140:141], v18 offset:10560
	ds_read_b64 v[142:143], v18 offset:12672
	ds_read_b64 v[130:131], v18 offset:14784
	ds_read_b64 v[144:145], v18 offset:16896
	ds_read_b64 v[148:149], v18 offset:19008
	ds_read_b64 v[150:151], v18 offset:21120
	ds_read_b64 v[152:153], v18 offset:23232
	s_waitcnt lgkmcnt(10)
	v_pk_mul_f32 v[162:163], v[132:133], s[10:11]
	s_mov_b32 s64, s11
	v_pk_fma_f32 v[162:163], v[132:133], s[8:9], v[162:163] op_sel:[0,0,1] op_sel_hi:[1,0,0]
	s_waitcnt lgkmcnt(2)
	v_pk_mul_f32 v[178:179], v[148:149], s[42:43]
	v_pk_add_f32 v[194:195], v[132:133], v[148:149]
	v_pk_add_f32 v[132:133], v[132:133], v[148:149] neg_lo:[0,1] neg_hi:[0,1]
	v_pk_mul_f32 v[164:165], v[134:135], s[18:19]
	s_mov_b32 s41, s16
	v_pk_fma_f32 v[178:179], v[148:149], s[64:65], v[178:179] op_sel:[0,0,1] op_sel_hi:[1,0,0] neg_lo:[1,0,0] neg_hi:[1,0,0]
	v_pk_mul_f32 v[148:149], v[132:133], s[18:19]
	v_pk_fma_f32 v[164:165], v[134:135], s[16:17], v[164:165] op_sel:[0,0,1] op_sel_hi:[1,0,0]
	s_mov_b32 s68, s19
	s_waitcnt lgkmcnt(1)
	v_pk_mul_f32 v[180:181], v[150:151], s[40:41]
	v_pk_fma_f32 v[132:133], v[132:133], s[16:17], v[148:149] op_sel:[0,0,1] op_sel_hi:[1,0,0]
	v_pk_add_f32 v[148:149], v[134:135], v[150:151]
	v_pk_add_f32 v[134:135], v[134:135], v[150:151] neg_lo:[0,1] neg_hi:[0,1]
	v_pk_mul_f32 v[166:167], v[136:137], s[26:27]
	s_mov_b32 s66, s37
	s_mov_b32 s39, s24
	v_pk_fma_f32 v[180:181], v[150:151], s[68:69], v[180:181] op_sel:[0,0,1] op_sel_hi:[1,0,0] neg_lo:[1,0,0] neg_hi:[1,0,0]
	v_pk_mul_f32 v[150:151], v[134:135], s[36:37]
	ds_read_b64 v[154:155], v18 offset:25344
	ds_read_b64 v[156:157], v18 offset:27456
	ds_read_b64 v[158:159], v18 offset:29568
	ds_read_b64 v[160:161], v18 offset:31680
	v_pk_fma_f32 v[166:167], v[136:137], s[24:25], v[166:167] op_sel:[0,0,1] op_sel_hi:[1,0,0]
	s_mov_b32 s0, s27
	s_waitcnt lgkmcnt(4)
	v_pk_mul_f32 v[182:183], v[152:153], s[38:39]
	v_pk_fma_f32 v[134:135], v[134:135], s[66:67], v[150:151] op_sel:[0,0,1] op_sel_hi:[1,0,0]
	v_pk_add_f32 v[150:151], v[136:137], v[152:153]
	v_pk_add_f32 v[136:137], v[136:137], v[152:153] neg_lo:[0,1] neg_hi:[0,1]
	v_pk_mul_f32 v[168:169], v[138:139], s[36:37]
	v_pk_fma_f32 v[182:183], v[152:153], s[0:1], v[182:183] op_sel:[0,0,1] op_sel_hi:[1,0,0] neg_lo:[1,0,0] neg_hi:[1,0,0]
	v_pk_mul_f32 v[152:153], v[136:137], s[40:41]
	v_pk_fma_f32 v[168:169], v[138:139], s[66:67], v[168:169] op_sel:[0,0,1] op_sel_hi:[1,0,0]
	v_pk_mul_f32 v[170:171], v[140:141], s[38:39]
	s_waitcnt lgkmcnt(3)
	v_pk_mul_f32 v[184:185], v[154:155], s[36:37]
	v_pk_fma_f32 v[136:137], v[136:137], s[68:69], v[152:153] op_sel:[0,0,1] op_sel_hi:[1,0,0]
	v_pk_add_f32 v[152:153], v[138:139], v[154:155]
	v_pk_add_f32 v[138:139], v[138:139], v[154:155] neg_lo:[0,1] neg_hi:[0,1]
	v_pk_fma_f32 v[170:171], v[140:141], s[0:1], v[170:171] op_sel:[0,0,1] op_sel_hi:[1,0,0]
	v_pk_fma_f32 v[184:185], v[154:155], s[66:67], v[184:185] op_sel:[0,0,1] op_sel_hi:[1,0,0] neg_lo:[1,0,0] neg_hi:[1,0,0]
	s_waitcnt lgkmcnt(2)
	v_pk_mul_f32 v[186:187], v[156:157], s[26:27]
	v_pk_mul_f32 v[154:155], v[138:139], 1.0 op_sel:[1,0] op_sel_hi:[0,0] neg_hi:[1,0]
	v_pk_add_f32 v[138:139], v[140:141], v[156:157]
	v_pk_add_f32 v[140:141], v[140:141], v[156:157] neg_lo:[0,1] neg_hi:[0,1]
	v_pk_mul_f32 v[172:173], v[142:143], s[40:41]
	v_pk_fma_f32 v[186:187], v[156:157], s[24:25], v[186:187] op_sel:[0,0,1] op_sel_hi:[1,0,0] neg_lo:[1,0,0] neg_hi:[1,0,0]
	v_pk_mul_f32 v[156:157], v[140:141], s[40:41]
	v_pk_fma_f32 v[172:173], v[142:143], s[68:69], v[172:173] op_sel:[0,0,1] op_sel_hi:[1,0,0]
	s_waitcnt lgkmcnt(1)
	v_pk_mul_f32 v[188:189], v[158:159], s[18:19]
	v_pk_fma_f32 v[140:141], v[140:141], s[68:69], v[156:157] op_sel:[0,0,1] op_sel_hi:[1,0,0] neg_lo:[1,0,0] neg_hi:[1,0,0]
	v_pk_add_f32 v[156:157], v[142:143], v[158:159]
	v_pk_add_f32 v[142:143], v[142:143], v[158:159] neg_lo:[0,1] neg_hi:[0,1]
	v_pk_mul_f32 v[174:175], v[130:131], s[42:43]
	v_pk_fma_f32 v[188:189], v[158:159], s[16:17], v[188:189] op_sel:[0,0,1] op_sel_hi:[1,0,0] neg_lo:[1,0,0] neg_hi:[1,0,0]
	v_pk_mul_f32 v[158:159], v[142:143], s[36:37]
	v_pk_fma_f32 v[174:175], v[130:131], s[64:65], v[174:175] op_sel:[0,0,1] op_sel_hi:[1,0,0]
	s_waitcnt lgkmcnt(0)
	v_pk_mul_f32 v[190:191], v[160:161], s[10:11]
	v_pk_fma_f32 v[142:143], v[142:143], s[66:67], v[158:159] op_sel:[0,0,1] op_sel_hi:[1,0,0] neg_lo:[1,0,0] neg_hi:[1,0,0]
	v_pk_add_f32 v[158:159], v[130:131], v[160:161]
	v_pk_add_f32 v[130:131], v[130:131], v[160:161] neg_lo:[0,1] neg_hi:[0,1]
	v_pk_mul_f32 v[176:177], v[144:145], 1.0 op_sel:[1,0] op_sel_hi:[0,0] neg_hi:[1,0]
	v_pk_fma_f32 v[190:191], v[160:161], s[8:9], v[190:191] op_sel:[0,0,1] op_sel_hi:[1,0,0] neg_lo:[1,0,0] neg_hi:[1,0,0]
	v_pk_mul_f32 v[160:161], v[130:131], s[18:19]
	v_pk_add_f32 v[192:193], v[128:129], v[144:145]
	v_pk_add_f32 v[144:145], v[128:129], v[144:145] neg_lo:[0,1] neg_hi:[0,1]
	v_pk_fma_f32 v[130:131], v[130:131], s[16:17], v[160:161] op_sel:[0,0,1] op_sel_hi:[1,0,0] neg_lo:[1,0,0] neg_hi:[1,0,0]
	v_pk_add_f32 v[160:161], v[128:129], v[176:177]
	v_pk_add_f32 v[128:129], v[128:129], v[176:177] neg_lo:[0,1] neg_hi:[0,1]
	v_pk_add_f32 v[176:177], v[162:163], v[178:179]
	v_pk_add_f32 v[162:163], v[162:163], v[178:179] neg_lo:[0,1] neg_hi:[0,1]
	v_cvt_f32_ubyte0_e32 v2, v2
	v_pk_mul_f32 v[178:179], v[162:163], s[18:19]
	v_mul_f32_e32 v2, 0x39000000, v2
	v_pk_fma_f32 v[162:163], v[162:163], s[16:17], v[178:179] op_sel:[0,0,1] op_sel_hi:[1,0,0]
	v_pk_add_f32 v[178:179], v[164:165], v[180:181]
	v_pk_add_f32 v[164:165], v[164:165], v[180:181] neg_lo:[0,1] neg_hi:[0,1]
	v_sin_f32_e32 v34, v2
	v_pk_mul_f32 v[180:181], v[164:165], s[36:37]
	v_cos_f32_e32 v30, v2
	v_pk_fma_f32 v[164:165], v[164:165], s[66:67], v[180:181] op_sel:[0,0,1] op_sel_hi:[1,0,0]
	v_pk_add_f32 v[180:181], v[166:167], v[182:183]
	v_pk_add_f32 v[166:167], v[166:167], v[182:183] neg_lo:[0,1] neg_hi:[0,1]
	v_xor_b32_e32 v31, 0x80000000, v34
	v_pk_mul_f32 v[182:183], v[166:167], s[40:41]
	v_mov_b32_e32 v35, v31
	v_pk_fma_f32 v[166:167], v[166:167], s[68:69], v[182:183] op_sel:[0,0,1] op_sel_hi:[1,0,0]
	v_pk_add_f32 v[182:183], v[168:169], v[184:185]
	v_pk_add_f32 v[184:185], v[168:169], v[184:185] neg_lo:[0,1] neg_hi:[0,1]
	v_pk_mul_f32 v[2:3], v[30:31], v[34:35] op_sel:[1,0] op_sel_hi:[0,1]
	v_pk_add_f32 v[168:169], v[170:171], v[186:187]
	v_pk_add_f32 v[170:171], v[170:171], v[186:187] neg_lo:[0,1] neg_hi:[0,1]
	v_pk_fma_f32 v[44:45], v[30:31], v[30:31], v[2:3] op_sel_hi:[1,0,1]
	v_pk_mul_f32 v[186:187], v[170:171], s[40:41]
	v_pk_mul_f32 v[2:3], v[34:35], v[44:45] op_sel:[0,1] op_sel_hi:[1,0]
	v_pk_fma_f32 v[170:171], v[170:171], s[68:69], v[186:187] op_sel:[0,0,1] op_sel_hi:[1,0,0] neg_lo:[1,0,0] neg_hi:[1,0,0]
	v_pk_add_f32 v[186:187], v[172:173], v[188:189]
	v_pk_add_f32 v[172:173], v[172:173], v[188:189] neg_lo:[0,1] neg_hi:[0,1]
	v_pk_mul_f32 v[54:55], v[44:45], 1.0 op_sel:[1,0] op_sel_hi:[1,0] neg_lo:[1,0]
	v_pk_mul_f32 v[188:189], v[172:173], s[36:37]
	s_nop 0
	v_pk_fma_f32 v[172:173], v[172:173], s[66:67], v[188:189] op_sel:[0,0,1] op_sel_hi:[1,0,0] neg_lo:[1,0,0] neg_hi:[1,0,0]
	v_pk_add_f32 v[188:189], v[174:175], v[190:191]
	v_pk_add_f32 v[174:175], v[174:175], v[190:191] neg_lo:[0,1] neg_hi:[0,1]
	v_pk_fma_f32 v[46:47], v[30:31], v[44:45], v[2:3] op_sel_hi:[0,1,1]
	v_pk_mul_f32 v[190:191], v[174:175], s[18:19]
	v_pk_mul_f32 v[2:3], v[44:45], v[54:55] op_sel:[1,0] op_sel_hi:[0,1]
	v_pk_fma_f32 v[174:175], v[174:175], s[16:17], v[190:191] op_sel:[0,0,1] op_sel_hi:[1,0,0] neg_lo:[1,0,0] neg_hi:[1,0,0]
	v_pk_add_f32 v[190:191], v[192:193], v[152:153]
	v_pk_add_f32 v[152:153], v[192:193], v[152:153] neg_lo:[0,1] neg_hi:[0,1]
	v_pk_add_f32 v[192:193], v[194:195], v[138:139]
	v_pk_add_f32 v[138:139], v[194:195], v[138:139] neg_lo:[0,1] neg_hi:[0,1]
	v_pk_fma_f32 v[52:53], v[44:45], v[44:45], v[2:3] op_sel_hi:[1,0,1]
	v_pk_mul_f32 v[194:195], v[138:139], s[36:37]
	v_pk_mul_f32 v[58:59], v[52:53], 1.0 op_sel:[1,0] op_sel_hi:[1,0] neg_lo:[1,0]
	v_pk_fma_f32 v[138:139], v[138:139], s[66:67], v[194:195] op_sel:[0,0,1] op_sel_hi:[1,0,0]
	v_pk_add_f32 v[194:195], v[148:149], v[156:157]
	v_pk_add_f32 v[156:157], v[148:149], v[156:157] neg_lo:[0,1] neg_hi:[0,1]
	v_pk_add_f32 v[148:149], v[150:151], v[158:159]
	v_pk_add_f32 v[150:151], v[150:151], v[158:159] neg_lo:[0,1] neg_hi:[0,1]
	v_pk_mul_f32 v[2:3], v[52:53], v[58:59] op_sel:[1,0] op_sel_hi:[0,1]
	v_pk_mul_f32 v[158:159], v[150:151], s[36:37]
	v_pk_fma_f32 v[48:49], v[52:53], v[52:53], v[2:3] op_sel_hi:[1,0,1]
	v_pk_fma_f32 v[150:151], v[150:151], s[66:67], v[158:159] op_sel:[0,0,1] op_sel_hi:[1,0,0] neg_lo:[1,0,0] neg_hi:[1,0,0]
	v_pk_add_f32 v[158:159], v[144:145], v[154:155]
	v_pk_add_f32 v[144:145], v[144:145], v[154:155] neg_lo:[0,1] neg_hi:[0,1]
	v_pk_add_f32 v[154:155], v[132:133], v[140:141]
	v_pk_add_f32 v[132:133], v[132:133], v[140:141] neg_lo:[0,1] neg_hi:[0,1]
	v_pk_mul_f32 v[2:3], v[58:59], v[48:49] op_sel:[0,1] op_sel_hi:[1,0]
	v_pk_mul_f32 v[140:141], v[132:133], s[36:37]
	v_pk_fma_f32 v[36:37], v[52:53], v[48:49], v[2:3] op_sel_hi:[0,1,1]
	v_pk_fma_f32 v[132:133], v[132:133], s[66:67], v[140:141] op_sel:[0,0,1] op_sel_hi:[1,0,0]
	v_pk_add_f32 v[140:141], v[134:135], v[142:143]
	v_pk_add_f32 v[142:143], v[134:135], v[142:143] neg_lo:[0,1] neg_hi:[0,1]
	v_pk_mul_f32 v[2:3], v[58:59], v[36:37] op_sel:[0,1] op_sel_hi:[1,0]
	v_pk_add_f32 v[134:135], v[136:137], v[130:131]
	v_pk_add_f32 v[130:131], v[136:137], v[130:131] neg_lo:[0,1] neg_hi:[0,1]
	v_pk_fma_f32 v[26:27], v[52:53], v[36:37], v[2:3] op_sel_hi:[0,1,1]
	v_pk_mul_f32 v[136:137], v[130:131], s[36:37]
	v_pk_mul_f32 v[2:3], v[58:59], v[26:27] op_sel:[0,1] op_sel_hi:[1,0]
	v_pk_fma_f32 v[130:131], v[130:131], s[66:67], v[136:137] op_sel:[0,0,1] op_sel_hi:[1,0,0] neg_lo:[1,0,0] neg_hi:[1,0,0]
	v_pk_add_f32 v[136:137], v[160:161], v[182:183]
	v_pk_add_f32 v[160:161], v[160:161], v[182:183] neg_lo:[0,1] neg_hi:[0,1]
	v_pk_add_f32 v[182:183], v[176:177], v[168:169]
	v_pk_add_f32 v[168:169], v[176:177], v[168:169] neg_lo:[0,1] neg_hi:[0,1]
	v_pk_fma_f32 v[20:21], v[52:53], v[26:27], v[2:3] op_sel_hi:[0,1,1]
	v_pk_mul_f32 v[176:177], v[168:169], s[36:37]
	v_pk_mul_f32 v[2:3], v[58:59], v[20:21] op_sel:[0,1] op_sel_hi:[1,0]
	v_pk_fma_f32 v[168:169], v[168:169], s[66:67], v[176:177] op_sel:[0,0,1] op_sel_hi:[1,0,0]
	v_pk_add_f32 v[176:177], v[178:179], v[186:187]
	v_pk_add_f32 v[186:187], v[178:179], v[186:187] neg_lo:[0,1] neg_hi:[0,1]
	v_pk_fma_f32 v[10:11], v[52:53], v[20:21], v[2:3] op_sel_hi:[0,1,1]
	v_pk_add_f32 v[178:179], v[180:181], v[188:189]
	v_pk_add_f32 v[180:181], v[180:181], v[188:189] neg_lo:[0,1] neg_hi:[0,1]
	v_pk_mul_f32 v[2:3], v[58:59], v[10:11] op_sel:[0,1] op_sel_hi:[1,0]
	v_pk_mul_f32 v[188:189], v[180:181], s[36:37]
	v_pk_fma_f32 v[4:5], v[52:53], v[10:11], v[2:3] op_sel_hi:[0,1,1]
	v_pk_fma_f32 v[180:181], v[180:181], s[66:67], v[188:189] op_sel:[0,0,1] op_sel_hi:[1,0,0] neg_lo:[1,0,0] neg_hi:[1,0,0]
	v_pk_add_f32 v[188:189], v[128:129], v[184:185] op_sel:[0,1] op_sel_hi:[1,0] neg_hi:[0,1]
	v_pk_add_f32 v[128:129], v[128:129], v[184:185] op_sel:[0,1] op_sel_hi:[1,0] neg_lo:[0,1]
	v_pk_add_f32 v[184:185], v[162:163], v[170:171]
	v_pk_add_f32 v[162:163], v[162:163], v[170:171] neg_lo:[0,1] neg_hi:[0,1]
	v_pk_mul_f32 v[72:73], v[46:47], 1.0 op_sel:[1,0] op_sel_hi:[1,0] neg_lo:[1,0]
	v_pk_mul_f32 v[170:171], v[162:163], s[36:37]
	s_nop 0
	v_pk_fma_f32 v[162:163], v[162:163], s[66:67], v[170:171] op_sel:[0,0,1] op_sel_hi:[1,0,0]
	v_pk_add_f32 v[170:171], v[164:165], v[172:173]
	v_pk_add_f32 v[172:173], v[164:165], v[172:173] neg_lo:[0,1] neg_hi:[0,1]
	v_pk_mul_f32 v[2:3], v[72:73], v[4:5] op_sel:[0,1] op_sel_hi:[1,0]
	v_pk_add_f32 v[164:165], v[166:167], v[174:175]
	v_pk_add_f32 v[166:167], v[166:167], v[174:175] neg_lo:[0,1] neg_hi:[0,1]
	v_pk_mul_f32 v[14:15], v[34:35], v[4:5] op_sel:[0,1] op_sel_hi:[1,0]
	v_pk_mul_f32 v[174:175], v[166:167], s[36:37]
	v_pk_mul_f32 v[40:41], v[34:35], v[10:11] op_sel:[0,1] op_sel_hi:[1,0]
	v_pk_fma_f32 v[166:167], v[166:167], s[66:67], v[174:175] op_sel:[0,0,1] op_sel_hi:[1,0,0] neg_lo:[1,0,0] neg_hi:[1,0,0]
	v_pk_add_f32 v[174:175], v[190:191], v[194:195]
	v_pk_add_f32 v[190:191], v[190:191], v[194:195] neg_lo:[0,1] neg_hi:[0,1]
	v_pk_add_f32 v[194:195], v[192:193], v[148:149]
	v_pk_add_f32 v[192:193], v[192:193], v[148:149] neg_lo:[0,1] neg_hi:[0,1]
	v_pk_mul_f32 v[66:67], v[34:35], v[20:21] op_sel:[0,1] op_sel_hi:[1,0]
	v_pk_add_f32 v[148:149], v[152:153], v[156:157] op_sel:[0,1] op_sel_hi:[1,0] neg_hi:[0,1]
	v_pk_add_f32 v[152:153], v[152:153], v[156:157] op_sel:[0,1] op_sel_hi:[1,0] neg_lo:[0,1]
	v_pk_add_f32 v[156:157], v[138:139], v[150:151]
	v_pk_add_f32 v[150:151], v[138:139], v[150:151] neg_lo:[0,1] neg_hi:[0,1]
	v_pk_mul_f32 v[82:83], v[34:35], v[26:27] op_sel:[0,1] op_sel_hi:[1,0]
	v_pk_add_f32 v[138:139], v[158:159], v[140:141]
	v_pk_add_f32 v[140:141], v[158:159], v[140:141] neg_lo:[0,1] neg_hi:[0,1]
	v_pk_add_f32 v[158:159], v[154:155], v[134:135]
	v_pk_add_f32 v[154:155], v[154:155], v[134:135] neg_lo:[0,1] neg_hi:[0,1]
	v_pk_mul_f32 v[96:97], v[34:35], v[36:37] op_sel:[0,1] op_sel_hi:[1,0]
	v_pk_add_f32 v[134:135], v[144:145], v[142:143] op_sel:[0,1] op_sel_hi:[1,0] neg_hi:[0,1]
	v_pk_add_f32 v[142:143], v[144:145], v[142:143] op_sel:[0,1] op_sel_hi:[1,0] neg_lo:[0,1]
	v_pk_add_f32 v[144:145], v[132:133], v[130:131]
	v_pk_add_f32 v[132:133], v[132:133], v[130:131] neg_lo:[0,1] neg_hi:[0,1]
	v_pk_mul_f32 v[110:111], v[34:35], v[48:49] op_sel:[0,1] op_sel_hi:[1,0]
	v_pk_add_f32 v[130:131], v[136:137], v[176:177]
	v_pk_add_f32 v[136:137], v[136:137], v[176:177] neg_lo:[0,1] neg_hi:[0,1]
	v_pk_add_f32 v[176:177], v[182:183], v[178:179]
	v_pk_add_f32 v[182:183], v[182:183], v[178:179] neg_lo:[0,1] neg_hi:[0,1]
	v_pk_mul_f32 v[124:125], v[34:35], v[52:53] op_sel:[0,1] op_sel_hi:[1,0]
	v_pk_add_f32 v[178:179], v[160:161], v[186:187] op_sel:[0,1] op_sel_hi:[1,0] neg_hi:[0,1]
	v_pk_add_f32 v[160:161], v[160:161], v[186:187] op_sel:[0,1] op_sel_hi:[1,0] neg_lo:[0,1]
	v_pk_add_f32 v[186:187], v[168:169], v[180:181]
	v_pk_add_f32 v[180:181], v[168:169], v[180:181] neg_lo:[0,1] neg_hi:[0,1]
	v_pk_fma_f32 v[2:3], v[46:47], v[4:5], v[2:3] op_sel_hi:[0,1,1]
	v_pk_add_f32 v[168:169], v[188:189], v[170:171]
	v_pk_add_f32 v[170:171], v[188:189], v[170:171] neg_lo:[0,1] neg_hi:[0,1]
	v_pk_add_f32 v[188:189], v[184:185], v[164:165]
	v_pk_add_f32 v[184:185], v[184:185], v[164:165] neg_lo:[0,1] neg_hi:[0,1]
	v_pk_mul_f32 v[8:9], v[54:55], v[4:5] op_sel:[0,1] op_sel_hi:[1,0]
	v_pk_add_f32 v[164:165], v[128:129], v[172:173] op_sel:[0,1] op_sel_hi:[1,0] neg_hi:[0,1]
	v_pk_add_f32 v[128:129], v[128:129], v[172:173] op_sel:[0,1] op_sel_hi:[1,0] neg_lo:[0,1]
	v_pk_add_f32 v[172:173], v[162:163], v[166:167]
	v_pk_add_f32 v[166:167], v[162:163], v[166:167] neg_lo:[0,1] neg_hi:[0,1]
	v_pk_fma_f32 v[14:15], v[30:31], v[4:5], v[14:15] op_sel_hi:[0,1,1]
	v_pk_add_f32 v[162:163], v[174:175], v[194:195]
	v_pk_add_f32 v[174:175], v[174:175], v[194:195] neg_lo:[0,1] neg_hi:[0,1]
	v_pk_add_f32 v[194:195], v[190:191], v[192:193] op_sel:[0,1] op_sel_hi:[1,0] neg_hi:[0,1]
	v_pk_add_f32 v[190:191], v[190:191], v[192:193] op_sel:[0,1] op_sel_hi:[1,0] neg_lo:[0,1]
	v_pk_add_f32 v[192:193], v[148:149], v[156:157]
	v_pk_add_f32 v[148:149], v[148:149], v[156:157] neg_lo:[0,1] neg_hi:[0,1]
	v_pk_add_f32 v[156:157], v[152:153], v[150:151] op_sel:[0,1] op_sel_hi:[1,0] neg_hi:[0,1]
	v_pk_add_f32 v[150:151], v[152:153], v[150:151] op_sel:[0,1] op_sel_hi:[1,0] neg_lo:[0,1]
	v_pk_add_f32 v[152:153], v[138:139], v[158:159]
	v_pk_add_f32 v[138:139], v[138:139], v[158:159] neg_lo:[0,1] neg_hi:[0,1]
	v_pk_add_f32 v[158:159], v[140:141], v[154:155] op_sel:[0,1] op_sel_hi:[1,0] neg_hi:[0,1]
	v_pk_add_f32 v[140:141], v[140:141], v[154:155] op_sel:[0,1] op_sel_hi:[1,0] neg_lo:[0,1]
	v_pk_add_f32 v[154:155], v[134:135], v[144:145]
	v_pk_add_f32 v[134:135], v[134:135], v[144:145] neg_lo:[0,1] neg_hi:[0,1]
	v_pk_add_f32 v[144:145], v[142:143], v[132:133] op_sel:[0,1] op_sel_hi:[1,0] neg_hi:[0,1]
	v_pk_add_f32 v[132:133], v[142:143], v[132:133] op_sel:[0,1] op_sel_hi:[1,0] neg_lo:[0,1]
	v_pk_add_f32 v[142:143], v[130:131], v[176:177]
	v_pk_mul_f32 v[24:25], v[72:73], v[10:11] op_sel:[0,1] op_sel_hi:[1,0]
	v_pk_mul_f32 v[34:35], v[34:35], v[142:143] op_sel:[0,1] op_sel_hi:[1,0]
	v_pk_mul_f32 v[32:33], v[54:55], v[10:11] op_sel:[0,1] op_sel_hi:[1,0]
	v_pk_fma_f32 v[40:41], v[30:31], v[10:11], v[40:41] op_sel_hi:[0,1,1]
	v_pk_mul_f32 v[56:57], v[72:73], v[20:21] op_sel:[0,1] op_sel_hi:[1,0]
	v_pk_mul_f32 v[62:63], v[54:55], v[20:21] op_sel:[0,1] op_sel_hi:[1,0]
	v_pk_fma_f32 v[66:67], v[30:31], v[20:21], v[66:67] op_sel_hi:[0,1,1]
	v_pk_mul_f32 v[74:75], v[72:73], v[26:27] op_sel:[0,1] op_sel_hi:[1,0]
	v_pk_mul_f32 v[78:79], v[54:55], v[26:27] op_sel:[0,1] op_sel_hi:[1,0]
	v_pk_fma_f32 v[82:83], v[30:31], v[26:27], v[82:83] op_sel_hi:[0,1,1]
	v_pk_mul_f32 v[88:89], v[72:73], v[36:37] op_sel:[0,1] op_sel_hi:[1,0]
	v_pk_mul_f32 v[92:93], v[54:55], v[36:37] op_sel:[0,1] op_sel_hi:[1,0]
	v_pk_fma_f32 v[96:97], v[30:31], v[36:37], v[96:97] op_sel_hi:[0,1,1]
	v_pk_mul_f32 v[102:103], v[72:73], v[48:49] op_sel:[0,1] op_sel_hi:[1,0]
	v_pk_mul_f32 v[106:107], v[54:55], v[48:49] op_sel:[0,1] op_sel_hi:[1,0]
	v_pk_fma_f32 v[110:111], v[30:31], v[48:49], v[110:111] op_sel_hi:[0,1,1]
	v_pk_mul_f32 v[116:117], v[52:53], v[72:73] op_sel:[1,0] op_sel_hi:[0,1]
	v_pk_mul_f32 v[120:121], v[54:55], v[52:53] op_sel:[0,1] op_sel_hi:[1,0]
	v_pk_fma_f32 v[124:125], v[30:31], v[52:53], v[124:125] op_sel_hi:[0,1,1]
	v_pk_add_f32 v[130:131], v[130:131], v[176:177] neg_lo:[0,1] neg_hi:[0,1]
	v_pk_add_f32 v[176:177], v[136:137], v[182:183] op_sel:[0,1] op_sel_hi:[1,0] neg_hi:[0,1]
	v_pk_add_f32 v[136:137], v[136:137], v[182:183] op_sel:[0,1] op_sel_hi:[1,0] neg_lo:[0,1]
	v_pk_add_f32 v[182:183], v[178:179], v[186:187]
	v_pk_add_f32 v[178:179], v[178:179], v[186:187] neg_lo:[0,1] neg_hi:[0,1]
	v_pk_add_f32 v[186:187], v[160:161], v[180:181] op_sel:[0,1] op_sel_hi:[1,0] neg_hi:[0,1]
	v_pk_add_f32 v[160:161], v[160:161], v[180:181] op_sel:[0,1] op_sel_hi:[1,0] neg_lo:[0,1]
	v_pk_add_f32 v[180:181], v[168:169], v[188:189]
	v_pk_fma_f32 v[30:31], v[30:31], v[142:143], v[34:35] op_sel_hi:[0,1,1]
	v_pk_mul_f32 v[34:35], v[54:55], v[152:153] op_sel:[0,1] op_sel_hi:[1,0]
	v_xor_b32_e32 v6, 0x80000000, v3
	v_pk_fma_f32 v[8:9], v[44:45], v[4:5], v[8:9] op_sel_hi:[0,1,1]
	v_pk_fma_f32 v[24:25], v[46:47], v[10:11], v[24:25] op_sel_hi:[0,1,1]
	v_pk_fma_f32 v[32:33], v[44:45], v[10:11], v[32:33] op_sel_hi:[0,1,1]
	v_pk_fma_f32 v[56:57], v[46:47], v[20:21], v[56:57] op_sel_hi:[0,1,1]
	v_pk_fma_f32 v[62:63], v[44:45], v[20:21], v[62:63] op_sel_hi:[0,1,1]
	v_pk_fma_f32 v[74:75], v[46:47], v[26:27], v[74:75] op_sel_hi:[0,1,1]
	v_pk_fma_f32 v[78:79], v[44:45], v[26:27], v[78:79] op_sel_hi:[0,1,1]
	v_pk_fma_f32 v[88:89], v[46:47], v[36:37], v[88:89] op_sel_hi:[0,1,1]
	v_pk_fma_f32 v[92:93], v[44:45], v[36:37], v[92:93] op_sel_hi:[0,1,1]
	v_pk_fma_f32 v[102:103], v[46:47], v[48:49], v[102:103] op_sel_hi:[0,1,1]
	v_pk_fma_f32 v[106:107], v[44:45], v[48:49], v[106:107] op_sel_hi:[0,1,1]
	v_pk_mul_f32 v[114:115], v[48:49], 1.0 op_sel:[1,0] op_sel_hi:[1,0] neg_lo:[1,0]
	v_pk_fma_f32 v[116:117], v[52:53], v[46:47], v[116:117] op_sel_hi:[1,0,1]
	v_pk_fma_f32 v[120:121], v[44:45], v[52:53], v[120:121] op_sel_hi:[0,1,1]
	v_mov_b32_e32 v7, v3
	v_pk_add_f32 v[168:169], v[168:169], v[188:189] neg_lo:[0,1] neg_hi:[0,1]
	v_pk_add_f32 v[188:189], v[170:171], v[184:185] op_sel:[0,1] op_sel_hi:[1,0] neg_hi:[0,1]
	v_pk_add_f32 v[170:171], v[170:171], v[184:185] op_sel:[0,1] op_sel_hi:[1,0] neg_lo:[0,1]
	v_pk_add_f32 v[184:185], v[164:165], v[172:173]
	v_pk_add_f32 v[164:165], v[164:165], v[172:173] neg_lo:[0,1] neg_hi:[0,1]
	v_pk_add_f32 v[172:173], v[128:129], v[166:167] op_sel:[0,1] op_sel_hi:[1,0] neg_hi:[0,1]
	v_pk_add_f32 v[128:129], v[128:129], v[166:167] op_sel:[0,1] op_sel_hi:[1,0] neg_lo:[0,1]
	v_pk_fma_f32 v[34:35], v[44:45], v[152:153], v[34:35] op_sel_hi:[0,1,1]
	v_pk_mul_f32 v[44:45], v[72:73], v[180:181] op_sel:[0,1] op_sel_hi:[1,0]
	v_xor_b32_e32 v12, 0x80000000, v9
	v_xor_b32_e32 v16, 0x80000000, v15
	v_xor_b32_e32 v22, 0x80000000, v5
	v_xor_b32_e32 v28, 0x80000000, v25
	v_xor_b32_e32 v38, 0x80000000, v33
	v_xor_b32_e32 v42, 0x80000000, v41
	v_xor_b32_e32 v50, 0x80000000, v11
	v_xor_b32_e32 v60, 0x80000000, v57
	v_xor_b32_e32 v64, 0x80000000, v63
	v_xor_b32_e32 v68, 0x80000000, v67
	v_xor_b32_e32 v70, 0x80000000, v21
	v_xor_b32_e32 v76, 0x80000000, v75
	v_xor_b32_e32 v80, 0x80000000, v79
	v_xor_b32_e32 v84, 0x80000000, v83
	v_xor_b32_e32 v86, 0x80000000, v27
	v_xor_b32_e32 v90, 0x80000000, v89
	v_xor_b32_e32 v94, 0x80000000, v93
	v_xor_b32_e32 v98, 0x80000000, v97
	v_xor_b32_e32 v100, 0x80000000, v37
	v_xor_b32_e32 v104, 0x80000000, v103
	v_xor_b32_e32 v108, 0x80000000, v107
	v_xor_b32_e32 v112, 0x80000000, v111
	v_pk_mul_f32 v[118:119], v[116:117], 1.0 op_sel:[1,0] op_sel_hi:[1,0] neg_lo:[1,0]
	v_pk_mul_f32 v[122:123], v[120:121], 1.0 op_sel:[1,0] op_sel_hi:[1,0] neg_lo:[1,0]
	v_pk_mul_f32 v[126:127], v[124:125], 1.0 op_sel:[1,0] op_sel_hi:[1,0] neg_lo:[1,0]
	v_mov_b32_e32 v113, v111
	v_mov_b32_e32 v109, v107
	v_mov_b32_e32 v105, v103
	v_mov_b32_e32 v101, v37
	v_mov_b32_e32 v99, v97
	v_mov_b32_e32 v95, v93
	v_mov_b32_e32 v91, v89
	v_mov_b32_e32 v87, v27
	v_mov_b32_e32 v85, v83
	v_mov_b32_e32 v81, v79
	v_mov_b32_e32 v77, v75
	v_mov_b32_e32 v71, v21
	v_mov_b32_e32 v69, v67
	v_mov_b32_e32 v65, v63
	v_mov_b32_e32 v61, v57
	v_mov_b32_e32 v51, v11
	v_mov_b32_e32 v43, v41
	v_mov_b32_e32 v39, v33
	v_mov_b32_e32 v29, v25
	v_mov_b32_e32 v23, v5
	v_mov_b32_e32 v17, v15
	v_mov_b32_e32 v13, v9
	v_pk_fma_f32 v[44:45], v[46:47], v[180:181], v[44:45] op_sel_hi:[0,1,1]
	v_pk_mul_f32 v[46:47], v[58:59], v[192:193] op_sel:[0,1] op_sel_hi:[1,0]
	v_pk_mul_f32 v[72:73], v[114:115], v[194:195] op_sel:[0,1] op_sel_hi:[1,0]
	v_pk_mul_f32 v[6:7], v[128:129], v[6:7] op_sel:[1,0] op_sel_hi:[0,1]
	v_pk_fma_f32 v[46:47], v[52:53], v[192:193], v[46:47] op_sel_hi:[0,1,1]
	v_pk_mul_f32 v[52:53], v[126:127], v[182:183] op_sel:[0,1] op_sel_hi:[1,0]
	v_pk_mul_f32 v[54:55], v[122:123], v[154:155] op_sel:[0,1] op_sel_hi:[1,0]
	v_pk_mul_f32 v[58:59], v[118:119], v[184:185] op_sel:[0,1] op_sel_hi:[1,0]
	v_pk_fma_f32 v[48:49], v[48:49], v[194:195], v[72:73] op_sel_hi:[0,1,1]
	v_pk_mul_f32 v[72:73], v[112:113], v[176:177] op_sel:[0,1] op_sel_hi:[1,0]
	v_pk_mul_f32 v[108:109], v[108:109], v[158:159] op_sel:[0,1] op_sel_hi:[1,0]
	v_pk_mul_f32 v[104:105], v[104:105], v[188:189] op_sel:[0,1] op_sel_hi:[1,0]
	v_pk_mul_f32 v[100:101], v[100:101], v[156:157] op_sel:[0,1] op_sel_hi:[1,0]
	v_pk_mul_f32 v[98:99], v[98:99], v[186:187] op_sel:[0,1] op_sel_hi:[1,0]
	v_pk_mul_f32 v[94:95], v[94:95], v[144:145] op_sel:[0,1] op_sel_hi:[1,0]
	v_pk_mul_f32 v[90:91], v[90:91], v[172:173] op_sel:[0,1] op_sel_hi:[1,0]
	v_pk_mul_f32 v[86:87], v[174:175], v[86:87] op_sel:[1,0] op_sel_hi:[0,1]
	v_pk_mul_f32 v[84:85], v[130:131], v[84:85] op_sel:[1,0] op_sel_hi:[0,1]
	v_pk_mul_f32 v[80:81], v[138:139], v[80:81] op_sel:[1,0] op_sel_hi:[0,1]
	v_pk_mul_f32 v[76:77], v[168:169], v[76:77] op_sel:[1,0] op_sel_hi:[0,1]
	v_pk_mul_f32 v[70:71], v[148:149], v[70:71] op_sel:[1,0] op_sel_hi:[0,1]
	v_pk_mul_f32 v[68:69], v[178:179], v[68:69] op_sel:[1,0] op_sel_hi:[0,1]
	v_pk_mul_f32 v[64:65], v[134:135], v[64:65] op_sel:[1,0] op_sel_hi:[0,1]
	v_pk_mul_f32 v[60:61], v[164:165], v[60:61] op_sel:[1,0] op_sel_hi:[0,1]
	v_pk_mul_f32 v[50:51], v[190:191], v[50:51] op_sel:[1,0] op_sel_hi:[0,1]
	v_pk_mul_f32 v[42:43], v[136:137], v[42:43] op_sel:[1,0] op_sel_hi:[0,1]
	v_pk_mul_f32 v[38:39], v[140:141], v[38:39] op_sel:[1,0] op_sel_hi:[0,1]
	v_pk_mul_f32 v[28:29], v[170:171], v[28:29] op_sel:[1,0] op_sel_hi:[0,1]
	v_pk_mul_f32 v[22:23], v[150:151], v[22:23] op_sel:[1,0] op_sel_hi:[0,1]
	v_pk_mul_f32 v[16:17], v[160:161], v[16:17] op_sel:[1,0] op_sel_hi:[0,1]
	v_pk_mul_f32 v[12:13], v[132:133], v[12:13] op_sel:[1,0] op_sel_hi:[0,1]
	v_pk_fma_f32 v[2:3], v[128:129], v[2:3], v[6:7] op_sel_hi:[1,0,1]
	v_pk_fma_f32 v[52:53], v[124:125], v[182:183], v[52:53] op_sel_hi:[0,1,1]
	v_pk_fma_f32 v[54:55], v[120:121], v[154:155], v[54:55] op_sel_hi:[0,1,1]
	v_pk_fma_f32 v[58:59], v[116:117], v[184:185], v[58:59] op_sel_hi:[0,1,1]
	v_pk_fma_f32 v[72:73], v[110:111], v[176:177], v[72:73] op_sel_hi:[0,1,1]
	v_pk_fma_f32 v[106:107], v[106:107], v[158:159], v[108:109] op_sel_hi:[0,1,1]
	v_pk_fma_f32 v[102:103], v[102:103], v[188:189], v[104:105] op_sel_hi:[0,1,1]
	v_pk_fma_f32 v[36:37], v[36:37], v[156:157], v[100:101] op_sel_hi:[0,1,1]
	v_pk_fma_f32 v[96:97], v[96:97], v[186:187], v[98:99] op_sel_hi:[0,1,1]
	v_pk_fma_f32 v[92:93], v[92:93], v[144:145], v[94:95] op_sel_hi:[0,1,1]
	v_pk_fma_f32 v[88:89], v[88:89], v[172:173], v[90:91] op_sel_hi:[0,1,1]
	v_pk_fma_f32 v[26:27], v[174:175], v[26:27], v[86:87] op_sel_hi:[1,0,1]
	v_pk_fma_f32 v[82:83], v[130:131], v[82:83], v[84:85] op_sel_hi:[1,0,1]
	v_pk_fma_f32 v[78:79], v[138:139], v[78:79], v[80:81] op_sel_hi:[1,0,1]
	v_pk_fma_f32 v[74:75], v[168:169], v[74:75], v[76:77] op_sel_hi:[1,0,1]
	v_pk_fma_f32 v[20:21], v[148:149], v[20:21], v[70:71] op_sel_hi:[1,0,1]
	v_pk_fma_f32 v[66:67], v[178:179], v[66:67], v[68:69] op_sel_hi:[1,0,1]
	v_pk_fma_f32 v[62:63], v[134:135], v[62:63], v[64:65] op_sel_hi:[1,0,1]
	v_pk_fma_f32 v[56:57], v[164:165], v[56:57], v[60:61] op_sel_hi:[1,0,1]
	v_pk_fma_f32 v[10:11], v[190:191], v[10:11], v[50:51] op_sel_hi:[1,0,1]
	v_pk_fma_f32 v[40:41], v[136:137], v[40:41], v[42:43] op_sel_hi:[1,0,1]
	v_pk_fma_f32 v[32:33], v[140:141], v[32:33], v[38:39] op_sel_hi:[1,0,1]
	v_pk_fma_f32 v[24:25], v[170:171], v[24:25], v[28:29] op_sel_hi:[1,0,1]
	v_pk_fma_f32 v[4:5], v[150:151], v[4:5], v[22:23] op_sel_hi:[1,0,1]
	v_pk_fma_f32 v[14:15], v[160:161], v[14:15], v[16:17] op_sel_hi:[1,0,1]
	v_pk_fma_f32 v[8:9], v[132:133], v[8:9], v[12:13] op_sel_hi:[1,0,1]
	ds_write_b64 v18, v[162:163]
	ds_write_b64 v18, v[26:27] offset:2112
	ds_write_b64 v18, v[48:49] offset:4224
	ds_write_b64 v18, v[10:11] offset:6336
	ds_write_b64 v18, v[46:47] offset:8448
	ds_write_b64 v18, v[20:21] offset:10560
	ds_write_b64 v18, v[36:37] offset:12672
	ds_write_b64 v18, v[4:5] offset:14784
	ds_write_b64 v18, v[34:35] offset:16896
	ds_write_b64 v18, v[78:79] offset:19008
	ds_write_b64 v18, v[106:107] offset:21120
	ds_write_b64 v18, v[32:33] offset:23232
	ds_write_b64 v18, v[54:55] offset:25344
	ds_write_b64 v18, v[62:63] offset:27456
	ds_write_b64 v18, v[92:93] offset:29568
	ds_write_b64 v18, v[8:9] offset:31680
	ds_write_b64 v18, v[30:31] offset:33792
	ds_write_b64 v18, v[82:83] offset:35904
	ds_write_b64 v18, v[72:73] offset:38016
	ds_write_b64 v18, v[40:41] offset:40128
	ds_write_b64 v18, v[52:53] offset:42240
	ds_write_b64 v18, v[66:67] offset:44352
	ds_write_b64 v18, v[96:97] offset:46464
	ds_write_b64 v18, v[14:15] offset:48576
	ds_write_b64 v18, v[44:45] offset:50688
	ds_write_b64 v18, v[74:75] offset:52800
	ds_write_b64 v18, v[102:103] offset:54912
	ds_write_b64 v18, v[24:25] offset:57024
	ds_write_b64 v18, v[58:59] offset:59136
	ds_write_b64 v18, v[56:57] offset:61248
	ds_write_b64 v18, v[88:89] offset:63360
	ds_write_b64 v18, v[2:3] offset:65472
	v_mov_b32_e32 v3, v210
	s_waitcnt lgkmcnt(0)
	s_barrier
	s_add_i32 s64, s62, s48
	v_and_b32_e32 v5, 15, v3
	v_cvt_f32_ubyte0_e32 v2, v5
	v_mul_f32_e32 v4, 0x3b800000, v2
	v_sin_f32_e32 v2, v4
	v_cos_f32_e32 v4, v4
	v_lshlrev_b32_e32 v64, 3, v5
	v_lshlrev_b32_e32 v18, 4, v3
	v_xor_b32_e32 v5, 0x80000000, v2
	v_mov_b32_e32 v3, v5
	v_pk_mul_f32 v[6:7], v[4:5], v[2:3] op_sel:[1,0] op_sel_hi:[0,1]
	v_pk_fma_f32 v[6:7], v[4:5], v[4:5], v[6:7] op_sel_hi:[1,0,1]
	s_ashr_i32 s65, s64, 31
	v_pk_mul_f32 v[12:13], 1.0, v[6:7] op_sel:[0,1] op_sel_hi:[0,1] neg_lo:[0,1]
	v_pk_mul_f32 v[10:11], v[6:7], v[12:13] op_sel:[1,0] op_sel_hi:[0,1]
	v_pk_fma_f32 v[10:11], v[6:7], v[6:7], v[10:11] op_sel_hi:[1,0,1]
	v_pk_mul_f32 v[8:9], v[2:3], v[6:7] op_sel:[0,1] op_sel_hi:[1,0]
	v_pk_mul_f32 v[14:15], 1.0, v[10:11] op_sel:[0,1] op_sel_hi:[0,1] neg_lo:[0,1]
	v_pk_mul_f32 v[32:33], v[10:11], v[14:15] op_sel:[1,0] op_sel_hi:[0,1]
	v_pk_fma_f32 v[32:33], v[10:11], v[10:11], v[32:33] op_sel_hi:[1,0,1]
	v_pk_mul_f32 v[16:17], v[2:3], v[10:11] op_sel:[0,1] op_sel_hi:[1,0]
	v_pk_mul_f32 v[48:49], v[14:15], v[32:33] op_sel:[0,1] op_sel_hi:[1,0]
	v_pk_mul_f32 v[36:37], v[2:3], v[32:33] op_sel:[0,1] op_sel_hi:[1,0]
	v_pk_fma_f32 v[48:49], v[10:11], v[32:33], v[48:49] op_sel_hi:[0,1,1]
	v_pk_mul_f32 v[52:53], v[2:3], v[48:49] op_sel:[0,1] op_sel_hi:[1,0]
	v_pk_fma_f32 v[8:9], v[4:5], v[6:7], v[8:9] op_sel_hi:[0,1,1]
	v_pk_fma_f32 v[16:17], v[4:5], v[10:11], v[16:17] op_sel_hi:[0,1,1]
	v_pk_fma_f32 v[36:37], v[4:5], v[32:33], v[36:37] op_sel_hi:[0,1,1]
	v_pk_fma_f32 v[52:53], v[4:5], v[48:49], v[52:53] op_sel_hi:[0,1,1]
	v_and_b32_e32 v5, 0xffffff00, v18
	v_lshlrev_b32_e32 v18, 3, v5
	v_add3_u32 v18, 0, v64, v18
	v_ashrrev_i32_e32 v64, 2, v5
	v_add_u32_e32 v106, v18, v64
	ds_read2_b64 v[64:67], v106 offset1:16
	ds_read2_b64 v[68:71], v106 offset0:33 offset1:49
	ds_read2_b64 v[72:75], v106 offset0:66 offset1:82
	ds_read2_b64 v[76:79], v106 offset0:132 offset1:148
	ds_read2_b64 v[80:83], v106 offset0:99 offset1:115
	ds_read2_b64 v[84:87], v106 offset0:165 offset1:181
	ds_read2_b64 v[88:91], v106 offset0:198 offset1:214
	ds_read2_b64 v[92:95], v106 offset0:231 offset1:247
	s_waitcnt lgkmcnt(4)
	v_pk_add_f32 v[96:97], v[64:65], v[76:77]
	v_pk_add_f32 v[64:65], v[64:65], v[76:77] neg_lo:[0,1] neg_hi:[0,1]
	v_pk_add_f32 v[76:77], v[66:67], v[78:79]
	v_pk_add_f32 v[66:67], v[66:67], v[78:79] neg_lo:[0,1] neg_hi:[0,1]
	s_waitcnt lgkmcnt(1)
	v_pk_add_f32 v[98:99], v[74:75], v[90:91]
	v_pk_mul_f32 v[78:79], v[66:67], s[18:19]
	v_pk_add_f32 v[74:75], v[74:75], v[90:91] neg_lo:[0,1] neg_hi:[0,1]
	v_pk_fma_f32 v[66:67], v[66:67], s[16:17], v[78:79] op_sel:[0,0,1] op_sel_hi:[1,0,0]
	v_pk_add_f32 v[78:79], v[68:69], v[84:85]
	v_pk_add_f32 v[68:69], v[68:69], v[84:85] neg_lo:[0,1] neg_hi:[0,1]
	v_pk_mul_f32 v[90:91], v[74:75], s[40:41]
	v_pk_mul_f32 v[84:85], v[68:69], s[36:37]
	v_pk_fma_f32 v[74:75], v[74:75], s[68:69], v[90:91] op_sel:[0,0,1] op_sel_hi:[1,0,0] neg_lo:[1,0,0] neg_hi:[1,0,0]
	v_pk_fma_f32 v[68:69], v[68:69], s[66:67], v[84:85] op_sel:[0,0,1] op_sel_hi:[1,0,0]
	v_pk_add_f32 v[84:85], v[70:71], v[86:87]
	v_pk_add_f32 v[70:71], v[70:71], v[86:87] neg_lo:[0,1] neg_hi:[0,1]
	s_waitcnt lgkmcnt(0)
	v_pk_add_f32 v[90:91], v[80:81], v[92:93]
	v_pk_add_f32 v[80:81], v[80:81], v[92:93] neg_lo:[0,1] neg_hi:[0,1]
	v_pk_mul_f32 v[86:87], v[70:71], s[40:41]
	v_pk_mul_f32 v[92:93], v[80:81], s[36:37]
	v_pk_fma_f32 v[70:71], v[70:71], s[68:69], v[86:87] op_sel:[0,0,1] op_sel_hi:[1,0,0]
	v_pk_add_f32 v[86:87], v[72:73], v[88:89]
	v_pk_add_f32 v[88:89], v[72:73], v[88:89] neg_lo:[0,1] neg_hi:[0,1]
	v_pk_fma_f32 v[80:81], v[80:81], s[66:67], v[92:93] op_sel:[0,0,1] op_sel_hi:[1,0,0] neg_lo:[1,0,0] neg_hi:[1,0,0]
	v_pk_add_f32 v[92:93], v[82:83], v[94:95]
	v_pk_add_f32 v[82:83], v[82:83], v[94:95] neg_lo:[0,1] neg_hi:[0,1]
	s_nop 0
	v_pk_mul_f32 v[94:95], v[82:83], s[18:19]
	s_nop 0
	v_pk_fma_f32 v[82:83], v[82:83], s[16:17], v[94:95] op_sel:[0,0,1] op_sel_hi:[1,0,0] neg_lo:[1,0,0] neg_hi:[1,0,0]
	v_pk_add_f32 v[94:95], v[96:97], v[86:87]
	v_pk_add_f32 v[86:87], v[96:97], v[86:87] neg_lo:[0,1] neg_hi:[0,1]
	v_pk_add_f32 v[96:97], v[76:77], v[98:99]
	v_pk_add_f32 v[76:77], v[76:77], v[98:99] neg_lo:[0,1] neg_hi:[0,1]
	v_pk_add_f32 v[100:101], v[84:85], v[92:93]
	v_pk_add_f32 v[84:85], v[84:85], v[92:93] neg_lo:[0,1] neg_hi:[0,1]
	v_pk_add_f32 v[72:73], v[64:65], v[88:89] op_sel:[0,1] op_sel_hi:[1,0] neg_hi:[0,1]
	v_pk_add_f32 v[64:65], v[64:65], v[88:89] op_sel:[0,1] op_sel_hi:[1,0] neg_lo:[0,1]
	v_pk_add_f32 v[88:89], v[66:67], v[74:75]
	v_pk_add_f32 v[66:67], v[66:67], v[74:75] neg_lo:[0,1] neg_hi:[0,1]
	v_pk_mul_f32 v[98:99], v[76:77], s[36:37]
	v_pk_mul_f32 v[92:93], v[84:85], s[36:37]
	v_pk_mul_f32 v[74:75], v[66:67], s[36:37]
	v_pk_fma_f32 v[76:77], v[76:77], s[66:67], v[98:99] op_sel:[0,0,1] op_sel_hi:[1,0,0]
	v_pk_add_f32 v[98:99], v[78:79], v[90:91]
	v_pk_add_f32 v[90:91], v[78:79], v[90:91] neg_lo:[0,1] neg_hi:[0,1]
	v_pk_fma_f32 v[84:85], v[84:85], s[66:67], v[92:93] op_sel:[0,0,1] op_sel_hi:[1,0,0] neg_lo:[1,0,0] neg_hi:[1,0,0]
	v_pk_fma_f32 v[66:67], v[66:67], s[66:67], v[74:75] op_sel:[0,0,1] op_sel_hi:[1,0,0]
	v_pk_add_f32 v[74:75], v[68:69], v[80:81]
	v_pk_add_f32 v[92:93], v[70:71], v[82:83]
	v_pk_add_f32 v[70:71], v[70:71], v[82:83] neg_lo:[0,1] neg_hi:[0,1]
	v_pk_add_f32 v[80:81], v[68:69], v[80:81] neg_lo:[0,1] neg_hi:[0,1]
	v_pk_mul_f32 v[82:83], v[70:71], s[36:37]
	v_pk_add_f32 v[102:103], v[72:73], v[74:75]
	v_pk_add_f32 v[72:73], v[72:73], v[74:75] neg_lo:[0,1] neg_hi:[0,1]
	v_pk_add_f32 v[74:75], v[88:89], v[92:93]
	v_pk_add_f32 v[92:93], v[88:89], v[92:93] neg_lo:[0,1] neg_hi:[0,1]
	v_pk_mul_f32 v[20:21], v[8:9], 1.0 op_sel:[1,0] op_sel_hi:[1,0] neg_lo:[1,0]
	v_pk_mul_f32 v[24:25], v[12:13], v[10:11] op_sel:[0,1] op_sel_hi:[1,0]
	v_pk_fma_f32 v[70:71], v[70:71], s[66:67], v[82:83] op_sel:[0,0,1] op_sel_hi:[1,0,0] neg_lo:[1,0,0] neg_hi:[1,0,0]
	v_pk_add_f32 v[78:79], v[86:87], v[90:91] op_sel:[0,1] op_sel_hi:[1,0] neg_hi:[0,1]
	v_pk_add_f32 v[86:87], v[86:87], v[90:91] op_sel:[0,1] op_sel_hi:[1,0] neg_lo:[0,1]
	v_pk_add_f32 v[90:91], v[76:77], v[84:85]
	v_pk_add_f32 v[84:85], v[76:77], v[84:85] neg_lo:[0,1] neg_hi:[0,1]
	v_pk_mul_f32 v[22:23], v[16:17], 1.0 op_sel:[1,0] op_sel_hi:[1,0] neg_lo:[1,0]
	v_pk_fma_f32 v[24:25], v[6:7], v[10:11], v[24:25] op_sel_hi:[0,1,1]
	v_pk_mul_f32 v[28:29], v[10:11], v[20:21] op_sel:[1,0] op_sel_hi:[0,1]
	v_pk_add_f32 v[68:69], v[64:65], v[80:81] op_sel:[0,1] op_sel_hi:[1,0] neg_hi:[0,1]
	v_pk_add_f32 v[64:65], v[64:65], v[80:81] op_sel:[0,1] op_sel_hi:[1,0] neg_lo:[0,1]
	v_pk_add_f32 v[80:81], v[66:67], v[70:71]
	v_pk_add_f32 v[70:71], v[66:67], v[70:71] neg_lo:[0,1] neg_hi:[0,1]
	v_pk_add_f32 v[88:89], v[72:73], v[92:93] op_sel:[0,1] op_sel_hi:[1,0] neg_hi:[0,1]
	v_pk_mul_f32 v[26:27], v[24:25], 1.0 op_sel:[1,0] op_sel_hi:[1,0] neg_lo:[1,0]
	v_pk_fma_f32 v[28:29], v[10:11], v[8:9], v[28:29] op_sel_hi:[1,0,1]
	v_pk_add_f32 v[76:77], v[86:87], v[84:85] op_sel:[0,1] op_sel_hi:[1,0] neg_hi:[0,1]
	v_pk_add_f32 v[72:73], v[72:73], v[92:93] op_sel:[0,1] op_sel_hi:[1,0] neg_lo:[0,1]
	v_pk_mul_f32 v[92:93], v[22:23], v[88:89] op_sel:[0,1] op_sel_hi:[1,0]
	v_pk_mul_f32 v[30:31], v[28:29], 1.0 op_sel:[1,0] op_sel_hi:[1,0] neg_lo:[1,0]
	v_pk_add_f32 v[82:83], v[94:95], v[98:99]
	v_pk_add_f32 v[94:95], v[94:95], v[98:99] neg_lo:[0,1] neg_hi:[0,1]
	v_pk_add_f32 v[98:99], v[96:97], v[100:101]
	v_pk_add_f32 v[66:67], v[64:65], v[70:71] op_sel:[0,1] op_sel_hi:[1,0] neg_hi:[0,1]
	v_pk_fma_f32 v[88:89], v[16:17], v[88:89], v[92:93] op_sel_hi:[0,1,1]
	v_pk_mul_f32 v[92:93], v[26:27], v[76:77] op_sel:[0,1] op_sel_hi:[1,0]
	v_pk_mul_f32 v[34:35], v[32:33], 1.0 op_sel:[1,0] op_sel_hi:[1,0] neg_lo:[1,0]
	v_pk_mul_f32 v[40:41], v[12:13], v[32:33] op_sel:[0,1] op_sel_hi:[1,0]
	v_pk_add_f32 v[104:105], v[82:83], v[98:99]
	v_pk_add_f32 v[82:83], v[82:83], v[98:99] neg_lo:[0,1] neg_hi:[0,1]
	v_pk_fma_f32 v[76:77], v[24:25], v[76:77], v[92:93] op_sel_hi:[0,1,1]
	v_pk_mul_f32 v[92:93], v[30:31], v[66:67] op_sel:[0,1] op_sel_hi:[1,0]
	v_pk_mul_f32 v[38:39], v[36:37], 1.0 op_sel:[1,0] op_sel_hi:[1,0] neg_lo:[1,0]
	v_pk_fma_f32 v[40:41], v[6:7], v[32:33], v[40:41] op_sel_hi:[0,1,1]
	v_pk_mul_f32 v[44:45], v[20:21], v[32:33] op_sel:[0,1] op_sel_hi:[1,0]
	v_pk_add_f32 v[84:85], v[86:87], v[84:85] op_sel:[0,1] op_sel_hi:[1,0] neg_lo:[0,1]
	v_pk_add_f32 v[86:87], v[102:103], v[74:75]
	v_pk_add_f32 v[74:75], v[102:103], v[74:75] neg_lo:[0,1] neg_hi:[0,1]
	v_pk_fma_f32 v[66:67], v[28:29], v[66:67], v[92:93] op_sel_hi:[0,1,1]
	v_pk_mul_f32 v[92:93], v[34:35], v[82:83] op_sel:[0,1] op_sel_hi:[1,0]
	v_pk_mul_f32 v[42:43], v[40:41], 1.0 op_sel:[1,0] op_sel_hi:[1,0] neg_lo:[1,0]
	v_pk_fma_f32 v[44:45], v[8:9], v[32:33], v[44:45] op_sel_hi:[0,1,1]
	v_pk_add_f32 v[100:101], v[96:97], v[100:101] neg_lo:[0,1] neg_hi:[0,1]
	v_pk_add_f32 v[98:99], v[78:79], v[90:91]
	v_pk_add_f32 v[78:79], v[78:79], v[90:91] neg_lo:[0,1] neg_hi:[0,1]
	v_pk_fma_f32 v[82:83], v[32:33], v[82:83], v[92:93] op_sel_hi:[0,1,1]
	v_pk_mul_f32 v[92:93], v[38:39], v[74:75] op_sel:[0,1] op_sel_hi:[1,0]
	v_pk_mul_f32 v[46:47], v[44:45], 1.0 op_sel:[1,0] op_sel_hi:[1,0] neg_lo:[1,0]
	v_pk_add_f32 v[90:91], v[68:69], v[80:81]
	v_pk_add_f32 v[68:69], v[68:69], v[80:81] neg_lo:[0,1] neg_hi:[0,1]
	v_pk_fma_f32 v[74:75], v[36:37], v[74:75], v[92:93] op_sel_hi:[0,1,1]
	v_pk_mul_f32 v[92:93], v[42:43], v[78:79] op_sel:[0,1] op_sel_hi:[1,0]
	v_pk_mul_f32 v[50:51], v[48:49], 1.0 op_sel:[1,0] op_sel_hi:[1,0] neg_lo:[1,0]
	v_pk_mul_f32 v[56:57], v[12:13], v[48:49] op_sel:[0,1] op_sel_hi:[1,0]
	v_pk_add_f32 v[96:97], v[94:95], v[100:101] op_sel:[0,1] op_sel_hi:[1,0] neg_hi:[0,1]
	v_pk_add_f32 v[94:95], v[94:95], v[100:101] op_sel:[0,1] op_sel_hi:[1,0] neg_lo:[0,1]
	v_pk_fma_f32 v[78:79], v[40:41], v[78:79], v[92:93] op_sel_hi:[0,1,1]
	v_pk_mul_f32 v[92:93], v[46:47], v[68:69] op_sel:[0,1] op_sel_hi:[1,0]
	v_pk_mul_f32 v[54:55], v[52:53], 1.0 op_sel:[1,0] op_sel_hi:[1,0] neg_lo:[1,0]
	v_pk_fma_f32 v[56:57], v[6:7], v[48:49], v[56:57] op_sel_hi:[0,1,1]
	v_pk_mul_f32 v[60:61], v[20:21], v[48:49] op_sel:[0,1] op_sel_hi:[1,0]
	v_pk_fma_f32 v[68:69], v[44:45], v[68:69], v[92:93] op_sel_hi:[0,1,1]
	v_pk_mul_f32 v[92:93], v[50:51], v[94:95] op_sel:[0,1] op_sel_hi:[1,0]
	v_pk_mul_f32 v[58:59], v[56:57], 1.0 op_sel:[1,0] op_sel_hi:[1,0] neg_lo:[1,0]
	v_pk_fma_f32 v[60:61], v[8:9], v[48:49], v[60:61] op_sel_hi:[0,1,1]
	v_pk_add_f32 v[64:65], v[64:65], v[70:71] op_sel:[0,1] op_sel_hi:[1,0] neg_lo:[0,1]
	v_pk_mul_f32 v[70:71], v[2:3], v[86:87] op_sel:[0,1] op_sel_hi:[1,0]
	v_pk_fma_f32 v[92:93], v[48:49], v[94:95], v[92:93] op_sel_hi:[0,1,1]
	v_pk_mul_f32 v[94:95], v[54:55], v[72:73] op_sel:[0,1] op_sel_hi:[1,0]
	v_pk_mul_f32 v[62:63], v[60:61], 1.0 op_sel:[1,0] op_sel_hi:[1,0] neg_lo:[1,0]
	v_pk_fma_f32 v[70:71], v[4:5], v[86:87], v[70:71] op_sel_hi:[0,1,1]
	v_pk_mul_f32 v[86:87], v[20:21], v[90:91] op_sel:[0,1] op_sel_hi:[1,0]
	v_pk_fma_f32 v[72:73], v[52:53], v[72:73], v[94:95] op_sel_hi:[0,1,1]
	v_pk_mul_f32 v[94:95], v[58:59], v[84:85] op_sel:[0,1] op_sel_hi:[1,0]
	v_add_u32_e32 v5, 0x2000, v5
	v_pk_mul_f32 v[80:81], v[12:13], v[98:99] op_sel:[0,1] op_sel_hi:[1,0]
	v_pk_fma_f32 v[86:87], v[8:9], v[90:91], v[86:87] op_sel_hi:[0,1,1]
	v_pk_mul_f32 v[90:91], v[14:15], v[96:97] op_sel:[0,1] op_sel_hi:[1,0]
	v_pk_fma_f32 v[84:85], v[56:57], v[84:85], v[94:95] op_sel_hi:[0,1,1]
	v_pk_mul_f32 v[94:95], v[62:63], v[64:65] op_sel:[0,1] op_sel_hi:[1,0]
	v_ashrrev_i32_e32 v5, 2, v5
	v_pk_fma_f32 v[80:81], v[6:7], v[98:99], v[80:81] op_sel_hi:[0,1,1]
	v_pk_fma_f32 v[90:91], v[10:11], v[96:97], v[90:91] op_sel_hi:[0,1,1]
	v_pk_fma_f32 v[64:65], v[60:61], v[64:65], v[94:95] op_sel_hi:[0,1,1]
	ds_write2_b64 v106, v[104:105], v[82:83] offset1:16
	ds_write2_b64 v106, v[90:91], v[92:93] offset0:33 offset1:49
	ds_write2_b64 v106, v[80:81], v[78:79] offset0:66 offset1:82
	ds_write2_b64 v106, v[76:77], v[84:85] offset0:99 offset1:115
	ds_write2_b64 v106, v[70:71], v[74:75] offset0:132 offset1:148
	ds_write2_b64 v106, v[88:89], v[72:73] offset0:165 offset1:181
	ds_write2_b64 v106, v[86:87], v[68:69] offset0:198 offset1:214
	ds_write2_b64 v106, v[66:67], v[64:65] offset0:231 offset1:247
	v_add3_u32 v18, v18, v5, s5
	ds_read2_b64 v[64:67], v18 offset1:16
	ds_read2_b64 v[68:71], v18 offset0:33 offset1:49
	ds_read2_b64 v[72:75], v18 offset0:66 offset1:82
	ds_read2_b64 v[76:79], v18 offset0:132 offset1:148
	ds_read2_b64 v[80:83], v18 offset0:99 offset1:115
	ds_read2_b64 v[84:87], v18 offset0:165 offset1:181
	ds_read2_b64 v[88:91], v18 offset0:198 offset1:214
	ds_read2_b64 v[92:95], v18 offset0:231 offset1:247
	s_waitcnt lgkmcnt(4)
	v_pk_add_f32 v[96:97], v[64:65], v[76:77]
	v_pk_add_f32 v[64:65], v[64:65], v[76:77] neg_lo:[0,1] neg_hi:[0,1]
	v_pk_add_f32 v[76:77], v[66:67], v[78:79]
	v_pk_add_f32 v[66:67], v[66:67], v[78:79] neg_lo:[0,1] neg_hi:[0,1]
	s_waitcnt lgkmcnt(1)
	v_pk_add_f32 v[98:99], v[74:75], v[90:91]
	v_pk_mul_f32 v[78:79], v[66:67], s[18:19]
	v_pk_add_f32 v[74:75], v[74:75], v[90:91] neg_lo:[0,1] neg_hi:[0,1]
	v_pk_fma_f32 v[66:67], v[66:67], s[16:17], v[78:79] op_sel:[0,0,1] op_sel_hi:[1,0,0]
	v_pk_add_f32 v[78:79], v[68:69], v[84:85]
	v_pk_add_f32 v[68:69], v[68:69], v[84:85] neg_lo:[0,1] neg_hi:[0,1]
	v_pk_mul_f32 v[90:91], v[74:75], s[40:41]
	v_pk_mul_f32 v[84:85], v[68:69], s[36:37]
	v_pk_fma_f32 v[74:75], v[74:75], s[68:69], v[90:91] op_sel:[0,0,1] op_sel_hi:[1,0,0] neg_lo:[1,0,0] neg_hi:[1,0,0]
	s_waitcnt lgkmcnt(0)
	v_pk_add_f32 v[90:91], v[80:81], v[92:93]
	v_pk_add_f32 v[80:81], v[80:81], v[92:93] neg_lo:[0,1] neg_hi:[0,1]
	v_pk_fma_f32 v[68:69], v[68:69], s[66:67], v[84:85] op_sel:[0,0,1] op_sel_hi:[1,0,0]
	v_pk_add_f32 v[84:85], v[70:71], v[86:87]
	v_pk_add_f32 v[70:71], v[70:71], v[86:87] neg_lo:[0,1] neg_hi:[0,1]
	v_pk_mul_f32 v[92:93], v[80:81], s[36:37]
	v_pk_mul_f32 v[86:87], v[70:71], s[40:41]
	v_pk_fma_f32 v[80:81], v[80:81], s[66:67], v[92:93] op_sel:[0,0,1] op_sel_hi:[1,0,0] neg_lo:[1,0,0] neg_hi:[1,0,0]
	v_pk_add_f32 v[92:93], v[82:83], v[94:95]
	v_pk_add_f32 v[82:83], v[82:83], v[94:95] neg_lo:[0,1] neg_hi:[0,1]
	v_pk_fma_f32 v[70:71], v[70:71], s[68:69], v[86:87] op_sel:[0,0,1] op_sel_hi:[1,0,0]
	v_pk_add_f32 v[86:87], v[72:73], v[88:89]
	v_pk_mul_f32 v[94:95], v[82:83], s[18:19]
	v_pk_add_f32 v[88:89], v[72:73], v[88:89] neg_lo:[0,1] neg_hi:[0,1]
	v_pk_fma_f32 v[82:83], v[82:83], s[16:17], v[94:95] op_sel:[0,0,1] op_sel_hi:[1,0,0] neg_lo:[1,0,0] neg_hi:[1,0,0]
	v_pk_add_f32 v[94:95], v[96:97], v[86:87]
	v_pk_add_f32 v[86:87], v[96:97], v[86:87] neg_lo:[0,1] neg_hi:[0,1]
	v_pk_add_f32 v[96:97], v[76:77], v[98:99]
	v_pk_add_f32 v[76:77], v[76:77], v[98:99] neg_lo:[0,1] neg_hi:[0,1]
	s_nop 0
	v_pk_mul_f32 v[98:99], v[76:77], s[36:37]
	v_pk_add_f32 v[100:101], v[84:85], v[92:93]
	v_pk_add_f32 v[84:85], v[84:85], v[92:93] neg_lo:[0,1] neg_hi:[0,1]
	v_pk_fma_f32 v[76:77], v[76:77], s[66:67], v[98:99] op_sel:[0,0,1] op_sel_hi:[1,0,0]
	v_pk_add_f32 v[98:99], v[78:79], v[90:91]
	v_pk_add_f32 v[90:91], v[78:79], v[90:91] neg_lo:[0,1] neg_hi:[0,1]
	v_pk_mul_f32 v[92:93], v[84:85], s[36:37]
	v_pk_add_f32 v[72:73], v[64:65], v[88:89] op_sel:[0,1] op_sel_hi:[1,0] neg_hi:[0,1]
	v_pk_add_f32 v[64:65], v[64:65], v[88:89] op_sel:[0,1] op_sel_hi:[1,0] neg_lo:[0,1]
	v_pk_add_f32 v[88:89], v[66:67], v[74:75]
	v_pk_add_f32 v[66:67], v[66:67], v[74:75] neg_lo:[0,1] neg_hi:[0,1]
	v_pk_fma_f32 v[84:85], v[84:85], s[66:67], v[92:93] op_sel:[0,0,1] op_sel_hi:[1,0,0] neg_lo:[1,0,0] neg_hi:[1,0,0]
	v_pk_mul_f32 v[74:75], v[66:67], s[36:37]
	s_nop 0
	v_pk_fma_f32 v[66:67], v[66:67], s[66:67], v[74:75] op_sel:[0,0,1] op_sel_hi:[1,0,0]
	v_pk_add_f32 v[74:75], v[68:69], v[80:81]
	v_pk_add_f32 v[92:93], v[70:71], v[82:83]
	v_pk_add_f32 v[70:71], v[70:71], v[82:83] neg_lo:[0,1] neg_hi:[0,1]
	v_pk_add_f32 v[78:79], v[86:87], v[90:91] op_sel:[0,1] op_sel_hi:[1,0] neg_hi:[0,1]
	v_pk_add_f32 v[86:87], v[86:87], v[90:91] op_sel:[0,1] op_sel_hi:[1,0] neg_lo:[0,1]
	v_pk_add_f32 v[90:91], v[76:77], v[84:85]
	v_pk_add_f32 v[84:85], v[76:77], v[84:85] neg_lo:[0,1] neg_hi:[0,1]
	v_pk_add_f32 v[80:81], v[68:69], v[80:81] neg_lo:[0,1] neg_hi:[0,1]
	v_pk_mul_f32 v[82:83], v[70:71], s[36:37]
	v_pk_add_f32 v[102:103], v[72:73], v[74:75]
	v_pk_add_f32 v[72:73], v[72:73], v[74:75] neg_lo:[0,1] neg_hi:[0,1]
	v_pk_add_f32 v[74:75], v[88:89], v[92:93]
	v_pk_fma_f32 v[70:71], v[70:71], s[66:67], v[82:83] op_sel:[0,0,1] op_sel_hi:[1,0,0] neg_lo:[1,0,0] neg_hi:[1,0,0]
	v_pk_add_f32 v[82:83], v[94:95], v[98:99]
	v_pk_add_f32 v[94:95], v[94:95], v[98:99] neg_lo:[0,1] neg_hi:[0,1]
	v_pk_add_f32 v[98:99], v[96:97], v[100:101]
	v_pk_add_f32 v[76:77], v[86:87], v[84:85] op_sel:[0,1] op_sel_hi:[1,0] neg_hi:[0,1]
	v_pk_add_f32 v[84:85], v[86:87], v[84:85] op_sel:[0,1] op_sel_hi:[1,0] neg_lo:[0,1]
	v_pk_add_f32 v[86:87], v[102:103], v[74:75]
	v_pk_add_f32 v[100:101], v[96:97], v[100:101] neg_lo:[0,1] neg_hi:[0,1]
	v_pk_add_f32 v[68:69], v[64:65], v[80:81] op_sel:[0,1] op_sel_hi:[1,0] neg_hi:[0,1]
	v_pk_add_f32 v[64:65], v[64:65], v[80:81] op_sel:[0,1] op_sel_hi:[1,0] neg_lo:[0,1]
	v_pk_add_f32 v[80:81], v[66:67], v[70:71]
	v_pk_add_f32 v[104:105], v[82:83], v[98:99]
	v_pk_add_f32 v[82:83], v[82:83], v[98:99] neg_lo:[0,1] neg_hi:[0,1]
	v_pk_add_f32 v[98:99], v[78:79], v[90:91]
	v_pk_mul_f32 v[2:3], v[2:3], v[86:87] op_sel:[0,1] op_sel_hi:[1,0]
	v_pk_add_f32 v[92:93], v[88:89], v[92:93] neg_lo:[0,1] neg_hi:[0,1]
	v_pk_add_f32 v[78:79], v[78:79], v[90:91] neg_lo:[0,1] neg_hi:[0,1]
	v_pk_add_f32 v[90:91], v[68:69], v[80:81]
	v_pk_fma_f32 v[2:3], v[4:5], v[86:87], v[2:3] op_sel_hi:[0,1,1]
	v_pk_mul_f32 v[4:5], v[12:13], v[98:99] op_sel:[0,1] op_sel_hi:[1,0]
	v_pk_add_f32 v[70:71], v[66:67], v[70:71] neg_lo:[0,1] neg_hi:[0,1]
	v_pk_add_f32 v[96:97], v[94:95], v[100:101] op_sel:[0,1] op_sel_hi:[1,0] neg_hi:[0,1]
	v_pk_fma_f32 v[4:5], v[6:7], v[98:99], v[4:5] op_sel_hi:[0,1,1]
	v_pk_mul_f32 v[6:7], v[20:21], v[90:91] op_sel:[0,1] op_sel_hi:[1,0]
	v_pk_add_f32 v[88:89], v[72:73], v[92:93] op_sel:[0,1] op_sel_hi:[1,0] neg_hi:[0,1]
	v_pk_fma_f32 v[6:7], v[8:9], v[90:91], v[6:7] op_sel_hi:[0,1,1]
	v_pk_mul_f32 v[8:9], v[14:15], v[96:97] op_sel:[0,1] op_sel_hi:[1,0]
	v_pk_add_f32 v[66:67], v[64:65], v[70:71] op_sel:[0,1] op_sel_hi:[1,0] neg_hi:[0,1]
	v_pk_fma_f32 v[8:9], v[10:11], v[96:97], v[8:9] op_sel_hi:[0,1,1]
	v_pk_mul_f32 v[10:11], v[22:23], v[88:89] op_sel:[0,1] op_sel_hi:[1,0]
	v_pk_add_f32 v[94:95], v[94:95], v[100:101] op_sel:[0,1] op_sel_hi:[1,0] neg_lo:[0,1]
	v_pk_add_f32 v[74:75], v[102:103], v[74:75] neg_lo:[0,1] neg_hi:[0,1]
	v_pk_add_f32 v[72:73], v[72:73], v[92:93] op_sel:[0,1] op_sel_hi:[1,0] neg_lo:[0,1]
	v_pk_add_f32 v[68:69], v[68:69], v[80:81] neg_lo:[0,1] neg_hi:[0,1]
	v_pk_add_f32 v[64:65], v[64:65], v[70:71] op_sel:[0,1] op_sel_hi:[1,0] neg_lo:[0,1]
	v_pk_fma_f32 v[10:11], v[16:17], v[88:89], v[10:11] op_sel_hi:[0,1,1]
	v_pk_mul_f32 v[12:13], v[26:27], v[76:77] op_sel:[0,1] op_sel_hi:[1,0]
	v_pk_mul_f32 v[14:15], v[30:31], v[66:67] op_sel:[0,1] op_sel_hi:[1,0]
	v_pk_mul_f32 v[16:17], v[34:35], v[82:83] op_sel:[0,1] op_sel_hi:[1,0]
	v_pk_fma_f32 v[12:13], v[24:25], v[76:77], v[12:13] op_sel_hi:[0,1,1]
	v_pk_fma_f32 v[14:15], v[28:29], v[66:67], v[14:15] op_sel_hi:[0,1,1]
	v_pk_fma_f32 v[16:17], v[32:33], v[82:83], v[16:17] op_sel_hi:[0,1,1]
	v_pk_mul_f32 v[20:21], v[38:39], v[74:75] op_sel:[0,1] op_sel_hi:[1,0]
	v_pk_mul_f32 v[22:23], v[42:43], v[78:79] op_sel:[0,1] op_sel_hi:[1,0]
	v_pk_mul_f32 v[24:25], v[46:47], v[68:69] op_sel:[0,1] op_sel_hi:[1,0]
	v_pk_mul_f32 v[26:27], v[50:51], v[94:95] op_sel:[0,1] op_sel_hi:[1,0]
	v_pk_mul_f32 v[28:29], v[54:55], v[72:73] op_sel:[0,1] op_sel_hi:[1,0]
	v_pk_mul_f32 v[30:31], v[58:59], v[84:85] op_sel:[0,1] op_sel_hi:[1,0]
	v_pk_mul_f32 v[32:33], v[62:63], v[64:65] op_sel:[0,1] op_sel_hi:[1,0]
	v_pk_fma_f32 v[20:21], v[36:37], v[74:75], v[20:21] op_sel_hi:[0,1,1]
	v_pk_fma_f32 v[22:23], v[40:41], v[78:79], v[22:23] op_sel_hi:[0,1,1]
	v_pk_fma_f32 v[24:25], v[44:45], v[68:69], v[24:25] op_sel_hi:[0,1,1]
	v_pk_fma_f32 v[26:27], v[48:49], v[94:95], v[26:27] op_sel_hi:[0,1,1]
	v_pk_fma_f32 v[28:29], v[52:53], v[72:73], v[28:29] op_sel_hi:[0,1,1]
	v_pk_fma_f32 v[30:31], v[56:57], v[84:85], v[30:31] op_sel_hi:[0,1,1]
	v_pk_fma_f32 v[32:33], v[60:61], v[64:65], v[32:33] op_sel_hi:[0,1,1]
	ds_write2_b64 v18, v[104:105], v[16:17] offset1:16
	ds_write2_b64 v18, v[8:9], v[26:27] offset0:33 offset1:49
	ds_write2_b64 v18, v[4:5], v[22:23] offset0:66 offset1:82
	ds_write2_b64 v18, v[12:13], v[30:31] offset0:99 offset1:115
	ds_write2_b64 v18, v[2:3], v[20:21] offset0:132 offset1:148
	ds_write2_b64 v18, v[10:11], v[28:29] offset0:165 offset1:181
	ds_write2_b64 v18, v[6:7], v[24:25] offset0:198 offset1:214
	ds_write2_b64 v18, v[14:15], v[32:33] offset0:231 offset1:247
	v_ashrrev_i32_e32 v2, 31, v210
	v_add_u32_sdwa v2, v210, v2 dst_sel:DWORD dst_unused:UNUSED_PAD src0_sel:DWORD src1_sel:BYTE_3
	s_lshl_b64 s[0:1], s[64:65], 15
	v_and_b32_e32 v2, 0xffffff00, v2
	s_add_u32 s0, s29, s0
	v_sub_u32_e32 v2, v210, v2
	s_addc_u32 s1, s85, s1
	v_ashrrev_i32_e32 v3, 31, v2
	v_lshl_add_u64 v[14:15], v[2:3], 3, s[0:1]
	s_movk_i32 s0, 0x1000
	v_add_co_u32_e32 v16, vcc, s0, v14
	s_movk_i32 s0, 0x3000
	s_nop 0
	v_addc_co_u32_e32 v17, vcc, 0, v15, vcc
	v_add_co_u32_e32 v2, vcc, s92, v14
	s_waitcnt lgkmcnt(0)
	s_nop 0
	v_addc_co_u32_e32 v3, vcc, 0, v15, vcc
	v_add_co_u32_e32 v22, vcc, s0, v14
	s_movk_i32 s0, 0x5000
	s_nop 0
	v_addc_co_u32_e32 v23, vcc, 0, v15, vcc
	v_add_co_u32_e32 v8, vcc, s95, v14
	s_barrier
	s_nop 0
	v_addc_co_u32_e32 v9, vcc, 0, v15, vcc
	v_add_co_u32_e32 v26, vcc, s0, v14
	s_nop 1
	v_addc_co_u32_e32 v27, vcc, 0, v15, vcc
	v_add_co_u32_e32 v10, vcc, s96, v14
	global_load_dwordx2 v[12:13], v[2:3], off nt
	global_load_dwordx2 v[6:7], v[2:3], off offset:2048 nt
	global_load_dwordx2 v[4:5], v[8:9], off offset:-4096 nt
	global_load_dwordx2 v[122:123], v[8:9], off nt
	v_addc_co_u32_e32 v11, vcc, 0, v15, vcc
	v_add_co_u32_e32 v28, vcc, s97, v14
	global_load_dwordx2 v[46:47], v[8:9], off offset:2048 nt
	global_load_dwordx2 v[38:39], v[10:11], off offset:-4096 nt
	global_load_dwordx2 v[20:21], v[10:11], off nt
	s_nop 0
	global_load_dwordx2 v[10:11], v[10:11], off offset:2048 nt
	v_addc_co_u32_e32 v29, vcc, 0, v15, vcc
	global_load_dwordx2 v[24:25], v[2:3], off offset:-4096 nt
	s_nop 0
	global_load_dwordx2 v[26:27], v[26:27], off offset:2048 nt
	s_nop 0
	global_load_dwordx2 v[8:9], v[28:29], off nt
	global_load_dwordx2 v[2:3], v[28:29], off offset:2048 nt
	global_load_dwordx2 v[30:31], v[14:15], off offset:2048 nt
	s_nop 0
	global_load_dwordx2 v[28:29], v[16:17], off offset:2048 nt
	s_nop 0
	global_load_dwordx2 v[16:17], v[22:23], off offset:2048 nt
	global_load_dwordx2 v[32:33], v[14:15], off nt
	v_mov_b32_e32 v14, v210
	s_waitcnt vmcnt(15)
	v_cvt_f32_f16_sdwa v164, v12 dst_sel:DWORD dst_unused:UNUSED_PAD src0_sel:WORD_1
	v_ashrrev_i32_e32 v15, 31, v14
	v_add_u32_sdwa v15, v14, v15 dst_sel:DWORD dst_unused:UNUSED_PAD src0_sel:DWORD src1_sel:BYTE_3
	v_ashrrev_i32_e32 v15, 8, v15
	v_mul_i32_i24_e32 v18, 0x100, v15
	v_sub_u32_e32 v18, v14, v18
	v_lshlrev_b32_e32 v14, 13, v15
	v_lshlrev_b32_e32 v15, 1, v18
	v_bfrev_b32_e32 v15, v15
	v_lshrrev_b32_e32 v15, 23, v15
	v_sub_u32_e32 v15, 0x200, v15
	v_bfrev_b32_e32 v15, v15
	v_lshrrev_b32_e32 v15, 19, v15
	v_and_b32_e32 v15, 0x1ff0, v15
	v_cmp_eq_u32_e64 s[0:1], 0, v18
	v_lshl_add_u32 v22, v18, 5, v14
	v_lshl_add_u32 v23, v22, 3, 0
	v_cndmask_b32_e64 v15, v15, 16, s[0:1]
	v_or_b32_e32 v14, v15, v14
	v_ashrrev_i32_e32 v22, 2, v22
	v_ashrrev_i32_e32 v15, 5, v14
	v_add_u32_e32 v211, v23, v22
	v_lshlrev_b32_e32 v14, 3, v14
	v_lshlrev_b32_e32 v15, 3, v15
	v_add3_u32 v212, 0, v14, v15
	ds_read2_b64 v[34:37], v211 offset1:1
	ds_read2_b64 v[40:43], v211 offset0:2 offset1:3
	ds_read2_b64 v[48:51], v212 offset1:1
	ds_read2_b64 v[52:55], v212 offset0:2 offset1:3
	ds_read2_b64 v[56:59], v211 offset0:4 offset1:5
	ds_read2_b64 v[60:63], v211 offset0:6 offset1:7
	ds_read2_b64 v[68:71], v212 offset0:4 offset1:5
	ds_read2_b64 v[72:75], v212 offset0:6 offset1:7
	ds_read2_b64 v[64:67], v211 offset0:8 offset1:9
	ds_read2_b64 v[76:79], v211 offset0:10 offset1:11
	ds_read2_b64 v[80:83], v212 offset0:8 offset1:9
	ds_read2_b64 v[98:101], v212 offset0:10 offset1:11
	ds_read2_b64 v[84:87], v211 offset0:12 offset1:13
	ds_read2_b64 v[88:91], v211 offset0:14 offset1:15
	ds_read2_b64 v[102:105], v212 offset0:12 offset1:13
	ds_read2_b64 v[106:109], v212 offset0:14 offset1:15
	s_waitcnt lgkmcnt(7)
	v_pk_add_f32 v[14:15], v[34:35], v[64:65]
	v_pk_add_f32 v[22:23], v[34:35], v[64:65] neg_lo:[0,1] neg_hi:[0,1]
	v_pk_add_f32 v[34:35], v[36:37], v[66:67]
	v_pk_add_f32 v[36:37], v[36:37], v[66:67] neg_lo:[0,1] neg_hi:[0,1]
	v_cmp_ne_u32_e32 vcc, 0, v18
	v_pk_mul_f32 v[44:45], v[36:37], s[18:19]
	v_bfrev_b32_e32 v18, v18
	v_pk_fma_f32 v[36:37], v[36:37], s[16:17], v[44:45] op_sel:[0,0,1] op_sel_hi:[1,0,0]
	s_waitcnt lgkmcnt(6)
	v_pk_add_f32 v[44:45], v[40:41], v[76:77]
	v_pk_add_f32 v[40:41], v[40:41], v[76:77] neg_lo:[0,1] neg_hi:[0,1]
	v_cvt_f32_ubyte3_e32 v18, v18
	v_pk_mul_f32 v[64:65], v[40:41], s[36:37]
	v_mul_f32_e32 v18, 0x38800000, v18
	v_pk_fma_f32 v[40:41], v[40:41], s[66:67], v[64:65] op_sel:[0,0,1] op_sel_hi:[1,0,0]
	v_pk_add_f32 v[64:65], v[42:43], v[78:79]
	v_pk_add_f32 v[42:43], v[42:43], v[78:79] neg_lo:[0,1] neg_hi:[0,1]
	s_waitcnt lgkmcnt(3)
	v_pk_add_f32 v[78:79], v[58:59], v[86:87]
	v_pk_mul_f32 v[66:67], v[42:43], s[40:41]
	v_pk_add_f32 v[58:59], v[58:59], v[86:87] neg_lo:[0,1] neg_hi:[0,1]
	v_pk_fma_f32 v[42:43], v[42:43], s[68:69], v[66:67] op_sel:[0,0,1] op_sel_hi:[1,0,0]
	v_pk_add_f32 v[66:67], v[56:57], v[84:85]
	v_pk_add_f32 v[76:77], v[56:57], v[84:85] neg_lo:[0,1] neg_hi:[0,1]
	v_pk_mul_f32 v[84:85], v[58:59], s[40:41]
	s_nop 0
	v_pk_fma_f32 v[58:59], v[58:59], s[68:69], v[84:85] op_sel:[0,0,1] op_sel_hi:[1,0,0] neg_lo:[1,0,0] neg_hi:[1,0,0]
	s_waitcnt lgkmcnt(2)
	v_pk_add_f32 v[84:85], v[60:61], v[88:89]
	v_pk_add_f32 v[60:61], v[60:61], v[88:89] neg_lo:[0,1] neg_hi:[0,1]
	s_nop 0
	v_pk_mul_f32 v[86:87], v[60:61], s[36:37]
	v_pk_add_f32 v[56:57], v[22:23], v[76:77] op_sel:[0,1] op_sel_hi:[1,0] neg_hi:[0,1]
	v_pk_fma_f32 v[60:61], v[60:61], s[66:67], v[86:87] op_sel:[0,0,1] op_sel_hi:[1,0,0] neg_lo:[1,0,0] neg_hi:[1,0,0]
	v_pk_add_f32 v[86:87], v[62:63], v[90:91]
	v_pk_add_f32 v[62:63], v[62:63], v[90:91] neg_lo:[0,1] neg_hi:[0,1]
	v_pk_add_f32 v[90:91], v[64:65], v[86:87]
	v_pk_mul_f32 v[88:89], v[62:63], s[18:19]
	v_pk_add_f32 v[64:65], v[64:65], v[86:87] neg_lo:[0,1] neg_hi:[0,1]
	v_pk_fma_f32 v[62:63], v[62:63], s[16:17], v[88:89] op_sel:[0,0,1] op_sel_hi:[1,0,0] neg_lo:[1,0,0] neg_hi:[1,0,0]
	v_pk_add_f32 v[88:89], v[14:15], v[66:67]
	v_pk_add_f32 v[14:15], v[14:15], v[66:67] neg_lo:[0,1] neg_hi:[0,1]
	v_pk_add_f32 v[66:67], v[34:35], v[78:79]
	v_pk_add_f32 v[34:35], v[34:35], v[78:79] neg_lo:[0,1] neg_hi:[0,1]
	v_pk_add_f32 v[22:23], v[22:23], v[76:77] op_sel:[0,1] op_sel_hi:[1,0] neg_lo:[0,1]
	v_pk_mul_f32 v[78:79], v[34:35], s[36:37]
	v_pk_add_f32 v[76:77], v[36:37], v[58:59]
	v_pk_add_f32 v[36:37], v[36:37], v[58:59] neg_lo:[0,1] neg_hi:[0,1]
	v_pk_fma_f32 v[34:35], v[34:35], s[66:67], v[78:79] op_sel:[0,0,1] op_sel_hi:[1,0,0]
	v_pk_add_f32 v[78:79], v[44:45], v[84:85]
	v_pk_add_f32 v[84:85], v[44:45], v[84:85] neg_lo:[0,1] neg_hi:[0,1]
	v_pk_mul_f32 v[86:87], v[64:65], s[36:37]
	v_pk_mul_f32 v[58:59], v[36:37], s[36:37]
	v_pk_fma_f32 v[64:65], v[64:65], s[66:67], v[86:87] op_sel:[0,0,1] op_sel_hi:[1,0,0] neg_lo:[1,0,0] neg_hi:[1,0,0]
	v_pk_fma_f32 v[36:37], v[36:37], s[66:67], v[58:59] op_sel:[0,0,1] op_sel_hi:[1,0,0]
	v_pk_add_f32 v[58:59], v[40:41], v[60:61]
	v_pk_add_f32 v[86:87], v[42:43], v[62:63]
	v_pk_add_f32 v[42:43], v[42:43], v[62:63] neg_lo:[0,1] neg_hi:[0,1]
	s_nop 0
	v_pk_mul_f32 v[62:63], v[42:43], s[36:37]
	v_pk_add_f32 v[44:45], v[14:15], v[84:85] op_sel:[0,1] op_sel_hi:[1,0] neg_hi:[0,1]
	v_pk_add_f32 v[14:15], v[14:15], v[84:85] op_sel:[0,1] op_sel_hi:[1,0] neg_lo:[0,1]
	v_pk_add_f32 v[84:85], v[34:35], v[64:65]
	v_pk_add_f32 v[64:65], v[34:35], v[64:65] neg_lo:[0,1] neg_hi:[0,1]
	v_pk_add_f32 v[94:95], v[56:57], v[58:59]
	v_pk_add_f32 v[56:57], v[56:57], v[58:59] neg_lo:[0,1] neg_hi:[0,1]
	v_pk_add_f32 v[58:59], v[76:77], v[86:87]
	v_pk_fma_f32 v[42:43], v[42:43], s[66:67], v[62:63] op_sel:[0,0,1] op_sel_hi:[1,0,0] neg_lo:[1,0,0] neg_hi:[1,0,0]
	v_pk_add_f32 v[62:63], v[88:89], v[78:79]
	v_pk_add_f32 v[78:79], v[88:89], v[78:79] neg_lo:[0,1] neg_hi:[0,1]
	v_pk_add_f32 v[88:89], v[66:67], v[90:91]
	v_pk_add_f32 v[110:111], v[76:77], v[86:87] neg_lo:[0,1] neg_hi:[0,1]
	v_pk_add_f32 v[86:87], v[94:95], v[58:59]
	v_pk_add_f32 v[34:35], v[94:95], v[58:59] neg_lo:[0,1] neg_hi:[0,1]
	v_pk_add_f32 v[58:59], v[50:51], v[82:83]
	v_pk_add_f32 v[50:51], v[50:51], v[82:83] neg_lo:[0,1] neg_hi:[0,1]
	v_pk_add_f32 v[60:61], v[40:41], v[60:61] neg_lo:[0,1] neg_hi:[0,1]
	v_pk_add_f32 v[148:149], v[62:63], v[88:89]
	v_pk_add_f32 v[138:139], v[62:63], v[88:89] neg_lo:[0,1] neg_hi:[0,1]
	v_pk_mul_f32 v[62:63], v[50:51], s[18:19]
	v_pk_add_f32 v[90:91], v[66:67], v[90:91] neg_lo:[0,1] neg_hi:[0,1]
	v_pk_fma_f32 v[50:51], v[50:51], s[16:17], v[62:63] op_sel:[0,0,1] op_sel_hi:[1,0,0]
	v_pk_add_f32 v[62:63], v[52:53], v[98:99]
	v_pk_add_f32 v[52:53], v[52:53], v[98:99] neg_lo:[0,1] neg_hi:[0,1]
	v_pk_add_f32 v[112:113], v[22:23], v[60:61] op_sel:[0,1] op_sel_hi:[1,0] neg_hi:[0,1]
	v_pk_add_f32 v[114:115], v[22:23], v[60:61] op_sel:[0,1] op_sel_hi:[1,0] neg_lo:[0,1]
	v_pk_add_f32 v[96:97], v[44:45], v[84:85]
	v_pk_add_f32 v[66:67], v[44:45], v[84:85] neg_lo:[0,1] neg_hi:[0,1]
	v_pk_add_f32 v[60:61], v[14:15], v[64:65] op_sel:[0,1] op_sel_hi:[1,0] neg_hi:[0,1]
	v_pk_add_f32 v[84:85], v[14:15], v[64:65] op_sel:[0,1] op_sel_hi:[1,0] neg_lo:[0,1]
	v_pk_mul_f32 v[64:65], v[52:53], s[36:37]
	s_nop 0
	v_pk_fma_f32 v[52:53], v[52:53], s[66:67], v[64:65] op_sel:[0,0,1] op_sel_hi:[1,0,0]
	v_pk_add_f32 v[64:65], v[54:55], v[100:101]
	v_pk_add_f32 v[54:55], v[54:55], v[100:101] neg_lo:[0,1] neg_hi:[0,1]
	s_nop 0
	v_pk_mul_f32 v[76:77], v[54:55], s[40:41]
	v_pk_add_f32 v[92:93], v[78:79], v[90:91] op_sel:[0,1] op_sel_hi:[1,0] neg_hi:[0,1]
	v_pk_fma_f32 v[54:55], v[54:55], s[68:69], v[76:77] op_sel:[0,0,1] op_sel_hi:[1,0,0]
	s_waitcnt lgkmcnt(1)
	v_pk_add_f32 v[76:77], v[68:69], v[102:103]
	v_pk_add_f32 v[88:89], v[78:79], v[90:91] op_sel:[0,1] op_sel_hi:[1,0] neg_lo:[0,1]
	v_pk_add_f32 v[78:79], v[68:69], v[102:103] neg_lo:[0,1] neg_hi:[0,1]
	v_pk_add_f32 v[68:69], v[70:71], v[104:105]
	v_pk_add_f32 v[70:71], v[70:71], v[104:105] neg_lo:[0,1] neg_hi:[0,1]
	v_pk_add_f32 v[40:41], v[56:57], v[110:111] op_sel:[0,1] op_sel_hi:[1,0] neg_hi:[0,1]
	v_pk_add_f32 v[44:45], v[56:57], v[110:111] op_sel:[0,1] op_sel_hi:[1,0] neg_lo:[0,1]
	v_pk_add_f32 v[56:57], v[48:49], v[80:81]
	v_pk_add_f32 v[48:49], v[48:49], v[80:81] neg_lo:[0,1] neg_hi:[0,1]
	v_pk_mul_f32 v[80:81], v[70:71], s[40:41]
	v_cndmask_b32_e64 v18, v18, v208, s[0:1]
	v_pk_fma_f32 v[70:71], v[70:71], s[68:69], v[80:81] op_sel:[0,0,1] op_sel_hi:[1,0,0] neg_lo:[1,0,0] neg_hi:[1,0,0]
	s_waitcnt lgkmcnt(0)
	v_pk_add_f32 v[80:81], v[72:73], v[106:107]
	v_pk_add_f32 v[72:73], v[72:73], v[106:107] neg_lo:[0,1] neg_hi:[0,1]
	v_pk_add_f32 v[22:23], v[36:37], v[42:43]
	v_pk_mul_f32 v[82:83], v[72:73], s[36:37]
	v_pk_add_f32 v[116:117], v[36:37], v[42:43] neg_lo:[0,1] neg_hi:[0,1]
	v_pk_fma_f32 v[72:73], v[72:73], s[66:67], v[82:83] op_sel:[0,0,1] op_sel_hi:[1,0,0] neg_lo:[1,0,0] neg_hi:[1,0,0]
	v_pk_add_f32 v[82:83], v[74:75], v[108:109]
	v_pk_add_f32 v[74:75], v[74:75], v[108:109] neg_lo:[0,1] neg_hi:[0,1]
	s_nop 0
	v_pk_mul_f32 v[90:91], v[74:75], s[18:19]
	s_nop 0
	v_pk_fma_f32 v[74:75], v[74:75], s[16:17], v[90:91] op_sel:[0,0,1] op_sel_hi:[1,0,0] neg_lo:[1,0,0] neg_hi:[1,0,0]
	v_pk_add_f32 v[90:91], v[56:57], v[76:77]
	v_pk_add_f32 v[56:57], v[56:57], v[76:77] neg_lo:[0,1] neg_hi:[0,1]
	v_pk_add_f32 v[76:77], v[58:59], v[68:69]
	v_pk_add_f32 v[58:59], v[58:59], v[68:69] neg_lo:[0,1] neg_hi:[0,1]
	v_pk_add_f32 v[14:15], v[114:115], v[116:117] op_sel:[0,1] op_sel_hi:[1,0] neg_hi:[0,1]
	v_pk_mul_f32 v[68:69], v[58:59], s[36:37]
	v_pk_add_f32 v[36:37], v[114:115], v[116:117] op_sel:[0,1] op_sel_hi:[1,0] neg_lo:[0,1]
	v_pk_fma_f32 v[58:59], v[58:59], s[66:67], v[68:69] op_sel:[0,0,1] op_sel_hi:[1,0,0]
	v_pk_add_f32 v[68:69], v[62:63], v[80:81]
	v_pk_add_f32 v[80:81], v[62:63], v[80:81] neg_lo:[0,1] neg_hi:[0,1]
	s_waitcnt vmcnt(0)
	v_cvt_f32_f16_e32 v193, v33
	s_nop 0
	s_nop 0
	v_pk_add_f32 v[62:63], v[64:65], v[82:83]
	v_pk_add_f32 v[64:65], v[64:65], v[82:83] neg_lo:[0,1] neg_hi:[0,1]
	v_cvt_f32_f16_sdwa v192, v32 dst_sel:DWORD dst_unused:UNUSED_PAD src0_sel:WORD_1
	v_pk_mul_f32 v[82:83], v[64:65], s[36:37]
	v_cvt_f32_f16_e32 v194, v32
	v_pk_fma_f32 v[64:65], v[64:65], s[66:67], v[82:83] op_sel:[0,0,1] op_sel_hi:[1,0,0] neg_lo:[1,0,0] neg_hi:[1,0,0]
	v_pk_add_f32 v[82:83], v[48:49], v[78:79] op_sel:[0,1] op_sel_hi:[1,0] neg_hi:[0,1]
	v_pk_add_f32 v[48:49], v[48:49], v[78:79] op_sel:[0,1] op_sel_hi:[1,0] neg_lo:[0,1]
	v_pk_add_f32 v[78:79], v[50:51], v[70:71]
	v_pk_add_f32 v[50:51], v[50:51], v[70:71] neg_lo:[0,1] neg_hi:[0,1]
	v_cvt_f32_f16_sdwa v195, v33 dst_sel:DWORD dst_unused:UNUSED_PAD src0_sel:WORD_1
	v_pk_mul_f32 v[70:71], v[50:51], s[36:37]
	v_cvt_f32_f16_sdwa v170, v30 dst_sel:DWORD dst_unused:UNUSED_PAD src0_sel:WORD_1
	v_pk_fma_f32 v[50:51], v[50:51], s[66:67], v[70:71] op_sel:[0,0,1] op_sel_hi:[1,0,0]
	v_pk_add_f32 v[70:71], v[52:53], v[72:73]
	v_pk_add_f32 v[72:73], v[52:53], v[72:73] neg_lo:[0,1] neg_hi:[0,1]
	v_cvt_f32_f16_e32 v171, v31
	s_nop 0
	s_nop 0
	v_pk_add_f32 v[52:53], v[54:55], v[74:75]
	v_pk_add_f32 v[54:55], v[54:55], v[74:75] neg_lo:[0,1] neg_hi:[0,1]
	v_cvt_f32_f16_sdwa v185, v31 dst_sel:DWORD dst_unused:UNUSED_PAD src0_sel:WORD_1
	v_pk_mul_f32 v[74:75], v[54:55], s[36:37]
	v_cvt_f32_f16_e32 v184, v30
	v_pk_fma_f32 v[54:55], v[54:55], s[66:67], v[74:75] op_sel:[0,0,1] op_sel_hi:[1,0,0] neg_lo:[1,0,0] neg_hi:[1,0,0]
	v_pk_add_f32 v[74:75], v[90:91], v[68:69]
	v_pk_add_f32 v[68:69], v[90:91], v[68:69] neg_lo:[0,1] neg_hi:[0,1]
	v_pk_add_f32 v[90:91], v[76:77], v[62:63]
	v_pk_add_f32 v[62:63], v[76:77], v[62:63] neg_lo:[0,1] neg_hi:[0,1]
	v_cvt_f32_f16_sdwa v172, v24 dst_sel:DWORD dst_unused:UNUSED_PAD src0_sel:WORD_1
	v_pk_mul_f32 v[76:77], v[62:63], 1.0 op_sel:[1,0] op_sel_hi:[0,0] neg_hi:[1,0]
	s_nop 0
	v_pk_add_f32 v[62:63], v[56:57], v[80:81] op_sel:[0,1] op_sel_hi:[1,0] neg_hi:[0,1]
	v_pk_add_f32 v[56:57], v[56:57], v[80:81] op_sel:[0,1] op_sel_hi:[1,0] neg_lo:[0,1]
	v_pk_add_f32 v[80:81], v[58:59], v[64:65]
	v_pk_add_f32 v[58:59], v[58:59], v[64:65] neg_lo:[0,1] neg_hi:[0,1]
	v_cvt_f32_f16_e32 v173, v25
	v_pk_mul_f32 v[64:65], v[58:59], 1.0 op_sel:[1,0] op_sel_hi:[0,0] neg_hi:[1,0]
	v_pk_add_f32 v[58:59], v[82:83], v[70:71]
	v_pk_add_f32 v[70:71], v[82:83], v[70:71] neg_lo:[0,1] neg_hi:[0,1]
	v_pk_add_f32 v[82:83], v[78:79], v[52:53]
	v_pk_add_f32 v[52:53], v[78:79], v[52:53] neg_lo:[0,1] neg_hi:[0,1]
	v_pk_add_f32 v[118:119], v[58:59], v[82:83]
	v_pk_add_f32 v[134:135], v[58:59], v[82:83] neg_lo:[0,1] neg_hi:[0,1]
	v_cos_f32_e32 v83, v18
	v_sin_f32_e32 v82, v18
	v_cvt_f32_f16_sdwa v181, v25 dst_sel:DWORD dst_unused:UNUSED_PAD src0_sel:WORD_1
	v_cvt_f32_f16_e32 v180, v24
	v_cvt_f32_f16_sdwa v174, v28 dst_sel:DWORD dst_unused:UNUSED_PAD src0_sel:WORD_1
	v_cvt_f32_f16_e32 v175, v29
	v_cvt_f32_f16_sdwa v179, v29 dst_sel:DWORD dst_unused:UNUSED_PAD src0_sel:WORD_1
	v_cvt_f32_f16_e32 v178, v28
	v_cvt_f32_f16_e32 v165, v13
	v_cvt_f32_f16_sdwa v167, v13 dst_sel:DWORD dst_unused:UNUSED_PAD src0_sel:WORD_1
	v_cvt_f32_f16_e32 v166, v12
	v_cvt_f32_f16_e32 v154, v6
	v_cvt_f32_f16_e32 v155, v7
	v_cvt_f32_f16_sdwa v157, v7 dst_sel:DWORD dst_unused:UNUSED_PAD src0_sel:WORD_1
	v_cvt_f32_f16_sdwa v156, v6 dst_sel:DWORD dst_unused:UNUSED_PAD src0_sel:WORD_1
	v_cvt_f32_f16_sdwa v140, v4 dst_sel:DWORD dst_unused:UNUSED_PAD src0_sel:WORD_1
	v_cvt_f32_f16_e32 v141, v5
	v_cvt_f32_f16_sdwa v143, v5 dst_sel:DWORD dst_unused:UNUSED_PAD src0_sel:WORD_1
	v_cvt_f32_f16_e32 v142, v4
	v_cvt_f32_f16_e32 v124, v16
	v_cvt_f32_f16_e32 v125, v17
	v_cvt_f32_f16_sdwa v127, v17 dst_sel:DWORD dst_unused:UNUSED_PAD src0_sel:WORD_1
	v_cvt_f32_f16_sdwa v126, v16 dst_sel:DWORD dst_unused:UNUSED_PAD src0_sel:WORD_1
	v_cvt_f32_f16_sdwa v114, v122 dst_sel:DWORD dst_unused:UNUSED_PAD src0_sel:WORD_1
	v_cvt_f32_f16_e32 v115, v123
	v_cvt_f32_f16_sdwa v117, v123 dst_sel:DWORD dst_unused:UNUSED_PAD src0_sel:WORD_1
	v_cvt_f32_f16_e32 v116, v122
	v_pk_mul_f32 v[78:79], v[52:53], 1.0 op_sel:[1,0] op_sel_hi:[0,0] neg_hi:[1,0]
	s_nop 0
	v_pk_add_f32 v[52:53], v[48:49], v[72:73] op_sel:[0,1] op_sel_hi:[1,0] neg_hi:[0,1]
	v_pk_add_f32 v[48:49], v[48:49], v[72:73] op_sel:[0,1] op_sel_hi:[1,0] neg_lo:[0,1]
	v_pk_add_f32 v[72:73], v[50:51], v[54:55]
	v_pk_add_f32 v[50:51], v[50:51], v[54:55] neg_lo:[0,1] neg_hi:[0,1]
	v_pk_fma_f32 v[160:161], v[82:83], 0, v[82:83] op_sel:[0,0,1] op_sel_hi:[1,0,0] neg_lo:[1,0,0] neg_hi:[1,0,0]
	v_pk_mul_f32 v[54:55], v[50:51], 1.0 op_sel:[1,0] op_sel_hi:[0,0] neg_hi:[1,0]
	v_pk_fma_f32 v[198:199], v[82:83], 0, v[82:83] op_sel:[0,0,1] op_sel_hi:[1,0,0]
	v_pk_add_f32 v[42:43], v[112:113], v[22:23]
	v_pk_add_f32 v[22:23], v[112:113], v[22:23] neg_lo:[0,1] neg_hi:[0,1]
	v_pk_add_f32 v[98:99], v[74:75], v[90:91]
	v_pk_add_f32 v[100:101], v[74:75], v[90:91] neg_lo:[0,1] neg_hi:[0,1]
	v_pk_add_f32 v[102:103], v[68:69], v[76:77]
	v_pk_add_f32 v[106:107], v[68:69], v[76:77] neg_lo:[0,1] neg_hi:[0,1]
	v_pk_add_f32 v[104:105], v[62:63], v[80:81]
	v_pk_add_f32 v[108:109], v[62:63], v[80:81] neg_lo:[0,1] neg_hi:[0,1]
	v_pk_add_f32 v[110:111], v[56:57], v[64:65]
	v_pk_add_f32 v[112:113], v[56:57], v[64:65] neg_lo:[0,1] neg_hi:[0,1]
	v_pk_add_f32 v[152:153], v[70:71], v[78:79]
	v_pk_add_f32 v[162:163], v[70:71], v[78:79] neg_lo:[0,1] neg_hi:[0,1]
	v_pk_add_f32 v[176:177], v[52:53], v[72:73]
	v_pk_add_f32 v[182:183], v[52:53], v[72:73] neg_lo:[0,1] neg_hi:[0,1]
	v_pk_add_f32 v[188:189], v[48:49], v[54:55]
	v_pk_add_f32 v[196:197], v[48:49], v[54:55] neg_lo:[0,1] neg_hi:[0,1]
	v_pk_mul_f32 v[186:187], v[82:83], 0 op_sel_hi:[1,0]
	v_mov_b32_e32 v190, v160
	v_mov_b32_e32 v191, v199
	v_mul_f32_e32 v18, 0x3f3504f3, v83
	v_mul_f32_e32 v158, 0xbec3ef15, v83
	v_mul_f32_e32 v132, 0xbf6c835e, v83
	s_and_saveexec_b64 s[0:1], vcc
	s_xor_b64 s[0:1], exec, s[0:1]
	s_cbranch_execz .LBB0_536
	v_pk_add_f32 v[4:5], v[148:149], v[196:197]
	v_pk_add_f32 v[6:7], v[148:149], v[196:197] neg_lo:[0,1] neg_hi:[0,1]
	v_mul_f32_e32 v4, 0.5, v4
	v_mul_f32_e32 v12, 0.5, v7
	v_mov_b32_e32 v7, v5
	v_pk_mul_f32 v[6:7], v[6:7], s[44:45]
	v_pk_mov_b32 v[16:17], v[198:199], v[160:161] op_sel:[1,0]
	v_pk_mul_f32 v[24:25], v[190:191], v[6:7] op_sel:[0,1] op_sel_hi:[1,0]
	v_pk_mul_f32 v[6:7], v[190:191], v[6:7]
	v_pk_add_f32 v[24:25], v[24:25], v[24:25] op_sel:[0,1] op_sel_hi:[0,1]
	v_pk_add_f32 v[28:29], v[4:5], v[24:25] op_sel_hi:[0,1] neg_hi:[0,1]
	v_pk_add_f32 v[4:5], v[6:7], v[6:7] op_sel:[0,1] op_sel_hi:[0,1] neg_lo:[0,1] neg_hi:[0,1]
	v_pk_add_f32 v[6:7], v[12:13], v[4:5] op_sel_hi:[0,1] neg_hi:[0,1]
	v_pk_mul_f32 v[4:5], v[6:7], v[194:195]
	v_pk_mul_f32 v[6:7], v[6:7], v[192:193]
	v_pk_fma_f32 v[4:5], v[28:29], v[192:193], v[4:5]
	v_pk_fma_f32 v[6:7], v[28:29], v[194:195], v[6:7] neg_lo:[0,0,1] neg_hi:[0,0,1]
	s_mov_b32 s66, s19
	v_pk_add_f32 v[12:13], v[6:7], v[4:5] op_sel:[0,1] op_sel_hi:[1,0] neg_lo:[0,1]
	v_pk_add_f32 v[28:29], v[6:7], v[4:5] op_sel:[0,1] op_sel_hi:[1,0]
	v_pk_add_f32 v[4:5], v[4:5], v[6:7] op_sel:[1,0] op_sel_hi:[0,1] neg_lo:[0,1] neg_hi:[0,1]
	s_nop 0
	v_pk_mul_f32 v[12:13], v[12:13], 0.5 op_sel_hi:[1,0]
	v_mov_b32_e32 v29, v5
	v_mul_f32_e32 v24, v190, v12
	v_pk_fma_f32 v[30:31], v[190:191], v[12:13], v[24:25] op_sel_hi:[1,1,0] neg_lo:[1,0,0] neg_hi:[1,0,0]
	v_mul_f32_e32 v24, v160, v13
	v_pk_fma_f32 v[12:13], v[16:17], v[12:13], v[24:25] op_sel_hi:[1,1,0]
	v_mov_b32_e32 v16, v83
	v_mov_b32_e32 v30, v12
	v_pk_fma_f32 v[4:5], v[28:29], 0.5, v[12:13] op_sel_hi:[1,0,1] neg_lo:[0,0,1] neg_hi:[0,0,1]
	v_pk_fma_f32 v[122:123], v[28:29], 0.5, v[30:31] op_sel_hi:[1,0,1]
	v_pk_fma_f32 v[6:7], v[28:29], 0.5, v[30:31] op_sel_hi:[1,0,1] neg_lo:[1,0,0] neg_hi:[1,0,0]
	v_mov_b32_e32 v5, v123
	v_pk_mul_f32 v[24:25], v[4:5], s[46:47] op_sel_hi:[1,0]
	v_pk_add_f32 v[4:5], v[138:139], v[188:189]
	v_pk_add_f32 v[12:13], v[138:139], v[188:189] neg_lo:[0,1] neg_hi:[0,1]
	v_mov_b32_e32 v17, v82
	v_mul_f32_e32 v6, 0.5, v13
	v_pk_add_f32 v[28:29], v[186:187], v[16:17] neg_lo:[0,1] neg_hi:[0,1]
	v_pk_add_f32 v[30:31], v[186:187], v[16:17]
	v_mov_b32_e32 v13, v5
	v_pk_mov_b32 v[32:33], v[28:29], v[30:31] op_sel:[1,0]
	v_pk_mul_f32 v[12:13], v[12:13], s[44:45]
	v_mul_f32_e32 v4, 0.5, v4
	v_pk_mul_f32 v[48:49], v[32:33], v[12:13] op_sel:[0,1] op_sel_hi:[1,0]
	v_pk_mul_f32 v[12:13], v[32:33], v[12:13]
	v_pk_add_f32 v[48:49], v[48:49], v[48:49] op_sel:[0,1] op_sel_hi:[0,1]
	v_pk_add_f32 v[50:51], v[4:5], v[48:49] op_sel_hi:[0,1] neg_hi:[0,1]
	v_pk_add_f32 v[4:5], v[12:13], v[12:13] op_sel:[0,1] op_sel_hi:[0,1] neg_lo:[0,1] neg_hi:[0,1]
	v_pk_add_f32 v[12:13], v[6:7], v[4:5] op_sel_hi:[0,1] neg_hi:[0,1]
	v_pk_mul_f32 v[4:5], v[12:13], v[184:185]
	v_pk_mul_f32 v[12:13], v[12:13], v[170:171]
	v_pk_fma_f32 v[4:5], v[50:51], v[170:171], v[4:5]
	v_pk_fma_f32 v[12:13], v[50:51], v[184:185], v[12:13] neg_lo:[0,0,1] neg_hi:[0,0,1]
	v_mov_b32_e32 v31, v29
	v_pk_add_f32 v[48:49], v[12:13], v[4:5] op_sel:[0,1] op_sel_hi:[1,0] neg_lo:[0,1]
	v_pk_add_f32 v[50:51], v[12:13], v[4:5] op_sel:[0,1] op_sel_hi:[1,0]
	v_pk_add_f32 v[4:5], v[4:5], v[12:13] op_sel:[1,0] op_sel_hi:[0,1] neg_lo:[0,1] neg_hi:[0,1]
	v_pk_mul_f32 v[48:49], v[48:49], 0.5 op_sel_hi:[1,0]
	v_mov_b32_e32 v51, v5
	v_mul_f32_e32 v6, v29, v48
	v_pk_fma_f32 v[32:33], v[32:33], v[48:49], v[6:7] op_sel_hi:[1,1,0] neg_lo:[1,0,0] neg_hi:[1,0,0]
	v_mul_f32_e32 v6, v29, v49
	v_pk_fma_f32 v[28:29], v[30:31], v[48:49], v[6:7] op_sel_hi:[1,1,0]
	v_pk_mul_f32 v[12:13], v[16:17], s[36:37]
	v_mov_b32_e32 v32, v28
	v_pk_fma_f32 v[4:5], v[50:51], 0.5, v[28:29] op_sel_hi:[1,0,1] neg_lo:[0,0,1] neg_hi:[0,0,1]
	v_pk_fma_f32 v[138:139], v[50:51], 0.5, v[32:33] op_sel_hi:[1,0,1]
	v_pk_add_f32 v[16:17], v[92:93], v[182:183]
	v_mov_b32_e32 v5, v139
	v_pk_add_f32 v[28:29], v[92:93], v[182:183] neg_lo:[0,1] neg_hi:[0,1]
	v_pk_mul_f32 v[30:31], v[4:5], s[46:47] op_sel_hi:[1,0]
	v_pk_fma_f32 v[4:5], v[50:51], 0.5, v[32:33] op_sel_hi:[1,0,1] neg_lo:[1,0,0] neg_hi:[1,0,0]
	v_mul_f32_e32 v6, 0.5, v29
	v_pk_add_f32 v[32:33], v[18:19], v[12:13] op_sel:[0,1] op_sel_hi:[0,1] neg_lo:[0,1] neg_hi:[0,1]
	v_pk_add_f32 v[48:49], v[18:19], v[12:13] op_sel:[0,1] op_sel_hi:[0,1]
	v_mov_b32_e32 v29, v17
	v_mul_f32_e32 v4, 0.5, v16
	v_mov_b32_e32 v50, v32
	v_mov_b32_e32 v51, v49
	v_pk_mul_f32 v[16:17], v[28:29], s[44:45]
	v_pk_mov_b32 v[48:49], v[48:49], v[32:33] op_sel:[1,0]
	v_pk_mul_f32 v[28:29], v[50:51], v[16:17] op_sel:[0,1] op_sel_hi:[1,0]
	v_pk_mul_f32 v[16:17], v[50:51], v[16:17]
	v_pk_add_f32 v[28:29], v[28:29], v[28:29] op_sel:[0,1] op_sel_hi:[0,1]
	v_pk_add_f32 v[52:53], v[4:5], v[28:29] op_sel_hi:[0,1] neg_hi:[0,1]
	v_pk_add_f32 v[16:17], v[16:17], v[16:17] op_sel:[0,1] op_sel_hi:[0,1] neg_lo:[0,1] neg_hi:[0,1]
	v_pk_add_f32 v[28:29], v[6:7], v[16:17] op_sel_hi:[0,1] neg_hi:[0,1]
	v_pk_mul_f32 v[16:17], v[28:29], v[180:181]
	v_pk_mul_f32 v[28:29], v[28:29], v[172:173]
	v_pk_fma_f32 v[16:17], v[52:53], v[172:173], v[16:17]
	v_pk_fma_f32 v[28:29], v[52:53], v[180:181], v[28:29] neg_lo:[0,0,1] neg_hi:[0,0,1]
	v_sub_f32_e32 v6, v89, v177
	v_pk_add_f32 v[52:53], v[28:29], v[16:17] op_sel:[0,1] op_sel_hi:[1,0] neg_lo:[0,1]
	v_pk_add_f32 v[54:55], v[28:29], v[16:17] op_sel:[0,1] op_sel_hi:[1,0]
	v_pk_add_f32 v[16:17], v[16:17], v[28:29] op_sel:[1,0] op_sel_hi:[0,1] neg_lo:[0,1] neg_hi:[0,1]
	v_pk_mul_f32 v[52:53], v[52:53], 0.5 op_sel_hi:[1,0]
	v_mov_b32_e32 v55, v17
	v_mul_f32_e32 v4, v32, v52
	v_pk_fma_f32 v[56:57], v[50:51], v[52:53], v[4:5] op_sel_hi:[1,1,0] neg_lo:[1,0,0] neg_hi:[1,0,0]
	v_mul_f32_e32 v4, v32, v53
	v_pk_fma_f32 v[48:49], v[48:49], v[52:53], v[4:5] op_sel_hi:[1,1,0]
	v_pk_add_f32 v[28:29], v[88:89], v[176:177]
	v_mov_b32_e32 v56, v48
	v_pk_fma_f32 v[16:17], v[54:55], 0.5, v[48:49] op_sel_hi:[1,0,1] neg_lo:[0,0,1] neg_hi:[0,0,1]
	v_mov_b32_e32 v48, v12
	v_mov_b32_e32 v49, v88
	v_pk_mov_b32 v[12:13], v[12:13], v[176:177] op_sel:[1,0]
	v_mul_f32_e32 v18, 0.5, v29
	v_pk_add_f32 v[12:13], v[48:49], v[12:13] neg_lo:[0,1] neg_hi:[0,1]
	v_mul_f32_e32 v4, 0.5, v28
	v_pk_mul_f32 v[48:49], v[12:13], v[18:19]
	v_mov_b32_e32 v13, v32
	v_pk_fma_f32 v[50:51], v[50:51], v[48:49], v[48:49] op_sel:[0,1,0] op_sel_hi:[1,0,1]
	v_mov_b32_e32 v48, v49
	v_mov_b32_e32 v49, v18
	v_pk_mul_f32 v[48:49], v[12:13], v[48:49]
	v_pk_add_f32 v[52:53], v[4:5], v[50:51]
	v_mul_f32_e32 v6, 0.5, v6
	v_fma_f32 v53, v28, 0.5, -v50
	v_pk_add_f32 v[28:29], v[48:49], v[48:49] op_sel:[0,1] op_sel_hi:[0,1] neg_lo:[0,1] neg_hi:[0,1]
	v_pk_add_f32 v[48:49], v[6:7], v[28:29] op_sel_hi:[0,1] neg_hi:[0,1]
	v_pk_mul_f32 v[28:29], v[48:49], v[178:179]
	v_pk_mul_f32 v[48:49], v[48:49], v[174:175]
	v_pk_fma_f32 v[28:29], v[52:53], v[174:175], v[28:29]
	v_pk_fma_f32 v[48:49], v[52:53], v[178:179], v[48:49] neg_lo:[0,0,1] neg_hi:[0,0,1]
	v_pk_fma_f32 v[92:93], v[54:55], 0.5, v[56:57] op_sel_hi:[1,0,1]
	v_pk_add_f32 v[50:51], v[48:49], v[28:29] op_sel:[0,1] op_sel_hi:[1,0] neg_lo:[0,1]
	v_pk_add_f32 v[52:53], v[48:49], v[28:29] op_sel:[0,1] op_sel_hi:[1,0]
	v_mov_b32_e32 v17, v93
	v_pk_mul_f32 v[50:51], v[50:51], 0.5 op_sel_hi:[1,0]
	v_pk_mul_f32 v[64:65], v[16:17], s[46:47] op_sel_hi:[1,0]
	v_mul_f32_e32 v4, v12, v50
	v_pk_fma_f32 v[16:17], v[54:55], 0.5, v[56:57] op_sel_hi:[1,0,1] neg_lo:[1,0,0] neg_hi:[1,0,0]
	v_pk_fma_f32 v[54:55], v[12:13], v[50:51], v[4:5] op_sel_hi:[1,1,0] neg_lo:[1,0,0] neg_hi:[1,0,0]
	v_mov_b32_e32 v33, v12
	v_mul_f32_e32 v4, v12, v51
	v_pk_fma_f32 v[12:13], v[32:33], v[50:51], v[4:5] op_sel_hi:[1,1,0]
	v_pk_add_f32 v[28:29], v[28:29], v[48:49] op_sel:[1,0] op_sel_hi:[0,1] neg_lo:[0,1] neg_hi:[0,1]
	v_mov_b32_e32 v53, v29
	v_mov_b32_e32 v54, v12
	v_pk_fma_f32 v[12:13], v[52:53], 0.5, v[12:13] op_sel_hi:[1,0,1] neg_lo:[0,0,1] neg_hi:[0,0,1]
	v_pk_fma_f32 v[88:89], v[52:53], 0.5, v[54:55] op_sel_hi:[1,0,1]
	s_mov_b32 s67, s16
	v_mov_b32_e32 v13, v89
	v_pk_mul_f32 v[68:69], v[12:13], s[46:47] op_sel_hi:[1,0]
	v_pk_fma_f32 v[12:13], v[52:53], 0.5, v[54:55] op_sel_hi:[1,0,1] neg_lo:[1,0,0] neg_hi:[1,0,0]
	v_mov_b32_e32 v4, v83
	s_mov_b32 s17, s19
	v_pk_mul_f32 v[48:49], v[82:83], s[66:67] op_sel_hi:[0,1]
	v_pk_add_f32 v[28:29], v[96:97], v[162:163]
	v_pk_add_f32 v[32:33], v[96:97], v[162:163] neg_lo:[0,1] neg_hi:[0,1]
	v_pk_fma_f32 v[52:53], v[4:5], s[16:17], v[48:49] op_sel_hi:[0,1,1] neg_lo:[0,0,1] neg_hi:[0,0,1]
	v_mul_f32_e32 v12, 0.5, v33
	v_pk_fma_f32 v[50:51], v[4:5], s[16:17], v[48:49] op_sel_hi:[0,1,1]
	v_mov_b32_e32 v33, v29
	v_mul_f32_e32 v6, 0.5, v28
	v_mov_b32_e32 v54, v52
	v_mov_b32_e32 v55, v51
	v_pk_mul_f32 v[28:29], v[32:33], s[44:45]
	v_pk_mov_b32 v[56:57], v[50:51], v[52:53] op_sel:[1,0]
	v_pk_mul_f32 v[32:33], v[54:55], v[28:29] op_sel:[0,1] op_sel_hi:[1,0]
	v_pk_mul_f32 v[28:29], v[54:55], v[28:29]
	v_pk_add_f32 v[32:33], v[32:33], v[32:33] op_sel:[0,1] op_sel_hi:[0,1]
	v_pk_add_f32 v[58:59], v[6:7], v[32:33] op_sel_hi:[0,1] neg_hi:[0,1]
	v_pk_add_f32 v[28:29], v[28:29], v[28:29] op_sel:[0,1] op_sel_hi:[0,1] neg_lo:[0,1] neg_hi:[0,1]
	v_pk_add_f32 v[32:33], v[12:13], v[28:29] op_sel_hi:[0,1] neg_hi:[0,1]
	v_pk_mul_f32 v[28:29], v[32:33], v[166:167]
	v_pk_mul_f32 v[32:33], v[32:33], v[164:165]
	v_pk_fma_f32 v[28:29], v[58:59], v[164:165], v[28:29]
	v_pk_fma_f32 v[32:33], v[58:59], v[166:167], v[32:33] neg_lo:[0,0,1] neg_hi:[0,0,1]
	v_mov_b32_e32 v159, v66
	v_pk_add_f32 v[58:59], v[32:33], v[28:29] op_sel:[0,1] op_sel_hi:[1,0] neg_lo:[0,1]
	v_pk_add_f32 v[70:71], v[32:33], v[28:29] op_sel:[0,1] op_sel_hi:[1,0]
	v_pk_add_f32 v[28:29], v[28:29], v[32:33] op_sel:[1,0] op_sel_hi:[0,1] neg_lo:[0,1] neg_hi:[0,1]
	v_pk_mul_f32 v[58:59], v[58:59], 0.5 op_sel_hi:[1,0]
	v_mov_b32_e32 v71, v29
	v_mul_f32_e32 v6, v52, v58
	v_pk_fma_f32 v[72:73], v[54:55], v[58:59], v[6:7] op_sel_hi:[1,1,0] neg_lo:[1,0,0] neg_hi:[1,0,0]
	v_mul_f32_e32 v6, v52, v59
	v_pk_fma_f32 v[56:57], v[56:57], v[58:59], v[6:7] op_sel_hi:[1,1,0]
	v_sub_f32_e32 v12, v67, v153
	v_mov_b32_e32 v72, v56
	v_pk_fma_f32 v[28:29], v[70:71], 0.5, v[56:57] op_sel_hi:[1,0,1] neg_lo:[0,0,1] neg_hi:[0,0,1]
	v_pk_fma_f32 v[96:97], v[70:71], 0.5, v[72:73] op_sel_hi:[1,0,1]
	v_pk_mov_b32 v[56:57], v[48:49], v[152:153] op_sel:[1,0]
	v_mov_b32_e32 v29, v97
	v_pk_mul_f32 v[62:63], v[28:29], s[46:47] op_sel_hi:[1,0]
	v_pk_add_f32 v[28:29], v[66:67], v[152:153]
	v_pk_add_f32 v[56:57], v[158:159], v[56:57] neg_lo:[0,1] neg_hi:[0,1]
	v_mul_f32_e32 v18, 0.5, v29
	v_pk_mul_f32 v[58:59], v[56:57], v[18:19]
	v_mul_f32_e32 v6, 0.5, v28
	v_pk_fma_f32 v[54:55], v[54:55], v[58:59], v[58:59] op_sel:[0,1,0] op_sel_hi:[1,0,1]
	v_mov_b32_e32 v66, v56
	v_mov_b32_e32 v67, v52
	v_mov_b32_e32 v58, v59
	v_mov_b32_e32 v59, v18
	v_pk_mul_f32 v[58:59], v[66:67], v[58:59]
	v_pk_add_f32 v[66:67], v[6:7], v[54:55]
	v_mul_f32_e32 v12, 0.5, v12
	v_fma_f32 v67, v28, 0.5, -v54
	v_pk_add_f32 v[28:29], v[58:59], v[58:59] op_sel:[0,1] op_sel_hi:[0,1] neg_lo:[0,1] neg_hi:[0,1]
	v_pk_add_f32 v[54:55], v[12:13], v[28:29] op_sel_hi:[0,1] neg_hi:[0,1]
	v_pk_mul_f32 v[28:29], v[54:55], v[156:157]
	v_pk_mul_f32 v[54:55], v[54:55], v[154:155]
	v_pk_fma_f32 v[32:33], v[70:71], 0.5, v[72:73] op_sel_hi:[1,0,1] neg_lo:[1,0,0] neg_hi:[1,0,0]
	v_pk_fma_f32 v[58:59], v[66:67], v[154:155], v[28:29] neg_lo:[0,0,1] neg_hi:[0,0,1]
	v_pk_fma_f32 v[28:29], v[66:67], v[154:155], v[28:29]
	v_pk_fma_f32 v[70:71], v[66:67], v[156:157], v[54:55]
	v_pk_fma_f32 v[54:55], v[66:67], v[156:157], v[54:55] neg_lo:[0,0,1] neg_hi:[0,0,1]
	v_pk_add_f32 v[72:73], v[58:59], v[28:29] op_sel:[0,1] op_sel_hi:[1,0]
	v_pk_add_f32 v[66:67], v[70:71], v[54:55] op_sel_hi:[0,1] neg_lo:[0,1] neg_hi:[0,1]
	v_pk_add_f32 v[28:29], v[58:59], v[28:29] op_sel_hi:[0,1] neg_lo:[0,1] neg_hi:[0,1]
	v_pk_add_f32 v[54:55], v[70:71], v[54:55] op_sel:[0,1] op_sel_hi:[1,0]
	v_mov_b32_e32 v73, v67
	v_mov_b32_e32 v55, v29
	v_pk_mul_f32 v[28:29], v[54:55], 0.5 op_sel_hi:[1,0]
	v_mov_b32_e32 v133, v84
	v_pk_mul_f32 v[54:55], v[52:53], v[28:29] op_sel:[0,1] op_sel_hi:[0,0]
	v_pk_fma_f32 v[58:59], v[56:57], v[28:29], v[54:55] op_sel_hi:[0,1,1]
	v_pk_fma_f32 v[28:29], v[56:57], v[28:29], v[54:55] op_sel_hi:[0,1,1] neg_hi:[0,0,1]
	v_pk_fma_f32 v[54:55], v[72:73], 0.5, v[58:59] op_sel_hi:[1,0,1] neg_lo:[0,0,1] neg_hi:[0,0,1]
	v_pk_fma_f32 v[66:67], v[72:73], 0.5, v[28:29] op_sel_hi:[1,0,1]
	v_pk_add_f32 v[56:57], v[60:61], v[134:135] neg_lo:[0,1] neg_hi:[0,1]
	v_mov_b32_e32 v55, v67
	v_pk_mul_f32 v[90:91], v[54:55], s[46:47] op_sel_hi:[1,0]
	v_pk_add_f32 v[54:55], v[134:135], v[60:61]
	v_mul_f32_e32 v12, 0.5, v57
	v_mov_b32_e32 v57, v55
	v_mul_f32_e32 v6, 0.5, v54
	v_pk_mov_b32 v[58:59], v[52:53], v[50:51] op_sel:[1,0]
	v_pk_mul_f32 v[54:55], v[56:57], s[44:45]
	v_pk_fma_f32 v[28:29], v[72:73], 0.5, v[28:29] op_sel_hi:[1,0,1] neg_lo:[1,0,0] neg_hi:[1,0,0]
	v_pk_mul_f32 v[56:57], v[58:59], v[54:55] op_sel:[0,1] op_sel_hi:[1,0]
	v_pk_mul_f32 v[54:55], v[58:59], v[54:55]
	v_pk_add_f32 v[56:57], v[56:57], v[56:57] op_sel:[0,1] op_sel_hi:[0,1]
	v_pk_add_f32 v[60:61], v[6:7], v[56:57] op_sel_hi:[0,1] neg_hi:[0,1]
	v_pk_add_f32 v[54:55], v[54:55], v[54:55] op_sel:[0,1] op_sel_hi:[0,1] neg_lo:[0,1] neg_hi:[0,1]
	v_pk_add_f32 v[56:57], v[12:13], v[54:55] op_sel_hi:[0,1] neg_hi:[0,1]
	v_pk_mul_f32 v[54:55], v[56:57], v[142:143]
	v_pk_mul_f32 v[56:57], v[56:57], v[140:141]
	v_pk_fma_f32 v[54:55], v[60:61], v[140:141], v[54:55]
	v_pk_fma_f32 v[56:57], v[60:61], v[142:143], v[56:57] neg_lo:[0,0,1] neg_hi:[0,0,1]
	v_mov_b32_e32 v51, v53
	v_pk_add_f32 v[60:61], v[56:57], v[54:55] op_sel:[0,1] op_sel_hi:[1,0] neg_lo:[0,1]
	v_pk_add_f32 v[70:71], v[56:57], v[54:55] op_sel:[0,1] op_sel_hi:[1,0]
	v_pk_add_f32 v[54:55], v[54:55], v[56:57] op_sel:[1,0] op_sel_hi:[0,1] neg_lo:[0,1] neg_hi:[0,1]
	v_pk_mul_f32 v[60:61], v[60:61], 0.5 op_sel_hi:[1,0]
	v_mov_b32_e32 v71, v55
	v_mul_f32_e32 v6, v53, v60
	v_pk_fma_f32 v[72:73], v[58:59], v[60:61], v[6:7] op_sel_hi:[1,1,0] neg_lo:[1,0,0] neg_hi:[1,0,0]
	v_mul_f32_e32 v6, v53, v61
	v_pk_fma_f32 v[50:51], v[50:51], v[60:61], v[6:7] op_sel_hi:[1,1,0]
	v_pk_add_f32 v[54:55], v[118:119], v[84:85]
	v_mov_b32_e32 v72, v50
	v_mov_b32_e32 v49, v118
	v_pk_fma_f32 v[50:51], v[70:71], 0.5, v[50:51] op_sel_hi:[1,0,1] neg_lo:[0,0,1] neg_hi:[0,0,1]
	v_pk_fma_f32 v[60:61], v[70:71], 0.5, v[72:73] op_sel_hi:[1,0,1]
	v_mul_f32_e32 v18, 0.5, v55
	v_pk_add_f32 v[48:49], v[132:133], v[48:49] neg_lo:[0,1] neg_hi:[0,1]
	v_mov_b32_e32 v51, v61
	v_pk_mul_f32 v[56:57], v[48:49], v[18:19]
	v_pk_mul_f32 v[94:95], v[50:51], s[46:47] op_sel_hi:[1,0]
	v_pk_fma_f32 v[50:51], v[70:71], 0.5, v[72:73] op_sel_hi:[1,0,1] neg_lo:[1,0,0] neg_hi:[1,0,0]
	v_mul_f32_e32 v6, 0.5, v54
	v_pk_fma_f32 v[58:59], v[58:59], v[56:57], v[56:57] op_sel:[0,1,0] op_sel_hi:[1,0,1]
	v_mov_b32_e32 v70, v48
	v_mov_b32_e32 v71, v53
	v_mov_b32_e32 v56, v57
	v_mov_b32_e32 v57, v18
	v_sub_f32_e32 v12, v85, v119
	v_pk_mul_f32 v[56:57], v[70:71], v[56:57]
	v_pk_add_f32 v[70:71], v[6:7], v[58:59]
	v_mul_f32_e32 v12, 0.5, v12
	v_fma_f32 v71, v54, 0.5, -v58
	v_pk_add_f32 v[54:55], v[56:57], v[56:57] op_sel:[0,1] op_sel_hi:[0,1] neg_lo:[0,1] neg_hi:[0,1]
	v_pk_add_f32 v[56:57], v[12:13], v[54:55] op_sel_hi:[0,1] neg_hi:[0,1]
	v_pk_mul_f32 v[54:55], v[56:57], v[126:127]
	v_pk_mul_f32 v[56:57], v[56:57], v[124:125]
	v_pk_fma_f32 v[58:59], v[70:71], v[124:125], v[54:55] neg_lo:[0,0,1] neg_hi:[0,0,1]
	v_pk_fma_f32 v[54:55], v[70:71], v[124:125], v[54:55]
	v_pk_fma_f32 v[72:73], v[70:71], v[126:127], v[56:57]
	v_pk_fma_f32 v[56:57], v[70:71], v[126:127], v[56:57] neg_lo:[0,0,1] neg_hi:[0,0,1]
	v_pk_add_f32 v[70:71], v[58:59], v[54:55] op_sel:[0,1] op_sel_hi:[1,0]
	v_pk_add_f32 v[74:75], v[72:73], v[56:57] op_sel_hi:[0,1] neg_lo:[0,1] neg_hi:[0,1]
	v_pk_add_f32 v[54:55], v[58:59], v[54:55] op_sel_hi:[0,1] neg_lo:[0,1] neg_hi:[0,1]
	v_pk_add_f32 v[56:57], v[72:73], v[56:57] op_sel:[0,1] op_sel_hi:[1,0]
	v_mov_b32_e32 v71, v75
	v_mov_b32_e32 v57, v55
	v_pk_mul_f32 v[54:55], v[56:57], 0.5 op_sel_hi:[1,0]
	s_mov_b32 s66, s11
	v_pk_mul_f32 v[52:53], v[52:53], v[54:55] op_sel:[1,1] op_sel_hi:[1,0]
	s_mov_b32 s67, s8
	v_pk_fma_f32 v[56:57], v[48:49], v[54:55], v[52:53] op_sel_hi:[0,1,1]
	v_pk_fma_f32 v[48:49], v[48:49], v[54:55], v[52:53] op_sel_hi:[0,1,1] neg_hi:[0,0,1]
	s_nop 0
	v_pk_fma_f32 v[52:53], v[70:71], 0.5, v[56:57] op_sel_hi:[1,0,1] neg_lo:[0,0,1] neg_hi:[0,0,1]
	v_pk_fma_f32 v[84:85], v[70:71], 0.5, v[48:49] op_sel_hi:[1,0,1]
	s_mov_b32 s9, s11
	v_mov_b32_e32 v53, v85
	v_pk_mul_f32 v[80:81], v[52:53], s[46:47] op_sel_hi:[1,0]
	v_pk_mul_f32 v[118:119], v[82:83], s[66:67] op_sel_hi:[0,1]
	v_pk_add_f32 v[52:53], v[86:87], v[112:113]
	v_pk_add_f32 v[54:55], v[86:87], v[112:113] neg_lo:[0,1] neg_hi:[0,1]
	v_pk_fma_f32 v[58:59], v[4:5], s[8:9], v[118:119] op_sel_hi:[0,1,1] neg_lo:[0,0,1] neg_hi:[0,0,1]
	v_mul_f32_e32 v12, 0.5, v55
	v_pk_fma_f32 v[72:73], v[4:5], s[8:9], v[118:119] op_sel_hi:[0,1,1]
	v_mov_b32_e32 v55, v53
	v_mul_f32_e32 v6, 0.5, v52
	v_mov_b32_e32 v56, v58
	v_mov_b32_e32 v57, v73
	v_pk_mul_f32 v[52:53], v[54:55], s[44:45]
	v_pk_fma_f32 v[48:49], v[70:71], 0.5, v[48:49] op_sel_hi:[1,0,1] neg_lo:[1,0,0] neg_hi:[1,0,0]
	v_pk_mul_f32 v[54:55], v[56:57], v[52:53] op_sel:[0,1] op_sel_hi:[1,0]
	v_pk_mul_f32 v[52:53], v[56:57], v[52:53]
	v_pk_add_f32 v[54:55], v[54:55], v[54:55] op_sel:[0,1] op_sel_hi:[0,1]
	v_pk_add_f32 v[74:75], v[6:7], v[54:55] op_sel_hi:[0,1] neg_hi:[0,1]
	v_pk_add_f32 v[52:53], v[52:53], v[52:53] op_sel:[0,1] op_sel_hi:[0,1] neg_lo:[0,1] neg_hi:[0,1]
	v_pk_add_f32 v[54:55], v[12:13], v[52:53] op_sel_hi:[0,1] neg_hi:[0,1]
	v_pk_mul_f32 v[52:53], v[54:55], v[116:117]
	v_pk_mul_f32 v[54:55], v[54:55], v[114:115]
	v_pk_fma_f32 v[52:53], v[74:75], v[114:115], v[52:53]
	v_pk_fma_f32 v[54:55], v[74:75], v[116:117], v[54:55] neg_lo:[0,0,1] neg_hi:[0,0,1]
	v_pk_mov_b32 v[70:71], v[72:73], v[58:59] op_sel:[1,0]
	v_pk_add_f32 v[74:75], v[54:55], v[52:53] op_sel:[0,1] op_sel_hi:[1,0] neg_lo:[0,1]
	v_pk_add_f32 v[76:77], v[54:55], v[52:53] op_sel:[0,1] op_sel_hi:[1,0]
	v_pk_add_f32 v[52:53], v[52:53], v[54:55] op_sel:[1,0] op_sel_hi:[0,1] neg_lo:[0,1] neg_hi:[0,1]
	v_pk_mul_f32 v[74:75], v[74:75], 0.5 op_sel_hi:[1,0]
	v_mov_b32_e32 v77, v53
	v_mul_f32_e32 v6, v58, v74
	v_pk_fma_f32 v[112:113], v[56:57], v[74:75], v[6:7] op_sel_hi:[1,1,0] neg_lo:[1,0,0] neg_hi:[1,0,0]
	v_mul_f32_e32 v6, v58, v75
	v_pk_fma_f32 v[70:71], v[70:71], v[74:75], v[6:7] op_sel_hi:[1,1,0]
	v_pk_add_f32 v[54:55], v[34:35], v[110:111]
	v_mov_b32_e32 v112, v70
	v_pk_fma_f32 v[52:53], v[76:77], 0.5, v[70:71] op_sel_hi:[1,0,1] neg_lo:[0,0,1] neg_hi:[0,0,1]
	v_pk_fma_f32 v[86:87], v[76:77], 0.5, v[112:113] op_sel_hi:[1,0,1]
	v_sub_f32_e32 v12, v35, v111
	v_mov_b32_e32 v53, v87
	v_pk_mul_f32 v[78:79], v[52:53], s[46:47] op_sel_hi:[1,0]
	v_mul_f32_e32 v52, 0xbe47c5c2, v83
	v_mov_b32_e32 v53, v34
	v_pk_mov_b32 v[34:35], v[118:119], v[110:111] op_sel:[1,0]
	v_mul_f32_e32 v18, 0.5, v55
	v_pk_add_f32 v[34:35], v[52:53], v[34:35] neg_lo:[0,1] neg_hi:[0,1]
	v_mov_b32_e32 v71, v58
	v_pk_mul_f32 v[52:53], v[34:35], v[18:19]
	v_mov_b32_e32 v70, v34
	v_pk_fma_f32 v[56:57], v[56:57], v[52:53], v[52:53] op_sel:[0,1,0] op_sel_hi:[1,0,1]
	v_mov_b32_e32 v52, v53
	v_mov_b32_e32 v53, v18
	v_mul_f32_e32 v6, 0.5, v54
	v_pk_mul_f32 v[52:53], v[70:71], v[52:53]
	v_cvt_f32_f16_e32 v70, v46
	v_cvt_f32_f16_e32 v71, v47
	v_cvt_f32_f16_sdwa v47, v47 dst_sel:DWORD dst_unused:UNUSED_PAD src0_sel:WORD_1
	v_cvt_f32_f16_sdwa v46, v46 dst_sel:DWORD dst_unused:UNUSED_PAD src0_sel:WORD_1
	v_pk_fma_f32 v[74:75], v[76:77], 0.5, v[112:113] op_sel_hi:[1,0,1] neg_lo:[1,0,0] neg_hi:[1,0,0]
	v_mul_f32_e32 v12, 0.5, v12
	v_pk_add_f32 v[76:77], v[6:7], v[56:57]
	v_pk_add_f32 v[52:53], v[52:53], v[52:53] op_sel:[0,1] op_sel_hi:[0,1] neg_lo:[0,1] neg_hi:[0,1]
	v_fma_f32 v77, v54, 0.5, -v56
	v_pk_add_f32 v[54:55], v[12:13], v[52:53] op_sel_hi:[0,1] neg_hi:[0,1]
	v_pk_mul_f32 v[52:53], v[54:55], v[46:47]
	v_pk_mul_f32 v[54:55], v[54:55], v[70:71]
	v_pk_fma_f32 v[56:57], v[76:77], v[70:71], v[52:53] neg_lo:[0,0,1] neg_hi:[0,0,1]
	v_pk_fma_f32 v[52:53], v[76:77], v[70:71], v[52:53]
	v_pk_fma_f32 v[70:71], v[76:77], v[46:47], v[54:55]
	v_pk_fma_f32 v[46:47], v[76:77], v[46:47], v[54:55] neg_lo:[0,0,1] neg_hi:[0,0,1]
	v_pk_add_f32 v[54:55], v[56:57], v[52:53] op_sel:[0,1] op_sel_hi:[1,0]
	v_pk_add_f32 v[76:77], v[70:71], v[46:47] op_sel_hi:[0,1] neg_lo:[0,1] neg_hi:[0,1]
	v_pk_add_f32 v[52:53], v[56:57], v[52:53] op_sel_hi:[0,1] neg_lo:[0,1] neg_hi:[0,1]
	v_pk_add_f32 v[46:47], v[70:71], v[46:47] op_sel:[0,1] op_sel_hi:[1,0]
	v_mov_b32_e32 v55, v77
	v_mov_b32_e32 v47, v53
	v_pk_mul_f32 v[46:47], v[46:47], 0.5 op_sel_hi:[1,0]
	s_mov_b32 s25, s27
	v_pk_mul_f32 v[52:53], v[58:59], v[46:47] op_sel:[0,1] op_sel_hi:[0,0]
	v_pk_fma_f32 v[56:57], v[34:35], v[46:47], v[52:53] op_sel_hi:[0,1,1]
	v_pk_fma_f32 v[46:47], v[34:35], v[46:47], v[52:53] op_sel_hi:[0,1,1] neg_hi:[0,0,1]
	s_nop 0
	v_pk_fma_f32 v[52:53], v[54:55], 0.5, v[56:57] op_sel_hi:[1,0,1] neg_lo:[0,0,1] neg_hi:[0,0,1]
	v_pk_fma_f32 v[34:35], v[54:55], 0.5, v[46:47] op_sel_hi:[1,0,1]
	s_mov_b32 s66, s27
	v_mov_b32_e32 v53, v35
	v_pk_mul_f32 v[136:137], v[52:53], s[46:47] op_sel_hi:[1,0]
	v_pk_fma_f32 v[52:53], v[54:55], 0.5, v[46:47] op_sel_hi:[1,0,1] neg_lo:[1,0,0] neg_hi:[1,0,0]
	s_mov_b32 s67, s24
	v_pk_mul_f32 v[46:47], v[82:83], s[24:25] op_sel_hi:[0,1]
	v_pk_add_f32 v[54:55], v[108:109], v[40:41]
	v_pk_add_f32 v[40:41], v[40:41], v[108:109] neg_lo:[0,1] neg_hi:[0,1]
	v_pk_fma_f32 v[108:109], v[4:5], s[66:67], v[46:47] op_sel_hi:[0,1,1] neg_lo:[0,0,1] neg_hi:[0,0,1]
	v_mul_f32_e32 v12, 0.5, v41
	v_pk_fma_f32 v[70:71], v[4:5], s[66:67], v[46:47] op_sel_hi:[0,1,1]
	v_mov_b32_e32 v41, v55
	v_mov_b32_e32 v56, v108
	v_mov_b32_e32 v57, v71
	v_pk_mul_f32 v[40:41], v[40:41], s[44:45]
	v_mul_f32_e32 v6, 0.5, v54
	v_pk_mul_f32 v[54:55], v[56:57], v[40:41] op_sel:[0,1] op_sel_hi:[1,0]
	v_cvt_f32_f16_sdwa v76, v38 dst_sel:DWORD dst_unused:UNUSED_PAD src0_sel:WORD_1
	v_cvt_f32_f16_e32 v77, v39
	v_cvt_f32_f16_sdwa v39, v39 dst_sel:DWORD dst_unused:UNUSED_PAD src0_sel:WORD_1
	v_cvt_f32_f16_e32 v38, v38
	v_pk_mul_f32 v[40:41], v[56:57], v[40:41]
	v_pk_add_f32 v[54:55], v[54:55], v[54:55] op_sel:[0,1] op_sel_hi:[0,1]
	v_pk_add_f32 v[112:113], v[6:7], v[54:55] op_sel_hi:[0,1] neg_hi:[0,1]
	s_nop 0
	v_pk_add_f32 v[40:41], v[40:41], v[40:41] op_sel:[0,1] op_sel_hi:[0,1] neg_lo:[0,1] neg_hi:[0,1]
	v_pk_add_f32 v[54:55], v[12:13], v[40:41] op_sel_hi:[0,1] neg_hi:[0,1]
	v_pk_mul_f32 v[40:41], v[54:55], v[38:39]
	v_pk_mul_f32 v[54:55], v[54:55], v[76:77]
	v_pk_fma_f32 v[40:41], v[112:113], v[76:77], v[40:41]
	v_pk_fma_f32 v[38:39], v[112:113], v[38:39], v[54:55] neg_lo:[0,0,1] neg_hi:[0,0,1]
	v_pk_mov_b32 v[110:111], v[70:71], v[108:109] op_sel:[1,0]
	v_pk_add_f32 v[54:55], v[38:39], v[40:41] op_sel:[0,1] op_sel_hi:[1,0] neg_lo:[0,1]
	v_pk_add_f32 v[76:77], v[38:39], v[40:41] op_sel:[0,1] op_sel_hi:[1,0]
	v_pk_add_f32 v[38:39], v[40:41], v[38:39] op_sel:[1,0] op_sel_hi:[0,1] neg_lo:[0,1] neg_hi:[0,1]
	v_pk_mul_f32 v[54:55], v[54:55], 0.5 op_sel_hi:[1,0]
	v_mov_b32_e32 v77, v39
	v_mul_f32_e32 v4, v108, v54
	v_pk_fma_f32 v[112:113], v[56:57], v[54:55], v[4:5] op_sel_hi:[1,1,0] neg_lo:[1,0,0] neg_hi:[1,0,0]
	v_mul_f32_e32 v4, v108, v55
	v_pk_fma_f32 v[54:55], v[110:111], v[54:55], v[4:5] op_sel_hi:[1,1,0]
	v_sub_f32_e32 v6, v45, v105
	v_mov_b32_e32 v112, v54
	v_pk_fma_f32 v[40:41], v[76:77], 0.5, v[54:55] op_sel_hi:[1,0,1] neg_lo:[0,0,1] neg_hi:[0,0,1]
	v_pk_fma_f32 v[38:39], v[76:77], 0.5, v[112:113] op_sel_hi:[1,0,1]
	v_pk_add_f32 v[54:55], v[104:105], v[44:45]
	v_mov_b32_e32 v41, v39
	v_pk_mul_f32 v[130:131], v[40:41], s[46:47] op_sel_hi:[1,0]
	v_mul_f32_e32 v40, 0xbf54db31, v83
	v_mov_b32_e32 v41, v44
	v_pk_mov_b32 v[44:45], v[46:47], v[104:105] op_sel:[1,0]
	v_mul_f32_e32 v18, 0.5, v55
	v_pk_add_f32 v[40:41], v[40:41], v[44:45] neg_lo:[0,1] neg_hi:[0,1]
	v_mov_b32_e32 v105, v108
	v_pk_mul_f32 v[44:45], v[40:41], v[18:19]
	v_mov_b32_e32 v104, v40
	v_pk_fma_f32 v[56:57], v[56:57], v[44:45], v[44:45] op_sel:[0,1,0] op_sel_hi:[1,0,1]
	v_mov_b32_e32 v44, v45
	v_mov_b32_e32 v45, v18
	v_mul_f32_e32 v4, 0.5, v54
	v_pk_mul_f32 v[44:45], v[104:105], v[44:45]
	v_cvt_f32_f16_e32 v104, v26
	v_cvt_f32_f16_e32 v105, v27
	v_cvt_f32_f16_sdwa v27, v27 dst_sel:DWORD dst_unused:UNUSED_PAD src0_sel:WORD_1
	v_cvt_f32_f16_sdwa v26, v26 dst_sel:DWORD dst_unused:UNUSED_PAD src0_sel:WORD_1
	v_mul_f32_e32 v6, 0.5, v6
	v_pk_add_f32 v[110:111], v[4:5], v[56:57]
	v_pk_add_f32 v[44:45], v[44:45], v[44:45] op_sel:[0,1] op_sel_hi:[0,1] neg_lo:[0,1] neg_hi:[0,1]
	v_fma_f32 v111, v54, 0.5, -v56
	v_pk_add_f32 v[54:55], v[6:7], v[44:45] op_sel_hi:[0,1] neg_hi:[0,1]
	v_pk_mul_f32 v[44:45], v[54:55], v[26:27]
	v_pk_mul_f32 v[54:55], v[54:55], v[104:105]
	v_pk_fma_f32 v[56:57], v[110:111], v[104:105], v[44:45] neg_lo:[0,0,1] neg_hi:[0,0,1]
	v_pk_fma_f32 v[44:45], v[110:111], v[104:105], v[44:45]
	v_pk_fma_f32 v[104:105], v[110:111], v[26:27], v[54:55]
	v_pk_fma_f32 v[26:27], v[110:111], v[26:27], v[54:55] neg_lo:[0,0,1] neg_hi:[0,0,1]
	v_pk_add_f32 v[54:55], v[56:57], v[44:45] op_sel:[0,1] op_sel_hi:[1,0]
	v_pk_add_f32 v[110:111], v[104:105], v[26:27] op_sel_hi:[0,1] neg_lo:[0,1] neg_hi:[0,1]
	v_pk_add_f32 v[44:45], v[56:57], v[44:45] op_sel_hi:[0,1] neg_lo:[0,1] neg_hi:[0,1]
	v_pk_add_f32 v[26:27], v[104:105], v[26:27] op_sel:[0,1] op_sel_hi:[1,0]
	v_mov_b32_e32 v55, v111
	v_mov_b32_e32 v27, v45
	v_pk_mul_f32 v[26:27], v[26:27], 0.5 op_sel_hi:[1,0]
	v_mov_b32_e32 v47, v102
	v_pk_mul_f32 v[44:45], v[108:109], v[26:27] op_sel:[0,1] op_sel_hi:[0,0]
	v_pk_fma_f32 v[56:57], v[40:41], v[26:27], v[44:45] op_sel_hi:[0,1,1]
	v_pk_fma_f32 v[40:41], v[40:41], v[26:27], v[44:45] op_sel_hi:[0,1,1] neg_hi:[0,0,1]
	v_pk_fma_f32 v[44:45], v[54:55], 0.5, v[56:57] op_sel_hi:[1,0,1] neg_lo:[0,0,1] neg_hi:[0,0,1]
	v_pk_fma_f32 v[26:27], v[54:55], 0.5, v[40:41] op_sel_hi:[1,0,1]
	v_pk_fma_f32 v[56:57], v[54:55], 0.5, v[40:41] op_sel_hi:[1,0,1] neg_lo:[1,0,0] neg_hi:[1,0,0]
	v_pk_add_f32 v[40:41], v[106:107], v[42:43]
	v_pk_add_f32 v[42:43], v[42:43], v[106:107] neg_lo:[0,1] neg_hi:[0,1]
	v_mov_b32_e32 v45, v27
	v_mul_f32_e32 v6, 0.5, v43
	v_mov_b32_e32 v43, v41
	v_pk_mul_f32 v[120:121], v[44:45], s[46:47] op_sel_hi:[1,0]
	v_mul_f32_e32 v4, 0.5, v40
	v_pk_mov_b32 v[44:45], v[108:109], v[70:71] op_sel:[1,0]
	v_pk_mul_f32 v[40:41], v[42:43], s[44:45]
	v_cvt_f32_f16_sdwa v54, v20 dst_sel:DWORD dst_unused:UNUSED_PAD src0_sel:WORD_1
	v_pk_mul_f32 v[42:43], v[44:45], v[40:41] op_sel:[0,1] op_sel_hi:[1,0]
	v_cvt_f32_f16_e32 v55, v21
	v_cvt_f32_f16_sdwa v21, v21 dst_sel:DWORD dst_unused:UNUSED_PAD src0_sel:WORD_1
	v_cvt_f32_f16_e32 v20, v20
	v_pk_mul_f32 v[40:41], v[44:45], v[40:41]
	v_pk_add_f32 v[42:43], v[42:43], v[42:43] op_sel:[0,1] op_sel_hi:[0,1]
	v_pk_add_f32 v[104:105], v[4:5], v[42:43] op_sel_hi:[0,1] neg_hi:[0,1]
	s_nop 0
	v_pk_add_f32 v[40:41], v[40:41], v[40:41] op_sel:[0,1] op_sel_hi:[0,1] neg_lo:[0,1] neg_hi:[0,1]
	v_pk_add_f32 v[42:43], v[6:7], v[40:41] op_sel_hi:[0,1] neg_hi:[0,1]
	v_pk_mul_f32 v[40:41], v[42:43], v[20:21]
	v_pk_mul_f32 v[42:43], v[42:43], v[54:55]
	v_pk_fma_f32 v[40:41], v[104:105], v[54:55], v[40:41]
	v_pk_fma_f32 v[20:21], v[104:105], v[20:21], v[42:43] neg_lo:[0,0,1] neg_hi:[0,0,1]
	v_mov_b32_e32 v71, v109
	v_pk_add_f32 v[42:43], v[20:21], v[40:41] op_sel:[0,1] op_sel_hi:[1,0] neg_lo:[0,1]
	v_pk_add_f32 v[54:55], v[20:21], v[40:41] op_sel:[0,1] op_sel_hi:[1,0]
	v_pk_add_f32 v[20:21], v[40:41], v[20:21] op_sel:[1,0] op_sel_hi:[0,1] neg_lo:[0,1] neg_hi:[0,1]
	v_pk_mul_f32 v[42:43], v[42:43], 0.5 op_sel_hi:[1,0]
	v_mov_b32_e32 v55, v21
	v_mul_f32_e32 v4, v109, v42
	v_pk_fma_f32 v[104:105], v[44:45], v[42:43], v[4:5] op_sel_hi:[1,1,0] neg_lo:[1,0,0] neg_hi:[1,0,0]
	v_mul_f32_e32 v4, v109, v43
	v_pk_fma_f32 v[42:43], v[70:71], v[42:43], v[4:5] op_sel_hi:[1,1,0]
	v_sub_f32_e32 v6, v23, v103
	v_mov_b32_e32 v104, v42
	v_pk_fma_f32 v[40:41], v[54:55], 0.5, v[42:43] op_sel_hi:[1,0,1] neg_lo:[0,0,1] neg_hi:[0,0,1]
	v_pk_fma_f32 v[20:21], v[54:55], 0.5, v[104:105] op_sel_hi:[1,0,1]
	v_pk_add_f32 v[42:43], v[102:103], v[22:23]
	v_mov_b32_e32 v41, v21
	v_pk_mul_f32 v[128:129], v[40:41], s[46:47] op_sel_hi:[1,0]
	v_mul_f32_e32 v40, 0xbf0e39da, v83
	v_mov_b32_e32 v41, v22
	v_mul_f32_e32 v18, 0.5, v43
	v_pk_add_f32 v[22:23], v[40:41], v[46:47] neg_lo:[0,1] neg_hi:[0,1]
	v_mov_b32_e32 v47, v109
	v_pk_mul_f32 v[40:41], v[22:23], v[18:19]
	v_mov_b32_e32 v46, v22
	v_pk_fma_f32 v[44:45], v[44:45], v[40:41], v[40:41] op_sel:[0,1,0] op_sel_hi:[1,0,1]
	v_mov_b32_e32 v40, v41
	v_mov_b32_e32 v41, v18
	v_mul_f32_e32 v4, 0.5, v42
	v_pk_mul_f32 v[40:41], v[46:47], v[40:41]
	v_cvt_f32_f16_e32 v46, v10
	v_cvt_f32_f16_e32 v47, v11
	v_cvt_f32_f16_sdwa v11, v11 dst_sel:DWORD dst_unused:UNUSED_PAD src0_sel:WORD_1
	v_cvt_f32_f16_sdwa v10, v10 dst_sel:DWORD dst_unused:UNUSED_PAD src0_sel:WORD_1
	v_pk_fma_f32 v[70:71], v[54:55], 0.5, v[104:105] op_sel_hi:[1,0,1] neg_lo:[1,0,0] neg_hi:[1,0,0]
	v_mul_f32_e32 v6, 0.5, v6
	v_pk_add_f32 v[54:55], v[4:5], v[44:45]
	v_pk_add_f32 v[40:41], v[40:41], v[40:41] op_sel:[0,1] op_sel_hi:[0,1] neg_lo:[0,1] neg_hi:[0,1]
	v_fma_f32 v55, v42, 0.5, -v44
	v_pk_add_f32 v[42:43], v[6:7], v[40:41] op_sel_hi:[0,1] neg_hi:[0,1]
	v_pk_mul_f32 v[40:41], v[42:43], v[10:11]
	v_pk_mul_f32 v[42:43], v[42:43], v[46:47]
	v_pk_fma_f32 v[44:45], v[54:55], v[46:47], v[40:41] neg_lo:[0,0,1] neg_hi:[0,0,1]
	v_pk_fma_f32 v[40:41], v[54:55], v[46:47], v[40:41]
	v_pk_fma_f32 v[46:47], v[54:55], v[10:11], v[42:43]
	v_pk_fma_f32 v[10:11], v[54:55], v[10:11], v[42:43] neg_lo:[0,0,1] neg_hi:[0,0,1]
	v_pk_add_f32 v[42:43], v[44:45], v[40:41] op_sel:[0,1] op_sel_hi:[1,0]
	v_pk_add_f32 v[54:55], v[46:47], v[10:11] op_sel_hi:[0,1] neg_lo:[0,1] neg_hi:[0,1]
	v_pk_add_f32 v[40:41], v[44:45], v[40:41] op_sel_hi:[0,1] neg_lo:[0,1] neg_hi:[0,1]
	v_pk_add_f32 v[10:11], v[46:47], v[10:11] op_sel:[0,1] op_sel_hi:[1,0]
	v_mov_b32_e32 v43, v55
	v_mov_b32_e32 v11, v41
	v_pk_mul_f32 v[10:11], v[10:11], 0.5 op_sel_hi:[1,0]
	v_mov_b32_e32 v119, v98
	v_pk_mul_f32 v[40:41], v[108:109], v[10:11] op_sel:[1,1] op_sel_hi:[1,0]
	v_pk_fma_f32 v[76:77], v[76:77], 0.5, v[112:113] op_sel_hi:[1,0,1] neg_lo:[1,0,0] neg_hi:[1,0,0]
	v_pk_fma_f32 v[44:45], v[22:23], v[10:11], v[40:41] op_sel_hi:[0,1,1]
	v_pk_fma_f32 v[10:11], v[22:23], v[10:11], v[40:41] op_sel_hi:[0,1,1] neg_hi:[0,0,1]
	v_pk_fma_f32 v[22:23], v[42:43], 0.5, v[44:45] op_sel_hi:[1,0,1] neg_lo:[0,0,1] neg_hi:[0,0,1]
	v_pk_fma_f32 v[40:41], v[42:43], 0.5, v[10:11] op_sel_hi:[1,0,1]
	v_pk_fma_f32 v[54:55], v[42:43], 0.5, v[10:11] op_sel_hi:[1,0,1] neg_lo:[1,0,0] neg_hi:[1,0,0]
	v_pk_add_f32 v[10:11], v[100:101], v[14:15]
	v_pk_add_f32 v[14:15], v[14:15], v[100:101] neg_lo:[0,1] neg_hi:[0,1]
	v_mov_b32_e32 v23, v41
	v_mul_f32_e32 v6, 0.5, v15
	v_mov_b32_e32 v15, v11
	v_pk_mul_f32 v[150:151], v[22:23], s[46:47] op_sel_hi:[1,0]
	v_mul_f32_e32 v4, 0.5, v10
	v_pk_mov_b32 v[22:23], v[58:59], v[72:73] op_sel:[1,0]
	v_pk_mul_f32 v[10:11], v[14:15], s[44:45]
	v_cvt_f32_f16_sdwa v42, v8 dst_sel:DWORD dst_unused:UNUSED_PAD src0_sel:WORD_1
	v_pk_mul_f32 v[14:15], v[22:23], v[10:11] op_sel:[0,1] op_sel_hi:[1,0]
	v_cvt_f32_f16_e32 v43, v9
	v_cvt_f32_f16_sdwa v9, v9 dst_sel:DWORD dst_unused:UNUSED_PAD src0_sel:WORD_1
	v_cvt_f32_f16_e32 v8, v8
	v_pk_mul_f32 v[10:11], v[22:23], v[10:11]
	v_pk_add_f32 v[14:15], v[14:15], v[14:15] op_sel:[0,1] op_sel_hi:[0,1]
	v_pk_add_f32 v[44:45], v[4:5], v[14:15] op_sel_hi:[0,1] neg_hi:[0,1]
	s_nop 0
	v_pk_add_f32 v[10:11], v[10:11], v[10:11] op_sel:[0,1] op_sel_hi:[0,1] neg_lo:[0,1] neg_hi:[0,1]
	v_pk_add_f32 v[14:15], v[6:7], v[10:11] op_sel_hi:[0,1] neg_hi:[0,1]
	v_pk_mul_f32 v[10:11], v[14:15], v[8:9]
	v_pk_mul_f32 v[14:15], v[14:15], v[42:43]
	v_pk_fma_f32 v[10:11], v[44:45], v[42:43], v[10:11]
	v_pk_fma_f32 v[8:9], v[44:45], v[8:9], v[14:15] neg_lo:[0,0,1] neg_hi:[0,0,1]
	v_mov_b32_e32 v73, v59
	v_pk_add_f32 v[14:15], v[8:9], v[10:11] op_sel:[0,1] op_sel_hi:[1,0] neg_lo:[0,1]
	v_pk_add_f32 v[42:43], v[8:9], v[10:11] op_sel:[0,1] op_sel_hi:[1,0]
	v_pk_add_f32 v[8:9], v[10:11], v[8:9] op_sel:[1,0] op_sel_hi:[0,1] neg_lo:[0,1] neg_hi:[0,1]
	v_pk_mul_f32 v[14:15], v[14:15], 0.5 op_sel_hi:[1,0]
	v_mov_b32_e32 v43, v9
	v_mul_f32_e32 v4, v59, v14
	v_pk_fma_f32 v[44:45], v[22:23], v[14:15], v[4:5] op_sel_hi:[1,1,0] neg_lo:[1,0,0] neg_hi:[1,0,0]
	v_mul_f32_e32 v4, v59, v15
	v_pk_fma_f32 v[14:15], v[72:73], v[14:15], v[4:5] op_sel_hi:[1,1,0]
	v_sub_f32_e32 v6, v37, v99
	v_mov_b32_e32 v44, v14
	v_pk_fma_f32 v[8:9], v[42:43], 0.5, v[14:15] op_sel_hi:[1,0,1] neg_lo:[0,0,1] neg_hi:[0,0,1]
	v_pk_fma_f32 v[10:11], v[42:43], 0.5, v[44:45] op_sel_hi:[1,0,1]
	v_pk_add_f32 v[14:15], v[98:99], v[36:37]
	v_mov_b32_e32 v9, v11
	v_pk_mul_f32 v[168:169], v[8:9], s[46:47] op_sel_hi:[1,0]
	v_mul_f32_e32 v8, 0xbf7b14be, v83
	v_mov_b32_e32 v9, v36
	v_mul_f32_e32 v18, 0.5, v15
	v_pk_add_f32 v[8:9], v[8:9], v[118:119] neg_lo:[0,1] neg_hi:[0,1]
	v_pk_fma_f32 v[72:73], v[42:43], 0.5, v[44:45] op_sel_hi:[1,0,1] neg_lo:[1,0,0] neg_hi:[1,0,0]
	v_pk_mul_f32 v[36:37], v[8:9], v[18:19]
	v_mov_b32_e32 v42, v8
	v_pk_fma_f32 v[22:23], v[22:23], v[36:37], v[36:37] op_sel:[0,1,0] op_sel_hi:[1,0,1]
	v_mov_b32_e32 v43, v59
	v_mov_b32_e32 v36, v37
	v_mov_b32_e32 v37, v18
	v_mul_f32_e32 v4, 0.5, v14
	v_pk_mul_f32 v[36:37], v[42:43], v[36:37]
	v_cvt_f32_f16_e32 v44, v2
	v_cvt_f32_f16_e32 v45, v3
	v_cvt_f32_f16_sdwa v3, v3 dst_sel:DWORD dst_unused:UNUSED_PAD src0_sel:WORD_1
	v_cvt_f32_f16_sdwa v2, v2 dst_sel:DWORD dst_unused:UNUSED_PAD src0_sel:WORD_1
	v_mul_f32_e32 v6, 0.5, v6
	v_pk_add_f32 v[46:47], v[4:5], v[22:23]
	v_fma_f32 v4, v14, 0.5, -v22
	v_pk_add_f32 v[22:23], v[36:37], v[36:37] op_sel:[0,1] op_sel_hi:[0,1] neg_lo:[0,1] neg_hi:[0,1]
	v_pk_add_f32 v[36:37], v[6:7], v[22:23] op_sel_hi:[0,1] neg_hi:[0,1]
	v_mov_b32_e32 v14, v46
	v_mov_b32_e32 v15, v4
	v_pk_mul_f32 v[22:23], v[4:5], v[44:45] op_sel_hi:[0,1]
	v_pk_mul_f32 v[82:83], v[36:37], v[2:3]
	v_pk_mul_f32 v[46:47], v[46:47], v[2:3]
	v_pk_mul_f32 v[36:37], v[36:37], v[44:45]
	v_pk_fma_f32 v[98:99], v[14:15], v[44:45], v[82:83] neg_lo:[0,0,1] neg_hi:[0,0,1]
	v_pk_fma_f32 v[2:3], v[14:15], v[2:3], v[36:37] neg_lo:[0,0,1] neg_hi:[0,0,1]
	v_add_f32_e32 v4, v23, v83
	v_add_f32_e32 v6, v46, v36
	v_pk_add_f32 v[22:23], v[6:7], v[2:3] op_sel_hi:[0,1] neg_lo:[0,1] neg_hi:[0,1]
	v_pk_add_f32 v[36:37], v[98:99], v[4:5] op_sel_hi:[1,0] neg_lo:[0,1] neg_hi:[0,1]
	v_pk_add_f32 v[2:3], v[6:7], v[2:3] op_sel_hi:[0,1]
	v_mov_b32_e32 v37, v3
	v_pk_mul_f32 v[2:3], v[36:37], 0.5 op_sel_hi:[1,0]
	v_pk_add_f32 v[14:15], v[98:99], v[4:5] op_sel_hi:[1,0]
	v_mul_f32_e32 v4, v59, v3
	v_pk_fma_f32 v[36:37], v[42:43], v[2:3], v[4:5] op_sel_hi:[1,1,0] neg_lo:[0,0,1] neg_hi:[0,0,1]
	v_pk_mov_b32 v[42:43], v[58:59], v[8:9] op_sel:[1,0]
	v_mul_f32_e32 v4, v8, v3
	v_pk_fma_f32 v[2:3], v[42:43], v[2:3], v[4:5] op_sel_hi:[1,1,0]
	v_mov_b32_e32 v15, v23
	v_pk_fma_f32 v[8:9], v[14:15], 0.5, v[2:3] op_sel_hi:[1,0,1] neg_lo:[0,0,1] neg_hi:[0,0,1]
	v_pk_fma_f32 v[42:43], v[14:15], 0.5, v[36:37] op_sel_hi:[1,0,0]
	v_pk_fma_f32 v[2:3], v[14:15], 0.5, v[2:3] op_sel_hi:[1,0,1]
	v_mov_b32_e32 v9, v43
	v_pk_fma_f32 v[58:59], v[22:23], 0.5, v[36:37] op_sel_hi:[1,0,0] neg_lo:[1,0,0] neg_hi:[1,0,0]
	v_pk_mul_f32 v[144:145], v[8:9], s[46:47] op_sel_hi:[1,0]
	v_mov_b32_e32 v58, v2
	v_mov_b32_e32 v72, v10
	v_mov_b32_e32 v54, v40
	v_mov_b32_e32 v70, v20
	v_mov_b32_e32 v56, v26
	v_mov_b32_e32 v76, v38
	v_mov_b32_e32 v52, v34
	v_mov_b32_e32 v74, v86
	v_mov_b32_e32 v48, v84
	v_mov_b32_e32 v50, v60
	v_mov_b32_e32 v28, v66
	v_mov_b32_e32 v32, v96
	v_mov_b32_e32 v12, v88
	v_mov_b32_e32 v16, v92
	v_mov_b32_e32 v4, v138
	v_mov_b32_e32 v6, v122

.LBB0_538:
	s_or_b64 exec, exec, s[0:1]
	v_pk_mul_f32 v[22:23], v[32:33], s[46:47] op_sel_hi:[1,0]
	v_pk_add_f32 v[26:27], v[24:25], v[30:31]
	v_pk_add_f32 v[24:25], v[24:25], v[30:31] neg_lo:[0,1] neg_hi:[0,1]
	v_pk_add_f32 v[30:31], v[64:65], v[68:69]
	v_pk_add_f32 v[32:33], v[64:65], v[68:69] neg_lo:[0,1] neg_hi:[0,1]
	v_pk_add_f32 v[34:35], v[62:63], v[90:91]
	v_pk_add_f32 v[38:39], v[94:95], v[80:81]
	v_pk_add_f32 v[68:69], v[26:27], v[30:31]
	v_pk_add_f32 v[26:27], v[26:27], v[30:31] neg_lo:[0,1] neg_hi:[0,1]
	v_pk_mul_f32 v[30:31], v[32:33], 1.0 op_sel:[1,0] op_sel_hi:[0,0] neg_lo:[1,0]
	v_pk_mul_f32 v[20:21], v[50:51], s[46:47] op_sel_hi:[1,0]
	v_pk_add_f32 v[36:37], v[62:63], v[90:91] neg_lo:[0,1] neg_hi:[0,1]
	v_pk_add_f32 v[42:43], v[78:79], v[136:137]
	v_pk_add_f32 v[46:47], v[130:131], v[120:121]
	v_pk_add_f32 v[32:33], v[24:25], v[30:31]
	v_pk_add_f32 v[24:25], v[24:25], v[30:31] neg_lo:[0,1] neg_hi:[0,1]
	v_pk_add_f32 v[30:31], v[34:35], v[38:39]
	v_pk_add_f32 v[34:35], v[34:35], v[38:39] neg_lo:[0,1] neg_hi:[0,1]
	v_pk_add_f32 v[38:39], v[94:95], v[80:81] neg_lo:[0,1] neg_hi:[0,1]
	v_pk_add_f32 v[44:45], v[78:79], v[136:137] neg_lo:[0,1] neg_hi:[0,1]
	v_pk_add_f32 v[60:61], v[128:129], v[150:151]
	v_pk_add_f32 v[64:65], v[168:169], v[144:145]
	v_pk_add_f32 v[40:41], v[36:37], v[38:39] op_sel:[0,1] op_sel_hi:[1,0] neg_lo:[0,1]
	v_pk_add_f32 v[36:37], v[36:37], v[38:39] op_sel:[0,1] op_sel_hi:[1,0] neg_hi:[0,1]
	v_pk_add_f32 v[38:39], v[42:43], v[46:47]
	v_pk_add_f32 v[42:43], v[42:43], v[46:47] neg_lo:[0,1] neg_hi:[0,1]
	v_pk_add_f32 v[46:47], v[130:131], v[120:121] neg_lo:[0,1] neg_hi:[0,1]
	v_pk_add_f32 v[62:63], v[128:129], v[150:151] neg_lo:[0,1] neg_hi:[0,1]
	v_pk_add_f32 v[50:51], v[44:45], v[46:47] op_sel:[0,1] op_sel_hi:[1,0] neg_lo:[0,1]
	v_pk_add_f32 v[44:45], v[44:45], v[46:47] op_sel:[0,1] op_sel_hi:[1,0] neg_hi:[0,1]
	v_pk_add_f32 v[46:47], v[60:61], v[64:65]
	v_pk_add_f32 v[60:61], v[60:61], v[64:65] neg_lo:[0,1] neg_hi:[0,1]
	v_pk_add_f32 v[64:65], v[168:169], v[144:145] neg_lo:[0,1] neg_hi:[0,1]
	s_mov_b32 s66, s37
	s_mov_b32 s67, s36
	v_pk_add_f32 v[66:67], v[62:63], v[64:65] op_sel:[0,1] op_sel_hi:[1,0] neg_lo:[0,1]
	v_pk_add_f32 v[62:63], v[62:63], v[64:65] op_sel:[0,1] op_sel_hi:[1,0] neg_hi:[0,1]
	v_pk_add_f32 v[64:65], v[68:69], v[30:31]
	v_pk_add_f32 v[30:31], v[68:69], v[30:31] neg_lo:[0,1] neg_hi:[0,1]
	s_mov_b32 s0, s37
	v_pk_mul_f32 v[68:69], v[40:41], s[66:67]
	s_mov_b32 s68, s19
	v_pk_fma_f32 v[40:41], v[40:41], s[0:1], v[68:69] op_sel:[0,0,1] op_sel_hi:[1,0,0]
	s_mov_b32 s69, s18
	v_pk_add_f32 v[68:69], v[32:33], v[40:41]
	v_pk_add_f32 v[32:33], v[32:33], v[40:41] neg_lo:[0,1] neg_hi:[0,1]
	v_pk_mul_f32 v[40:41], v[34:35], 1.0 op_sel:[1,0] op_sel_hi:[0,0] neg_lo:[1,0]
	s_nop 0
	v_pk_add_f32 v[34:35], v[26:27], v[40:41]
	v_pk_add_f32 v[26:27], v[26:27], v[40:41] neg_lo:[0,1] neg_hi:[0,1]
	v_pk_mul_f32 v[40:41], v[36:37], s[66:67]
	s_mov_b32 s72, s19
	v_pk_fma_f32 v[36:37], v[36:37], s[0:1], v[40:41] op_sel:[0,0,1] op_sel_hi:[1,0,0] neg_lo:[1,0,0] neg_hi:[1,0,0]
	v_pk_mul_f32 v[2:3], v[72:73], s[46:47] op_sel_hi:[1,0]
	v_pk_add_f32 v[40:41], v[24:25], v[36:37]
	v_pk_add_f32 v[24:25], v[24:25], v[36:37] neg_lo:[0,1] neg_hi:[0,1]
	v_pk_add_f32 v[36:37], v[38:39], v[46:47]
	v_pk_add_f32 v[38:39], v[38:39], v[46:47] neg_lo:[0,1] neg_hi:[0,1]
	v_pk_mul_f32 v[46:47], v[66:67], s[66:67]
	v_pk_mul_f32 v[8:9], v[70:71], s[46:47] op_sel_hi:[1,0]
	v_pk_fma_f32 v[46:47], v[66:67], s[0:1], v[46:47] op_sel:[0,0,1] op_sel_hi:[1,0,0]
	v_pk_mul_f32 v[10:11], v[76:77], s[46:47] op_sel_hi:[1,0]
	v_pk_add_f32 v[66:67], v[50:51], v[46:47]
	v_pk_add_f32 v[46:47], v[50:51], v[46:47] neg_lo:[0,1] neg_hi:[0,1]
	v_pk_mul_f32 v[50:51], v[60:61], 1.0 op_sel:[1,0] op_sel_hi:[0,0] neg_lo:[1,0]
	v_pk_add_f32 v[60:61], v[42:43], v[50:51]
	v_pk_add_f32 v[42:43], v[42:43], v[50:51] neg_lo:[0,1] neg_hi:[0,1]
	v_pk_mul_f32 v[50:51], v[62:63], s[66:67]
	v_pk_mul_f32 v[14:15], v[74:75], s[46:47] op_sel_hi:[1,0]
	v_pk_fma_f32 v[50:51], v[62:63], s[0:1], v[50:51] op_sel:[0,0,1] op_sel_hi:[1,0,0] neg_lo:[1,0,0] neg_hi:[1,0,0]
	v_pk_mul_f32 v[16:17], v[16:17], s[46:47] op_sel_hi:[1,0]
	v_pk_add_f32 v[62:63], v[44:45], v[50:51]
	v_pk_add_f32 v[44:45], v[44:45], v[50:51] neg_lo:[0,1] neg_hi:[0,1]
	v_pk_add_f32 v[50:51], v[64:65], v[36:37]
	v_pk_add_f32 v[36:37], v[64:65], v[36:37] neg_lo:[0,1] neg_hi:[0,1]
	v_pk_mul_f32 v[64:65], v[66:67], s[68:69]
	v_pk_mul_f32 v[6:7], v[6:7], s[46:47] op_sel_hi:[1,0]
	v_pk_fma_f32 v[64:65], v[66:67], s[16:17], v[64:65] op_sel:[0,0,1] op_sel_hi:[1,0,0]
	s_mov_b32 s17, s40
	v_pk_add_f32 v[66:67], v[68:69], v[64:65]
	v_pk_add_f32 v[64:65], v[68:69], v[64:65] neg_lo:[0,1] neg_hi:[0,1]
	v_pk_mul_f32 v[68:69], v[60:61], s[66:67]
	s_ashr_i32 s63, s62, 31
	v_pk_fma_f32 v[60:61], s[0:1], v[60:61], v[68:69] op_sel:[0,0,1] op_sel_hi:[0,1,0]
	v_pk_add_f32 v[68:69], v[34:35], v[60:61]
	v_pk_add_f32 v[34:35], v[34:35], v[60:61] neg_lo:[0,1] neg_hi:[0,1]
	v_pk_mul_f32 v[60:61], v[62:63], s[16:17]
	s_nop 0
	v_pk_fma_f32 v[60:61], s[72:73], v[62:63], v[60:61] op_sel:[0,0,1] op_sel_hi:[0,1,0]
	v_pk_add_f32 v[62:63], v[40:41], v[60:61]
	v_pk_add_f32 v[40:41], v[40:41], v[60:61] neg_lo:[0,1] neg_hi:[0,1]
	v_pk_mul_f32 v[60:61], v[38:39], 1.0 op_sel:[1,0] op_sel_hi:[0,0] neg_lo:[1,0]
	v_pk_add_f32 v[38:39], v[30:31], v[60:61]
	v_pk_add_f32 v[30:31], v[30:31], v[60:61] neg_lo:[0,1] neg_hi:[0,1]
	v_pk_mul_f32 v[60:61], v[46:47], s[16:17]
	s_nop 0
	v_pk_fma_f32 v[46:47], s[72:73], v[46:47], v[60:61] op_sel:[0,0,1] op_sel_hi:[0,1,0] neg_lo:[0,1,0] neg_hi:[0,1,0]
	v_pk_add_f32 v[60:61], v[32:33], v[46:47]
	v_pk_add_f32 v[32:33], v[32:33], v[46:47] neg_lo:[0,1] neg_hi:[0,1]
	v_pk_mul_f32 v[46:47], v[42:43], s[66:67]
	s_nop 0
	v_pk_fma_f32 v[42:43], s[0:1], v[42:43], v[46:47] op_sel:[0,0,1] op_sel_hi:[0,1,0] neg_lo:[0,1,0] neg_hi:[0,1,0]
	v_pk_add_f32 v[46:47], v[26:27], v[42:43]
	v_pk_add_f32 v[26:27], v[26:27], v[42:43] neg_lo:[0,1] neg_hi:[0,1]
	v_pk_mul_f32 v[42:43], v[44:45], s[68:69]
	s_nop 0
	v_pk_fma_f32 v[42:43], s[16:17], v[44:45], v[42:43] op_sel:[0,0,1] op_sel_hi:[0,1,0] neg_lo:[0,1,0] neg_hi:[0,1,0]
	v_pk_add_f32 v[44:45], v[24:25], v[42:43]
	v_pk_add_f32 v[24:25], v[24:25], v[42:43] neg_lo:[0,1] neg_hi:[0,1]
	v_pk_fma_f32 v[42:43], v[58:59], s[46:47], v[2:3] op_sel_hi:[1,0,1]
	v_pk_fma_f32 v[2:3], v[58:59], s[46:47], v[2:3] op_sel_hi:[1,0,1] neg_lo:[0,0,1] neg_hi:[0,0,1]
	v_pk_fma_f32 v[58:59], v[54:55], s[46:47], v[8:9] op_sel_hi:[1,0,1]
	v_pk_fma_f32 v[8:9], v[54:55], s[46:47], v[8:9] op_sel_hi:[1,0,1] neg_lo:[0,0,1] neg_hi:[0,0,1]
	v_pk_fma_f32 v[54:55], v[56:57], s[46:47], v[10:11] op_sel_hi:[1,0,1]
	v_pk_fma_f32 v[10:11], v[56:57], s[46:47], v[10:11] op_sel_hi:[1,0,1] neg_lo:[0,0,1] neg_hi:[0,0,1]
	v_pk_fma_f32 v[56:57], v[52:53], s[46:47], v[14:15] op_sel_hi:[1,0,1]
	v_pk_fma_f32 v[14:15], v[52:53], s[46:47], v[14:15] op_sel_hi:[1,0,1] neg_lo:[0,0,1] neg_hi:[0,0,1]
	v_pk_fma_f32 v[52:53], v[48:49], s[46:47], v[20:21] op_sel_hi:[1,0,1]
	v_pk_fma_f32 v[20:21], v[48:49], s[46:47], v[20:21] op_sel_hi:[1,0,1] neg_lo:[0,0,1] neg_hi:[0,0,1]
	v_pk_fma_f32 v[48:49], v[28:29], s[46:47], v[22:23] op_sel_hi:[1,0,1]
	v_pk_fma_f32 v[22:23], v[28:29], s[46:47], v[22:23] op_sel_hi:[1,0,1] neg_lo:[0,0,1] neg_hi:[0,0,1]
	v_pk_fma_f32 v[28:29], v[12:13], s[46:47], v[16:17] op_sel_hi:[1,0,1]
	v_pk_fma_f32 v[12:13], v[12:13], s[46:47], v[16:17] op_sel_hi:[1,0,1] neg_lo:[0,0,1] neg_hi:[0,0,1]
	v_pk_fma_f32 v[16:17], v[4:5], s[46:47], v[6:7] op_sel_hi:[1,0,1]
	v_pk_fma_f32 v[4:5], v[4:5], s[46:47], v[6:7] op_sel_hi:[1,0,1] neg_lo:[0,0,1] neg_hi:[0,0,1]
	v_pk_add_f32 v[6:7], v[58:59], v[42:43]
	v_pk_add_f32 v[42:43], v[42:43], v[58:59] neg_lo:[0,1] neg_hi:[0,1]
	v_pk_mul_f32 v[58:59], v[8:9], 1.0 op_sel:[1,0] op_sel_hi:[0,0] neg_lo:[1,0]
	v_pk_add_f32 v[8:9], v[2:3], v[58:59]
	v_pk_add_f32 v[2:3], v[2:3], v[58:59] neg_lo:[0,1] neg_hi:[0,1]
	v_pk_add_f32 v[58:59], v[56:57], v[54:55]
	v_pk_add_f32 v[54:55], v[54:55], v[56:57] neg_lo:[0,1] neg_hi:[0,1]
	v_pk_mul_f32 v[56:57], v[14:15], 1.0 op_sel:[1,0] op_sel_hi:[0,0] neg_lo:[1,0]
	v_pk_add_f32 v[14:15], v[10:11], v[56:57]
	v_pk_add_f32 v[10:11], v[10:11], v[56:57] neg_lo:[0,1] neg_hi:[0,1]
	v_pk_add_f32 v[56:57], v[48:49], v[52:53]
	v_pk_add_f32 v[48:49], v[52:53], v[48:49] neg_lo:[0,1] neg_hi:[0,1]
	v_pk_mul_f32 v[52:53], v[22:23], 1.0 op_sel:[1,0] op_sel_hi:[0,0] neg_lo:[1,0]
	v_pk_add_f32 v[22:23], v[20:21], v[52:53]
	v_pk_add_f32 v[20:21], v[20:21], v[52:53] neg_lo:[0,1] neg_hi:[0,1]
	v_pk_add_f32 v[52:53], v[16:17], v[28:29]
	v_pk_add_f32 v[16:17], v[28:29], v[16:17] neg_lo:[0,1] neg_hi:[0,1]
	v_pk_mul_f32 v[28:29], v[4:5], 1.0 op_sel:[1,0] op_sel_hi:[0,0] neg_lo:[1,0]
	v_pk_add_f32 v[4:5], v[12:13], v[28:29]
	v_pk_add_f32 v[12:13], v[12:13], v[28:29] neg_lo:[0,1] neg_hi:[0,1]
	v_pk_add_f32 v[28:29], v[58:59], v[6:7]
	v_pk_add_f32 v[6:7], v[6:7], v[58:59] neg_lo:[0,1] neg_hi:[0,1]
	v_pk_mul_f32 v[58:59], v[14:15], s[66:67]
	s_nop 0
	v_pk_fma_f32 v[14:15], s[0:1], v[14:15], v[58:59] op_sel:[0,0,1] op_sel_hi:[0,1,0]
	v_pk_add_f32 v[58:59], v[14:15], v[8:9]
	v_pk_add_f32 v[8:9], v[8:9], v[14:15] neg_lo:[0,1] neg_hi:[0,1]
	v_pk_mul_f32 v[14:15], v[54:55], 1.0 op_sel:[1,0] op_sel_hi:[0,0] neg_lo:[1,0]
	v_pk_add_f32 v[54:55], v[14:15], v[42:43]
	v_pk_add_f32 v[14:15], v[42:43], v[14:15] neg_lo:[0,1] neg_hi:[0,1]
	v_pk_mul_f32 v[42:43], v[10:11], s[66:67]
	s_nop 0
	v_pk_fma_f32 v[10:11], s[0:1], v[10:11], v[42:43] op_sel:[0,0,1] op_sel_hi:[0,1,0] neg_lo:[0,1,0] neg_hi:[0,1,0]
	v_pk_add_f32 v[42:43], v[10:11], v[2:3]
	v_pk_add_f32 v[2:3], v[2:3], v[10:11] neg_lo:[0,1] neg_hi:[0,1]
	v_pk_add_f32 v[10:11], v[52:53], v[56:57]
	v_pk_add_f32 v[52:53], v[56:57], v[52:53] neg_lo:[0,1] neg_hi:[0,1]
	v_pk_mul_f32 v[56:57], v[4:5], s[66:67]
	s_nop 0
	v_pk_fma_f32 v[4:5], s[0:1], v[4:5], v[56:57] op_sel:[0,0,1] op_sel_hi:[0,1,0]
	v_pk_add_f32 v[56:57], v[4:5], v[22:23]
	v_pk_add_f32 v[4:5], v[22:23], v[4:5] neg_lo:[0,1] neg_hi:[0,1]
	v_pk_mul_f32 v[22:23], v[16:17], 1.0 op_sel:[1,0] op_sel_hi:[0,0] neg_lo:[1,0]
	v_pk_add_f32 v[16:17], v[22:23], v[48:49]
	v_pk_add_f32 v[22:23], v[48:49], v[22:23] neg_lo:[0,1] neg_hi:[0,1]
	v_pk_mul_f32 v[48:49], v[12:13], s[66:67]
	s_nop 0
	v_pk_fma_f32 v[12:13], s[0:1], v[12:13], v[48:49] op_sel:[0,0,1] op_sel_hi:[0,1,0] neg_lo:[0,1,0] neg_hi:[0,1,0]
	v_pk_add_f32 v[48:49], v[12:13], v[20:21]
	v_pk_add_f32 v[12:13], v[20:21], v[12:13] neg_lo:[0,1] neg_hi:[0,1]
	v_pk_add_f32 v[20:21], v[10:11], v[28:29]
	v_pk_add_f32 v[10:11], v[28:29], v[10:11] neg_lo:[0,1] neg_hi:[0,1]
	v_pk_mul_f32 v[28:29], v[56:57], s[68:69]
	s_nop 0
	v_pk_fma_f32 v[28:29], s[16:17], v[56:57], v[28:29] op_sel:[0,0,1] op_sel_hi:[0,1,0]
	v_pk_add_f32 v[56:57], v[28:29], v[58:59]
	v_pk_add_f32 v[28:29], v[58:59], v[28:29] neg_lo:[0,1] neg_hi:[0,1]
	v_pk_mul_f32 v[58:59], v[16:17], s[66:67]
	s_nop 0
	v_pk_fma_f32 v[16:17], s[0:1], v[16:17], v[58:59] op_sel:[0,0,1] op_sel_hi:[0,1,0]
	v_pk_add_f32 v[58:59], v[16:17], v[54:55]
	v_pk_add_f32 v[16:17], v[54:55], v[16:17] neg_lo:[0,1] neg_hi:[0,1]
	v_pk_mul_f32 v[54:55], v[48:49], s[16:17]
	s_nop 0
	v_pk_fma_f32 v[48:49], s[72:73], v[48:49], v[54:55] op_sel:[0,0,1] op_sel_hi:[0,1,0]
	v_pk_add_f32 v[54:55], v[48:49], v[42:43]
	v_pk_add_f32 v[42:43], v[42:43], v[48:49] neg_lo:[0,1] neg_hi:[0,1]
	v_pk_mul_f32 v[48:49], v[52:53], 1.0 op_sel:[1,0] op_sel_hi:[0,0] neg_lo:[1,0]
	v_pk_add_f32 v[52:53], v[48:49], v[6:7]
	v_pk_add_f32 v[6:7], v[6:7], v[48:49] neg_lo:[0,1] neg_hi:[0,1]
	v_pk_mul_f32 v[48:49], v[4:5], s[16:17]
	s_nop 0
	v_pk_fma_f32 v[4:5], s[72:73], v[4:5], v[48:49] op_sel:[0,0,1] op_sel_hi:[0,1,0] neg_lo:[0,1,0] neg_hi:[0,1,0]
	v_pk_add_f32 v[48:49], v[4:5], v[8:9]
	v_pk_add_f32 v[4:5], v[8:9], v[4:5] neg_lo:[0,1] neg_hi:[0,1]
	v_pk_mul_f32 v[8:9], v[22:23], s[66:67]
	s_nop 0
	v_pk_fma_f32 v[8:9], s[0:1], v[22:23], v[8:9] op_sel:[0,0,1] op_sel_hi:[0,1,0] neg_lo:[0,1,0] neg_hi:[0,1,0]
	v_pk_add_f32 v[22:23], v[8:9], v[14:15]
	v_pk_add_f32 v[8:9], v[14:15], v[8:9] neg_lo:[0,1] neg_hi:[0,1]
	v_pk_mul_f32 v[14:15], v[12:13], s[68:69]
	s_nop 0
	v_pk_fma_f32 v[12:13], s[16:17], v[12:13], v[14:15] op_sel:[0,0,1] op_sel_hi:[0,1,0] neg_lo:[0,1,0] neg_hi:[0,1,0]
	v_pk_add_f32 v[14:15], v[12:13], v[2:3]
	v_pk_add_f32 v[2:3], v[2:3], v[12:13] neg_lo:[0,1] neg_hi:[0,1]
	ds_write_b64 v211, v[50:51]
	ds_write_b64 v212, v[20:21]
	ds_write_b64 v211, v[66:67] offset:8
	ds_write_b64 v212, v[56:57] offset:8
	ds_write_b64 v211, v[68:69] offset:16
	ds_write_b64 v212, v[58:59] offset:16
	ds_write_b64 v211, v[62:63] offset:24
	ds_write_b64 v212, v[54:55] offset:24
	ds_write_b64 v211, v[38:39] offset:32
	ds_write_b64 v212, v[52:53] offset:32
	ds_write_b64 v211, v[60:61] offset:40
	ds_write_b64 v212, v[48:49] offset:40
	ds_write_b64 v211, v[46:47] offset:48
	ds_write_b64 v212, v[22:23] offset:48
	ds_write_b64 v211, v[44:45] offset:56
	ds_write_b64 v212, v[14:15] offset:56
	ds_write_b64 v211, v[36:37] offset:64
	ds_write_b64 v212, v[10:11] offset:64
	ds_write_b64 v211, v[64:65] offset:72
	ds_write_b64 v212, v[28:29] offset:72
	ds_write_b64 v211, v[34:35] offset:80
	ds_write_b64 v212, v[16:17] offset:80
	ds_write_b64 v211, v[40:41] offset:88
	ds_write_b64 v212, v[42:43] offset:88
	ds_write_b64 v211, v[30:31] offset:96
	ds_write_b64 v212, v[6:7] offset:96
	ds_write_b64 v211, v[32:33] offset:104
	ds_write_b64 v212, v[4:5] offset:104
	ds_write_b64 v211, v[26:27] offset:112
	ds_write_b64 v212, v[8:9] offset:112
	ds_write_b64 v211, v[24:25] offset:120
	ds_write_b64 v212, v[2:3] offset:120
	v_mov_b32_e32 v2, v210
	s_waitcnt lgkmcnt(0)
	s_barrier
	s_nop 0
	v_and_b32_e32 v4, 15, v2
	v_cvt_f32_ubyte0_e32 v3, v4
	v_mul_f32_e32 v5, 0x3b800000, v3
	v_sin_f32_e32 v3, v5
	v_lshlrev_b32_e32 v6, 4, v2
	v_cos_f32_e32 v2, v5
	v_lshlrev_b32_e32 v7, 3, v4
	v_pk_mul_f32 v[16:17], v[2:3], 1.0 op_sel:[1,0] op_sel_hi:[1,0] neg_lo:[1,0]
	s_nop 0
	v_pk_mul_f32 v[4:5], v[2:3], v[16:17] op_sel:[1,0] op_sel_hi:[0,1]
	v_pk_fma_f32 v[40:41], v[2:3], v[2:3], v[4:5] op_sel_hi:[0,1,1]
	v_pk_mul_f32 v[4:5], v[16:17], v[40:41] op_sel:[0,1] op_sel_hi:[1,0]
	v_pk_mul_f32 v[44:45], v[40:41], 1.0 op_sel:[1,0] op_sel_hi:[1,0] neg_lo:[1,0]
	v_pk_fma_f32 v[42:43], v[2:3], v[40:41], v[4:5] op_sel_hi:[0,1,1]
	v_pk_mul_f32 v[4:5], v[40:41], v[44:45] op_sel:[1,0] op_sel_hi:[0,1]
	v_pk_fma_f32 v[46:47], v[40:41], v[40:41], v[4:5] op_sel_hi:[1,0,1]
	v_pk_mul_f32 v[50:51], v[42:43], 1.0 op_sel:[1,0] op_sel_hi:[1,0] neg_lo:[1,0]
	v_pk_mul_f32 v[4:5], v[46:47], v[16:17] op_sel:[1,0] op_sel_hi:[0,1]
	v_pk_fma_f32 v[52:53], v[2:3], v[46:47], v[4:5] op_sel_hi:[0,1,1]
	v_pk_mul_f32 v[4:5], v[44:45], v[46:47] op_sel:[0,1] op_sel_hi:[1,0]
	v_pk_mul_f32 v[48:49], v[46:47], 1.0 op_sel:[1,0] op_sel_hi:[1,0] neg_lo:[1,0]
	v_pk_fma_f32 v[56:57], v[40:41], v[46:47], v[4:5] op_sel_hi:[0,1,1]
	v_pk_mul_f32 v[4:5], v[46:47], v[50:51] op_sel:[1,0] op_sel_hi:[0,1]
	v_pk_fma_f32 v[60:61], v[46:47], v[42:43], v[4:5] op_sel_hi:[1,0,1]
	v_pk_mul_f32 v[4:5], v[46:47], v[48:49] op_sel:[1,0] op_sel_hi:[0,1]
	v_pk_fma_f32 v[64:65], v[46:47], v[46:47], v[4:5] op_sel_hi:[1,0,1]
	v_pk_mul_f32 v[54:55], v[52:53], 1.0 op_sel:[1,0] op_sel_hi:[1,0] neg_lo:[1,0]
	v_pk_mul_f32 v[4:5], v[64:65], v[16:17] op_sel:[1,0] op_sel_hi:[0,1]
	v_pk_fma_f32 v[68:69], v[2:3], v[64:65], v[4:5] op_sel_hi:[0,1,1]
	v_pk_mul_f32 v[4:5], v[44:45], v[64:65] op_sel:[0,1] op_sel_hi:[1,0]
	v_pk_mul_f32 v[58:59], v[56:57], 1.0 op_sel:[1,0] op_sel_hi:[1,0] neg_lo:[1,0]
	v_pk_fma_f32 v[72:73], v[40:41], v[64:65], v[4:5] op_sel_hi:[0,1,1]
	v_pk_mul_f32 v[4:5], v[64:65], v[50:51] op_sel:[1,0] op_sel_hi:[0,1]
	v_pk_fma_f32 v[76:77], v[42:43], v[64:65], v[4:5] op_sel_hi:[0,1,1]
	v_pk_mul_f32 v[4:5], v[48:49], v[64:65] op_sel:[0,1] op_sel_hi:[1,0]
	v_pk_mul_f32 v[62:63], v[60:61], 1.0 op_sel:[1,0] op_sel_hi:[1,0] neg_lo:[1,0]
	v_pk_fma_f32 v[80:81], v[46:47], v[64:65], v[4:5] op_sel_hi:[0,1,1]
	v_pk_mul_f32 v[4:5], v[80:81], v[16:17] op_sel:[1,0] op_sel_hi:[0,1]
	v_pk_fma_f32 v[84:85], v[2:3], v[80:81], v[4:5] op_sel_hi:[0,1,1]
	v_pk_mul_f32 v[4:5], v[44:45], v[80:81] op_sel:[0,1] op_sel_hi:[1,0]
	v_and_b32_e32 v3, 0xffffff00, v6
	v_pk_fma_f32 v[88:89], v[40:41], v[80:81], v[4:5] op_sel_hi:[0,1,1]
	v_pk_mul_f32 v[4:5], v[50:51], v[80:81] op_sel:[0,1] op_sel_hi:[1,0]
	v_xor_b32_e32 v66, 0x80000000, v65
	v_pk_fma_f32 v[92:93], v[42:43], v[80:81], v[4:5] op_sel_hi:[0,1,1]
	v_lshlrev_b32_e32 v4, 3, v3
	v_add3_u32 v18, 0, v7, v4
	v_ashrrev_i32_e32 v4, 2, v3
	v_add_u32_e32 v98, v18, v4
	ds_read2_b64 v[4:7], v98 offset1:16
	ds_read2_b64 v[8:11], v98 offset0:33 offset1:49
	ds_read2_b64 v[12:15], v98 offset0:66 offset1:82
	ds_read2_b64 v[20:23], v98 offset0:132 offset1:148
	ds_read2_b64 v[24:27], v98 offset0:99 offset1:115
	ds_read2_b64 v[28:31], v98 offset0:165 offset1:181
	ds_read2_b64 v[32:35], v98 offset0:198 offset1:214
	ds_read2_b64 v[36:39], v98 offset0:231 offset1:247
	s_waitcnt lgkmcnt(4)
	v_pk_mul_f32 v[96:97], v[16:17], v[20:21] op_sel:[0,1] op_sel_hi:[1,0]
	v_mov_b32_e32 v67, v65
	v_pk_fma_f32 v[20:21], v[2:3], v[20:21], v[96:97] op_sel_hi:[0,1,1]
	v_pk_mul_f32 v[96:97], v[12:13], v[44:45] op_sel:[1,0] op_sel_hi:[0,1]
	v_pk_fma_f32 v[12:13], v[12:13], v[40:41], v[96:97] op_sel_hi:[1,0,1]
	s_waitcnt lgkmcnt(1)
	v_pk_mul_f32 v[96:97], v[50:51], v[32:33] op_sel:[0,1] op_sel_hi:[1,0]
	v_xor_b32_e32 v70, 0x80000000, v69
	v_pk_fma_f32 v[32:33], v[42:43], v[32:33], v[96:97] op_sel_hi:[0,1,1]
	v_pk_mul_f32 v[96:97], v[8:9], v[48:49] op_sel:[1,0] op_sel_hi:[0,1]
	v_pk_fma_f32 v[8:9], v[8:9], v[46:47], v[96:97] op_sel_hi:[1,0,1]
	v_pk_mul_f32 v[96:97], v[28:29], v[54:55] op_sel:[1,0] op_sel_hi:[0,1]
	v_pk_fma_f32 v[28:29], v[28:29], v[52:53], v[96:97] op_sel_hi:[1,0,1]
	v_pk_mul_f32 v[96:97], v[24:25], v[58:59] op_sel:[1,0] op_sel_hi:[0,1]
	v_pk_fma_f32 v[24:25], v[24:25], v[56:57], v[96:97] op_sel_hi:[1,0,1]
	s_waitcnt lgkmcnt(0)
	v_pk_mul_f32 v[96:97], v[36:37], v[62:63] op_sel:[1,0] op_sel_hi:[0,1]
	v_mov_b32_e32 v71, v69
	v_pk_fma_f32 v[36:37], v[36:37], v[60:61], v[96:97] op_sel_hi:[1,0,1]
	v_pk_mul_f32 v[96:97], v[6:7], v[66:67] op_sel:[1,0] op_sel_hi:[0,1]
	v_pk_mul_f32 v[74:75], v[72:73], 1.0 op_sel:[1,0] op_sel_hi:[1,0] neg_lo:[1,0]
	v_pk_fma_f32 v[6:7], v[6:7], v[64:65], v[96:97] op_sel_hi:[1,0,1]
	v_pk_mul_f32 v[96:97], v[22:23], v[70:71] op_sel:[1,0] op_sel_hi:[0,1]
	v_pk_mul_f32 v[78:79], v[76:77], 1.0 op_sel:[1,0] op_sel_hi:[1,0] neg_lo:[1,0]
	v_pk_fma_f32 v[22:23], v[22:23], v[68:69], v[96:97] op_sel_hi:[1,0,1]
	v_pk_mul_f32 v[96:97], v[14:15], v[74:75] op_sel:[1,0] op_sel_hi:[0,1]
	v_pk_mul_f32 v[82:83], v[80:81], 1.0 op_sel:[1,0] op_sel_hi:[1,0] neg_lo:[1,0]
	v_pk_fma_f32 v[14:15], v[14:15], v[72:73], v[96:97] op_sel_hi:[1,0,1]
	v_pk_mul_f32 v[96:97], v[34:35], v[78:79] op_sel:[1,0] op_sel_hi:[0,1]
	v_pk_mul_f32 v[86:87], v[84:85], 1.0 op_sel:[1,0] op_sel_hi:[1,0] neg_lo:[1,0]
	v_pk_fma_f32 v[34:35], v[34:35], v[76:77], v[96:97] op_sel_hi:[1,0,1]
	v_pk_mul_f32 v[96:97], v[10:11], v[82:83] op_sel:[1,0] op_sel_hi:[0,1]
	v_pk_mul_f32 v[90:91], v[88:89], 1.0 op_sel:[1,0] op_sel_hi:[1,0] neg_lo:[1,0]
	v_pk_fma_f32 v[10:11], v[10:11], v[80:81], v[96:97] op_sel_hi:[1,0,1]
	v_pk_mul_f32 v[96:97], v[30:31], v[86:87] op_sel:[1,0] op_sel_hi:[0,1]
	v_pk_mul_f32 v[94:95], v[92:93], 1.0 op_sel:[1,0] op_sel_hi:[1,0] neg_lo:[1,0]
	v_pk_fma_f32 v[30:31], v[30:31], v[84:85], v[96:97] op_sel_hi:[1,0,1]
	v_pk_mul_f32 v[96:97], v[26:27], v[90:91] op_sel:[1,0] op_sel_hi:[0,1]
	v_pk_fma_f32 v[26:27], v[26:27], v[88:89], v[96:97] op_sel_hi:[1,0,1]
	v_pk_mul_f32 v[96:97], v[38:39], v[94:95] op_sel:[1,0] op_sel_hi:[0,1]
	v_pk_fma_f32 v[38:39], v[38:39], v[92:93], v[96:97] op_sel_hi:[1,0,1]
	v_pk_add_f32 v[96:97], v[4:5], v[6:7]
	v_pk_add_f32 v[4:5], v[4:5], v[6:7] neg_lo:[0,1] neg_hi:[0,1]
	v_pk_add_f32 v[6:7], v[8:9], v[10:11]
	v_pk_add_f32 v[8:9], v[8:9], v[10:11] neg_lo:[0,1] neg_hi:[0,1]
	v_pk_add_f32 v[10:11], v[12:13], v[14:15]
	v_pk_add_f32 v[12:13], v[12:13], v[14:15] neg_lo:[0,1] neg_hi:[0,1]
	v_pk_add_f32 v[14:15], v[24:25], v[26:27]
	v_pk_add_f32 v[24:25], v[24:25], v[26:27] neg_lo:[0,1] neg_hi:[0,1]
	v_pk_add_f32 v[26:27], v[20:21], v[22:23]
	v_pk_add_f32 v[20:21], v[20:21], v[22:23] neg_lo:[0,1] neg_hi:[0,1]
	v_pk_add_f32 v[22:23], v[28:29], v[30:31]
	v_pk_add_f32 v[28:29], v[28:29], v[30:31] neg_lo:[0,1] neg_hi:[0,1]
	v_pk_add_f32 v[30:31], v[32:33], v[34:35]
	v_pk_add_f32 v[32:33], v[32:33], v[34:35] neg_lo:[0,1] neg_hi:[0,1]
	v_pk_add_f32 v[34:35], v[36:37], v[38:39]
	v_pk_add_f32 v[36:37], v[36:37], v[38:39] neg_lo:[0,1] neg_hi:[0,1]
	v_pk_add_f32 v[38:39], v[96:97], v[6:7]
	v_pk_add_f32 v[6:7], v[96:97], v[6:7] neg_lo:[0,1] neg_hi:[0,1]
	v_pk_mul_f32 v[96:97], v[8:9], 1.0 op_sel:[1,0] op_sel_hi:[0,0] neg_lo:[1,0]
	v_pk_add_f32 v[8:9], v[4:5], v[96:97]
	v_pk_add_f32 v[4:5], v[4:5], v[96:97] neg_lo:[0,1] neg_hi:[0,1]
	v_pk_add_f32 v[96:97], v[10:11], v[14:15]
	v_pk_add_f32 v[10:11], v[10:11], v[14:15] neg_lo:[0,1] neg_hi:[0,1]
	v_pk_mul_f32 v[14:15], v[24:25], 1.0 op_sel:[1,0] op_sel_hi:[0,0] neg_lo:[1,0]
	v_pk_add_f32 v[24:25], v[12:13], v[14:15]
	v_pk_add_f32 v[12:13], v[12:13], v[14:15] neg_lo:[0,1] neg_hi:[0,1]
	v_pk_add_f32 v[14:15], v[26:27], v[22:23]
	v_pk_add_f32 v[22:23], v[26:27], v[22:23] neg_lo:[0,1] neg_hi:[0,1]
	v_pk_mul_f32 v[26:27], v[28:29], 1.0 op_sel:[1,0] op_sel_hi:[0,0] neg_lo:[1,0]
	v_pk_add_f32 v[28:29], v[20:21], v[26:27]
	v_pk_add_f32 v[20:21], v[20:21], v[26:27] neg_lo:[0,1] neg_hi:[0,1]
	v_pk_add_f32 v[26:27], v[30:31], v[34:35]
	v_pk_add_f32 v[30:31], v[30:31], v[34:35] neg_lo:[0,1] neg_hi:[0,1]
	v_pk_mul_f32 v[34:35], v[36:37], 1.0 op_sel:[1,0] op_sel_hi:[0,0] neg_lo:[1,0]
	v_pk_add_f32 v[36:37], v[32:33], v[34:35]
	v_pk_add_f32 v[32:33], v[32:33], v[34:35] neg_lo:[0,1] neg_hi:[0,1]
	v_pk_add_f32 v[34:35], v[38:39], v[96:97]
	v_pk_add_f32 v[38:39], v[38:39], v[96:97] neg_lo:[0,1] neg_hi:[0,1]
	v_pk_mul_f32 v[96:97], v[24:25], s[66:67]
	v_add_u32_e32 v3, 0x2000, v3
	v_pk_fma_f32 v[24:25], v[24:25], s[0:1], v[96:97] op_sel:[0,0,1] op_sel_hi:[1,0,0]
	v_ashrrev_i32_e32 v3, 2, v3
	v_pk_add_f32 v[96:97], v[8:9], v[24:25]
	v_pk_add_f32 v[8:9], v[8:9], v[24:25] neg_lo:[0,1] neg_hi:[0,1]
	v_pk_mul_f32 v[24:25], v[10:11], 1.0 op_sel:[1,0] op_sel_hi:[0,0] neg_lo:[1,0]
	v_pk_add_f32 v[10:11], v[6:7], v[24:25]
	v_pk_add_f32 v[6:7], v[6:7], v[24:25] neg_lo:[0,1] neg_hi:[0,1]
	v_pk_mul_f32 v[24:25], v[12:13], s[66:67]
	v_add3_u32 v18, v18, v3, s5
	v_pk_fma_f32 v[12:13], s[0:1], v[12:13], v[24:25] op_sel:[0,0,1] op_sel_hi:[0,1,0] neg_lo:[0,1,0] neg_hi:[0,1,0]
	v_pk_add_f32 v[24:25], v[4:5], v[12:13]
	v_pk_add_f32 v[4:5], v[4:5], v[12:13] neg_lo:[0,1] neg_hi:[0,1]
	v_pk_add_f32 v[12:13], v[14:15], v[26:27]
	v_pk_add_f32 v[14:15], v[14:15], v[26:27] neg_lo:[0,1] neg_hi:[0,1]
	v_pk_mul_f32 v[26:27], v[36:37], s[66:67]
	s_nop 0
	v_pk_fma_f32 v[26:27], s[0:1], v[36:37], v[26:27] op_sel:[0,0,1] op_sel_hi:[0,1,0]
	v_pk_add_f32 v[36:37], v[28:29], v[26:27]
	v_pk_add_f32 v[26:27], v[28:29], v[26:27] neg_lo:[0,1] neg_hi:[0,1]
	v_pk_mul_f32 v[28:29], v[30:31], 1.0 op_sel:[1,0] op_sel_hi:[0,0] neg_lo:[1,0]
	v_pk_add_f32 v[30:31], v[22:23], v[28:29]
	v_pk_add_f32 v[22:23], v[22:23], v[28:29] neg_lo:[0,1] neg_hi:[0,1]
	v_pk_mul_f32 v[28:29], v[32:33], s[66:67]
	s_nop 0
	v_pk_fma_f32 v[28:29], s[0:1], v[32:33], v[28:29] op_sel:[0,0,1] op_sel_hi:[0,1,0] neg_lo:[0,1,0] neg_hi:[0,1,0]
	v_pk_add_f32 v[32:33], v[20:21], v[28:29]
	v_pk_add_f32 v[20:21], v[20:21], v[28:29] neg_lo:[0,1] neg_hi:[0,1]
	v_pk_add_f32 v[28:29], v[34:35], v[12:13]
	v_pk_add_f32 v[12:13], v[34:35], v[12:13] neg_lo:[0,1] neg_hi:[0,1]
	v_pk_mul_f32 v[34:35], v[36:37], s[68:69]
	s_nop 0
	v_pk_fma_f32 v[34:35], s[16:17], v[36:37], v[34:35] op_sel:[0,0,1] op_sel_hi:[0,1,0]
	v_pk_add_f32 v[36:37], v[96:97], v[34:35]
	v_pk_add_f32 v[34:35], v[96:97], v[34:35] neg_lo:[0,1] neg_hi:[0,1]
	v_pk_mul_f32 v[96:97], v[30:31], s[66:67]
	s_nop 0
	v_pk_fma_f32 v[30:31], s[0:1], v[30:31], v[96:97] op_sel:[0,0,1] op_sel_hi:[0,1,0]
	v_pk_add_f32 v[96:97], v[10:11], v[30:31]
	v_pk_add_f32 v[10:11], v[10:11], v[30:31] neg_lo:[0,1] neg_hi:[0,1]
	v_pk_mul_f32 v[30:31], v[32:33], s[16:17]
	s_nop 0
	v_pk_fma_f32 v[30:31], s[72:73], v[32:33], v[30:31] op_sel:[0,0,1] op_sel_hi:[0,1,0]
	v_pk_add_f32 v[32:33], v[24:25], v[30:31]
	v_pk_add_f32 v[24:25], v[24:25], v[30:31] neg_lo:[0,1] neg_hi:[0,1]
	v_pk_mul_f32 v[30:31], v[14:15], 1.0 op_sel:[1,0] op_sel_hi:[0,0] neg_lo:[1,0]
	v_pk_add_f32 v[14:15], v[38:39], v[30:31]
	v_pk_add_f32 v[30:31], v[38:39], v[30:31] neg_lo:[0,1] neg_hi:[0,1]
	v_pk_mul_f32 v[38:39], v[26:27], s[16:17]
	s_nop 0
	v_pk_fma_f32 v[26:27], s[72:73], v[26:27], v[38:39] op_sel:[0,0,1] op_sel_hi:[0,1,0] neg_lo:[0,1,0] neg_hi:[0,1,0]
	v_pk_add_f32 v[38:39], v[8:9], v[26:27]
	v_pk_add_f32 v[8:9], v[8:9], v[26:27] neg_lo:[0,1] neg_hi:[0,1]
	v_pk_mul_f32 v[26:27], v[22:23], s[66:67]
	s_nop 0
	v_pk_fma_f32 v[22:23], s[0:1], v[22:23], v[26:27] op_sel:[0,0,1] op_sel_hi:[0,1,0] neg_lo:[0,1,0] neg_hi:[0,1,0]
	v_pk_add_f32 v[26:27], v[6:7], v[22:23]
	v_pk_add_f32 v[6:7], v[6:7], v[22:23] neg_lo:[0,1] neg_hi:[0,1]
	v_pk_mul_f32 v[22:23], v[20:21], s[68:69]
	s_nop 0
	v_pk_fma_f32 v[20:21], s[16:17], v[20:21], v[22:23] op_sel:[0,0,1] op_sel_hi:[0,1,0] neg_lo:[0,1,0] neg_hi:[0,1,0]
	v_pk_add_f32 v[22:23], v[4:5], v[20:21]
	v_pk_add_f32 v[4:5], v[4:5], v[20:21] neg_lo:[0,1] neg_hi:[0,1]
	ds_write2_b64 v98, v[28:29], v[36:37] offset1:16
	ds_write2_b64 v98, v[96:97], v[32:33] offset0:33 offset1:49
	ds_write2_b64 v98, v[14:15], v[38:39] offset0:66 offset1:82
	ds_write2_b64 v98, v[26:27], v[22:23] offset0:99 offset1:115
	ds_write2_b64 v98, v[12:13], v[34:35] offset0:132 offset1:148
	ds_write2_b64 v98, v[10:11], v[24:25] offset0:165 offset1:181
	ds_write2_b64 v98, v[30:31], v[8:9] offset0:198 offset1:214
	ds_write2_b64 v98, v[6:7], v[4:5] offset0:231 offset1:247
	ds_read2_b64 v[4:7], v18 offset1:16
	ds_read2_b64 v[8:11], v18 offset0:33 offset1:49
	ds_read2_b64 v[12:15], v18 offset0:66 offset1:82
	ds_read2_b64 v[20:23], v18 offset0:132 offset1:148
	ds_read2_b64 v[24:27], v18 offset0:99 offset1:115
	ds_read2_b64 v[28:31], v18 offset0:165 offset1:181
	ds_read2_b64 v[32:35], v18 offset0:198 offset1:214
	ds_read2_b64 v[36:39], v18 offset0:231 offset1:247
	s_waitcnt lgkmcnt(4)
	v_pk_mul_f32 v[16:17], v[20:21], v[16:17] op_sel:[1,0] op_sel_hi:[0,1]
	v_pk_fma_f32 v[2:3], v[2:3], v[20:21], v[16:17] op_sel_hi:[0,1,1]
	v_pk_mul_f32 v[16:17], v[44:45], v[12:13] op_sel:[0,1] op_sel_hi:[1,0]
	v_pk_mul_f32 v[20:21], v[48:49], v[8:9] op_sel:[0,1] op_sel_hi:[1,0]
	v_pk_fma_f32 v[12:13], v[40:41], v[12:13], v[16:17] op_sel_hi:[0,1,1]
	s_waitcnt lgkmcnt(1)
	v_pk_mul_f32 v[16:17], v[50:51], v[32:33] op_sel:[0,1] op_sel_hi:[1,0]
	v_pk_fma_f32 v[8:9], v[46:47], v[8:9], v[20:21] op_sel_hi:[0,1,1]
	v_pk_fma_f32 v[16:17], v[42:43], v[32:33], v[16:17] op_sel_hi:[0,1,1]
	v_pk_mul_f32 v[32:33], v[66:67], v[6:7] op_sel:[0,1] op_sel_hi:[1,0]
	v_pk_mul_f32 v[20:21], v[54:55], v[28:29] op_sel:[0,1] op_sel_hi:[1,0]
	v_pk_fma_f32 v[6:7], v[64:65], v[6:7], v[32:33] op_sel_hi:[0,1,1]
	v_pk_mul_f32 v[32:33], v[70:71], v[22:23] op_sel:[0,1] op_sel_hi:[1,0]
	v_pk_fma_f32 v[20:21], v[52:53], v[28:29], v[20:21] op_sel_hi:[0,1,1]
	v_pk_fma_f32 v[22:23], v[68:69], v[22:23], v[32:33] op_sel_hi:[0,1,1]
	v_pk_mul_f32 v[32:33], v[74:75], v[14:15] op_sel:[0,1] op_sel_hi:[1,0]
	v_pk_mul_f32 v[28:29], v[58:59], v[24:25] op_sel:[0,1] op_sel_hi:[1,0]
	v_pk_fma_f32 v[14:15], v[72:73], v[14:15], v[32:33] op_sel_hi:[0,1,1]
	v_pk_mul_f32 v[32:33], v[78:79], v[34:35] op_sel:[0,1] op_sel_hi:[1,0]
	v_pk_fma_f32 v[24:25], v[56:57], v[24:25], v[28:29] op_sel_hi:[0,1,1]
	v_pk_fma_f32 v[32:33], v[76:77], v[34:35], v[32:33] op_sel_hi:[0,1,1]
	v_pk_mul_f32 v[34:35], v[82:83], v[10:11] op_sel:[0,1] op_sel_hi:[1,0]
	s_waitcnt lgkmcnt(0)
	v_pk_mul_f32 v[28:29], v[62:63], v[36:37] op_sel:[0,1] op_sel_hi:[1,0]
	v_pk_fma_f32 v[10:11], v[80:81], v[10:11], v[34:35] op_sel_hi:[0,1,1]
	v_pk_mul_f32 v[34:35], v[86:87], v[30:31] op_sel:[0,1] op_sel_hi:[1,0]
	v_pk_fma_f32 v[28:29], v[60:61], v[36:37], v[28:29] op_sel_hi:[0,1,1]
	v_pk_fma_f32 v[30:31], v[84:85], v[30:31], v[34:35] op_sel_hi:[0,1,1]
	v_pk_mul_f32 v[34:35], v[90:91], v[26:27] op_sel:[0,1] op_sel_hi:[1,0]
	v_pk_add_f32 v[36:37], v[4:5], v[6:7]
	v_pk_fma_f32 v[26:27], v[88:89], v[26:27], v[34:35] op_sel_hi:[0,1,1]
	v_pk_mul_f32 v[34:35], v[94:95], v[38:39] op_sel:[0,1] op_sel_hi:[1,0]
	v_pk_add_f32 v[4:5], v[4:5], v[6:7] neg_lo:[0,1] neg_hi:[0,1]
	v_pk_fma_f32 v[34:35], v[92:93], v[38:39], v[34:35] op_sel_hi:[0,1,1]
	v_pk_add_f32 v[6:7], v[8:9], v[10:11]
	v_pk_add_f32 v[8:9], v[8:9], v[10:11] neg_lo:[0,1] neg_hi:[0,1]
	v_pk_add_f32 v[10:11], v[12:13], v[14:15]
	v_pk_add_f32 v[12:13], v[12:13], v[14:15] neg_lo:[0,1] neg_hi:[0,1]
	v_pk_add_f32 v[14:15], v[24:25], v[26:27]
	v_pk_add_f32 v[24:25], v[24:25], v[26:27] neg_lo:[0,1] neg_hi:[0,1]
	v_pk_add_f32 v[26:27], v[2:3], v[22:23]
	v_pk_add_f32 v[2:3], v[2:3], v[22:23] neg_lo:[0,1] neg_hi:[0,1]
	v_pk_add_f32 v[22:23], v[20:21], v[30:31]
	v_pk_add_f32 v[20:21], v[20:21], v[30:31] neg_lo:[0,1] neg_hi:[0,1]
	v_pk_add_f32 v[30:31], v[16:17], v[32:33]
	v_pk_add_f32 v[16:17], v[16:17], v[32:33] neg_lo:[0,1] neg_hi:[0,1]
	v_pk_add_f32 v[32:33], v[28:29], v[34:35]
	v_pk_add_f32 v[28:29], v[28:29], v[34:35] neg_lo:[0,1] neg_hi:[0,1]
	v_pk_add_f32 v[34:35], v[36:37], v[6:7]
	v_pk_add_f32 v[6:7], v[36:37], v[6:7] neg_lo:[0,1] neg_hi:[0,1]
	v_pk_mul_f32 v[36:37], v[8:9], 1.0 op_sel:[1,0] op_sel_hi:[0,0] neg_lo:[1,0]
	v_pk_add_f32 v[8:9], v[4:5], v[36:37]
	v_pk_add_f32 v[4:5], v[4:5], v[36:37] neg_lo:[0,1] neg_hi:[0,1]
	v_pk_add_f32 v[36:37], v[10:11], v[14:15]
	v_pk_add_f32 v[10:11], v[10:11], v[14:15] neg_lo:[0,1] neg_hi:[0,1]
	v_pk_mul_f32 v[14:15], v[24:25], 1.0 op_sel:[1,0] op_sel_hi:[0,0] neg_lo:[1,0]
	v_pk_add_f32 v[24:25], v[12:13], v[14:15]
	v_pk_add_f32 v[12:13], v[12:13], v[14:15] neg_lo:[0,1] neg_hi:[0,1]
	v_pk_add_f32 v[14:15], v[26:27], v[22:23]
	v_pk_add_f32 v[22:23], v[26:27], v[22:23] neg_lo:[0,1] neg_hi:[0,1]
	v_pk_mul_f32 v[26:27], v[20:21], 1.0 op_sel:[1,0] op_sel_hi:[0,0] neg_lo:[1,0]
	v_pk_add_f32 v[20:21], v[2:3], v[26:27]
	v_pk_add_f32 v[2:3], v[2:3], v[26:27] neg_lo:[0,1] neg_hi:[0,1]
	v_pk_add_f32 v[26:27], v[30:31], v[32:33]
	v_pk_add_f32 v[30:31], v[30:31], v[32:33] neg_lo:[0,1] neg_hi:[0,1]
	v_pk_mul_f32 v[32:33], v[28:29], 1.0 op_sel:[1,0] op_sel_hi:[0,0] neg_lo:[1,0]
	v_pk_add_f32 v[28:29], v[16:17], v[32:33]
	v_pk_add_f32 v[16:17], v[16:17], v[32:33] neg_lo:[0,1] neg_hi:[0,1]
	v_pk_add_f32 v[32:33], v[34:35], v[36:37]
	v_pk_add_f32 v[34:35], v[34:35], v[36:37] neg_lo:[0,1] neg_hi:[0,1]
	v_pk_mul_f32 v[36:37], v[24:25], s[66:67]
	v_mov_b32_e32 v39, 0
	v_pk_fma_f32 v[24:25], v[24:25], s[0:1], v[36:37] op_sel:[0,0,1] op_sel_hi:[1,0,0]
	v_mov_b32_e32 v41, 0
	v_pk_add_f32 v[36:37], v[8:9], v[24:25]
	v_pk_add_f32 v[8:9], v[8:9], v[24:25] neg_lo:[0,1] neg_hi:[0,1]
	v_pk_mul_f32 v[24:25], v[10:11], 1.0 op_sel:[1,0] op_sel_hi:[0,0] neg_lo:[1,0]
	v_pk_add_f32 v[10:11], v[6:7], v[24:25]
	v_pk_add_f32 v[6:7], v[6:7], v[24:25] neg_lo:[0,1] neg_hi:[0,1]
	v_pk_mul_f32 v[24:25], v[12:13], s[66:67]
	s_nop 0
	v_pk_fma_f32 v[12:13], s[0:1], v[12:13], v[24:25] op_sel:[0,0,1] op_sel_hi:[0,1,0] neg_lo:[0,1,0] neg_hi:[0,1,0]
	v_pk_add_f32 v[24:25], v[4:5], v[12:13]
	v_pk_add_f32 v[4:5], v[4:5], v[12:13] neg_lo:[0,1] neg_hi:[0,1]
	v_pk_add_f32 v[12:13], v[14:15], v[26:27]
	v_pk_add_f32 v[14:15], v[14:15], v[26:27] neg_lo:[0,1] neg_hi:[0,1]
	v_pk_mul_f32 v[26:27], v[28:29], s[66:67]
	s_nop 0
	v_pk_fma_f32 v[26:27], s[0:1], v[28:29], v[26:27] op_sel:[0,0,1] op_sel_hi:[0,1,0]
	v_pk_add_f32 v[28:29], v[20:21], v[26:27]
	v_pk_add_f32 v[20:21], v[20:21], v[26:27] neg_lo:[0,1] neg_hi:[0,1]
	v_pk_mul_f32 v[26:27], v[30:31], 1.0 op_sel:[1,0] op_sel_hi:[0,0] neg_lo:[1,0]
	v_pk_add_f32 v[30:31], v[22:23], v[26:27]
	v_pk_add_f32 v[22:23], v[22:23], v[26:27] neg_lo:[0,1] neg_hi:[0,1]
	v_pk_mul_f32 v[26:27], v[16:17], s[66:67]
	s_nop 0
	v_pk_fma_f32 v[16:17], s[0:1], v[16:17], v[26:27] op_sel:[0,0,1] op_sel_hi:[0,1,0] neg_lo:[0,1,0] neg_hi:[0,1,0]
	v_pk_add_f32 v[26:27], v[2:3], v[16:17]
	v_pk_add_f32 v[2:3], v[2:3], v[16:17] neg_lo:[0,1] neg_hi:[0,1]
	v_pk_add_f32 v[16:17], v[32:33], v[12:13]
	v_pk_add_f32 v[12:13], v[32:33], v[12:13] neg_lo:[0,1] neg_hi:[0,1]
	v_pk_mul_f32 v[32:33], v[28:29], s[68:69]
	s_nop 0
	v_pk_fma_f32 v[28:29], s[16:17], v[28:29], v[32:33] op_sel:[0,0,1] op_sel_hi:[0,1,0]
	v_pk_add_f32 v[32:33], v[36:37], v[28:29]
	v_pk_add_f32 v[28:29], v[36:37], v[28:29] neg_lo:[0,1] neg_hi:[0,1]
	v_pk_mul_f32 v[36:37], v[30:31], s[66:67]
	s_nop 0
	v_pk_fma_f32 v[30:31], s[0:1], v[30:31], v[36:37] op_sel:[0,0,1] op_sel_hi:[0,1,0]
	v_pk_add_f32 v[36:37], v[10:11], v[30:31]
	v_pk_add_f32 v[10:11], v[10:11], v[30:31] neg_lo:[0,1] neg_hi:[0,1]
	v_pk_mul_f32 v[30:31], v[26:27], s[16:17]
	s_nop 0
	v_pk_fma_f32 v[26:27], s[72:73], v[26:27], v[30:31] op_sel:[0,0,1] op_sel_hi:[0,1,0]
	v_pk_add_f32 v[30:31], v[24:25], v[26:27]
	v_pk_add_f32 v[24:25], v[24:25], v[26:27] neg_lo:[0,1] neg_hi:[0,1]
	v_pk_mul_f32 v[26:27], v[14:15], 1.0 op_sel:[1,0] op_sel_hi:[0,0] neg_lo:[1,0]
	v_pk_add_f32 v[14:15], v[34:35], v[26:27]
	v_pk_add_f32 v[26:27], v[34:35], v[26:27] neg_lo:[0,1] neg_hi:[0,1]
	v_pk_mul_f32 v[34:35], v[20:21], s[16:17]
	s_nop 0
	v_pk_fma_f32 v[20:21], s[72:73], v[20:21], v[34:35] op_sel:[0,0,1] op_sel_hi:[0,1,0] neg_lo:[0,1,0] neg_hi:[0,1,0]
	v_pk_add_f32 v[34:35], v[8:9], v[20:21]
	v_pk_add_f32 v[8:9], v[8:9], v[20:21] neg_lo:[0,1] neg_hi:[0,1]
	v_pk_mul_f32 v[20:21], v[22:23], s[66:67]
	s_nop 0
	v_pk_fma_f32 v[20:21], v[22:23], s[0:1], v[20:21] op_sel:[0,0,1] op_sel_hi:[1,0,0] neg_lo:[1,0,0] neg_hi:[1,0,0]
	s_lshl_b64 s[0:1], s[62:63], 2
	v_pk_add_f32 v[22:23], v[6:7], v[20:21]
	v_pk_add_f32 v[6:7], v[6:7], v[20:21] neg_lo:[0,1] neg_hi:[0,1]
	v_pk_mul_f32 v[20:21], v[2:3], s[68:69]
	s_add_u32 s0, s49, s0
	v_pk_fma_f32 v[2:3], v[2:3], s[16:17], v[20:21] op_sel:[0,0,1] op_sel_hi:[1,0,0] neg_lo:[1,0,0] neg_hi:[1,0,0]
	s_addc_u32 s1, s60, s1
	v_pk_add_f32 v[20:21], v[4:5], v[2:3]
	v_pk_add_f32 v[2:3], v[4:5], v[2:3] neg_lo:[0,1] neg_hi:[0,1]
	ds_write2_b64 v18, v[16:17], v[32:33] offset1:16
	ds_write2_b64 v18, v[36:37], v[30:31] offset0:33 offset1:49
	ds_write2_b64 v18, v[14:15], v[34:35] offset0:66 offset1:82
	ds_write2_b64 v18, v[22:23], v[20:21] offset0:99 offset1:115
	ds_write2_b64 v18, v[12:13], v[28:29] offset0:132 offset1:148
	ds_write2_b64 v18, v[10:11], v[24:25] offset0:165 offset1:181
	ds_write2_b64 v18, v[26:27], v[8:9] offset0:198 offset1:214
	ds_write2_b64 v18, v[6:7], v[2:3] offset0:231 offset1:247
	s_waitcnt lgkmcnt(0)
	s_barrier
	s_lshl_b64 s[62:63], s[64:65], 2
	v_ashrrev_i32_e32 v2, 31, v210
	s_add_u32 s62, s22, s62
	v_lshrrev_b32_e32 v2, 23, v2
	global_load_dword v30, v206, s[0:1]
	global_load_dword v20, v207, s[0:1]
	s_addc_u32 s63, s23, s63
	global_load_dword v31, v205, s[0:1]
	global_load_dword v24, v205, s[62:63]
	s_lshl_b64 s[0:1], s[64:65], 16
	v_add_u32_e32 v2, v210, v2
	s_add_u32 s0, s87, s0
	v_ashrrev_i32_e32 v2, 9, v2
	s_addc_u32 s1, s90, s1
	v_mul_i32_i24_e32 v3, 0x200, v2
	s_add_u32 s0, s0, 0x8000
	v_sub_u32_e32 v21, v210, v3
	v_lshlrev_b32_e32 v36, 13, v2
	s_addc_u32 s1, s1, 0
	v_ashrrev_i32_e32 v37, 31, v36
	v_lshlrev_b32_e32 v32, 4, v21
	v_lshl_add_u64 v[2:3], v[36:37], 1, s[0:1]
	v_ashrrev_i32_e32 v33, 31, v32
	v_lshl_add_u64 v[2:3], v[32:33], 1, v[2:3]
	global_load_dwordx4 v[10:13], v[2:3], off offset:16 nt
	global_load_dwordx4 v[14:17], v[2:3], off nt
	v_cmp_lt_i32_e32 vcc, 0, v21
	s_and_saveexec_b64 s[62:63], vcc
	s_cbranch_execz .LBB0_540
	global_load_ushort v41, v[2:3], off offset:-2

.LBB0_546:
	s_or_b64 exec, exec, s[0:1]
	v_mov_b32_e32 v25, v210
	s_mov_b32 s62, s37
	v_and_b32_e32 v28, 0xff, v25
	v_lshlrev_b32_e32 v34, 5, v25
	v_cvt_f32_ubyte0_e32 v25, v25
	v_mul_f32_e32 v25, 0x39000000, v25
	v_sin_f32_e32 v43, v25
	v_cos_f32_e32 v42, v25
	v_and_or_b32 v28, v34, s33, v28
	v_ashrrev_i32_e32 v34, 5, v28
	v_pk_mul_f32 v[44:45], v[42:43], 1.0 op_sel:[1,0] op_sel_hi:[1,0] neg_lo:[1,0]
	s_nop 0
	v_pk_mul_f32 v[46:47], v[42:43], v[44:45] op_sel:[1,0] op_sel_hi:[0,1]
	v_pk_fma_f32 v[46:47], v[42:43], v[42:43], v[46:47] op_sel_hi:[1,0,1]
	v_lshlrev_b32_e32 v28, 3, v28
	v_pk_mul_f32 v[50:51], 1.0, v[46:47] op_sel:[0,1] op_sel_hi:[0,1] neg_lo:[0,1]
	v_pk_mul_f32 v[52:53], v[46:47], v[50:51] op_sel:[1,0] op_sel_hi:[0,1]
	v_pk_fma_f32 v[52:53], v[46:47], v[46:47], v[52:53] op_sel_hi:[1,0,1]
	v_lshlrev_b32_e32 v34, 3, v34
	v_pk_mul_f32 v[54:55], 1.0, v[52:53] op_sel:[0,1] op_sel_hi:[0,1] neg_lo:[0,1]
	v_pk_mul_f32 v[70:71], v[52:53], v[54:55] op_sel:[1,0] op_sel_hi:[0,1]
	v_pk_fma_f32 v[70:71], v[52:53], v[52:53], v[70:71] op_sel_hi:[1,0,1]
	v_pk_mul_f32 v[48:49], v[44:45], v[46:47] op_sel:[0,1] op_sel_hi:[1,0]
	v_pk_mul_f32 v[86:87], v[54:55], v[70:71] op_sel:[0,1] op_sel_hi:[1,0]
	v_add3_u32 v25, 0, v28, v34
	v_pk_fma_f32 v[86:87], v[52:53], v[70:71], v[86:87] op_sel_hi:[0,1,1]
	v_pk_mul_f32 v[102:103], v[54:55], v[86:87] op_sel:[0,1] op_sel_hi:[1,0]
	v_pk_fma_f32 v[48:49], v[42:43], v[46:47], v[48:49] op_sel_hi:[0,1,1]
	v_pk_fma_f32 v[102:103], v[52:53], v[86:87], v[102:103] op_sel_hi:[0,1,1]
	v_pk_mul_f32 v[118:119], v[54:55], v[102:103] op_sel:[0,1] op_sel_hi:[1,0]
	v_pk_mul_f32 v[56:57], v[48:49], 1.0 op_sel:[1,0] op_sel_hi:[1,0] neg_lo:[1,0]
	v_pk_fma_f32 v[118:119], v[52:53], v[102:103], v[118:119] op_sel_hi:[0,1,1]
	v_pk_mul_f32 v[134:135], v[118:119], v[54:55] op_sel:[1,0] op_sel_hi:[0,1]
	v_pk_fma_f32 v[134:135], v[52:53], v[118:119], v[134:135] op_sel_hi:[0,1,1]
	v_pk_mul_f32 v[152:153], v[54:55], v[134:135] op_sel:[0,1] op_sel_hi:[1,0]
	v_pk_mul_f32 v[58:59], v[44:45], v[52:53] op_sel:[0,1] op_sel_hi:[1,0]
	v_pk_fma_f32 v[152:153], v[52:53], v[134:135], v[152:153] op_sel_hi:[0,1,1]
	v_pk_mul_f32 v[74:75], v[44:45], v[70:71] op_sel:[0,1] op_sel_hi:[1,0]
	v_pk_mul_f32 v[90:91], v[44:45], v[86:87] op_sel:[0,1] op_sel_hi:[1,0]
	v_pk_mul_f32 v[106:107], v[44:45], v[102:103] op_sel:[0,1] op_sel_hi:[1,0]
	v_pk_mul_f32 v[122:123], v[44:45], v[118:119] op_sel:[0,1] op_sel_hi:[1,0]
	v_pk_mul_f32 v[138:139], v[44:45], v[134:135] op_sel:[0,1] op_sel_hi:[1,0]
	v_pk_mul_f32 v[156:157], v[44:45], v[152:153] op_sel:[0,1] op_sel_hi:[1,0]
	ds_read_b64 v[168:169], v25
	ds_read_b64 v[170:171], v25 offset:2112
	ds_read_b64 v[172:173], v25 offset:4224
	ds_read_b64 v[174:175], v25 offset:6336
	ds_read_b64 v[176:177], v25 offset:8448
	ds_read_b64 v[178:179], v25 offset:10560
	ds_read_b64 v[180:181], v25 offset:12672
	ds_read_b64 v[182:183], v25 offset:14784
	ds_read_b64 v[184:185], v25 offset:16896
	ds_read_b64 v[186:187], v25 offset:19008
	ds_read_b64 v[188:189], v25 offset:21120
	ds_read_b64 v[190:191], v25 offset:23232
	ds_read_b64 v[192:193], v25 offset:25344
	ds_read_b64 v[194:195], v25 offset:27456
	ds_read_b64 v[196:197], v25 offset:29568
	ds_read_b64 v[198:199], v25 offset:31680
	ds_read_b64 v[212:213], v25 offset:33792
	ds_read_b64 v[214:215], v25 offset:35904
	ds_read_b64 v[216:217], v25 offset:38016
	ds_read_b64 v[218:219], v25 offset:40128
	ds_read_b64 v[220:221], v25 offset:42240
	ds_read_b64 v[222:223], v25 offset:44352
	ds_read_b64 v[224:225], v25 offset:46464
	ds_read_b64 v[226:227], v25 offset:48576
	ds_read_b64 v[228:229], v25 offset:50688
	ds_read_b64 v[230:231], v25 offset:52800
	ds_read_b64 v[232:233], v25 offset:54912
	ds_read_b64 v[234:235], v25 offset:57024
	ds_read_b64 v[236:237], v25 offset:59136
	ds_read_b64 v[238:239], v25 offset:61248
	ds_read_b64 v[240:241], v25 offset:63360
	ds_read_b64 v[242:243], v25 offset:65472
	s_waitcnt lgkmcnt(14)
	v_pk_mul_f32 v[44:45], v[44:45], v[212:213] op_sel:[0,1] op_sel_hi:[1,0]
	v_pk_fma_f32 v[58:59], v[42:43], v[52:53], v[58:59] op_sel_hi:[0,1,1]
	v_pk_mul_f32 v[62:63], v[50:51], v[52:53] op_sel:[0,1] op_sel_hi:[1,0]
	v_pk_mul_f32 v[66:67], v[52:53], v[56:57] op_sel:[1,0] op_sel_hi:[0,1]
	v_pk_fma_f32 v[74:75], v[42:43], v[70:71], v[74:75] op_sel_hi:[0,1,1]
	v_pk_mul_f32 v[78:79], v[50:51], v[70:71] op_sel:[0,1] op_sel_hi:[1,0]
	v_pk_fma_f32 v[90:91], v[42:43], v[86:87], v[90:91] op_sel_hi:[0,1,1]
	v_pk_mul_f32 v[94:95], v[50:51], v[86:87] op_sel:[0,1] op_sel_hi:[1,0]
	v_pk_fma_f32 v[106:107], v[42:43], v[102:103], v[106:107] op_sel_hi:[0,1,1]
	v_pk_mul_f32 v[110:111], v[50:51], v[102:103] op_sel:[0,1] op_sel_hi:[1,0]
	v_pk_fma_f32 v[122:123], v[42:43], v[118:119], v[122:123] op_sel_hi:[0,1,1]
	v_pk_mul_f32 v[126:127], v[50:51], v[118:119] op_sel:[0,1] op_sel_hi:[1,0]
	v_pk_fma_f32 v[138:139], v[42:43], v[134:135], v[138:139] op_sel_hi:[0,1,1]
	v_pk_mul_f32 v[142:143], v[50:51], v[134:135] op_sel:[0,1] op_sel_hi:[1,0]
	v_pk_fma_f32 v[156:157], v[42:43], v[152:153], v[156:157] op_sel_hi:[0,1,1]
	v_pk_mul_f32 v[160:161], v[50:51], v[152:153] op_sel:[0,1] op_sel_hi:[1,0]
	v_pk_fma_f32 v[42:43], v[42:43], v[212:213], v[44:45] op_sel_hi:[0,1,1]
	v_pk_mul_f32 v[44:45], v[184:185], v[50:51] op_sel:[1,0] op_sel_hi:[0,1]
	v_pk_fma_f32 v[62:63], v[46:47], v[52:53], v[62:63] op_sel_hi:[0,1,1]
	v_pk_fma_f32 v[66:67], v[52:53], v[48:49], v[66:67] op_sel_hi:[1,0,1]
	v_pk_fma_f32 v[78:79], v[46:47], v[70:71], v[78:79] op_sel_hi:[0,1,1]
	v_pk_mul_f32 v[82:83], v[56:57], v[70:71] op_sel:[0,1] op_sel_hi:[1,0]
	v_pk_fma_f32 v[94:95], v[46:47], v[86:87], v[94:95] op_sel_hi:[0,1,1]
	v_pk_mul_f32 v[98:99], v[56:57], v[86:87] op_sel:[0,1] op_sel_hi:[1,0]
	v_pk_fma_f32 v[110:111], v[46:47], v[102:103], v[110:111] op_sel_hi:[0,1,1]
	v_pk_mul_f32 v[114:115], v[56:57], v[102:103] op_sel:[0,1] op_sel_hi:[1,0]
	v_pk_fma_f32 v[126:127], v[46:47], v[118:119], v[126:127] op_sel_hi:[0,1,1]
	v_pk_mul_f32 v[130:131], v[56:57], v[118:119] op_sel:[0,1] op_sel_hi:[1,0]
	v_pk_fma_f32 v[142:143], v[46:47], v[134:135], v[142:143] op_sel_hi:[0,1,1]
	v_pk_mul_f32 v[148:149], v[56:57], v[134:135] op_sel:[0,1] op_sel_hi:[1,0]
	v_pk_fma_f32 v[160:161], v[46:47], v[152:153], v[160:161] op_sel_hi:[0,1,1]
	v_pk_mul_f32 v[164:165], v[56:57], v[152:153] op_sel:[0,1] op_sel_hi:[1,0]
	v_pk_fma_f32 v[44:45], v[184:185], v[46:47], v[44:45] op_sel_hi:[1,0,1]
	s_waitcnt lgkmcnt(7)
	v_pk_mul_f32 v[46:47], v[56:57], v[228:229] op_sel:[0,1] op_sel_hi:[1,0]
	v_xor_b32_e32 v60, 0x80000000, v59
	v_xor_b32_e32 v64, 0x80000000, v63
	v_xor_b32_e32 v68, 0x80000000, v67
	v_xor_b32_e32 v72, 0x80000000, v71
	v_pk_fma_f32 v[82:83], v[48:49], v[70:71], v[82:83] op_sel_hi:[0,1,1]
	v_pk_fma_f32 v[98:99], v[48:49], v[86:87], v[98:99] op_sel_hi:[0,1,1]
	v_pk_fma_f32 v[114:115], v[48:49], v[102:103], v[114:115] op_sel_hi:[0,1,1]
	v_pk_fma_f32 v[130:131], v[48:49], v[118:119], v[130:131] op_sel_hi:[0,1,1]
	v_pk_fma_f32 v[148:149], v[48:49], v[134:135], v[148:149] op_sel_hi:[0,1,1]
	v_pk_fma_f32 v[164:165], v[48:49], v[152:153], v[164:165] op_sel_hi:[0,1,1]
	v_mov_b32_e32 v61, v59
	v_mov_b32_e32 v65, v63
	v_mov_b32_e32 v69, v67
	v_mov_b32_e32 v73, v71
	v_pk_fma_f32 v[46:47], v[48:49], v[228:229], v[46:47] op_sel_hi:[0,1,1]
	v_pk_mul_f32 v[48:49], v[176:177], v[54:55] op_sel:[1,0] op_sel_hi:[0,1]
	v_xor_b32_e32 v76, 0x80000000, v75
	v_xor_b32_e32 v80, 0x80000000, v79
	v_xor_b32_e32 v84, 0x80000000, v83
	v_xor_b32_e32 v88, 0x80000000, v87
	v_xor_b32_e32 v92, 0x80000000, v91
	v_xor_b32_e32 v96, 0x80000000, v95
	v_xor_b32_e32 v100, 0x80000000, v99
	v_xor_b32_e32 v104, 0x80000000, v103
	v_xor_b32_e32 v136, 0x80000000, v135
	v_mov_b32_e32 v77, v75
	v_mov_b32_e32 v81, v79
	v_mov_b32_e32 v85, v83
	v_mov_b32_e32 v89, v87
	v_mov_b32_e32 v93, v91
	v_mov_b32_e32 v97, v95
	v_mov_b32_e32 v101, v99
	v_mov_b32_e32 v105, v103
	v_mov_b32_e32 v137, v135
	v_pk_fma_f32 v[48:49], v[176:177], v[52:53], v[48:49] op_sel_hi:[1,0,1]
	v_pk_mul_f32 v[50:51], v[60:61], v[220:221] op_sel:[0,1] op_sel_hi:[1,0]
	v_pk_mul_f32 v[52:53], v[192:193], v[64:65] op_sel:[1,0] op_sel_hi:[0,1]
	s_waitcnt lgkmcnt(3)
	v_pk_mul_f32 v[54:55], v[68:69], v[236:237] op_sel:[0,1] op_sel_hi:[1,0]
	v_pk_mul_f32 v[56:57], v[172:173], v[72:73] op_sel:[1,0] op_sel_hi:[0,1]
	v_xor_b32_e32 v108, 0x80000000, v107
	v_xor_b32_e32 v112, 0x80000000, v111
	v_xor_b32_e32 v116, 0x80000000, v115
	v_xor_b32_e32 v120, 0x80000000, v119
	v_xor_b32_e32 v124, 0x80000000, v123
	v_xor_b32_e32 v128, 0x80000000, v127
	v_xor_b32_e32 v132, 0x80000000, v131
	v_xor_b32_e32 v140, 0x80000000, v139
	v_xor_b32_e32 v144, 0x80000000, v143
	v_xor_b32_e32 v150, 0x80000000, v149
	v_xor_b32_e32 v154, 0x80000000, v153
	v_xor_b32_e32 v158, 0x80000000, v157
	v_xor_b32_e32 v162, 0x80000000, v161
	v_xor_b32_e32 v166, 0x80000000, v165
	v_mov_b32_e32 v109, v107
	v_mov_b32_e32 v113, v111
	v_mov_b32_e32 v117, v115
	v_mov_b32_e32 v121, v119
	v_mov_b32_e32 v125, v123
	v_mov_b32_e32 v129, v127
	v_mov_b32_e32 v133, v131
	v_mov_b32_e32 v141, v139
	v_mov_b32_e32 v145, v143
	v_mov_b32_e32 v151, v149
	v_mov_b32_e32 v155, v153
	v_mov_b32_e32 v159, v157
	v_mov_b32_e32 v163, v161
	v_mov_b32_e32 v167, v165
	v_pk_fma_f32 v[50:51], v[58:59], v[220:221], v[50:51] op_sel_hi:[0,1,1]
	v_pk_fma_f32 v[52:53], v[192:193], v[62:63], v[52:53] op_sel_hi:[1,0,1]
	v_pk_fma_f32 v[54:55], v[66:67], v[236:237], v[54:55] op_sel_hi:[0,1,1]
	v_pk_fma_f32 v[56:57], v[172:173], v[70:71], v[56:57] op_sel_hi:[1,0,1]
	v_pk_mul_f32 v[58:59], v[216:217], v[76:77] op_sel:[1,0] op_sel_hi:[0,1]
	v_pk_mul_f32 v[60:61], v[188:189], v[80:81] op_sel:[1,0] op_sel_hi:[0,1]
	v_pk_mul_f32 v[62:63], v[84:85], v[232:233] op_sel:[0,1] op_sel_hi:[1,0]
	v_pk_mul_f32 v[64:65], v[180:181], v[88:89] op_sel:[1,0] op_sel_hi:[0,1]
	v_pk_mul_f32 v[66:67], v[224:225], v[92:93] op_sel:[1,0] op_sel_hi:[0,1]
	v_pk_mul_f32 v[68:69], v[196:197], v[96:97] op_sel:[1,0] op_sel_hi:[0,1]
	s_waitcnt lgkmcnt(1)
	v_pk_mul_f32 v[70:71], v[100:101], v[240:241] op_sel:[0,1] op_sel_hi:[1,0]
	v_pk_mul_f32 v[72:73], v[170:171], v[104:105] op_sel:[1,0] op_sel_hi:[0,1]
	v_pk_mul_f32 v[88:89], v[174:175], v[136:137] op_sel:[1,0] op_sel_hi:[0,1]
	v_pk_fma_f32 v[58:59], v[216:217], v[74:75], v[58:59] op_sel_hi:[1,0,1]
	v_pk_fma_f32 v[60:61], v[188:189], v[78:79], v[60:61] op_sel_hi:[1,0,1]
	v_pk_fma_f32 v[62:63], v[82:83], v[232:233], v[62:63] op_sel_hi:[0,1,1]
	v_pk_fma_f32 v[64:65], v[180:181], v[86:87], v[64:65] op_sel_hi:[1,0,1]
	v_pk_fma_f32 v[66:67], v[224:225], v[90:91], v[66:67] op_sel_hi:[1,0,1]
	v_pk_fma_f32 v[68:69], v[196:197], v[94:95], v[68:69] op_sel_hi:[1,0,1]
	v_pk_fma_f32 v[70:71], v[98:99], v[240:241], v[70:71] op_sel_hi:[0,1,1]
	v_pk_fma_f32 v[72:73], v[170:171], v[102:103], v[72:73] op_sel_hi:[1,0,1]
	v_pk_mul_f32 v[74:75], v[214:215], v[108:109] op_sel:[1,0] op_sel_hi:[0,1]
	v_pk_mul_f32 v[76:77], v[186:187], v[112:113] op_sel:[1,0] op_sel_hi:[0,1]
	v_pk_mul_f32 v[78:79], v[230:231], v[116:117] op_sel:[1,0] op_sel_hi:[0,1]
	v_pk_mul_f32 v[80:81], v[178:179], v[120:121] op_sel:[1,0] op_sel_hi:[0,1]
	v_pk_mul_f32 v[82:83], v[222:223], v[124:125] op_sel:[1,0] op_sel_hi:[0,1]
	v_pk_mul_f32 v[84:85], v[194:195], v[128:129] op_sel:[1,0] op_sel_hi:[0,1]
	v_pk_mul_f32 v[86:87], v[132:133], v[238:239] op_sel:[0,1] op_sel_hi:[1,0]
	v_pk_fma_f32 v[88:89], v[174:175], v[134:135], v[88:89] op_sel_hi:[1,0,1]
	v_pk_mul_f32 v[90:91], v[218:219], v[140:141] op_sel:[1,0] op_sel_hi:[0,1]
	v_pk_mul_f32 v[92:93], v[190:191], v[144:145] op_sel:[1,0] op_sel_hi:[0,1]
	v_pk_mul_f32 v[94:95], v[234:235], v[150:151] op_sel:[1,0] op_sel_hi:[0,1]
	v_pk_mul_f32 v[96:97], v[182:183], v[154:155] op_sel:[1,0] op_sel_hi:[0,1]
	v_pk_mul_f32 v[98:99], v[226:227], v[158:159] op_sel:[1,0] op_sel_hi:[0,1]
	v_pk_mul_f32 v[100:101], v[198:199], v[162:163] op_sel:[1,0] op_sel_hi:[0,1]
	s_waitcnt lgkmcnt(0)
	v_pk_mul_f32 v[102:103], v[242:243], v[166:167] op_sel:[1,0] op_sel_hi:[0,1]
	v_pk_fma_f32 v[74:75], v[214:215], v[106:107], v[74:75] op_sel_hi:[1,0,1]
	v_pk_fma_f32 v[76:77], v[186:187], v[110:111], v[76:77] op_sel_hi:[1,0,1]
	v_pk_fma_f32 v[78:79], v[230:231], v[114:115], v[78:79] op_sel_hi:[1,0,1]
	v_pk_fma_f32 v[80:81], v[178:179], v[118:119], v[80:81] op_sel_hi:[1,0,1]
	v_pk_fma_f32 v[82:83], v[222:223], v[122:123], v[82:83] op_sel_hi:[1,0,1]
	v_pk_fma_f32 v[84:85], v[194:195], v[126:127], v[84:85] op_sel_hi:[1,0,1]
	v_pk_fma_f32 v[86:87], v[130:131], v[238:239], v[86:87] op_sel_hi:[0,1,1]
	v_pk_fma_f32 v[90:91], v[218:219], v[138:139], v[90:91] op_sel_hi:[1,0,1]
	v_pk_fma_f32 v[92:93], v[190:191], v[142:143], v[92:93] op_sel_hi:[1,0,1]
	v_pk_fma_f32 v[94:95], v[234:235], v[148:149], v[94:95] op_sel_hi:[1,0,1]
	v_pk_fma_f32 v[96:97], v[182:183], v[152:153], v[96:97] op_sel_hi:[1,0,1]
	v_pk_fma_f32 v[98:99], v[226:227], v[156:157], v[98:99] op_sel_hi:[1,0,1]
	v_pk_fma_f32 v[100:101], v[198:199], v[160:161], v[100:101] op_sel_hi:[1,0,1]
	v_pk_fma_f32 v[102:103], v[242:243], v[164:165], v[102:103] op_sel_hi:[1,0,1]
	v_pk_add_f32 v[104:105], v[168:169], v[72:73]
	v_pk_add_f32 v[106:107], v[56:57], v[88:89]
	v_pk_add_f32 v[56:57], v[56:57], v[88:89] neg_lo:[0,1] neg_hi:[0,1]
	v_pk_add_f32 v[72:73], v[168:169], v[72:73] neg_lo:[0,1] neg_hi:[0,1]
	v_pk_add_f32 v[88:89], v[48:49], v[80:81]
	v_pk_add_f32 v[48:49], v[48:49], v[80:81] neg_lo:[0,1] neg_hi:[0,1]
	v_pk_add_f32 v[80:81], v[64:65], v[96:97]
	v_pk_add_f32 v[64:65], v[64:65], v[96:97] neg_lo:[0,1] neg_hi:[0,1]
	v_pk_add_f32 v[96:97], v[44:45], v[76:77]
	v_pk_add_f32 v[44:45], v[44:45], v[76:77] neg_lo:[0,1] neg_hi:[0,1]
	v_pk_add_f32 v[76:77], v[60:61], v[92:93]
	v_pk_add_f32 v[60:61], v[60:61], v[92:93] neg_lo:[0,1] neg_hi:[0,1]
	v_pk_add_f32 v[92:93], v[52:53], v[84:85]
	v_pk_add_f32 v[52:53], v[52:53], v[84:85] neg_lo:[0,1] neg_hi:[0,1]
	v_pk_add_f32 v[84:85], v[68:69], v[100:101]
	v_pk_add_f32 v[68:69], v[68:69], v[100:101] neg_lo:[0,1] neg_hi:[0,1]
	v_pk_add_f32 v[100:101], v[42:43], v[74:75]
	v_pk_add_f32 v[42:43], v[42:43], v[74:75] neg_lo:[0,1] neg_hi:[0,1]
	v_pk_add_f32 v[74:75], v[58:59], v[90:91]
	v_pk_add_f32 v[58:59], v[58:59], v[90:91] neg_lo:[0,1] neg_hi:[0,1]
	v_pk_add_f32 v[90:91], v[50:51], v[82:83]
	v_pk_add_f32 v[50:51], v[50:51], v[82:83] neg_lo:[0,1] neg_hi:[0,1]
	v_pk_add_f32 v[82:83], v[66:67], v[98:99]
	v_pk_add_f32 v[66:67], v[66:67], v[98:99] neg_lo:[0,1] neg_hi:[0,1]
	v_pk_add_f32 v[98:99], v[46:47], v[78:79]
	v_pk_add_f32 v[46:47], v[46:47], v[78:79] neg_lo:[0,1] neg_hi:[0,1]
	v_pk_add_f32 v[78:79], v[62:63], v[94:95]
	v_pk_add_f32 v[62:63], v[62:63], v[94:95] neg_lo:[0,1] neg_hi:[0,1]
	v_pk_add_f32 v[94:95], v[54:55], v[86:87]
	v_pk_add_f32 v[54:55], v[54:55], v[86:87] neg_lo:[0,1] neg_hi:[0,1]
	v_pk_add_f32 v[86:87], v[70:71], v[102:103]
	v_pk_add_f32 v[70:71], v[70:71], v[102:103] neg_lo:[0,1] neg_hi:[0,1]
	v_pk_add_f32 v[102:103], v[104:105], v[106:107]
	v_pk_add_f32 v[104:105], v[104:105], v[106:107] neg_lo:[0,1] neg_hi:[0,1]
	v_pk_mul_f32 v[106:107], v[56:57], 1.0 op_sel:[1,0] op_sel_hi:[0,0] neg_lo:[1,0]
	v_pk_add_f32 v[56:57], v[72:73], v[106:107]
	v_pk_add_f32 v[72:73], v[72:73], v[106:107] neg_lo:[0,1] neg_hi:[0,1]
	v_pk_add_f32 v[106:107], v[88:89], v[80:81]
	v_pk_add_f32 v[80:81], v[88:89], v[80:81] neg_lo:[0,1] neg_hi:[0,1]
	v_pk_mul_f32 v[88:89], v[64:65], 1.0 op_sel:[1,0] op_sel_hi:[0,0] neg_lo:[1,0]
	v_pk_add_f32 v[64:65], v[48:49], v[88:89]
	v_pk_add_f32 v[48:49], v[48:49], v[88:89] neg_lo:[0,1] neg_hi:[0,1]
	v_pk_add_f32 v[88:89], v[96:97], v[76:77]
	v_pk_add_f32 v[76:77], v[96:97], v[76:77] neg_lo:[0,1] neg_hi:[0,1]
	v_pk_mul_f32 v[96:97], v[60:61], 1.0 op_sel:[1,0] op_sel_hi:[0,0] neg_lo:[1,0]
	v_pk_add_f32 v[60:61], v[44:45], v[96:97]
	v_pk_add_f32 v[44:45], v[44:45], v[96:97] neg_lo:[0,1] neg_hi:[0,1]
	v_pk_add_f32 v[96:97], v[92:93], v[84:85]
	v_pk_add_f32 v[84:85], v[92:93], v[84:85] neg_lo:[0,1] neg_hi:[0,1]
	v_pk_mul_f32 v[92:93], v[68:69], 1.0 op_sel:[1,0] op_sel_hi:[0,0] neg_lo:[1,0]
	v_pk_add_f32 v[68:69], v[52:53], v[92:93]
	v_pk_add_f32 v[52:53], v[52:53], v[92:93] neg_lo:[0,1] neg_hi:[0,1]
	v_pk_add_f32 v[92:93], v[100:101], v[74:75]
	v_pk_add_f32 v[74:75], v[100:101], v[74:75] neg_lo:[0,1] neg_hi:[0,1]
	v_pk_mul_f32 v[100:101], v[58:59], 1.0 op_sel:[1,0] op_sel_hi:[0,0] neg_lo:[1,0]
	v_pk_add_f32 v[58:59], v[42:43], v[100:101]
	v_pk_add_f32 v[42:43], v[42:43], v[100:101] neg_lo:[0,1] neg_hi:[0,1]
	v_pk_add_f32 v[100:101], v[90:91], v[82:83]
	v_pk_add_f32 v[82:83], v[90:91], v[82:83] neg_lo:[0,1] neg_hi:[0,1]
	v_pk_mul_f32 v[90:91], v[66:67], 1.0 op_sel:[1,0] op_sel_hi:[0,0] neg_lo:[1,0]
	v_pk_add_f32 v[66:67], v[50:51], v[90:91]
	v_pk_add_f32 v[50:51], v[50:51], v[90:91] neg_lo:[0,1] neg_hi:[0,1]
	v_pk_add_f32 v[90:91], v[98:99], v[78:79]
	v_pk_add_f32 v[78:79], v[98:99], v[78:79] neg_lo:[0,1] neg_hi:[0,1]
	v_pk_mul_f32 v[98:99], v[62:63], 1.0 op_sel:[1,0] op_sel_hi:[0,0] neg_lo:[1,0]
	v_pk_add_f32 v[62:63], v[46:47], v[98:99]
	v_pk_add_f32 v[46:47], v[46:47], v[98:99] neg_lo:[0,1] neg_hi:[0,1]
	v_pk_add_f32 v[98:99], v[94:95], v[86:87]
	v_pk_add_f32 v[86:87], v[94:95], v[86:87] neg_lo:[0,1] neg_hi:[0,1]
	v_pk_mul_f32 v[94:95], v[70:71], 1.0 op_sel:[1,0] op_sel_hi:[0,0] neg_lo:[1,0]
	s_mov_b32 s63, s36
	v_pk_add_f32 v[70:71], v[54:55], v[94:95]
	v_pk_add_f32 v[54:55], v[54:55], v[94:95] neg_lo:[0,1] neg_hi:[0,1]
	v_pk_add_f32 v[94:95], v[102:103], v[106:107]
	v_pk_add_f32 v[102:103], v[102:103], v[106:107] neg_lo:[0,1] neg_hi:[0,1]
	s_mov_b32 s0, s37
	v_pk_mul_f32 v[106:107], v[64:65], s[62:63]
	s_mov_b32 s64, s19
	v_pk_fma_f32 v[64:65], v[64:65], s[0:1], v[106:107] op_sel:[0,0,1] op_sel_hi:[1,0,0]
	s_mov_b32 s65, s18
	v_pk_add_f32 v[106:107], v[56:57], v[64:65]
	v_pk_add_f32 v[56:57], v[56:57], v[64:65] neg_lo:[0,1] neg_hi:[0,1]
	v_pk_mul_f32 v[64:65], v[80:81], 1.0 op_sel:[1,0] op_sel_hi:[0,0] neg_lo:[1,0]
	s_nop 0
	v_pk_add_f32 v[80:81], v[104:105], v[64:65]
	v_pk_add_f32 v[64:65], v[104:105], v[64:65] neg_lo:[0,1] neg_hi:[0,1]
	v_pk_mul_f32 v[104:105], v[48:49], s[62:63]
	s_mov_b32 s66, s19
	v_pk_fma_f32 v[48:49], v[48:49], s[0:1], v[104:105] op_sel:[0,0,1] op_sel_hi:[1,0,0] neg_lo:[1,0,0] neg_hi:[1,0,0]
	s_mov_b32 s68, s11
	v_pk_add_f32 v[104:105], v[72:73], v[48:49]
	v_pk_add_f32 v[48:49], v[72:73], v[48:49] neg_lo:[0,1] neg_hi:[0,1]
	v_pk_add_f32 v[72:73], v[88:89], v[96:97]
	v_pk_add_f32 v[88:89], v[88:89], v[96:97] neg_lo:[0,1] neg_hi:[0,1]
	v_pk_mul_f32 v[96:97], v[68:69], s[62:63]
	s_mov_b32 s69, s10
	v_pk_fma_f32 v[68:69], v[68:69], s[0:1], v[96:97] op_sel:[0,0,1] op_sel_hi:[1,0,0]
	s_mov_b32 s72, s27
	v_pk_add_f32 v[96:97], v[60:61], v[68:69]
	v_pk_add_f32 v[60:61], v[60:61], v[68:69] neg_lo:[0,1] neg_hi:[0,1]
	v_pk_mul_f32 v[68:69], v[84:85], 1.0 op_sel:[1,0] op_sel_hi:[0,0] neg_lo:[1,0]
	s_nop 0
	v_pk_add_f32 v[84:85], v[76:77], v[68:69]
	v_pk_add_f32 v[68:69], v[76:77], v[68:69] neg_lo:[0,1] neg_hi:[0,1]
	v_pk_mul_f32 v[76:77], v[52:53], s[62:63]
	v_pk_mul_f32 v[108:109], v[96:97], s[64:65]
	v_pk_fma_f32 v[52:53], v[52:53], s[0:1], v[76:77] op_sel:[0,0,1] op_sel_hi:[1,0,0] neg_lo:[1,0,0] neg_hi:[1,0,0]
	v_pk_fma_f32 v[96:97], v[96:97], s[16:17], v[108:109] op_sel:[0,0,1] op_sel_hi:[1,0,0]
	v_pk_add_f32 v[76:77], v[44:45], v[52:53]
	v_pk_add_f32 v[44:45], v[44:45], v[52:53] neg_lo:[0,1] neg_hi:[0,1]
	v_pk_add_f32 v[52:53], v[92:93], v[100:101]
	v_pk_add_f32 v[92:93], v[92:93], v[100:101] neg_lo:[0,1] neg_hi:[0,1]
	v_pk_mul_f32 v[100:101], v[66:67], s[62:63]
	s_mov_b32 s17, s40
	v_pk_fma_f32 v[66:67], v[66:67], s[0:1], v[100:101] op_sel:[0,0,1] op_sel_hi:[1,0,0]
	v_pk_add_f32 v[108:109], v[106:107], v[96:97]
	v_pk_add_f32 v[100:101], v[58:59], v[66:67]
	v_pk_add_f32 v[58:59], v[58:59], v[66:67] neg_lo:[0,1] neg_hi:[0,1]
	v_pk_mul_f32 v[66:67], v[82:83], 1.0 op_sel:[1,0] op_sel_hi:[0,0] neg_lo:[1,0]
	v_pk_add_f32 v[82:83], v[74:75], v[66:67]
	v_pk_add_f32 v[66:67], v[74:75], v[66:67] neg_lo:[0,1] neg_hi:[0,1]
	v_pk_mul_f32 v[74:75], v[50:51], s[62:63]
	v_pk_add_f32 v[96:97], v[106:107], v[96:97] neg_lo:[0,1] neg_hi:[0,1]
	v_pk_fma_f32 v[50:51], v[50:51], s[0:1], v[74:75] op_sel:[0,0,1] op_sel_hi:[1,0,0] neg_lo:[1,0,0] neg_hi:[1,0,0]
	v_pk_mul_f32 v[106:107], v[84:85], s[62:63]
	v_pk_add_f32 v[74:75], v[42:43], v[50:51]
	v_pk_add_f32 v[42:43], v[42:43], v[50:51] neg_lo:[0,1] neg_hi:[0,1]
	v_pk_add_f32 v[50:51], v[90:91], v[98:99]
	v_pk_add_f32 v[90:91], v[90:91], v[98:99] neg_lo:[0,1] neg_hi:[0,1]
	v_pk_mul_f32 v[98:99], v[70:71], s[62:63]
	v_pk_fma_f32 v[84:85], v[84:85], s[0:1], v[106:107] op_sel:[0,0,1] op_sel_hi:[1,0,0]
	v_pk_fma_f32 v[70:71], v[70:71], s[0:1], v[98:99] op_sel:[0,0,1] op_sel_hi:[1,0,0]
	v_pk_add_f32 v[106:107], v[80:81], v[84:85]
	v_pk_add_f32 v[98:99], v[62:63], v[70:71]
	v_pk_add_f32 v[62:63], v[62:63], v[70:71] neg_lo:[0,1] neg_hi:[0,1]
	v_pk_mul_f32 v[70:71], v[86:87], 1.0 op_sel:[1,0] op_sel_hi:[0,0] neg_lo:[1,0]
	v_pk_mul_f32 v[110:111], v[98:99], s[64:65]
	v_pk_add_f32 v[86:87], v[78:79], v[70:71]
	v_pk_add_f32 v[70:71], v[78:79], v[70:71] neg_lo:[0,1] neg_hi:[0,1]
	v_pk_mul_f32 v[78:79], v[54:55], s[62:63]
	v_pk_fma_f32 v[98:99], v[98:99], s[16:17], v[110:111] op_sel:[0,0,1] op_sel_hi:[1,0,0]
	v_pk_fma_f32 v[54:55], v[54:55], s[0:1], v[78:79] op_sel:[0,0,1] op_sel_hi:[1,0,0] neg_lo:[1,0,0] neg_hi:[1,0,0]
	v_pk_add_f32 v[110:111], v[100:101], v[98:99]
	v_pk_add_f32 v[98:99], v[100:101], v[98:99] neg_lo:[0,1] neg_hi:[0,1]
	v_pk_mul_f32 v[100:101], v[86:87], s[62:63]
	v_pk_add_f32 v[78:79], v[46:47], v[54:55]
	v_pk_fma_f32 v[86:87], v[86:87], s[0:1], v[100:101] op_sel:[0,0,1] op_sel_hi:[1,0,0]
	v_pk_add_f32 v[46:47], v[46:47], v[54:55] neg_lo:[0,1] neg_hi:[0,1]
	v_pk_add_f32 v[100:101], v[82:83], v[86:87]
	v_pk_add_f32 v[82:83], v[82:83], v[86:87] neg_lo:[0,1] neg_hi:[0,1]
	v_pk_mul_f32 v[86:87], v[78:79], s[16:17]
	v_pk_add_f32 v[80:81], v[80:81], v[84:85] neg_lo:[0,1] neg_hi:[0,1]
	v_pk_fma_f32 v[78:79], v[78:79], s[66:67], v[86:87] op_sel:[0,0,1] op_sel_hi:[1,0,0]
	v_pk_mul_f32 v[84:85], v[76:77], s[16:17]
	v_pk_add_f32 v[86:87], v[74:75], v[78:79]
	v_pk_add_f32 v[74:75], v[74:75], v[78:79] neg_lo:[0,1] neg_hi:[0,1]
	v_pk_mul_f32 v[78:79], v[90:91], 1.0 op_sel:[1,0] op_sel_hi:[0,0] neg_lo:[1,0]
	v_pk_add_f32 v[90:91], v[92:93], v[78:79]
	v_pk_add_f32 v[78:79], v[92:93], v[78:79] neg_lo:[0,1] neg_hi:[0,1]
	v_pk_mul_f32 v[92:93], v[62:63], s[16:17]
	v_pk_fma_f32 v[76:77], v[76:77], s[66:67], v[84:85] op_sel:[0,0,1] op_sel_hi:[1,0,0]
	v_pk_fma_f32 v[62:63], v[62:63], s[66:67], v[92:93] op_sel:[0,0,1] op_sel_hi:[1,0,0] neg_lo:[1,0,0] neg_hi:[1,0,0]
	v_pk_add_f32 v[84:85], v[104:105], v[76:77]
	v_pk_add_f32 v[92:93], v[58:59], v[62:63]
	v_pk_add_f32 v[58:59], v[58:59], v[62:63] neg_lo:[0,1] neg_hi:[0,1]
	v_pk_mul_f32 v[62:63], v[70:71], s[62:63]
	v_pk_add_f32 v[76:77], v[104:105], v[76:77] neg_lo:[0,1] neg_hi:[0,1]
	v_pk_fma_f32 v[62:63], v[70:71], s[0:1], v[62:63] op_sel:[0,0,1] op_sel_hi:[1,0,0] neg_lo:[1,0,0] neg_hi:[1,0,0]
	v_pk_mul_f32 v[104:105], v[88:89], 1.0 op_sel:[1,0] op_sel_hi:[0,0] neg_lo:[1,0]
	v_pk_add_f32 v[70:71], v[66:67], v[62:63]
	v_pk_add_f32 v[62:63], v[66:67], v[62:63] neg_lo:[0,1] neg_hi:[0,1]
	v_pk_mul_f32 v[66:67], v[46:47], s[64:65]
	s_nop 0
	v_pk_fma_f32 v[46:47], v[46:47], s[16:17], v[66:67] op_sel:[0,0,1] op_sel_hi:[1,0,0] neg_lo:[1,0,0] neg_hi:[1,0,0]
	s_mov_b32 s73, s26
	v_pk_add_f32 v[66:67], v[42:43], v[46:47]
	v_pk_add_f32 v[42:43], v[42:43], v[46:47] neg_lo:[0,1] neg_hi:[0,1]
	v_pk_mul_f32 v[46:47], v[110:111], s[68:69]
	v_pk_add_f32 v[88:89], v[102:103], v[104:105]
	v_pk_fma_f32 v[46:47], v[110:111], s[8:9], v[46:47] op_sel:[0,0,1] op_sel_hi:[1,0,0]
	v_pk_add_f32 v[102:103], v[102:103], v[104:105] neg_lo:[0,1] neg_hi:[0,1]
	v_pk_add_f32 v[46:47], v[108:109], v[46:47]
	v_pk_mul_f32 v[108:109], v[100:101], s[64:65]
	v_pk_mul_f32 v[104:105], v[60:61], s[16:17]
	v_pk_fma_f32 v[100:101], v[100:101], s[16:17], v[108:109] op_sel:[0,0,1] op_sel_hi:[1,0,0]
	v_pk_fma_f32 v[60:61], v[60:61], s[66:67], v[104:105] op_sel:[0,0,1] op_sel_hi:[1,0,0] neg_lo:[1,0,0] neg_hi:[1,0,0]
	v_pk_add_f32 v[100:101], v[106:107], v[100:101]
	v_pk_mul_f32 v[106:107], v[86:87], s[72:73]
	v_pk_add_f32 v[104:105], v[56:57], v[60:61]
	v_pk_fma_f32 v[86:87], v[86:87], s[24:25], v[106:107] op_sel:[0,0,1] op_sel_hi:[1,0,0]
	v_pk_add_f32 v[56:57], v[56:57], v[60:61] neg_lo:[0,1] neg_hi:[0,1]
	v_pk_mul_f32 v[60:61], v[68:69], s[62:63]
	v_pk_add_f32 v[84:85], v[84:85], v[86:87]
	v_pk_mul_f32 v[86:87], v[90:91], s[62:63]
	v_pk_fma_f32 v[60:61], v[68:69], s[0:1], v[60:61] op_sel:[0,0,1] op_sel_hi:[1,0,0] neg_lo:[1,0,0] neg_hi:[1,0,0]
	v_pk_fma_f32 v[86:87], v[90:91], s[0:1], v[86:87] op_sel:[0,0,1] op_sel_hi:[1,0,0]
	v_pk_mul_f32 v[90:91], v[70:71], s[16:17]
	v_pk_add_f32 v[68:69], v[64:65], v[60:61]
	v_pk_fma_f32 v[70:71], v[70:71], s[66:67], v[90:91] op_sel:[0,0,1] op_sel_hi:[1,0,0]
	s_mov_b32 s9, s42
	s_mov_b32 s25, s38
	v_pk_add_f32 v[68:69], v[68:69], v[70:71]
	s_mov_b32 s76, s11
	v_pk_mul_f32 v[70:71], v[66:67], s[8:9]
	s_mov_b32 s74, s27
	v_pk_fma_f32 v[66:67], v[66:67], s[76:77], v[70:71] op_sel:[0,0,1] op_sel_hi:[1,0,0]
	v_pk_mul_f32 v[70:71], v[74:75], s[24:25]
	v_pk_add_f32 v[60:61], v[64:65], v[60:61] neg_lo:[0,1] neg_hi:[0,1]
	v_pk_fma_f32 v[70:71], v[74:75], s[74:75], v[70:71] op_sel:[0,0,1] op_sel_hi:[1,0,0] neg_lo:[1,0,0] neg_hi:[1,0,0]
	v_pk_mul_f32 v[64:65], v[44:45], s[64:65]
	v_pk_add_f32 v[70:71], v[76:77], v[70:71]
	v_pk_mul_f32 v[76:77], v[58:59], s[72:73]
	v_pk_fma_f32 v[44:45], v[44:45], s[16:17], v[64:65] op_sel:[0,0,1] op_sel_hi:[1,0,0] neg_lo:[1,0,0] neg_hi:[1,0,0]
	v_pk_fma_f32 v[58:59], v[58:59], s[24:25], v[76:77] op_sel:[0,0,1] op_sel_hi:[1,0,0] neg_lo:[1,0,0] neg_hi:[1,0,0]
	v_pk_add_f32 v[64:65], v[48:49], v[44:45]
	v_pk_add_f32 v[56:57], v[56:57], v[58:59]
	v_pk_mul_f32 v[58:59], v[62:63], s[64:65]
	v_pk_add_f32 v[44:45], v[48:49], v[44:45] neg_lo:[0,1] neg_hi:[0,1]
	v_pk_fma_f32 v[58:59], s[16:17], v[62:63], v[58:59] op_sel:[0,0,1] op_sel_hi:[0,1,0] neg_lo:[0,1,0] neg_hi:[0,1,0]
	v_pk_add_f32 v[58:59], v[60:61], v[58:59]
	v_pk_mul_f32 v[60:61], v[42:43], s[68:69]
	v_pk_add_f32 v[54:55], v[94:95], v[72:73] neg_lo:[0,1] neg_hi:[0,1]
	v_pk_add_f32 v[64:65], v[64:65], v[66:67]
	v_pk_add_f32 v[66:67], v[52:53], v[50:51] neg_lo:[0,1] neg_hi:[0,1]
	v_pk_fma_f32 v[42:43], v[42:43], s[8:9], v[60:61] op_sel:[0,0,1] op_sel_hi:[1,0,0] neg_lo:[1,0,0] neg_hi:[1,0,0]
	v_pk_add_f32 v[86:87], v[88:89], v[86:87]
	v_pk_mul_f32 v[88:89], v[92:93], s[24:25]
	v_pk_add_f32 v[48:49], v[54:55], v[66:67] op_sel:[0,1] op_sel_hi:[1,0] neg_lo:[0,1]
	v_pk_mul_f32 v[54:55], v[98:99], s[8:9]
	v_pk_mul_f32 v[66:67], v[82:83], s[16:17]
	v_pk_mul_f32 v[74:75], v[78:79], s[62:63]
	v_pk_add_f32 v[42:43], v[44:45], v[42:43]
	v_pk_add_f32 v[44:45], v[94:95], v[72:73]
	v_pk_add_f32 v[50:51], v[52:53], v[50:51]
	v_pk_fma_f32 v[88:89], v[92:93], s[74:75], v[88:89] op_sel:[0,0,1] op_sel_hi:[1,0,0]
	v_pk_fma_f32 v[54:55], v[98:99], s[76:77], v[54:55] op_sel:[0,0,1] op_sel_hi:[1,0,0] neg_lo:[1,0,0] neg_hi:[1,0,0]
	v_pk_fma_f32 v[66:67], v[82:83], s[66:67], v[66:67] op_sel:[0,0,1] op_sel_hi:[1,0,0] neg_lo:[1,0,0] neg_hi:[1,0,0]
	v_pk_fma_f32 v[74:75], v[78:79], s[0:1], v[74:75] op_sel:[0,0,1] op_sel_hi:[1,0,0] neg_lo:[1,0,0] neg_hi:[1,0,0]
	v_pk_add_f32 v[44:45], v[44:45], v[50:51]
	v_lshl_add_u32 v21, v21, 3, v36
	v_pk_add_f32 v[88:89], v[104:105], v[88:89]
	v_pk_add_f32 v[54:55], v[96:97], v[54:55]
	v_pk_add_f32 v[66:67], v[80:81], v[66:67]
	v_pk_add_f32 v[74:75], v[102:103], v[74:75]
	ds_write_b64 v25, v[44:45]
	ds_write_b64 v25, v[46:47] offset:2112
	ds_write_b64 v25, v[100:101] offset:4224
	ds_write_b64 v25, v[84:85] offset:6336
	ds_write_b64 v25, v[86:87] offset:8448
	ds_write_b64 v25, v[88:89] offset:10560
	ds_write_b64 v25, v[68:69] offset:12672
	ds_write_b64 v25, v[64:65] offset:14784
	ds_write_b64 v25, v[48:49] offset:16896
	ds_write_b64 v25, v[54:55] offset:19008
	ds_write_b64 v25, v[66:67] offset:21120
	ds_write_b64 v25, v[70:71] offset:23232
	ds_write_b64 v25, v[74:75] offset:25344
	ds_write_b64 v25, v[56:57] offset:27456
	ds_write_b64 v25, v[58:59] offset:29568
	ds_write_b64 v25, v[42:43] offset:31680
	v_ashrrev_i32_e32 v25, 5, v21
	v_lshlrev_b32_e32 v21, 3, v21
	v_lshlrev_b32_e32 v25, 3, v25
	s_waitcnt vmcnt(0)
	v_lshlrev_b32_e32 v41, 16, v41
	v_lshlrev_b32_e32 v39, 16, v39
	v_lshlrev_b32_e32 v35, 16, v35
	v_lshlrev_b32_e32 v29, 16, v29
	v_and_b32_e32 v48, 0xffff0000, v14
	v_add3_u32 v21, 0, v21, v25
	v_mov_b32_e32 v40, v48
	s_waitcnt lgkmcnt(0)
	s_barrier
	v_pk_mul_f32 v[44:45], v[30:31], v[40:41]
	ds_read2_b64 v[40:43], v21 offset1:1
	v_lshlrev_b32_e32 v28, 16, v14
	v_lshlrev_b32_e32 v49, 16, v15
	v_pk_fma_f32 v[44:45], v[30:31], v[28:29], v[44:45] op_sel:[0,0,1] op_sel_hi:[1,0,0]
	v_mov_b32_e32 v28, v31
	v_pk_fma_f32 v[44:45], v[20:21], v[48:49], v[44:45] op_sel_hi:[0,1,1]
	v_pk_add_f32 v[50:51], v[24:25], v[44:45] op_sel_hi:[0,1]
	ds_read2_b64 v[44:47], v21 offset0:2 offset1:3
	s_waitcnt lgkmcnt(1)
	v_pk_mul_f32 v[40:41], v[50:51], v[40:41]
	v_and_b32_e32 v51, 16, v16
	v_and_b32_e32 v50, 0xffff0000, v15
	v_pk_mov_b32 v[14:15], v[48:49], v[50:51] op_sel:[1,0]
	v_lshlrev_b32_e32 v53, 16, v16
	v_pk_mul_f32 v[14:15], v[30:31], v[14:15] op_sel_hi:[0,1]
	v_mov_b32_e32 v52, v50
	v_pk_fma_f32 v[14:15], v[28:29], v[48:49], v[14:15] op_sel_hi:[0,1,1]
	v_pk_fma_f32 v[14:15], v[20:21], v[52:53], v[14:15] op_sel_hi:[0,1,1]
	v_pk_add_f32 v[14:15], v[24:25], v[14:15] op_sel_hi:[0,1]
	v_pk_mul_f32 v[14:15], v[14:15], v[42:43]
	v_and_b32_e32 v43, 16, v17
	v_and_b32_e32 v42, 0xffff0000, v16
	v_lshlrev_b32_e32 v49, 16, v17
	v_mov_b32_e32 v48, v42
	v_pk_mov_b32 v[42:43], v[52:53], v[42:43] op_sel:[1,0]
	v_pk_mov_b32 v[16:17], v[16:17], v[10:11] op_sel:[1,0]
	v_pk_mul_f32 v[42:43], v[30:31], v[42:43] op_sel_hi:[0,1]
	v_and_b32_e32 v17, 16, v17
	v_and_b32_e32 v16, 0xffff0000, v16
	v_pk_fma_f32 v[42:43], v[28:29], v[52:53], v[42:43] op_sel_hi:[0,1,1]
	v_mov_b32_e32 v50, v16
	v_pk_mov_b32 v[16:17], v[48:49], v[16:17] op_sel:[1,0]
	v_pk_fma_f32 v[42:43], v[20:21], v[48:49], v[42:43] op_sel_hi:[0,1,1]
	v_pk_mul_f32 v[16:17], v[30:31], v[16:17] op_sel_hi:[0,1]
	v_pk_add_f32 v[42:43], v[24:25], v[42:43] op_sel_hi:[0,1]
	v_lshlrev_b32_e32 v51, 16, v10
	v_pk_fma_f32 v[16:17], v[28:29], v[48:49], v[16:17] op_sel_hi:[0,1,1]
	s_waitcnt lgkmcnt(0)
	v_pk_mul_f32 v[42:43], v[42:43], v[44:45]
	v_pk_fma_f32 v[16:17], v[20:21], v[50:51], v[16:17] op_sel_hi:[0,1,1]
	v_and_b32_e32 v45, 16, v11
	v_and_b32_e32 v44, 0xffff0000, v10
	v_pk_add_f32 v[16:17], v[24:25], v[16:17] op_sel_hi:[0,1]
	v_mov_b32_e32 v52, v44
	v_pk_mov_b32 v[44:45], v[50:51], v[44:45] op_sel:[1,0]
	v_pk_mul_f32 v[16:17], v[16:17], v[46:47]
	v_pk_mul_f32 v[48:49], v[30:31], v[44:45] op_sel_hi:[0,1]
	ds_read2_b64 v[44:47], v21 offset0:4 offset1:5
	v_lshlrev_b32_e32 v53, 16, v11
	v_pk_fma_f32 v[48:49], v[28:29], v[50:51], v[48:49] op_sel_hi:[0,1,1]
	v_pk_fma_f32 v[48:49], v[20:21], v[52:53], v[48:49] op_sel_hi:[0,1,1]
	v_pk_add_f32 v[54:55], v[24:25], v[48:49] op_sel_hi:[0,1]
	ds_read2_b64 v[48:51], v21 offset0:6 offset1:7
	s_waitcnt lgkmcnt(1)
	v_pk_mul_f32 v[44:45], v[54:55], v[44:45]
	v_and_b32_e32 v55, 16, v12
	v_and_b32_e32 v54, 0xffff0000, v11
	v_pk_mov_b32 v[10:11], v[52:53], v[54:55] op_sel:[1,0]
	v_lshlrev_b32_e32 v57, 16, v12
	v_pk_mul_f32 v[10:11], v[30:31], v[10:11] op_sel_hi:[0,1]
	v_mov_b32_e32 v56, v54
	v_pk_fma_f32 v[10:11], v[28:29], v[52:53], v[10:11] op_sel_hi:[0,1,1]
	v_pk_fma_f32 v[10:11], v[20:21], v[56:57], v[10:11] op_sel_hi:[0,1,1]
	v_pk_add_f32 v[10:11], v[24:25], v[10:11] op_sel_hi:[0,1]
	v_and_b32_e32 v38, 0xffff0000, v13
	v_pk_mul_f32 v[10:11], v[10:11], v[46:47]
	v_and_b32_e32 v47, 16, v13
	v_and_b32_e32 v46, 0xffff0000, v12
	v_lshlrev_b32_e32 v53, 16, v13
	v_mov_b32_e32 v52, v46
	v_pk_mov_b32 v[12:13], v[56:57], v[46:47] op_sel:[1,0]
	v_mov_b32_e32 v46, v53
	v_mov_b32_e32 v47, v38
	v_pk_mul_f32 v[12:13], v[30:31], v[12:13] op_sel_hi:[0,1]
	v_pk_mul_f32 v[46:47], v[30:31], v[46:47] op_sel_hi:[0,1]
	v_pk_fma_f32 v[12:13], v[28:29], v[56:57], v[12:13] op_sel_hi:[0,1,1]
	v_pk_fma_f32 v[46:47], v[28:29], v[52:53], v[46:47] op_sel_hi:[0,1,1]
	v_pk_fma_f32 v[12:13], v[20:21], v[52:53], v[12:13] op_sel_hi:[0,1,1]
	v_pk_fma_f32 v[38:39], v[20:21], v[38:39], v[46:47] op_sel_hi:[0,1,1]
	s_xor_b64 s[50:51], s[50:51], -1
	v_pk_add_f32 v[12:13], v[24:25], v[12:13] op_sel_hi:[0,1]
	v_pk_add_f32 v[38:39], v[24:25], v[38:39] op_sel_hi:[0,1]
	s_waitcnt lgkmcnt(0)
	v_pk_mul_f32 v[12:13], v[12:13], v[48:49]
	v_pk_mul_f32 v[38:39], v[38:39], v[50:51]
	s_mov_b64 s[0:1], -1
	s_and_b64 vcc, exec, s[50:51]
	s_cbranch_vccz .LBB0_548
	v_bfe_u32 v46, v15, 16, 1
	v_add3_u32 v47, v15, v46, s4
	v_bfe_u32 v46, v14, 16, 1
	v_bfe_u32 v48, v16, 16, 1
	v_bfe_u32 v50, v42, 16, 1
	v_bfe_u32 v34, v17, 16, 1
	v_bfe_u32 v49, v40, 16, 1
	v_add3_u32 v50, v42, v50, s4
	v_add3_u32 v48, v16, v48, s4
	v_add3_u32 v46, v14, v46, s4
	v_bfe_u32 v25, v43, 16, 1
	v_bfe_u32 v28, v41, 16, 1
	v_add3_u32 v34, v17, v34, s4
	v_add3_u32 v49, v40, v49, s4
	v_lshrrev_b32_e32 v51, 16, v46
	v_lshrrev_b32_e32 v52, 16, v48
	v_lshrrev_b32_e32 v48, 16, v50
	v_bfe_u32 v50, v11, 16, 1
	v_add3_u32 v28, v41, v28, s4
	v_add3_u32 v25, v43, v25, s4
	v_lshrrev_b32_e32 v46, 16, v49
	v_and_or_b32 v49, v34, s91, v52
	v_and_or_b32 v47, v47, s91, v51
	v_add3_u32 v51, v11, v50, s4
	v_bfe_u32 v50, v10, 16, 1
	v_bfe_u32 v52, v38, 16, 1
	v_bfe_u32 v53, v44, 16, 1
	v_bfe_u32 v54, v12, 16, 1
	v_lshl_add_u64 v[36:37], v[36:37], 1, s[70:71]
	v_and_or_b32 v48, v25, s91, v48
	v_and_or_b32 v46, v28, s91, v46
	v_bfe_u32 v25, v13, 16, 1
	v_bfe_u32 v28, v45, 16, 1
	v_bfe_u32 v34, v39, 16, 1
	v_add3_u32 v54, v12, v54, s4
	v_add3_u32 v53, v44, v53, s4
	v_add3_u32 v52, v38, v52, s4
	v_add3_u32 v50, v10, v50, s4
	v_add3_u32 v34, v39, v34, s4
	v_add3_u32 v28, v45, v28, s4
	v_add3_u32 v25, v13, v25, s4
	v_lshrrev_b32_e32 v55, 16, v50
	v_lshrrev_b32_e32 v56, 16, v52
	v_lshrrev_b32_e32 v50, 16, v53
	v_lshrrev_b32_e32 v52, 16, v54
	v_lshl_add_u64 v[32:33], v[32:33], 1, v[36:37]
	v_and_or_b32 v52, v25, s91, v52
	v_and_or_b32 v50, v28, s91, v50
	v_and_or_b32 v53, v34, s91, v56
	v_and_or_b32 v51, v51, s91, v55
	global_store_dwordx4 v[32:33], v[46:49], off
	global_store_dwordx4 v[32:33], v[50:53], off offset:16
	s_mov_b64 s[0:1], 0

.LBB0_560:
	s_or_b64 exec, exec, s[0:1]
	v_mov_b32_e32 v2, v142
	s_waitcnt lgkmcnt(0)
	s_barrier
	s_mov_b32 s41, s38
	v_and_b32_e32 v4, 0x1ff, v2
	v_lshlrev_b32_e32 v2, 5, v2
	v_and_or_b32 v2, v2, s34, v4
	v_ashrrev_i32_e32 v6, 5, v2
	v_lshlrev_b32_e32 v2, 3, v2
	v_lshlrev_b32_e32 v7, 3, v6
	v_add3_u32 v2, 0, v2, v7
	v_add_u32_e32 v143, 0x10800, v2
	ds_read_b64 v[128:129], v2
	ds_read_b64 v[130:131], v2 offset:4224
	ds_read_b64 v[144:145], v2 offset:8448
	ds_read_b64 v[148:149], v2 offset:12672
	ds_read_b64 v[150:151], v2 offset:16896
	ds_read_b64 v[152:153], v2 offset:21120
	ds_read_b64 v[154:155], v2 offset:25344
	ds_read_b64 v[156:157], v2 offset:29568
	ds_read_b64 v[158:159], v2 offset:33792
	ds_read_b64 v[160:161], v2 offset:38016
	ds_read_b64 v[162:163], v2 offset:42240
	ds_read_b64 v[164:165], v2 offset:46464
	ds_read_b64 v[166:167], v2 offset:50688
	ds_read_b64 v[168:169], v2 offset:54912
	ds_read_b64 v[170:171], v2 offset:59136
	ds_read_b64 v[172:173], v2 offset:63360
	v_add_u32_e32 v212, 0x11880, v2
	v_add_u32_e32 v213, 0x12900, v2
	v_add_u32_e32 v214, 0x13980, v2
	ds_read_b64 v[174:175], v143
	ds_read_b64 v[176:177], v212
	ds_read_b64 v[178:179], v213
	ds_read_b64 v[180:181], v214
	v_add_u32_e32 v215, 0x14a00, v2
	s_waitcnt lgkmcnt(3)
	v_pk_add_f32 v[210:211], v[128:129], v[174:175]
	v_pk_add_f32 v[128:129], v[128:129], v[174:175] neg_lo:[0,1] neg_hi:[0,1]
	s_waitcnt lgkmcnt(2)
	v_pk_add_f32 v[174:175], v[130:131], v[176:177]
	v_pk_add_f32 v[130:131], v[130:131], v[176:177] neg_lo:[0,1] neg_hi:[0,1]
	v_add_u32_e32 v216, 0x15a80, v2
	v_pk_mul_f32 v[176:177], v[130:131], s[20:21]
	v_add_u32_e32 v217, 0x16b00, v2
	v_pk_fma_f32 v[130:131], v[130:131], s[10:11], v[176:177] op_sel:[0,0,1] op_sel_hi:[1,0,0]
	s_waitcnt lgkmcnt(1)
	v_pk_add_f32 v[176:177], v[144:145], v[178:179]
	v_pk_add_f32 v[144:145], v[144:145], v[178:179] neg_lo:[0,1] neg_hi:[0,1]
	v_add_u32_e32 v218, 0x17b80, v2
	v_pk_mul_f32 v[178:179], v[144:145], s[24:25]
	ds_read_b64 v[182:183], v215
	ds_read_b64 v[184:185], v216
	ds_read_b64 v[186:187], v217
	ds_read_b64 v[188:189], v218
	v_pk_fma_f32 v[144:145], v[144:145], s[22:23], v[178:179] op_sel:[0,0,1] op_sel_hi:[1,0,0]
	s_waitcnt lgkmcnt(4)
	v_pk_add_f32 v[178:179], v[148:149], v[180:181]
	v_pk_add_f32 v[148:149], v[148:149], v[180:181] neg_lo:[0,1] neg_hi:[0,1]
	s_mov_b32 s43, s26
	v_pk_mul_f32 v[180:181], v[148:149], s[36:37]
	s_mov_b32 s0, s37
	v_pk_fma_f32 v[148:149], v[148:149], s[26:27], v[180:181] op_sel:[0,0,1] op_sel_hi:[1,0,0]
	s_waitcnt lgkmcnt(3)
	v_pk_add_f32 v[180:181], v[150:151], v[182:183]
	v_pk_add_f32 v[150:151], v[150:151], v[182:183] neg_lo:[0,1] neg_hi:[0,1]
	s_mov_b32 s45, s22
	v_pk_mul_f32 v[182:183], v[150:151], s[40:41]
	v_add_u32_e32 v219, 0x18c00, v2
	v_pk_fma_f32 v[150:151], v[150:151], s[38:39], v[182:183] op_sel:[0,0,1] op_sel_hi:[1,0,0]
	s_waitcnt lgkmcnt(2)
	v_pk_add_f32 v[182:183], v[152:153], v[184:185]
	v_pk_add_f32 v[152:153], v[152:153], v[184:185] neg_lo:[0,1] neg_hi:[0,1]
	s_mov_b32 s50, s25
	v_pk_mul_f32 v[184:185], v[152:153], s[42:43]
	v_add_u32_e32 v220, 0x19c80, v2
	v_pk_fma_f32 v[152:153], v[152:153], s[0:1], v[184:185] op_sel:[0,0,1] op_sel_hi:[1,0,0]
	s_waitcnt lgkmcnt(1)
	v_pk_add_f32 v[184:185], v[154:155], v[186:187]
	v_pk_add_f32 v[154:155], v[154:155], v[186:187] neg_lo:[0,1] neg_hi:[0,1]
	v_add_u32_e32 v221, 0x1ad00, v2
	v_pk_mul_f32 v[186:187], v[154:155], s[44:45]
	v_add_u32_e32 v222, 0x1bd80, v2
	ds_read_b64 v[190:191], v219
	ds_read_b64 v[192:193], v220
	ds_read_b64 v[194:195], v221
	ds_read_b64 v[196:197], v222
	v_pk_fma_f32 v[154:155], v[154:155], s[50:51], v[186:187] op_sel:[0,0,1] op_sel_hi:[1,0,0]
	s_waitcnt lgkmcnt(4)
	v_pk_add_f32 v[186:187], v[156:157], v[188:189]
	v_pk_add_f32 v[156:157], v[156:157], v[188:189] neg_lo:[0,1] neg_hi:[0,1]
	v_add_u32_e32 v223, 0x1ce00, v2
	v_pk_mul_f32 v[188:189], v[156:157], s[8:9]
	v_add_u32_e32 v224, 0x1de80, v2
	v_pk_fma_f32 v[156:157], v[156:157], s[16:17], v[188:189] op_sel:[0,0,1] op_sel_hi:[1,0,0]
	s_waitcnt lgkmcnt(3)
	v_pk_add_f32 v[188:189], v[158:159], v[190:191]
	v_pk_add_f32 v[190:191], v[158:159], v[190:191] neg_lo:[0,1] neg_hi:[0,1]
	v_add_u32_e32 v225, 0x1ef00, v2
	s_waitcnt lgkmcnt(2)
	v_pk_add_f32 v[158:159], v[160:161], v[192:193]
	v_pk_add_f32 v[160:161], v[160:161], v[192:193] neg_lo:[0,1] neg_hi:[0,1]
	v_add_u32_e32 v226, 0x1ff80, v2
	v_pk_mul_f32 v[192:193], v[160:161], s[8:9]
	ds_read_b64 v[198:199], v223
	ds_read_b64 v[204:205], v224
	ds_read_b64 v[206:207], v225
	ds_read_b64 v[208:209], v226
	v_pk_fma_f32 v[160:161], v[160:161], s[16:17], v[192:193] op_sel:[0,0,1] op_sel_hi:[1,0,0] neg_lo:[1,0,0] neg_hi:[1,0,0]
	s_waitcnt lgkmcnt(5)
	v_pk_add_f32 v[192:193], v[162:163], v[194:195]
	v_pk_add_f32 v[162:163], v[162:163], v[194:195] neg_lo:[0,1] neg_hi:[0,1]
	v_cvt_f32_u32_e32 v5, v4
	v_pk_mul_f32 v[194:195], v[162:163], s[44:45]
	v_mul_f32_e32 v5, 0x38800000, v5
	v_pk_fma_f32 v[162:163], v[162:163], s[50:51], v[194:195] op_sel:[0,0,1] op_sel_hi:[1,0,0] neg_lo:[1,0,0] neg_hi:[1,0,0]
	s_waitcnt lgkmcnt(4)
	v_pk_add_f32 v[194:195], v[164:165], v[196:197]
	v_pk_add_f32 v[164:165], v[164:165], v[196:197] neg_lo:[0,1] neg_hi:[0,1]
	v_sin_f32_e32 v4, v5
	v_pk_mul_f32 v[196:197], v[164:165], s[42:43]
	v_cos_f32_e32 v6, v5
	v_pk_fma_f32 v[164:165], v[164:165], s[0:1], v[196:197] op_sel:[0,0,1] op_sel_hi:[1,0,0] neg_lo:[1,0,0] neg_hi:[1,0,0]
	s_waitcnt lgkmcnt(3)
	v_pk_add_f32 v[196:197], v[166:167], v[198:199]
	v_pk_add_f32 v[166:167], v[166:167], v[198:199] neg_lo:[0,1] neg_hi:[0,1]
	v_xor_b32_e32 v7, 0x80000000, v4
	v_pk_mul_f32 v[198:199], v[166:167], s[40:41]
	v_mov_b32_e32 v5, v7
	v_pk_fma_f32 v[166:167], v[166:167], s[38:39], v[198:199] op_sel:[0,0,1] op_sel_hi:[1,0,0] neg_lo:[1,0,0] neg_hi:[1,0,0]
	s_waitcnt lgkmcnt(2)
	v_pk_add_f32 v[198:199], v[168:169], v[204:205]
	v_pk_add_f32 v[168:169], v[168:169], v[204:205] neg_lo:[0,1] neg_hi:[0,1]
	v_pk_mul_f32 v[8:9], v[6:7], v[4:5] op_sel:[1,0] op_sel_hi:[0,1]
	v_pk_mul_f32 v[204:205], v[168:169], s[36:37]
	v_pk_fma_f32 v[8:9], v[6:7], v[6:7], v[8:9] op_sel_hi:[1,0,1]
	v_pk_fma_f32 v[168:169], v[168:169], s[26:27], v[204:205] op_sel:[0,0,1] op_sel_hi:[1,0,0] neg_lo:[1,0,0] neg_hi:[1,0,0]
	s_waitcnt lgkmcnt(1)
	v_pk_add_f32 v[204:205], v[170:171], v[206:207]
	v_pk_add_f32 v[170:171], v[170:171], v[206:207] neg_lo:[0,1] neg_hi:[0,1]
	v_pk_mul_f32 v[14:15], v[8:9], 1.0 op_sel:[1,0] op_sel_hi:[1,0] neg_lo:[1,0]
	v_pk_mul_f32 v[206:207], v[170:171], s[24:25]
	s_nop 0
	v_pk_fma_f32 v[170:171], v[170:171], s[22:23], v[206:207] op_sel:[0,0,1] op_sel_hi:[1,0,0] neg_lo:[1,0,0] neg_hi:[1,0,0]
	s_waitcnt lgkmcnt(0)
	v_pk_add_f32 v[206:207], v[172:173], v[208:209]
	v_pk_add_f32 v[172:173], v[172:173], v[208:209] neg_lo:[0,1] neg_hi:[0,1]
	v_pk_mul_f32 v[12:13], v[8:9], v[14:15] op_sel:[1,0] op_sel_hi:[0,1]
	v_pk_mul_f32 v[208:209], v[172:173], s[20:21]
	v_pk_fma_f32 v[12:13], v[8:9], v[8:9], v[12:13] op_sel_hi:[1,0,1]
	v_pk_fma_f32 v[172:173], v[172:173], s[10:11], v[208:209] op_sel:[0,0,1] op_sel_hi:[1,0,0] neg_lo:[1,0,0] neg_hi:[1,0,0]
	v_pk_add_f32 v[208:209], v[210:211], v[188:189]
	v_pk_add_f32 v[188:189], v[210:211], v[188:189] neg_lo:[0,1] neg_hi:[0,1]
	v_pk_add_f32 v[210:211], v[174:175], v[158:159]
	v_pk_add_f32 v[158:159], v[174:175], v[158:159] neg_lo:[0,1] neg_hi:[0,1]
	v_pk_mul_f32 v[16:17], v[12:13], 1.0 op_sel:[1,0] op_sel_hi:[1,0] neg_lo:[1,0]
	v_pk_mul_f32 v[174:175], v[158:159], s[24:25]
	s_nop 0
	v_pk_fma_f32 v[158:159], v[158:159], s[22:23], v[174:175] op_sel:[0,0,1] op_sel_hi:[1,0,0]
	v_pk_add_f32 v[174:175], v[176:177], v[192:193]
	v_pk_add_f32 v[176:177], v[176:177], v[192:193] neg_lo:[0,1] neg_hi:[0,1]
	v_pk_mul_f32 v[28:29], v[12:13], v[16:17] op_sel:[1,0] op_sel_hi:[0,1]
	v_pk_mul_f32 v[192:193], v[176:177], s[40:41]
	v_pk_fma_f32 v[28:29], v[12:13], v[12:13], v[28:29] op_sel_hi:[1,0,1]
	v_pk_fma_f32 v[176:177], v[176:177], s[38:39], v[192:193] op_sel:[0,0,1] op_sel_hi:[1,0,0]
	v_pk_add_f32 v[192:193], v[178:179], v[194:195]
	v_pk_add_f32 v[178:179], v[178:179], v[194:195] neg_lo:[0,1] neg_hi:[0,1]
	v_pk_mul_f32 v[44:45], v[16:17], v[28:29] op_sel:[0,1] op_sel_hi:[1,0]
	v_pk_mul_f32 v[194:195], v[178:179], s[44:45]
	v_pk_fma_f32 v[44:45], v[12:13], v[28:29], v[44:45] op_sel_hi:[0,1,1]
	v_pk_fma_f32 v[178:179], v[178:179], s[50:51], v[194:195] op_sel:[0,0,1] op_sel_hi:[1,0,0]
	v_pk_add_f32 v[194:195], v[180:181], v[196:197]
	v_pk_add_f32 v[196:197], v[180:181], v[196:197] neg_lo:[0,1] neg_hi:[0,1]
	v_pk_mul_f32 v[60:61], v[16:17], v[44:45] op_sel:[0,1] op_sel_hi:[1,0]
	v_pk_add_f32 v[180:181], v[182:183], v[198:199]
	v_pk_add_f32 v[182:183], v[182:183], v[198:199] neg_lo:[0,1] neg_hi:[0,1]
	v_pk_fma_f32 v[60:61], v[12:13], v[44:45], v[60:61] op_sel_hi:[0,1,1]
	v_pk_mul_f32 v[198:199], v[182:183], s[44:45]
	v_pk_mul_f32 v[76:77], v[16:17], v[60:61] op_sel:[0,1] op_sel_hi:[1,0]
	v_pk_fma_f32 v[182:183], v[182:183], s[50:51], v[198:199] op_sel:[0,0,1] op_sel_hi:[1,0,0] neg_lo:[1,0,0] neg_hi:[1,0,0]
	v_pk_add_f32 v[198:199], v[184:185], v[204:205]
	v_pk_add_f32 v[184:185], v[184:185], v[204:205] neg_lo:[0,1] neg_hi:[0,1]
	v_pk_fma_f32 v[76:77], v[12:13], v[60:61], v[76:77] op_sel_hi:[0,1,1]
	v_pk_mul_f32 v[204:205], v[184:185], s[40:41]
	v_pk_mul_f32 v[92:93], v[16:17], v[76:77] op_sel:[0,1] op_sel_hi:[1,0]
	v_pk_fma_f32 v[184:185], v[184:185], s[38:39], v[204:205] op_sel:[0,0,1] op_sel_hi:[1,0,0] neg_lo:[1,0,0] neg_hi:[1,0,0]
	v_pk_add_f32 v[204:205], v[186:187], v[206:207]
	v_pk_add_f32 v[186:187], v[186:187], v[206:207] neg_lo:[0,1] neg_hi:[0,1]
	v_pk_fma_f32 v[92:93], v[12:13], v[76:77], v[92:93] op_sel_hi:[0,1,1]
	v_pk_mul_f32 v[206:207], v[186:187], s[24:25]
	v_pk_mul_f32 v[108:109], v[16:17], v[92:93] op_sel:[0,1] op_sel_hi:[1,0]
	v_pk_fma_f32 v[186:187], v[186:187], s[22:23], v[206:207] op_sel:[0,0,1] op_sel_hi:[1,0,0] neg_lo:[1,0,0] neg_hi:[1,0,0]
	v_pk_add_f32 v[206:207], v[128:129], v[190:191] op_sel:[0,1] op_sel_hi:[1,0] neg_hi:[0,1]
	v_pk_add_f32 v[128:129], v[128:129], v[190:191] op_sel:[0,1] op_sel_hi:[1,0] neg_lo:[0,1]
	v_pk_add_f32 v[190:191], v[130:131], v[160:161]
	v_pk_add_f32 v[130:131], v[130:131], v[160:161] neg_lo:[0,1] neg_hi:[0,1]
	v_pk_mul_f32 v[10:11], v[4:5], v[8:9] op_sel:[0,1] op_sel_hi:[1,0]
	v_pk_mul_f32 v[160:161], v[130:131], s[24:25]
	v_pk_fma_f32 v[108:109], v[12:13], v[92:93], v[108:109] op_sel_hi:[0,1,1]
	v_pk_fma_f32 v[130:131], v[130:131], s[22:23], v[160:161] op_sel:[0,0,1] op_sel_hi:[1,0,0]
	v_pk_add_f32 v[160:161], v[144:145], v[162:163]
	v_pk_add_f32 v[144:145], v[144:145], v[162:163] neg_lo:[0,1] neg_hi:[0,1]
	v_pk_fma_f32 v[10:11], v[6:7], v[8:9], v[10:11] op_sel_hi:[0,1,1]
	v_pk_mul_f32 v[162:163], v[144:145], s[40:41]
	v_pk_mul_f32 v[18:19], v[4:5], v[12:13] op_sel:[0,1] op_sel_hi:[1,0]
	v_pk_fma_f32 v[144:145], v[144:145], s[38:39], v[162:163] op_sel:[0,0,1] op_sel_hi:[1,0,0]
	v_pk_add_f32 v[162:163], v[148:149], v[164:165]
	v_pk_add_f32 v[148:149], v[148:149], v[164:165] neg_lo:[0,1] neg_hi:[0,1]
	v_pk_mul_f32 v[32:33], v[4:5], v[28:29] op_sel:[0,1] op_sel_hi:[1,0]
	v_pk_mul_f32 v[164:165], v[148:149], s[44:45]
	v_pk_mul_f32 v[48:49], v[4:5], v[44:45] op_sel:[0,1] op_sel_hi:[1,0]
	v_pk_fma_f32 v[148:149], v[148:149], s[50:51], v[164:165] op_sel:[0,0,1] op_sel_hi:[1,0,0]
	v_pk_add_f32 v[164:165], v[150:151], v[166:167]
	v_pk_add_f32 v[166:167], v[150:151], v[166:167] neg_lo:[0,1] neg_hi:[0,1]
	v_pk_mul_f32 v[64:65], v[4:5], v[60:61] op_sel:[0,1] op_sel_hi:[1,0]
	v_pk_add_f32 v[150:151], v[152:153], v[168:169]
	v_pk_add_f32 v[152:153], v[152:153], v[168:169] neg_lo:[0,1] neg_hi:[0,1]
	v_pk_mul_f32 v[80:81], v[4:5], v[76:77] op_sel:[0,1] op_sel_hi:[1,0]
	v_pk_mul_f32 v[168:169], v[152:153], s[44:45]
	v_pk_mul_f32 v[96:97], v[4:5], v[92:93] op_sel:[0,1] op_sel_hi:[1,0]
	v_pk_fma_f32 v[152:153], v[152:153], s[50:51], v[168:169] op_sel:[0,0,1] op_sel_hi:[1,0,0] neg_lo:[1,0,0] neg_hi:[1,0,0]
	v_pk_add_f32 v[168:169], v[154:155], v[170:171]
	v_pk_add_f32 v[154:155], v[154:155], v[170:171] neg_lo:[0,1] neg_hi:[0,1]
	v_pk_mul_f32 v[112:113], v[4:5], v[108:109] op_sel:[0,1] op_sel_hi:[1,0]
	v_pk_mul_f32 v[170:171], v[154:155], s[40:41]
	v_pk_mul_f32 v[22:23], v[10:11], 1.0 op_sel:[1,0] op_sel_hi:[1,0] neg_lo:[1,0]
	v_pk_fma_f32 v[154:155], v[154:155], s[38:39], v[170:171] op_sel:[0,0,1] op_sel_hi:[1,0,0] neg_lo:[1,0,0] neg_hi:[1,0,0]
	v_pk_add_f32 v[170:171], v[156:157], v[172:173]
	v_pk_add_f32 v[156:157], v[156:157], v[172:173] neg_lo:[0,1] neg_hi:[0,1]
	s_nop 0
	v_pk_mul_f32 v[172:173], v[156:157], s[24:25]
	v_pk_fma_f32 v[18:19], v[6:7], v[12:13], v[18:19] op_sel_hi:[0,1,1]
	v_pk_fma_f32 v[156:157], v[156:157], s[22:23], v[172:173] op_sel:[0,0,1] op_sel_hi:[1,0,0] neg_lo:[1,0,0] neg_hi:[1,0,0]
	v_pk_add_f32 v[172:173], v[208:209], v[194:195]
	v_pk_add_f32 v[194:195], v[208:209], v[194:195] neg_lo:[0,1] neg_hi:[0,1]
	v_pk_add_f32 v[208:209], v[210:211], v[180:181]
	v_pk_add_f32 v[180:181], v[210:211], v[180:181] neg_lo:[0,1] neg_hi:[0,1]
	v_pk_mul_f32 v[20:21], v[14:15], v[12:13] op_sel:[0,1] op_sel_hi:[1,0]
	v_pk_mul_f32 v[210:211], v[180:181], s[40:41]
	v_pk_fma_f32 v[32:33], v[6:7], v[28:29], v[32:33] op_sel_hi:[0,1,1]
	v_pk_fma_f32 v[180:181], v[180:181], s[38:39], v[210:211] op_sel:[0,0,1] op_sel_hi:[1,0,0]
	v_pk_add_f32 v[210:211], v[174:175], v[198:199]
	v_pk_add_f32 v[198:199], v[174:175], v[198:199] neg_lo:[0,1] neg_hi:[0,1]
	v_pk_mul_f32 v[36:37], v[14:15], v[28:29] op_sel:[0,1] op_sel_hi:[1,0]
	v_pk_add_f32 v[174:175], v[192:193], v[204:205]
	v_pk_add_f32 v[192:193], v[192:193], v[204:205] neg_lo:[0,1] neg_hi:[0,1]
	v_pk_fma_f32 v[48:49], v[6:7], v[44:45], v[48:49] op_sel_hi:[0,1,1]
	v_pk_mul_f32 v[204:205], v[192:193], s[40:41]
	v_pk_mul_f32 v[52:53], v[14:15], v[44:45] op_sel:[0,1] op_sel_hi:[1,0]
	v_pk_fma_f32 v[192:193], v[192:193], s[38:39], v[204:205] op_sel:[0,0,1] op_sel_hi:[1,0,0] neg_lo:[1,0,0] neg_hi:[1,0,0]
	v_pk_add_f32 v[204:205], v[188:189], v[196:197] op_sel:[0,1] op_sel_hi:[1,0] neg_hi:[0,1]
	v_pk_add_f32 v[188:189], v[188:189], v[196:197] op_sel:[0,1] op_sel_hi:[1,0] neg_lo:[0,1]
	v_pk_add_f32 v[196:197], v[158:159], v[182:183]
	v_pk_add_f32 v[158:159], v[158:159], v[182:183] neg_lo:[0,1] neg_hi:[0,1]
	v_pk_fma_f32 v[64:65], v[6:7], v[60:61], v[64:65] op_sel_hi:[0,1,1]
	v_pk_mul_f32 v[182:183], v[158:159], s[40:41]
	v_pk_mul_f32 v[68:69], v[14:15], v[60:61] op_sel:[0,1] op_sel_hi:[1,0]
	v_pk_fma_f32 v[158:159], v[158:159], s[38:39], v[182:183] op_sel:[0,0,1] op_sel_hi:[1,0,0]
	v_pk_add_f32 v[182:183], v[176:177], v[184:185]
	v_pk_add_f32 v[184:185], v[176:177], v[184:185] neg_lo:[0,1] neg_hi:[0,1]
	v_pk_fma_f32 v[80:81], v[6:7], v[76:77], v[80:81] op_sel_hi:[0,1,1]
	v_pk_add_f32 v[176:177], v[178:179], v[186:187]
	v_pk_add_f32 v[178:179], v[178:179], v[186:187] neg_lo:[0,1] neg_hi:[0,1]
	v_pk_mul_f32 v[84:85], v[14:15], v[76:77] op_sel:[0,1] op_sel_hi:[1,0]
	v_pk_mul_f32 v[186:187], v[178:179], s[40:41]
	v_pk_fma_f32 v[96:97], v[6:7], v[92:93], v[96:97] op_sel_hi:[0,1,1]
	v_pk_fma_f32 v[178:179], v[178:179], s[38:39], v[186:187] op_sel:[0,0,1] op_sel_hi:[1,0,0] neg_lo:[1,0,0] neg_hi:[1,0,0]
	v_pk_add_f32 v[186:187], v[206:207], v[164:165]
	v_pk_add_f32 v[164:165], v[206:207], v[164:165] neg_lo:[0,1] neg_hi:[0,1]
	v_pk_add_f32 v[206:207], v[190:191], v[150:151]
	v_pk_add_f32 v[150:151], v[190:191], v[150:151] neg_lo:[0,1] neg_hi:[0,1]
	v_pk_mul_f32 v[100:101], v[14:15], v[92:93] op_sel:[0,1] op_sel_hi:[1,0]
	v_pk_mul_f32 v[190:191], v[150:151], s[40:41]
	v_pk_fma_f32 v[112:113], v[6:7], v[108:109], v[112:113] op_sel_hi:[0,1,1]
	v_pk_fma_f32 v[150:151], v[150:151], s[38:39], v[190:191] op_sel:[0,0,1] op_sel_hi:[1,0,0]
	v_pk_add_f32 v[190:191], v[160:161], v[168:169]
	v_pk_add_f32 v[168:169], v[160:161], v[168:169] neg_lo:[0,1] neg_hi:[0,1]
	v_pk_mul_f32 v[116:117], v[14:15], v[108:109] op_sel:[0,1] op_sel_hi:[1,0]
	v_pk_add_f32 v[160:161], v[162:163], v[170:171]
	v_pk_add_f32 v[162:163], v[162:163], v[170:171] neg_lo:[0,1] neg_hi:[0,1]
	v_pk_fma_f32 v[20:21], v[8:9], v[12:13], v[20:21] op_sel_hi:[0,1,1]
	v_pk_mul_f32 v[170:171], v[162:163], s[40:41]
	v_pk_mul_f32 v[24:25], v[12:13], v[22:23] op_sel:[1,0] op_sel_hi:[0,1]
	v_pk_fma_f32 v[162:163], v[162:163], s[38:39], v[170:171] op_sel:[0,0,1] op_sel_hi:[1,0,0] neg_lo:[1,0,0] neg_hi:[1,0,0]
	v_pk_add_f32 v[170:171], v[128:129], v[166:167] op_sel:[0,1] op_sel_hi:[1,0] neg_hi:[0,1]
	v_pk_add_f32 v[128:129], v[128:129], v[166:167] op_sel:[0,1] op_sel_hi:[1,0] neg_lo:[0,1]
	v_pk_add_f32 v[166:167], v[130:131], v[152:153]
	v_pk_add_f32 v[130:131], v[130:131], v[152:153] neg_lo:[0,1] neg_hi:[0,1]
	v_pk_fma_f32 v[36:37], v[8:9], v[28:29], v[36:37] op_sel_hi:[0,1,1]
	v_pk_mul_f32 v[152:153], v[130:131], s[40:41]
	v_pk_mul_f32 v[40:41], v[22:23], v[28:29] op_sel:[0,1] op_sel_hi:[1,0]
	v_pk_fma_f32 v[130:131], v[130:131], s[38:39], v[152:153] op_sel:[0,0,1] op_sel_hi:[1,0,0]
	v_pk_add_f32 v[152:153], v[144:145], v[154:155]
	v_pk_add_f32 v[154:155], v[144:145], v[154:155] neg_lo:[0,1] neg_hi:[0,1]
	v_pk_fma_f32 v[52:53], v[8:9], v[44:45], v[52:53] op_sel_hi:[0,1,1]
	v_pk_add_f32 v[144:145], v[148:149], v[156:157]
	v_pk_add_f32 v[148:149], v[148:149], v[156:157] neg_lo:[0,1] neg_hi:[0,1]
	v_pk_mul_f32 v[56:57], v[22:23], v[44:45] op_sel:[0,1] op_sel_hi:[1,0]
	v_pk_mul_f32 v[156:157], v[148:149], s[40:41]
	v_pk_fma_f32 v[68:69], v[8:9], v[60:61], v[68:69] op_sel_hi:[0,1,1]
	v_pk_fma_f32 v[148:149], v[148:149], s[38:39], v[156:157] op_sel:[0,0,1] op_sel_hi:[1,0,0] neg_lo:[1,0,0] neg_hi:[1,0,0]
	v_pk_add_f32 v[156:157], v[172:173], v[210:211]
	v_pk_add_f32 v[172:173], v[172:173], v[210:211] neg_lo:[0,1] neg_hi:[0,1]
	v_pk_add_f32 v[210:211], v[208:209], v[174:175]
	v_pk_add_f32 v[208:209], v[208:209], v[174:175] neg_lo:[0,1] neg_hi:[0,1]
	v_pk_mul_f32 v[72:73], v[22:23], v[60:61] op_sel:[0,1] op_sel_hi:[1,0]
	v_pk_add_f32 v[174:175], v[194:195], v[198:199] op_sel:[0,1] op_sel_hi:[1,0] neg_hi:[0,1]
	v_pk_add_f32 v[194:195], v[194:195], v[198:199] op_sel:[0,1] op_sel_hi:[1,0] neg_lo:[0,1]
	v_pk_add_f32 v[198:199], v[180:181], v[192:193]
	v_pk_add_f32 v[192:193], v[180:181], v[192:193] neg_lo:[0,1] neg_hi:[0,1]
	v_pk_fma_f32 v[84:85], v[8:9], v[76:77], v[84:85] op_sel_hi:[0,1,1]
	v_pk_add_f32 v[180:181], v[204:205], v[182:183]
	v_pk_add_f32 v[182:183], v[204:205], v[182:183] neg_lo:[0,1] neg_hi:[0,1]
	v_pk_add_f32 v[204:205], v[196:197], v[176:177]
	v_pk_add_f32 v[196:197], v[196:197], v[176:177] neg_lo:[0,1] neg_hi:[0,1]
	v_pk_mul_f32 v[88:89], v[22:23], v[76:77] op_sel:[0,1] op_sel_hi:[1,0]
	v_pk_add_f32 v[176:177], v[188:189], v[184:185] op_sel:[0,1] op_sel_hi:[1,0] neg_hi:[0,1]
	v_pk_add_f32 v[184:185], v[188:189], v[184:185] op_sel:[0,1] op_sel_hi:[1,0] neg_lo:[0,1]
	v_pk_add_f32 v[188:189], v[158:159], v[178:179]
	v_pk_add_f32 v[178:179], v[158:159], v[178:179] neg_lo:[0,1] neg_hi:[0,1]
	v_pk_fma_f32 v[100:101], v[8:9], v[92:93], v[100:101] op_sel_hi:[0,1,1]
	v_pk_add_f32 v[158:159], v[186:187], v[190:191]
	v_pk_add_f32 v[186:187], v[186:187], v[190:191] neg_lo:[0,1] neg_hi:[0,1]
	v_pk_add_f32 v[190:191], v[206:207], v[160:161]
	v_pk_add_f32 v[206:207], v[206:207], v[160:161] neg_lo:[0,1] neg_hi:[0,1]
	v_pk_mul_f32 v[104:105], v[22:23], v[92:93] op_sel:[0,1] op_sel_hi:[1,0]
	v_pk_add_f32 v[160:161], v[164:165], v[168:169] op_sel:[0,1] op_sel_hi:[1,0] neg_hi:[0,1]
	v_pk_add_f32 v[164:165], v[164:165], v[168:169] op_sel:[0,1] op_sel_hi:[1,0] neg_lo:[0,1]
	v_pk_add_f32 v[168:169], v[150:151], v[162:163]
	v_pk_add_f32 v[162:163], v[150:151], v[162:163] neg_lo:[0,1] neg_hi:[0,1]
	v_pk_fma_f32 v[116:117], v[8:9], v[108:109], v[116:117] op_sel_hi:[0,1,1]
	v_pk_add_f32 v[150:151], v[170:171], v[152:153]
	v_pk_add_f32 v[152:153], v[170:171], v[152:153] neg_lo:[0,1] neg_hi:[0,1]
	v_pk_add_f32 v[170:171], v[166:167], v[144:145]
	v_pk_add_f32 v[166:167], v[166:167], v[144:145] neg_lo:[0,1] neg_hi:[0,1]
	v_pk_mul_f32 v[120:121], v[22:23], v[108:109] op_sel:[0,1] op_sel_hi:[1,0]
	v_pk_add_f32 v[144:145], v[128:129], v[154:155] op_sel:[0,1] op_sel_hi:[1,0] neg_hi:[0,1]
	v_pk_add_f32 v[128:129], v[128:129], v[154:155] op_sel:[0,1] op_sel_hi:[1,0] neg_lo:[0,1]
	v_pk_add_f32 v[154:155], v[130:131], v[148:149]
	v_pk_add_f32 v[148:149], v[130:131], v[148:149] neg_lo:[0,1] neg_hi:[0,1]
	v_xor_b32_e32 v26, 0x80000000, v19
	v_pk_add_f32 v[130:131], v[156:157], v[210:211]
	v_pk_add_f32 v[156:157], v[156:157], v[210:211] neg_lo:[0,1] neg_hi:[0,1]
	v_pk_add_f32 v[210:211], v[172:173], v[208:209] op_sel:[0,1] op_sel_hi:[1,0] neg_hi:[0,1]
	v_pk_add_f32 v[172:173], v[172:173], v[208:209] op_sel:[0,1] op_sel_hi:[1,0] neg_lo:[0,1]
	v_pk_add_f32 v[208:209], v[174:175], v[198:199]
	v_pk_add_f32 v[174:175], v[174:175], v[198:199] neg_lo:[0,1] neg_hi:[0,1]
	v_pk_add_f32 v[198:199], v[194:195], v[192:193] op_sel:[0,1] op_sel_hi:[1,0] neg_hi:[0,1]
	v_pk_add_f32 v[192:193], v[194:195], v[192:193] op_sel:[0,1] op_sel_hi:[1,0] neg_lo:[0,1]
	v_pk_add_f32 v[194:195], v[180:181], v[204:205]
	v_pk_add_f32 v[180:181], v[180:181], v[204:205] neg_lo:[0,1] neg_hi:[0,1]
	v_pk_add_f32 v[204:205], v[182:183], v[196:197] op_sel:[0,1] op_sel_hi:[1,0] neg_hi:[0,1]
	v_pk_add_f32 v[182:183], v[182:183], v[196:197] op_sel:[0,1] op_sel_hi:[1,0] neg_lo:[0,1]
	v_pk_add_f32 v[196:197], v[176:177], v[188:189]
	v_pk_add_f32 v[176:177], v[176:177], v[188:189] neg_lo:[0,1] neg_hi:[0,1]
	v_pk_add_f32 v[188:189], v[184:185], v[178:179] op_sel:[0,1] op_sel_hi:[1,0] neg_hi:[0,1]
	v_pk_add_f32 v[178:179], v[184:185], v[178:179] op_sel:[0,1] op_sel_hi:[1,0] neg_lo:[0,1]
	v_pk_add_f32 v[184:185], v[158:159], v[190:191]
	v_pk_add_f32 v[158:159], v[158:159], v[190:191] neg_lo:[0,1] neg_hi:[0,1]
	v_pk_mul_f32 v[4:5], v[4:5], v[184:185] op_sel:[0,1] op_sel_hi:[1,0]
	v_pk_add_f32 v[190:191], v[186:187], v[206:207] op_sel:[0,1] op_sel_hi:[1,0] neg_hi:[0,1]
	v_pk_add_f32 v[186:187], v[186:187], v[206:207] op_sel:[0,1] op_sel_hi:[1,0] neg_lo:[0,1]
	v_pk_add_f32 v[206:207], v[160:161], v[168:169]
	v_pk_add_f32 v[160:161], v[160:161], v[168:169] neg_lo:[0,1] neg_hi:[0,1]
	v_pk_add_f32 v[168:169], v[164:165], v[162:163] op_sel:[0,1] op_sel_hi:[1,0] neg_hi:[0,1]
	v_pk_add_f32 v[162:163], v[164:165], v[162:163] op_sel:[0,1] op_sel_hi:[1,0] neg_lo:[0,1]
	v_pk_add_f32 v[164:165], v[150:151], v[170:171]
	v_pk_fma_f32 v[4:5], v[6:7], v[184:185], v[4:5] op_sel_hi:[0,1,1]
	v_pk_mul_f32 v[6:7], v[14:15], v[194:195] op_sel:[0,1] op_sel_hi:[1,0]
	v_xor_b32_e32 v30, 0x80000000, v21
	v_pk_fma_f32 v[6:7], v[8:9], v[194:195], v[6:7] op_sel_hi:[0,1,1]
	v_pk_mul_f32 v[8:9], v[22:23], v[164:165] op_sel:[0,1] op_sel_hi:[1,0]
	v_pk_fma_f32 v[24:25], v[12:13], v[10:11], v[24:25] op_sel_hi:[1,0,1]
	v_pk_fma_f32 v[40:41], v[10:11], v[28:29], v[40:41] op_sel_hi:[0,1,1]
	v_pk_fma_f32 v[56:57], v[10:11], v[44:45], v[56:57] op_sel_hi:[0,1,1]
	v_pk_fma_f32 v[72:73], v[10:11], v[60:61], v[72:73] op_sel_hi:[0,1,1]
	v_pk_fma_f32 v[88:89], v[10:11], v[76:77], v[88:89] op_sel_hi:[0,1,1]
	v_pk_fma_f32 v[104:105], v[10:11], v[92:93], v[104:105] op_sel_hi:[0,1,1]
	v_pk_fma_f32 v[120:121], v[10:11], v[108:109], v[120:121] op_sel_hi:[0,1,1]
	v_mov_b32_e32 v27, v19
	v_mov_b32_e32 v31, v21
	v_pk_fma_f32 v[8:9], v[10:11], v[164:165], v[8:9] op_sel_hi:[0,1,1]
	v_pk_mul_f32 v[10:11], v[16:17], v[208:209] op_sel:[0,1] op_sel_hi:[1,0]
	v_pk_mul_f32 v[34:35], v[24:25], 1.0 op_sel:[1,0] op_sel_hi:[1,0] neg_lo:[1,0]
	v_pk_mul_f32 v[38:39], v[28:29], 1.0 op_sel:[1,0] op_sel_hi:[1,0] neg_lo:[1,0]
	v_pk_mul_f32 v[42:43], v[32:33], 1.0 op_sel:[1,0] op_sel_hi:[1,0] neg_lo:[1,0]
	v_pk_mul_f32 v[46:47], v[36:37], 1.0 op_sel:[1,0] op_sel_hi:[1,0] neg_lo:[1,0]
	v_pk_add_f32 v[150:151], v[150:151], v[170:171] neg_lo:[0,1] neg_hi:[0,1]
	v_pk_add_f32 v[170:171], v[152:153], v[166:167] op_sel:[0,1] op_sel_hi:[1,0] neg_hi:[0,1]
	v_pk_add_f32 v[152:153], v[152:153], v[166:167] op_sel:[0,1] op_sel_hi:[1,0] neg_lo:[0,1]
	v_pk_add_f32 v[166:167], v[144:145], v[154:155]
	v_pk_fma_f32 v[10:11], v[12:13], v[208:209], v[10:11] op_sel_hi:[0,1,1]
	v_pk_mul_f32 v[12:13], v[26:27], v[206:207] op_sel:[0,1] op_sel_hi:[1,0]
	v_pk_mul_f32 v[14:15], v[30:31], v[196:197] op_sel:[0,1] op_sel_hi:[1,0]
	v_xor_b32_e32 v50, 0x80000000, v41
	v_xor_b32_e32 v54, 0x80000000, v45
	v_xor_b32_e32 v58, 0x80000000, v49
	v_xor_b32_e32 v62, 0x80000000, v53
	v_xor_b32_e32 v66, 0x80000000, v57
	v_xor_b32_e32 v70, 0x80000000, v61
	v_xor_b32_e32 v74, 0x80000000, v65
	v_mov_b32_e32 v51, v41
	v_mov_b32_e32 v55, v45
	v_mov_b32_e32 v59, v49
	v_mov_b32_e32 v63, v53
	v_mov_b32_e32 v67, v57
	v_mov_b32_e32 v71, v61
	v_mov_b32_e32 v75, v65
	v_pk_add_f32 v[144:145], v[144:145], v[154:155] neg_lo:[0,1] neg_hi:[0,1]
	v_pk_add_f32 v[154:155], v[128:129], v[148:149] op_sel:[0,1] op_sel_hi:[1,0] neg_hi:[0,1]
	v_pk_fma_f32 v[12:13], v[18:19], v[206:207], v[12:13] op_sel_hi:[0,1,1]
	v_pk_fma_f32 v[14:15], v[20:21], v[196:197], v[14:15] op_sel_hi:[0,1,1]
	v_pk_mul_f32 v[16:17], v[34:35], v[166:167] op_sel:[0,1] op_sel_hi:[1,0]
	v_pk_mul_f32 v[18:19], v[38:39], v[210:211] op_sel:[0,1] op_sel_hi:[1,0]
	v_pk_mul_f32 v[20:21], v[42:43], v[190:191] op_sel:[0,1] op_sel_hi:[1,0]
	v_pk_mul_f32 v[22:23], v[46:47], v[204:205] op_sel:[0,1] op_sel_hi:[1,0]
	v_xor_b32_e32 v78, 0x80000000, v69
	v_xor_b32_e32 v82, 0x80000000, v73
	v_xor_b32_e32 v86, 0x80000000, v77
	v_xor_b32_e32 v90, 0x80000000, v81
	v_xor_b32_e32 v94, 0x80000000, v85
	v_xor_b32_e32 v98, 0x80000000, v89
	v_xor_b32_e32 v102, 0x80000000, v93
	v_xor_b32_e32 v106, 0x80000000, v97
	v_xor_b32_e32 v110, 0x80000000, v101
	v_xor_b32_e32 v114, 0x80000000, v105
	v_xor_b32_e32 v118, 0x80000000, v109
	v_xor_b32_e32 v122, 0x80000000, v113
	v_xor_b32_e32 v124, 0x80000000, v117
	v_xor_b32_e32 v126, 0x80000000, v121
	v_mov_b32_e32 v79, v69
	v_mov_b32_e32 v83, v73
	v_mov_b32_e32 v87, v77
	v_mov_b32_e32 v91, v81
	v_mov_b32_e32 v95, v85
	v_mov_b32_e32 v99, v89
	v_mov_b32_e32 v103, v93
	v_mov_b32_e32 v107, v97
	v_mov_b32_e32 v111, v101
	v_mov_b32_e32 v115, v105
	v_mov_b32_e32 v119, v109
	v_mov_b32_e32 v123, v113
	v_mov_b32_e32 v125, v117
	v_mov_b32_e32 v127, v121
	v_pk_add_f32 v[128:129], v[128:129], v[148:149] op_sel:[0,1] op_sel_hi:[1,0] neg_lo:[0,1]
	v_pk_fma_f32 v[16:17], v[24:25], v[166:167], v[16:17] op_sel_hi:[0,1,1]
	v_pk_fma_f32 v[18:19], v[28:29], v[210:211], v[18:19] op_sel_hi:[0,1,1]
	v_pk_fma_f32 v[20:21], v[32:33], v[190:191], v[20:21] op_sel_hi:[0,1,1]
	v_pk_fma_f32 v[22:23], v[36:37], v[204:205], v[22:23] op_sel_hi:[0,1,1]
	v_pk_mul_f32 v[24:25], v[50:51], v[170:171] op_sel:[0,1] op_sel_hi:[1,0]
	v_pk_mul_f32 v[26:27], v[54:55], v[198:199] op_sel:[0,1] op_sel_hi:[1,0]
	v_pk_mul_f32 v[28:29], v[58:59], v[168:169] op_sel:[0,1] op_sel_hi:[1,0]
	v_pk_mul_f32 v[30:31], v[62:63], v[188:189] op_sel:[0,1] op_sel_hi:[1,0]
	v_pk_mul_f32 v[32:33], v[66:67], v[154:155] op_sel:[0,1] op_sel_hi:[1,0]
	v_pk_mul_f32 v[34:35], v[70:71], v[156:157] op_sel:[0,1] op_sel_hi:[1,0]
	v_pk_mul_f32 v[36:37], v[74:75], v[158:159] op_sel:[0,1] op_sel_hi:[1,0]
	v_pk_fma_f32 v[24:25], v[40:41], v[170:171], v[24:25] op_sel_hi:[0,1,1]
	v_pk_fma_f32 v[26:27], v[44:45], v[198:199], v[26:27] op_sel_hi:[0,1,1]
	v_pk_fma_f32 v[28:29], v[48:49], v[168:169], v[28:29] op_sel_hi:[0,1,1]
	v_pk_fma_f32 v[30:31], v[52:53], v[188:189], v[30:31] op_sel_hi:[0,1,1]
	v_pk_fma_f32 v[32:33], v[56:57], v[154:155], v[32:33] op_sel_hi:[0,1,1]
	v_pk_fma_f32 v[34:35], v[60:61], v[156:157], v[34:35] op_sel_hi:[0,1,1]
	v_pk_fma_f32 v[36:37], v[64:65], v[158:159], v[36:37] op_sel_hi:[0,1,1]
	v_pk_mul_f32 v[38:39], v[78:79], v[180:181] op_sel:[0,1] op_sel_hi:[1,0]
	v_pk_mul_f32 v[40:41], v[82:83], v[150:151] op_sel:[0,1] op_sel_hi:[1,0]
	v_pk_mul_f32 v[42:43], v[86:87], v[174:175] op_sel:[0,1] op_sel_hi:[1,0]
	v_pk_mul_f32 v[44:45], v[90:91], v[160:161] op_sel:[0,1] op_sel_hi:[1,0]
	v_pk_mul_f32 v[46:47], v[94:95], v[176:177] op_sel:[0,1] op_sel_hi:[1,0]
	v_pk_mul_f32 v[48:49], v[98:99], v[144:145] op_sel:[0,1] op_sel_hi:[1,0]
	v_pk_mul_f32 v[50:51], v[102:103], v[172:173] op_sel:[0,1] op_sel_hi:[1,0]
	v_pk_mul_f32 v[52:53], v[106:107], v[186:187] op_sel:[0,1] op_sel_hi:[1,0]
	v_pk_mul_f32 v[54:55], v[110:111], v[182:183] op_sel:[0,1] op_sel_hi:[1,0]
	v_pk_mul_f32 v[56:57], v[114:115], v[152:153] op_sel:[0,1] op_sel_hi:[1,0]
	v_pk_mul_f32 v[58:59], v[118:119], v[192:193] op_sel:[0,1] op_sel_hi:[1,0]
	v_pk_mul_f32 v[60:61], v[122:123], v[162:163] op_sel:[0,1] op_sel_hi:[1,0]
	v_pk_mul_f32 v[62:63], v[124:125], v[178:179] op_sel:[0,1] op_sel_hi:[1,0]
	v_pk_mul_f32 v[64:65], v[126:127], v[128:129] op_sel:[0,1] op_sel_hi:[1,0]
	v_pk_fma_f32 v[38:39], v[68:69], v[180:181], v[38:39] op_sel_hi:[0,1,1]
	v_pk_fma_f32 v[40:41], v[72:73], v[150:151], v[40:41] op_sel_hi:[0,1,1]
	v_pk_fma_f32 v[42:43], v[76:77], v[174:175], v[42:43] op_sel_hi:[0,1,1]
	v_pk_fma_f32 v[44:45], v[80:81], v[160:161], v[44:45] op_sel_hi:[0,1,1]
	v_pk_fma_f32 v[46:47], v[84:85], v[176:177], v[46:47] op_sel_hi:[0,1,1]
	v_pk_fma_f32 v[48:49], v[88:89], v[144:145], v[48:49] op_sel_hi:[0,1,1]
	v_pk_fma_f32 v[50:51], v[92:93], v[172:173], v[50:51] op_sel_hi:[0,1,1]
	v_pk_fma_f32 v[52:53], v[96:97], v[186:187], v[52:53] op_sel_hi:[0,1,1]
	v_pk_fma_f32 v[54:55], v[100:101], v[182:183], v[54:55] op_sel_hi:[0,1,1]
	v_pk_fma_f32 v[56:57], v[104:105], v[152:153], v[56:57] op_sel_hi:[0,1,1]
	v_pk_fma_f32 v[58:59], v[108:109], v[192:193], v[58:59] op_sel_hi:[0,1,1]
	v_pk_fma_f32 v[60:61], v[112:113], v[162:163], v[60:61] op_sel_hi:[0,1,1]
	v_pk_fma_f32 v[62:63], v[116:117], v[178:179], v[62:63] op_sel_hi:[0,1,1]
	v_pk_fma_f32 v[64:65], v[120:121], v[128:129], v[64:65] op_sel_hi:[0,1,1]
	ds_write_b64 v2, v[130:131]
	ds_write_b64 v2, v[34:35] offset:4224
	ds_write_b64 v2, v[18:19] offset:8448
	ds_write_b64 v2, v[50:51] offset:12672
	ds_write_b64 v2, v[10:11] offset:16896
	ds_write_b64 v2, v[42:43] offset:21120
	ds_write_b64 v2, v[26:27] offset:25344
	ds_write_b64 v2, v[58:59] offset:29568
	ds_write_b64 v2, v[6:7] offset:33792
	ds_write_b64 v2, v[38:39] offset:38016
	ds_write_b64 v2, v[22:23] offset:42240
	ds_write_b64 v2, v[54:55] offset:46464
	ds_write_b64 v2, v[14:15] offset:50688
	ds_write_b64 v2, v[46:47] offset:54912
	ds_write_b64 v2, v[30:31] offset:59136
	ds_write_b64 v2, v[62:63] offset:63360
	ds_write_b64 v143, v[4:5]
	ds_write_b64 v212, v[36:37]
	ds_write_b64 v213, v[20:21]
	ds_write_b64 v214, v[52:53]
	ds_write_b64 v215, v[12:13]
	ds_write_b64 v216, v[44:45]
	ds_write_b64 v217, v[28:29]
	ds_write_b64 v218, v[60:61]
	ds_write_b64 v219, v[8:9]
	ds_write_b64 v220, v[40:41]
	ds_write_b64 v221, v[24:25]
	ds_write_b64 v222, v[56:57]
	ds_write_b64 v223, v[16:17]
	ds_write_b64 v224, v[48:49]
	ds_write_b64 v225, v[32:33]
	ds_write_b64 v226, v[64:65]
	v_mov_b32_e32 v2, v142
	s_waitcnt lgkmcnt(0)
	s_barrier
	s_nop 0
	v_and_b32_e32 v4, 15, v2
	v_lshlrev_b32_e32 v2, 5, v2
	v_and_b32_e32 v2, 0xfffffe00, v2
	v_lshl_add_u32 v5, v2, 3, 0
	v_lshlrev_b32_e32 v7, 3, v4
	v_ashrrev_i32_e32 v2, 2, v2
	v_add3_u32 v2, v5, v7, v2
	v_add_u32_e32 v143, 0x800, v2
	ds_read2_b64 v[128:131], v2 offset1:16
	ds_read2_b64 v[148:151], v2 offset0:33 offset1:49
	ds_read2_b64 v[152:155], v2 offset0:66 offset1:82
	ds_read2_b64 v[156:159], v2 offset0:99 offset1:115
	ds_read2_b64 v[160:163], v2 offset0:132 offset1:148
	ds_read2_b64 v[164:167], v2 offset0:165 offset1:181
	ds_read2_b64 v[168:171], v2 offset0:198 offset1:214
	ds_read2_b64 v[172:175], v2 offset0:231 offset1:247
	ds_read2_b64 v[176:179], v143 offset0:8 offset1:24
	ds_read2_b64 v[180:183], v143 offset0:41 offset1:57
	ds_read2_b64 v[184:187], v143 offset0:74 offset1:90
	ds_read2_b64 v[188:191], v143 offset0:107 offset1:123
	ds_read2_b64 v[192:195], v143 offset0:140 offset1:156
	ds_read2_b64 v[196:199], v143 offset0:173 offset1:189
	ds_read2_b64 v[204:207], v143 offset0:206 offset1:222
	ds_read2_b64 v[208:211], v143 offset0:239 offset1:255
	s_waitcnt lgkmcnt(7)
	v_pk_add_f32 v[144:145], v[128:129], v[176:177]
	v_pk_add_f32 v[128:129], v[128:129], v[176:177] neg_lo:[0,1] neg_hi:[0,1]
	v_pk_add_f32 v[176:177], v[130:131], v[178:179]
	v_pk_add_f32 v[130:131], v[130:131], v[178:179] neg_lo:[0,1] neg_hi:[0,1]
	v_cvt_f32_ubyte0_e32 v4, v4
	v_pk_mul_f32 v[178:179], v[130:131], s[20:21]
	v_mul_f32_e32 v6, 0x3b000000, v4
	v_pk_fma_f32 v[130:131], v[130:131], s[10:11], v[178:179] op_sel:[0,0,1] op_sel_hi:[1,0,0]
	s_waitcnt lgkmcnt(6)
	v_pk_add_f32 v[178:179], v[148:149], v[180:181]
	v_pk_add_f32 v[148:149], v[148:149], v[180:181] neg_lo:[0,1] neg_hi:[0,1]
	v_sin_f32_e32 v4, v6
	v_pk_mul_f32 v[180:181], v[148:149], s[24:25]
	v_cos_f32_e32 v6, v6
	v_pk_fma_f32 v[148:149], v[148:149], s[22:23], v[180:181] op_sel:[0,0,1] op_sel_hi:[1,0,0]
	v_pk_add_f32 v[180:181], v[150:151], v[182:183]
	v_pk_add_f32 v[150:151], v[150:151], v[182:183] neg_lo:[0,1] neg_hi:[0,1]
	v_xor_b32_e32 v7, 0x80000000, v4
	v_pk_mul_f32 v[182:183], v[150:151], s[36:37]
	v_mov_b32_e32 v5, v7
	v_pk_fma_f32 v[150:151], v[150:151], s[26:27], v[182:183] op_sel:[0,0,1] op_sel_hi:[1,0,0]
	s_waitcnt lgkmcnt(5)
	v_pk_add_f32 v[182:183], v[152:153], v[184:185]
	v_pk_add_f32 v[152:153], v[152:153], v[184:185] neg_lo:[0,1] neg_hi:[0,1]
	v_pk_mul_f32 v[8:9], v[6:7], v[4:5] op_sel:[1,0] op_sel_hi:[0,1]
	v_pk_mul_f32 v[184:185], v[152:153], s[40:41]
	v_pk_fma_f32 v[8:9], v[6:7], v[6:7], v[8:9] op_sel_hi:[1,0,1]
	v_pk_fma_f32 v[152:153], v[152:153], s[38:39], v[184:185] op_sel:[0,0,1] op_sel_hi:[1,0,0]
	v_pk_add_f32 v[184:185], v[154:155], v[186:187]
	v_pk_add_f32 v[154:155], v[154:155], v[186:187] neg_lo:[0,1] neg_hi:[0,1]
	v_pk_mul_f32 v[14:15], v[8:9], 1.0 op_sel:[1,0] op_sel_hi:[1,0] neg_lo:[1,0]
	v_pk_mul_f32 v[186:187], v[154:155], s[42:43]
	s_nop 0
	v_pk_fma_f32 v[154:155], v[154:155], s[0:1], v[186:187] op_sel:[0,0,1] op_sel_hi:[1,0,0]
	s_waitcnt lgkmcnt(4)
	v_pk_add_f32 v[186:187], v[156:157], v[188:189]
	v_pk_add_f32 v[156:157], v[156:157], v[188:189] neg_lo:[0,1] neg_hi:[0,1]
	v_pk_mul_f32 v[12:13], v[8:9], v[14:15] op_sel:[1,0] op_sel_hi:[0,1]
	v_pk_mul_f32 v[188:189], v[156:157], s[44:45]
	v_pk_fma_f32 v[12:13], v[8:9], v[8:9], v[12:13] op_sel_hi:[1,0,1]
	v_pk_fma_f32 v[156:157], v[156:157], s[50:51], v[188:189] op_sel:[0,0,1] op_sel_hi:[1,0,0]
	v_pk_add_f32 v[188:189], v[158:159], v[190:191]
	v_pk_add_f32 v[158:159], v[158:159], v[190:191] neg_lo:[0,1] neg_hi:[0,1]
	v_pk_mul_f32 v[16:17], v[12:13], 1.0 op_sel:[1,0] op_sel_hi:[1,0] neg_lo:[1,0]
	v_pk_mul_f32 v[190:191], v[158:159], s[8:9]
	s_nop 0
	v_pk_fma_f32 v[158:159], v[158:159], s[16:17], v[190:191] op_sel:[0,0,1] op_sel_hi:[1,0,0]
	s_waitcnt lgkmcnt(3)
	v_pk_add_f32 v[190:191], v[160:161], v[192:193]
	v_pk_add_f32 v[192:193], v[160:161], v[192:193] neg_lo:[0,1] neg_hi:[0,1]
	v_pk_mul_f32 v[28:29], v[12:13], v[16:17] op_sel:[1,0] op_sel_hi:[0,1]
	v_pk_add_f32 v[160:161], v[162:163], v[194:195]
	v_pk_add_f32 v[162:163], v[162:163], v[194:195] neg_lo:[0,1] neg_hi:[0,1]
	v_pk_fma_f32 v[28:29], v[12:13], v[12:13], v[28:29] op_sel_hi:[1,0,1]
	v_pk_mul_f32 v[194:195], v[162:163], s[8:9]
	v_pk_mul_f32 v[44:45], v[16:17], v[28:29] op_sel:[0,1] op_sel_hi:[1,0]
	v_pk_fma_f32 v[162:163], v[162:163], s[16:17], v[194:195] op_sel:[0,0,1] op_sel_hi:[1,0,0] neg_lo:[1,0,0] neg_hi:[1,0,0]
	s_waitcnt lgkmcnt(2)
	v_pk_add_f32 v[194:195], v[164:165], v[196:197]
	v_pk_add_f32 v[164:165], v[164:165], v[196:197] neg_lo:[0,1] neg_hi:[0,1]
	v_pk_fma_f32 v[44:45], v[12:13], v[28:29], v[44:45] op_sel_hi:[0,1,1]
	v_pk_mul_f32 v[196:197], v[164:165], s[44:45]
	v_pk_mul_f32 v[60:61], v[16:17], v[44:45] op_sel:[0,1] op_sel_hi:[1,0]
	v_pk_fma_f32 v[164:165], v[164:165], s[50:51], v[196:197] op_sel:[0,0,1] op_sel_hi:[1,0,0] neg_lo:[1,0,0] neg_hi:[1,0,0]
	v_pk_add_f32 v[196:197], v[166:167], v[198:199]
	v_pk_add_f32 v[166:167], v[166:167], v[198:199] neg_lo:[0,1] neg_hi:[0,1]
	v_pk_fma_f32 v[60:61], v[12:13], v[44:45], v[60:61] op_sel_hi:[0,1,1]
	v_pk_mul_f32 v[198:199], v[166:167], s[42:43]
	v_pk_mul_f32 v[76:77], v[16:17], v[60:61] op_sel:[0,1] op_sel_hi:[1,0]
	v_pk_fma_f32 v[166:167], v[166:167], s[0:1], v[198:199] op_sel:[0,0,1] op_sel_hi:[1,0,0] neg_lo:[1,0,0] neg_hi:[1,0,0]
	s_waitcnt lgkmcnt(1)
	v_pk_add_f32 v[198:199], v[168:169], v[204:205]
	v_pk_add_f32 v[168:169], v[168:169], v[204:205] neg_lo:[0,1] neg_hi:[0,1]
	v_pk_fma_f32 v[76:77], v[12:13], v[60:61], v[76:77] op_sel_hi:[0,1,1]
	v_pk_mul_f32 v[204:205], v[168:169], s[40:41]
	v_pk_mul_f32 v[92:93], v[16:17], v[76:77] op_sel:[0,1] op_sel_hi:[1,0]
	v_pk_fma_f32 v[168:169], v[168:169], s[38:39], v[204:205] op_sel:[0,0,1] op_sel_hi:[1,0,0] neg_lo:[1,0,0] neg_hi:[1,0,0]
	v_pk_add_f32 v[204:205], v[170:171], v[206:207]
	v_pk_add_f32 v[170:171], v[170:171], v[206:207] neg_lo:[0,1] neg_hi:[0,1]
	v_pk_fma_f32 v[92:93], v[12:13], v[76:77], v[92:93] op_sel_hi:[0,1,1]
	v_pk_mul_f32 v[206:207], v[170:171], s[36:37]
	v_pk_mul_f32 v[108:109], v[16:17], v[92:93] op_sel:[0,1] op_sel_hi:[1,0]
	v_pk_fma_f32 v[170:171], v[170:171], s[26:27], v[206:207] op_sel:[0,0,1] op_sel_hi:[1,0,0] neg_lo:[1,0,0] neg_hi:[1,0,0]
	s_waitcnt lgkmcnt(0)
	v_pk_add_f32 v[206:207], v[172:173], v[208:209]
	v_pk_add_f32 v[172:173], v[172:173], v[208:209] neg_lo:[0,1] neg_hi:[0,1]
	v_pk_mul_f32 v[10:11], v[4:5], v[8:9] op_sel:[0,1] op_sel_hi:[1,0]
	v_pk_mul_f32 v[208:209], v[172:173], s[24:25]
	v_pk_fma_f32 v[108:109], v[12:13], v[92:93], v[108:109] op_sel_hi:[0,1,1]
	v_pk_fma_f32 v[172:173], v[172:173], s[22:23], v[208:209] op_sel:[0,0,1] op_sel_hi:[1,0,0] neg_lo:[1,0,0] neg_hi:[1,0,0]
	v_pk_add_f32 v[208:209], v[174:175], v[210:211]
	v_pk_add_f32 v[174:175], v[174:175], v[210:211] neg_lo:[0,1] neg_hi:[0,1]
	v_pk_fma_f32 v[10:11], v[6:7], v[8:9], v[10:11] op_sel_hi:[0,1,1]
	v_pk_mul_f32 v[210:211], v[174:175], s[20:21]
	v_pk_mul_f32 v[18:19], v[4:5], v[12:13] op_sel:[0,1] op_sel_hi:[1,0]
	v_pk_fma_f32 v[174:175], v[174:175], s[10:11], v[210:211] op_sel:[0,0,1] op_sel_hi:[1,0,0] neg_lo:[1,0,0] neg_hi:[1,0,0]
	v_pk_add_f32 v[210:211], v[144:145], v[190:191]
	v_pk_add_f32 v[144:145], v[144:145], v[190:191] neg_lo:[0,1] neg_hi:[0,1]
	v_pk_add_f32 v[190:191], v[176:177], v[160:161]
	v_pk_add_f32 v[160:161], v[176:177], v[160:161] neg_lo:[0,1] neg_hi:[0,1]
	v_pk_mul_f32 v[32:33], v[4:5], v[28:29] op_sel:[0,1] op_sel_hi:[1,0]
	v_pk_mul_f32 v[176:177], v[160:161], s[24:25]
	v_pk_mul_f32 v[48:49], v[4:5], v[44:45] op_sel:[0,1] op_sel_hi:[1,0]
	v_pk_fma_f32 v[160:161], v[160:161], s[22:23], v[176:177] op_sel:[0,0,1] op_sel_hi:[1,0,0]
	v_pk_add_f32 v[176:177], v[178:179], v[194:195]
	v_pk_add_f32 v[178:179], v[178:179], v[194:195] neg_lo:[0,1] neg_hi:[0,1]
	v_pk_mul_f32 v[64:65], v[4:5], v[60:61] op_sel:[0,1] op_sel_hi:[1,0]
	v_pk_mul_f32 v[194:195], v[178:179], s[40:41]
	v_pk_mul_f32 v[80:81], v[4:5], v[76:77] op_sel:[0,1] op_sel_hi:[1,0]
	v_pk_fma_f32 v[178:179], v[178:179], s[38:39], v[194:195] op_sel:[0,0,1] op_sel_hi:[1,0,0]
	v_pk_add_f32 v[194:195], v[180:181], v[196:197]
	v_pk_add_f32 v[180:181], v[180:181], v[196:197] neg_lo:[0,1] neg_hi:[0,1]
	v_pk_mul_f32 v[96:97], v[4:5], v[92:93] op_sel:[0,1] op_sel_hi:[1,0]
	v_pk_mul_f32 v[196:197], v[180:181], s[44:45]
	v_pk_mul_f32 v[112:113], v[4:5], v[108:109] op_sel:[0,1] op_sel_hi:[1,0]
	v_pk_fma_f32 v[180:181], v[180:181], s[50:51], v[196:197] op_sel:[0,0,1] op_sel_hi:[1,0,0]
	v_pk_add_f32 v[196:197], v[182:183], v[198:199]
	v_pk_add_f32 v[198:199], v[182:183], v[198:199] neg_lo:[0,1] neg_hi:[0,1]
	v_pk_mul_f32 v[22:23], v[10:11], 1.0 op_sel:[1,0] op_sel_hi:[1,0] neg_lo:[1,0]
	v_pk_add_f32 v[182:183], v[184:185], v[204:205]
	v_pk_add_f32 v[184:185], v[184:185], v[204:205] neg_lo:[0,1] neg_hi:[0,1]
	s_nop 0
	v_pk_mul_f32 v[204:205], v[184:185], s[44:45]
	v_pk_fma_f32 v[18:19], v[6:7], v[12:13], v[18:19] op_sel_hi:[0,1,1]
	v_pk_fma_f32 v[184:185], v[184:185], s[50:51], v[204:205] op_sel:[0,0,1] op_sel_hi:[1,0,0] neg_lo:[1,0,0] neg_hi:[1,0,0]
	v_pk_add_f32 v[204:205], v[186:187], v[206:207]
	v_pk_add_f32 v[186:187], v[186:187], v[206:207] neg_lo:[0,1] neg_hi:[0,1]
	v_pk_mul_f32 v[20:21], v[14:15], v[12:13] op_sel:[0,1] op_sel_hi:[1,0]
	v_pk_mul_f32 v[206:207], v[186:187], s[40:41]
	v_pk_fma_f32 v[32:33], v[6:7], v[28:29], v[32:33] op_sel_hi:[0,1,1]
	v_pk_fma_f32 v[186:187], v[186:187], s[38:39], v[206:207] op_sel:[0,0,1] op_sel_hi:[1,0,0] neg_lo:[1,0,0] neg_hi:[1,0,0]
	v_pk_add_f32 v[206:207], v[188:189], v[208:209]
	v_pk_add_f32 v[188:189], v[188:189], v[208:209] neg_lo:[0,1] neg_hi:[0,1]
	v_pk_mul_f32 v[36:37], v[14:15], v[28:29] op_sel:[0,1] op_sel_hi:[1,0]
	v_pk_mul_f32 v[208:209], v[188:189], s[24:25]
	v_pk_fma_f32 v[48:49], v[6:7], v[44:45], v[48:49] op_sel_hi:[0,1,1]
	v_pk_fma_f32 v[188:189], v[188:189], s[22:23], v[208:209] op_sel:[0,0,1] op_sel_hi:[1,0,0] neg_lo:[1,0,0] neg_hi:[1,0,0]
	v_pk_add_f32 v[208:209], v[128:129], v[192:193] op_sel:[0,1] op_sel_hi:[1,0] neg_hi:[0,1]
	v_pk_add_f32 v[128:129], v[128:129], v[192:193] op_sel:[0,1] op_sel_hi:[1,0] neg_lo:[0,1]
	v_pk_add_f32 v[192:193], v[130:131], v[162:163]
	v_pk_add_f32 v[130:131], v[130:131], v[162:163] neg_lo:[0,1] neg_hi:[0,1]
	v_pk_mul_f32 v[52:53], v[14:15], v[44:45] op_sel:[0,1] op_sel_hi:[1,0]
	v_pk_mul_f32 v[162:163], v[130:131], s[24:25]
	v_pk_fma_f32 v[64:65], v[6:7], v[60:61], v[64:65] op_sel_hi:[0,1,1]
	v_pk_fma_f32 v[130:131], v[130:131], s[22:23], v[162:163] op_sel:[0,0,1] op_sel_hi:[1,0,0]
	v_pk_add_f32 v[162:163], v[148:149], v[164:165]
	v_pk_add_f32 v[148:149], v[148:149], v[164:165] neg_lo:[0,1] neg_hi:[0,1]
	v_pk_mul_f32 v[68:69], v[14:15], v[60:61] op_sel:[0,1] op_sel_hi:[1,0]
	v_pk_mul_f32 v[164:165], v[148:149], s[40:41]
	v_pk_fma_f32 v[80:81], v[6:7], v[76:77], v[80:81] op_sel_hi:[0,1,1]
	v_pk_fma_f32 v[148:149], v[148:149], s[38:39], v[164:165] op_sel:[0,0,1] op_sel_hi:[1,0,0]
	v_pk_add_f32 v[164:165], v[150:151], v[166:167]
	v_pk_add_f32 v[150:151], v[150:151], v[166:167] neg_lo:[0,1] neg_hi:[0,1]
	v_pk_mul_f32 v[84:85], v[14:15], v[76:77] op_sel:[0,1] op_sel_hi:[1,0]
	v_pk_mul_f32 v[166:167], v[150:151], s[44:45]
	v_pk_fma_f32 v[96:97], v[6:7], v[92:93], v[96:97] op_sel_hi:[0,1,1]
	v_pk_fma_f32 v[150:151], v[150:151], s[50:51], v[166:167] op_sel:[0,0,1] op_sel_hi:[1,0,0]
	v_pk_add_f32 v[166:167], v[152:153], v[168:169]
	v_pk_add_f32 v[168:169], v[152:153], v[168:169] neg_lo:[0,1] neg_hi:[0,1]
	v_pk_mul_f32 v[100:101], v[14:15], v[92:93] op_sel:[0,1] op_sel_hi:[1,0]
	v_pk_add_f32 v[152:153], v[154:155], v[170:171]
	v_pk_add_f32 v[154:155], v[154:155], v[170:171] neg_lo:[0,1] neg_hi:[0,1]
	v_pk_fma_f32 v[112:113], v[6:7], v[108:109], v[112:113] op_sel_hi:[0,1,1]
	v_pk_mul_f32 v[170:171], v[154:155], s[44:45]
	v_pk_mul_f32 v[116:117], v[14:15], v[108:109] op_sel:[0,1] op_sel_hi:[1,0]
	v_pk_fma_f32 v[154:155], v[154:155], s[50:51], v[170:171] op_sel:[0,0,1] op_sel_hi:[1,0,0] neg_lo:[1,0,0] neg_hi:[1,0,0]
	v_pk_add_f32 v[170:171], v[156:157], v[172:173]
	v_pk_add_f32 v[156:157], v[156:157], v[172:173] neg_lo:[0,1] neg_hi:[0,1]
	v_pk_fma_f32 v[20:21], v[8:9], v[12:13], v[20:21] op_sel_hi:[0,1,1]
	v_pk_mul_f32 v[172:173], v[156:157], s[40:41]
	v_pk_mul_f32 v[24:25], v[12:13], v[22:23] op_sel:[1,0] op_sel_hi:[0,1]
	v_pk_fma_f32 v[156:157], v[156:157], s[38:39], v[172:173] op_sel:[0,0,1] op_sel_hi:[1,0,0] neg_lo:[1,0,0] neg_hi:[1,0,0]
	v_pk_add_f32 v[172:173], v[158:159], v[174:175]
	v_pk_add_f32 v[158:159], v[158:159], v[174:175] neg_lo:[0,1] neg_hi:[0,1]
	v_pk_fma_f32 v[36:37], v[8:9], v[28:29], v[36:37] op_sel_hi:[0,1,1]
	v_pk_mul_f32 v[174:175], v[158:159], s[24:25]
	v_pk_mul_f32 v[40:41], v[22:23], v[28:29] op_sel:[0,1] op_sel_hi:[1,0]
	v_pk_fma_f32 v[158:159], v[158:159], s[22:23], v[174:175] op_sel:[0,0,1] op_sel_hi:[1,0,0] neg_lo:[1,0,0] neg_hi:[1,0,0]
	v_pk_add_f32 v[174:175], v[210:211], v[196:197]
	v_pk_add_f32 v[196:197], v[210:211], v[196:197] neg_lo:[0,1] neg_hi:[0,1]
	v_pk_add_f32 v[210:211], v[190:191], v[182:183]
	v_pk_add_f32 v[182:183], v[190:191], v[182:183] neg_lo:[0,1] neg_hi:[0,1]
	v_pk_fma_f32 v[52:53], v[8:9], v[44:45], v[52:53] op_sel_hi:[0,1,1]
	v_pk_mul_f32 v[190:191], v[182:183], s[40:41]
	v_pk_mul_f32 v[56:57], v[22:23], v[44:45] op_sel:[0,1] op_sel_hi:[1,0]
	v_pk_fma_f32 v[182:183], v[182:183], s[38:39], v[190:191] op_sel:[0,0,1] op_sel_hi:[1,0,0]
	v_pk_add_f32 v[190:191], v[176:177], v[204:205]
	v_pk_add_f32 v[204:205], v[176:177], v[204:205] neg_lo:[0,1] neg_hi:[0,1]
	v_pk_fma_f32 v[68:69], v[8:9], v[60:61], v[68:69] op_sel_hi:[0,1,1]
	v_pk_add_f32 v[176:177], v[194:195], v[206:207]
	v_pk_add_f32 v[194:195], v[194:195], v[206:207] neg_lo:[0,1] neg_hi:[0,1]
	v_pk_mul_f32 v[72:73], v[22:23], v[60:61] op_sel:[0,1] op_sel_hi:[1,0]
	v_pk_mul_f32 v[206:207], v[194:195], s[40:41]
	v_pk_fma_f32 v[84:85], v[8:9], v[76:77], v[84:85] op_sel_hi:[0,1,1]
	v_pk_fma_f32 v[194:195], v[194:195], s[38:39], v[206:207] op_sel:[0,0,1] op_sel_hi:[1,0,0] neg_lo:[1,0,0] neg_hi:[1,0,0]
	v_pk_add_f32 v[206:207], v[144:145], v[198:199] op_sel:[0,1] op_sel_hi:[1,0] neg_hi:[0,1]
	v_pk_add_f32 v[144:145], v[144:145], v[198:199] op_sel:[0,1] op_sel_hi:[1,0] neg_lo:[0,1]
	v_pk_add_f32 v[198:199], v[160:161], v[184:185]
	v_pk_add_f32 v[160:161], v[160:161], v[184:185] neg_lo:[0,1] neg_hi:[0,1]
	v_pk_mul_f32 v[88:89], v[22:23], v[76:77] op_sel:[0,1] op_sel_hi:[1,0]
	v_pk_mul_f32 v[184:185], v[160:161], s[40:41]
	v_pk_fma_f32 v[100:101], v[8:9], v[92:93], v[100:101] op_sel_hi:[0,1,1]
	v_pk_fma_f32 v[160:161], v[160:161], s[38:39], v[184:185] op_sel:[0,0,1] op_sel_hi:[1,0,0]
	v_pk_add_f32 v[184:185], v[178:179], v[186:187]
	v_pk_add_f32 v[186:187], v[178:179], v[186:187] neg_lo:[0,1] neg_hi:[0,1]
	v_pk_mul_f32 v[104:105], v[22:23], v[92:93] op_sel:[0,1] op_sel_hi:[1,0]
	v_pk_add_f32 v[178:179], v[180:181], v[188:189]
	v_pk_add_f32 v[180:181], v[180:181], v[188:189] neg_lo:[0,1] neg_hi:[0,1]
	v_pk_fma_f32 v[116:117], v[8:9], v[108:109], v[116:117] op_sel_hi:[0,1,1]
	v_pk_mul_f32 v[188:189], v[180:181], s[40:41]
	v_pk_mul_f32 v[120:121], v[22:23], v[108:109] op_sel:[0,1] op_sel_hi:[1,0]
	v_pk_fma_f32 v[180:181], v[180:181], s[38:39], v[188:189] op_sel:[0,0,1] op_sel_hi:[1,0,0] neg_lo:[1,0,0] neg_hi:[1,0,0]
	v_pk_add_f32 v[188:189], v[208:209], v[166:167]
	v_pk_add_f32 v[166:167], v[208:209], v[166:167] neg_lo:[0,1] neg_hi:[0,1]
	v_pk_add_f32 v[208:209], v[192:193], v[152:153]
	v_pk_add_f32 v[152:153], v[192:193], v[152:153] neg_lo:[0,1] neg_hi:[0,1]
	v_xor_b32_e32 v26, 0x80000000, v19
	v_pk_mul_f32 v[192:193], v[152:153], s[40:41]
	v_xor_b32_e32 v30, 0x80000000, v21
	v_pk_fma_f32 v[152:153], v[152:153], s[38:39], v[192:193] op_sel:[0,0,1] op_sel_hi:[1,0,0]
	v_pk_add_f32 v[192:193], v[162:163], v[170:171]
	v_pk_add_f32 v[170:171], v[162:163], v[170:171] neg_lo:[0,1] neg_hi:[0,1]
	v_pk_fma_f32 v[24:25], v[12:13], v[10:11], v[24:25] op_sel_hi:[1,0,1]
	v_pk_add_f32 v[162:163], v[164:165], v[172:173]
	v_pk_add_f32 v[164:165], v[164:165], v[172:173] neg_lo:[0,1] neg_hi:[0,1]
	v_pk_fma_f32 v[40:41], v[10:11], v[28:29], v[40:41] op_sel_hi:[0,1,1]
	v_pk_mul_f32 v[172:173], v[164:165], s[40:41]
	v_pk_fma_f32 v[56:57], v[10:11], v[44:45], v[56:57] op_sel_hi:[0,1,1]
	v_pk_fma_f32 v[164:165], v[164:165], s[38:39], v[172:173] op_sel:[0,0,1] op_sel_hi:[1,0,0] neg_lo:[1,0,0] neg_hi:[1,0,0]
	v_pk_add_f32 v[172:173], v[128:129], v[168:169] op_sel:[0,1] op_sel_hi:[1,0] neg_hi:[0,1]
	v_pk_add_f32 v[128:129], v[128:129], v[168:169] op_sel:[0,1] op_sel_hi:[1,0] neg_lo:[0,1]
	v_pk_add_f32 v[168:169], v[130:131], v[154:155]
	v_pk_add_f32 v[130:131], v[130:131], v[154:155] neg_lo:[0,1] neg_hi:[0,1]
	v_pk_fma_f32 v[72:73], v[10:11], v[60:61], v[72:73] op_sel_hi:[0,1,1]
	v_pk_mul_f32 v[154:155], v[130:131], s[40:41]
	v_pk_fma_f32 v[88:89], v[10:11], v[76:77], v[88:89] op_sel_hi:[0,1,1]
	v_pk_fma_f32 v[130:131], v[130:131], s[38:39], v[154:155] op_sel:[0,0,1] op_sel_hi:[1,0,0]
	v_pk_add_f32 v[154:155], v[148:149], v[156:157]
	v_pk_add_f32 v[156:157], v[148:149], v[156:157] neg_lo:[0,1] neg_hi:[0,1]
	v_pk_fma_f32 v[104:105], v[10:11], v[92:93], v[104:105] op_sel_hi:[0,1,1]
	v_pk_add_f32 v[148:149], v[150:151], v[158:159]
	v_pk_add_f32 v[150:151], v[150:151], v[158:159] neg_lo:[0,1] neg_hi:[0,1]
	v_pk_fma_f32 v[120:121], v[10:11], v[108:109], v[120:121] op_sel_hi:[0,1,1]
	v_pk_mul_f32 v[158:159], v[150:151], s[40:41]
	v_mov_b32_e32 v27, v19
	v_pk_fma_f32 v[150:151], v[150:151], s[38:39], v[158:159] op_sel:[0,0,1] op_sel_hi:[1,0,0] neg_lo:[1,0,0] neg_hi:[1,0,0]
	v_pk_add_f32 v[158:159], v[174:175], v[190:191]
	v_pk_add_f32 v[174:175], v[174:175], v[190:191] neg_lo:[0,1] neg_hi:[0,1]
	v_pk_add_f32 v[190:191], v[210:211], v[176:177]
	v_pk_add_f32 v[210:211], v[210:211], v[176:177] neg_lo:[0,1] neg_hi:[0,1]
	v_mov_b32_e32 v31, v21
	v_pk_add_f32 v[176:177], v[196:197], v[204:205] op_sel:[0,1] op_sel_hi:[1,0] neg_hi:[0,1]
	v_pk_add_f32 v[196:197], v[196:197], v[204:205] op_sel:[0,1] op_sel_hi:[1,0] neg_lo:[0,1]
	v_pk_add_f32 v[204:205], v[182:183], v[194:195]
	v_pk_add_f32 v[194:195], v[182:183], v[194:195] neg_lo:[0,1] neg_hi:[0,1]
	v_xor_b32_e32 v34, 0x80000000, v25
	v_pk_add_f32 v[182:183], v[206:207], v[184:185]
	v_pk_add_f32 v[184:185], v[206:207], v[184:185] neg_lo:[0,1] neg_hi:[0,1]
	v_pk_add_f32 v[206:207], v[198:199], v[178:179]
	v_pk_add_f32 v[198:199], v[198:199], v[178:179] neg_lo:[0,1] neg_hi:[0,1]
	v_xor_b32_e32 v38, 0x80000000, v29
	v_pk_add_f32 v[178:179], v[144:145], v[186:187] op_sel:[0,1] op_sel_hi:[1,0] neg_hi:[0,1]
	v_pk_add_f32 v[144:145], v[144:145], v[186:187] op_sel:[0,1] op_sel_hi:[1,0] neg_lo:[0,1]
	v_pk_add_f32 v[186:187], v[160:161], v[180:181]
	v_pk_add_f32 v[180:181], v[160:161], v[180:181] neg_lo:[0,1] neg_hi:[0,1]
	v_xor_b32_e32 v42, 0x80000000, v33
	v_pk_add_f32 v[160:161], v[188:189], v[192:193]
	v_pk_add_f32 v[188:189], v[188:189], v[192:193] neg_lo:[0,1] neg_hi:[0,1]
	v_pk_add_f32 v[192:193], v[208:209], v[162:163]
	v_pk_add_f32 v[208:209], v[208:209], v[162:163] neg_lo:[0,1] neg_hi:[0,1]
	v_xor_b32_e32 v46, 0x80000000, v37
	v_pk_add_f32 v[162:163], v[166:167], v[170:171] op_sel:[0,1] op_sel_hi:[1,0] neg_hi:[0,1]
	v_pk_add_f32 v[166:167], v[166:167], v[170:171] op_sel:[0,1] op_sel_hi:[1,0] neg_lo:[0,1]
	v_pk_add_f32 v[170:171], v[152:153], v[164:165]
	v_pk_add_f32 v[164:165], v[152:153], v[164:165] neg_lo:[0,1] neg_hi:[0,1]
	v_mov_b32_e32 v35, v25
	v_pk_add_f32 v[152:153], v[172:173], v[154:155]
	v_pk_add_f32 v[154:155], v[172:173], v[154:155] neg_lo:[0,1] neg_hi:[0,1]
	v_pk_add_f32 v[172:173], v[168:169], v[148:149]
	v_pk_add_f32 v[168:169], v[168:169], v[148:149] neg_lo:[0,1] neg_hi:[0,1]
	v_mov_b32_e32 v39, v29
	v_pk_add_f32 v[148:149], v[128:129], v[156:157] op_sel:[0,1] op_sel_hi:[1,0] neg_hi:[0,1]
	v_pk_add_f32 v[128:129], v[128:129], v[156:157] op_sel:[0,1] op_sel_hi:[1,0] neg_lo:[0,1]
	v_pk_add_f32 v[156:157], v[130:131], v[150:151]
	v_pk_add_f32 v[130:131], v[130:131], v[150:151] neg_lo:[0,1] neg_hi:[0,1]
	v_mov_b32_e32 v43, v33
	v_pk_mul_f32 v[150:151], v[130:131], 1.0 op_sel:[1,0] op_sel_hi:[0,0] neg_hi:[1,0]
	v_pk_add_f32 v[130:131], v[158:159], v[190:191]
	v_pk_add_f32 v[158:159], v[158:159], v[190:191] neg_lo:[0,1] neg_hi:[0,1]
	v_pk_add_f32 v[190:191], v[174:175], v[210:211] op_sel:[0,1] op_sel_hi:[1,0] neg_hi:[0,1]
	v_pk_add_f32 v[174:175], v[174:175], v[210:211] op_sel:[0,1] op_sel_hi:[1,0] neg_lo:[0,1]
	v_pk_add_f32 v[210:211], v[176:177], v[204:205]
	v_pk_add_f32 v[176:177], v[176:177], v[204:205] neg_lo:[0,1] neg_hi:[0,1]
	v_pk_add_f32 v[204:205], v[196:197], v[194:195] op_sel:[0,1] op_sel_hi:[1,0] neg_hi:[0,1]
	v_pk_add_f32 v[194:195], v[196:197], v[194:195] op_sel:[0,1] op_sel_hi:[1,0] neg_lo:[0,1]
	v_pk_add_f32 v[196:197], v[182:183], v[206:207]
	v_pk_add_f32 v[182:183], v[182:183], v[206:207] neg_lo:[0,1] neg_hi:[0,1]
	v_pk_add_f32 v[206:207], v[184:185], v[198:199] op_sel:[0,1] op_sel_hi:[1,0] neg_hi:[0,1]
	v_pk_add_f32 v[184:185], v[184:185], v[198:199] op_sel:[0,1] op_sel_hi:[1,0] neg_lo:[0,1]
	v_pk_add_f32 v[198:199], v[178:179], v[186:187]
	v_pk_add_f32 v[178:179], v[178:179], v[186:187] neg_lo:[0,1] neg_hi:[0,1]
	v_pk_add_f32 v[186:187], v[144:145], v[180:181] op_sel:[0,1] op_sel_hi:[1,0] neg_hi:[0,1]
	v_pk_add_f32 v[144:145], v[144:145], v[180:181] op_sel:[0,1] op_sel_hi:[1,0] neg_lo:[0,1]
	v_pk_add_f32 v[180:181], v[160:161], v[192:193]
	v_pk_add_f32 v[160:161], v[160:161], v[192:193] neg_lo:[0,1] neg_hi:[0,1]
	v_pk_mul_f32 v[4:5], v[4:5], v[180:181] op_sel:[0,1] op_sel_hi:[1,0]
	v_pk_add_f32 v[192:193], v[188:189], v[208:209] op_sel:[0,1] op_sel_hi:[1,0] neg_hi:[0,1]
	v_pk_add_f32 v[188:189], v[188:189], v[208:209] op_sel:[0,1] op_sel_hi:[1,0] neg_lo:[0,1]
	v_pk_add_f32 v[208:209], v[162:163], v[170:171]
	v_pk_add_f32 v[162:163], v[162:163], v[170:171] neg_lo:[0,1] neg_hi:[0,1]
	v_pk_add_f32 v[170:171], v[166:167], v[164:165] op_sel:[0,1] op_sel_hi:[1,0] neg_hi:[0,1]
	v_pk_add_f32 v[164:165], v[166:167], v[164:165] op_sel:[0,1] op_sel_hi:[1,0] neg_lo:[0,1]
	v_pk_add_f32 v[166:167], v[152:153], v[172:173]
	v_pk_fma_f32 v[4:5], v[6:7], v[180:181], v[4:5] op_sel_hi:[0,1,1]
	v_pk_mul_f32 v[6:7], v[14:15], v[196:197] op_sel:[0,1] op_sel_hi:[1,0]
	v_mov_b32_e32 v47, v37
	v_pk_fma_f32 v[6:7], v[8:9], v[196:197], v[6:7] op_sel_hi:[0,1,1]
	v_pk_mul_f32 v[8:9], v[22:23], v[166:167] op_sel:[0,1] op_sel_hi:[1,0]
	v_pk_add_f32 v[152:153], v[152:153], v[172:173] neg_lo:[0,1] neg_hi:[0,1]
	v_pk_fma_f32 v[8:9], v[10:11], v[166:167], v[8:9] op_sel_hi:[0,1,1]
	v_pk_mul_f32 v[10:11], v[16:17], v[210:211] op_sel:[0,1] op_sel_hi:[1,0]
	v_pk_add_f32 v[172:173], v[154:155], v[168:169] op_sel:[0,1] op_sel_hi:[1,0] neg_hi:[0,1]
	v_pk_add_f32 v[154:155], v[154:155], v[168:169] op_sel:[0,1] op_sel_hi:[1,0] neg_lo:[0,1]
	v_pk_add_f32 v[168:169], v[148:149], v[156:157]
	v_pk_fma_f32 v[10:11], v[12:13], v[210:211], v[10:11] op_sel_hi:[0,1,1]
	v_pk_mul_f32 v[12:13], v[26:27], v[208:209] op_sel:[0,1] op_sel_hi:[1,0]
	v_pk_mul_f32 v[14:15], v[30:31], v[198:199] op_sel:[0,1] op_sel_hi:[1,0]
	v_xor_b32_e32 v50, 0x80000000, v41
	v_xor_b32_e32 v54, 0x80000000, v45
	v_xor_b32_e32 v58, 0x80000000, v49
	v_xor_b32_e32 v62, 0x80000000, v53
	v_xor_b32_e32 v66, 0x80000000, v57
	v_xor_b32_e32 v70, 0x80000000, v61
	v_xor_b32_e32 v74, 0x80000000, v65
	v_mov_b32_e32 v51, v41
	v_mov_b32_e32 v55, v45
	v_mov_b32_e32 v59, v49
	v_mov_b32_e32 v63, v53
	v_mov_b32_e32 v67, v57
	v_mov_b32_e32 v71, v61
	v_mov_b32_e32 v75, v65
	v_pk_add_f32 v[148:149], v[148:149], v[156:157] neg_lo:[0,1] neg_hi:[0,1]
	v_pk_add_f32 v[156:157], v[128:129], v[150:151]
	v_pk_fma_f32 v[12:13], v[18:19], v[208:209], v[12:13] op_sel_hi:[0,1,1]
	v_pk_fma_f32 v[14:15], v[20:21], v[198:199], v[14:15] op_sel_hi:[0,1,1]
	v_pk_mul_f32 v[16:17], v[34:35], v[168:169] op_sel:[0,1] op_sel_hi:[1,0]
	v_pk_mul_f32 v[18:19], v[38:39], v[190:191] op_sel:[0,1] op_sel_hi:[1,0]
	v_pk_mul_f32 v[20:21], v[42:43], v[192:193] op_sel:[0,1] op_sel_hi:[1,0]
	v_pk_mul_f32 v[22:23], v[46:47], v[206:207] op_sel:[0,1] op_sel_hi:[1,0]
	v_xor_b32_e32 v78, 0x80000000, v69
	v_xor_b32_e32 v82, 0x80000000, v73
	v_xor_b32_e32 v86, 0x80000000, v77
	v_xor_b32_e32 v90, 0x80000000, v81
	v_xor_b32_e32 v94, 0x80000000, v85
	v_xor_b32_e32 v98, 0x80000000, v89
	v_xor_b32_e32 v102, 0x80000000, v93
	v_xor_b32_e32 v106, 0x80000000, v97
	v_xor_b32_e32 v110, 0x80000000, v101
	v_xor_b32_e32 v114, 0x80000000, v105
	v_xor_b32_e32 v118, 0x80000000, v109
	v_xor_b32_e32 v122, 0x80000000, v113
	v_xor_b32_e32 v124, 0x80000000, v117
	v_xor_b32_e32 v126, 0x80000000, v121
	v_mov_b32_e32 v79, v69
	v_mov_b32_e32 v83, v73
	v_mov_b32_e32 v87, v77
	v_mov_b32_e32 v91, v81
	v_mov_b32_e32 v95, v85
	v_mov_b32_e32 v99, v89
	v_mov_b32_e32 v103, v93
	v_mov_b32_e32 v107, v97
	v_mov_b32_e32 v111, v101
	v_mov_b32_e32 v115, v105
	v_mov_b32_e32 v119, v109
	v_mov_b32_e32 v123, v113
	v_mov_b32_e32 v125, v117
	v_mov_b32_e32 v127, v121
	v_pk_add_f32 v[128:129], v[128:129], v[150:151] neg_lo:[0,1] neg_hi:[0,1]
	v_pk_fma_f32 v[16:17], v[24:25], v[168:169], v[16:17] op_sel_hi:[0,1,1]
	v_pk_fma_f32 v[18:19], v[28:29], v[190:191], v[18:19] op_sel_hi:[0,1,1]
	v_pk_fma_f32 v[20:21], v[32:33], v[192:193], v[20:21] op_sel_hi:[0,1,1]
	v_pk_fma_f32 v[22:23], v[36:37], v[206:207], v[22:23] op_sel_hi:[0,1,1]
	v_pk_mul_f32 v[24:25], v[50:51], v[172:173] op_sel:[0,1] op_sel_hi:[1,0]
	v_pk_mul_f32 v[26:27], v[54:55], v[204:205] op_sel:[0,1] op_sel_hi:[1,0]
	v_pk_mul_f32 v[28:29], v[58:59], v[170:171] op_sel:[0,1] op_sel_hi:[1,0]
	v_pk_mul_f32 v[30:31], v[62:63], v[186:187] op_sel:[0,1] op_sel_hi:[1,0]
	v_pk_mul_f32 v[32:33], v[66:67], v[156:157] op_sel:[0,1] op_sel_hi:[1,0]
	v_pk_mul_f32 v[34:35], v[70:71], v[158:159] op_sel:[0,1] op_sel_hi:[1,0]
	v_pk_mul_f32 v[36:37], v[74:75], v[160:161] op_sel:[0,1] op_sel_hi:[1,0]
	v_pk_fma_f32 v[24:25], v[40:41], v[172:173], v[24:25] op_sel_hi:[0,1,1]
	v_pk_fma_f32 v[26:27], v[44:45], v[204:205], v[26:27] op_sel_hi:[0,1,1]
	v_pk_fma_f32 v[28:29], v[48:49], v[170:171], v[28:29] op_sel_hi:[0,1,1]
	v_pk_fma_f32 v[30:31], v[52:53], v[186:187], v[30:31] op_sel_hi:[0,1,1]
	v_pk_fma_f32 v[32:33], v[56:57], v[156:157], v[32:33] op_sel_hi:[0,1,1]
	v_pk_fma_f32 v[34:35], v[60:61], v[158:159], v[34:35] op_sel_hi:[0,1,1]
	v_pk_fma_f32 v[36:37], v[64:65], v[160:161], v[36:37] op_sel_hi:[0,1,1]
	v_pk_mul_f32 v[38:39], v[78:79], v[182:183] op_sel:[0,1] op_sel_hi:[1,0]
	v_pk_mul_f32 v[40:41], v[82:83], v[152:153] op_sel:[0,1] op_sel_hi:[1,0]
	v_pk_mul_f32 v[42:43], v[86:87], v[176:177] op_sel:[0,1] op_sel_hi:[1,0]
	v_pk_mul_f32 v[44:45], v[90:91], v[162:163] op_sel:[0,1] op_sel_hi:[1,0]
	v_pk_mul_f32 v[46:47], v[94:95], v[178:179] op_sel:[0,1] op_sel_hi:[1,0]
	v_pk_mul_f32 v[48:49], v[98:99], v[148:149] op_sel:[0,1] op_sel_hi:[1,0]
	v_pk_mul_f32 v[50:51], v[102:103], v[174:175] op_sel:[0,1] op_sel_hi:[1,0]
	v_pk_mul_f32 v[52:53], v[106:107], v[188:189] op_sel:[0,1] op_sel_hi:[1,0]
	v_pk_mul_f32 v[54:55], v[110:111], v[184:185] op_sel:[0,1] op_sel_hi:[1,0]
	v_pk_mul_f32 v[56:57], v[114:115], v[154:155] op_sel:[0,1] op_sel_hi:[1,0]
	v_pk_mul_f32 v[58:59], v[118:119], v[194:195] op_sel:[0,1] op_sel_hi:[1,0]
	v_pk_mul_f32 v[60:61], v[122:123], v[164:165] op_sel:[0,1] op_sel_hi:[1,0]
	v_pk_mul_f32 v[62:63], v[124:125], v[144:145] op_sel:[0,1] op_sel_hi:[1,0]
	v_pk_mul_f32 v[64:65], v[126:127], v[128:129] op_sel:[0,1] op_sel_hi:[1,0]
	v_pk_fma_f32 v[38:39], v[68:69], v[182:183], v[38:39] op_sel_hi:[0,1,1]
	v_pk_fma_f32 v[40:41], v[72:73], v[152:153], v[40:41] op_sel_hi:[0,1,1]
	v_pk_fma_f32 v[42:43], v[76:77], v[176:177], v[42:43] op_sel_hi:[0,1,1]
	v_pk_fma_f32 v[44:45], v[80:81], v[162:163], v[44:45] op_sel_hi:[0,1,1]
	v_pk_fma_f32 v[46:47], v[84:85], v[178:179], v[46:47] op_sel_hi:[0,1,1]
	v_pk_fma_f32 v[48:49], v[88:89], v[148:149], v[48:49] op_sel_hi:[0,1,1]
	v_pk_fma_f32 v[50:51], v[92:93], v[174:175], v[50:51] op_sel_hi:[0,1,1]
	v_pk_fma_f32 v[52:53], v[96:97], v[188:189], v[52:53] op_sel_hi:[0,1,1]
	v_pk_fma_f32 v[54:55], v[100:101], v[184:185], v[54:55] op_sel_hi:[0,1,1]
	v_pk_fma_f32 v[56:57], v[104:105], v[154:155], v[56:57] op_sel_hi:[0,1,1]
	v_pk_fma_f32 v[58:59], v[108:109], v[194:195], v[58:59] op_sel_hi:[0,1,1]
	v_pk_fma_f32 v[60:61], v[112:113], v[164:165], v[60:61] op_sel_hi:[0,1,1]
	v_pk_fma_f32 v[62:63], v[116:117], v[144:145], v[62:63] op_sel_hi:[0,1,1]
	v_pk_fma_f32 v[64:65], v[120:121], v[128:129], v[64:65] op_sel_hi:[0,1,1]
	ds_write2_b64 v2, v[130:131], v[34:35] offset1:16
	ds_write2_b64 v2, v[18:19], v[50:51] offset0:33 offset1:49
	ds_write2_b64 v2, v[10:11], v[42:43] offset0:66 offset1:82
	ds_write2_b64 v2, v[26:27], v[58:59] offset0:99 offset1:115
	ds_write2_b64 v2, v[6:7], v[38:39] offset0:132 offset1:148
	ds_write2_b64 v2, v[22:23], v[54:55] offset0:165 offset1:181
	ds_write2_b64 v2, v[14:15], v[46:47] offset0:198 offset1:214
	ds_write2_b64 v2, v[30:31], v[62:63] offset0:231 offset1:247
	ds_write2_b64 v143, v[4:5], v[36:37] offset0:8 offset1:24
	ds_write2_b64 v143, v[20:21], v[52:53] offset0:41 offset1:57
	ds_write2_b64 v143, v[12:13], v[44:45] offset0:74 offset1:90
	ds_write2_b64 v143, v[28:29], v[60:61] offset0:107 offset1:123
	ds_write2_b64 v143, v[8:9], v[40:41] offset0:140 offset1:156
	ds_write2_b64 v143, v[24:25], v[56:57] offset0:173 offset1:189
	ds_write2_b64 v143, v[16:17], v[48:49] offset0:206 offset1:222
	ds_write2_b64 v143, v[32:33], v[64:65] offset0:239 offset1:255
	s_waitcnt lgkmcnt(0)
	s_barrier
	s_nop 0
	v_ashrrev_i32_e32 v2, 31, v142
	v_lshrrev_b32_e32 v2, 23, v2
	v_add_u32_e32 v2, v142, v2
	v_ashrrev_i32_e32 v2, 9, v2
	v_mul_i32_i24_e32 v4, 0x200, v2
	v_sub_u32_e32 v144, v142, v4
	v_lshlrev_b32_e32 v143, 14, v2
	v_lshlrev_b32_e32 v2, 1, v144
	v_bfrev_b32_e32 v2, v2
	v_lshrrev_b32_e32 v2, 22, v2
	v_sub_u32_e32 v2, 0x400, v2
	v_bfrev_b32_e32 v2, v2
	v_lshrrev_b32_e32 v2, 18, v2
	v_and_b32_e32 v2, 0x3ff0, v2
	v_cmp_eq_u32_e32 vcc, 0, v144
	v_lshl_add_u32 v4, v144, 5, v143
	v_lshlrev_b32_e32 v5, 3, v4
	v_cndmask_b32_e64 v2, v2, 16, vcc
	v_ashrrev_i32_e32 v4, 2, v4
	v_or_b32_e32 v2, v2, v143
	v_add3_u32 v56, 0, v5, v4
	v_ashrrev_i32_e32 v4, 5, v2
	v_lshlrev_b32_e32 v2, 3, v2
	v_lshlrev_b32_e32 v4, 3, v4
	v_add3_u32 v2, 0, v2, v4
	ds_read2_b64 v[4:7], v56 offset1:1
	ds_read2_b64 v[8:11], v56 offset0:2 offset1:3
	ds_read2_b64 v[12:15], v2 offset1:1
	ds_read2_b64 v[16:19], v2 offset0:2 offset1:3
	ds_read2_b64 v[20:23], v56 offset0:4 offset1:5
	ds_read2_b64 v[24:27], v56 offset0:6 offset1:7
	ds_read2_b64 v[28:31], v2 offset0:4 offset1:5
	ds_read2_b64 v[32:35], v2 offset0:6 offset1:7
	ds_read2_b64 v[36:39], v56 offset0:8 offset1:9
	ds_read2_b64 v[40:43], v56 offset0:10 offset1:11
	ds_read2_b64 v[48:51], v2 offset0:8 offset1:9
	ds_read2_b64 v[52:55], v2 offset0:10 offset1:11
	ds_read2_b64 v[44:47], v56 offset0:12 offset1:13
	ds_read2_b64 v[56:59], v56 offset0:14 offset1:15
	ds_read2_b64 v[70:73], v2 offset0:12 offset1:13
	ds_read2_b64 v[98:101], v2 offset0:14 offset1:15
	s_waitcnt lgkmcnt(7)
	v_pk_add_f32 v[60:61], v[4:5], v[36:37]
	v_pk_add_f32 v[4:5], v[4:5], v[36:37] neg_lo:[0,1] neg_hi:[0,1]
	v_pk_add_f32 v[36:37], v[6:7], v[38:39]
	v_pk_add_f32 v[6:7], v[6:7], v[38:39] neg_lo:[0,1] neg_hi:[0,1]
	s_waitcnt lgkmcnt(3)
	v_pk_add_f32 v[62:63], v[22:23], v[46:47]
	v_pk_mul_f32 v[38:39], v[6:7], s[24:25]
	v_pk_add_f32 v[22:23], v[22:23], v[46:47] neg_lo:[0,1] neg_hi:[0,1]
	v_pk_fma_f32 v[6:7], v[6:7], s[22:23], v[38:39] op_sel:[0,0,1] op_sel_hi:[1,0,0]
	v_pk_add_f32 v[38:39], v[8:9], v[40:41]
	v_pk_add_f32 v[8:9], v[8:9], v[40:41] neg_lo:[0,1] neg_hi:[0,1]
	v_pk_mul_f32 v[46:47], v[22:23], s[44:45]
	v_pk_mul_f32 v[40:41], v[8:9], s[40:41]
	v_pk_fma_f32 v[22:23], v[22:23], s[50:51], v[46:47] op_sel:[0,0,1] op_sel_hi:[1,0,0] neg_lo:[1,0,0] neg_hi:[1,0,0]
	v_pk_fma_f32 v[8:9], v[8:9], s[38:39], v[40:41] op_sel:[0,0,1] op_sel_hi:[1,0,0]
	v_pk_add_f32 v[40:41], v[10:11], v[42:43]
	v_pk_add_f32 v[10:11], v[10:11], v[42:43] neg_lo:[0,1] neg_hi:[0,1]
	s_waitcnt lgkmcnt(2)
	v_pk_add_f32 v[46:47], v[24:25], v[56:57]
	v_pk_add_f32 v[24:25], v[24:25], v[56:57] neg_lo:[0,1] neg_hi:[0,1]
	v_pk_mul_f32 v[42:43], v[10:11], s[44:45]
	v_pk_mul_f32 v[56:57], v[24:25], s[40:41]
	v_pk_fma_f32 v[10:11], v[10:11], s[50:51], v[42:43] op_sel:[0,0,1] op_sel_hi:[1,0,0]
	v_pk_add_f32 v[42:43], v[20:21], v[44:45]
	v_pk_add_f32 v[44:45], v[20:21], v[44:45] neg_lo:[0,1] neg_hi:[0,1]
	v_pk_fma_f32 v[24:25], v[24:25], s[38:39], v[56:57] op_sel:[0,0,1] op_sel_hi:[1,0,0] neg_lo:[1,0,0] neg_hi:[1,0,0]
	v_pk_add_f32 v[56:57], v[26:27], v[58:59]
	v_pk_add_f32 v[26:27], v[26:27], v[58:59] neg_lo:[0,1] neg_hi:[0,1]
	s_nop 0
	v_pk_mul_f32 v[58:59], v[26:27], s[24:25]
	v_pk_add_f32 v[64:65], v[40:41], v[56:57]
	v_pk_add_f32 v[40:41], v[40:41], v[56:57] neg_lo:[0,1] neg_hi:[0,1]
	v_pk_fma_f32 v[26:27], v[26:27], s[22:23], v[58:59] op_sel:[0,0,1] op_sel_hi:[1,0,0] neg_lo:[1,0,0] neg_hi:[1,0,0]
	v_pk_mul_f32 v[56:57], v[40:41], s[40:41]
	v_pk_add_f32 v[20:21], v[4:5], v[44:45] op_sel:[0,1] op_sel_hi:[1,0] neg_hi:[0,1]
	v_pk_add_f32 v[4:5], v[4:5], v[44:45] op_sel:[0,1] op_sel_hi:[1,0] neg_lo:[0,1]
	v_pk_add_f32 v[44:45], v[6:7], v[22:23]
	v_pk_add_f32 v[6:7], v[6:7], v[22:23] neg_lo:[0,1] neg_hi:[0,1]
	v_pk_fma_f32 v[40:41], v[40:41], s[38:39], v[56:57] op_sel:[0,0,1] op_sel_hi:[1,0,0] neg_lo:[1,0,0] neg_hi:[1,0,0]
	v_pk_mul_f32 v[22:23], v[6:7], s[40:41]
	v_pk_add_f32 v[56:57], v[10:11], v[26:27]
	v_pk_add_f32 v[10:11], v[10:11], v[26:27] neg_lo:[0,1] neg_hi:[0,1]
	v_pk_add_f32 v[58:59], v[60:61], v[42:43]
	v_pk_add_f32 v[42:43], v[60:61], v[42:43] neg_lo:[0,1] neg_hi:[0,1]
	v_pk_add_f32 v[60:61], v[36:37], v[62:63]
	v_pk_add_f32 v[36:37], v[36:37], v[62:63] neg_lo:[0,1] neg_hi:[0,1]
	v_pk_fma_f32 v[6:7], v[6:7], s[38:39], v[22:23] op_sel:[0,0,1] op_sel_hi:[1,0,0]
	v_pk_add_f32 v[22:23], v[8:9], v[24:25]
	v_pk_add_f32 v[24:25], v[8:9], v[24:25] neg_lo:[0,1] neg_hi:[0,1]
	v_pk_mul_f32 v[26:27], v[10:11], s[40:41]
	v_pk_mul_f32 v[62:63], v[36:37], s[40:41]
	v_pk_fma_f32 v[10:11], v[10:11], s[38:39], v[26:27] op_sel:[0,0,1] op_sel_hi:[1,0,0] neg_lo:[1,0,0] neg_hi:[1,0,0]
	v_pk_fma_f32 v[36:37], v[36:37], s[38:39], v[62:63] op_sel:[0,0,1] op_sel_hi:[1,0,0]
	v_pk_add_f32 v[62:63], v[38:39], v[46:47]
	v_pk_add_f32 v[66:67], v[20:21], v[22:23]
	v_pk_add_f32 v[20:21], v[20:21], v[22:23] neg_lo:[0,1] neg_hi:[0,1]
	v_pk_add_f32 v[22:23], v[44:45], v[56:57]
	v_pk_add_f32 v[44:45], v[44:45], v[56:57] neg_lo:[0,1] neg_hi:[0,1]
	v_pk_add_f32 v[8:9], v[4:5], v[24:25] op_sel:[0,1] op_sel_hi:[1,0] neg_hi:[0,1]
	v_pk_add_f32 v[4:5], v[4:5], v[24:25] op_sel:[0,1] op_sel_hi:[1,0] neg_lo:[0,1]
	v_pk_add_f32 v[24:25], v[6:7], v[10:11]
	v_pk_add_f32 v[10:11], v[6:7], v[10:11] neg_lo:[0,1] neg_hi:[0,1]
	v_pk_add_f32 v[26:27], v[58:59], v[62:63]
	v_pk_add_f32 v[58:59], v[58:59], v[62:63] neg_lo:[0,1] neg_hi:[0,1]
	v_pk_add_f32 v[62:63], v[60:61], v[64:65]
	v_pk_add_f32 v[60:61], v[60:61], v[64:65] neg_lo:[0,1] neg_hi:[0,1]
	v_pk_mul_f32 v[56:57], v[44:45], 1.0 op_sel:[1,0] op_sel_hi:[0,0] neg_hi:[1,0]
	v_pk_mul_f32 v[64:65], v[60:61], 1.0 op_sel:[1,0] op_sel_hi:[0,0] neg_hi:[1,0]
	v_pk_add_f32 v[130:131], v[26:27], v[62:63]
	v_pk_add_f32 v[92:93], v[26:27], v[62:63] neg_lo:[0,1] neg_hi:[0,1]
	v_pk_add_f32 v[62:63], v[20:21], v[56:57]
	v_pk_add_f32 v[78:79], v[20:21], v[56:57] neg_lo:[0,1] neg_hi:[0,1]
	v_pk_add_f32 v[56:57], v[4:5], v[10:11] op_sel:[0,1] op_sel_hi:[1,0] neg_hi:[0,1]
	v_pk_add_f32 v[90:91], v[4:5], v[10:11] op_sel:[0,1] op_sel_hi:[1,0] neg_lo:[0,1]
	v_pk_add_f32 v[10:11], v[14:15], v[50:51] neg_lo:[0,1] neg_hi:[0,1]
	v_pk_add_f32 v[46:47], v[38:39], v[46:47] neg_lo:[0,1] neg_hi:[0,1]
	v_pk_add_f32 v[84:85], v[58:59], v[64:65]
	v_pk_add_f32 v[86:87], v[58:59], v[64:65] neg_lo:[0,1] neg_hi:[0,1]
	v_pk_add_f32 v[80:81], v[8:9], v[24:25]
	v_pk_add_f32 v[64:65], v[8:9], v[24:25] neg_lo:[0,1] neg_hi:[0,1]
	v_pk_add_f32 v[4:5], v[12:13], v[48:49]
	v_pk_add_f32 v[6:7], v[12:13], v[48:49] neg_lo:[0,1] neg_hi:[0,1]
	v_pk_add_f32 v[8:9], v[14:15], v[50:51]
	v_pk_mul_f32 v[12:13], v[10:11], s[24:25]
	v_pk_add_f32 v[14:15], v[16:17], v[52:53] neg_lo:[0,1] neg_hi:[0,1]
	v_pk_fma_f32 v[10:11], v[10:11], s[22:23], v[12:13] op_sel:[0,0,1] op_sel_hi:[1,0,0]
	v_pk_add_f32 v[12:13], v[16:17], v[52:53]
	v_pk_mul_f32 v[16:17], v[14:15], s[40:41]
	v_pk_add_f32 v[38:39], v[42:43], v[46:47] op_sel:[0,1] op_sel_hi:[1,0] neg_hi:[0,1]
	v_pk_add_f32 v[42:43], v[42:43], v[46:47] op_sel:[0,1] op_sel_hi:[1,0] neg_lo:[0,1]
	v_pk_add_f32 v[46:47], v[36:37], v[40:41]
	v_pk_fma_f32 v[14:15], v[14:15], s[38:39], v[16:17] op_sel:[0,0,1] op_sel_hi:[1,0,0]
	v_pk_add_f32 v[16:17], v[18:19], v[54:55]
	v_pk_add_f32 v[18:19], v[18:19], v[54:55] neg_lo:[0,1] neg_hi:[0,1]
	v_pk_add_f32 v[88:89], v[38:39], v[46:47]
	v_pk_add_f32 v[68:69], v[38:39], v[46:47] neg_lo:[0,1] neg_hi:[0,1]
	v_pk_add_f32 v[96:97], v[66:67], v[22:23]
	v_pk_add_f32 v[46:47], v[66:67], v[22:23] neg_lo:[0,1] neg_hi:[0,1]
	v_pk_mul_f32 v[20:21], v[18:19], s[44:45]
	s_waitcnt lgkmcnt(1)
	v_pk_add_f32 v[24:25], v[28:29], v[70:71] neg_lo:[0,1] neg_hi:[0,1]
	v_pk_add_f32 v[26:27], v[30:31], v[72:73] neg_lo:[0,1] neg_hi:[0,1]
	v_pk_fma_f32 v[18:19], v[18:19], s[50:51], v[20:21] op_sel:[0,0,1] op_sel_hi:[1,0,0]
	v_pk_add_f32 v[20:21], v[28:29], v[70:71]
	v_pk_add_f32 v[22:23], v[30:31], v[72:73]
	v_pk_mul_f32 v[28:29], v[26:27], s[44:45]
	s_waitcnt lgkmcnt(0)
	v_pk_add_f32 v[30:31], v[32:33], v[98:99] neg_lo:[0,1] neg_hi:[0,1]
	v_pk_fma_f32 v[26:27], v[26:27], s[50:51], v[28:29] op_sel:[0,0,1] op_sel_hi:[1,0,0] neg_lo:[1,0,0] neg_hi:[1,0,0]
	v_pk_add_f32 v[28:29], v[32:33], v[98:99]
	v_pk_mul_f32 v[32:33], v[30:31], s[40:41]
	v_pk_add_f32 v[36:37], v[36:37], v[40:41] neg_lo:[0,1] neg_hi:[0,1]
	v_pk_fma_f32 v[30:31], v[30:31], s[38:39], v[32:33] op_sel:[0,0,1] op_sel_hi:[1,0,0] neg_lo:[1,0,0] neg_hi:[1,0,0]
	v_pk_add_f32 v[32:33], v[34:35], v[100:101]
	v_pk_add_f32 v[34:35], v[34:35], v[100:101] neg_lo:[0,1] neg_hi:[0,1]
	v_pk_mul_f32 v[40:41], v[36:37], 1.0 op_sel:[1,0] op_sel_hi:[0,0] neg_hi:[1,0]
	v_pk_mul_f32 v[36:37], v[34:35], s[24:25]
	v_mov_b32_e32 v2, v130
	v_pk_fma_f32 v[34:35], v[34:35], s[22:23], v[36:37] op_sel:[0,0,1] op_sel_hi:[1,0,0] neg_lo:[1,0,0] neg_hi:[1,0,0]
	v_pk_add_f32 v[36:37], v[4:5], v[20:21]
	v_pk_add_f32 v[4:5], v[4:5], v[20:21] neg_lo:[0,1] neg_hi:[0,1]
	v_pk_add_f32 v[20:21], v[8:9], v[22:23]
	v_pk_add_f32 v[8:9], v[8:9], v[22:23] neg_lo:[0,1] neg_hi:[0,1]
	v_cmp_ne_u32_e64 s[0:1], 0, v144
	v_pk_mul_f32 v[22:23], v[8:9], s[40:41]
	v_pk_add_f32 v[74:75], v[42:43], v[40:41]
	v_pk_fma_f32 v[8:9], v[8:9], s[38:39], v[22:23] op_sel:[0,0,1] op_sel_hi:[1,0,0]
	v_pk_add_f32 v[22:23], v[12:13], v[28:29]
	v_pk_add_f32 v[28:29], v[12:13], v[28:29] neg_lo:[0,1] neg_hi:[0,1]
	v_pk_add_f32 v[94:95], v[42:43], v[40:41] neg_lo:[0,1] neg_hi:[0,1]
	v_pk_add_f32 v[12:13], v[16:17], v[32:33]
	v_pk_add_f32 v[16:17], v[16:17], v[32:33] neg_lo:[0,1] neg_hi:[0,1]
	s_nop 0
	v_pk_mul_f32 v[32:33], v[16:17], s[40:41]
	s_nop 0
	v_pk_fma_f32 v[16:17], v[16:17], s[38:39], v[32:33] op_sel:[0,0,1] op_sel_hi:[1,0,0] neg_lo:[1,0,0] neg_hi:[1,0,0]
	v_pk_add_f32 v[32:33], v[6:7], v[24:25] op_sel:[0,1] op_sel_hi:[1,0] neg_hi:[0,1]
	v_pk_add_f32 v[6:7], v[6:7], v[24:25] op_sel:[0,1] op_sel_hi:[1,0] neg_lo:[0,1]
	v_pk_add_f32 v[24:25], v[10:11], v[26:27]
	v_pk_add_f32 v[10:11], v[10:11], v[26:27] neg_lo:[0,1] neg_hi:[0,1]
	s_nop 0
	v_pk_mul_f32 v[26:27], v[10:11], s[40:41]
	s_nop 0
	v_pk_fma_f32 v[10:11], v[10:11], s[38:39], v[26:27] op_sel:[0,0,1] op_sel_hi:[1,0,0]
	v_pk_add_f32 v[26:27], v[14:15], v[30:31]
	v_pk_add_f32 v[30:31], v[14:15], v[30:31] neg_lo:[0,1] neg_hi:[0,1]
	s_nop 0
	v_pk_add_f32 v[14:15], v[18:19], v[34:35]
	v_pk_add_f32 v[18:19], v[18:19], v[34:35] neg_lo:[0,1] neg_hi:[0,1]
	s_nop 0
	v_pk_mul_f32 v[34:35], v[18:19], s[40:41]
	s_nop 0
	v_pk_fma_f32 v[18:19], v[18:19], s[38:39], v[34:35] op_sel:[0,0,1] op_sel_hi:[1,0,0] neg_lo:[1,0,0] neg_hi:[1,0,0]
	v_pk_add_f32 v[34:35], v[36:37], v[22:23]
	v_pk_add_f32 v[22:23], v[36:37], v[22:23] neg_lo:[0,1] neg_hi:[0,1]
	v_pk_add_f32 v[36:37], v[20:21], v[12:13]
	v_pk_add_f32 v[12:13], v[20:21], v[12:13] neg_lo:[0,1] neg_hi:[0,1]
	v_pk_add_f32 v[98:99], v[34:35], v[36:37]
	v_pk_mul_f32 v[20:21], v[12:13], 1.0 op_sel:[1,0] op_sel_hi:[0,0] neg_hi:[1,0]
	v_pk_add_f32 v[12:13], v[4:5], v[28:29] op_sel:[0,1] op_sel_hi:[1,0] neg_hi:[0,1]
	v_pk_add_f32 v[4:5], v[4:5], v[28:29] op_sel:[0,1] op_sel_hi:[1,0] neg_lo:[0,1]
	v_pk_add_f32 v[28:29], v[8:9], v[16:17]
	v_pk_add_f32 v[8:9], v[8:9], v[16:17] neg_lo:[0,1] neg_hi:[0,1]
	v_pk_add_f32 v[100:101], v[34:35], v[36:37] neg_lo:[0,1] neg_hi:[0,1]
	v_pk_mul_f32 v[16:17], v[8:9], 1.0 op_sel:[1,0] op_sel_hi:[0,0] neg_hi:[1,0]
	v_pk_add_f32 v[8:9], v[32:33], v[26:27]
	v_pk_add_f32 v[26:27], v[32:33], v[26:27] neg_lo:[0,1] neg_hi:[0,1]
	v_pk_add_f32 v[32:33], v[24:25], v[14:15]
	v_pk_add_f32 v[14:15], v[24:25], v[14:15] neg_lo:[0,1] neg_hi:[0,1]
	v_pk_add_f32 v[102:103], v[22:23], v[20:21]
	v_pk_mul_f32 v[24:25], v[14:15], 1.0 op_sel:[1,0] op_sel_hi:[0,0] neg_hi:[1,0]
	v_pk_add_f32 v[14:15], v[6:7], v[30:31] op_sel:[0,1] op_sel_hi:[1,0] neg_hi:[0,1]
	v_pk_add_f32 v[6:7], v[6:7], v[30:31] op_sel:[0,1] op_sel_hi:[1,0] neg_lo:[0,1]
	v_pk_add_f32 v[30:31], v[10:11], v[18:19]
	v_pk_add_f32 v[10:11], v[10:11], v[18:19] neg_lo:[0,1] neg_hi:[0,1]
	v_pk_add_f32 v[104:105], v[22:23], v[20:21] neg_lo:[0,1] neg_hi:[0,1]
	v_pk_mul_f32 v[18:19], v[10:11], 1.0 op_sel:[1,0] op_sel_hi:[0,0] neg_hi:[1,0]
	v_pk_add_f32 v[106:107], v[12:13], v[28:29]
	v_pk_add_f32 v[108:109], v[12:13], v[28:29] neg_lo:[0,1] neg_hi:[0,1]
	v_pk_add_f32 v[110:111], v[4:5], v[16:17]
	v_pk_add_f32 v[112:113], v[4:5], v[16:17] neg_lo:[0,1] neg_hi:[0,1]
	v_pk_add_f32 v[114:115], v[8:9], v[32:33]
	v_pk_add_f32 v[116:117], v[8:9], v[32:33] neg_lo:[0,1] neg_hi:[0,1]
	v_pk_add_f32 v[118:119], v[26:27], v[24:25]
	v_pk_add_f32 v[120:121], v[26:27], v[24:25] neg_lo:[0,1] neg_hi:[0,1]
	v_pk_add_f32 v[122:123], v[14:15], v[30:31]
	v_pk_add_f32 v[124:125], v[14:15], v[30:31] neg_lo:[0,1] neg_hi:[0,1]
	v_pk_add_f32 v[126:127], v[6:7], v[18:19]
	v_pk_add_f32 v[128:129], v[6:7], v[18:19] neg_lo:[0,1] neg_hi:[0,1]
	v_mov_b32_e32 v4, v131
	v_mov_b32_e32 v5, v3
	v_mov_b64_e32 v[6:7], v[2:3]
	s_and_saveexec_b64 s[50:51], s[0:1]
	s_xor_b64 s[0:1], exec, s[50:51]
	s_cbranch_execz .LBB0_562
	v_pk_add_f32 v[4:5], v[96:97], v[112:113]
	v_pk_add_f32 v[24:25], v[96:97], v[112:113] neg_lo:[0,1] neg_hi:[0,1]
	v_pk_add_f32 v[148:149], v[130:131], v[128:129]
	v_pk_add_f32 v[8:9], v[130:131], v[128:129] neg_lo:[0,1] neg_hi:[0,1]
	v_pk_add_f32 v[128:129], v[126:127], v[92:93]
	v_pk_add_f32 v[10:11], v[126:127], v[92:93] neg_lo:[0,1] neg_hi:[0,1]
	v_pk_add_f32 v[92:93], v[84:85], v[124:125]
	v_pk_add_f32 v[12:13], v[84:85], v[124:125] neg_lo:[0,1] neg_hi:[0,1]
	v_pk_add_f32 v[84:85], v[122:123], v[86:87]
	v_pk_add_f32 v[14:15], v[122:123], v[86:87] neg_lo:[0,1] neg_hi:[0,1]
	v_pk_add_f32 v[86:87], v[88:89], v[120:121]
	v_pk_add_f32 v[16:17], v[88:89], v[120:121] neg_lo:[0,1] neg_hi:[0,1]
	v_pk_add_f32 v[88:89], v[118:119], v[68:69]
	v_pk_add_f32 v[18:19], v[118:119], v[68:69] neg_lo:[0,1] neg_hi:[0,1]
	v_pk_add_f32 v[68:69], v[74:75], v[116:117]
	v_pk_add_f32 v[20:21], v[74:75], v[116:117] neg_lo:[0,1] neg_hi:[0,1]
	v_pk_add_f32 v[74:75], v[114:115], v[94:95]
	v_pk_add_f32 v[22:23], v[114:115], v[94:95] neg_lo:[0,1] neg_hi:[0,1]
	v_mov_b32_e32 v6, v4
	v_mov_b32_e32 v7, v25
	v_pk_mov_b32 v[4:5], v[4:5], v[24:25] op_sel:[1,0]
	v_pk_add_f32 v[94:95], v[110:111], v[46:47]
	v_pk_add_f32 v[24:25], v[110:111], v[46:47] neg_lo:[0,1] neg_hi:[0,1]
	v_pk_add_f32 v[46:47], v[62:63], v[108:109]
	v_pk_add_f32 v[26:27], v[62:63], v[108:109] neg_lo:[0,1] neg_hi:[0,1]
	v_pk_add_f32 v[62:63], v[106:107], v[78:79]
	v_pk_add_f32 v[28:29], v[106:107], v[78:79] neg_lo:[0,1] neg_hi:[0,1]
	v_pk_add_f32 v[78:79], v[80:81], v[104:105]
	v_pk_add_f32 v[30:31], v[80:81], v[104:105] neg_lo:[0,1] neg_hi:[0,1]
	v_pk_add_f32 v[80:81], v[102:103], v[64:65]
	v_pk_add_f32 v[32:33], v[102:103], v[64:65] neg_lo:[0,1] neg_hi:[0,1]
	v_pk_add_f32 v[64:65], v[56:57], v[100:101]
	v_pk_add_f32 v[34:35], v[56:57], v[100:101] neg_lo:[0,1] neg_hi:[0,1]
	v_pk_add_f32 v[56:57], v[98:99], v[90:91]
	v_pk_add_f32 v[36:37], v[98:99], v[90:91] neg_lo:[0,1] neg_hi:[0,1]
	v_pk_mul_f32 v[6:7], v[6:7], 0.5 op_sel_hi:[1,0]
	v_pk_mul_f32 v[4:5], v[4:5], s[46:47]
	v_mov_b32_e32 v39, v8
	v_mov_b32_e32 v38, v149
	v_mov_b32_e32 v41, v10
	v_mov_b32_e32 v40, v129
	v_mov_b32_e32 v43, v12
	v_mov_b32_e32 v42, v93
	v_mov_b32_e32 v45, v14
	v_mov_b32_e32 v44, v85
	v_mov_b32_e32 v49, v16
	v_mov_b32_e32 v48, v87
	v_mov_b32_e32 v51, v18
	v_mov_b32_e32 v50, v89
	v_mov_b32_e32 v53, v20
	v_mov_b32_e32 v52, v69
	v_mov_b32_e32 v55, v22
	v_mov_b32_e32 v54, v75
	v_mov_b32_e32 v59, v24
	v_mov_b32_e32 v58, v95
	v_mov_b32_e32 v61, v26
	v_mov_b32_e32 v60, v47
	v_mov_b32_e32 v67, v28
	v_mov_b32_e32 v66, v63
	v_mov_b32_e32 v71, v30
	v_mov_b32_e32 v70, v79
	v_mov_b32_e32 v73, v32
	v_mov_b32_e32 v72, v81
	v_mov_b32_e32 v77, v34
	v_mov_b32_e32 v76, v65
	v_mov_b32_e32 v83, v36
	v_mov_b32_e32 v82, v57
	v_mov_b32_e32 v8, v148
	v_mov_b32_e32 v10, v128
	v_mov_b32_e32 v12, v92
	v_mov_b32_e32 v14, v84
	v_mov_b32_e32 v16, v86
	v_mov_b32_e32 v18, v88
	v_mov_b32_e32 v20, v68
	v_mov_b32_e32 v22, v74
	v_mov_b32_e32 v24, v94
	v_mov_b32_e32 v26, v46
	v_mov_b32_e32 v28, v62
	v_mov_b32_e32 v30, v78
	v_mov_b32_e32 v32, v80
	v_mov_b32_e32 v34, v64
	v_mov_b32_e32 v36, v56

.LBB0_574:
	s_or_b64 exec, exec, s[0:1]
	v_mov_b32_e32 v2, v142
	s_waitcnt lgkmcnt(0)
	s_barrier
	s_mov_b32 s19, s16
	v_and_b32_e32 v4, 0xff, v2
	v_lshlrev_b32_e32 v5, 5, v2
	v_and_or_b32 v4, v5, s68, v4
	v_ashrrev_i32_e32 v5, 5, v4
	v_cvt_f32_ubyte0_e32 v2, v2
	v_lshlrev_b32_e32 v7, 3, v4
	v_mul_f32_e32 v2, 0x39000000, v2
	v_lshlrev_b32_e32 v5, 3, v5
	v_sin_f32_e32 v4, v2
	v_cos_f32_e32 v6, v2
	v_add3_u32 v2, 0, v7, v5
	ds_read_b64 v[128:129], v2
	ds_read_b64 v[130:131], v2 offset:2112
	ds_read_b64 v[144:145], v2 offset:4224
	ds_read_b64 v[148:149], v2 offset:6336
	ds_read_b64 v[150:151], v2 offset:8448
	ds_read_b64 v[152:153], v2 offset:10560
	ds_read_b64 v[154:155], v2 offset:12672
	ds_read_b64 v[156:157], v2 offset:14784
	ds_read_b64 v[158:159], v2 offset:16896
	ds_read_b64 v[160:161], v2 offset:19008
	ds_read_b64 v[162:163], v2 offset:21120
	ds_read_b64 v[164:165], v2 offset:23232
	ds_read_b64 v[166:167], v2 offset:25344
	ds_read_b64 v[168:169], v2 offset:27456
	ds_read_b64 v[170:171], v2 offset:29568
	ds_read_b64 v[172:173], v2 offset:31680
	ds_read_b64 v[174:175], v2 offset:33792
	ds_read_b64 v[176:177], v2 offset:35904
	ds_read_b64 v[178:179], v2 offset:38016
	ds_read_b64 v[180:181], v2 offset:40128
	ds_read_b64 v[182:183], v2 offset:42240
	ds_read_b64 v[184:185], v2 offset:44352
	ds_read_b64 v[186:187], v2 offset:46464
	ds_read_b64 v[188:189], v2 offset:48576
	ds_read_b64 v[190:191], v2 offset:50688
	ds_read_b64 v[192:193], v2 offset:52800
	ds_read_b64 v[194:195], v2 offset:54912
	ds_read_b64 v[196:197], v2 offset:57024
	ds_read_b64 v[198:199], v2 offset:59136
	ds_read_b64 v[204:205], v2 offset:61248
	ds_read_b64 v[206:207], v2 offset:63360
	ds_read_b64 v[208:209], v2 offset:65472
	s_waitcnt lgkmcnt(14)
	v_pk_add_f32 v[210:211], v[128:129], v[174:175]
	v_pk_add_f32 v[128:129], v[128:129], v[174:175] neg_lo:[0,1] neg_hi:[0,1]
	v_pk_add_f32 v[174:175], v[130:131], v[176:177]
	v_pk_add_f32 v[130:131], v[130:131], v[176:177] neg_lo:[0,1] neg_hi:[0,1]
	s_mov_b32 s0, s9
	v_pk_mul_f32 v[176:177], v[130:131], s[18:19]
	s_mov_b32 s41, s38
	v_pk_fma_f32 v[130:131], v[130:131], s[0:1], v[176:177] op_sel:[0,0,1] op_sel_hi:[1,0,0]
	s_waitcnt lgkmcnt(13)
	v_pk_add_f32 v[176:177], v[144:145], v[178:179]
	v_pk_add_f32 v[144:145], v[144:145], v[178:179] neg_lo:[0,1] neg_hi:[0,1]
	s_mov_b32 s43, s26
	v_pk_mul_f32 v[178:179], v[144:145], s[24:25]
	s_mov_b32 s62, s37
	v_pk_fma_f32 v[144:145], v[144:145], s[22:23], v[178:179] op_sel:[0,0,1] op_sel_hi:[1,0,0]
	s_waitcnt lgkmcnt(12)
	v_pk_add_f32 v[178:179], v[148:149], v[180:181]
	v_pk_add_f32 v[148:149], v[148:149], v[180:181] neg_lo:[0,1] neg_hi:[0,1]
	s_mov_b32 s45, s22
	v_pk_mul_f32 v[180:181], v[148:149], s[36:37]
	s_mov_b32 s50, s25
	v_pk_fma_f32 v[148:149], v[148:149], s[26:27], v[180:181] op_sel:[0,0,1] op_sel_hi:[1,0,0]
	s_waitcnt lgkmcnt(11)
	v_pk_add_f32 v[180:181], v[150:151], v[182:183]
	v_pk_add_f32 v[150:151], v[150:151], v[182:183] neg_lo:[0,1] neg_hi:[0,1]
	v_xor_b32_e32 v7, 0x80000000, v4
	v_pk_mul_f32 v[182:183], v[150:151], s[40:41]
	v_mov_b32_e32 v5, v7
	v_pk_fma_f32 v[150:151], v[150:151], s[38:39], v[182:183] op_sel:[0,0,1] op_sel_hi:[1,0,0]
	s_waitcnt lgkmcnt(10)
	v_pk_add_f32 v[182:183], v[152:153], v[184:185]
	v_pk_add_f32 v[152:153], v[152:153], v[184:185] neg_lo:[0,1] neg_hi:[0,1]
	v_pk_mul_f32 v[8:9], v[6:7], v[4:5] op_sel:[1,0] op_sel_hi:[0,1]
	v_pk_mul_f32 v[184:185], v[152:153], s[42:43]
	v_pk_fma_f32 v[8:9], v[6:7], v[6:7], v[8:9] op_sel_hi:[1,0,1]
	v_pk_fma_f32 v[152:153], v[152:153], s[62:63], v[184:185] op_sel:[0,0,1] op_sel_hi:[1,0,0]
	s_waitcnt lgkmcnt(9)
	v_pk_add_f32 v[184:185], v[154:155], v[186:187]
	v_pk_add_f32 v[154:155], v[154:155], v[186:187] neg_lo:[0,1] neg_hi:[0,1]
	v_pk_mul_f32 v[14:15], v[8:9], 1.0 op_sel:[1,0] op_sel_hi:[1,0] neg_lo:[1,0]
	v_pk_mul_f32 v[186:187], v[154:155], s[44:45]
	s_nop 0
	v_pk_fma_f32 v[154:155], v[154:155], s[50:51], v[186:187] op_sel:[0,0,1] op_sel_hi:[1,0,0]
	s_waitcnt lgkmcnt(8)
	v_pk_add_f32 v[186:187], v[156:157], v[188:189]
	v_pk_add_f32 v[156:157], v[156:157], v[188:189] neg_lo:[0,1] neg_hi:[0,1]
	v_pk_mul_f32 v[12:13], v[8:9], v[14:15] op_sel:[1,0] op_sel_hi:[0,1]
	v_pk_mul_f32 v[188:189], v[156:157], s[8:9]
	v_pk_fma_f32 v[12:13], v[8:9], v[8:9], v[12:13] op_sel_hi:[1,0,1]
	v_pk_fma_f32 v[156:157], v[156:157], s[16:17], v[188:189] op_sel:[0,0,1] op_sel_hi:[1,0,0]
	s_waitcnt lgkmcnt(7)
	v_pk_add_f32 v[188:189], v[158:159], v[190:191]
	v_pk_add_f32 v[190:191], v[158:159], v[190:191] neg_lo:[0,1] neg_hi:[0,1]
	v_pk_mul_f32 v[16:17], v[12:13], 1.0 op_sel:[1,0] op_sel_hi:[1,0] neg_lo:[1,0]
	s_waitcnt lgkmcnt(6)
	v_pk_add_f32 v[158:159], v[160:161], v[192:193]
	v_pk_add_f32 v[160:161], v[160:161], v[192:193] neg_lo:[0,1] neg_hi:[0,1]
	s_nop 0
	v_pk_mul_f32 v[192:193], v[160:161], s[8:9]
	v_pk_mul_f32 v[28:29], v[12:13], v[16:17] op_sel:[1,0] op_sel_hi:[0,1]
	v_pk_fma_f32 v[160:161], v[160:161], s[16:17], v[192:193] op_sel:[0,0,1] op_sel_hi:[1,0,0] neg_lo:[1,0,0] neg_hi:[1,0,0]
	s_waitcnt lgkmcnt(5)
	v_pk_add_f32 v[192:193], v[162:163], v[194:195]
	v_pk_add_f32 v[162:163], v[162:163], v[194:195] neg_lo:[0,1] neg_hi:[0,1]
	v_pk_fma_f32 v[28:29], v[12:13], v[12:13], v[28:29] op_sel_hi:[1,0,1]
	v_pk_mul_f32 v[194:195], v[162:163], s[44:45]
	v_pk_mul_f32 v[44:45], v[16:17], v[28:29] op_sel:[0,1] op_sel_hi:[1,0]
	v_pk_fma_f32 v[162:163], v[162:163], s[50:51], v[194:195] op_sel:[0,0,1] op_sel_hi:[1,0,0] neg_lo:[1,0,0] neg_hi:[1,0,0]
	s_waitcnt lgkmcnt(4)
	v_pk_add_f32 v[194:195], v[164:165], v[196:197]
	v_pk_add_f32 v[164:165], v[164:165], v[196:197] neg_lo:[0,1] neg_hi:[0,1]
	v_pk_fma_f32 v[44:45], v[12:13], v[28:29], v[44:45] op_sel_hi:[0,1,1]
	v_pk_mul_f32 v[196:197], v[164:165], s[42:43]
	v_pk_mul_f32 v[60:61], v[16:17], v[44:45] op_sel:[0,1] op_sel_hi:[1,0]
	v_pk_fma_f32 v[164:165], v[164:165], s[62:63], v[196:197] op_sel:[0,0,1] op_sel_hi:[1,0,0] neg_lo:[1,0,0] neg_hi:[1,0,0]
	s_waitcnt lgkmcnt(3)
	v_pk_add_f32 v[196:197], v[166:167], v[198:199]
	v_pk_add_f32 v[166:167], v[166:167], v[198:199] neg_lo:[0,1] neg_hi:[0,1]
	v_pk_fma_f32 v[60:61], v[12:13], v[44:45], v[60:61] op_sel_hi:[0,1,1]
	v_pk_mul_f32 v[198:199], v[166:167], s[40:41]
	v_pk_mul_f32 v[76:77], v[16:17], v[60:61] op_sel:[0,1] op_sel_hi:[1,0]
	v_pk_fma_f32 v[166:167], v[166:167], s[38:39], v[198:199] op_sel:[0,0,1] op_sel_hi:[1,0,0] neg_lo:[1,0,0] neg_hi:[1,0,0]
	s_waitcnt lgkmcnt(2)
	v_pk_add_f32 v[198:199], v[168:169], v[204:205]
	v_pk_add_f32 v[168:169], v[168:169], v[204:205] neg_lo:[0,1] neg_hi:[0,1]
	v_pk_fma_f32 v[76:77], v[12:13], v[60:61], v[76:77] op_sel_hi:[0,1,1]
	v_pk_mul_f32 v[204:205], v[168:169], s[36:37]
	v_pk_mul_f32 v[92:93], v[16:17], v[76:77] op_sel:[0,1] op_sel_hi:[1,0]
	v_pk_fma_f32 v[168:169], v[168:169], s[26:27], v[204:205] op_sel:[0,0,1] op_sel_hi:[1,0,0] neg_lo:[1,0,0] neg_hi:[1,0,0]
	s_waitcnt lgkmcnt(1)
	v_pk_add_f32 v[204:205], v[170:171], v[206:207]
	v_pk_add_f32 v[170:171], v[170:171], v[206:207] neg_lo:[0,1] neg_hi:[0,1]
	v_pk_fma_f32 v[92:93], v[12:13], v[76:77], v[92:93] op_sel_hi:[0,1,1]
	v_pk_mul_f32 v[206:207], v[170:171], s[24:25]
	v_pk_mul_f32 v[108:109], v[16:17], v[92:93] op_sel:[0,1] op_sel_hi:[1,0]
	v_pk_fma_f32 v[170:171], v[170:171], s[22:23], v[206:207] op_sel:[0,0,1] op_sel_hi:[1,0,0] neg_lo:[1,0,0] neg_hi:[1,0,0]
	s_waitcnt lgkmcnt(0)
	v_pk_add_f32 v[206:207], v[172:173], v[208:209]
	v_pk_add_f32 v[172:173], v[172:173], v[208:209] neg_lo:[0,1] neg_hi:[0,1]
	v_pk_mul_f32 v[10:11], v[4:5], v[8:9] op_sel:[0,1] op_sel_hi:[1,0]
	v_pk_mul_f32 v[208:209], v[172:173], s[18:19]
	v_pk_fma_f32 v[108:109], v[12:13], v[92:93], v[108:109] op_sel_hi:[0,1,1]
	v_pk_fma_f32 v[172:173], v[172:173], s[0:1], v[208:209] op_sel:[0,0,1] op_sel_hi:[1,0,0] neg_lo:[1,0,0] neg_hi:[1,0,0]
	v_pk_add_f32 v[208:209], v[210:211], v[188:189]
	v_pk_add_f32 v[188:189], v[210:211], v[188:189] neg_lo:[0,1] neg_hi:[0,1]
	v_pk_add_f32 v[210:211], v[174:175], v[158:159]
	v_pk_add_f32 v[158:159], v[174:175], v[158:159] neg_lo:[0,1] neg_hi:[0,1]
	v_pk_fma_f32 v[10:11], v[6:7], v[8:9], v[10:11] op_sel_hi:[0,1,1]
	v_pk_mul_f32 v[174:175], v[158:159], s[24:25]
	v_pk_mul_f32 v[18:19], v[4:5], v[12:13] op_sel:[0,1] op_sel_hi:[1,0]
	v_pk_fma_f32 v[158:159], v[158:159], s[22:23], v[174:175] op_sel:[0,0,1] op_sel_hi:[1,0,0]
	v_pk_add_f32 v[174:175], v[176:177], v[192:193]
	v_pk_add_f32 v[176:177], v[176:177], v[192:193] neg_lo:[0,1] neg_hi:[0,1]
	v_pk_mul_f32 v[32:33], v[4:5], v[28:29] op_sel:[0,1] op_sel_hi:[1,0]
	v_pk_mul_f32 v[192:193], v[176:177], s[40:41]
	v_pk_mul_f32 v[48:49], v[4:5], v[44:45] op_sel:[0,1] op_sel_hi:[1,0]
	v_pk_fma_f32 v[176:177], v[176:177], s[38:39], v[192:193] op_sel:[0,0,1] op_sel_hi:[1,0,0]
	v_pk_add_f32 v[192:193], v[178:179], v[194:195]
	v_pk_add_f32 v[178:179], v[178:179], v[194:195] neg_lo:[0,1] neg_hi:[0,1]
	v_pk_mul_f32 v[64:65], v[4:5], v[60:61] op_sel:[0,1] op_sel_hi:[1,0]
	v_pk_mul_f32 v[194:195], v[178:179], s[44:45]
	v_pk_mul_f32 v[80:81], v[4:5], v[76:77] op_sel:[0,1] op_sel_hi:[1,0]
	v_pk_fma_f32 v[178:179], v[178:179], s[50:51], v[194:195] op_sel:[0,0,1] op_sel_hi:[1,0,0]
	v_pk_add_f32 v[194:195], v[180:181], v[196:197]
	v_pk_add_f32 v[196:197], v[180:181], v[196:197] neg_lo:[0,1] neg_hi:[0,1]
	v_pk_mul_f32 v[96:97], v[4:5], v[92:93] op_sel:[0,1] op_sel_hi:[1,0]
	v_pk_add_f32 v[180:181], v[182:183], v[198:199]
	v_pk_add_f32 v[182:183], v[182:183], v[198:199] neg_lo:[0,1] neg_hi:[0,1]
	v_pk_mul_f32 v[112:113], v[4:5], v[108:109] op_sel:[0,1] op_sel_hi:[1,0]
	v_pk_mul_f32 v[198:199], v[182:183], s[44:45]
	v_pk_mul_f32 v[22:23], v[10:11], 1.0 op_sel:[1,0] op_sel_hi:[1,0] neg_lo:[1,0]
	v_pk_fma_f32 v[182:183], v[182:183], s[50:51], v[198:199] op_sel:[0,0,1] op_sel_hi:[1,0,0] neg_lo:[1,0,0] neg_hi:[1,0,0]
	v_pk_add_f32 v[198:199], v[184:185], v[204:205]
	v_pk_add_f32 v[184:185], v[184:185], v[204:205] neg_lo:[0,1] neg_hi:[0,1]
	s_nop 0
	v_pk_mul_f32 v[204:205], v[184:185], s[40:41]
	v_pk_fma_f32 v[18:19], v[6:7], v[12:13], v[18:19] op_sel_hi:[0,1,1]
	v_pk_fma_f32 v[184:185], v[184:185], s[38:39], v[204:205] op_sel:[0,0,1] op_sel_hi:[1,0,0] neg_lo:[1,0,0] neg_hi:[1,0,0]
	v_pk_add_f32 v[204:205], v[186:187], v[206:207]
	v_pk_add_f32 v[186:187], v[186:187], v[206:207] neg_lo:[0,1] neg_hi:[0,1]
	v_pk_mul_f32 v[20:21], v[14:15], v[12:13] op_sel:[0,1] op_sel_hi:[1,0]
	v_pk_mul_f32 v[206:207], v[186:187], s[24:25]
	v_pk_fma_f32 v[32:33], v[6:7], v[28:29], v[32:33] op_sel_hi:[0,1,1]
	v_pk_fma_f32 v[186:187], v[186:187], s[22:23], v[206:207] op_sel:[0,0,1] op_sel_hi:[1,0,0] neg_lo:[1,0,0] neg_hi:[1,0,0]
	v_pk_add_f32 v[206:207], v[128:129], v[190:191] op_sel:[0,1] op_sel_hi:[1,0] neg_hi:[0,1]
	v_pk_add_f32 v[128:129], v[128:129], v[190:191] op_sel:[0,1] op_sel_hi:[1,0] neg_lo:[0,1]
	v_pk_add_f32 v[190:191], v[130:131], v[160:161]
	v_pk_add_f32 v[130:131], v[130:131], v[160:161] neg_lo:[0,1] neg_hi:[0,1]
	v_pk_mul_f32 v[36:37], v[14:15], v[28:29] op_sel:[0,1] op_sel_hi:[1,0]
	v_pk_mul_f32 v[160:161], v[130:131], s[24:25]
	v_pk_fma_f32 v[48:49], v[6:7], v[44:45], v[48:49] op_sel_hi:[0,1,1]
	v_pk_fma_f32 v[130:131], v[130:131], s[22:23], v[160:161] op_sel:[0,0,1] op_sel_hi:[1,0,0]
	v_pk_add_f32 v[160:161], v[144:145], v[162:163]
	v_pk_add_f32 v[144:145], v[144:145], v[162:163] neg_lo:[0,1] neg_hi:[0,1]
	v_pk_mul_f32 v[52:53], v[14:15], v[44:45] op_sel:[0,1] op_sel_hi:[1,0]
	v_pk_mul_f32 v[162:163], v[144:145], s[40:41]
	v_pk_fma_f32 v[64:65], v[6:7], v[60:61], v[64:65] op_sel_hi:[0,1,1]
	v_pk_fma_f32 v[144:145], v[144:145], s[38:39], v[162:163] op_sel:[0,0,1] op_sel_hi:[1,0,0]
	v_pk_add_f32 v[162:163], v[148:149], v[164:165]
	v_pk_add_f32 v[148:149], v[148:149], v[164:165] neg_lo:[0,1] neg_hi:[0,1]
	v_pk_mul_f32 v[68:69], v[14:15], v[60:61] op_sel:[0,1] op_sel_hi:[1,0]
	v_pk_mul_f32 v[164:165], v[148:149], s[44:45]
	v_pk_fma_f32 v[80:81], v[6:7], v[76:77], v[80:81] op_sel_hi:[0,1,1]
	v_pk_fma_f32 v[148:149], v[148:149], s[50:51], v[164:165] op_sel:[0,0,1] op_sel_hi:[1,0,0]
	v_pk_add_f32 v[164:165], v[150:151], v[166:167]
	v_pk_add_f32 v[166:167], v[150:151], v[166:167] neg_lo:[0,1] neg_hi:[0,1]
	v_pk_mul_f32 v[84:85], v[14:15], v[76:77] op_sel:[0,1] op_sel_hi:[1,0]
	v_pk_add_f32 v[150:151], v[152:153], v[168:169]
	v_pk_add_f32 v[152:153], v[152:153], v[168:169] neg_lo:[0,1] neg_hi:[0,1]
	v_pk_fma_f32 v[96:97], v[6:7], v[92:93], v[96:97] op_sel_hi:[0,1,1]
	v_pk_mul_f32 v[168:169], v[152:153], s[44:45]
	v_pk_mul_f32 v[100:101], v[14:15], v[92:93] op_sel:[0,1] op_sel_hi:[1,0]
	v_pk_fma_f32 v[152:153], v[152:153], s[50:51], v[168:169] op_sel:[0,0,1] op_sel_hi:[1,0,0] neg_lo:[1,0,0] neg_hi:[1,0,0]
	v_pk_add_f32 v[168:169], v[154:155], v[170:171]
	v_pk_add_f32 v[154:155], v[154:155], v[170:171] neg_lo:[0,1] neg_hi:[0,1]
	v_pk_fma_f32 v[112:113], v[6:7], v[108:109], v[112:113] op_sel_hi:[0,1,1]
	v_pk_mul_f32 v[170:171], v[154:155], s[40:41]
	v_pk_mul_f32 v[116:117], v[14:15], v[108:109] op_sel:[0,1] op_sel_hi:[1,0]
	v_pk_fma_f32 v[154:155], v[154:155], s[38:39], v[170:171] op_sel:[0,0,1] op_sel_hi:[1,0,0] neg_lo:[1,0,0] neg_hi:[1,0,0]
	v_pk_add_f32 v[170:171], v[156:157], v[172:173]
	v_pk_add_f32 v[156:157], v[156:157], v[172:173] neg_lo:[0,1] neg_hi:[0,1]
	v_pk_fma_f32 v[20:21], v[8:9], v[12:13], v[20:21] op_sel_hi:[0,1,1]
	v_pk_mul_f32 v[172:173], v[156:157], s[24:25]
	v_pk_mul_f32 v[24:25], v[12:13], v[22:23] op_sel:[1,0] op_sel_hi:[0,1]
	v_pk_fma_f32 v[156:157], v[156:157], s[22:23], v[172:173] op_sel:[0,0,1] op_sel_hi:[1,0,0] neg_lo:[1,0,0] neg_hi:[1,0,0]
	v_pk_add_f32 v[172:173], v[208:209], v[194:195]
	v_pk_add_f32 v[194:195], v[208:209], v[194:195] neg_lo:[0,1] neg_hi:[0,1]
	v_pk_add_f32 v[208:209], v[210:211], v[180:181]
	v_pk_add_f32 v[180:181], v[210:211], v[180:181] neg_lo:[0,1] neg_hi:[0,1]
	v_pk_fma_f32 v[36:37], v[8:9], v[28:29], v[36:37] op_sel_hi:[0,1,1]
	v_pk_mul_f32 v[210:211], v[180:181], s[40:41]
	v_pk_mul_f32 v[40:41], v[22:23], v[28:29] op_sel:[0,1] op_sel_hi:[1,0]
	v_pk_fma_f32 v[180:181], v[180:181], s[38:39], v[210:211] op_sel:[0,0,1] op_sel_hi:[1,0,0]
	v_pk_add_f32 v[210:211], v[174:175], v[198:199]
	v_pk_add_f32 v[198:199], v[174:175], v[198:199] neg_lo:[0,1] neg_hi:[0,1]
	v_pk_fma_f32 v[52:53], v[8:9], v[44:45], v[52:53] op_sel_hi:[0,1,1]
	v_pk_add_f32 v[174:175], v[192:193], v[204:205]
	v_pk_add_f32 v[192:193], v[192:193], v[204:205] neg_lo:[0,1] neg_hi:[0,1]
	v_pk_mul_f32 v[56:57], v[22:23], v[44:45] op_sel:[0,1] op_sel_hi:[1,0]
	v_pk_mul_f32 v[204:205], v[192:193], s[40:41]
	v_pk_fma_f32 v[68:69], v[8:9], v[60:61], v[68:69] op_sel_hi:[0,1,1]
	v_pk_fma_f32 v[192:193], v[192:193], s[38:39], v[204:205] op_sel:[0,0,1] op_sel_hi:[1,0,0] neg_lo:[1,0,0] neg_hi:[1,0,0]
	v_pk_add_f32 v[204:205], v[188:189], v[196:197] op_sel:[0,1] op_sel_hi:[1,0] neg_hi:[0,1]
	v_pk_add_f32 v[188:189], v[188:189], v[196:197] op_sel:[0,1] op_sel_hi:[1,0] neg_lo:[0,1]
	v_pk_add_f32 v[196:197], v[158:159], v[182:183]
	v_pk_add_f32 v[158:159], v[158:159], v[182:183] neg_lo:[0,1] neg_hi:[0,1]
	v_pk_mul_f32 v[72:73], v[22:23], v[60:61] op_sel:[0,1] op_sel_hi:[1,0]
	v_pk_mul_f32 v[182:183], v[158:159], s[40:41]
	v_pk_fma_f32 v[84:85], v[8:9], v[76:77], v[84:85] op_sel_hi:[0,1,1]
	v_pk_fma_f32 v[158:159], v[158:159], s[38:39], v[182:183] op_sel:[0,0,1] op_sel_hi:[1,0,0]
	v_pk_add_f32 v[182:183], v[176:177], v[184:185]
	v_pk_add_f32 v[184:185], v[176:177], v[184:185] neg_lo:[0,1] neg_hi:[0,1]
	v_pk_mul_f32 v[88:89], v[22:23], v[76:77] op_sel:[0,1] op_sel_hi:[1,0]
	v_pk_add_f32 v[176:177], v[178:179], v[186:187]
	v_pk_add_f32 v[178:179], v[178:179], v[186:187] neg_lo:[0,1] neg_hi:[0,1]
	v_pk_fma_f32 v[100:101], v[8:9], v[92:93], v[100:101] op_sel_hi:[0,1,1]
	v_pk_mul_f32 v[186:187], v[178:179], s[40:41]
	v_pk_mul_f32 v[104:105], v[22:23], v[92:93] op_sel:[0,1] op_sel_hi:[1,0]
	v_pk_fma_f32 v[178:179], v[178:179], s[38:39], v[186:187] op_sel:[0,0,1] op_sel_hi:[1,0,0] neg_lo:[1,0,0] neg_hi:[1,0,0]
	v_pk_add_f32 v[186:187], v[206:207], v[164:165]
	v_pk_add_f32 v[164:165], v[206:207], v[164:165] neg_lo:[0,1] neg_hi:[0,1]
	v_pk_add_f32 v[206:207], v[190:191], v[150:151]
	v_pk_add_f32 v[150:151], v[190:191], v[150:151] neg_lo:[0,1] neg_hi:[0,1]
	v_pk_fma_f32 v[116:117], v[8:9], v[108:109], v[116:117] op_sel_hi:[0,1,1]
	v_pk_mul_f32 v[190:191], v[150:151], s[40:41]
	v_pk_mul_f32 v[120:121], v[22:23], v[108:109] op_sel:[0,1] op_sel_hi:[1,0]
	v_pk_fma_f32 v[150:151], v[150:151], s[38:39], v[190:191] op_sel:[0,0,1] op_sel_hi:[1,0,0]
	v_pk_add_f32 v[190:191], v[160:161], v[168:169]
	v_pk_add_f32 v[168:169], v[160:161], v[168:169] neg_lo:[0,1] neg_hi:[0,1]
	v_xor_b32_e32 v26, 0x80000000, v19
	v_pk_add_f32 v[160:161], v[162:163], v[170:171]
	v_pk_add_f32 v[162:163], v[162:163], v[170:171] neg_lo:[0,1] neg_hi:[0,1]
	v_xor_b32_e32 v30, 0x80000000, v21
	v_pk_mul_f32 v[170:171], v[162:163], s[40:41]
	v_pk_fma_f32 v[24:25], v[12:13], v[10:11], v[24:25] op_sel_hi:[1,0,1]
	v_pk_fma_f32 v[162:163], v[162:163], s[38:39], v[170:171] op_sel:[0,0,1] op_sel_hi:[1,0,0] neg_lo:[1,0,0] neg_hi:[1,0,0]
	v_pk_add_f32 v[170:171], v[128:129], v[166:167] op_sel:[0,1] op_sel_hi:[1,0] neg_hi:[0,1]
	v_pk_add_f32 v[128:129], v[128:129], v[166:167] op_sel:[0,1] op_sel_hi:[1,0] neg_lo:[0,1]
	v_pk_add_f32 v[166:167], v[130:131], v[152:153]
	v_pk_add_f32 v[130:131], v[130:131], v[152:153] neg_lo:[0,1] neg_hi:[0,1]
	v_pk_fma_f32 v[40:41], v[10:11], v[28:29], v[40:41] op_sel_hi:[0,1,1]
	v_pk_mul_f32 v[152:153], v[130:131], s[40:41]
	v_pk_fma_f32 v[56:57], v[10:11], v[44:45], v[56:57] op_sel_hi:[0,1,1]
	v_pk_fma_f32 v[130:131], v[130:131], s[38:39], v[152:153] op_sel:[0,0,1] op_sel_hi:[1,0,0]
	v_pk_add_f32 v[152:153], v[144:145], v[154:155]
	v_pk_add_f32 v[154:155], v[144:145], v[154:155] neg_lo:[0,1] neg_hi:[0,1]
	v_pk_fma_f32 v[72:73], v[10:11], v[60:61], v[72:73] op_sel_hi:[0,1,1]
	v_pk_add_f32 v[144:145], v[148:149], v[156:157]
	v_pk_add_f32 v[148:149], v[148:149], v[156:157] neg_lo:[0,1] neg_hi:[0,1]
	v_pk_fma_f32 v[88:89], v[10:11], v[76:77], v[88:89] op_sel_hi:[0,1,1]
	v_pk_mul_f32 v[156:157], v[148:149], s[40:41]
	v_pk_fma_f32 v[104:105], v[10:11], v[92:93], v[104:105] op_sel_hi:[0,1,1]
	v_pk_fma_f32 v[148:149], v[148:149], s[38:39], v[156:157] op_sel:[0,0,1] op_sel_hi:[1,0,0] neg_lo:[1,0,0] neg_hi:[1,0,0]
	v_pk_add_f32 v[156:157], v[172:173], v[210:211]
	v_pk_add_f32 v[172:173], v[172:173], v[210:211] neg_lo:[0,1] neg_hi:[0,1]
	v_pk_add_f32 v[210:211], v[208:209], v[174:175]
	v_pk_add_f32 v[208:209], v[208:209], v[174:175] neg_lo:[0,1] neg_hi:[0,1]
	v_pk_fma_f32 v[120:121], v[10:11], v[108:109], v[120:121] op_sel_hi:[0,1,1]
	v_pk_add_f32 v[174:175], v[194:195], v[198:199] op_sel:[0,1] op_sel_hi:[1,0] neg_hi:[0,1]
	v_pk_add_f32 v[194:195], v[194:195], v[198:199] op_sel:[0,1] op_sel_hi:[1,0] neg_lo:[0,1]
	v_pk_add_f32 v[198:199], v[180:181], v[192:193]
	v_pk_add_f32 v[192:193], v[180:181], v[192:193] neg_lo:[0,1] neg_hi:[0,1]
	v_mov_b32_e32 v27, v19
	v_pk_add_f32 v[180:181], v[204:205], v[182:183]
	v_pk_add_f32 v[182:183], v[204:205], v[182:183] neg_lo:[0,1] neg_hi:[0,1]
	v_pk_add_f32 v[204:205], v[196:197], v[176:177]
	v_pk_add_f32 v[196:197], v[196:197], v[176:177] neg_lo:[0,1] neg_hi:[0,1]
	v_mov_b32_e32 v31, v21
	v_pk_add_f32 v[176:177], v[188:189], v[184:185] op_sel:[0,1] op_sel_hi:[1,0] neg_hi:[0,1]
	v_pk_add_f32 v[184:185], v[188:189], v[184:185] op_sel:[0,1] op_sel_hi:[1,0] neg_lo:[0,1]
	v_pk_add_f32 v[188:189], v[158:159], v[178:179]
	v_pk_add_f32 v[178:179], v[158:159], v[178:179] neg_lo:[0,1] neg_hi:[0,1]
	v_xor_b32_e32 v34, 0x80000000, v25
	v_pk_add_f32 v[158:159], v[186:187], v[190:191]
	v_pk_add_f32 v[186:187], v[186:187], v[190:191] neg_lo:[0,1] neg_hi:[0,1]
	v_pk_add_f32 v[190:191], v[206:207], v[160:161]
	v_pk_add_f32 v[206:207], v[206:207], v[160:161] neg_lo:[0,1] neg_hi:[0,1]
	v_xor_b32_e32 v38, 0x80000000, v29
	v_pk_add_f32 v[160:161], v[164:165], v[168:169] op_sel:[0,1] op_sel_hi:[1,0] neg_hi:[0,1]
	v_pk_add_f32 v[164:165], v[164:165], v[168:169] op_sel:[0,1] op_sel_hi:[1,0] neg_lo:[0,1]
	v_pk_add_f32 v[168:169], v[150:151], v[162:163]
	v_pk_add_f32 v[162:163], v[150:151], v[162:163] neg_lo:[0,1] neg_hi:[0,1]
	v_xor_b32_e32 v42, 0x80000000, v33
	v_pk_add_f32 v[150:151], v[170:171], v[152:153]
	v_pk_add_f32 v[152:153], v[170:171], v[152:153] neg_lo:[0,1] neg_hi:[0,1]
	v_pk_add_f32 v[170:171], v[166:167], v[144:145]
	v_pk_add_f32 v[166:167], v[166:167], v[144:145] neg_lo:[0,1] neg_hi:[0,1]
	v_xor_b32_e32 v46, 0x80000000, v37
	v_pk_add_f32 v[144:145], v[128:129], v[154:155] op_sel:[0,1] op_sel_hi:[1,0] neg_hi:[0,1]
	v_pk_add_f32 v[128:129], v[128:129], v[154:155] op_sel:[0,1] op_sel_hi:[1,0] neg_lo:[0,1]
	v_pk_add_f32 v[154:155], v[130:131], v[148:149]
	v_pk_add_f32 v[130:131], v[130:131], v[148:149] neg_lo:[0,1] neg_hi:[0,1]
	v_mov_b32_e32 v35, v25
	v_pk_mul_f32 v[148:149], v[130:131], 1.0 op_sel:[1,0] op_sel_hi:[0,0] neg_hi:[1,0]
	v_pk_add_f32 v[130:131], v[156:157], v[210:211]
	v_pk_add_f32 v[156:157], v[156:157], v[210:211] neg_lo:[0,1] neg_hi:[0,1]
	v_pk_add_f32 v[210:211], v[172:173], v[208:209] op_sel:[0,1] op_sel_hi:[1,0] neg_hi:[0,1]
	v_pk_add_f32 v[172:173], v[172:173], v[208:209] op_sel:[0,1] op_sel_hi:[1,0] neg_lo:[0,1]
	v_pk_add_f32 v[208:209], v[174:175], v[198:199]
	v_pk_add_f32 v[174:175], v[174:175], v[198:199] neg_lo:[0,1] neg_hi:[0,1]
	v_pk_add_f32 v[198:199], v[194:195], v[192:193] op_sel:[0,1] op_sel_hi:[1,0] neg_hi:[0,1]
	v_pk_add_f32 v[192:193], v[194:195], v[192:193] op_sel:[0,1] op_sel_hi:[1,0] neg_lo:[0,1]
	v_pk_add_f32 v[194:195], v[180:181], v[204:205]
	v_pk_add_f32 v[180:181], v[180:181], v[204:205] neg_lo:[0,1] neg_hi:[0,1]
	v_pk_add_f32 v[204:205], v[182:183], v[196:197] op_sel:[0,1] op_sel_hi:[1,0] neg_hi:[0,1]
	v_pk_add_f32 v[182:183], v[182:183], v[196:197] op_sel:[0,1] op_sel_hi:[1,0] neg_lo:[0,1]
	v_pk_add_f32 v[196:197], v[176:177], v[188:189]
	v_pk_add_f32 v[176:177], v[176:177], v[188:189] neg_lo:[0,1] neg_hi:[0,1]
	v_pk_add_f32 v[188:189], v[184:185], v[178:179] op_sel:[0,1] op_sel_hi:[1,0] neg_hi:[0,1]
	v_pk_add_f32 v[178:179], v[184:185], v[178:179] op_sel:[0,1] op_sel_hi:[1,0] neg_lo:[0,1]
	v_pk_add_f32 v[184:185], v[158:159], v[190:191]
	v_pk_add_f32 v[158:159], v[158:159], v[190:191] neg_lo:[0,1] neg_hi:[0,1]
	v_pk_mul_f32 v[4:5], v[4:5], v[184:185] op_sel:[0,1] op_sel_hi:[1,0]
	v_pk_add_f32 v[190:191], v[186:187], v[206:207] op_sel:[0,1] op_sel_hi:[1,0] neg_hi:[0,1]
	v_pk_add_f32 v[186:187], v[186:187], v[206:207] op_sel:[0,1] op_sel_hi:[1,0] neg_lo:[0,1]
	v_pk_add_f32 v[206:207], v[160:161], v[168:169]
	v_pk_add_f32 v[160:161], v[160:161], v[168:169] neg_lo:[0,1] neg_hi:[0,1]
	v_pk_add_f32 v[168:169], v[164:165], v[162:163] op_sel:[0,1] op_sel_hi:[1,0] neg_hi:[0,1]
	v_pk_add_f32 v[162:163], v[164:165], v[162:163] op_sel:[0,1] op_sel_hi:[1,0] neg_lo:[0,1]
	v_pk_add_f32 v[164:165], v[150:151], v[170:171]
	v_pk_fma_f32 v[4:5], v[6:7], v[184:185], v[4:5] op_sel_hi:[0,1,1]
	v_pk_mul_f32 v[6:7], v[14:15], v[194:195] op_sel:[0,1] op_sel_hi:[1,0]
	v_mov_b32_e32 v39, v29
	v_pk_fma_f32 v[6:7], v[8:9], v[194:195], v[6:7] op_sel_hi:[0,1,1]
	v_pk_mul_f32 v[8:9], v[22:23], v[164:165] op_sel:[0,1] op_sel_hi:[1,0]
	v_mov_b32_e32 v43, v33
	v_pk_fma_f32 v[8:9], v[10:11], v[164:165], v[8:9] op_sel_hi:[0,1,1]
	v_pk_mul_f32 v[10:11], v[16:17], v[208:209] op_sel:[0,1] op_sel_hi:[1,0]
	v_mov_b32_e32 v47, v37
	v_pk_add_f32 v[150:151], v[150:151], v[170:171] neg_lo:[0,1] neg_hi:[0,1]
	v_pk_add_f32 v[170:171], v[152:153], v[166:167] op_sel:[0,1] op_sel_hi:[1,0] neg_hi:[0,1]
	v_pk_add_f32 v[152:153], v[152:153], v[166:167] op_sel:[0,1] op_sel_hi:[1,0] neg_lo:[0,1]
	v_pk_add_f32 v[166:167], v[144:145], v[154:155]
	v_pk_fma_f32 v[10:11], v[12:13], v[208:209], v[10:11] op_sel_hi:[0,1,1]
	v_pk_mul_f32 v[12:13], v[26:27], v[206:207] op_sel:[0,1] op_sel_hi:[1,0]
	v_pk_mul_f32 v[14:15], v[30:31], v[196:197] op_sel:[0,1] op_sel_hi:[1,0]
	v_xor_b32_e32 v50, 0x80000000, v41
	v_xor_b32_e32 v54, 0x80000000, v45
	v_xor_b32_e32 v58, 0x80000000, v49
	v_xor_b32_e32 v62, 0x80000000, v53
	v_xor_b32_e32 v66, 0x80000000, v57
	v_xor_b32_e32 v70, 0x80000000, v61
	v_xor_b32_e32 v74, 0x80000000, v65
	v_mov_b32_e32 v51, v41
	v_mov_b32_e32 v55, v45
	v_mov_b32_e32 v59, v49
	v_mov_b32_e32 v63, v53
	v_mov_b32_e32 v67, v57
	v_mov_b32_e32 v71, v61
	v_mov_b32_e32 v75, v65
	v_pk_add_f32 v[144:145], v[144:145], v[154:155] neg_lo:[0,1] neg_hi:[0,1]
	v_pk_add_f32 v[154:155], v[128:129], v[148:149]
	v_pk_fma_f32 v[12:13], v[18:19], v[206:207], v[12:13] op_sel_hi:[0,1,1]
	v_pk_fma_f32 v[14:15], v[20:21], v[196:197], v[14:15] op_sel_hi:[0,1,1]
	v_pk_mul_f32 v[16:17], v[34:35], v[166:167] op_sel:[0,1] op_sel_hi:[1,0]
	v_pk_mul_f32 v[18:19], v[38:39], v[210:211] op_sel:[0,1] op_sel_hi:[1,0]
	v_pk_mul_f32 v[20:21], v[42:43], v[190:191] op_sel:[0,1] op_sel_hi:[1,0]
	v_pk_mul_f32 v[22:23], v[46:47], v[204:205] op_sel:[0,1] op_sel_hi:[1,0]
	v_xor_b32_e32 v78, 0x80000000, v69
	v_xor_b32_e32 v82, 0x80000000, v73
	v_xor_b32_e32 v86, 0x80000000, v77
	v_xor_b32_e32 v90, 0x80000000, v81
	v_xor_b32_e32 v94, 0x80000000, v85
	v_xor_b32_e32 v98, 0x80000000, v89
	v_xor_b32_e32 v102, 0x80000000, v93
	v_xor_b32_e32 v106, 0x80000000, v97
	v_xor_b32_e32 v110, 0x80000000, v101
	v_xor_b32_e32 v114, 0x80000000, v105
	v_xor_b32_e32 v118, 0x80000000, v109
	v_xor_b32_e32 v122, 0x80000000, v113
	v_xor_b32_e32 v124, 0x80000000, v117
	v_xor_b32_e32 v126, 0x80000000, v121
	v_mov_b32_e32 v79, v69
	v_mov_b32_e32 v83, v73
	v_mov_b32_e32 v87, v77
	v_mov_b32_e32 v91, v81
	v_mov_b32_e32 v95, v85
	v_mov_b32_e32 v99, v89
	v_mov_b32_e32 v103, v93
	v_mov_b32_e32 v107, v97
	v_mov_b32_e32 v111, v101
	v_mov_b32_e32 v115, v105
	v_mov_b32_e32 v119, v109
	v_mov_b32_e32 v123, v113
	v_mov_b32_e32 v125, v117
	v_mov_b32_e32 v127, v121
	v_pk_add_f32 v[128:129], v[128:129], v[148:149] neg_lo:[0,1] neg_hi:[0,1]
	v_pk_fma_f32 v[16:17], v[24:25], v[166:167], v[16:17] op_sel_hi:[0,1,1]
	v_pk_fma_f32 v[18:19], v[28:29], v[210:211], v[18:19] op_sel_hi:[0,1,1]
	v_pk_fma_f32 v[20:21], v[32:33], v[190:191], v[20:21] op_sel_hi:[0,1,1]
	v_pk_fma_f32 v[22:23], v[36:37], v[204:205], v[22:23] op_sel_hi:[0,1,1]
	v_pk_mul_f32 v[24:25], v[50:51], v[170:171] op_sel:[0,1] op_sel_hi:[1,0]
	v_pk_mul_f32 v[26:27], v[54:55], v[198:199] op_sel:[0,1] op_sel_hi:[1,0]
	v_pk_mul_f32 v[28:29], v[58:59], v[168:169] op_sel:[0,1] op_sel_hi:[1,0]
	v_pk_mul_f32 v[30:31], v[62:63], v[188:189] op_sel:[0,1] op_sel_hi:[1,0]
	v_pk_mul_f32 v[32:33], v[66:67], v[154:155] op_sel:[0,1] op_sel_hi:[1,0]
	v_pk_mul_f32 v[34:35], v[70:71], v[156:157] op_sel:[0,1] op_sel_hi:[1,0]
	v_pk_mul_f32 v[36:37], v[74:75], v[158:159] op_sel:[0,1] op_sel_hi:[1,0]
	v_pk_fma_f32 v[24:25], v[40:41], v[170:171], v[24:25] op_sel_hi:[0,1,1]
	v_pk_fma_f32 v[26:27], v[44:45], v[198:199], v[26:27] op_sel_hi:[0,1,1]
	v_pk_fma_f32 v[28:29], v[48:49], v[168:169], v[28:29] op_sel_hi:[0,1,1]
	v_pk_fma_f32 v[30:31], v[52:53], v[188:189], v[30:31] op_sel_hi:[0,1,1]
	v_pk_fma_f32 v[32:33], v[56:57], v[154:155], v[32:33] op_sel_hi:[0,1,1]
	v_pk_fma_f32 v[34:35], v[60:61], v[156:157], v[34:35] op_sel_hi:[0,1,1]
	v_pk_fma_f32 v[36:37], v[64:65], v[158:159], v[36:37] op_sel_hi:[0,1,1]
	v_pk_mul_f32 v[38:39], v[78:79], v[180:181] op_sel:[0,1] op_sel_hi:[1,0]
	v_pk_mul_f32 v[40:41], v[82:83], v[150:151] op_sel:[0,1] op_sel_hi:[1,0]
	v_pk_mul_f32 v[42:43], v[86:87], v[174:175] op_sel:[0,1] op_sel_hi:[1,0]
	v_pk_mul_f32 v[44:45], v[90:91], v[160:161] op_sel:[0,1] op_sel_hi:[1,0]
	v_pk_mul_f32 v[46:47], v[94:95], v[176:177] op_sel:[0,1] op_sel_hi:[1,0]
	v_pk_mul_f32 v[48:49], v[98:99], v[144:145] op_sel:[0,1] op_sel_hi:[1,0]
	v_pk_mul_f32 v[50:51], v[102:103], v[172:173] op_sel:[0,1] op_sel_hi:[1,0]
	v_pk_mul_f32 v[52:53], v[106:107], v[186:187] op_sel:[0,1] op_sel_hi:[1,0]
	v_pk_mul_f32 v[54:55], v[110:111], v[182:183] op_sel:[0,1] op_sel_hi:[1,0]
	v_pk_mul_f32 v[56:57], v[114:115], v[152:153] op_sel:[0,1] op_sel_hi:[1,0]
	v_pk_mul_f32 v[58:59], v[118:119], v[192:193] op_sel:[0,1] op_sel_hi:[1,0]
	v_pk_mul_f32 v[60:61], v[122:123], v[162:163] op_sel:[0,1] op_sel_hi:[1,0]
	v_pk_mul_f32 v[62:63], v[124:125], v[178:179] op_sel:[0,1] op_sel_hi:[1,0]
	v_pk_mul_f32 v[64:65], v[126:127], v[128:129] op_sel:[0,1] op_sel_hi:[1,0]
	v_pk_fma_f32 v[38:39], v[68:69], v[180:181], v[38:39] op_sel_hi:[0,1,1]
	v_pk_fma_f32 v[40:41], v[72:73], v[150:151], v[40:41] op_sel_hi:[0,1,1]
	v_pk_fma_f32 v[42:43], v[76:77], v[174:175], v[42:43] op_sel_hi:[0,1,1]
	v_pk_fma_f32 v[44:45], v[80:81], v[160:161], v[44:45] op_sel_hi:[0,1,1]
	v_pk_fma_f32 v[46:47], v[84:85], v[176:177], v[46:47] op_sel_hi:[0,1,1]
	v_pk_fma_f32 v[48:49], v[88:89], v[144:145], v[48:49] op_sel_hi:[0,1,1]
	v_pk_fma_f32 v[50:51], v[92:93], v[172:173], v[50:51] op_sel_hi:[0,1,1]
	v_pk_fma_f32 v[52:53], v[96:97], v[186:187], v[52:53] op_sel_hi:[0,1,1]
	v_pk_fma_f32 v[54:55], v[100:101], v[182:183], v[54:55] op_sel_hi:[0,1,1]
	v_pk_fma_f32 v[56:57], v[104:105], v[152:153], v[56:57] op_sel_hi:[0,1,1]
	v_pk_fma_f32 v[58:59], v[108:109], v[192:193], v[58:59] op_sel_hi:[0,1,1]
	v_pk_fma_f32 v[60:61], v[112:113], v[162:163], v[60:61] op_sel_hi:[0,1,1]
	v_pk_fma_f32 v[62:63], v[116:117], v[178:179], v[62:63] op_sel_hi:[0,1,1]
	v_pk_fma_f32 v[64:65], v[120:121], v[128:129], v[64:65] op_sel_hi:[0,1,1]
	ds_write_b64 v2, v[130:131]
	ds_write_b64 v2, v[34:35] offset:2112
	ds_write_b64 v2, v[18:19] offset:4224
	ds_write_b64 v2, v[50:51] offset:6336
	ds_write_b64 v2, v[10:11] offset:8448
	ds_write_b64 v2, v[42:43] offset:10560
	ds_write_b64 v2, v[26:27] offset:12672
	ds_write_b64 v2, v[58:59] offset:14784
	ds_write_b64 v2, v[6:7] offset:16896
	ds_write_b64 v2, v[38:39] offset:19008
	ds_write_b64 v2, v[22:23] offset:21120
	ds_write_b64 v2, v[54:55] offset:23232
	ds_write_b64 v2, v[14:15] offset:25344
	ds_write_b64 v2, v[46:47] offset:27456
	ds_write_b64 v2, v[30:31] offset:29568
	ds_write_b64 v2, v[62:63] offset:31680
	ds_write_b64 v2, v[4:5] offset:33792
	ds_write_b64 v2, v[36:37] offset:35904
	ds_write_b64 v2, v[20:21] offset:38016
	ds_write_b64 v2, v[52:53] offset:40128
	ds_write_b64 v2, v[12:13] offset:42240
	ds_write_b64 v2, v[44:45] offset:44352
	ds_write_b64 v2, v[28:29] offset:46464
	ds_write_b64 v2, v[60:61] offset:48576
	ds_write_b64 v2, v[8:9] offset:50688
	ds_write_b64 v2, v[40:41] offset:52800
	ds_write_b64 v2, v[24:25] offset:54912
	ds_write_b64 v2, v[56:57] offset:57024
	ds_write_b64 v2, v[16:17] offset:59136
	ds_write_b64 v2, v[48:49] offset:61248
	ds_write_b64 v2, v[32:33] offset:63360
	ds_write_b64 v2, v[64:65] offset:65472
	v_mov_b32_e32 v2, v142
	s_waitcnt lgkmcnt(0)
	s_barrier
	s_nop 0
	v_and_b32_e32 v5, 15, v2
	v_cvt_f32_ubyte0_e32 v4, v5
	v_mul_f32_e32 v6, 0x3b800000, v4
	v_sin_f32_e32 v4, v6
	v_cos_f32_e32 v6, v6
	v_lshlrev_b32_e32 v64, 3, v5
	v_lshlrev_b32_e32 v2, 4, v2
	v_xor_b32_e32 v7, 0x80000000, v4
	v_mov_b32_e32 v5, v7
	v_pk_mul_f32 v[8:9], v[6:7], v[4:5] op_sel:[1,0] op_sel_hi:[0,1]
	v_pk_fma_f32 v[8:9], v[6:7], v[6:7], v[8:9] op_sel_hi:[1,0,1]
	v_and_b32_e32 v2, 0xffffff00, v2
	v_pk_mul_f32 v[14:15], 1.0, v[8:9] op_sel:[0,1] op_sel_hi:[0,1] neg_lo:[0,1]
	v_pk_mul_f32 v[12:13], v[8:9], v[14:15] op_sel:[1,0] op_sel_hi:[0,1]
	v_pk_fma_f32 v[12:13], v[8:9], v[8:9], v[12:13] op_sel_hi:[1,0,1]
	v_pk_mul_f32 v[10:11], v[4:5], v[8:9] op_sel:[0,1] op_sel_hi:[1,0]
	v_pk_mul_f32 v[16:17], 1.0, v[12:13] op_sel:[0,1] op_sel_hi:[0,1] neg_lo:[0,1]
	v_pk_mul_f32 v[32:33], v[12:13], v[16:17] op_sel:[1,0] op_sel_hi:[0,1]
	v_pk_fma_f32 v[32:33], v[12:13], v[12:13], v[32:33] op_sel_hi:[1,0,1]
	v_pk_mul_f32 v[18:19], v[4:5], v[12:13] op_sel:[0,1] op_sel_hi:[1,0]
	v_pk_mul_f32 v[48:49], v[16:17], v[32:33] op_sel:[0,1] op_sel_hi:[1,0]
	v_pk_mul_f32 v[36:37], v[4:5], v[32:33] op_sel:[0,1] op_sel_hi:[1,0]
	v_pk_fma_f32 v[48:49], v[12:13], v[32:33], v[48:49] op_sel_hi:[0,1,1]
	v_pk_mul_f32 v[52:53], v[4:5], v[48:49] op_sel:[0,1] op_sel_hi:[1,0]
	v_pk_fma_f32 v[10:11], v[6:7], v[8:9], v[10:11] op_sel_hi:[0,1,1]
	v_pk_fma_f32 v[18:19], v[6:7], v[12:13], v[18:19] op_sel_hi:[0,1,1]
	v_pk_fma_f32 v[36:37], v[6:7], v[32:33], v[36:37] op_sel_hi:[0,1,1]
	v_pk_fma_f32 v[52:53], v[6:7], v[48:49], v[52:53] op_sel_hi:[0,1,1]
	v_lshlrev_b32_e32 v7, 3, v2
	v_add3_u32 v7, 0, v64, v7
	v_ashrrev_i32_e32 v64, 2, v2
	v_add_u32_e32 v106, v7, v64
	ds_read2_b64 v[64:67], v106 offset1:16
	ds_read2_b64 v[68:71], v106 offset0:33 offset1:49
	ds_read2_b64 v[72:75], v106 offset0:66 offset1:82
	ds_read2_b64 v[76:79], v106 offset0:132 offset1:148
	ds_read2_b64 v[80:83], v106 offset0:99 offset1:115
	ds_read2_b64 v[84:87], v106 offset0:165 offset1:181
	ds_read2_b64 v[88:91], v106 offset0:198 offset1:214
	ds_read2_b64 v[92:95], v106 offset0:231 offset1:247
	s_waitcnt lgkmcnt(4)
	v_pk_add_f32 v[96:97], v[64:65], v[76:77]
	v_pk_add_f32 v[64:65], v[64:65], v[76:77] neg_lo:[0,1] neg_hi:[0,1]
	v_pk_add_f32 v[76:77], v[66:67], v[78:79]
	v_pk_add_f32 v[66:67], v[66:67], v[78:79] neg_lo:[0,1] neg_hi:[0,1]
	s_waitcnt lgkmcnt(1)
	v_pk_add_f32 v[98:99], v[74:75], v[90:91]
	v_pk_mul_f32 v[78:79], v[66:67], s[24:25]
	v_pk_add_f32 v[74:75], v[74:75], v[90:91] neg_lo:[0,1] neg_hi:[0,1]
	v_pk_fma_f32 v[66:67], v[66:67], s[22:23], v[78:79] op_sel:[0,0,1] op_sel_hi:[1,0,0]
	v_pk_add_f32 v[78:79], v[68:69], v[84:85]
	v_pk_add_f32 v[68:69], v[68:69], v[84:85] neg_lo:[0,1] neg_hi:[0,1]
	v_pk_mul_f32 v[90:91], v[74:75], s[44:45]
	v_pk_mul_f32 v[84:85], v[68:69], s[40:41]
	v_pk_fma_f32 v[74:75], v[74:75], s[50:51], v[90:91] op_sel:[0,0,1] op_sel_hi:[1,0,0] neg_lo:[1,0,0] neg_hi:[1,0,0]
	v_pk_fma_f32 v[68:69], v[68:69], s[38:39], v[84:85] op_sel:[0,0,1] op_sel_hi:[1,0,0]
	v_pk_add_f32 v[84:85], v[70:71], v[86:87]
	v_pk_add_f32 v[70:71], v[70:71], v[86:87] neg_lo:[0,1] neg_hi:[0,1]
	s_waitcnt lgkmcnt(0)
	v_pk_add_f32 v[90:91], v[80:81], v[92:93]
	v_pk_add_f32 v[80:81], v[80:81], v[92:93] neg_lo:[0,1] neg_hi:[0,1]
	v_pk_mul_f32 v[86:87], v[70:71], s[44:45]
	v_pk_mul_f32 v[92:93], v[80:81], s[40:41]
	v_pk_fma_f32 v[70:71], v[70:71], s[50:51], v[86:87] op_sel:[0,0,1] op_sel_hi:[1,0,0]
	v_pk_add_f32 v[86:87], v[72:73], v[88:89]
	v_pk_add_f32 v[88:89], v[72:73], v[88:89] neg_lo:[0,1] neg_hi:[0,1]
	v_pk_fma_f32 v[80:81], v[80:81], s[38:39], v[92:93] op_sel:[0,0,1] op_sel_hi:[1,0,0] neg_lo:[1,0,0] neg_hi:[1,0,0]
	v_pk_add_f32 v[92:93], v[82:83], v[94:95]
	v_pk_add_f32 v[82:83], v[82:83], v[94:95] neg_lo:[0,1] neg_hi:[0,1]
	s_nop 0
	v_pk_mul_f32 v[94:95], v[82:83], s[24:25]
	s_nop 0
	v_pk_fma_f32 v[82:83], v[82:83], s[22:23], v[94:95] op_sel:[0,0,1] op_sel_hi:[1,0,0] neg_lo:[1,0,0] neg_hi:[1,0,0]
	v_pk_add_f32 v[94:95], v[96:97], v[86:87]
	v_pk_add_f32 v[86:87], v[96:97], v[86:87] neg_lo:[0,1] neg_hi:[0,1]
	v_pk_add_f32 v[96:97], v[76:77], v[98:99]
	v_pk_add_f32 v[76:77], v[76:77], v[98:99] neg_lo:[0,1] neg_hi:[0,1]
	v_pk_add_f32 v[100:101], v[84:85], v[92:93]
	v_pk_add_f32 v[84:85], v[84:85], v[92:93] neg_lo:[0,1] neg_hi:[0,1]
	v_pk_add_f32 v[72:73], v[64:65], v[88:89] op_sel:[0,1] op_sel_hi:[1,0] neg_hi:[0,1]
	v_pk_add_f32 v[64:65], v[64:65], v[88:89] op_sel:[0,1] op_sel_hi:[1,0] neg_lo:[0,1]
	v_pk_add_f32 v[88:89], v[66:67], v[74:75]
	v_pk_add_f32 v[66:67], v[66:67], v[74:75] neg_lo:[0,1] neg_hi:[0,1]
	v_pk_mul_f32 v[98:99], v[76:77], s[40:41]
	v_pk_mul_f32 v[92:93], v[84:85], s[40:41]
	v_pk_mul_f32 v[74:75], v[66:67], s[40:41]
	v_pk_fma_f32 v[76:77], v[76:77], s[38:39], v[98:99] op_sel:[0,0,1] op_sel_hi:[1,0,0]
	v_pk_add_f32 v[98:99], v[78:79], v[90:91]
	v_pk_add_f32 v[90:91], v[78:79], v[90:91] neg_lo:[0,1] neg_hi:[0,1]
	v_pk_fma_f32 v[84:85], v[84:85], s[38:39], v[92:93] op_sel:[0,0,1] op_sel_hi:[1,0,0] neg_lo:[1,0,0] neg_hi:[1,0,0]
	v_pk_fma_f32 v[66:67], v[66:67], s[38:39], v[74:75] op_sel:[0,0,1] op_sel_hi:[1,0,0]
	v_pk_add_f32 v[74:75], v[68:69], v[80:81]
	v_pk_add_f32 v[92:93], v[70:71], v[82:83]
	v_pk_add_f32 v[70:71], v[70:71], v[82:83] neg_lo:[0,1] neg_hi:[0,1]
	v_pk_add_f32 v[80:81], v[68:69], v[80:81] neg_lo:[0,1] neg_hi:[0,1]
	v_pk_mul_f32 v[82:83], v[70:71], s[40:41]
	v_pk_add_f32 v[102:103], v[72:73], v[74:75]
	v_pk_add_f32 v[72:73], v[72:73], v[74:75] neg_lo:[0,1] neg_hi:[0,1]
	v_pk_add_f32 v[74:75], v[88:89], v[92:93]
	v_pk_add_f32 v[92:93], v[88:89], v[92:93] neg_lo:[0,1] neg_hi:[0,1]
	v_pk_mul_f32 v[20:21], v[10:11], 1.0 op_sel:[1,0] op_sel_hi:[1,0] neg_lo:[1,0]
	v_pk_mul_f32 v[24:25], v[14:15], v[12:13] op_sel:[0,1] op_sel_hi:[1,0]
	v_pk_fma_f32 v[70:71], v[70:71], s[38:39], v[82:83] op_sel:[0,0,1] op_sel_hi:[1,0,0] neg_lo:[1,0,0] neg_hi:[1,0,0]
	v_pk_add_f32 v[78:79], v[86:87], v[90:91] op_sel:[0,1] op_sel_hi:[1,0] neg_hi:[0,1]
	v_pk_add_f32 v[86:87], v[86:87], v[90:91] op_sel:[0,1] op_sel_hi:[1,0] neg_lo:[0,1]
	v_pk_add_f32 v[90:91], v[76:77], v[84:85]
	v_pk_add_f32 v[84:85], v[76:77], v[84:85] neg_lo:[0,1] neg_hi:[0,1]
	v_pk_mul_f32 v[22:23], v[18:19], 1.0 op_sel:[1,0] op_sel_hi:[1,0] neg_lo:[1,0]
	v_pk_fma_f32 v[24:25], v[8:9], v[12:13], v[24:25] op_sel_hi:[0,1,1]
	v_pk_mul_f32 v[28:29], v[12:13], v[20:21] op_sel:[1,0] op_sel_hi:[0,1]
	v_pk_add_f32 v[68:69], v[64:65], v[80:81] op_sel:[0,1] op_sel_hi:[1,0] neg_hi:[0,1]
	v_pk_add_f32 v[64:65], v[64:65], v[80:81] op_sel:[0,1] op_sel_hi:[1,0] neg_lo:[0,1]
	v_pk_add_f32 v[80:81], v[66:67], v[70:71]
	v_pk_add_f32 v[70:71], v[66:67], v[70:71] neg_lo:[0,1] neg_hi:[0,1]
	v_pk_add_f32 v[88:89], v[72:73], v[92:93] op_sel:[0,1] op_sel_hi:[1,0] neg_hi:[0,1]
	v_pk_mul_f32 v[26:27], v[24:25], 1.0 op_sel:[1,0] op_sel_hi:[1,0] neg_lo:[1,0]
	v_pk_fma_f32 v[28:29], v[12:13], v[10:11], v[28:29] op_sel_hi:[1,0,1]
	v_pk_add_f32 v[76:77], v[86:87], v[84:85] op_sel:[0,1] op_sel_hi:[1,0] neg_hi:[0,1]
	v_pk_add_f32 v[72:73], v[72:73], v[92:93] op_sel:[0,1] op_sel_hi:[1,0] neg_lo:[0,1]
	v_pk_mul_f32 v[92:93], v[22:23], v[88:89] op_sel:[0,1] op_sel_hi:[1,0]
	v_pk_mul_f32 v[30:31], v[28:29], 1.0 op_sel:[1,0] op_sel_hi:[1,0] neg_lo:[1,0]
	v_pk_add_f32 v[82:83], v[94:95], v[98:99]
	v_pk_add_f32 v[94:95], v[94:95], v[98:99] neg_lo:[0,1] neg_hi:[0,1]
	v_pk_add_f32 v[98:99], v[96:97], v[100:101]
	v_pk_add_f32 v[66:67], v[64:65], v[70:71] op_sel:[0,1] op_sel_hi:[1,0] neg_hi:[0,1]
	v_pk_fma_f32 v[88:89], v[18:19], v[88:89], v[92:93] op_sel_hi:[0,1,1]
	v_pk_mul_f32 v[92:93], v[26:27], v[76:77] op_sel:[0,1] op_sel_hi:[1,0]
	v_pk_mul_f32 v[34:35], v[32:33], 1.0 op_sel:[1,0] op_sel_hi:[1,0] neg_lo:[1,0]
	v_pk_mul_f32 v[40:41], v[14:15], v[32:33] op_sel:[0,1] op_sel_hi:[1,0]
	v_pk_add_f32 v[104:105], v[82:83], v[98:99]
	v_pk_add_f32 v[82:83], v[82:83], v[98:99] neg_lo:[0,1] neg_hi:[0,1]
	v_pk_fma_f32 v[76:77], v[24:25], v[76:77], v[92:93] op_sel_hi:[0,1,1]
	v_pk_mul_f32 v[92:93], v[30:31], v[66:67] op_sel:[0,1] op_sel_hi:[1,0]
	v_pk_mul_f32 v[38:39], v[36:37], 1.0 op_sel:[1,0] op_sel_hi:[1,0] neg_lo:[1,0]
	v_pk_fma_f32 v[40:41], v[8:9], v[32:33], v[40:41] op_sel_hi:[0,1,1]
	v_pk_mul_f32 v[44:45], v[20:21], v[32:33] op_sel:[0,1] op_sel_hi:[1,0]
	v_pk_add_f32 v[84:85], v[86:87], v[84:85] op_sel:[0,1] op_sel_hi:[1,0] neg_lo:[0,1]
	v_pk_add_f32 v[86:87], v[102:103], v[74:75]
	v_pk_add_f32 v[74:75], v[102:103], v[74:75] neg_lo:[0,1] neg_hi:[0,1]
	v_pk_fma_f32 v[66:67], v[28:29], v[66:67], v[92:93] op_sel_hi:[0,1,1]
	v_pk_mul_f32 v[92:93], v[34:35], v[82:83] op_sel:[0,1] op_sel_hi:[1,0]
	v_pk_mul_f32 v[42:43], v[40:41], 1.0 op_sel:[1,0] op_sel_hi:[1,0] neg_lo:[1,0]
	v_pk_fma_f32 v[44:45], v[10:11], v[32:33], v[44:45] op_sel_hi:[0,1,1]
	v_pk_add_f32 v[100:101], v[96:97], v[100:101] neg_lo:[0,1] neg_hi:[0,1]
	v_pk_add_f32 v[98:99], v[78:79], v[90:91]
	v_pk_add_f32 v[78:79], v[78:79], v[90:91] neg_lo:[0,1] neg_hi:[0,1]
	v_pk_fma_f32 v[82:83], v[32:33], v[82:83], v[92:93] op_sel_hi:[0,1,1]
	v_pk_mul_f32 v[92:93], v[38:39], v[74:75] op_sel:[0,1] op_sel_hi:[1,0]
	v_pk_mul_f32 v[46:47], v[44:45], 1.0 op_sel:[1,0] op_sel_hi:[1,0] neg_lo:[1,0]
	v_pk_add_f32 v[90:91], v[68:69], v[80:81]
	v_pk_add_f32 v[68:69], v[68:69], v[80:81] neg_lo:[0,1] neg_hi:[0,1]
	v_pk_fma_f32 v[74:75], v[36:37], v[74:75], v[92:93] op_sel_hi:[0,1,1]
	v_pk_mul_f32 v[92:93], v[42:43], v[78:79] op_sel:[0,1] op_sel_hi:[1,0]
	v_pk_mul_f32 v[50:51], v[48:49], 1.0 op_sel:[1,0] op_sel_hi:[1,0] neg_lo:[1,0]
	v_pk_mul_f32 v[56:57], v[14:15], v[48:49] op_sel:[0,1] op_sel_hi:[1,0]
	v_pk_add_f32 v[96:97], v[94:95], v[100:101] op_sel:[0,1] op_sel_hi:[1,0] neg_hi:[0,1]
	v_pk_add_f32 v[94:95], v[94:95], v[100:101] op_sel:[0,1] op_sel_hi:[1,0] neg_lo:[0,1]
	v_pk_fma_f32 v[78:79], v[40:41], v[78:79], v[92:93] op_sel_hi:[0,1,1]
	v_pk_mul_f32 v[92:93], v[46:47], v[68:69] op_sel:[0,1] op_sel_hi:[1,0]
	v_pk_mul_f32 v[54:55], v[52:53], 1.0 op_sel:[1,0] op_sel_hi:[1,0] neg_lo:[1,0]
	v_pk_fma_f32 v[56:57], v[8:9], v[48:49], v[56:57] op_sel_hi:[0,1,1]
	v_pk_mul_f32 v[60:61], v[20:21], v[48:49] op_sel:[0,1] op_sel_hi:[1,0]
	v_pk_fma_f32 v[68:69], v[44:45], v[68:69], v[92:93] op_sel_hi:[0,1,1]
	v_pk_mul_f32 v[92:93], v[50:51], v[94:95] op_sel:[0,1] op_sel_hi:[1,0]
	v_pk_mul_f32 v[58:59], v[56:57], 1.0 op_sel:[1,0] op_sel_hi:[1,0] neg_lo:[1,0]
	v_pk_fma_f32 v[60:61], v[10:11], v[48:49], v[60:61] op_sel_hi:[0,1,1]
	v_pk_add_f32 v[64:65], v[64:65], v[70:71] op_sel:[0,1] op_sel_hi:[1,0] neg_lo:[0,1]
	v_pk_mul_f32 v[70:71], v[4:5], v[86:87] op_sel:[0,1] op_sel_hi:[1,0]
	v_pk_fma_f32 v[92:93], v[48:49], v[94:95], v[92:93] op_sel_hi:[0,1,1]
	v_pk_mul_f32 v[94:95], v[54:55], v[72:73] op_sel:[0,1] op_sel_hi:[1,0]
	v_pk_mul_f32 v[62:63], v[60:61], 1.0 op_sel:[1,0] op_sel_hi:[1,0] neg_lo:[1,0]
	v_pk_fma_f32 v[70:71], v[6:7], v[86:87], v[70:71] op_sel_hi:[0,1,1]
	v_pk_mul_f32 v[86:87], v[20:21], v[90:91] op_sel:[0,1] op_sel_hi:[1,0]
	v_pk_fma_f32 v[72:73], v[52:53], v[72:73], v[94:95] op_sel_hi:[0,1,1]
	v_pk_mul_f32 v[94:95], v[58:59], v[84:85] op_sel:[0,1] op_sel_hi:[1,0]
	v_add_u32_e32 v2, 0x2000, v2
	v_pk_mul_f32 v[80:81], v[14:15], v[98:99] op_sel:[0,1] op_sel_hi:[1,0]
	v_pk_fma_f32 v[86:87], v[10:11], v[90:91], v[86:87] op_sel_hi:[0,1,1]
	v_pk_mul_f32 v[90:91], v[16:17], v[96:97] op_sel:[0,1] op_sel_hi:[1,0]
	v_pk_fma_f32 v[84:85], v[56:57], v[84:85], v[94:95] op_sel_hi:[0,1,1]
	v_pk_mul_f32 v[94:95], v[62:63], v[64:65] op_sel:[0,1] op_sel_hi:[1,0]
	v_ashrrev_i32_e32 v2, 2, v2
	v_pk_fma_f32 v[80:81], v[8:9], v[98:99], v[80:81] op_sel_hi:[0,1,1]
	v_pk_fma_f32 v[90:91], v[12:13], v[96:97], v[90:91] op_sel_hi:[0,1,1]
	v_pk_fma_f32 v[64:65], v[60:61], v[64:65], v[94:95] op_sel_hi:[0,1,1]
	ds_write2_b64 v106, v[104:105], v[82:83] offset1:16
	ds_write2_b64 v106, v[90:91], v[92:93] offset0:33 offset1:49
	ds_write2_b64 v106, v[80:81], v[78:79] offset0:66 offset1:82
	ds_write2_b64 v106, v[76:77], v[84:85] offset0:99 offset1:115
	ds_write2_b64 v106, v[70:71], v[74:75] offset0:132 offset1:148
	ds_write2_b64 v106, v[88:89], v[72:73] offset0:165 offset1:181
	ds_write2_b64 v106, v[86:87], v[68:69] offset0:198 offset1:214
	ds_write2_b64 v106, v[66:67], v[64:65] offset0:231 offset1:247
	v_add3_u32 v2, v7, v2, s60
	ds_read2_b64 v[64:67], v2 offset1:16
	ds_read2_b64 v[68:71], v2 offset0:33 offset1:49
	ds_read2_b64 v[72:75], v2 offset0:66 offset1:82
	ds_read2_b64 v[76:79], v2 offset0:132 offset1:148
	ds_read2_b64 v[80:83], v2 offset0:99 offset1:115
	ds_read2_b64 v[84:87], v2 offset0:165 offset1:181
	ds_read2_b64 v[88:91], v2 offset0:198 offset1:214
	ds_read2_b64 v[92:95], v2 offset0:231 offset1:247
	s_waitcnt lgkmcnt(4)
	v_pk_add_f32 v[96:97], v[64:65], v[76:77]
	v_pk_add_f32 v[64:65], v[64:65], v[76:77] neg_lo:[0,1] neg_hi:[0,1]
	v_pk_add_f32 v[76:77], v[66:67], v[78:79]
	v_pk_add_f32 v[66:67], v[66:67], v[78:79] neg_lo:[0,1] neg_hi:[0,1]
	s_waitcnt lgkmcnt(1)
	v_pk_add_f32 v[98:99], v[74:75], v[90:91]
	v_pk_mul_f32 v[78:79], v[66:67], s[24:25]
	v_pk_add_f32 v[74:75], v[74:75], v[90:91] neg_lo:[0,1] neg_hi:[0,1]
	v_pk_fma_f32 v[66:67], v[66:67], s[22:23], v[78:79] op_sel:[0,0,1] op_sel_hi:[1,0,0]
	v_pk_add_f32 v[78:79], v[68:69], v[84:85]
	v_pk_add_f32 v[68:69], v[68:69], v[84:85] neg_lo:[0,1] neg_hi:[0,1]
	v_pk_mul_f32 v[90:91], v[74:75], s[44:45]
	v_pk_mul_f32 v[84:85], v[68:69], s[40:41]
	v_pk_fma_f32 v[74:75], v[74:75], s[50:51], v[90:91] op_sel:[0,0,1] op_sel_hi:[1,0,0] neg_lo:[1,0,0] neg_hi:[1,0,0]
	s_waitcnt lgkmcnt(0)
	v_pk_add_f32 v[90:91], v[80:81], v[92:93]
	v_pk_add_f32 v[80:81], v[80:81], v[92:93] neg_lo:[0,1] neg_hi:[0,1]
	v_pk_fma_f32 v[68:69], v[68:69], s[38:39], v[84:85] op_sel:[0,0,1] op_sel_hi:[1,0,0]
	v_pk_add_f32 v[84:85], v[70:71], v[86:87]
	v_pk_add_f32 v[70:71], v[70:71], v[86:87] neg_lo:[0,1] neg_hi:[0,1]
	v_pk_mul_f32 v[92:93], v[80:81], s[40:41]
	v_pk_mul_f32 v[86:87], v[70:71], s[44:45]
	v_pk_fma_f32 v[80:81], v[80:81], s[38:39], v[92:93] op_sel:[0,0,1] op_sel_hi:[1,0,0] neg_lo:[1,0,0] neg_hi:[1,0,0]
	v_pk_add_f32 v[92:93], v[82:83], v[94:95]
	v_pk_add_f32 v[82:83], v[82:83], v[94:95] neg_lo:[0,1] neg_hi:[0,1]
	v_pk_fma_f32 v[70:71], v[70:71], s[50:51], v[86:87] op_sel:[0,0,1] op_sel_hi:[1,0,0]
	v_pk_add_f32 v[86:87], v[72:73], v[88:89]
	v_pk_mul_f32 v[94:95], v[82:83], s[24:25]
	v_pk_add_f32 v[88:89], v[72:73], v[88:89] neg_lo:[0,1] neg_hi:[0,1]
	v_pk_fma_f32 v[82:83], v[82:83], s[22:23], v[94:95] op_sel:[0,0,1] op_sel_hi:[1,0,0] neg_lo:[1,0,0] neg_hi:[1,0,0]
	v_pk_add_f32 v[94:95], v[96:97], v[86:87]
	v_pk_add_f32 v[86:87], v[96:97], v[86:87] neg_lo:[0,1] neg_hi:[0,1]
	v_pk_add_f32 v[96:97], v[76:77], v[98:99]
	v_pk_add_f32 v[76:77], v[76:77], v[98:99] neg_lo:[0,1] neg_hi:[0,1]
	s_nop 0
	v_pk_mul_f32 v[98:99], v[76:77], s[40:41]
	v_pk_add_f32 v[100:101], v[84:85], v[92:93]
	v_pk_add_f32 v[84:85], v[84:85], v[92:93] neg_lo:[0,1] neg_hi:[0,1]
	v_pk_fma_f32 v[76:77], v[76:77], s[38:39], v[98:99] op_sel:[0,0,1] op_sel_hi:[1,0,0]
	v_pk_add_f32 v[98:99], v[78:79], v[90:91]
	v_pk_add_f32 v[90:91], v[78:79], v[90:91] neg_lo:[0,1] neg_hi:[0,1]
	v_pk_mul_f32 v[92:93], v[84:85], s[40:41]
	v_pk_add_f32 v[72:73], v[64:65], v[88:89] op_sel:[0,1] op_sel_hi:[1,0] neg_hi:[0,1]
	v_pk_add_f32 v[64:65], v[64:65], v[88:89] op_sel:[0,1] op_sel_hi:[1,0] neg_lo:[0,1]
	v_pk_add_f32 v[88:89], v[66:67], v[74:75]
	v_pk_add_f32 v[66:67], v[66:67], v[74:75] neg_lo:[0,1] neg_hi:[0,1]
	v_pk_fma_f32 v[84:85], v[84:85], s[38:39], v[92:93] op_sel:[0,0,1] op_sel_hi:[1,0,0] neg_lo:[1,0,0] neg_hi:[1,0,0]
	v_pk_mul_f32 v[74:75], v[66:67], s[40:41]
	s_nop 0
	v_pk_fma_f32 v[66:67], v[66:67], s[38:39], v[74:75] op_sel:[0,0,1] op_sel_hi:[1,0,0]
	v_pk_add_f32 v[74:75], v[68:69], v[80:81]
	v_pk_add_f32 v[92:93], v[70:71], v[82:83]
	v_pk_add_f32 v[70:71], v[70:71], v[82:83] neg_lo:[0,1] neg_hi:[0,1]
	v_pk_add_f32 v[78:79], v[86:87], v[90:91] op_sel:[0,1] op_sel_hi:[1,0] neg_hi:[0,1]
	v_pk_add_f32 v[86:87], v[86:87], v[90:91] op_sel:[0,1] op_sel_hi:[1,0] neg_lo:[0,1]
	v_pk_add_f32 v[90:91], v[76:77], v[84:85]
	v_pk_add_f32 v[84:85], v[76:77], v[84:85] neg_lo:[0,1] neg_hi:[0,1]
	v_pk_add_f32 v[80:81], v[68:69], v[80:81] neg_lo:[0,1] neg_hi:[0,1]
	v_pk_mul_f32 v[82:83], v[70:71], s[40:41]
	v_pk_add_f32 v[102:103], v[72:73], v[74:75]
	v_pk_add_f32 v[72:73], v[72:73], v[74:75] neg_lo:[0,1] neg_hi:[0,1]
	v_pk_add_f32 v[74:75], v[88:89], v[92:93]
	v_pk_fma_f32 v[70:71], v[70:71], s[38:39], v[82:83] op_sel:[0,0,1] op_sel_hi:[1,0,0] neg_lo:[1,0,0] neg_hi:[1,0,0]
	v_pk_add_f32 v[82:83], v[94:95], v[98:99]
	v_pk_add_f32 v[94:95], v[94:95], v[98:99] neg_lo:[0,1] neg_hi:[0,1]
	v_pk_add_f32 v[98:99], v[96:97], v[100:101]
	v_pk_add_f32 v[76:77], v[86:87], v[84:85] op_sel:[0,1] op_sel_hi:[1,0] neg_hi:[0,1]
	v_pk_add_f32 v[84:85], v[86:87], v[84:85] op_sel:[0,1] op_sel_hi:[1,0] neg_lo:[0,1]
	v_pk_add_f32 v[86:87], v[102:103], v[74:75]
	v_pk_add_f32 v[100:101], v[96:97], v[100:101] neg_lo:[0,1] neg_hi:[0,1]
	v_pk_add_f32 v[68:69], v[64:65], v[80:81] op_sel:[0,1] op_sel_hi:[1,0] neg_hi:[0,1]
	v_pk_add_f32 v[64:65], v[64:65], v[80:81] op_sel:[0,1] op_sel_hi:[1,0] neg_lo:[0,1]
	v_pk_add_f32 v[80:81], v[66:67], v[70:71]
	v_pk_add_f32 v[104:105], v[82:83], v[98:99]
	v_pk_add_f32 v[82:83], v[82:83], v[98:99] neg_lo:[0,1] neg_hi:[0,1]
	v_pk_add_f32 v[98:99], v[78:79], v[90:91]
	v_pk_mul_f32 v[4:5], v[4:5], v[86:87] op_sel:[0,1] op_sel_hi:[1,0]
	v_pk_add_f32 v[92:93], v[88:89], v[92:93] neg_lo:[0,1] neg_hi:[0,1]
	v_pk_add_f32 v[78:79], v[78:79], v[90:91] neg_lo:[0,1] neg_hi:[0,1]
	v_pk_add_f32 v[90:91], v[68:69], v[80:81]
	v_pk_fma_f32 v[4:5], v[6:7], v[86:87], v[4:5] op_sel_hi:[0,1,1]
	v_pk_mul_f32 v[6:7], v[14:15], v[98:99] op_sel:[0,1] op_sel_hi:[1,0]
	v_pk_add_f32 v[70:71], v[66:67], v[70:71] neg_lo:[0,1] neg_hi:[0,1]
	v_pk_add_f32 v[96:97], v[94:95], v[100:101] op_sel:[0,1] op_sel_hi:[1,0] neg_hi:[0,1]
	v_pk_fma_f32 v[6:7], v[8:9], v[98:99], v[6:7] op_sel_hi:[0,1,1]
	v_pk_mul_f32 v[8:9], v[20:21], v[90:91] op_sel:[0,1] op_sel_hi:[1,0]
	v_pk_add_f32 v[88:89], v[72:73], v[92:93] op_sel:[0,1] op_sel_hi:[1,0] neg_hi:[0,1]
	v_pk_fma_f32 v[8:9], v[10:11], v[90:91], v[8:9] op_sel_hi:[0,1,1]
	v_pk_mul_f32 v[10:11], v[16:17], v[96:97] op_sel:[0,1] op_sel_hi:[1,0]
	v_pk_add_f32 v[66:67], v[64:65], v[70:71] op_sel:[0,1] op_sel_hi:[1,0] neg_hi:[0,1]
	v_pk_fma_f32 v[10:11], v[12:13], v[96:97], v[10:11] op_sel_hi:[0,1,1]
	v_pk_mul_f32 v[12:13], v[22:23], v[88:89] op_sel:[0,1] op_sel_hi:[1,0]
	v_pk_add_f32 v[94:95], v[94:95], v[100:101] op_sel:[0,1] op_sel_hi:[1,0] neg_lo:[0,1]
	v_pk_add_f32 v[74:75], v[102:103], v[74:75] neg_lo:[0,1] neg_hi:[0,1]
	v_pk_add_f32 v[72:73], v[72:73], v[92:93] op_sel:[0,1] op_sel_hi:[1,0] neg_lo:[0,1]
	v_pk_add_f32 v[68:69], v[68:69], v[80:81] neg_lo:[0,1] neg_hi:[0,1]
	v_pk_add_f32 v[64:65], v[64:65], v[70:71] op_sel:[0,1] op_sel_hi:[1,0] neg_lo:[0,1]
	v_pk_fma_f32 v[12:13], v[18:19], v[88:89], v[12:13] op_sel_hi:[0,1,1]
	v_pk_mul_f32 v[14:15], v[26:27], v[76:77] op_sel:[0,1] op_sel_hi:[1,0]
	v_pk_mul_f32 v[16:17], v[30:31], v[66:67] op_sel:[0,1] op_sel_hi:[1,0]
	v_pk_mul_f32 v[18:19], v[34:35], v[82:83] op_sel:[0,1] op_sel_hi:[1,0]
	v_pk_fma_f32 v[14:15], v[24:25], v[76:77], v[14:15] op_sel_hi:[0,1,1]
	v_pk_fma_f32 v[16:17], v[28:29], v[66:67], v[16:17] op_sel_hi:[0,1,1]
	v_pk_fma_f32 v[18:19], v[32:33], v[82:83], v[18:19] op_sel_hi:[0,1,1]
	v_pk_mul_f32 v[20:21], v[38:39], v[74:75] op_sel:[0,1] op_sel_hi:[1,0]
	v_pk_mul_f32 v[22:23], v[42:43], v[78:79] op_sel:[0,1] op_sel_hi:[1,0]
	v_pk_mul_f32 v[24:25], v[46:47], v[68:69] op_sel:[0,1] op_sel_hi:[1,0]
	v_pk_mul_f32 v[26:27], v[50:51], v[94:95] op_sel:[0,1] op_sel_hi:[1,0]
	v_pk_mul_f32 v[28:29], v[54:55], v[72:73] op_sel:[0,1] op_sel_hi:[1,0]
	v_pk_mul_f32 v[30:31], v[58:59], v[84:85] op_sel:[0,1] op_sel_hi:[1,0]
	v_pk_mul_f32 v[32:33], v[62:63], v[64:65] op_sel:[0,1] op_sel_hi:[1,0]
	v_pk_fma_f32 v[20:21], v[36:37], v[74:75], v[20:21] op_sel_hi:[0,1,1]
	v_pk_fma_f32 v[22:23], v[40:41], v[78:79], v[22:23] op_sel_hi:[0,1,1]
	v_pk_fma_f32 v[24:25], v[44:45], v[68:69], v[24:25] op_sel_hi:[0,1,1]
	v_pk_fma_f32 v[26:27], v[48:49], v[94:95], v[26:27] op_sel_hi:[0,1,1]
	v_pk_fma_f32 v[28:29], v[52:53], v[72:73], v[28:29] op_sel_hi:[0,1,1]
	v_pk_fma_f32 v[30:31], v[56:57], v[84:85], v[30:31] op_sel_hi:[0,1,1]
	v_pk_fma_f32 v[32:33], v[60:61], v[64:65], v[32:33] op_sel_hi:[0,1,1]
	ds_write2_b64 v2, v[104:105], v[18:19] offset1:16
	ds_write2_b64 v2, v[10:11], v[26:27] offset0:33 offset1:49
	ds_write2_b64 v2, v[6:7], v[22:23] offset0:66 offset1:82
	ds_write2_b64 v2, v[14:15], v[30:31] offset0:99 offset1:115
	ds_write2_b64 v2, v[4:5], v[20:21] offset0:132 offset1:148
	ds_write2_b64 v2, v[12:13], v[28:29] offset0:165 offset1:181
	ds_write2_b64 v2, v[8:9], v[24:25] offset0:198 offset1:214
	ds_write2_b64 v2, v[16:17], v[32:33] offset0:231 offset1:247
	s_waitcnt lgkmcnt(0)
	s_barrier
	s_nop 0
	v_ashrrev_i32_e32 v2, 31, v142
	v_add_u32_sdwa v2, v142, v2 dst_sel:DWORD dst_unused:UNUSED_PAD src0_sel:DWORD src1_sel:BYTE_3
	v_ashrrev_i32_e32 v145, 8, v2
	v_mul_i32_i24_e32 v2, 0x100, v145
	v_sub_u32_e32 v144, v142, v2
	v_lshlrev_b32_e32 v2, 1, v144
	v_bfrev_b32_e32 v2, v2
	v_lshrrev_b32_e32 v2, 23, v2
	v_sub_u32_e32 v2, 0x200, v2
	v_bfrev_b32_e32 v2, v2
	v_lshrrev_b32_e32 v2, 19, v2
	v_lshlrev_b32_e32 v143, 13, v145
	v_and_b32_e32 v2, 0x1ff0, v2
	v_cmp_eq_u32_e32 vcc, 0, v144
	v_lshl_add_u32 v4, v144, 5, v143
	v_lshlrev_b32_e32 v5, 3, v4
	v_cndmask_b32_e64 v2, v2, 16, vcc
	v_ashrrev_i32_e32 v4, 2, v4
	v_or_b32_e32 v2, v2, v143
	v_add3_u32 v56, 0, v5, v4
	v_ashrrev_i32_e32 v4, 5, v2
	v_lshlrev_b32_e32 v2, 3, v2
	v_lshlrev_b32_e32 v4, 3, v4
	v_add3_u32 v2, 0, v2, v4
	ds_read2_b64 v[4:7], v56 offset1:1
	ds_read2_b64 v[8:11], v56 offset0:2 offset1:3
	ds_read2_b64 v[12:15], v2 offset1:1
	ds_read2_b64 v[16:19], v2 offset0:2 offset1:3
	ds_read2_b64 v[20:23], v56 offset0:4 offset1:5
	ds_read2_b64 v[24:27], v56 offset0:6 offset1:7
	ds_read2_b64 v[28:31], v2 offset0:4 offset1:5
	ds_read2_b64 v[32:35], v2 offset0:6 offset1:7
	ds_read2_b64 v[36:39], v56 offset0:8 offset1:9
	ds_read2_b64 v[40:43], v56 offset0:10 offset1:11
	ds_read2_b64 v[44:47], v2 offset0:8 offset1:9
	ds_read2_b64 v[52:55], v2 offset0:10 offset1:11
	ds_read2_b64 v[48:51], v56 offset0:12 offset1:13
	ds_read2_b64 v[56:59], v56 offset0:14 offset1:15
	ds_read2_b64 v[62:65], v2 offset0:12 offset1:13
	ds_read2_b64 v[74:77], v2 offset0:14 offset1:15
	s_waitcnt lgkmcnt(7)
	v_pk_add_f32 v[60:61], v[4:5], v[36:37]
	v_pk_add_f32 v[4:5], v[4:5], v[36:37] neg_lo:[0,1] neg_hi:[0,1]
	v_pk_add_f32 v[36:37], v[6:7], v[38:39]
	v_pk_add_f32 v[6:7], v[6:7], v[38:39] neg_lo:[0,1] neg_hi:[0,1]
	s_waitcnt lgkmcnt(3)
	v_pk_add_f32 v[66:67], v[22:23], v[50:51]
	v_pk_mul_f32 v[38:39], v[6:7], s[24:25]
	v_pk_add_f32 v[22:23], v[22:23], v[50:51] neg_lo:[0,1] neg_hi:[0,1]
	v_pk_fma_f32 v[6:7], v[6:7], s[22:23], v[38:39] op_sel:[0,0,1] op_sel_hi:[1,0,0]
	v_pk_add_f32 v[38:39], v[8:9], v[40:41]
	v_pk_add_f32 v[8:9], v[8:9], v[40:41] neg_lo:[0,1] neg_hi:[0,1]
	v_pk_mul_f32 v[50:51], v[22:23], s[44:45]
	v_pk_mul_f32 v[40:41], v[8:9], s[40:41]
	v_pk_fma_f32 v[22:23], v[22:23], s[50:51], v[50:51] op_sel:[0,0,1] op_sel_hi:[1,0,0] neg_lo:[1,0,0] neg_hi:[1,0,0]
	v_pk_fma_f32 v[8:9], v[8:9], s[38:39], v[40:41] op_sel:[0,0,1] op_sel_hi:[1,0,0]
	v_pk_add_f32 v[40:41], v[10:11], v[42:43]
	v_pk_add_f32 v[10:11], v[10:11], v[42:43] neg_lo:[0,1] neg_hi:[0,1]
	s_waitcnt lgkmcnt(2)
	v_pk_add_f32 v[50:51], v[24:25], v[56:57]
	v_pk_add_f32 v[24:25], v[24:25], v[56:57] neg_lo:[0,1] neg_hi:[0,1]
	v_pk_mul_f32 v[42:43], v[10:11], s[44:45]
	v_pk_mul_f32 v[56:57], v[24:25], s[40:41]
	v_pk_fma_f32 v[10:11], v[10:11], s[50:51], v[42:43] op_sel:[0,0,1] op_sel_hi:[1,0,0]
	v_pk_add_f32 v[42:43], v[20:21], v[48:49]
	v_pk_add_f32 v[48:49], v[20:21], v[48:49] neg_lo:[0,1] neg_hi:[0,1]
	v_pk_fma_f32 v[24:25], v[24:25], s[38:39], v[56:57] op_sel:[0,0,1] op_sel_hi:[1,0,0] neg_lo:[1,0,0] neg_hi:[1,0,0]
	v_pk_add_f32 v[56:57], v[26:27], v[58:59]
	v_pk_add_f32 v[26:27], v[26:27], v[58:59] neg_lo:[0,1] neg_hi:[0,1]
	s_nop 0
	v_pk_mul_f32 v[58:59], v[26:27], s[24:25]
	v_pk_add_f32 v[68:69], v[40:41], v[56:57]
	v_pk_add_f32 v[40:41], v[40:41], v[56:57] neg_lo:[0,1] neg_hi:[0,1]
	v_pk_fma_f32 v[26:27], v[26:27], s[22:23], v[58:59] op_sel:[0,0,1] op_sel_hi:[1,0,0] neg_lo:[1,0,0] neg_hi:[1,0,0]
	v_pk_mul_f32 v[56:57], v[40:41], s[40:41]
	v_pk_add_f32 v[20:21], v[4:5], v[48:49] op_sel:[0,1] op_sel_hi:[1,0] neg_hi:[0,1]
	v_pk_add_f32 v[4:5], v[4:5], v[48:49] op_sel:[0,1] op_sel_hi:[1,0] neg_lo:[0,1]
	v_pk_add_f32 v[48:49], v[6:7], v[22:23]
	v_pk_add_f32 v[6:7], v[6:7], v[22:23] neg_lo:[0,1] neg_hi:[0,1]
	v_pk_fma_f32 v[40:41], v[40:41], s[38:39], v[56:57] op_sel:[0,0,1] op_sel_hi:[1,0,0] neg_lo:[1,0,0] neg_hi:[1,0,0]
	v_pk_mul_f32 v[22:23], v[6:7], s[40:41]
	v_pk_add_f32 v[56:57], v[10:11], v[26:27]
	v_pk_add_f32 v[10:11], v[10:11], v[26:27] neg_lo:[0,1] neg_hi:[0,1]
	v_pk_add_f32 v[58:59], v[60:61], v[42:43]
	v_pk_add_f32 v[42:43], v[60:61], v[42:43] neg_lo:[0,1] neg_hi:[0,1]
	v_pk_add_f32 v[60:61], v[36:37], v[66:67]
	v_pk_add_f32 v[36:37], v[36:37], v[66:67] neg_lo:[0,1] neg_hi:[0,1]
	v_pk_fma_f32 v[6:7], v[6:7], s[38:39], v[22:23] op_sel:[0,0,1] op_sel_hi:[1,0,0]
	v_pk_add_f32 v[22:23], v[8:9], v[24:25]
	v_pk_add_f32 v[24:25], v[8:9], v[24:25] neg_lo:[0,1] neg_hi:[0,1]
	v_pk_mul_f32 v[26:27], v[10:11], s[40:41]
	v_pk_mul_f32 v[66:67], v[36:37], s[40:41]
	v_pk_fma_f32 v[10:11], v[10:11], s[38:39], v[26:27] op_sel:[0,0,1] op_sel_hi:[1,0,0] neg_lo:[1,0,0] neg_hi:[1,0,0]
	v_pk_fma_f32 v[36:37], v[36:37], s[38:39], v[66:67] op_sel:[0,0,1] op_sel_hi:[1,0,0]
	v_pk_add_f32 v[66:67], v[38:39], v[50:51]
	v_pk_add_f32 v[8:9], v[4:5], v[24:25] op_sel:[0,1] op_sel_hi:[1,0] neg_hi:[0,1]
	v_pk_add_f32 v[4:5], v[4:5], v[24:25] op_sel:[0,1] op_sel_hi:[1,0] neg_lo:[0,1]
	v_pk_add_f32 v[24:25], v[6:7], v[10:11]
	v_pk_add_f32 v[10:11], v[6:7], v[10:11] neg_lo:[0,1] neg_hi:[0,1]
	v_pk_add_f32 v[26:27], v[58:59], v[66:67]
	v_pk_add_f32 v[58:59], v[58:59], v[66:67] neg_lo:[0,1] neg_hi:[0,1]
	v_pk_add_f32 v[66:67], v[60:61], v[68:69]
	v_pk_add_f32 v[68:69], v[60:61], v[68:69] neg_lo:[0,1] neg_hi:[0,1]
	v_pk_add_f32 v[60:61], v[4:5], v[10:11] op_sel:[0,1] op_sel_hi:[1,0] neg_hi:[0,1]
	v_pk_add_f32 v[90:91], v[4:5], v[10:11] op_sel:[0,1] op_sel_hi:[1,0] neg_lo:[0,1]
	v_pk_add_f32 v[10:11], v[14:15], v[46:47] neg_lo:[0,1] neg_hi:[0,1]
	v_pk_add_f32 v[50:51], v[38:39], v[50:51] neg_lo:[0,1] neg_hi:[0,1]
	v_pk_add_f32 v[84:85], v[58:59], v[68:69] op_sel:[0,1] op_sel_hi:[1,0] neg_hi:[0,1]
	v_pk_add_f32 v[86:87], v[58:59], v[68:69] op_sel:[0,1] op_sel_hi:[1,0] neg_lo:[0,1]
	v_pk_add_f32 v[82:83], v[8:9], v[24:25]
	v_pk_add_f32 v[68:69], v[8:9], v[24:25] neg_lo:[0,1] neg_hi:[0,1]
	v_pk_add_f32 v[4:5], v[12:13], v[44:45]
	v_pk_add_f32 v[6:7], v[12:13], v[44:45] neg_lo:[0,1] neg_hi:[0,1]
	v_pk_add_f32 v[8:9], v[14:15], v[46:47]
	v_pk_mul_f32 v[12:13], v[10:11], s[24:25]
	v_pk_add_f32 v[14:15], v[16:17], v[52:53] neg_lo:[0,1] neg_hi:[0,1]
	v_pk_add_f32 v[70:71], v[20:21], v[22:23]
	v_pk_add_f32 v[20:21], v[20:21], v[22:23] neg_lo:[0,1] neg_hi:[0,1]
	v_pk_add_f32 v[22:23], v[48:49], v[56:57]
	v_pk_add_f32 v[48:49], v[48:49], v[56:57] neg_lo:[0,1] neg_hi:[0,1]
	v_pk_fma_f32 v[10:11], v[10:11], s[22:23], v[12:13] op_sel:[0,0,1] op_sel_hi:[1,0,0]
	v_pk_add_f32 v[12:13], v[16:17], v[52:53]
	v_pk_mul_f32 v[16:17], v[14:15], s[40:41]
	v_pk_add_f32 v[38:39], v[42:43], v[50:51] op_sel:[0,1] op_sel_hi:[1,0] neg_hi:[0,1]
	v_pk_add_f32 v[42:43], v[42:43], v[50:51] op_sel:[0,1] op_sel_hi:[1,0] neg_lo:[0,1]
	v_pk_add_f32 v[50:51], v[36:37], v[40:41]
	v_pk_mul_f32 v[56:57], v[48:49], 1.0 op_sel:[1,0] op_sel_hi:[0,0] neg_hi:[1,0]
	v_pk_fma_f32 v[14:15], v[14:15], s[38:39], v[16:17] op_sel:[0,0,1] op_sel_hi:[1,0,0]
	v_pk_add_f32 v[16:17], v[18:19], v[54:55]
	v_pk_add_f32 v[18:19], v[18:19], v[54:55] neg_lo:[0,1] neg_hi:[0,1]
	v_pk_add_f32 v[130:131], v[26:27], v[66:67]
	v_pk_add_f32 v[92:93], v[26:27], v[66:67] neg_lo:[0,1] neg_hi:[0,1]
	v_pk_add_f32 v[88:89], v[38:39], v[50:51]
	v_pk_add_f32 v[72:73], v[38:39], v[50:51] neg_lo:[0,1] neg_hi:[0,1]
	v_pk_add_f32 v[96:97], v[70:71], v[22:23]
	v_pk_add_f32 v[50:51], v[70:71], v[22:23] neg_lo:[0,1] neg_hi:[0,1]
	v_pk_add_f32 v[66:67], v[20:21], v[56:57]
	v_pk_add_f32 v[80:81], v[20:21], v[56:57] neg_lo:[0,1] neg_hi:[0,1]
	v_pk_mul_f32 v[20:21], v[18:19], s[44:45]
	s_waitcnt lgkmcnt(1)
	v_pk_add_f32 v[24:25], v[28:29], v[62:63] neg_lo:[0,1] neg_hi:[0,1]
	v_pk_add_f32 v[26:27], v[30:31], v[64:65] neg_lo:[0,1] neg_hi:[0,1]
	v_pk_fma_f32 v[18:19], v[18:19], s[50:51], v[20:21] op_sel:[0,0,1] op_sel_hi:[1,0,0]
	v_pk_add_f32 v[20:21], v[28:29], v[62:63]
	v_pk_add_f32 v[22:23], v[30:31], v[64:65]
	v_pk_mul_f32 v[28:29], v[26:27], s[44:45]
	s_waitcnt lgkmcnt(0)
	v_pk_add_f32 v[30:31], v[32:33], v[74:75] neg_lo:[0,1] neg_hi:[0,1]
	v_pk_fma_f32 v[26:27], v[26:27], s[50:51], v[28:29] op_sel:[0,0,1] op_sel_hi:[1,0,0] neg_lo:[1,0,0] neg_hi:[1,0,0]
	v_pk_add_f32 v[28:29], v[32:33], v[74:75]
	v_pk_mul_f32 v[32:33], v[30:31], s[40:41]
	v_pk_add_f32 v[36:37], v[36:37], v[40:41] neg_lo:[0,1] neg_hi:[0,1]
	v_pk_fma_f32 v[30:31], v[30:31], s[38:39], v[32:33] op_sel:[0,0,1] op_sel_hi:[1,0,0] neg_lo:[1,0,0] neg_hi:[1,0,0]
	v_pk_add_f32 v[32:33], v[34:35], v[76:77]
	v_pk_add_f32 v[34:35], v[34:35], v[76:77] neg_lo:[0,1] neg_hi:[0,1]
	v_pk_mul_f32 v[40:41], v[36:37], 1.0 op_sel:[1,0] op_sel_hi:[0,0] neg_hi:[1,0]
	v_pk_mul_f32 v[36:37], v[34:35], s[24:25]
	v_mov_b32_e32 v2, v130
	v_pk_fma_f32 v[34:35], v[34:35], s[22:23], v[36:37] op_sel:[0,0,1] op_sel_hi:[1,0,0] neg_lo:[1,0,0] neg_hi:[1,0,0]
	v_pk_add_f32 v[36:37], v[4:5], v[20:21]
	v_pk_add_f32 v[4:5], v[4:5], v[20:21] neg_lo:[0,1] neg_hi:[0,1]
	v_pk_add_f32 v[20:21], v[8:9], v[22:23]
	v_pk_add_f32 v[8:9], v[8:9], v[22:23] neg_lo:[0,1] neg_hi:[0,1]
	v_cmp_ne_u32_e64 s[0:1], 0, v144
	v_pk_mul_f32 v[22:23], v[8:9], s[40:41]
	v_pk_add_f32 v[78:79], v[42:43], v[40:41]
	v_pk_fma_f32 v[8:9], v[8:9], s[38:39], v[22:23] op_sel:[0,0,1] op_sel_hi:[1,0,0]
	v_pk_add_f32 v[22:23], v[12:13], v[28:29]
	v_pk_add_f32 v[28:29], v[12:13], v[28:29] neg_lo:[0,1] neg_hi:[0,1]
	v_pk_add_f32 v[94:95], v[42:43], v[40:41] neg_lo:[0,1] neg_hi:[0,1]
	v_pk_add_f32 v[12:13], v[16:17], v[32:33]
	v_pk_add_f32 v[16:17], v[16:17], v[32:33] neg_lo:[0,1] neg_hi:[0,1]
	s_nop 0
	v_pk_mul_f32 v[32:33], v[16:17], s[40:41]
	s_nop 0
	v_pk_fma_f32 v[16:17], v[16:17], s[38:39], v[32:33] op_sel:[0,0,1] op_sel_hi:[1,0,0] neg_lo:[1,0,0] neg_hi:[1,0,0]
	v_pk_add_f32 v[32:33], v[6:7], v[24:25] op_sel:[0,1] op_sel_hi:[1,0] neg_hi:[0,1]
	v_pk_add_f32 v[6:7], v[6:7], v[24:25] op_sel:[0,1] op_sel_hi:[1,0] neg_lo:[0,1]
	v_pk_add_f32 v[24:25], v[10:11], v[26:27]
	v_pk_add_f32 v[10:11], v[10:11], v[26:27] neg_lo:[0,1] neg_hi:[0,1]
	s_nop 0
	v_pk_mul_f32 v[26:27], v[10:11], s[40:41]
	s_nop 0
	v_pk_fma_f32 v[10:11], v[10:11], s[38:39], v[26:27] op_sel:[0,0,1] op_sel_hi:[1,0,0]
	v_pk_add_f32 v[26:27], v[14:15], v[30:31]
	v_pk_add_f32 v[30:31], v[14:15], v[30:31] neg_lo:[0,1] neg_hi:[0,1]
	s_nop 0
	v_pk_add_f32 v[14:15], v[18:19], v[34:35]
	v_pk_add_f32 v[18:19], v[18:19], v[34:35] neg_lo:[0,1] neg_hi:[0,1]
	s_nop 0
	v_pk_mul_f32 v[34:35], v[18:19], s[40:41]
	s_nop 0
	v_pk_fma_f32 v[18:19], v[18:19], s[38:39], v[34:35] op_sel:[0,0,1] op_sel_hi:[1,0,0] neg_lo:[1,0,0] neg_hi:[1,0,0]
	v_pk_add_f32 v[34:35], v[36:37], v[22:23]
	v_pk_add_f32 v[22:23], v[36:37], v[22:23] neg_lo:[0,1] neg_hi:[0,1]
	v_pk_add_f32 v[36:37], v[20:21], v[12:13]
	v_pk_add_f32 v[12:13], v[20:21], v[12:13] neg_lo:[0,1] neg_hi:[0,1]
	v_pk_add_f32 v[98:99], v[34:35], v[36:37]
	v_pk_mul_f32 v[20:21], v[12:13], 1.0 op_sel:[1,0] op_sel_hi:[0,0] neg_hi:[1,0]
	v_pk_add_f32 v[12:13], v[4:5], v[28:29] op_sel:[0,1] op_sel_hi:[1,0] neg_hi:[0,1]
	v_pk_add_f32 v[4:5], v[4:5], v[28:29] op_sel:[0,1] op_sel_hi:[1,0] neg_lo:[0,1]
	v_pk_add_f32 v[28:29], v[8:9], v[16:17]
	v_pk_add_f32 v[8:9], v[8:9], v[16:17] neg_lo:[0,1] neg_hi:[0,1]
	v_pk_add_f32 v[100:101], v[34:35], v[36:37] neg_lo:[0,1] neg_hi:[0,1]
	v_pk_mul_f32 v[16:17], v[8:9], 1.0 op_sel:[1,0] op_sel_hi:[0,0] neg_hi:[1,0]
	v_pk_add_f32 v[8:9], v[32:33], v[26:27]
	v_pk_add_f32 v[26:27], v[32:33], v[26:27] neg_lo:[0,1] neg_hi:[0,1]
	v_pk_add_f32 v[32:33], v[24:25], v[14:15]
	v_pk_add_f32 v[14:15], v[24:25], v[14:15] neg_lo:[0,1] neg_hi:[0,1]
	v_pk_add_f32 v[102:103], v[22:23], v[20:21]
	v_pk_mul_f32 v[24:25], v[14:15], 1.0 op_sel:[1,0] op_sel_hi:[0,0] neg_hi:[1,0]
	v_pk_add_f32 v[14:15], v[6:7], v[30:31] op_sel:[0,1] op_sel_hi:[1,0] neg_hi:[0,1]
	v_pk_add_f32 v[6:7], v[6:7], v[30:31] op_sel:[0,1] op_sel_hi:[1,0] neg_lo:[0,1]
	v_pk_add_f32 v[30:31], v[10:11], v[18:19]
	v_pk_add_f32 v[10:11], v[10:11], v[18:19] neg_lo:[0,1] neg_hi:[0,1]
	v_pk_add_f32 v[104:105], v[22:23], v[20:21] neg_lo:[0,1] neg_hi:[0,1]
	v_pk_mul_f32 v[18:19], v[10:11], 1.0 op_sel:[1,0] op_sel_hi:[0,0] neg_hi:[1,0]
	v_pk_add_f32 v[106:107], v[12:13], v[28:29]
	v_pk_add_f32 v[108:109], v[12:13], v[28:29] neg_lo:[0,1] neg_hi:[0,1]
	v_pk_add_f32 v[110:111], v[4:5], v[16:17]
	v_pk_add_f32 v[112:113], v[4:5], v[16:17] neg_lo:[0,1] neg_hi:[0,1]
	v_pk_add_f32 v[114:115], v[8:9], v[32:33]
	v_pk_add_f32 v[116:117], v[8:9], v[32:33] neg_lo:[0,1] neg_hi:[0,1]
	v_pk_add_f32 v[118:119], v[26:27], v[24:25]
	v_pk_add_f32 v[120:121], v[26:27], v[24:25] neg_lo:[0,1] neg_hi:[0,1]
	v_pk_add_f32 v[122:123], v[14:15], v[30:31]
	v_pk_add_f32 v[124:125], v[14:15], v[30:31] neg_lo:[0,1] neg_hi:[0,1]
	v_pk_add_f32 v[126:127], v[6:7], v[18:19]
	v_pk_add_f32 v[128:129], v[6:7], v[18:19] neg_lo:[0,1] neg_hi:[0,1]
	v_mov_b32_e32 v4, v131
	v_mov_b32_e32 v5, v3
	v_mov_b64_e32 v[6:7], v[2:3]
	s_and_saveexec_b64 s[50:51], s[0:1]
	s_xor_b64 s[0:1], exec, s[50:51]
	s_cbranch_execz .LBB0_576
	v_pk_add_f32 v[4:5], v[96:97], v[112:113]
	v_pk_add_f32 v[24:25], v[96:97], v[112:113] neg_lo:[0,1] neg_hi:[0,1]
	v_pk_add_f32 v[148:149], v[130:131], v[128:129]
	v_pk_add_f32 v[8:9], v[130:131], v[128:129] neg_lo:[0,1] neg_hi:[0,1]
	v_pk_add_f32 v[128:129], v[126:127], v[92:93]
	v_pk_add_f32 v[10:11], v[126:127], v[92:93] neg_lo:[0,1] neg_hi:[0,1]
	v_pk_add_f32 v[92:93], v[84:85], v[124:125]
	v_pk_add_f32 v[12:13], v[84:85], v[124:125] neg_lo:[0,1] neg_hi:[0,1]
	v_pk_add_f32 v[84:85], v[122:123], v[86:87]
	v_pk_add_f32 v[14:15], v[122:123], v[86:87] neg_lo:[0,1] neg_hi:[0,1]
	v_pk_add_f32 v[86:87], v[88:89], v[120:121]
	v_pk_add_f32 v[16:17], v[88:89], v[120:121] neg_lo:[0,1] neg_hi:[0,1]
	v_pk_add_f32 v[88:89], v[118:119], v[72:73]
	v_pk_add_f32 v[18:19], v[118:119], v[72:73] neg_lo:[0,1] neg_hi:[0,1]
	v_pk_add_f32 v[72:73], v[78:79], v[116:117]
	v_pk_add_f32 v[20:21], v[78:79], v[116:117] neg_lo:[0,1] neg_hi:[0,1]
	v_pk_add_f32 v[78:79], v[114:115], v[94:95]
	v_pk_add_f32 v[22:23], v[114:115], v[94:95] neg_lo:[0,1] neg_hi:[0,1]
	v_mov_b32_e32 v6, v4
	v_mov_b32_e32 v7, v25
	v_pk_mov_b32 v[4:5], v[4:5], v[24:25] op_sel:[1,0]
	v_pk_add_f32 v[94:95], v[110:111], v[50:51]
	v_pk_add_f32 v[24:25], v[110:111], v[50:51] neg_lo:[0,1] neg_hi:[0,1]
	v_pk_add_f32 v[50:51], v[66:67], v[108:109]
	v_pk_add_f32 v[26:27], v[66:67], v[108:109] neg_lo:[0,1] neg_hi:[0,1]
	v_pk_add_f32 v[66:67], v[106:107], v[80:81]
	v_pk_add_f32 v[28:29], v[106:107], v[80:81] neg_lo:[0,1] neg_hi:[0,1]
	v_pk_add_f32 v[80:81], v[82:83], v[104:105]
	v_pk_add_f32 v[30:31], v[82:83], v[104:105] neg_lo:[0,1] neg_hi:[0,1]
	v_pk_add_f32 v[82:83], v[102:103], v[68:69]
	v_pk_add_f32 v[32:33], v[102:103], v[68:69] neg_lo:[0,1] neg_hi:[0,1]
	v_pk_add_f32 v[68:69], v[60:61], v[100:101]
	v_pk_add_f32 v[34:35], v[60:61], v[100:101] neg_lo:[0,1] neg_hi:[0,1]
	v_pk_add_f32 v[60:61], v[98:99], v[90:91]
	v_pk_add_f32 v[36:37], v[98:99], v[90:91] neg_lo:[0,1] neg_hi:[0,1]
	v_pk_mul_f32 v[6:7], v[6:7], 0.5 op_sel_hi:[1,0]
	v_pk_mul_f32 v[4:5], v[4:5], s[46:47]
	v_mov_b32_e32 v39, v8
	v_mov_b32_e32 v38, v149
	v_mov_b32_e32 v41, v10
	v_mov_b32_e32 v40, v129
	v_mov_b32_e32 v43, v12
	v_mov_b32_e32 v42, v93
	v_mov_b32_e32 v45, v14
	v_mov_b32_e32 v44, v85
	v_mov_b32_e32 v47, v16
	v_mov_b32_e32 v46, v87
	v_mov_b32_e32 v49, v18
	v_mov_b32_e32 v48, v89
	v_mov_b32_e32 v53, v20
	v_mov_b32_e32 v52, v73
	v_mov_b32_e32 v55, v22
	v_mov_b32_e32 v54, v79
	v_mov_b32_e32 v57, v24
	v_mov_b32_e32 v56, v95
	v_mov_b32_e32 v59, v26
	v_mov_b32_e32 v58, v51
	v_mov_b32_e32 v63, v28
	v_mov_b32_e32 v62, v67
	v_mov_b32_e32 v65, v30
	v_mov_b32_e32 v64, v81
	v_mov_b32_e32 v71, v32
	v_mov_b32_e32 v70, v83
	v_mov_b32_e32 v75, v34
	v_mov_b32_e32 v74, v69
	v_mov_b32_e32 v77, v36
	v_mov_b32_e32 v76, v61
	v_mov_b32_e32 v8, v148
	v_mov_b32_e32 v10, v128
	v_mov_b32_e32 v12, v92
	v_mov_b32_e32 v14, v84
	v_mov_b32_e32 v16, v86
	v_mov_b32_e32 v18, v88
	v_mov_b32_e32 v20, v72
	v_mov_b32_e32 v22, v78
	v_mov_b32_e32 v24, v94
	v_mov_b32_e32 v26, v50
	v_mov_b32_e32 v28, v66
	v_mov_b32_e32 v30, v80
	v_mov_b32_e32 v32, v82
	v_mov_b32_e32 v34, v68
	v_mov_b32_e32 v36, v60
